# all flat ops converted to global (LDS waits no longer stall on VMEM) + attention K/V prefetch waits counted
# baseline (speedup 1.0000x reference)
; #define LAS __attribute__((address_space(3)))
; __device__ __forceinline__ int otid() { int t = threadIdx.x; asm volatile("" : "+v"(t)); return t; }
; __device__ __forceinline__ unsigned xb_add(unsigned* p, unsigned v) { return __hip_atomic_fetch_add(p, v, __ATOMIC_RELAXED, __HIP_MEMORY_SCOPE_AGENT); }
; __device__ __forceinline__ unsigned xb_xcc_id() { return (unsigned)__builtin_amdgcn_s_getreg((3 << 11) | 20) & 0xFu; }
; __global__ void __launch_bounds__(512, 2) mega(Params p) {
;   cg::grid_group grid = cg::this_grid();
;   extern __shared__ __attribute__((aligned(16))) unsigned char shm[];
;   LAS unsigned char* lds = (LAS unsigned char*)shm;
;   LAS float* tile = (LAS float*)shm;
;   volatile LAS unsigned* bst = (volatile LAS unsigned*)(lds + STAGE_BYTES + 2048 + 8192);
;   if (otid() == 0) { const unsigned x = xb_xcc_id(); bst[0] = x; bst[3] = xb_add((unsigned*)((unsigned char*)karg(15) + WS_BAR) + XB_XCNT(x), 1u); }
_Z4mega6Params:
	s_add_u32 s6, s0, 0x80
	s_addc_u32 s7, s1, 0
	v_writelane_b32 v255, s0, 0
	s_load_dword s20, s[0:1], 0x80
	v_and_b32_e32 v252, 0x3ff, v0
	v_mov_b32_e32 v1, v252
	v_writelane_b32 v255, s1, 1
	s_movk_i32 s0, 0x3ff
	s_nop 0
	v_cmp_eq_u32_e32 vcc, 0, v1
	s_and_saveexec_b64 s[4:5], vcc
	s_cbranch_execz .LBB0_2
	s_getreg_b32 s1, hwreg(HW_REG_XCC_ID, 0, 4)
	s_and_b32 s1, s1, 15
	s_add_i32 s3, 0, 0x22800
	v_readlane_b32 s8, v255, 0
	v_mov_b32_e32 v1, s3
	v_mov_b32_e32 v2, s1
	v_readlane_b32 s9, v255, 1
	ds_write_b32 v1, v2
	s_lshl_b32 s1, s1, 8
	v_mov_b64_e32 v[2:3], s[8:9]
	global_load_dwordx2 v[2:3], v[2:3], off offset:120 sc0 sc1
	s_waitcnt vmcnt(0) lgkmcnt(0)
	v_readfirstlane_b32 s8, v2
	v_readfirstlane_b32 s3, v3
	s_add_u32 s1, s8, s1
	s_addc_u32 s3, s3, 0
	v_mov_b32_e32 v1, s1
	v_add_co_u32_e32 v2, vcc, 0x4cc80000, v1
	v_mov_b32_e32 v1, s3
	s_nop 0
	v_addc_co_u32_e32 v3, vcc, 0, v1, vcc
	v_mov_b32_e32 v1, 1
	global_atomic_add v1, v[2:3], v1, off offset:256 sc0
	s_add_i32 s1, 0, 0x2280c
	v_mov_b32_e32 v2, s1
	s_waitcnt vmcnt(0) lgkmcnt(0)
	ds_write_b32 v2, v1

; __device__ __forceinline__ int otid() { int t = threadIdx.x; asm volatile("" : "+v"(t)); return t; }
; __device__ __forceinline__ unsigned xb_ld(unsigned* p) { return __hip_atomic_load(p, __ATOMIC_RELAXED, __HIP_MEMORY_SCOPE_AGENT); }
; __global__ void __launch_bounds__(512, 2) mega(Params p) {
;     ...
;   if (otid() == 0) {
;     unsigned* bar = (unsigned*)((unsigned char*)karg(15) + WS_BAR); const unsigned x = bst[0]; unsigned mine = 1, cnt = 0;
;     for (unsigned jx = 0; jx < 16; ++jx) { const unsigned c = xb_ld(&bar[XB_XCNT(jx)]); cnt += (c > 0u) ? 1u : 0u; mine = (jx == x) ? c : mine; }
;     bst[1] = mine; bst[2] = cnt;
;     unsigned okc = (cnt == 8u && gridDim.x == 256u) ? 1u : 0u;
;     for (unsigned jx = 0; jx < 8; ++jx) okc &= (xb_ld(&bar[XB_XCNT(jx)]) == 32u) ? 1u : 0u;
;     bst[3] = okc ? (x + 8u * bst[3]) : blockIdx.x;
;   }
.LBB0_12:
	s_or_b64 exec, exec, s[4:5]
	v_mov_b32_e32 v0, v252
	s_barrier
	s_nop 0
	v_cmp_eq_u32_e32 vcc, 0, v0
	s_and_saveexec_b64 s[22:23], vcc
	s_cbranch_execz .LBB0_16
	v_readlane_b32 s0, v255, 0
	v_readlane_b32 s1, v255, 1
	s_nop 1
	v_mov_b64_e32 v[0:1], s[0:1]
	global_load_dwordx2 v[2:3], v[0:1], off offset:120 sc0 sc1
	s_waitcnt vmcnt(0)
	s_add_i32 s0, 0, 0x22800
	v_mov_b32_e32 v0, s0
	ds_read_b32 v0, v0
	s_waitcnt lgkmcnt(0)
	v_readfirstlane_b32 s1, v2
	v_readfirstlane_b32 s0, v3
	s_nop 0
	v_mov_b32_e32 v1, s1
	v_add_co_u32_e32 v2, vcc, 0x4cc80000, v1
	v_mov_b32_e32 v5, s0
	s_nop 0
	v_addc_co_u32_e32 v3, vcc, 0, v5, vcc
	global_load_dword v6, v[2:3], off offset:256 sc1
	global_load_dword v7, v[2:3], off offset:512 sc1
	global_load_dword v8, v[2:3], off offset:768 sc1
	global_load_dword v9, v[2:3], off offset:1024 sc1
	global_load_dword v10, v[2:3], off offset:1280 sc1
	global_load_dword v11, v[2:3], off offset:1536 sc1
	global_load_dword v12, v[2:3], off offset:1792 sc1
	global_load_dword v13, v[2:3], off offset:2048 sc1
	global_load_dword v14, v[2:3], off offset:2304 sc1
	global_load_dword v15, v[2:3], off offset:2560 sc1
	global_load_dword v16, v[2:3], off offset:2816 sc1
	global_load_dword v17, v[2:3], off offset:3072 sc1
	global_load_dword v18, v[2:3], off offset:3328 sc1
	global_load_dword v19, v[2:3], off offset:3584 sc1
	global_load_dword v20, v[2:3], off offset:3840 sc1
	s_mov_b32 s0, 0x4cc81000
	v_add_co_u32_e32 v4, vcc, s0, v1
	s_add_i32 s0, 0, 0x22804
	s_nop 0
	v_addc_co_u32_e32 v5, vcc, 0, v5, vcc
	global_load_dword v1, v[4:5], off sc1
	v_cmp_eq_u32_e32 vcc, 0, v0
	s_add_i32 s1, 0, 0x22808
	v_mov_b32_e32 v4, s0
	v_mov_b32_e32 v5, s1
	s_cmpk_eq_i32 s20, 0x100
	s_cselect_b64 s[0:1], -1, 0
	s_waitcnt vmcnt(0) lgkmcnt(0)
	v_cndmask_b32_e32 v21, 1, v6, vcc
	v_cmp_ne_u32_e32 vcc, 0, v7
	s_nop 1
	v_cndmask_b32_e64 v22, 0, 1, vcc
	v_cmp_ne_u32_e32 vcc, 0, v8
	s_nop 1
	v_cndmask_b32_e64 v23, 0, 1, vcc
	v_cmp_ne_u32_e32 vcc, 0, v10
	s_nop 1
	v_cndmask_b32_e64 v24, 0, 1, vcc
	v_cmp_ne_u32_e32 vcc, 0, v12
	s_nop 1
	v_cndmask_b32_e64 v25, 0, 1, vcc
	v_cmp_ne_u32_e32 vcc, 0, v14
	s_nop 1
	v_cndmask_b32_e64 v26, 0, 1, vcc
	v_cmp_ne_u32_e32 vcc, 0, v16
	s_nop 1
	v_cndmask_b32_e64 v27, 0, 1, vcc
	v_cmp_ne_u32_e32 vcc, 0, v18
	s_nop 1
	v_cndmask_b32_e64 v28, 0, 1, vcc
	v_cmp_ne_u32_e32 vcc, 0, v20
	s_nop 1
	v_cndmask_b32_e64 v29, 0, 1, vcc
	v_cmp_ne_u32_e32 vcc, 0, v6
	s_nop 1
	v_addc_co_u32_e32 v6, vcc, 0, v22, vcc
	v_cmp_eq_u32_e32 vcc, 1, v0
	s_nop 1
	v_cndmask_b32_e32 v7, v21, v7, vcc
	v_cmp_eq_u32_e32 vcc, 2, v0
	s_nop 1
	v_cndmask_b32_e32 v7, v7, v8, vcc
	v_cmp_ne_u32_e32 vcc, 0, v9
	s_nop 1
	v_addc_co_u32_e32 v6, vcc, v6, v23, vcc
	v_cmp_eq_u32_e32 vcc, 3, v0
	s_nop 1
	v_cndmask_b32_e32 v7, v7, v9, vcc
	v_cmp_ne_u32_e32 vcc, 0, v11
	s_nop 1
	v_addc_co_u32_e32 v6, vcc, v6, v24, vcc
	v_cmp_eq_u32_e32 vcc, 4, v0
	s_nop 1
	v_cndmask_b32_e32 v7, v7, v10, vcc
	v_cmp_ne_u32_e32 vcc, 0, v13
	s_nop 1
	v_addc_co_u32_e32 v6, vcc, v6, v25, vcc
	v_cmp_eq_u32_e32 vcc, 5, v0
	s_nop 1
	v_cndmask_b32_e32 v7, v7, v11, vcc
	v_cmp_ne_u32_e32 vcc, 0, v15
	s_nop 1
	v_addc_co_u32_e32 v6, vcc, v6, v26, vcc
	v_cmp_eq_u32_e32 vcc, 6, v0
	s_nop 1
	v_cndmask_b32_e32 v7, v7, v12, vcc
	v_cmp_ne_u32_e32 vcc, 0, v17
	s_nop 1
	v_addc_co_u32_e32 v6, vcc, v6, v27, vcc
	v_cmp_eq_u32_e32 vcc, 7, v0
	s_nop 1
	v_cndmask_b32_e32 v7, v7, v13, vcc
	v_cmp_ne_u32_e32 vcc, 0, v19
	s_nop 1
	v_addc_co_u32_e32 v6, vcc, v6, v28, vcc
	v_cmp_eq_u32_e32 vcc, 8, v0
	s_nop 1
	v_cndmask_b32_e32 v7, v7, v14, vcc
	v_cmp_ne_u32_e32 vcc, 0, v1
	s_nop 1
	v_addc_co_u32_e32 v6, vcc, v6, v29, vcc
	v_cmp_eq_u32_e32 vcc, 9, v0
	s_nop 1
	v_cndmask_b32_e32 v7, v7, v15, vcc
	v_cmp_eq_u32_e32 vcc, 10, v0
	s_nop 1
	v_cndmask_b32_e32 v7, v7, v16, vcc
	v_cmp_eq_u32_e32 vcc, 11, v0
	s_nop 1
	v_cndmask_b32_e32 v7, v7, v17, vcc
	v_cmp_eq_u32_e32 vcc, 12, v0
	s_nop 1
	v_cndmask_b32_e32 v7, v7, v18, vcc
	v_cmp_eq_u32_e32 vcc, 13, v0
	s_nop 1
	v_cndmask_b32_e32 v7, v7, v19, vcc
	v_cmp_eq_u32_e32 vcc, 14, v0
	s_nop 1
	v_cndmask_b32_e32 v7, v7, v20, vcc
	v_cmp_eq_u32_e32 vcc, 15, v0
	s_nop 1
	v_cndmask_b32_e32 v1, v7, v1, vcc
	ds_write_b32 v4, v1
	ds_write_b32 v5, v6
	global_load_dword v1, v[2:3], off offset:256 sc1
	global_load_dword v4, v[2:3], off offset:512 sc1
	global_load_dword v5, v[2:3], off offset:768 sc1
	global_load_dword v7, v[2:3], off offset:1024 sc1
	global_load_dword v8, v[2:3], off offset:1280 sc1
	global_load_dword v9, v[2:3], off offset:1536 sc1
	global_load_dword v10, v[2:3], off offset:1792 sc1
	global_load_dword v11, v[2:3], off offset:2048 sc1
	v_cmp_eq_u32_e32 vcc, 8, v6
	s_waitcnt vmcnt(0) lgkmcnt(0)
	v_cmp_eq_u32_e64 s[4:5], 32, v1
	v_cmp_eq_u32_e64 s[6:7], 32, v4
	v_cmp_eq_u32_e64 s[8:9], 32, v5
	v_cmp_eq_u32_e64 s[10:11], 32, v7
	v_cmp_eq_u32_e64 s[12:13], 32, v8
	v_cmp_eq_u32_e64 s[14:15], 32, v9
	v_cmp_eq_u32_e64 s[16:17], 32, v10
	v_cmp_eq_u32_e64 s[18:19], 32, v11
	s_and_b64 s[16:17], s[18:19], s[16:17]
	s_and_b64 s[14:15], s[16:17], s[14:15]
	s_and_b64 s[12:13], s[14:15], s[12:13]
	s_and_b64 s[10:11], s[12:13], s[10:11]
	s_and_b64 s[8:9], s[10:11], s[8:9]
	s_and_b64 s[6:7], s[8:9], s[6:7]
	s_and_b64 s[4:5], s[6:7], s[4:5]
	s_and_b64 s[4:5], s[4:5], vcc
	s_and_b64 s[0:1], s[4:5], s[0:1]
	v_mov_b32_e32 v1, s2
	s_and_saveexec_b64 s[2:3], s[0:1]
	s_cbranch_execz .LBB0_15
	s_add_i32 s0, 0, 0x2280c
	v_mov_b32_e32 v1, s0
	ds_read_b32 v1, v1
	s_waitcnt lgkmcnt(0)
	v_lshlrev_b32_e32 v1, 3, v1
	v_add_u32_e32 v1, v1, v0

; #define LAS __attribute__((address_space(3)))
; __device__ __forceinline__ unsigned cvt_pk_bf16(float lo, float hi) { unsigned r; asm("v_cvt_pk_bf16_f32 %0, %1, %2" : "=v"(r) : "v"(lo), "v"(hi)); return r; }
; __device__ __forceinline__ int otid() { int t = threadIdx.x; asm volatile("" : "+v"(t)); return t; }
; __device__ __forceinline__ int obid() { extern __shared__ __attribute__((aligned(16))) unsigned char shm_vb[]; return __builtin_amdgcn_readfirstlane(*(volatile LAS int*)((LAS unsigned char*)shm_vb + VB_OFF)); }
; __device__ __forceinline__ void phase_wT(const float* __restrict__ src, int ldn, int n0, int K, int N, bf16_t* __restrict__ dst, LAS float* tile, const float* __restrict__ gain = nullptr) {
;   const int tk = K / 64, tn = N / 256, nt = tk * tn, t = otid(), w = t >> 6, lane = t & 63;
;   for (int ti = obid(); ti < nt; ti += gridDim.x) {
;     const int kt = ti % tk, ntile = ti / tk;
;     float4 v[8];
; #pragma unroll
;     for (int i = 0; i < 8; ++i) v[i] = *(const float4*)(src + (size_t)(kt * 64 + w + 8 * i) * ldn + n0 + ntile * 256 + lane * 4);
; __device__ __forceinline__ void phase_cvt(const float* __restrict__ src, int ld, int rows, int ncols, bf16_t* __restrict__ dst, const float* __restrict__ gain = nullptr) {
;   const size_t n8 = (size_t)rows * ncols / 8, gs = (size_t)gridDim.x * 512;
;   const int c8 = ncols / 8;
;   for (size_t i = (size_t)obid() * 512 + otid(); i < n8; i += gs) {
;     const size_t r = i / c8; const int c = (int)(i % c8) * 8;
;     const float* s = src + r * ld + c;
;     float4 v0 = *(const float4*)s, v1 = *(const float4*)(s + 4);
;     if (gain) { const float g = gain[r]; v0.x *= g; v0.y *= g; v0.z *= g; v0.w *= g; v1.x *= g; v1.y *= g; v1.z *= g; v1.w *= g; }
;     uint4 o; o.x = cvt_pk_bf16(v0.x, v0.y); o.y = cvt_pk_bf16(v0.z, v0.w); o.z = cvt_pk_bf16(v1.x, v1.y); o.w = cvt_pk_bf16(v1.z, v1.w);
;     *(uint4*)(dst + r * ncols + c) = o;
;   }
.LBB0_18:
	s_lshr_b32 s4, s0, 1
	s_bitcmp1_b32 s0, 0
	s_mov_b32 s22, s0
	s_cselect_b64 s[0:1], -1, 0
	v_writelane_b32 v255, s0, 26
	s_and_b64 vcc, exec, s[0:1]
	s_mov_b64 s[2:3], -1
	v_writelane_b32 v255, s1, 27
	s_cbranch_vccz .LBB0_53
	v_readlane_b32 s0, v255, 0
	v_readlane_b32 s1, v255, 1
	s_mov_b32 s5, s12
	s_mov_b64 s[8:9], 0x100000
	v_mov_b64_e32 v[0:1], s[0:1]
	global_load_dwordx2 v[2:3], v[0:1], off offset:72 sc0 sc1
	s_waitcnt vmcnt(0)
	global_load_dwordx2 v[4:5], v[0:1], off offset:120 sc0 sc1
	s_waitcnt vmcnt(0)
	global_load_dwordx2 v[6:7], v[0:1], off offset:32 sc0 sc1
	s_waitcnt vmcnt(0)
	v_mov_b32_e32 v0, s74
	ds_read_b32 v8, v0
	v_mov_b32_e32 v0, v252
	s_lshl_b32 s6, s22, 11
	v_ashrrev_i32_e32 v1, 31, v0
	s_waitcnt lgkmcnt(0)
	v_readfirstlane_b32 s46, v8
	s_ashr_i32 s47, s46, 31
	s_lshl_b64 s[0:1], s[46:47], 9
	v_lshl_add_u64 v[8:9], s[0:1], 0, v[0:1]
	s_mov_b32 s7, s12
	s_lshl_b64 s[2:3], s[4:5], 24
	v_cmp_gt_u64_e32 vcc, s[8:9], v[8:9]
	v_readfirstlane_b32 s1, v3
	v_readfirstlane_b32 s17, v2
	v_readfirstlane_b32 s0, v5
	v_readfirstlane_b32 s13, v4
	v_readfirstlane_b32 s45, v7
	v_readfirstlane_b32 s44, v6
	s_and_saveexec_b64 s[8:9], vcc
	s_cbranch_execz .LBB0_24
	s_lshl_b64 s[18:19], s[2:3], 2
	s_add_u32 s36, s17, s18
	s_addc_u32 s37, s1, s19
	s_add_u32 s38, s13, 0x6900000
	s_addc_u32 s39, s0, 0
	s_lshl_b64 s[0:1], s[6:7], 2
	s_add_u32 s40, s44, s0
	s_addc_u32 s41, s45, s1
	s_cmp_lg_u64 s[44:45], 0
	s_cselect_b64 s[44:45], -1, 0
	s_lshl_b64 s[0:1], s[46:47], 12
	s_mov_b64 s[42:43], 0
	v_lshl_add_u64 v[10:11], v[0:1], 3, s[0:1]
	s_branch .LBB0_22
.LBB0_21:
	s_waitcnt vmcnt(0) lgkmcnt(0)
	v_cvt_pk_bf16_f32 v4, v4, v5
	v_cvt_pk_bf16_f32 v5, v6, v7
	v_cvt_pk_bf16_f32 v6, v0, v1
	v_lshlrev_b64 v[0:1], 13, v[12:13]
	v_lshl_add_u64 v[8:9], v[8:9], 0, s[14:15]
	s_mov_b64 s[0:1], 0xfffff
	v_lshl_add_u64 v[0:1], s[38:39], 0, v[0:1]
	v_lshlrev_b32_e32 v80, 1, v14
	v_cmp_lt_u64_e32 vcc, s[0:1], v[8:9]
	v_lshl_add_u64 v[0:1], v[0:1], 0, v[80:81]
	s_or_b64 s[42:43], vcc, s[42:43]
	v_lshl_add_u64 v[10:11], v[10:11], 0, s[24:25]
	v_cvt_pk_bf16_f32 v7, v2, v3
	global_store_dwordx4 v[0:1], v[4:7], off
	s_andn2_b64 exec, exec, s[42:43]
	s_cbranch_execz .LBB0_24
.LBB0_22:
	v_lshrrev_b64 v[12:13], 9, v[8:9]
	v_and_b32_e32 v14, 0xff8, v10
	v_lshlrev_b64 v[0:1], 15, v[12:13]
	v_lshl_add_u64 v[0:1], s[36:37], 0, v[0:1]
	v_lshlrev_b32_e32 v80, 2, v14
	v_lshl_add_u64 v[0:1], v[0:1], 0, v[80:81]
	global_load_dwordx4 v[4:7], v[0:1], off
	s_nop 0
	global_load_dwordx4 v[0:3], v[0:1], off offset:16
	s_andn2_b64 vcc, exec, s[44:45]
	s_cbranch_vccnz .LBB0_21
	v_lshl_add_u64 v[16:17], v[12:13], 2, s[40:41]
	global_load_dword v16, v[16:17], off
	s_waitcnt vmcnt(0) lgkmcnt(0)
	v_pk_mul_f32 v[4:5], v[4:5], v[16:17] op_sel_hi:[1,0]
	v_pk_mul_f32 v[6:7], v[6:7], v[16:17] op_sel_hi:[1,0]
	v_pk_mul_f32 v[0:1], v[0:1], v[16:17] op_sel_hi:[1,0]
	v_pk_mul_f32 v[2:3], v[2:3], v[16:17] op_sel_hi:[1,0]
	s_branch .LBB0_21
.LBB0_24:
	s_or_b64 exec, exec, s[8:9]
	v_readlane_b32 s0, v255, 0
	v_readlane_b32 s1, v255, 1
	s_nop 1
	v_mov_b64_e32 v[0:1], s[0:1]
	global_load_dwordx2 v[2:3], v[0:1], off offset:72 sc0 sc1
	s_waitcnt vmcnt(0)
	global_load_dwordx2 v[4:5], v[0:1], off offset:120 sc0 sc1
	s_waitcnt vmcnt(0)
	global_load_dwordx2 v[6:7], v[0:1], off offset:32 sc0 sc1
	s_waitcnt vmcnt(0)
	v_mov_b32_e32 v0, v252
	v_mov_b32_e32 v1, s74
	ds_read_b32 v1, v1
	s_waitcnt lgkmcnt(0)
	v_readfirstlane_b32 s0, v1
	s_cmpk_gt_i32 s0, 0x1ff
	v_readfirstlane_b32 s1, v3
	v_readfirstlane_b32 s13, v2
	v_readfirstlane_b32 s39, v5
	v_readfirstlane_b32 s38, v4
	v_readfirstlane_b32 s19, v7
	v_readfirstlane_b32 s18, v6
	s_cbranch_scc1 .LBB0_29
	s_lshl_b64 s[8:9], s[6:7], 2
	s_add_u32 s8, s18, s8
	s_addc_u32 s9, s19, s9
	s_lshl_b64 s[28:29], s[2:3], 2
	s_add_u32 s28, s13, s28
	v_lshlrev_b32_e32 v4, 4, v0
	s_addc_u32 s29, s1, s29
	v_and_b32_e32 v80, 0x3f0, v4
	v_lshl_add_u64 v[2:3], s[28:29], 0, v[80:81]
	s_mov_b64 s[28:29], 0x4000
	v_ashrrev_i32_e32 v40, 3, v0
	v_ashrrev_i32_e32 v38, 6, v0
	v_lshl_add_u64 v[32:33], v[2:3], 0, s[28:29]
	v_and_b32_e32 v0, 7, v0
	v_lshlrev_b32_e32 v3, 2, v40
	v_lshlrev_b32_e32 v1, 13, v0
	v_and_b32_e32 v3, 12, v3
	v_lshlrev_b32_e32 v2, 2, v0
	v_add3_u32 v3, 0, v1, v3
	v_lshlrev_b32_e32 v0, 4, v0
	v_mov_b32_e32 v1, v81
	v_mov_b32_e32 v9, 0x3f0
	s_movk_i32 s13, 0x50
	s_cmp_lg_u64 s[18:19], 0
	v_lshl_add_u64 v[0:1], s[38:39], 0, v[0:1]
	s_mov_b64 s[18:19], 0x1100000
	s_mov_b32 s1, 0x3ffffffc
	v_bitop3_b32 v7, v4, s13, v9 bitop3:0x6c
	s_movk_i32 s13, 0x60
	v_lshl_add_u64 v[34:35], v[0:1], 0, s[18:19]
	v_bitop3_b32 v0, v40, v2, s1 bitop3:0x6c
	v_bitop3_b32 v8, v4, s13, v9 bitop3:0x6c
	s_movk_i32 s13, 0x70
	v_add_u32_e32 v42, 64, v40
	v_lshl_add_u32 v41, v0, 2, v3
	v_bitop3_b32 v0, v4, 16, v9 bitop3:0x6c
	v_bitop3_b32 v1, v4, 32, v9 bitop3:0x6c
	v_bitop3_b32 v5, v4, 48, v9 bitop3:0x6c
	v_bitop3_b32 v6, v4, 64, v9 bitop3:0x6c
	v_bitop3_b32 v4, v4, s13, v9 bitop3:0x6c
	v_bitop3_b32 v9, v42, v2, s1 bitop3:0x6c
	v_add_u32_e32 v44, 0x80, v40
	v_add_u32_e32 v46, 0xc0, v40
	v_lshl_add_u32 v39, v38, 10, 0
	v_lshl_add_u32 v43, v9, 2, v3
	v_bitop3_b32 v9, v44, v2, s1 bitop3:0x6c
	v_bitop3_b32 v2, v46, v2, s1 bitop3:0x6c
	s_cselect_b64 s[36:37], -1, 0
	v_lshl_add_u32 v45, v9, 2, v3
	v_lshl_add_u32 v47, v2, 2, v3
	s_lshl_b32 s1, s0, 6
	s_lshl_b32 s13, s20, 6
	v_add_u32_e32 v48, v39, v0
	v_add_u32_e32 v49, v39, v1
	v_add_u32_e32 v50, v39, v5
	v_add_u32_e32 v51, v39, v6
	v_add_u32_e32 v52, v39, v7
	v_add_u32_e32 v53, v39, v8
	v_add_u32_e32 v54, v39, v4
	s_branch .LBB0_27
; #define LAS __attribute__((address_space(3)))
; __device__ __forceinline__ unsigned cvt_pk_bf16(float lo, float hi) { unsigned r; asm("v_cvt_pk_bf16_f32 %0, %1, %2" : "=v"(r) : "v"(lo), "v"(hi)); return r; }
; __device__ __forceinline__ int otid() { int t = threadIdx.x; asm volatile("" : "+v"(t)); return t; }
; __device__ __forceinline__ int obid() { extern __shared__ __attribute__((aligned(16))) unsigned char shm_vb[]; return __builtin_amdgcn_readfirstlane(*(volatile LAS int*)((LAS unsigned char*)shm_vb + VB_OFF)); }
; __device__ __forceinline__ void phase_wT(const float* __restrict__ src, int ldn, int n0, int K, int N, bf16_t* __restrict__ dst, LAS float* tile, const float* __restrict__ gain = nullptr) {
;   const int tk = K / 64, tn = N / 256, nt = tk * tn, t = otid(), w = t >> 6, lane = t & 63;
;   for (int ti = obid(); ti < nt; ti += gridDim.x) {
;     const int kt = ti % tk, ntile = ti / tk;
;     float4 v[8];
; #pragma unroll
;     for (int i = 0; i < 8; ++i) v[i] = *(const float4*)(src + (size_t)(kt * 64 + w + 8 * i) * ldn + n0 + ntile * 256 + lane * 4);
;     if (gain) {
; #pragma unroll
;       for (int i = 0; i < 8; ++i) { const float gk = gain[kt * 64 + w + 8 * i]; v[i].x *= gk; v[i].y *= gk; v[i].z *= gk; v[i].w *= gk; }
;     }
; #pragma unroll
;     for (int i = 0; i < 8; ++i) { const int k = w + 8 * i; *(LAS f32x4*)(tile + k * 256 + ((lane ^ (i & 7)) << 2)) = (f32x4){v[i].x, v[i].y, v[i].z, v[i].w}; }
;     __syncthreads();
;     const int nr = t >> 3, kc = (t & 7) * 8, ksw = (t & 7);
; #pragma unroll
;     for (int p = 0; p < 4; ++p) {
;       const int n = p * 64 + nr;
;       const LAS float* sp = tile + kc * 256 + ((((n >> 2) ^ ksw)) << 2) + (n & 3);
;       uint4 o; o.x = cvt_pk_bf16(sp[0], sp[256]); o.y = cvt_pk_bf16(sp[512], sp[768]); o.z = cvt_pk_bf16(sp[1024], sp[1280]); o.w = cvt_pk_bf16(sp[1536], sp[1792]);
;       *(uint4*)(dst + (size_t)(ntile * 256 + n) * K + kt * 64 + kc) = o;
;     }
;     __syncthreads();
;   }
; }
.LBB0_26:
	v_add_u32_e32 v36, v39, v80
	s_waitcnt vmcnt(0) lgkmcnt(0)
	ds_write_b128 v36, v[4:7]
	ds_write_b128 v48, v[0:3] offset:8192
	ds_write_b128 v49, v[12:15] offset:16384
	ds_write_b128 v50, v[8:11] offset:24576
	ds_write_b128 v51, v[20:23] offset:32768
	ds_write_b128 v52, v[16:19] offset:40960
	ds_write_b128 v53, v[28:31] offset:49152
	ds_write_b128 v54, v[24:27] offset:57344
	s_waitcnt lgkmcnt(0)
	s_barrier
	ds_read2st64_b32 v[0:1], v41 offset1:4
	ds_read2st64_b32 v[2:3], v41 offset0:8 offset1:12
	ds_read2st64_b32 v[4:5], v41 offset0:16 offset1:20
	ds_read2st64_b32 v[6:7], v41 offset0:24 offset1:28
	s_sub_i32 s17, 0, s17
	s_add_i32 s18, s1, s17
	s_waitcnt lgkmcnt(3)
	v_cvt_pk_bf16_f32 v0, v0, v1
	s_waitcnt lgkmcnt(2)
	v_cvt_pk_bf16_f32 v1, v2, v3
	s_waitcnt lgkmcnt(1)
	v_cvt_pk_bf16_f32 v2, v4, v5
	v_add_u32_e32 v4, s38, v40
	s_ashr_i32 s19, s18, 31
	s_waitcnt lgkmcnt(0)
	v_cvt_pk_bf16_f32 v3, v6, v7
	v_ashrrev_i32_e32 v5, 31, v4
	ds_read2st64_b32 v[6:7], v43 offset1:4
	ds_read2st64_b32 v[10:11], v43 offset0:8 offset1:12
	ds_read2st64_b32 v[12:13], v43 offset0:16 offset1:20
	ds_read2st64_b32 v[14:15], v43 offset0:24 offset1:28
	v_lshl_add_u64 v[8:9], s[18:19], 1, v[34:35]
	v_lshlrev_b64 v[4:5], 12, v[4:5]
	v_lshl_add_u64 v[4:5], v[8:9], 0, v[4:5]
	global_store_dwordx4 v[4:5], v[0:3], off
	v_add_u32_e32 v4, s38, v42
	v_ashrrev_i32_e32 v5, 31, v4
	s_waitcnt lgkmcnt(0)
	v_cvt_pk_bf16_f32 v0, v6, v7
	v_cvt_pk_bf16_f32 v1, v10, v11
	v_cvt_pk_bf16_f32 v2, v12, v13
	v_cvt_pk_bf16_f32 v3, v14, v15
	v_lshlrev_b64 v[4:5], 12, v[4:5]
	ds_read2st64_b32 v[6:7], v45 offset1:4
	ds_read2st64_b32 v[10:11], v45 offset0:8 offset1:12
	ds_read2st64_b32 v[12:13], v45 offset0:16 offset1:20
	ds_read2st64_b32 v[14:15], v45 offset0:24 offset1:28
	v_lshl_add_u64 v[4:5], v[8:9], 0, v[4:5]
	global_store_dwordx4 v[4:5], v[0:3], off
	v_add_u32_e32 v4, s38, v44
	v_ashrrev_i32_e32 v5, 31, v4
	v_lshlrev_b64 v[4:5], 12, v[4:5]
	s_waitcnt lgkmcnt(0)
	v_cvt_pk_bf16_f32 v0, v6, v7
	v_cvt_pk_bf16_f32 v1, v10, v11
	v_cvt_pk_bf16_f32 v2, v12, v13
	v_cvt_pk_bf16_f32 v3, v14, v15
	v_lshl_add_u64 v[4:5], v[8:9], 0, v[4:5]
	ds_read2st64_b32 v[6:7], v47 offset1:4
	ds_read2st64_b32 v[10:11], v47 offset0:8 offset1:12
	ds_read2st64_b32 v[12:13], v47 offset0:16 offset1:20
	ds_read2st64_b32 v[14:15], v47 offset0:24 offset1:28
	global_store_dwordx4 v[4:5], v[0:3], off
	v_add_u32_e32 v4, s38, v46
	v_ashrrev_i32_e32 v5, 31, v4
	v_lshlrev_b64 v[4:5], 12, v[4:5]
	s_add_i32 s0, s0, s20
	s_add_i32 s1, s1, s13
	v_lshl_add_u64 v[4:5], v[8:9], 0, v[4:5]
	s_cmpk_lt_i32 s0, 0x200
	s_waitcnt lgkmcnt(0)
	v_cvt_pk_bf16_f32 v0, v6, v7
	v_cvt_pk_bf16_f32 v1, v10, v11
	v_cvt_pk_bf16_f32 v2, v12, v13
	v_cvt_pk_bf16_f32 v3, v14, v15
	global_store_dwordx4 v[4:5], v[0:3], off
	s_waitcnt lgkmcnt(0)
	s_barrier
	s_cbranch_scc0 .LBB0_29
.LBB0_27:
	s_ashr_i32 s17, s0, 31
	s_lshr_b32 s17, s17, 27
	s_add_i32 s17, s0, s17
	s_ashr_i32 s18, s17, 5
	s_lshl_b32 s17, s18, 11
	s_sub_i32 s19, s1, s17
	v_add_u32_e32 v36, s19, v38
	s_lshl_b32 s38, s18, 8
	v_add_u32_e32 v2, 8, v36
	v_add_u32_e32 v8, 16, v36
	v_add_u32_e32 v10, 24, v36
	v_add_u32_e32 v16, 32, v36
	v_add_u32_e32 v18, 40, v36
	v_add_u32_e32 v26, 48, v36
	v_add_u32_e32 v28, 56, v36
	s_ashr_i32 s39, s38, 31
	v_ashrrev_i32_e32 v37, 31, v36
	v_ashrrev_i32_e32 v3, 31, v2
	v_ashrrev_i32_e32 v9, 31, v8
	v_ashrrev_i32_e32 v11, 31, v10
	v_ashrrev_i32_e32 v17, 31, v16
	v_ashrrev_i32_e32 v19, 31, v18
	v_ashrrev_i32_e32 v27, 31, v26
	v_ashrrev_i32_e32 v29, 31, v28
	v_lshl_add_u64 v[24:25], s[38:39], 2, v[32:33]
	v_lshlrev_b64 v[0:1], 15, v[36:37]
	v_lshlrev_b64 v[2:3], 15, v[2:3]
	v_lshlrev_b64 v[8:9], 15, v[8:9]
	v_lshlrev_b64 v[10:11], 15, v[10:11]
	v_lshlrev_b64 v[16:17], 15, v[16:17]
	v_lshlrev_b64 v[18:19], 15, v[18:19]
	v_lshlrev_b64 v[26:27], 15, v[26:27]
	v_lshlrev_b64 v[28:29], 15, v[28:29]
	v_lshl_add_u64 v[0:1], v[24:25], 0, v[0:1]
	v_lshl_add_u64 v[2:3], v[24:25], 0, v[2:3]
	v_lshl_add_u64 v[8:9], v[24:25], 0, v[8:9]
	v_lshl_add_u64 v[10:11], v[24:25], 0, v[10:11]
	v_lshl_add_u64 v[16:17], v[24:25], 0, v[16:17]
	v_lshl_add_u64 v[18:19], v[24:25], 0, v[18:19]
	v_lshl_add_u64 v[26:27], v[24:25], 0, v[26:27]
	v_lshl_add_u64 v[24:25], v[24:25], 0, v[28:29]
	global_load_dwordx4 v[4:7], v[0:1], off
	s_nop 0
	global_load_dwordx4 v[0:3], v[2:3], off
	s_nop 0
	global_load_dwordx4 v[12:15], v[8:9], off
	s_nop 0
	global_load_dwordx4 v[8:11], v[10:11], off
	s_nop 0
	global_load_dwordx4 v[20:23], v[16:17], off
	s_nop 0
	global_load_dwordx4 v[16:19], v[18:19], off
	s_nop 0
	global_load_dwordx4 v[28:31], v[26:27], off
	s_nop 0
	global_load_dwordx4 v[24:27], v[24:25], off
	s_andn2_b64 vcc, exec, s[36:37]
	s_cbranch_vccnz .LBB0_26
	v_lshl_add_u64 v[36:37], v[36:37], 2, s[8:9]
	global_load_dword v56, v[36:37], off
	global_load_dword v58, v[36:37], off offset:32
	global_load_dword v60, v[36:37], off offset:64
	global_load_dword v62, v[36:37], off offset:96
	global_load_dword v64, v[36:37], off offset:128
	global_load_dword v66, v[36:37], off offset:160
	global_load_dword v68, v[36:37], off offset:192
	s_nop 0
	global_load_dword v36, v[36:37], off offset:224
	s_waitcnt vmcnt(0) lgkmcnt(0)
	v_pk_mul_f32 v[4:5], v[4:5], v[56:57] op_sel_hi:[1,0]
	v_pk_mul_f32 v[6:7], v[6:7], v[56:57] op_sel_hi:[1,0]
	v_pk_mul_f32 v[0:1], v[0:1], v[58:59] op_sel_hi:[1,0]
	v_pk_mul_f32 v[2:3], v[2:3], v[58:59] op_sel_hi:[1,0]
	v_pk_mul_f32 v[12:13], v[12:13], v[60:61] op_sel_hi:[1,0]
	v_pk_mul_f32 v[14:15], v[14:15], v[60:61] op_sel_hi:[1,0]
	v_pk_mul_f32 v[8:9], v[8:9], v[62:63] op_sel_hi:[1,0]
	v_pk_mul_f32 v[10:11], v[10:11], v[62:63] op_sel_hi:[1,0]
	v_pk_mul_f32 v[20:21], v[20:21], v[64:65] op_sel_hi:[1,0]
	v_pk_mul_f32 v[22:23], v[22:23], v[64:65] op_sel_hi:[1,0]
	v_pk_mul_f32 v[16:17], v[16:17], v[66:67] op_sel_hi:[1,0]
	v_pk_mul_f32 v[18:19], v[18:19], v[66:67] op_sel_hi:[1,0]
	v_pk_mul_f32 v[28:29], v[28:29], v[68:69] op_sel_hi:[1,0]
	v_pk_mul_f32 v[30:31], v[30:31], v[68:69] op_sel_hi:[1,0]
	v_pk_mul_f32 v[24:25], v[24:25], v[36:37] op_sel_hi:[1,0]
	v_pk_mul_f32 v[26:27], v[26:27], v[36:37] op_sel_hi:[1,0]
	s_branch .LBB0_26
; #define LAS __attribute__((address_space(3)))
; __device__ __forceinline__ int otid() { int t = threadIdx.x; asm volatile("" : "+v"(t)); return t; }
; __device__ __forceinline__ int obid() { extern __shared__ __attribute__((aligned(16))) unsigned char shm_vb[]; return __builtin_amdgcn_readfirstlane(*(volatile LAS int*)((LAS unsigned char*)shm_vb + VB_OFF)); }
; #define IN(i) ((const float*)karg(i))
; #define WSB(off) ((bf16_t*)((unsigned char*)karg(15) + (off)))
; __device__ __forceinline__ void phase_wT(const float* __restrict__ src, int ldn, int n0, int K, int N, bf16_t* __restrict__ dst, LAS float* tile, const float* __restrict__ gain = nullptr) {
;   const int tk = K / 64, tn = N / 256, nt = tk * tn, t = otid(), w = t >> 6, lane = t & 63;
;   for (int ti = obid(); ti < nt; ti += gridDim.x) {
;     const int kt = ti % tk, ntile = ti / tk;
;     float4 v[8];
; #pragma unroll
;     for (int i = 0; i < 8; ++i) v[i] = *(const float4*)(src + (size_t)(kt * 64 + w + 8 * i) * ldn + n0 + ntile * 256 + lane * 4);
; __global__ void __launch_bounds__(512, 2) mega(Params p) {
;     ...
;       phase_wT(IN(10) + (size_t)j * 4096 * 2048, 2048, 0, 4096, 2048, WSB(WS_WB), tile);
.LBB0_29:
	v_readlane_b32 s0, v255, 0
	v_readlane_b32 s1, v255, 1
	v_mov_b32_e32 v2, v252
	v_mov_b32_e32 v3, s74
	v_mov_b64_e32 v[0:1], s[0:1]
	global_load_dwordx2 v[4:5], v[0:1], off offset:80 sc0 sc1
	s_waitcnt vmcnt(0)
	global_load_dwordx2 v[0:1], v[0:1], off offset:120 sc0 sc1
	s_waitcnt vmcnt(0)
	ds_read_b32 v3, v3
	s_waitcnt lgkmcnt(0)
	v_readfirstlane_b32 s0, v3
	s_cmpk_gt_i32 s0, 0x1ff
	v_readfirstlane_b32 s1, v5
	v_readfirstlane_b32 s13, v4
	v_readfirstlane_b32 s9, v1
	v_readfirstlane_b32 s8, v0
	s_cbranch_scc1 .LBB0_32
	s_lshl_b64 s[18:19], s[4:5], 25
	v_lshlrev_b32_e32 v8, 4, v2
	v_ashrrev_i32_e32 v6, 3, v2
	v_mov_b32_e32 v9, 0x3f0
	s_movk_i32 s5, 0x50
	v_ashrrev_i32_e32 v4, 6, v2
	v_and_b32_e32 v2, 7, v2
	v_lshlrev_b32_e32 v7, 2, v6
	v_bitop3_b32 v19, v8, s5, v9 bitop3:0x6c
	s_movk_i32 s5, 0x60
	s_add_u32 s18, s13, s18
	v_lshlrev_b32_e32 v3, 13, v2
	v_and_b32_e32 v7, 12, v7
	v_bitop3_b32 v20, v8, s5, v9 bitop3:0x6c
	s_movk_i32 s5, 0x70
	s_addc_u32 s19, s1, s19
	v_and_b32_e32 v80, 0x3f0, v8
	v_lshlrev_b32_e32 v13, 2, v2
	v_add3_u32 v14, 0, v3, v7
	v_lshlrev_b32_e32 v2, 4, v2
	v_mov_b32_e32 v3, v81
	s_mov_b32 s1, 0x3ffffffc
	v_bitop3_b32 v15, v8, 16, v9 bitop3:0x6c
	v_bitop3_b32 v16, v8, 32, v9 bitop3:0x6c
	v_bitop3_b32 v17, v8, 48, v9 bitop3:0x6c
	v_bitop3_b32 v18, v8, 64, v9 bitop3:0x6c
	v_bitop3_b32 v21, v8, s5, v9 bitop3:0x6c
	v_add_u32_e32 v8, 64, v6
	v_add_u32_e32 v10, 0x80, v6
	v_add_u32_e32 v12, 0xc0, v6
	v_lshl_add_u32 v5, v4, 10, 0
	v_lshl_add_u64 v[2:3], s[8:9], 0, v[2:3]
	s_mov_b64 s[8:9], 0x5000000
	v_bitop3_b32 v7, v6, v13, s1 bitop3:0x6c
	v_bitop3_b32 v9, v8, v13, s1 bitop3:0x6c
	v_bitop3_b32 v11, v10, v13, s1 bitop3:0x6c
	v_bitop3_b32 v13, v12, v13, s1 bitop3:0x6c
	v_lshl_add_u64 v[0:1], s[18:19], 0, v[80:81]
	v_lshl_add_u64 v[2:3], v[2:3], 0, s[8:9]
	v_lshl_add_u32 v7, v7, 2, v14
	v_lshl_add_u32 v9, v9, 2, v14
	v_lshl_add_u32 v11, v11, 2, v14
	v_lshl_add_u32 v13, v13, 2, v14
	s_lshl_b32 s1, s0, 6
	s_lshl_b32 s5, s20, 6
	v_add_u32_e32 v14, v5, v15
	v_add_u32_e32 v15, v5, v16
	v_add_u32_e32 v16, v5, v17
	v_add_u32_e32 v17, v5, v18
	v_add_u32_e32 v18, v5, v19
	v_add_u32_e32 v19, v5, v20
	v_add_u32_e32 v20, v5, v21
; #define LAS __attribute__((address_space(3)))
; __device__ __forceinline__ unsigned cvt_pk_bf16(float lo, float hi) { unsigned r; asm("v_cvt_pk_bf16_f32 %0, %1, %2" : "=v"(r) : "v"(lo), "v"(hi)); return r; }
; __device__ __forceinline__ int otid() { int t = threadIdx.x; asm volatile("" : "+v"(t)); return t; }
; __device__ __forceinline__ int obid() { extern __shared__ __attribute__((aligned(16))) unsigned char shm_vb[]; return __builtin_amdgcn_readfirstlane(*(volatile LAS int*)((LAS unsigned char*)shm_vb + VB_OFF)); }
; __device__ __forceinline__ void phase_wT(const float* __restrict__ src, int ldn, int n0, int K, int N, bf16_t* __restrict__ dst, LAS float* tile, const float* __restrict__ gain = nullptr) {
;   const int tk = K / 64, tn = N / 256, nt = tk * tn, t = otid(), w = t >> 6, lane = t & 63;
;   for (int ti = obid(); ti < nt; ti += gridDim.x) {
;     const int kt = ti % tk, ntile = ti / tk;
;     float4 v[8];
; #pragma unroll
;     for (int i = 0; i < 8; ++i) v[i] = *(const float4*)(src + (size_t)(kt * 64 + w + 8 * i) * ldn + n0 + ntile * 256 + lane * 4);
;     if (gain) {
; #pragma unroll
;       for (int i = 0; i < 8; ++i) { const float gk = gain[kt * 64 + w + 8 * i]; v[i].x *= gk; v[i].y *= gk; v[i].z *= gk; v[i].w *= gk; }
;     }
; #pragma unroll
;     for (int i = 0; i < 8; ++i) { const int k = w + 8 * i; *(LAS f32x4*)(tile + k * 256 + ((lane ^ (i & 7)) << 2)) = (f32x4){v[i].x, v[i].y, v[i].z, v[i].w}; }
;     __syncthreads();
;     const int nr = t >> 3, kc = (t & 7) * 8, ksw = (t & 7);
; #pragma unroll
;     for (int p = 0; p < 4; ++p) {
;       const int n = p * 64 + nr;
;       const LAS float* sp = tile + kc * 256 + ((((n >> 2) ^ ksw)) << 2) + (n & 3);
;       uint4 o; o.x = cvt_pk_bf16(sp[0], sp[256]); o.y = cvt_pk_bf16(sp[512], sp[768]); o.z = cvt_pk_bf16(sp[1024], sp[1280]); o.w = cvt_pk_bf16(sp[1536], sp[1792]);
;       *(uint4*)(dst + (size_t)(ntile * 256 + n) * K + kt * 64 + kc) = o;
;     }
;     __syncthreads();
;   }
; }
; __device__ __forceinline__ void phase_tmgen(bf16_t* __restrict__ tm) {
;   for (int i = obid() * 512 + otid(); i < 65536; i += gridDim.x * 512) {
;     const int r = i >> 8, m = i & 255, l = r & 127;
;     const float a = (float)((l * m) & 255) * (1.f / 128.f);
;     const float v = (r < 128 ? cospif(a) : sinpif(a)) * 0.0625f;
;     tm[i] = (bf16_t)(cvt_pk_bf16(v, 0.f) & 0xffffu);
;   }
.LBB0_31:
	s_ashr_i32 s8, s0, 31
	s_lshr_b32 s8, s8, 26
	s_add_i32 s8, s0, s8
	s_ashr_i32 s8, s8, 6
	s_lshl_b32 s9, s8, 12
	s_lshl_b32 s36, s8, 8
	s_sub_i32 s8, s1, s9
	v_add_u32_e32 v22, s8, v4
	v_add_u32_e32 v26, 8, v22
	v_add_u32_e32 v28, 16, v22
	v_add_u32_e32 v30, 24, v22
	v_add_u32_e32 v32, 32, v22
	v_add_u32_e32 v34, 40, v22
	v_add_u32_e32 v36, 48, v22
	v_add_u32_e32 v38, 56, v22
	s_ashr_i32 s37, s36, 31
	v_ashrrev_i32_e32 v23, 31, v22
	v_ashrrev_i32_e32 v27, 31, v26
	v_ashrrev_i32_e32 v29, 31, v28
	v_ashrrev_i32_e32 v31, 31, v30
	v_ashrrev_i32_e32 v33, 31, v32
	v_ashrrev_i32_e32 v35, 31, v34
	v_ashrrev_i32_e32 v37, 31, v36
	v_ashrrev_i32_e32 v39, 31, v38
	v_lshl_add_u64 v[24:25], s[36:37], 2, v[0:1]
	v_lshlrev_b64 v[22:23], 13, v[22:23]
	v_lshlrev_b64 v[26:27], 13, v[26:27]
	v_lshlrev_b64 v[28:29], 13, v[28:29]
	v_lshlrev_b64 v[30:31], 13, v[30:31]
	v_lshlrev_b64 v[32:33], 13, v[32:33]
	v_lshlrev_b64 v[34:35], 13, v[34:35]
	v_lshlrev_b64 v[36:37], 13, v[36:37]
	v_lshlrev_b64 v[38:39], 13, v[38:39]
	v_lshl_add_u64 v[22:23], v[24:25], 0, v[22:23]
	v_lshl_add_u64 v[26:27], v[24:25], 0, v[26:27]
	v_lshl_add_u64 v[40:41], v[24:25], 0, v[28:29]
	v_lshl_add_u64 v[42:43], v[24:25], 0, v[30:31]
	v_lshl_add_u64 v[44:45], v[24:25], 0, v[32:33]
	v_lshl_add_u64 v[46:47], v[24:25], 0, v[34:35]
	v_lshl_add_u64 v[48:49], v[24:25], 0, v[36:37]
	v_lshl_add_u64 v[50:51], v[24:25], 0, v[38:39]
	global_load_dwordx4 v[22:25], v[22:23], off
	s_nop 0
	global_load_dwordx4 v[26:29], v[26:27], off
	s_nop 0
	global_load_dwordx4 v[30:33], v[40:41], off
	global_load_dwordx4 v[34:37], v[42:43], off
	s_nop 0
	global_load_dwordx4 v[38:41], v[44:45], off
	s_nop 0
	global_load_dwordx4 v[42:45], v[46:47], off
	s_nop 0
	global_load_dwordx4 v[46:49], v[48:49], off
	s_nop 0
	global_load_dwordx4 v[50:53], v[50:51], off
	v_add_u32_e32 v21, v5, v80
	v_add_u32_e32 v54, s36, v6
	v_add_u32_e32 v56, s36, v8
	v_add_u32_e32 v58, s36, v10
	v_add_u32_e32 v60, s36, v12
	s_ashr_i32 s9, s8, 31
	v_ashrrev_i32_e32 v55, 31, v54
	s_add_i32 s0, s0, s20
	s_add_i32 s1, s1, s5
	v_ashrrev_i32_e32 v57, 31, v56
	v_ashrrev_i32_e32 v59, 31, v58
	v_ashrrev_i32_e32 v61, 31, v60
	v_lshl_add_u64 v[62:63], s[8:9], 1, v[2:3]
	v_lshlrev_b64 v[54:55], 13, v[54:55]
	v_lshlrev_b64 v[56:57], 13, v[56:57]
	v_lshlrev_b64 v[58:59], 13, v[58:59]
	v_lshlrev_b64 v[60:61], 13, v[60:61]
	s_cmpk_lt_i32 s0, 0x200
	v_lshl_add_u64 v[54:55], v[62:63], 0, v[54:55]
	v_lshl_add_u64 v[56:57], v[62:63], 0, v[56:57]
	v_lshl_add_u64 v[58:59], v[62:63], 0, v[58:59]
	v_lshl_add_u64 v[60:61], v[62:63], 0, v[60:61]
	s_waitcnt vmcnt(0) lgkmcnt(0)
	ds_write_b128 v21, v[22:25]
	ds_write_b128 v14, v[26:29] offset:8192
	ds_write_b128 v15, v[30:33] offset:16384
	ds_write_b128 v16, v[34:37] offset:24576
	ds_write_b128 v17, v[38:41] offset:32768
	ds_write_b128 v18, v[42:45] offset:40960
	ds_write_b128 v19, v[46:49] offset:49152
	ds_write_b128 v20, v[50:53] offset:57344
	s_waitcnt lgkmcnt(0)
	s_barrier
	ds_read2st64_b32 v[22:23], v7 offset1:4
	ds_read2st64_b32 v[24:25], v7 offset0:8 offset1:12
	ds_read2st64_b32 v[26:27], v7 offset0:16 offset1:20
	ds_read2st64_b32 v[28:29], v7 offset0:24 offset1:28
	ds_read2st64_b32 v[30:31], v9 offset1:4
	ds_read2st64_b32 v[32:33], v9 offset0:8 offset1:12
	ds_read2st64_b32 v[34:35], v9 offset0:16 offset1:20
	ds_read2st64_b32 v[36:37], v9 offset0:24 offset1:28
	ds_read2st64_b32 v[38:39], v11 offset1:4
	ds_read2st64_b32 v[40:41], v11 offset0:8 offset1:12
	ds_read2st64_b32 v[42:43], v11 offset0:16 offset1:20
	ds_read2st64_b32 v[44:45], v11 offset0:24 offset1:28
	ds_read2st64_b32 v[46:47], v13 offset1:4
	ds_read2st64_b32 v[48:49], v13 offset0:8 offset1:12
	ds_read2st64_b32 v[50:51], v13 offset0:16 offset1:20
	ds_read2st64_b32 v[52:53], v13 offset0:24 offset1:28
	s_waitcnt lgkmcnt(14)
	v_cvt_pk_bf16_f32 v22, v22, v23
	v_cvt_pk_bf16_f32 v23, v24, v25
	s_waitcnt lgkmcnt(13)
	v_cvt_pk_bf16_f32 v24, v26, v27
	s_waitcnt lgkmcnt(12)
	v_cvt_pk_bf16_f32 v25, v28, v29
	s_waitcnt lgkmcnt(11)
	v_cvt_pk_bf16_f32 v26, v30, v31
	s_waitcnt lgkmcnt(10)
	v_cvt_pk_bf16_f32 v27, v32, v33
	s_waitcnt lgkmcnt(9)
	v_cvt_pk_bf16_f32 v28, v34, v35
	s_waitcnt lgkmcnt(8)
	v_cvt_pk_bf16_f32 v29, v36, v37
	s_waitcnt lgkmcnt(7)
	v_cvt_pk_bf16_f32 v30, v38, v39
	s_waitcnt lgkmcnt(6)
	v_cvt_pk_bf16_f32 v31, v40, v41
	s_waitcnt lgkmcnt(5)
	v_cvt_pk_bf16_f32 v32, v42, v43
	s_waitcnt lgkmcnt(4)
	v_cvt_pk_bf16_f32 v33, v44, v45
	s_waitcnt lgkmcnt(3)
	v_cvt_pk_bf16_f32 v34, v46, v47
	s_waitcnt lgkmcnt(2)
	v_cvt_pk_bf16_f32 v35, v48, v49
	s_waitcnt lgkmcnt(1)
	v_cvt_pk_bf16_f32 v36, v50, v51
	s_waitcnt lgkmcnt(0)
	v_cvt_pk_bf16_f32 v37, v52, v53
	global_store_dwordx4 v[54:55], v[22:25], off
	global_store_dwordx4 v[56:57], v[26:29], off
	global_store_dwordx4 v[58:59], v[30:33], off
	global_store_dwordx4 v[60:61], v[34:37], off
	s_waitcnt lgkmcnt(0)
	s_barrier
	s_cbranch_scc1 .LBB0_31
.LBB0_32:
	v_mov_b64_e32 v[0:1], s[10:11]
	global_load_dwordx2 v[2:3], v[0:1], off sc0 sc1
	s_waitcnt vmcnt(0)
	v_mov_b32_e32 v0, s74
	ds_read_b32 v0, v0
	v_mov_b32_e32 v1, v252
	s_mov_b32 s5, 0x10000
	s_waitcnt lgkmcnt(0)
	v_readfirstlane_b32 s0, v0
	v_readfirstlane_b32 s1, v2
	s_nop 0
	v_lshl_add_u32 v0, s0, 9, v1
	v_readfirstlane_b32 s0, v3
	v_cmp_gt_i32_e32 vcc, s5, v0
	s_and_saveexec_b64 s[8:9], vcc
	s_cbranch_execz .LBB0_39
	s_add_u32 s36, s1, 0x7900000
	s_addc_u32 s37, s0, 0
	s_mov_b64 s[38:39], 0
	s_branch .LBB0_35
.LBB0_34:
	s_or_b64 exec, exec, s[18:19]
	v_mul_f32_e32 v2, 0x3d800000, v7
	v_cmp_lg_f32_e32 vcc, s86, v1
	s_mov_b32 s0, 0xffff
	s_nop 0
	v_cndmask_b32_e32 v1, v222, v2, vcc
	v_cvt_pk_bf16_f32 v4, v1, v81
	v_ashrrev_i32_e32 v1, 31, v0
	v_lshl_add_u64 v[2:3], v[0:1], 1, s[36:37]
	v_add_u32_e32 v0, s33, v0
	v_cmp_lt_i32_e32 vcc, s0, v0
	s_or_b64 s[38:39], vcc, s[38:39]
	global_store_short v[2:3], v4, off
	s_andn2_b64 exec, exec, s[38:39]
	s_cbranch_execz .LBB0_39

; __device__ __forceinline__ int otid() { int t = threadIdx.x; asm volatile("" : "+v"(t)); return t; }
; __device__ __forceinline__ int obid() { extern __shared__ __attribute__((aligned(16))) unsigned char shm_vb[]; return __builtin_amdgcn_readfirstlane(*(volatile LAS int*)((LAS unsigned char*)shm_vb + VB_OFF)); }
; __device__ __forceinline__ float wave_sum(float v) {
; #pragma unroll
;   for (int o = 32; o >= 1; o >>= 1) v += __shfl_xor(v, o);
;   return v;
; }
; __device__ __forceinline__ void phase_a128(const float* __restrict__ w, bf16_t* __restrict__ pk, const float* __restrict__ gain) {
;   const int tid = otid(), lane = tid & 63, nw = gridDim.x * 8;
;   for (int i = obid() * 8 + (tid >> 6); i < 16 * 2048; i += nw) {
;     const int g = i >> 11, d = i & 2047;
;     const float4 v = *(const float4*)(w + (size_t)d * 8192 + g * 256 + lane * 4);
;     const float s = wave_sum(v.x - v.y + v.z - v.w) * 0.0625f * gain[d];
.LBB0_39:
	s_or_b64 exec, exec, s[8:9]
	v_readlane_b32 s0, v255, 0
	v_readlane_b32 s1, v255, 1
	v_mov_b32_e32 v4, v252
	v_mov_b32_e32 v5, s74
	v_mov_b64_e32 v[0:1], s[0:1]
	global_load_dwordx2 v[2:3], v[0:1], off offset:72 sc0 sc1
	s_waitcnt vmcnt(0)
	global_load_dwordx2 v[6:7], v[0:1], off offset:120 sc0 sc1
	s_waitcnt vmcnt(0)
	global_load_dwordx2 v[0:1], v[0:1], off offset:32 sc0 sc1
	s_waitcnt vmcnt(0)
	ds_read_b32 v5, v5
	v_ashrrev_i32_e32 v8, 6, v4
	s_mov_b32 s17, 0x8000
	s_waitcnt lgkmcnt(0)
	v_readfirstlane_b32 s0, v5
	s_nop 1
	v_lshl_add_u32 v5, s0, 3, v8
	v_cmp_gt_i32_e32 vcc, s17, v5
	v_readfirstlane_b32 s1, v3
	v_readfirstlane_b32 s13, v2
	v_readfirstlane_b32 s9, v7
	v_readfirstlane_b32 s8, v6
	v_readfirstlane_b32 s0, v1
	v_readfirstlane_b32 s5, v0
	s_and_saveexec_b64 s[36:37], vcc
	s_cbranch_execz .LBB0_44
	v_and_b32_e32 v2, 64, v189
	v_add_u32_e32 v2, 64, v2
	v_xor_b32_e32 v3, 32, v189
	v_cmp_lt_i32_e32 vcc, v3, v2
	s_lshl_b64 s[2:3], s[2:3], 2
	s_add_u32 s38, s13, s2
	v_cndmask_b32_e32 v3, v189, v3, vcc
	v_lshlrev_b32_e32 v6, 2, v3
	v_xor_b32_e32 v3, 16, v189
	v_cmp_lt_i32_e32 vcc, v3, v2
	s_addc_u32 s39, s1, s3
	s_lshl_b64 s[2:3], s[6:7], 2
	v_cndmask_b32_e32 v3, v189, v3, vcc
	v_lshlrev_b32_e32 v7, 2, v3
	v_xor_b32_e32 v3, 8, v189
	v_cmp_lt_i32_e32 vcc, v3, v2
	v_and_b32_e32 v1, 63, v4
	s_add_u32 s40, s5, s2
	v_cndmask_b32_e32 v3, v189, v3, vcc
	v_lshlrev_b32_e32 v8, 2, v3
	v_xor_b32_e32 v3, 4, v189
	v_cmp_lt_i32_e32 vcc, v3, v2
	v_lshlrev_b32_e32 v0, 2, v1
	s_addc_u32 s41, s0, s3
	v_cndmask_b32_e32 v3, v189, v3, vcc
	v_lshlrev_b32_e32 v9, 2, v3
	v_xor_b32_e32 v3, 2, v189
	v_cmp_lt_i32_e32 vcc, v3, v2
	v_cmp_eq_u32_e64 s[2:3], 0, v1
	s_mov_b64 s[42:43], 0
	v_cndmask_b32_e32 v3, v189, v3, vcc
	v_lshlrev_b32_e32 v10, 2, v3
	v_xor_b32_e32 v3, 1, v189
	v_cmp_lt_i32_e32 vcc, v3, v2
	v_lshlrev_b32_e32 v0, 2, v0
	s_nop 0
	v_cndmask_b32_e32 v2, v189, v3, vcc
	v_lshlrev_b32_e32 v11, 2, v2
	s_branch .LBB0_42

; __device__ __forceinline__ unsigned cvt_pk_bf16(float lo, float hi) { unsigned r; asm("v_cvt_pk_bf16_f32 %0, %1, %2" : "=v"(r) : "v"(lo), "v"(hi)); return r; }
; __device__ __forceinline__ int obid() { extern __shared__ __attribute__((aligned(16))) unsigned char shm_vb[]; return __builtin_amdgcn_readfirstlane(*(volatile LAS int*)((LAS unsigned char*)shm_vb + VB_OFF)); }
; __device__ __forceinline__ void phase_a128(const float* __restrict__ w, bf16_t* __restrict__ pk, const float* __restrict__ gain) {
;     ...
;   for (int i = obid() * 8 + (tid >> 6); i < 16 * 2048; i += nw) {
;     const int g = i >> 11, d = i & 2047;
;     const float4 v = *(const float4*)(w + (size_t)d * 8192 + g * 256 + lane * 4);
;     const float s = wave_sum(v.x - v.y + v.z - v.w) * 0.0625f * gain[d];
;     if (lane == 0) pk[(size_t)(2048 + g) * 2048 + d] = (bf16_t)(cvt_pk_bf16(s, 0.f) & 0xffffu);
;   }
.LBB0_42:
	v_ashrrev_i32_e32 v2, 11, v5
	v_and_b32_e32 v12, 0x7ff, v5
	v_lshlrev_b32_e32 v80, 15, v12
	v_lshlrev_b32_e32 v16, 8, v2
	v_lshl_add_u64 v[14:15], s[38:39], 0, v[80:81]
	v_ashrrev_i32_e32 v17, 31, v16
	v_lshl_add_u64 v[14:15], v[16:17], 2, v[14:15]
	v_mov_b32_e32 v1, v81
	v_lshl_add_u64 v[14:15], v[14:15], 0, v[0:1]
	global_load_dwordx4 v[14:17], v[14:15], off
	s_waitcnt vmcnt(0) lgkmcnt(0)
	v_sub_f32_e32 v1, v14, v15
	v_add_f32_e32 v1, v1, v16
	v_sub_f32_e32 v1, v1, v17
	ds_bpermute_b32 v3, v6, v1
	s_waitcnt lgkmcnt(0)
	v_add_f32_e32 v1, v1, v3
	ds_bpermute_b32 v3, v7, v1
	s_waitcnt lgkmcnt(0)
	v_add_f32_e32 v1, v1, v3
	ds_bpermute_b32 v3, v8, v1
	s_waitcnt lgkmcnt(0)
	v_add_f32_e32 v1, v1, v3
	ds_bpermute_b32 v3, v9, v1
	s_waitcnt lgkmcnt(0)
	v_add_f32_e32 v1, v1, v3
	ds_bpermute_b32 v3, v10, v1
	s_waitcnt lgkmcnt(0)
	v_add_f32_e32 v1, v1, v3
	ds_bpermute_b32 v3, v11, v1
	s_and_saveexec_b64 s[44:45], s[2:3]
	s_cbranch_execz .LBB0_41
	v_lshlrev_b32_e32 v80, 2, v12
	v_lshl_add_u64 v[14:15], s[40:41], 0, v[80:81]
	global_load_dword v13, v[14:15], off
	s_waitcnt lgkmcnt(0)
	v_add_f32_e32 v1, v1, v3
	v_ashrrev_i32_e32 v3, 31, v2
	v_lshlrev_b64 v[2:3], 12, v[2:3]
	v_lshlrev_b32_e32 v80, 1, v12
	v_lshl_add_u64 v[2:3], s[8:9], 0, v[2:3]
	v_lshl_add_u64 v[2:3], v[2:3], 0, v[80:81]
	v_mul_f32_e32 v1, 0x3d800000, v1
	v_add_co_u32_e32 v2, vcc, 0x800000, v2
	s_waitcnt vmcnt(0)
	v_mul_f32_e32 v1, v1, v13
	v_addc_co_u32_e32 v3, vcc, 0, v3, vcc
	v_cvt_pk_bf16_f32 v1, v1, v81
	global_store_short v[2:3], v1, off
	s_branch .LBB0_41

; __device__ __forceinline__ unsigned cvt_pk_bf16(float lo, float hi) { unsigned r; asm("v_cvt_pk_bf16_f32 %0, %1, %2" : "=v"(r) : "v"(lo), "v"(hi)); return r; }
; __device__ __forceinline__ int otid() { int t = threadIdx.x; asm volatile("" : "+v"(t)); return t; }
; __device__ __forceinline__ int obid() { extern __shared__ __attribute__((aligned(16))) unsigned char shm_vb[]; return __builtin_amdgcn_readfirstlane(*(volatile LAS int*)((LAS unsigned char*)shm_vb + VB_OFF)); }
; __device__ __forceinline__ void phase_dftgen(bf16_t* __restrict__ dc, bf16_t* __restrict__ ds) {
;   const int cpr = DLD / 8;
;   const int n8 = 8192 * cpr, gs = gridDim.x * 512;
;   for (int i = obid() * 512 + otid(); i < n8; i += gs) {
;     const int k = i / cpr, n0 = (i % cpr) * 8;
;     const float a0 = (float)((k * n0) & 16383) * (1.f / 8192.f), a1 = (float)k * (1.f / 8192.f);
;     float c = cospif(a0), s = sinpif(a0); const float c1 = cospif(a1), s1 = sinpif(a1);
;     float cv[8], sv[8];
; #pragma unroll
;     for (int e = 0; e < 8; ++e) { cv[e] = c; sv[e] = s; const float cn = c * c1 - s * s1, sn = s * c1 + c * s1; c = cn; s = sn; }
;     uint4 o; o.x = cvt_pk_bf16(cv[0], cv[1]); o.y = cvt_pk_bf16(cv[2], cv[3]); o.z = cvt_pk_bf16(cv[4], cv[5]); o.w = cvt_pk_bf16(cv[6], cv[7]);
;     *(uint4*)(dc + (size_t)k * DLD + n0) = o;
;     o.x = cvt_pk_bf16(sv[0], sv[1]); o.y = cvt_pk_bf16(sv[2], sv[3]); o.z = cvt_pk_bf16(sv[4], sv[5]); o.w = cvt_pk_bf16(sv[6], sv[7]);
;     *(uint4*)(ds + (size_t)k * DLD + n0) = o;
;   }
; }
; __device__ __forceinline__ void phase_a128(const float* __restrict__ w, bf16_t* __restrict__ pk, const float* __restrict__ gain) {
;     ...
;   for (int i = obid() * 512 + tid; i < 240 * 2048 / 8; i += gridDim.x * 512) { unsigned z = 0; asm volatile("" : "+v"(z)); *(uint4*)(pk + (size_t)2064 * 2048 + (size_t)i * 8) = make_uint4(z, z, z, z); }
.LBB0_46:
	v_ashrrev_i32_e32 v1, 31, v0
	v_lshl_add_u64 v[6:7], v[0:1], 4, s[8:9]
	v_add_u32_e32 v0, s33, v0
	s_mov_b32 s0, 0xefff
	v_mov_b32_e32 v2, v81
	v_cmp_lt_i32_e32 vcc, s0, v0
	s_or_b64 s[18:19], vcc, s[18:19]
	v_mov_b32_e32 v3, v2
	v_mov_b32_e32 v4, v2
	v_mov_b32_e32 v5, v2
	global_store_dwordx4 v[6:7], v[2:5], off
	s_andn2_b64 exec, exec, s[18:19]
	s_cbranch_execnz .LBB0_46
.LBB0_47:
	s_or_b64 exec, exec, s[2:3]
	s_cmp_lg_u32 s22, 1
	s_cbranch_scc1 .LBB0_52
	v_mov_b64_e32 v[0:1], s[10:11]
	global_load_dwordx2 v[2:3], v[0:1], off sc0 sc1
	s_waitcnt vmcnt(0)
	global_load_dwordx2 v[0:1], v[0:1], off sc0 sc1
	s_waitcnt vmcnt(0)
	v_mov_b32_e32 v4, s74
	ds_read_b32 v4, v4
	v_mov_b32_e32 v5, v252
	s_mov_b32 s2, 0x440000
	s_waitcnt lgkmcnt(0)
	v_readfirstlane_b32 s0, v4
	v_readfirstlane_b32 s1, v3
	s_nop 0
	v_lshl_add_u32 v4, s0, 9, v5
	v_readfirstlane_b32 s8, v2
	v_readfirstlane_b32 s0, v1
	v_readfirstlane_b32 s5, v0
	v_cmp_gt_i32_e32 vcc, s2, v4
	s_and_saveexec_b64 s[2:3], vcc
	s_cbranch_execz .LBB0_51
	s_add_u32 s8, s8, 0x44480000
	s_addc_u32 s9, s1, 0
	s_add_u32 s36, s5, 0x48880000
	s_addc_u32 s37, s0, 0
	v_lshlrev_b32_e32 v5, 3, v4
	s_lshl_b32 s0, s33, 3
	s_mov_b64 s[38:39], 0
.LBB0_50:
	s_mov_b32 s1, 0x78787879
	v_mul_hi_i32 v0, v4, s1
	v_lshrrev_b32_e32 v1, 31, v0
	v_ashrrev_i32_e32 v0, 8, v0
	v_add_u32_e32 v3, v0, v1
	v_mul_i32_i24_e32 v2, 0x220, v3
	v_cvt_f32_i32_e32 v10, v3
	v_mul_hi_i32_i24_e32 v1, 0x1100, v3
	v_mul_i32_i24_e32 v0, 0x1100, v3
	v_lshlrev_b32_e32 v2, 3, v2
	v_lshlrev_b64 v[0:1], 1, v[0:1]
	v_sub_u32_e32 v2, v5, v2
	v_lshl_add_u64 v[6:7], s[8:9], 0, v[0:1]
	v_lshl_add_u64 v[8:9], s[36:37], 0, v[0:1]
	v_mul_lo_u32 v0, v2, v3
	v_ashrrev_i32_e32 v3, 31, v2
	v_and_b32_e32 v0, 0x3ff8, v0
	v_mul_f32_e32 v10, 0x39000000, v10
	v_add_u32_e32 v4, s33, v4
	s_mov_b32 s1, 0x43ffff
	v_lshlrev_b64 v[2:3], 1, v[2:3]
	v_cvt_f32_u32_e32 v11, v0
	v_mul_f32_e64 v13, |v10|, 0.5
	v_cmp_lt_i32_e32 vcc, s1, v4
	v_lshl_add_u64 v[0:1], v[6:7], 0, v[2:3]
	v_fract_f32_e32 v6, v13
	s_or_b64 s[38:39], vcc, s[38:39]
	v_add_f32_e32 v6, v6, v6
	v_cmp_neq_f32_e32 vcc, s86, v13
	v_cmp_gt_f32_e64 s[18:19], |v10|, 1.0
	v_lshl_add_u64 v[2:3], v[8:9], 0, v[2:3]
	v_cndmask_b32_e32 v6, 0, v6, vcc
	v_mul_f32_e32 v8, 0x39000000, v11
	v_cndmask_b32_e64 v6, |v10|, v6, s[18:19]
	v_and_b32_e32 v12, 0x7fffffff, v10
	v_mul_f32_e32 v9, 0.5, v8
	v_add_f32_e32 v11, v6, v6
	v_xor_b32_e32 v7, v12, v10
	v_fract_f32_e32 v12, v9
	v_rndne_f32_e32 v11, v11
	v_add_f32_e32 v12, v12, v12
	v_fmac_f32_e32 v6, -0.5, v11
	v_cmp_neq_f32_e32 vcc, s86, v9
	v_cvt_i32_f32_e32 v11, v11
	s_movk_i32 s1, 0x1f8
	v_cndmask_b32_e32 v9, 0, v12, vcc
	v_mul_f32_e32 v12, v6, v6
	v_cmp_lt_f32_e32 vcc, 1.0, v8
	v_fmamk_f32 v13, v12, 0x3e75aa41, v231
	v_fmamk_f32 v15, v12, 0x3d4be544, v253
	v_cndmask_b32_e32 v9, v8, v9, vcc
	v_add_f32_e32 v16, v9, v9
	v_fmaak_f32 v13, v12, v13, 0x40234736
	v_fmaak_f32 v15, v12, v15, 0xbfaad1da
	v_mul_f32_e32 v14, v6, v12
	v_rndne_f32_e32 v16, v16
	v_fmaak_f32 v13, v12, v13, 0xc0a55e0e
	v_fmaak_f32 v15, v12, v15, 0x4081e0d3
	v_and_b32_e32 v17, 2, v11
	v_and_b32_e32 v18, 1, v11
	v_lshlrev_b32_e32 v11, 30, v11
	v_fmac_f32_e32 v9, -0.5, v16
	v_mul_f32_e32 v13, v14, v13
	v_fmaak_f32 v14, v12, v15, 0xc09de9e6
	v_cvt_i32_f32_e32 v16, v16
	v_and_b32_e32 v11, 0x80000000, v11
	v_fmac_f32_e32 v13, 0x40490fdb, v6
	v_fma_f32 v6, v12, v14, 1.0
	v_cmp_eq_u32_e32 vcc, 0, v18
	v_mul_f32_e32 v12, v9, v9
	v_xor_b32_e32 v7, v7, v11
	v_fmamk_f32 v11, v12, 0x3e75aa41, v231
	v_fmamk_f32 v15, v12, 0x3d4be544, v253
	v_cndmask_b32_e64 v18, -v13, v6, vcc
	v_cndmask_b32_e32 v6, v6, v13, vcc
	v_cmp_eq_u32_e32 vcc, 0, v17
	v_mul_f32_e32 v14, v9, v12
	v_xor_b32_e32 v6, v7, v6
	v_cndmask_b32_e64 v13, -v18, v18, vcc
	v_cmp_class_f32_e64 vcc, v10, s1
	v_fmaak_f32 v10, v12, v11, 0x40234736
	v_fmaak_f32 v11, v12, v15, 0xbfaad1da
	v_fmaak_f32 v10, v12, v10, 0xc0a55e0e
	v_fmaak_f32 v11, v12, v11, 0x4081e0d3
	v_and_b32_e32 v15, 1, v16
	v_cndmask_b32_e32 v17, v222, v6, vcc
	v_mul_f32_e32 v6, v14, v10
	v_fmaak_f32 v10, v12, v11, 0xc09de9e6
	v_and_b32_e32 v7, 2, v16
	v_cndmask_b32_e32 v13, v222, v13, vcc
	v_fmac_f32_e32 v6, 0x40490fdb, v9
	v_fma_f32 v9, v12, v10, 1.0
	v_cmp_eq_u32_e32 vcc, 0, v15
	v_lshlrev_b32_e32 v16, 30, v16
	v_add_u32_e32 v5, s0, v5
	v_cndmask_b32_e64 v10, -v6, v9, vcc
	v_cndmask_b32_e32 v6, v9, v6, vcc
	v_cmp_eq_u32_e32 vcc, 0, v7
	v_bitop3_b32 v6, v16, v6, s82 bitop3:0x6c
	s_nop 0
	v_cndmask_b32_e64 v7, -v10, v10, vcc
	v_cmp_lg_f32_e32 vcc, s86, v8
	s_nop 1
	v_cndmask_b32_e32 v8, v222, v6, vcc
	v_cndmask_b32_e32 v7, v222, v7, vcc
	v_mul_f32_e32 v6, v17, v8
	v_mul_f32_e32 v9, v13, v8
	v_fma_f32 v11, v13, v7, -v6
	v_fmac_f32_e32 v9, v17, v7
	v_mul_f32_e32 v14, v17, v11
	v_mul_f32_e32 v12, v17, v9
	v_fmac_f32_e32 v14, v13, v9
	v_cvt_pk_bf16_f32 v6, v7, v11
	v_cvt_pk_bf16_f32 v10, v8, v9
	v_fma_f32 v7, v13, v11, -v12
	v_mul_f32_e32 v8, v17, v14
	v_mul_f32_e32 v9, v17, v7
	v_fma_f32 v8, v13, v7, -v8
	v_fmac_f32_e32 v9, v13, v14
	v_mul_f32_e32 v15, v17, v8
	v_mul_f32_e32 v12, v17, v9
	v_fmac_f32_e32 v15, v13, v9
	v_cvt_pk_bf16_f32 v7, v7, v8
	v_cvt_pk_bf16_f32 v11, v14, v9
	v_fma_f32 v8, v13, v8, -v12
	v_mul_f32_e32 v9, v17, v15
	v_mul_f32_e32 v14, v17, v8
	v_fma_f32 v9, v13, v8, -v9
	v_fmac_f32_e32 v14, v13, v15
	v_mul_f32_e32 v18, v17, v9
	v_mul_f32_e32 v16, v17, v14
	v_fmac_f32_e32 v18, v13, v14
	v_cvt_pk_bf16_f32 v8, v8, v9
	v_cvt_pk_bf16_f32 v12, v15, v14
	v_fma_f32 v9, v13, v9, -v16
	v_mul_f32_e32 v14, v17, v18
	v_mul_f32_e32 v15, v17, v9
	v_fma_f32 v14, v13, v9, -v14
	v_cvt_pk_bf16_f32 v9, v9, v14
	v_fmac_f32_e32 v15, v13, v18
	v_cvt_pk_bf16_f32 v13, v18, v15
	global_store_dwordx4 v[0:1], v[6:9], off
	global_store_dwordx4 v[2:3], v[10:13], off
	s_andn2_b64 exec, exec, s[38:39]
	s_cbranch_execnz .LBB0_50

; #define LAS __attribute__((address_space(3)))
; __device__ __forceinline__ unsigned cvt_pk_bf16(float lo, float hi) { unsigned r; asm("v_cvt_pk_bf16_f32 %0, %1, %2" : "=v"(r) : "v"(lo), "v"(hi)); return r; }
; __device__ __forceinline__ int otid() { int t = threadIdx.x; asm volatile("" : "+v"(t)); return t; }
; __device__ __forceinline__ int obid() { extern __shared__ __attribute__((aligned(16))) unsigned char shm_vb[]; return __builtin_amdgcn_readfirstlane(*(volatile LAS int*)((LAS unsigned char*)shm_vb + VB_OFF)); }
; #define IN(i) ((const float*)karg(i))
; #define WSB(off) ((bf16_t*)((unsigned char*)karg(15) + (off)))
; __device__ __forceinline__ void phase_wT(const float* __restrict__ src, int ldn, int n0, int K, int N, bf16_t* __restrict__ dst, LAS float* tile, const float* __restrict__ gain = nullptr) {
;   const int tk = K / 64, tn = N / 256, nt = tk * tn, t = otid(), w = t >> 6, lane = t & 63;
;   for (int ti = obid(); ti < nt; ti += gridDim.x) {
;     const int kt = ti % tk, ntile = ti / tk;
;     float4 v[8];
; #pragma unroll
;     for (int i = 0; i < 8; ++i) v[i] = *(const float4*)(src + (size_t)(kt * 64 + w + 8 * i) * ldn + n0 + ntile * 256 + lane * 4);
;     if (gain) {
; #pragma unroll
;       for (int i = 0; i < 8; ++i) { const float gk = gain[kt * 64 + w + 8 * i]; v[i].x *= gk; v[i].y *= gk; v[i].z *= gk; v[i].w *= gk; }
;     }
; #pragma unroll
;     for (int i = 0; i < 8; ++i) { const int k = w + 8 * i; *(LAS f32x4*)(tile + k * 256 + ((lane ^ (i & 7)) << 2)) = (f32x4){v[i].x, v[i].y, v[i].z, v[i].w}; }
;     __syncthreads();
;     const int nr = t >> 3, kc = (t & 7) * 8, ksw = (t & 7);
; #pragma unroll
;     for (int p = 0; p < 4; ++p) {
;       const int n = p * 64 + nr;
;       const LAS float* sp = tile + kc * 256 + ((((n >> 2) ^ ksw)) << 2) + (n & 3);
;       uint4 o; o.x = cvt_pk_bf16(sp[0], sp[256]); o.y = cvt_pk_bf16(sp[512], sp[768]); o.z = cvt_pk_bf16(sp[1024], sp[1280]); o.w = cvt_pk_bf16(sp[1536], sp[1792]);
;       *(uint4*)(dst + (size_t)(ntile * 256 + n) * K + kt * 64 + kc) = o;
;     }
;     __syncthreads();
;   }
; }
; __global__ void __launch_bounds__(512, 2) mega(Params p) {
;     ...
;       phase_wT(IN(5) + (size_t)j * 2048 * 20480, 20480, 0, 2048, 12288, WSB(WS_WA), tile, IN(4) + layer * DM);
.LBB0_53:
	s_and_b64 vcc, exec, s[2:3]
	s_cbranch_vccz .LBB0_72
	v_readlane_b32 s0, v255, 0
	v_readlane_b32 s1, v255, 1
	s_lshl_b32 s2, s4, 11
	s_lshl_b32 s6, s22, 11
	v_mov_b64_e32 v[0:1], s[0:1]
	global_load_dwordx2 v[2:3], v[0:1], off offset:40 sc0 sc1
	s_waitcnt vmcnt(0)
	global_load_dwordx2 v[4:5], v[0:1], off offset:120 sc0 sc1
	s_waitcnt vmcnt(0)
	global_load_dwordx2 v[6:7], v[0:1], off offset:32 sc0 sc1
	s_waitcnt vmcnt(0)
	v_mov_b32_e32 v0, v252
	v_mov_b32_e32 v1, s74
	ds_read_b32 v1, v1
	s_mul_i32 s8, s4, 0x2800000
	s_mul_hi_u32 s9, s2, 0x5000
	s_mov_b32 s7, s12
	s_waitcnt lgkmcnt(0)
	v_readfirstlane_b32 s0, v1
	s_cmpk_gt_i32 s0, 0x5ff
	v_readfirstlane_b32 s1, v3
	v_readfirstlane_b32 s3, v2
	v_readfirstlane_b32 s41, v5
	v_readfirstlane_b32 s40, v4
	v_readfirstlane_b32 s19, v7
	v_readfirstlane_b32 s18, v6
	s_cbranch_scc1 .LBB0_59
	s_lshl_b64 s[28:29], s[6:7], 2
	s_add_u32 s36, s18, s28
	v_ashrrev_i32_e32 v40, 3, v0
	s_addc_u32 s37, s19, s29
	v_ashrrev_i32_e32 v38, 6, v0
	s_lshl_b64 s[28:29], s[8:9], 2
	v_lshlrev_b32_e32 v2, 4, v0
	v_and_b32_e32 v0, 7, v0
	v_lshlrev_b32_e32 v4, 2, v40
	s_add_u32 s28, s3, s28
	v_lshlrev_b32_e32 v1, 13, v0
	v_and_b32_e32 v4, 12, v4
	v_mov_b32_e32 v9, 0x3f0
	s_movk_i32 s3, 0x50
	s_addc_u32 s29, s1, s29
	v_lshlrev_b32_e32 v3, 2, v0
	v_add3_u32 v4, 0, v1, v4
	v_lshlrev_b32_e32 v0, 4, v0
	v_mov_b32_e32 v1, v81
	s_mov_b32 s1, 0x3ffffffc
	v_bitop3_b32 v7, v2, s3, v9 bitop3:0x6c
	s_movk_i32 s3, 0x60
	v_lshl_add_u64 v[34:35], s[40:41], 0, v[0:1]
	v_bitop3_b32 v0, v40, v3, s1 bitop3:0x6c
	v_bitop3_b32 v8, v2, s3, v9 bitop3:0x6c
	s_movk_i32 s3, 0x70
	v_add_u32_e32 v42, 64, v40
	v_and_b32_e32 v80, 0x3f0, v2
	v_lshl_add_u32 v41, v0, 2, v4
	v_bitop3_b32 v0, v2, 16, v9 bitop3:0x6c
	v_bitop3_b32 v1, v2, 32, v9 bitop3:0x6c
	v_bitop3_b32 v5, v2, 48, v9 bitop3:0x6c
	v_bitop3_b32 v6, v2, 64, v9 bitop3:0x6c
	v_bitop3_b32 v2, v2, s3, v9 bitop3:0x6c
	v_bitop3_b32 v9, v42, v3, s1 bitop3:0x6c
	v_add_u32_e32 v44, 0x80, v40
	v_add_u32_e32 v46, 0xc0, v40
	s_cmp_lg_u64 s[18:19], 0
	v_lshl_add_u32 v39, v38, 10, 0
	v_lshl_add_u32 v43, v9, 2, v4
	v_bitop3_b32 v9, v44, v3, s1 bitop3:0x6c
	v_bitop3_b32 v3, v46, v3, s1 bitop3:0x6c
	v_lshl_add_u64 v[32:33], s[28:29], 0, v[80:81]
	s_cselect_b64 s[38:39], -1, 0
	v_lshl_add_u32 v45, v9, 2, v4
	v_lshl_add_u32 v47, v3, 2, v4
	s_lshl_b32 s1, s0, 6
	s_lshl_b32 s3, s20, 6
	v_add_u32_e32 v48, v39, v0
	v_add_u32_e32 v49, v39, v1
	v_add_u32_e32 v50, v39, v5
	v_add_u32_e32 v51, v39, v6
	v_add_u32_e32 v52, v39, v7
	v_add_u32_e32 v53, v39, v8
	v_add_u32_e32 v54, v39, v2
	s_branch .LBB0_57
.LBB0_56:
	v_add_u32_e32 v36, v39, v80
	s_waitcnt vmcnt(0) lgkmcnt(0)
	ds_write_b128 v36, v[4:7]
	ds_write_b128 v48, v[0:3] offset:8192
	ds_write_b128 v49, v[12:15] offset:16384
	ds_write_b128 v50, v[8:11] offset:24576
	ds_write_b128 v51, v[20:23] offset:32768
	ds_write_b128 v52, v[16:19] offset:40960
	ds_write_b128 v53, v[28:31] offset:49152
	ds_write_b128 v54, v[24:27] offset:57344
	s_waitcnt lgkmcnt(0)
	s_barrier
	ds_read2st64_b32 v[0:1], v41 offset1:4
	ds_read2st64_b32 v[2:3], v41 offset0:8 offset1:12
	ds_read2st64_b32 v[4:5], v41 offset0:16 offset1:20
	ds_read2st64_b32 v[6:7], v41 offset0:24 offset1:28
	s_sub_i32 s5, 0, s5
	s_add_i32 s18, s1, s5
	s_waitcnt lgkmcnt(3)
	v_cvt_pk_bf16_f32 v0, v0, v1
	s_waitcnt lgkmcnt(2)
	v_cvt_pk_bf16_f32 v1, v2, v3
	s_waitcnt lgkmcnt(1)
	v_cvt_pk_bf16_f32 v2, v4, v5
	v_add_u32_e32 v4, s40, v40
	s_ashr_i32 s19, s18, 31
	s_waitcnt lgkmcnt(0)
	v_cvt_pk_bf16_f32 v3, v6, v7
	v_ashrrev_i32_e32 v5, 31, v4
	ds_read2st64_b32 v[6:7], v43 offset1:4
	ds_read2st64_b32 v[10:11], v43 offset0:8 offset1:12
	ds_read2st64_b32 v[12:13], v43 offset0:16 offset1:20
	ds_read2st64_b32 v[14:15], v43 offset0:24 offset1:28
	v_lshl_add_u64 v[8:9], s[18:19], 1, v[34:35]
	v_lshlrev_b64 v[4:5], 12, v[4:5]
	v_lshl_add_u64 v[4:5], v[8:9], 0, v[4:5]
	global_store_dwordx4 v[4:5], v[0:3], off
	v_add_u32_e32 v4, s40, v42
	v_ashrrev_i32_e32 v5, 31, v4
	s_waitcnt lgkmcnt(0)
	v_cvt_pk_bf16_f32 v0, v6, v7
	v_cvt_pk_bf16_f32 v1, v10, v11
	v_cvt_pk_bf16_f32 v2, v12, v13
	v_cvt_pk_bf16_f32 v3, v14, v15
	v_lshlrev_b64 v[4:5], 12, v[4:5]
	ds_read2st64_b32 v[6:7], v45 offset1:4
	ds_read2st64_b32 v[10:11], v45 offset0:8 offset1:12
	ds_read2st64_b32 v[12:13], v45 offset0:16 offset1:20
	ds_read2st64_b32 v[14:15], v45 offset0:24 offset1:28
	v_lshl_add_u64 v[4:5], v[8:9], 0, v[4:5]
	global_store_dwordx4 v[4:5], v[0:3], off
	v_add_u32_e32 v4, s40, v44
	v_ashrrev_i32_e32 v5, 31, v4
	v_lshlrev_b64 v[4:5], 12, v[4:5]
	s_waitcnt lgkmcnt(0)
	v_cvt_pk_bf16_f32 v0, v6, v7
	v_cvt_pk_bf16_f32 v1, v10, v11
	v_cvt_pk_bf16_f32 v2, v12, v13
	v_cvt_pk_bf16_f32 v3, v14, v15
	v_lshl_add_u64 v[4:5], v[8:9], 0, v[4:5]
	ds_read2st64_b32 v[6:7], v47 offset1:4
	ds_read2st64_b32 v[10:11], v47 offset0:8 offset1:12
	ds_read2st64_b32 v[12:13], v47 offset0:16 offset1:20
	ds_read2st64_b32 v[14:15], v47 offset0:24 offset1:28
	global_store_dwordx4 v[4:5], v[0:3], off
	v_add_u32_e32 v4, s40, v46
	v_ashrrev_i32_e32 v5, 31, v4
	v_lshlrev_b64 v[4:5], 12, v[4:5]
	s_add_i32 s0, s0, s20
	s_add_i32 s1, s1, s3
	v_lshl_add_u64 v[4:5], v[8:9], 0, v[4:5]
	s_cmpk_lt_i32 s0, 0x600
	s_waitcnt lgkmcnt(0)
	v_cvt_pk_bf16_f32 v0, v6, v7
	v_cvt_pk_bf16_f32 v1, v10, v11
	v_cvt_pk_bf16_f32 v2, v12, v13
	v_cvt_pk_bf16_f32 v3, v14, v15
	global_store_dwordx4 v[4:5], v[0:3], off
	s_waitcnt lgkmcnt(0)
	s_barrier
	s_cbranch_scc0 .LBB0_59
; __device__ __forceinline__ void phase_wT(const float* __restrict__ src, int ldn, int n0, int K, int N, bf16_t* __restrict__ dst, LAS float* tile, const float* __restrict__ gain = nullptr) {
;     ...
;     float4 v[8];
; #pragma unroll
;     for (int i = 0; i < 8; ++i) v[i] = *(const float4*)(src + (size_t)(kt * 64 + w + 8 * i) * ldn + n0 + ntile * 256 + lane * 4);
;     if (gain) {
; #pragma unroll
;       for (int i = 0; i < 8; ++i) { const float gk = gain[kt * 64 + w + 8 * i]; v[i].x *= gk; v[i].y *= gk; v[i].z *= gk; v[i].w *= gk; }
;     }
.LBB0_57:
	s_ashr_i32 s5, s0, 31
	s_lshr_b32 s5, s5, 27
	s_add_i32 s5, s0, s5
	s_ashr_i32 s13, s5, 5
	s_lshl_b32 s5, s13, 11
	s_sub_i32 s17, s1, s5
	s_lshl_b32 s40, s13, 8
	v_add_u32_e32 v36, s17, v38
	s_ashr_i32 s41, s40, 31
	v_lshl_add_u64 v[24:25], s[40:41], 2, v[32:33]
	s_mov_b32 s13, 0x14000
	v_add_u32_e32 v2, 8, v36
	v_add_u32_e32 v8, 16, v36
	v_add_u32_e32 v10, 24, v36
	v_add_u32_e32 v16, 32, v36
	v_add_u32_e32 v18, 40, v36
	v_add_u32_e32 v26, 48, v36
	v_add_u32_e32 v28, 56, v36
	v_mad_i64_i32 v[0:1], s[18:19], v36, s13, v[24:25]
	v_mad_i64_i32 v[2:3], s[18:19], v2, s13, v[24:25]
	v_mad_i64_i32 v[8:9], s[18:19], v8, s13, v[24:25]
	v_mad_i64_i32 v[10:11], s[18:19], v10, s13, v[24:25]
	v_mad_i64_i32 v[16:17], s[18:19], v16, s13, v[24:25]
	v_mad_i64_i32 v[18:19], s[18:19], v18, s13, v[24:25]
	v_mad_i64_i32 v[26:27], s[18:19], v26, s13, v[24:25]
	v_mad_i64_i32 v[24:25], s[18:19], v28, s13, v[24:25]
	global_load_dwordx4 v[4:7], v[0:1], off
	s_nop 0
	global_load_dwordx4 v[0:3], v[2:3], off
	s_nop 0
	global_load_dwordx4 v[12:15], v[8:9], off
	s_nop 0
	global_load_dwordx4 v[8:11], v[10:11], off
	s_nop 0
	global_load_dwordx4 v[20:23], v[16:17], off
	s_nop 0
	global_load_dwordx4 v[16:19], v[18:19], off
	s_nop 0
	global_load_dwordx4 v[28:31], v[26:27], off
	s_nop 0
	global_load_dwordx4 v[24:27], v[24:25], off
	s_andn2_b64 vcc, exec, s[38:39]
	s_cbranch_vccnz .LBB0_56
	v_ashrrev_i32_e32 v37, 31, v36
	v_lshl_add_u64 v[36:37], v[36:37], 2, s[36:37]
	global_load_dword v56, v[36:37], off
	global_load_dword v58, v[36:37], off offset:32
	global_load_dword v60, v[36:37], off offset:64
	global_load_dword v62, v[36:37], off offset:96
	global_load_dword v64, v[36:37], off offset:128
	global_load_dword v66, v[36:37], off offset:160
	global_load_dword v68, v[36:37], off offset:192
	s_nop 0
	global_load_dword v36, v[36:37], off offset:224
	s_waitcnt vmcnt(0) lgkmcnt(0)
	v_pk_mul_f32 v[4:5], v[4:5], v[56:57] op_sel_hi:[1,0]
	v_pk_mul_f32 v[6:7], v[6:7], v[56:57] op_sel_hi:[1,0]
	v_pk_mul_f32 v[0:1], v[0:1], v[58:59] op_sel_hi:[1,0]
	v_pk_mul_f32 v[2:3], v[2:3], v[58:59] op_sel_hi:[1,0]
	v_pk_mul_f32 v[12:13], v[12:13], v[60:61] op_sel_hi:[1,0]
	v_pk_mul_f32 v[14:15], v[14:15], v[60:61] op_sel_hi:[1,0]
	v_pk_mul_f32 v[8:9], v[8:9], v[62:63] op_sel_hi:[1,0]
	v_pk_mul_f32 v[10:11], v[10:11], v[62:63] op_sel_hi:[1,0]
	v_pk_mul_f32 v[20:21], v[20:21], v[64:65] op_sel_hi:[1,0]
	v_pk_mul_f32 v[22:23], v[22:23], v[64:65] op_sel_hi:[1,0]
	v_pk_mul_f32 v[16:17], v[16:17], v[66:67] op_sel_hi:[1,0]
	v_pk_mul_f32 v[18:19], v[18:19], v[66:67] op_sel_hi:[1,0]
	v_pk_mul_f32 v[28:29], v[28:29], v[68:69] op_sel_hi:[1,0]
	v_pk_mul_f32 v[30:31], v[30:31], v[68:69] op_sel_hi:[1,0]
	v_pk_mul_f32 v[24:25], v[24:25], v[36:37] op_sel_hi:[1,0]
	v_pk_mul_f32 v[26:27], v[26:27], v[36:37] op_sel_hi:[1,0]
	s_branch .LBB0_56
; #define LAS __attribute__((address_space(3)))
; __device__ __forceinline__ unsigned cvt_pk_bf16(float lo, float hi) { unsigned r; asm("v_cvt_pk_bf16_f32 %0, %1, %2" : "=v"(r) : "v"(lo), "v"(hi)); return r; }
; __device__ __forceinline__ int otid() { int t = threadIdx.x; asm volatile("" : "+v"(t)); return t; }
; __device__ __forceinline__ int obid() { extern __shared__ __attribute__((aligned(16))) unsigned char shm_vb[]; return __builtin_amdgcn_readfirstlane(*(volatile LAS int*)((LAS unsigned char*)shm_vb + VB_OFF)); }
; #define IN(i) ((const float*)karg(i))
; #define WSB(off) ((bf16_t*)((unsigned char*)karg(15) + (off)))
; __device__ __forceinline__ void phase_wT(const float* __restrict__ src, int ldn, int n0, int K, int N, bf16_t* __restrict__ dst, LAS float* tile, const float* __restrict__ gain = nullptr) {
;   const int tk = K / 64, tn = N / 256, nt = tk * tn, t = otid(), w = t >> 6, lane = t & 63;
;   for (int ti = obid(); ti < nt; ti += gridDim.x) {
;     const int kt = ti % tk, ntile = ti / tk;
;     float4 v[8];
; #pragma unroll
;     for (int i = 0; i < 8; ++i) v[i] = *(const float4*)(src + (size_t)(kt * 64 + w + 8 * i) * ldn + n0 + ntile * 256 + lane * 4);
;     if (gain) {
; #pragma unroll
;       for (int i = 0; i < 8; ++i) { const float gk = gain[kt * 64 + w + 8 * i]; v[i].x *= gk; v[i].y *= gk; v[i].z *= gk; v[i].w *= gk; }
;     }
; #pragma unroll
;     for (int i = 0; i < 8; ++i) { const int k = w + 8 * i; *(LAS f32x4*)(tile + k * 256 + ((lane ^ (i & 7)) << 2)) = (f32x4){v[i].x, v[i].y, v[i].z, v[i].w}; }
;     __syncthreads();
;     const int nr = t >> 3, kc = (t & 7) * 8, ksw = (t & 7);
; #pragma unroll
;     for (int p = 0; p < 4; ++p) {
;       const int n = p * 64 + nr;
;       const LAS float* sp = tile + kc * 256 + ((((n >> 2) ^ ksw)) << 2) + (n & 3);
;       uint4 o; o.x = cvt_pk_bf16(sp[0], sp[256]); o.y = cvt_pk_bf16(sp[512], sp[768]); o.z = cvt_pk_bf16(sp[1024], sp[1280]); o.w = cvt_pk_bf16(sp[1536], sp[1792]);
;       *(uint4*)(dst + (size_t)(ntile * 256 + n) * K + kt * 64 + kc) = o;
;     }
;     __syncthreads();
;   }
; }
; __global__ void __launch_bounds__(512, 2) mega(Params p) {
;     ...
;       phase_wT(IN(5) + (size_t)j * 2048 * 20480, 20480, 18432, 2048, 2048, WSB(WS_WA) + (size_t)12288 * 2048, tile, IN(4) + layer * DM);
.LBB0_59:
	v_readlane_b32 s0, v255, 0
	v_readlane_b32 s1, v255, 1
	s_nop 1
	v_mov_b64_e32 v[0:1], s[0:1]
	global_load_dwordx2 v[2:3], v[0:1], off offset:40 sc0 sc1
	s_waitcnt vmcnt(0)
	global_load_dwordx2 v[4:5], v[0:1], off offset:120 sc0 sc1
	s_waitcnt vmcnt(0)
	global_load_dwordx2 v[6:7], v[0:1], off offset:32 sc0 sc1
	s_waitcnt vmcnt(0)
	v_mov_b32_e32 v0, v252
	v_mov_b32_e32 v1, s74
	ds_read_b32 v1, v1
	s_waitcnt lgkmcnt(0)
	v_readfirstlane_b32 s0, v1
	s_cmpk_gt_i32 s0, 0xff
	v_readfirstlane_b32 s1, v3
	v_readfirstlane_b32 s3, v2
	v_readfirstlane_b32 s41, v5
	v_readfirstlane_b32 s40, v4
	v_readfirstlane_b32 s19, v7
	v_readfirstlane_b32 s18, v6
	s_cbranch_scc1 .LBB0_64
	s_lshl_b64 s[28:29], s[6:7], 2
	s_add_u32 s36, s18, s28
	s_addc_u32 s37, s19, s29
	s_lshl_b64 s[28:29], s[8:9], 2
	s_add_u32 s28, s3, s28
	v_lshlrev_b32_e32 v4, 4, v0
	s_addc_u32 s29, s1, s29
	v_and_b32_e32 v80, 0x3f0, v4
	v_lshl_add_u64 v[2:3], s[28:29], 0, v[80:81]
	s_mov_b64 s[28:29], 0x12000
	v_ashrrev_i32_e32 v40, 3, v0
	v_ashrrev_i32_e32 v38, 6, v0
	v_lshl_add_u64 v[32:33], v[2:3], 0, s[28:29]
	v_and_b32_e32 v0, 7, v0
	v_lshlrev_b32_e32 v3, 2, v40
	v_lshlrev_b32_e32 v1, 13, v0
	v_and_b32_e32 v3, 12, v3
	v_lshlrev_b32_e32 v2, 2, v0
	v_add3_u32 v3, 0, v1, v3
	v_lshlrev_b32_e32 v0, 4, v0
	v_mov_b32_e32 v1, v81
	v_mov_b32_e32 v9, 0x3f0
	s_movk_i32 s3, 0x50
	s_cmp_lg_u64 s[18:19], 0
	v_lshl_add_u64 v[0:1], s[40:41], 0, v[0:1]
	s_mov_b64 s[18:19], 0x3000000
	s_mov_b32 s1, 0x3ffffffc
	v_bitop3_b32 v7, v4, s3, v9 bitop3:0x6c
	s_movk_i32 s3, 0x60
	v_lshl_add_u64 v[34:35], v[0:1], 0, s[18:19]
	v_bitop3_b32 v0, v40, v2, s1 bitop3:0x6c
	v_bitop3_b32 v8, v4, s3, v9 bitop3:0x6c
	s_movk_i32 s3, 0x70
	v_add_u32_e32 v42, 64, v40
	v_lshl_add_u32 v41, v0, 2, v3
	v_bitop3_b32 v0, v4, 16, v9 bitop3:0x6c
	v_bitop3_b32 v1, v4, 32, v9 bitop3:0x6c
	v_bitop3_b32 v5, v4, 48, v9 bitop3:0x6c
	v_bitop3_b32 v6, v4, 64, v9 bitop3:0x6c
	v_bitop3_b32 v4, v4, s3, v9 bitop3:0x6c
	v_bitop3_b32 v9, v42, v2, s1 bitop3:0x6c
	v_add_u32_e32 v44, 0x80, v40
	v_add_u32_e32 v46, 0xc0, v40
	v_lshl_add_u32 v39, v38, 10, 0
	v_lshl_add_u32 v43, v9, 2, v3
	v_bitop3_b32 v9, v44, v2, s1 bitop3:0x6c
	v_bitop3_b32 v2, v46, v2, s1 bitop3:0x6c
	s_cselect_b64 s[38:39], -1, 0
	v_lshl_add_u32 v45, v9, 2, v3
	v_lshl_add_u32 v47, v2, 2, v3
	s_lshl_b32 s1, s0, 6
	s_lshl_b32 s3, s20, 6
	v_add_u32_e32 v48, v39, v0
	v_add_u32_e32 v49, v39, v1
	v_add_u32_e32 v50, v39, v5
	v_add_u32_e32 v51, v39, v6
	v_add_u32_e32 v52, v39, v7
	v_add_u32_e32 v53, v39, v8
	v_add_u32_e32 v54, v39, v4
	s_branch .LBB0_62
.LBB0_61:
	v_add_u32_e32 v36, v39, v80
	s_waitcnt vmcnt(0) lgkmcnt(0)
	ds_write_b128 v36, v[4:7]
	ds_write_b128 v48, v[0:3] offset:8192
	ds_write_b128 v49, v[12:15] offset:16384
	ds_write_b128 v50, v[8:11] offset:24576
	ds_write_b128 v51, v[20:23] offset:32768
	ds_write_b128 v52, v[16:19] offset:40960
	ds_write_b128 v53, v[28:31] offset:49152
	ds_write_b128 v54, v[24:27] offset:57344
	s_waitcnt lgkmcnt(0)
	s_barrier
	ds_read2st64_b32 v[0:1], v41 offset1:4
	ds_read2st64_b32 v[2:3], v41 offset0:8 offset1:12
	ds_read2st64_b32 v[4:5], v41 offset0:16 offset1:20
	ds_read2st64_b32 v[6:7], v41 offset0:24 offset1:28
	s_sub_i32 s5, 0, s5
	s_add_i32 s18, s1, s5
	s_waitcnt lgkmcnt(3)
	v_cvt_pk_bf16_f32 v0, v0, v1
	s_waitcnt lgkmcnt(2)
	v_cvt_pk_bf16_f32 v1, v2, v3
	s_waitcnt lgkmcnt(1)
	v_cvt_pk_bf16_f32 v2, v4, v5
	v_add_u32_e32 v4, s40, v40
	s_ashr_i32 s19, s18, 31
	s_waitcnt lgkmcnt(0)
	v_cvt_pk_bf16_f32 v3, v6, v7
	v_ashrrev_i32_e32 v5, 31, v4
	ds_read2st64_b32 v[6:7], v43 offset1:4
	ds_read2st64_b32 v[10:11], v43 offset0:8 offset1:12
	ds_read2st64_b32 v[12:13], v43 offset0:16 offset1:20
	ds_read2st64_b32 v[14:15], v43 offset0:24 offset1:28
	v_lshl_add_u64 v[8:9], s[18:19], 1, v[34:35]
	v_lshlrev_b64 v[4:5], 12, v[4:5]
	v_lshl_add_u64 v[4:5], v[8:9], 0, v[4:5]
	global_store_dwordx4 v[4:5], v[0:3], off
	v_add_u32_e32 v4, s40, v42
	v_ashrrev_i32_e32 v5, 31, v4
	s_waitcnt lgkmcnt(0)
	v_cvt_pk_bf16_f32 v0, v6, v7
	v_cvt_pk_bf16_f32 v1, v10, v11
	v_cvt_pk_bf16_f32 v2, v12, v13
	v_cvt_pk_bf16_f32 v3, v14, v15
	v_lshlrev_b64 v[4:5], 12, v[4:5]
	ds_read2st64_b32 v[6:7], v45 offset1:4
	ds_read2st64_b32 v[10:11], v45 offset0:8 offset1:12
	ds_read2st64_b32 v[12:13], v45 offset0:16 offset1:20
	ds_read2st64_b32 v[14:15], v45 offset0:24 offset1:28
	v_lshl_add_u64 v[4:5], v[8:9], 0, v[4:5]
	global_store_dwordx4 v[4:5], v[0:3], off
	v_add_u32_e32 v4, s40, v44
	v_ashrrev_i32_e32 v5, 31, v4
	v_lshlrev_b64 v[4:5], 12, v[4:5]
	s_waitcnt lgkmcnt(0)
	v_cvt_pk_bf16_f32 v0, v6, v7
	v_cvt_pk_bf16_f32 v1, v10, v11
	v_cvt_pk_bf16_f32 v2, v12, v13
	v_cvt_pk_bf16_f32 v3, v14, v15
	v_lshl_add_u64 v[4:5], v[8:9], 0, v[4:5]
	ds_read2st64_b32 v[6:7], v47 offset1:4
	ds_read2st64_b32 v[10:11], v47 offset0:8 offset1:12
	ds_read2st64_b32 v[12:13], v47 offset0:16 offset1:20
	ds_read2st64_b32 v[14:15], v47 offset0:24 offset1:28
	global_store_dwordx4 v[4:5], v[0:3], off
	v_add_u32_e32 v4, s40, v46
	v_ashrrev_i32_e32 v5, 31, v4
	v_lshlrev_b64 v[4:5], 12, v[4:5]
	s_add_i32 s0, s0, s20
	s_add_i32 s1, s1, s3
	v_lshl_add_u64 v[4:5], v[8:9], 0, v[4:5]
	s_cmpk_lt_i32 s0, 0x100
	s_waitcnt lgkmcnt(0)
	v_cvt_pk_bf16_f32 v0, v6, v7
	v_cvt_pk_bf16_f32 v1, v10, v11
	v_cvt_pk_bf16_f32 v2, v12, v13
	v_cvt_pk_bf16_f32 v3, v14, v15
	global_store_dwordx4 v[4:5], v[0:3], off
	s_waitcnt lgkmcnt(0)
	s_barrier
	s_cbranch_scc0 .LBB0_64

; #define LAS __attribute__((address_space(3)))
; __device__ __forceinline__ unsigned cvt_pk_bf16(float lo, float hi) { unsigned r; asm("v_cvt_pk_bf16_f32 %0, %1, %2" : "=v"(r) : "v"(lo), "v"(hi)); return r; }
; __device__ __forceinline__ int otid() { int t = threadIdx.x; asm volatile("" : "+v"(t)); return t; }
; __device__ __forceinline__ int obid() { extern __shared__ __attribute__((aligned(16))) unsigned char shm_vb[]; return __builtin_amdgcn_readfirstlane(*(volatile LAS int*)((LAS unsigned char*)shm_vb + VB_OFF)); }
; #define IN(i) ((const float*)karg(i))
; #define WSB(off) ((bf16_t*)((unsigned char*)karg(15) + (off)))
; __device__ __forceinline__ void phase_wT(const float* __restrict__ src, int ldn, int n0, int K, int N, bf16_t* __restrict__ dst, LAS float* tile, const float* __restrict__ gain = nullptr) {
;   const int tk = K / 64, tn = N / 256, nt = tk * tn, t = otid(), w = t >> 6, lane = t & 63;
;   for (int ti = obid(); ti < nt; ti += gridDim.x) {
;     const int kt = ti % tk, ntile = ti / tk;
;     float4 v[8];
; #pragma unroll
;     for (int i = 0; i < 8; ++i) v[i] = *(const float4*)(src + (size_t)(kt * 64 + w + 8 * i) * ldn + n0 + ntile * 256 + lane * 4);
;     if (gain) {
; #pragma unroll
;       for (int i = 0; i < 8; ++i) { const float gk = gain[kt * 64 + w + 8 * i]; v[i].x *= gk; v[i].y *= gk; v[i].z *= gk; v[i].w *= gk; }
;     }
; #pragma unroll
;     for (int i = 0; i < 8; ++i) { const int k = w + 8 * i; *(LAS f32x4*)(tile + k * 256 + ((lane ^ (i & 7)) << 2)) = (f32x4){v[i].x, v[i].y, v[i].z, v[i].w}; }
;     __syncthreads();
;     const int nr = t >> 3, kc = (t & 7) * 8, ksw = (t & 7);
; #pragma unroll
;     for (int p = 0; p < 4; ++p) {
;       const int n = p * 64 + nr;
;       const LAS float* sp = tile + kc * 256 + ((((n >> 2) ^ ksw)) << 2) + (n & 3);
;       uint4 o; o.x = cvt_pk_bf16(sp[0], sp[256]); o.y = cvt_pk_bf16(sp[512], sp[768]); o.z = cvt_pk_bf16(sp[1024], sp[1280]); o.w = cvt_pk_bf16(sp[1536], sp[1792]);
;       *(uint4*)(dst + (size_t)(ntile * 256 + n) * K + kt * 64 + kc) = o;
;     }
;     __syncthreads();
;   }
; }
; __global__ void __launch_bounds__(512, 2) mega(Params p) {
;     ...
;       phase_wT(IN(5) + (size_t)j * 2048 * 20480, 20480, 12288, 2048, 6144, WSB(WS_WA) + (size_t)14336 * 2048, tile, IN(4) + layer * DM);
.LBB0_64:
	v_readlane_b32 s0, v255, 0
	v_readlane_b32 s1, v255, 1
	s_nop 1
	v_mov_b64_e32 v[0:1], s[0:1]
	global_load_dwordx2 v[2:3], v[0:1], off offset:40 sc0 sc1
	s_waitcnt vmcnt(0)
	global_load_dwordx2 v[4:5], v[0:1], off offset:120 sc0 sc1
	s_waitcnt vmcnt(0)
	global_load_dwordx2 v[6:7], v[0:1], off offset:32 sc0 sc1
	s_waitcnt vmcnt(0)
	v_mov_b32_e32 v0, v252
	v_mov_b32_e32 v1, s74
	ds_read_b32 v1, v1
	s_waitcnt lgkmcnt(0)
	v_readfirstlane_b32 s0, v1
	s_cmpk_gt_i32 s0, 0x2ff
	v_readfirstlane_b32 s1, v3
	v_readfirstlane_b32 s3, v2
	v_readfirstlane_b32 s39, v5
	v_readfirstlane_b32 s38, v4
	v_readfirstlane_b32 s19, v7
	v_readfirstlane_b32 s18, v6
	s_cbranch_scc1 .LBB0_69
	s_lshl_b64 s[28:29], s[6:7], 2
	s_add_u32 s36, s18, s28
	s_addc_u32 s37, s19, s29
	s_lshl_b64 s[8:9], s[8:9], 2
	s_add_u32 s8, s3, s8
	v_lshlrev_b32_e32 v4, 4, v0
	s_addc_u32 s9, s1, s9
	v_and_b32_e32 v80, 0x3f0, v4
	v_lshl_add_u64 v[2:3], s[8:9], 0, v[80:81]
	s_mov_b64 s[8:9], 0xc000
	v_ashrrev_i32_e32 v40, 3, v0
	v_ashrrev_i32_e32 v38, 6, v0
	v_lshl_add_u64 v[32:33], v[2:3], 0, s[8:9]
	v_and_b32_e32 v0, 7, v0
	v_lshlrev_b32_e32 v3, 2, v40
	v_lshlrev_b32_e32 v1, 13, v0
	v_and_b32_e32 v3, 12, v3
	v_lshlrev_b32_e32 v2, 2, v0
	v_add3_u32 v3, 0, v1, v3
	v_lshlrev_b32_e32 v0, 4, v0
	v_mov_b32_e32 v1, v81
	v_mov_b32_e32 v9, 0x3f0
	s_movk_i32 s3, 0x50
	s_cmp_lg_u64 s[18:19], 0
	v_lshl_add_u64 v[0:1], s[38:39], 0, v[0:1]
	s_mov_b64 s[18:19], 0x3800000
	s_mov_b32 s1, 0x3ffffffc
	v_bitop3_b32 v7, v4, s3, v9 bitop3:0x6c
	s_movk_i32 s3, 0x60
	v_lshl_add_u64 v[34:35], v[0:1], 0, s[18:19]
	v_bitop3_b32 v0, v40, v2, s1 bitop3:0x6c
	v_bitop3_b32 v8, v4, s3, v9 bitop3:0x6c
	s_movk_i32 s3, 0x70
	v_add_u32_e32 v42, 64, v40
	v_lshl_add_u32 v41, v0, 2, v3
	v_bitop3_b32 v0, v4, 16, v9 bitop3:0x6c
	v_bitop3_b32 v1, v4, 32, v9 bitop3:0x6c
	v_bitop3_b32 v5, v4, 48, v9 bitop3:0x6c
	v_bitop3_b32 v6, v4, 64, v9 bitop3:0x6c
	v_bitop3_b32 v4, v4, s3, v9 bitop3:0x6c
	v_bitop3_b32 v9, v42, v2, s1 bitop3:0x6c
	v_add_u32_e32 v44, 0x80, v40
	v_add_u32_e32 v46, 0xc0, v40
	v_lshl_add_u32 v39, v38, 10, 0
	v_lshl_add_u32 v43, v9, 2, v3
	v_bitop3_b32 v9, v44, v2, s1 bitop3:0x6c
	v_bitop3_b32 v2, v46, v2, s1 bitop3:0x6c
	s_cselect_b64 s[8:9], -1, 0
	v_lshl_add_u32 v45, v9, 2, v3
	v_lshl_add_u32 v47, v2, 2, v3
	s_lshl_b32 s1, s0, 6
	s_lshl_b32 s3, s20, 6
	v_add_u32_e32 v48, v39, v0
	v_add_u32_e32 v49, v39, v1
	v_add_u32_e32 v50, v39, v5
	v_add_u32_e32 v51, v39, v6
	v_add_u32_e32 v52, v39, v7
	v_add_u32_e32 v53, v39, v8
	v_add_u32_e32 v54, v39, v4
	s_branch .LBB0_67
.LBB0_66:
	v_add_u32_e32 v36, v39, v80
	s_waitcnt vmcnt(0) lgkmcnt(0)
	ds_write_b128 v36, v[4:7]
	ds_write_b128 v48, v[0:3] offset:8192
	ds_write_b128 v49, v[12:15] offset:16384
	ds_write_b128 v50, v[8:11] offset:24576
	ds_write_b128 v51, v[20:23] offset:32768
	ds_write_b128 v52, v[16:19] offset:40960
	ds_write_b128 v53, v[28:31] offset:49152
	ds_write_b128 v54, v[24:27] offset:57344
	s_waitcnt lgkmcnt(0)
	s_barrier
	ds_read2st64_b32 v[0:1], v41 offset1:4
	ds_read2st64_b32 v[2:3], v41 offset0:8 offset1:12
	ds_read2st64_b32 v[4:5], v41 offset0:16 offset1:20
	ds_read2st64_b32 v[6:7], v41 offset0:24 offset1:28
	s_sub_i32 s5, 0, s5
	s_add_i32 s18, s1, s5
	s_waitcnt lgkmcnt(3)
	v_cvt_pk_bf16_f32 v0, v0, v1
	s_waitcnt lgkmcnt(2)
	v_cvt_pk_bf16_f32 v1, v2, v3
	s_waitcnt lgkmcnt(1)
	v_cvt_pk_bf16_f32 v2, v4, v5
	v_add_u32_e32 v4, s38, v40
	s_ashr_i32 s19, s18, 31
	s_waitcnt lgkmcnt(0)
	v_cvt_pk_bf16_f32 v3, v6, v7
	v_ashrrev_i32_e32 v5, 31, v4
	ds_read2st64_b32 v[6:7], v43 offset1:4
	ds_read2st64_b32 v[10:11], v43 offset0:8 offset1:12
	ds_read2st64_b32 v[12:13], v43 offset0:16 offset1:20
	ds_read2st64_b32 v[14:15], v43 offset0:24 offset1:28
	v_lshl_add_u64 v[8:9], s[18:19], 1, v[34:35]
	v_lshlrev_b64 v[4:5], 12, v[4:5]
	v_lshl_add_u64 v[4:5], v[8:9], 0, v[4:5]
	global_store_dwordx4 v[4:5], v[0:3], off
	v_add_u32_e32 v4, s38, v42
	v_ashrrev_i32_e32 v5, 31, v4
	s_waitcnt lgkmcnt(0)
	v_cvt_pk_bf16_f32 v0, v6, v7
	v_cvt_pk_bf16_f32 v1, v10, v11
	v_cvt_pk_bf16_f32 v2, v12, v13
	v_cvt_pk_bf16_f32 v3, v14, v15
	v_lshlrev_b64 v[4:5], 12, v[4:5]
	ds_read2st64_b32 v[6:7], v45 offset1:4
	ds_read2st64_b32 v[10:11], v45 offset0:8 offset1:12
	ds_read2st64_b32 v[12:13], v45 offset0:16 offset1:20
	ds_read2st64_b32 v[14:15], v45 offset0:24 offset1:28
	v_lshl_add_u64 v[4:5], v[8:9], 0, v[4:5]
	global_store_dwordx4 v[4:5], v[0:3], off
	v_add_u32_e32 v4, s38, v44
	v_ashrrev_i32_e32 v5, 31, v4
	v_lshlrev_b64 v[4:5], 12, v[4:5]
	s_waitcnt lgkmcnt(0)
	v_cvt_pk_bf16_f32 v0, v6, v7
	v_cvt_pk_bf16_f32 v1, v10, v11
	v_cvt_pk_bf16_f32 v2, v12, v13
	v_cvt_pk_bf16_f32 v3, v14, v15
	v_lshl_add_u64 v[4:5], v[8:9], 0, v[4:5]
	ds_read2st64_b32 v[6:7], v47 offset1:4
	ds_read2st64_b32 v[10:11], v47 offset0:8 offset1:12
	ds_read2st64_b32 v[12:13], v47 offset0:16 offset1:20
	ds_read2st64_b32 v[14:15], v47 offset0:24 offset1:28
	global_store_dwordx4 v[4:5], v[0:3], off
	v_add_u32_e32 v4, s38, v46
	v_ashrrev_i32_e32 v5, 31, v4
	v_lshlrev_b64 v[4:5], 12, v[4:5]
	s_add_i32 s0, s0, s20
	s_add_i32 s1, s1, s3
	v_lshl_add_u64 v[4:5], v[8:9], 0, v[4:5]
	s_cmpk_lt_i32 s0, 0x300
	s_waitcnt lgkmcnt(0)
	v_cvt_pk_bf16_f32 v0, v6, v7
	v_cvt_pk_bf16_f32 v1, v10, v11
	v_cvt_pk_bf16_f32 v2, v12, v13
	v_cvt_pk_bf16_f32 v3, v14, v15
	global_store_dwordx4 v[4:5], v[0:3], off
	s_waitcnt lgkmcnt(0)
	s_barrier
	s_cbranch_scc0 .LBB0_69
; #define IN(i) ((const float*)karg(i))
; #define WSB(off) ((bf16_t*)((unsigned char*)karg(15) + (off)))
; __device__ __forceinline__ void phase_wT(const float* __restrict__ src, int ldn, int n0, int K, int N, bf16_t* __restrict__ dst, LAS float* tile, const float* __restrict__ gain = nullptr) {
;     ...
;     float4 v[8];
; #pragma unroll
;     for (int i = 0; i < 8; ++i) v[i] = *(const float4*)(src + (size_t)(kt * 64 + w + 8 * i) * ldn + n0 + ntile * 256 + lane * 4);
;     if (gain) {
; #pragma unroll
;       for (int i = 0; i < 8; ++i) { const float gk = gain[kt * 64 + w + 8 * i]; v[i].x *= gk; v[i].y *= gk; v[i].z *= gk; v[i].w *= gk; }
;     }
; __global__ void __launch_bounds__(512, 2) mega(Params p) {
;     ...
;       phase_wT(IN(8) + (size_t)j * 2048 * 2048, 2048, 0, 2048, 2048, WSB(WS_WB), tile);
.LBB0_67:
	s_ashr_i32 s5, s0, 31
	s_lshr_b32 s5, s5, 27
	s_add_i32 s5, s0, s5
	s_ashr_i32 s13, s5, 5
	s_lshl_b32 s5, s13, 11
	s_sub_i32 s17, s1, s5
	s_lshl_b32 s38, s13, 8
	v_add_u32_e32 v36, s17, v38
	s_ashr_i32 s39, s38, 31
	v_lshl_add_u64 v[24:25], s[38:39], 2, v[32:33]
	s_mov_b32 s13, 0x14000
	v_add_u32_e32 v2, 8, v36
	v_add_u32_e32 v8, 16, v36
	v_add_u32_e32 v10, 24, v36
	v_add_u32_e32 v16, 32, v36
	v_add_u32_e32 v18, 40, v36
	v_add_u32_e32 v26, 48, v36
	v_add_u32_e32 v28, 56, v36
	v_mad_i64_i32 v[0:1], s[18:19], v36, s13, v[24:25]
	v_mad_i64_i32 v[2:3], s[18:19], v2, s13, v[24:25]
	v_mad_i64_i32 v[8:9], s[18:19], v8, s13, v[24:25]
	v_mad_i64_i32 v[10:11], s[18:19], v10, s13, v[24:25]
	v_mad_i64_i32 v[16:17], s[18:19], v16, s13, v[24:25]
	v_mad_i64_i32 v[18:19], s[18:19], v18, s13, v[24:25]
	v_mad_i64_i32 v[26:27], s[18:19], v26, s13, v[24:25]
	v_mad_i64_i32 v[24:25], s[18:19], v28, s13, v[24:25]
	global_load_dwordx4 v[4:7], v[0:1], off
	s_nop 0
	global_load_dwordx4 v[0:3], v[2:3], off
	s_nop 0
	global_load_dwordx4 v[12:15], v[8:9], off
	s_nop 0
	global_load_dwordx4 v[8:11], v[10:11], off
	s_nop 0
	global_load_dwordx4 v[20:23], v[16:17], off
	s_nop 0
	global_load_dwordx4 v[16:19], v[18:19], off
	s_nop 0
	global_load_dwordx4 v[28:31], v[26:27], off
	s_nop 0
	global_load_dwordx4 v[24:27], v[24:25], off
	s_andn2_b64 vcc, exec, s[8:9]
	s_cbranch_vccnz .LBB0_66
	v_ashrrev_i32_e32 v37, 31, v36
	v_lshl_add_u64 v[36:37], v[36:37], 2, s[36:37]
	global_load_dword v56, v[36:37], off
	global_load_dword v58, v[36:37], off offset:32
	global_load_dword v60, v[36:37], off offset:64
	global_load_dword v62, v[36:37], off offset:96
	global_load_dword v64, v[36:37], off offset:128
	global_load_dword v66, v[36:37], off offset:160
	global_load_dword v68, v[36:37], off offset:192
	s_nop 0
	global_load_dword v36, v[36:37], off offset:224
	s_waitcnt vmcnt(0) lgkmcnt(0)
	v_pk_mul_f32 v[4:5], v[4:5], v[56:57] op_sel_hi:[1,0]
	v_pk_mul_f32 v[6:7], v[6:7], v[56:57] op_sel_hi:[1,0]
	v_pk_mul_f32 v[0:1], v[0:1], v[58:59] op_sel_hi:[1,0]
	v_pk_mul_f32 v[2:3], v[2:3], v[58:59] op_sel_hi:[1,0]
	v_pk_mul_f32 v[12:13], v[12:13], v[60:61] op_sel_hi:[1,0]
	v_pk_mul_f32 v[14:15], v[14:15], v[60:61] op_sel_hi:[1,0]
	v_pk_mul_f32 v[8:9], v[8:9], v[62:63] op_sel_hi:[1,0]
	v_pk_mul_f32 v[10:11], v[10:11], v[62:63] op_sel_hi:[1,0]
	v_pk_mul_f32 v[20:21], v[20:21], v[64:65] op_sel_hi:[1,0]
	v_pk_mul_f32 v[22:23], v[22:23], v[64:65] op_sel_hi:[1,0]
	v_pk_mul_f32 v[16:17], v[16:17], v[66:67] op_sel_hi:[1,0]
	v_pk_mul_f32 v[18:19], v[18:19], v[66:67] op_sel_hi:[1,0]
	v_pk_mul_f32 v[28:29], v[28:29], v[68:69] op_sel_hi:[1,0]
	v_pk_mul_f32 v[30:31], v[30:31], v[68:69] op_sel_hi:[1,0]
	v_pk_mul_f32 v[24:25], v[24:25], v[36:37] op_sel_hi:[1,0]
	v_pk_mul_f32 v[26:27], v[26:27], v[36:37] op_sel_hi:[1,0]
	s_branch .LBB0_66
.LBB0_69:
	v_readlane_b32 s0, v255, 0
	v_readlane_b32 s1, v255, 1
	v_mov_b32_e32 v2, v252
	v_mov_b32_e32 v3, s74
	v_mov_b64_e32 v[0:1], s[0:1]
	global_load_dwordx2 v[4:5], v[0:1], off offset:64 sc0 sc1
	s_waitcnt vmcnt(0)
	global_load_dwordx2 v[0:1], v[0:1], off offset:120 sc0 sc1
	s_waitcnt vmcnt(0)
	ds_read_b32 v3, v3
	s_waitcnt lgkmcnt(0)
	v_readfirstlane_b32 s0, v3
	s_cmpk_gt_i32 s0, 0xff
	v_readfirstlane_b32 s1, v5
	v_readfirstlane_b32 s5, v4
	v_readfirstlane_b32 s9, v1
	v_readfirstlane_b32 s8, v0
	s_cbranch_scc1 .LBB0_72
	s_mov_b32 s3, s12
	v_ashrrev_i32_e32 v6, 3, v2
	v_ashrrev_i32_e32 v4, 6, v2
	s_lshl_b64 s[2:3], s[2:3], 13
	v_lshlrev_b32_e32 v8, 4, v2
	v_and_b32_e32 v2, 7, v2
	v_lshlrev_b32_e32 v7, 2, v6
	s_add_u32 s2, s5, s2
	v_lshlrev_b32_e32 v3, 13, v2
	v_and_b32_e32 v7, 12, v7
	s_addc_u32 s3, s1, s3
	v_and_b32_e32 v80, 0x3f0, v8
	v_lshlrev_b32_e32 v13, 2, v2
	v_add3_u32 v14, 0, v3, v7
	v_lshlrev_b32_e32 v2, 4, v2
	v_mov_b32_e32 v3, v81
	v_lshl_add_u64 v[0:1], s[2:3], 0, v[80:81]
	v_lshl_add_u64 v[2:3], s[8:9], 0, v[2:3]
	s_mov_b64 s[2:3], 0x5000000
	v_lshl_add_u64 v[2:3], v[2:3], 0, s[2:3]
	v_mov_b32_e32 v9, 0x3f0
	s_movk_i32 s2, 0x50
	v_bitop3_b32 v19, v8, s2, v9 bitop3:0x6c
	s_movk_i32 s2, 0x60
	v_bitop3_b32 v20, v8, s2, v9 bitop3:0x6c
	s_movk_i32 s2, 0x70
	s_mov_b32 s1, 0x3ffffffc
	v_bitop3_b32 v15, v8, 16, v9 bitop3:0x6c
	v_bitop3_b32 v16, v8, 32, v9 bitop3:0x6c
	v_bitop3_b32 v17, v8, 48, v9 bitop3:0x6c
	v_bitop3_b32 v18, v8, 64, v9 bitop3:0x6c
	v_bitop3_b32 v21, v8, s2, v9 bitop3:0x6c
	v_add_u32_e32 v8, 64, v6
	v_add_u32_e32 v10, 0x80, v6
	v_add_u32_e32 v12, 0xc0, v6
	v_lshl_add_u32 v5, v4, 10, 0
	v_bitop3_b32 v7, v6, v13, s1 bitop3:0x6c
	v_bitop3_b32 v9, v8, v13, s1 bitop3:0x6c
	v_bitop3_b32 v11, v10, v13, s1 bitop3:0x6c
	v_bitop3_b32 v13, v12, v13, s1 bitop3:0x6c
	v_lshl_add_u32 v7, v7, 2, v14
	v_lshl_add_u32 v9, v9, 2, v14
	v_lshl_add_u32 v11, v11, 2, v14
	v_lshl_add_u32 v13, v13, 2, v14
	s_lshl_b32 s1, s0, 6
	s_lshl_b32 s5, s20, 6
	v_add_u32_e32 v14, v5, v15
	v_add_u32_e32 v15, v5, v16
	v_add_u32_e32 v16, v5, v17
	v_add_u32_e32 v17, v5, v18
	v_add_u32_e32 v18, v5, v19
	v_add_u32_e32 v19, v5, v20
	v_add_u32_e32 v20, v5, v21
; #define LAS __attribute__((address_space(3)))
; __device__ __forceinline__ unsigned cvt_pk_bf16(float lo, float hi) { unsigned r; asm("v_cvt_pk_bf16_f32 %0, %1, %2" : "=v"(r) : "v"(lo), "v"(hi)); return r; }
; __device__ __forceinline__ int otid() { int t = threadIdx.x; asm volatile("" : "+v"(t)); return t; }
; __device__ __forceinline__ int obid() { extern __shared__ __attribute__((aligned(16))) unsigned char shm_vb[]; return __builtin_amdgcn_readfirstlane(*(volatile LAS int*)((LAS unsigned char*)shm_vb + VB_OFF)); }
; __device__ __forceinline__ void phase_wT(const float* __restrict__ src, int ldn, int n0, int K, int N, bf16_t* __restrict__ dst, LAS float* tile, const float* __restrict__ gain = nullptr) {
;   const int tk = K / 64, tn = N / 256, nt = tk * tn, t = otid(), w = t >> 6, lane = t & 63;
;   for (int ti = obid(); ti < nt; ti += gridDim.x) {
;     const int kt = ti % tk, ntile = ti / tk;
;     float4 v[8];
; #pragma unroll
;     for (int i = 0; i < 8; ++i) v[i] = *(const float4*)(src + (size_t)(kt * 64 + w + 8 * i) * ldn + n0 + ntile * 256 + lane * 4);
;     if (gain) {
; #pragma unroll
;       for (int i = 0; i < 8; ++i) { const float gk = gain[kt * 64 + w + 8 * i]; v[i].x *= gk; v[i].y *= gk; v[i].z *= gk; v[i].w *= gk; }
;     }
; #pragma unroll
;     for (int i = 0; i < 8; ++i) { const int k = w + 8 * i; *(LAS f32x4*)(tile + k * 256 + ((lane ^ (i & 7)) << 2)) = (f32x4){v[i].x, v[i].y, v[i].z, v[i].w}; }
;     __syncthreads();
;     const int nr = t >> 3, kc = (t & 7) * 8, ksw = (t & 7);
; #pragma unroll
;     for (int p = 0; p < 4; ++p) {
;       const int n = p * 64 + nr;
;       const LAS float* sp = tile + kc * 256 + ((((n >> 2) ^ ksw)) << 2) + (n & 3);
;       uint4 o; o.x = cvt_pk_bf16(sp[0], sp[256]); o.y = cvt_pk_bf16(sp[512], sp[768]); o.z = cvt_pk_bf16(sp[1024], sp[1280]); o.w = cvt_pk_bf16(sp[1536], sp[1792]);
;       *(uint4*)(dst + (size_t)(ntile * 256 + n) * K + kt * 64 + kc) = o;
;     }
;     __syncthreads();
;   }
; }
.LBB0_71:
	s_ashr_i32 s2, s0, 31
	s_lshr_b32 s2, s2, 27
	s_add_i32 s2, s0, s2
	s_ashr_i32 s2, s2, 5
	s_lshl_b32 s3, s2, 11
	s_lshl_b32 s8, s2, 8
	s_sub_i32 s2, s1, s3
	v_add_u32_e32 v22, s2, v4
	v_add_u32_e32 v26, 8, v22
	v_add_u32_e32 v28, 16, v22
	v_add_u32_e32 v30, 24, v22
	v_add_u32_e32 v32, 32, v22
	v_add_u32_e32 v34, 40, v22
	v_add_u32_e32 v36, 48, v22
	v_add_u32_e32 v38, 56, v22
	s_ashr_i32 s9, s8, 31
	v_ashrrev_i32_e32 v23, 31, v22
	v_ashrrev_i32_e32 v27, 31, v26
	v_ashrrev_i32_e32 v29, 31, v28
	v_ashrrev_i32_e32 v31, 31, v30
	v_ashrrev_i32_e32 v33, 31, v32
	v_ashrrev_i32_e32 v35, 31, v34
	v_ashrrev_i32_e32 v37, 31, v36
	v_ashrrev_i32_e32 v39, 31, v38
	v_lshl_add_u64 v[24:25], s[8:9], 2, v[0:1]
	v_lshlrev_b64 v[22:23], 13, v[22:23]
	v_lshlrev_b64 v[26:27], 13, v[26:27]
	v_lshlrev_b64 v[28:29], 13, v[28:29]
	v_lshlrev_b64 v[30:31], 13, v[30:31]
	v_lshlrev_b64 v[32:33], 13, v[32:33]
	v_lshlrev_b64 v[34:35], 13, v[34:35]
	v_lshlrev_b64 v[36:37], 13, v[36:37]
	v_lshlrev_b64 v[38:39], 13, v[38:39]
	v_lshl_add_u64 v[22:23], v[24:25], 0, v[22:23]
	v_lshl_add_u64 v[26:27], v[24:25], 0, v[26:27]
	v_lshl_add_u64 v[40:41], v[24:25], 0, v[28:29]
	v_lshl_add_u64 v[42:43], v[24:25], 0, v[30:31]
	v_lshl_add_u64 v[44:45], v[24:25], 0, v[32:33]
	v_lshl_add_u64 v[46:47], v[24:25], 0, v[34:35]
	v_lshl_add_u64 v[48:49], v[24:25], 0, v[36:37]
	v_lshl_add_u64 v[50:51], v[24:25], 0, v[38:39]
	global_load_dwordx4 v[22:25], v[22:23], off
	s_nop 0
	global_load_dwordx4 v[26:29], v[26:27], off
	s_nop 0
	global_load_dwordx4 v[30:33], v[40:41], off
	global_load_dwordx4 v[34:37], v[42:43], off
	s_nop 0
	global_load_dwordx4 v[38:41], v[44:45], off
	s_nop 0
	global_load_dwordx4 v[42:45], v[46:47], off
	s_nop 0
	global_load_dwordx4 v[46:49], v[48:49], off
	s_nop 0
	global_load_dwordx4 v[50:53], v[50:51], off
	v_add_u32_e32 v21, v5, v80
	v_add_u32_e32 v54, s8, v6
	v_add_u32_e32 v56, s8, v8
	v_add_u32_e32 v58, s8, v10
	v_add_u32_e32 v60, s8, v12
	s_ashr_i32 s3, s2, 31
	v_ashrrev_i32_e32 v55, 31, v54
	s_add_i32 s0, s0, s20
	s_add_i32 s1, s1, s5
	v_ashrrev_i32_e32 v57, 31, v56
	v_ashrrev_i32_e32 v59, 31, v58
	v_ashrrev_i32_e32 v61, 31, v60
	v_lshl_add_u64 v[62:63], s[2:3], 1, v[2:3]
	v_lshlrev_b64 v[54:55], 12, v[54:55]
	v_lshlrev_b64 v[56:57], 12, v[56:57]
	v_lshlrev_b64 v[58:59], 12, v[58:59]
	v_lshlrev_b64 v[60:61], 12, v[60:61]
	s_cmpk_gt_i32 s0, 0xff
	v_lshl_add_u64 v[54:55], v[62:63], 0, v[54:55]
	v_lshl_add_u64 v[56:57], v[62:63], 0, v[56:57]
	v_lshl_add_u64 v[58:59], v[62:63], 0, v[58:59]
	v_lshl_add_u64 v[60:61], v[62:63], 0, v[60:61]
	s_waitcnt vmcnt(0) lgkmcnt(0)
	ds_write_b128 v21, v[22:25]
	ds_write_b128 v14, v[26:29] offset:8192
	ds_write_b128 v15, v[30:33] offset:16384
	ds_write_b128 v16, v[34:37] offset:24576
	ds_write_b128 v17, v[38:41] offset:32768
	ds_write_b128 v18, v[42:45] offset:40960
	ds_write_b128 v19, v[46:49] offset:49152
	ds_write_b128 v20, v[50:53] offset:57344
	s_waitcnt lgkmcnt(0)
	s_barrier
	ds_read2st64_b32 v[22:23], v7 offset1:4
	ds_read2st64_b32 v[24:25], v7 offset0:8 offset1:12
	ds_read2st64_b32 v[26:27], v7 offset0:16 offset1:20
	ds_read2st64_b32 v[28:29], v7 offset0:24 offset1:28
	ds_read2st64_b32 v[30:31], v9 offset1:4
	ds_read2st64_b32 v[32:33], v9 offset0:8 offset1:12
	ds_read2st64_b32 v[34:35], v9 offset0:16 offset1:20
	ds_read2st64_b32 v[36:37], v9 offset0:24 offset1:28
	ds_read2st64_b32 v[38:39], v11 offset1:4
	ds_read2st64_b32 v[40:41], v11 offset0:8 offset1:12
	ds_read2st64_b32 v[42:43], v11 offset0:16 offset1:20
	ds_read2st64_b32 v[44:45], v11 offset0:24 offset1:28
	ds_read2st64_b32 v[46:47], v13 offset1:4
	ds_read2st64_b32 v[48:49], v13 offset0:8 offset1:12
	ds_read2st64_b32 v[50:51], v13 offset0:16 offset1:20
	ds_read2st64_b32 v[52:53], v13 offset0:24 offset1:28
	s_waitcnt lgkmcnt(14)
	v_cvt_pk_bf16_f32 v22, v22, v23
	v_cvt_pk_bf16_f32 v23, v24, v25
	s_waitcnt lgkmcnt(13)
	v_cvt_pk_bf16_f32 v24, v26, v27
	s_waitcnt lgkmcnt(12)
	v_cvt_pk_bf16_f32 v25, v28, v29
	s_waitcnt lgkmcnt(11)
	v_cvt_pk_bf16_f32 v26, v30, v31
	s_waitcnt lgkmcnt(10)
	v_cvt_pk_bf16_f32 v27, v32, v33
	s_waitcnt lgkmcnt(9)
	v_cvt_pk_bf16_f32 v28, v34, v35
	s_waitcnt lgkmcnt(8)
	v_cvt_pk_bf16_f32 v29, v36, v37
	s_waitcnt lgkmcnt(7)
	v_cvt_pk_bf16_f32 v30, v38, v39
	s_waitcnt lgkmcnt(6)
	v_cvt_pk_bf16_f32 v31, v40, v41
	s_waitcnt lgkmcnt(5)
	v_cvt_pk_bf16_f32 v32, v42, v43
	s_waitcnt lgkmcnt(4)
	v_cvt_pk_bf16_f32 v33, v44, v45
	s_waitcnt lgkmcnt(3)
	v_cvt_pk_bf16_f32 v34, v46, v47
	s_waitcnt lgkmcnt(2)
	v_cvt_pk_bf16_f32 v35, v48, v49
	s_waitcnt lgkmcnt(1)
	v_cvt_pk_bf16_f32 v36, v50, v51
	s_waitcnt lgkmcnt(0)
	v_cvt_pk_bf16_f32 v37, v52, v53
	global_store_dwordx4 v[54:55], v[22:25], off
	global_store_dwordx4 v[56:57], v[26:29], off
	global_store_dwordx4 v[58:59], v[30:33], off
	global_store_dwordx4 v[60:61], v[34:37], off
	s_waitcnt lgkmcnt(0)
	s_barrier
	s_cbranch_scc0 .LBB0_71
; #define LAS __attribute__((address_space(3)))
; __device__ __forceinline__ unsigned cvt_pk_bf16(float lo, float hi) { unsigned r; asm("v_cvt_pk_bf16_f32 %0, %1, %2" : "=v"(r) : "v"(lo), "v"(hi)); return r; }
; __device__ __forceinline__ int otid() { int t = threadIdx.x; asm volatile("" : "+v"(t)); return t; }
; __device__ __forceinline__ int obid() { extern __shared__ __attribute__((aligned(16))) unsigned char shm_vb[]; return __builtin_amdgcn_readfirstlane(*(volatile LAS int*)((LAS unsigned char*)shm_vb + VB_OFF)); }
; #define IN(i) ((const float*)karg(i))
; #define WSB(off) ((bf16_t*)((unsigned char*)karg(15) + (off)))
; __device__ __forceinline__ void phase_wT(const float* __restrict__ src, int ldn, int n0, int K, int N, bf16_t* __restrict__ dst, LAS float* tile, const float* __restrict__ gain = nullptr) {
;   const int tk = K / 64, tn = N / 256, nt = tk * tn, t = otid(), w = t >> 6, lane = t & 63;
;   for (int ti = obid(); ti < nt; ti += gridDim.x) {
;     const int kt = ti % tk, ntile = ti / tk;
;     float4 v[8];
; #pragma unroll
;     for (int i = 0; i < 8; ++i) v[i] = *(const float4*)(src + (size_t)(kt * 64 + w + 8 * i) * ldn + n0 + ntile * 256 + lane * 4);
;     if (gain) {
; #pragma unroll
;       for (int i = 0; i < 8; ++i) { const float gk = gain[kt * 64 + w + 8 * i]; v[i].x *= gk; v[i].y *= gk; v[i].z *= gk; v[i].w *= gk; }
;     }
; #pragma unroll
;     for (int i = 0; i < 8; ++i) { const int k = w + 8 * i; *(LAS f32x4*)(tile + k * 256 + ((lane ^ (i & 7)) << 2)) = (f32x4){v[i].x, v[i].y, v[i].z, v[i].w}; }
;     __syncthreads();
;     const int nr = t >> 3, kc = (t & 7) * 8, ksw = (t & 7);
; #pragma unroll
;     for (int p = 0; p < 4; ++p) {
;       const int n = p * 64 + nr;
;       const LAS float* sp = tile + kc * 256 + ((((n >> 2) ^ ksw)) << 2) + (n & 3);
;       uint4 o; o.x = cvt_pk_bf16(sp[0], sp[256]); o.y = cvt_pk_bf16(sp[512], sp[768]); o.z = cvt_pk_bf16(sp[1024], sp[1280]); o.w = cvt_pk_bf16(sp[1536], sp[1792]);
;       *(uint4*)(dst + (size_t)(ntile * 256 + n) * K + kt * 64 + kc) = o;
;     }
;     __syncthreads();
;   }
; }
; __global__ void __launch_bounds__(512, 2) mega(Params p) {
;     ...
;     phase_wT(IN(12) + (size_t)layer * 2048 * 2048, 2048, 0, 2048, 2048, WSB(WS_WC), tile, IN(13) + layer * DM);
.LBB0_72:
	v_readlane_b32 s0, v255, 0
	v_readlane_b32 s1, v255, 1
	s_nop 1
	v_mov_b64_e32 v[0:1], s[0:1]
	global_load_dwordx2 v[2:3], v[0:1], off offset:96 sc0 sc1
	s_waitcnt vmcnt(0)
	global_load_dwordx2 v[4:5], v[0:1], off offset:120 sc0 sc1
	s_waitcnt vmcnt(0)
	global_load_dwordx2 v[6:7], v[0:1], off offset:104 sc0 sc1
	s_waitcnt vmcnt(0)
	v_mov_b32_e32 v0, v252
	v_mov_b32_e32 v1, s74
	ds_read_b32 v1, v1
	s_mov_b32 s0, s22
	s_mov_b32 s1, s12
	v_writelane_b32 v255, s0, 28
	s_waitcnt lgkmcnt(0)
	v_readfirstlane_b32 s5, v2
	v_writelane_b32 v255, s1, 29
	s_lshl_b64 s[0:1], s[0:1], 24
	v_writelane_b32 v255, s0, 30
	v_readfirstlane_b32 s9, v5
	v_readfirstlane_b32 s8, v4
	v_writelane_b32 v255, s1, 31
	v_readfirstlane_b32 s0, v1
	s_cmpk_gt_i32 s0, 0xff
	v_readfirstlane_b32 s1, v3
	v_readfirstlane_b32 s19, v7
	v_readfirstlane_b32 s18, v6
	s_cbranch_scc1 .LBB0_77
	s_lshl_b64 s[2:3], s[6:7], 2
	v_ashrrev_i32_e32 v40, 3, v0
	s_add_u32 s2, s18, s2
	v_ashrrev_i32_e32 v38, 6, v0
	v_lshlrev_b32_e32 v2, 4, v0
	v_and_b32_e32 v0, 7, v0
	v_lshlrev_b32_e32 v4, 2, v40
	s_addc_u32 s3, s19, s3
	v_readlane_b32 s6, v255, 30
	v_lshlrev_b32_e32 v1, 13, v0
	v_and_b32_e32 v4, 12, v4
	v_readlane_b32 s7, v255, 31
	s_add_u32 s6, s5, s6
	v_lshlrev_b32_e32 v3, 2, v0
	v_add3_u32 v4, 0, v1, v4
	v_lshlrev_b32_e32 v0, 4, v0
	v_mov_b32_e32 v1, v81
	v_mov_b32_e32 v9, 0x3f0
	s_movk_i32 s5, 0x50
	s_addc_u32 s7, s1, s7
	v_lshl_add_u64 v[0:1], s[8:9], 0, v[0:1]
	s_mov_b64 s[8:9], 0x6000000
	s_mov_b32 s1, 0x3ffffffc
	v_bitop3_b32 v7, v2, s5, v9 bitop3:0x6c
	s_movk_i32 s5, 0x60
	v_lshl_add_u64 v[34:35], v[0:1], 0, s[8:9]
	v_bitop3_b32 v0, v40, v3, s1 bitop3:0x6c
	v_bitop3_b32 v8, v2, s5, v9 bitop3:0x6c
	s_movk_i32 s5, 0x70
	v_add_u32_e32 v42, 64, v40
	v_and_b32_e32 v80, 0x3f0, v2
	v_lshl_add_u32 v41, v0, 2, v4
	v_bitop3_b32 v0, v2, 16, v9 bitop3:0x6c
	v_bitop3_b32 v1, v2, 32, v9 bitop3:0x6c
	v_bitop3_b32 v5, v2, 48, v9 bitop3:0x6c
	v_bitop3_b32 v6, v2, 64, v9 bitop3:0x6c
	v_bitop3_b32 v2, v2, s5, v9 bitop3:0x6c
	v_bitop3_b32 v9, v42, v3, s1 bitop3:0x6c
	v_add_u32_e32 v44, 0x80, v40
	v_add_u32_e32 v46, 0xc0, v40
	s_cmp_lg_u64 s[18:19], 0
	v_lshl_add_u32 v39, v38, 10, 0
	v_lshl_add_u32 v43, v9, 2, v4
	v_bitop3_b32 v9, v44, v3, s1 bitop3:0x6c
	v_bitop3_b32 v3, v46, v3, s1 bitop3:0x6c
	v_lshl_add_u64 v[32:33], s[6:7], 0, v[80:81]
	s_cselect_b64 s[6:7], -1, 0
	v_lshl_add_u32 v45, v9, 2, v4
	v_lshl_add_u32 v47, v3, 2, v4
	s_lshl_b32 s1, s0, 6
	s_lshl_b32 s5, s20, 6
	v_add_u32_e32 v48, v39, v0
	v_add_u32_e32 v49, v39, v1
	v_add_u32_e32 v50, v39, v5
	v_add_u32_e32 v51, v39, v6
	v_add_u32_e32 v52, v39, v7
	v_add_u32_e32 v53, v39, v8
	v_add_u32_e32 v54, v39, v2
	s_branch .LBB0_75
.LBB0_74:
	v_add_u32_e32 v36, v39, v80
	s_waitcnt vmcnt(0) lgkmcnt(0)
	ds_write_b128 v36, v[4:7]
	ds_write_b128 v48, v[0:3] offset:8192
	ds_write_b128 v49, v[12:15] offset:16384
	ds_write_b128 v50, v[8:11] offset:24576
	ds_write_b128 v51, v[20:23] offset:32768
	ds_write_b128 v52, v[16:19] offset:40960
	ds_write_b128 v53, v[28:31] offset:49152
	ds_write_b128 v54, v[24:27] offset:57344
	s_waitcnt lgkmcnt(0)
	s_barrier
	ds_read2st64_b32 v[0:1], v41 offset1:4
	ds_read2st64_b32 v[2:3], v41 offset0:8 offset1:12
	ds_read2st64_b32 v[4:5], v41 offset0:16 offset1:20
	ds_read2st64_b32 v[6:7], v41 offset0:24 offset1:28
	s_sub_i32 s9, 0, s13
	s_add_i32 s18, s1, s9
	s_waitcnt lgkmcnt(3)
	v_cvt_pk_bf16_f32 v0, v0, v1
	s_waitcnt lgkmcnt(2)
	v_cvt_pk_bf16_f32 v1, v2, v3
	s_waitcnt lgkmcnt(1)
	v_cvt_pk_bf16_f32 v2, v4, v5
	v_add_u32_e32 v4, s8, v40
	s_ashr_i32 s19, s18, 31
	s_waitcnt lgkmcnt(0)
	v_cvt_pk_bf16_f32 v3, v6, v7
	v_ashrrev_i32_e32 v5, 31, v4
	ds_read2st64_b32 v[6:7], v43 offset1:4
	ds_read2st64_b32 v[10:11], v43 offset0:8 offset1:12
	ds_read2st64_b32 v[12:13], v43 offset0:16 offset1:20
	ds_read2st64_b32 v[14:15], v43 offset0:24 offset1:28
	v_lshl_add_u64 v[8:9], s[18:19], 1, v[34:35]
	v_lshlrev_b64 v[4:5], 12, v[4:5]
	v_lshl_add_u64 v[4:5], v[8:9], 0, v[4:5]
	global_store_dwordx4 v[4:5], v[0:3], off
	v_add_u32_e32 v4, s8, v42
	v_ashrrev_i32_e32 v5, 31, v4
	s_waitcnt lgkmcnt(0)
	v_cvt_pk_bf16_f32 v0, v6, v7
	v_cvt_pk_bf16_f32 v1, v10, v11
	v_cvt_pk_bf16_f32 v2, v12, v13
	v_cvt_pk_bf16_f32 v3, v14, v15
	v_lshlrev_b64 v[4:5], 12, v[4:5]
	ds_read2st64_b32 v[6:7], v45 offset1:4
	ds_read2st64_b32 v[10:11], v45 offset0:8 offset1:12
	ds_read2st64_b32 v[12:13], v45 offset0:16 offset1:20
	ds_read2st64_b32 v[14:15], v45 offset0:24 offset1:28
	v_lshl_add_u64 v[4:5], v[8:9], 0, v[4:5]
	global_store_dwordx4 v[4:5], v[0:3], off
	v_add_u32_e32 v4, s8, v44
	v_ashrrev_i32_e32 v5, 31, v4
	v_lshlrev_b64 v[4:5], 12, v[4:5]
	s_waitcnt lgkmcnt(0)
	v_cvt_pk_bf16_f32 v0, v6, v7
	v_cvt_pk_bf16_f32 v1, v10, v11
	v_cvt_pk_bf16_f32 v2, v12, v13
	v_cvt_pk_bf16_f32 v3, v14, v15
	v_lshl_add_u64 v[4:5], v[8:9], 0, v[4:5]
	ds_read2st64_b32 v[6:7], v47 offset1:4
	ds_read2st64_b32 v[10:11], v47 offset0:8 offset1:12
	ds_read2st64_b32 v[12:13], v47 offset0:16 offset1:20
	ds_read2st64_b32 v[14:15], v47 offset0:24 offset1:28
	global_store_dwordx4 v[4:5], v[0:3], off
	v_add_u32_e32 v4, s8, v46
	v_ashrrev_i32_e32 v5, 31, v4
	v_lshlrev_b64 v[4:5], 12, v[4:5]
	s_add_i32 s0, s0, s20
	s_add_i32 s1, s1, s5
	v_lshl_add_u64 v[4:5], v[8:9], 0, v[4:5]
	s_cmpk_lt_i32 s0, 0x100
	s_waitcnt lgkmcnt(0)
	v_cvt_pk_bf16_f32 v0, v6, v7
	v_cvt_pk_bf16_f32 v1, v10, v11
	v_cvt_pk_bf16_f32 v2, v12, v13
	v_cvt_pk_bf16_f32 v3, v14, v15
	global_store_dwordx4 v[4:5], v[0:3], off
	s_waitcnt lgkmcnt(0)
	s_barrier
	s_cbranch_scc0 .LBB0_77
; #define IN(i) ((const float*)karg(i))
; #define WSB(off) ((bf16_t*)((unsigned char*)karg(15) + (off)))
; __device__ __forceinline__ void phase_wT(const float* __restrict__ src, int ldn, int n0, int K, int N, bf16_t* __restrict__ dst, LAS float* tile, const float* __restrict__ gain = nullptr) {
;     ...
;     float4 v[8];
; #pragma unroll
;     for (int i = 0; i < 8; ++i) v[i] = *(const float4*)(src + (size_t)(kt * 64 + w + 8 * i) * ldn + n0 + ntile * 256 + lane * 4);
;     if (gain) {
; #pragma unroll
;       for (int i = 0; i < 8; ++i) { const float gk = gain[kt * 64 + w + 8 * i]; v[i].x *= gk; v[i].y *= gk; v[i].z *= gk; v[i].w *= gk; }
;     }
; __global__ void __launch_bounds__(512, 2) mega(Params p) {
;     ...
;     phase_wT(IN(11) + (size_t)layer * 256 * 2048, 2048, 0, 256, 2048, WSB(WS_WD), tile);
.LBB0_75:
	s_ashr_i32 s8, s0, 31
	s_lshr_b32 s8, s8, 27
	s_add_i32 s8, s0, s8
	s_ashr_i32 s8, s8, 5
	s_lshl_b32 s13, s8, 11
	s_sub_i32 s9, s1, s13
	v_add_u32_e32 v36, s9, v38
	s_lshl_b32 s8, s8, 8
	v_add_u32_e32 v2, 8, v36
	v_add_u32_e32 v8, 16, v36
	v_add_u32_e32 v10, 24, v36
	v_add_u32_e32 v16, 32, v36
	v_add_u32_e32 v18, 40, v36
	v_add_u32_e32 v26, 48, v36
	v_add_u32_e32 v28, 56, v36
	s_ashr_i32 s9, s8, 31
	v_ashrrev_i32_e32 v37, 31, v36
	v_ashrrev_i32_e32 v3, 31, v2
	v_ashrrev_i32_e32 v9, 31, v8
	v_ashrrev_i32_e32 v11, 31, v10
	v_ashrrev_i32_e32 v17, 31, v16
	v_ashrrev_i32_e32 v19, 31, v18
	v_ashrrev_i32_e32 v27, 31, v26
	v_ashrrev_i32_e32 v29, 31, v28
	v_lshl_add_u64 v[24:25], s[8:9], 2, v[32:33]
	v_lshlrev_b64 v[0:1], 13, v[36:37]
	v_lshlrev_b64 v[2:3], 13, v[2:3]
	v_lshlrev_b64 v[8:9], 13, v[8:9]
	v_lshlrev_b64 v[10:11], 13, v[10:11]
	v_lshlrev_b64 v[16:17], 13, v[16:17]
	v_lshlrev_b64 v[18:19], 13, v[18:19]
	v_lshlrev_b64 v[26:27], 13, v[26:27]
	v_lshlrev_b64 v[28:29], 13, v[28:29]
	v_lshl_add_u64 v[0:1], v[24:25], 0, v[0:1]
	v_lshl_add_u64 v[2:3], v[24:25], 0, v[2:3]
	v_lshl_add_u64 v[8:9], v[24:25], 0, v[8:9]
	v_lshl_add_u64 v[10:11], v[24:25], 0, v[10:11]
	v_lshl_add_u64 v[16:17], v[24:25], 0, v[16:17]
	v_lshl_add_u64 v[18:19], v[24:25], 0, v[18:19]
	v_lshl_add_u64 v[26:27], v[24:25], 0, v[26:27]
	v_lshl_add_u64 v[24:25], v[24:25], 0, v[28:29]
	global_load_dwordx4 v[4:7], v[0:1], off
	s_nop 0
	global_load_dwordx4 v[0:3], v[2:3], off
	s_nop 0
	global_load_dwordx4 v[12:15], v[8:9], off
	s_nop 0
	global_load_dwordx4 v[8:11], v[10:11], off
	s_nop 0
	global_load_dwordx4 v[20:23], v[16:17], off
	s_nop 0
	global_load_dwordx4 v[16:19], v[18:19], off
	s_nop 0
	global_load_dwordx4 v[28:31], v[26:27], off
	s_nop 0
	global_load_dwordx4 v[24:27], v[24:25], off
	s_andn2_b64 vcc, exec, s[6:7]
	s_cbranch_vccnz .LBB0_74
	v_lshl_add_u64 v[36:37], v[36:37], 2, s[2:3]
	global_load_dword v56, v[36:37], off
	global_load_dword v58, v[36:37], off offset:32
	global_load_dword v60, v[36:37], off offset:64
	global_load_dword v62, v[36:37], off offset:96
	global_load_dword v64, v[36:37], off offset:128
	global_load_dword v66, v[36:37], off offset:160
	global_load_dword v68, v[36:37], off offset:192
	s_nop 0
	global_load_dword v36, v[36:37], off offset:224
	s_waitcnt vmcnt(0) lgkmcnt(0)
	v_pk_mul_f32 v[4:5], v[4:5], v[56:57] op_sel_hi:[1,0]
	v_pk_mul_f32 v[6:7], v[6:7], v[56:57] op_sel_hi:[1,0]
	v_pk_mul_f32 v[0:1], v[0:1], v[58:59] op_sel_hi:[1,0]
	v_pk_mul_f32 v[2:3], v[2:3], v[58:59] op_sel_hi:[1,0]
	v_pk_mul_f32 v[12:13], v[12:13], v[60:61] op_sel_hi:[1,0]
	v_pk_mul_f32 v[14:15], v[14:15], v[60:61] op_sel_hi:[1,0]
	v_pk_mul_f32 v[8:9], v[8:9], v[62:63] op_sel_hi:[1,0]
	v_pk_mul_f32 v[10:11], v[10:11], v[62:63] op_sel_hi:[1,0]
	v_pk_mul_f32 v[20:21], v[20:21], v[64:65] op_sel_hi:[1,0]
	v_pk_mul_f32 v[22:23], v[22:23], v[64:65] op_sel_hi:[1,0]
	v_pk_mul_f32 v[16:17], v[16:17], v[66:67] op_sel_hi:[1,0]
	v_pk_mul_f32 v[18:19], v[18:19], v[66:67] op_sel_hi:[1,0]
	v_pk_mul_f32 v[28:29], v[28:29], v[68:69] op_sel_hi:[1,0]
	v_pk_mul_f32 v[30:31], v[30:31], v[68:69] op_sel_hi:[1,0]
	v_pk_mul_f32 v[24:25], v[24:25], v[36:37] op_sel_hi:[1,0]
	v_pk_mul_f32 v[26:27], v[26:27], v[36:37] op_sel_hi:[1,0]
	s_branch .LBB0_74
.LBB0_77:
	v_readlane_b32 s0, v255, 0
	v_readlane_b32 s1, v255, 1
	v_mov_b32_e32 v2, v252
	v_mov_b32_e32 v3, s74
	v_mov_b64_e32 v[0:1], s[0:1]
	global_load_dwordx2 v[4:5], v[0:1], off offset:88 sc0 sc1
	s_waitcnt vmcnt(0)
	global_load_dwordx2 v[0:1], v[0:1], off offset:120 sc0 sc1
	s_waitcnt vmcnt(0)
	ds_read_b32 v3, v3
	s_waitcnt lgkmcnt(0)
	v_readfirstlane_b32 s0, v3
	s_cmp_gt_i32 s0, 31
	v_readfirstlane_b32 s1, v5
	v_readfirstlane_b32 s5, v4
	v_readfirstlane_b32 s3, v1
	v_readfirstlane_b32 s2, v0
	s_cbranch_scc1 .LBB0_80
	v_ashrrev_i32_e32 v6, 3, v2
	v_ashrrev_i32_e32 v4, 6, v2
	v_lshlrev_b32_e32 v8, 4, v2
	v_and_b32_e32 v2, 7, v2
	v_lshlrev_b32_e32 v7, 2, v6
	v_lshlrev_b32_e32 v3, 13, v2
	v_and_b32_e32 v7, 12, v7
	v_lshlrev_b32_e32 v13, 2, v2
	v_add3_u32 v14, 0, v3, v7
	v_lshlrev_b32_e32 v2, 4, v2
	v_mov_b32_e32 v3, v81
	v_readlane_b32 s6, v255, 28
	v_lshl_add_u64 v[2:3], s[2:3], 0, v[2:3]
	s_mov_b64 s[2:3], 0x6800000
	v_readlane_b32 s7, v255, 29
	v_lshl_add_u64 v[2:3], v[2:3], 0, s[2:3]
	v_mov_b32_e32 v9, 0x3f0
	s_movk_i32 s2, 0x50
	s_lshl_b64 s[6:7], s[6:7], 21
	v_bitop3_b32 v19, v8, s2, v9 bitop3:0x6c
	s_movk_i32 s2, 0x60
	s_add_u32 s6, s5, s6
	v_bitop3_b32 v20, v8, s2, v9 bitop3:0x6c
	s_movk_i32 s2, 0x70
	s_addc_u32 s7, s1, s7
	v_and_b32_e32 v80, 0x3f0, v8
	s_mov_b32 s1, 0x3ffffffc
	v_bitop3_b32 v15, v8, 16, v9 bitop3:0x6c
	v_bitop3_b32 v16, v8, 32, v9 bitop3:0x6c
	v_bitop3_b32 v17, v8, 48, v9 bitop3:0x6c
	v_bitop3_b32 v18, v8, 64, v9 bitop3:0x6c
	v_bitop3_b32 v21, v8, s2, v9 bitop3:0x6c
	v_add_u32_e32 v8, 64, v6
	v_add_u32_e32 v10, 0x80, v6
	v_add_u32_e32 v12, 0xc0, v6
	v_lshl_add_u32 v5, v4, 10, 0
	v_bitop3_b32 v7, v6, v13, s1 bitop3:0x6c
	v_bitop3_b32 v9, v8, v13, s1 bitop3:0x6c
	v_bitop3_b32 v11, v10, v13, s1 bitop3:0x6c
	v_bitop3_b32 v13, v12, v13, s1 bitop3:0x6c
	v_lshl_add_u64 v[0:1], s[6:7], 0, v[80:81]
	v_lshl_add_u32 v7, v7, 2, v14
	v_lshl_add_u32 v9, v9, 2, v14
	v_lshl_add_u32 v11, v11, 2, v14
	v_lshl_add_u32 v13, v13, 2, v14
	s_lshl_b32 s1, s0, 6
	s_lshl_b32 s5, s20, 6
	v_add_u32_e32 v14, v5, v15
	v_add_u32_e32 v15, v5, v16
	v_add_u32_e32 v16, v5, v17
	v_add_u32_e32 v17, v5, v18
	v_add_u32_e32 v18, v5, v19
	v_add_u32_e32 v19, v5, v20
	v_add_u32_e32 v20, v5, v21
; #define LAS __attribute__((address_space(3)))
; __device__ __forceinline__ unsigned cvt_pk_bf16(float lo, float hi) { unsigned r; asm("v_cvt_pk_bf16_f32 %0, %1, %2" : "=v"(r) : "v"(lo), "v"(hi)); return r; }
; __device__ __forceinline__ int otid() { int t = threadIdx.x; asm volatile("" : "+v"(t)); return t; }
; __device__ __forceinline__ int obid() { extern __shared__ __attribute__((aligned(16))) unsigned char shm_vb[]; return __builtin_amdgcn_readfirstlane(*(volatile LAS int*)((LAS unsigned char*)shm_vb + VB_OFF)); }
; __device__ __forceinline__ void phase_wT(const float* __restrict__ src, int ldn, int n0, int K, int N, bf16_t* __restrict__ dst, LAS float* tile, const float* __restrict__ gain = nullptr) {
;   const int tk = K / 64, tn = N / 256, nt = tk * tn, t = otid(), w = t >> 6, lane = t & 63;
;   for (int ti = obid(); ti < nt; ti += gridDim.x) {
;     const int kt = ti % tk, ntile = ti / tk;
;     float4 v[8];
; #pragma unroll
;     for (int i = 0; i < 8; ++i) v[i] = *(const float4*)(src + (size_t)(kt * 64 + w + 8 * i) * ldn + n0 + ntile * 256 + lane * 4);
;     if (gain) {
; #pragma unroll
;       for (int i = 0; i < 8; ++i) { const float gk = gain[kt * 64 + w + 8 * i]; v[i].x *= gk; v[i].y *= gk; v[i].z *= gk; v[i].w *= gk; }
;     }
; #pragma unroll
;     for (int i = 0; i < 8; ++i) { const int k = w + 8 * i; *(LAS f32x4*)(tile + k * 256 + ((lane ^ (i & 7)) << 2)) = (f32x4){v[i].x, v[i].y, v[i].z, v[i].w}; }
;     __syncthreads();
;     const int nr = t >> 3, kc = (t & 7) * 8, ksw = (t & 7);
; #pragma unroll
;     for (int p = 0; p < 4; ++p) {
;       const int n = p * 64 + nr;
;       const LAS float* sp = tile + kc * 256 + ((((n >> 2) ^ ksw)) << 2) + (n & 3);
;       uint4 o; o.x = cvt_pk_bf16(sp[0], sp[256]); o.y = cvt_pk_bf16(sp[512], sp[768]); o.z = cvt_pk_bf16(sp[1024], sp[1280]); o.w = cvt_pk_bf16(sp[1536], sp[1792]);
;       *(uint4*)(dst + (size_t)(ntile * 256 + n) * K + kt * 64 + kc) = o;
;     }
;     __syncthreads();
;   }
; }
.LBB0_79:
	s_ashr_i32 s2, s0, 31
	s_lshr_b32 s2, s2, 30
	s_add_i32 s2, s0, s2
	s_lshl_b32 s2, s2, 6
	s_and_b32 s6, s2, 0xffffff00
	s_sub_i32 s2, s1, s6
	v_add_u32_e32 v22, s2, v4
	v_add_u32_e32 v26, 8, v22
	v_add_u32_e32 v28, 16, v22
	v_add_u32_e32 v30, 24, v22
	v_add_u32_e32 v32, 32, v22
	v_add_u32_e32 v34, 40, v22
	v_add_u32_e32 v36, 48, v22
	v_add_u32_e32 v38, 56, v22
	s_ashr_i32 s7, s6, 31
	v_ashrrev_i32_e32 v23, 31, v22
	v_ashrrev_i32_e32 v27, 31, v26
	v_ashrrev_i32_e32 v29, 31, v28
	v_ashrrev_i32_e32 v31, 31, v30
	v_ashrrev_i32_e32 v33, 31, v32
	v_ashrrev_i32_e32 v35, 31, v34
	v_ashrrev_i32_e32 v37, 31, v36
	v_ashrrev_i32_e32 v39, 31, v38
	v_lshl_add_u64 v[24:25], s[6:7], 2, v[0:1]
	v_lshlrev_b64 v[22:23], 13, v[22:23]
	v_lshlrev_b64 v[26:27], 13, v[26:27]
	v_lshlrev_b64 v[28:29], 13, v[28:29]
	v_lshlrev_b64 v[30:31], 13, v[30:31]
	v_lshlrev_b64 v[32:33], 13, v[32:33]
	v_lshlrev_b64 v[34:35], 13, v[34:35]
	v_lshlrev_b64 v[36:37], 13, v[36:37]
	v_lshlrev_b64 v[38:39], 13, v[38:39]
	v_lshl_add_u64 v[22:23], v[24:25], 0, v[22:23]
	v_lshl_add_u64 v[26:27], v[24:25], 0, v[26:27]
	v_lshl_add_u64 v[40:41], v[24:25], 0, v[28:29]
	v_lshl_add_u64 v[42:43], v[24:25], 0, v[30:31]
	v_lshl_add_u64 v[44:45], v[24:25], 0, v[32:33]
	v_lshl_add_u64 v[46:47], v[24:25], 0, v[34:35]
	v_lshl_add_u64 v[48:49], v[24:25], 0, v[36:37]
	v_lshl_add_u64 v[50:51], v[24:25], 0, v[38:39]
	global_load_dwordx4 v[22:25], v[22:23], off
	s_nop 0
	global_load_dwordx4 v[26:29], v[26:27], off
	s_nop 0
	global_load_dwordx4 v[30:33], v[40:41], off
	global_load_dwordx4 v[34:37], v[42:43], off
	s_nop 0
	global_load_dwordx4 v[38:41], v[44:45], off
	s_nop 0
	global_load_dwordx4 v[42:45], v[46:47], off
	s_nop 0
	global_load_dwordx4 v[46:49], v[48:49], off
	s_nop 0
	global_load_dwordx4 v[50:53], v[50:51], off
	v_add_u32_e32 v21, v5, v80
	v_add_u32_e32 v54, s6, v6
	v_add_u32_e32 v56, s6, v8
	v_add_u32_e32 v58, s6, v10
	v_add_u32_e32 v60, s6, v12
	s_ashr_i32 s3, s2, 31
	v_ashrrev_i32_e32 v55, 31, v54
	s_add_i32 s0, s0, s20
	s_add_i32 s1, s1, s5
	v_ashrrev_i32_e32 v57, 31, v56
	v_ashrrev_i32_e32 v59, 31, v58
	v_ashrrev_i32_e32 v61, 31, v60
	v_lshl_add_u64 v[62:63], s[2:3], 1, v[2:3]
	v_lshlrev_b64 v[54:55], 9, v[54:55]
	v_lshlrev_b64 v[56:57], 9, v[56:57]
	v_lshlrev_b64 v[58:59], 9, v[58:59]
	v_lshlrev_b64 v[60:61], 9, v[60:61]
	s_cmp_lt_i32 s0, 32
	v_lshl_add_u64 v[54:55], v[62:63], 0, v[54:55]
	v_lshl_add_u64 v[56:57], v[62:63], 0, v[56:57]
	v_lshl_add_u64 v[58:59], v[62:63], 0, v[58:59]
	v_lshl_add_u64 v[60:61], v[62:63], 0, v[60:61]
	s_waitcnt vmcnt(0) lgkmcnt(0)
	ds_write_b128 v21, v[22:25]
	ds_write_b128 v14, v[26:29] offset:8192
	ds_write_b128 v15, v[30:33] offset:16384
	ds_write_b128 v16, v[34:37] offset:24576
	ds_write_b128 v17, v[38:41] offset:32768
	ds_write_b128 v18, v[42:45] offset:40960
	ds_write_b128 v19, v[46:49] offset:49152
	ds_write_b128 v20, v[50:53] offset:57344
	s_waitcnt lgkmcnt(0)
	s_barrier
	ds_read2st64_b32 v[22:23], v7 offset1:4
	ds_read2st64_b32 v[24:25], v7 offset0:8 offset1:12
	ds_read2st64_b32 v[26:27], v7 offset0:16 offset1:20
	ds_read2st64_b32 v[28:29], v7 offset0:24 offset1:28
	ds_read2st64_b32 v[30:31], v9 offset1:4
	ds_read2st64_b32 v[32:33], v9 offset0:8 offset1:12
	ds_read2st64_b32 v[34:35], v9 offset0:16 offset1:20
	ds_read2st64_b32 v[36:37], v9 offset0:24 offset1:28
	ds_read2st64_b32 v[38:39], v11 offset1:4
	ds_read2st64_b32 v[40:41], v11 offset0:8 offset1:12
	ds_read2st64_b32 v[42:43], v11 offset0:16 offset1:20
	ds_read2st64_b32 v[44:45], v11 offset0:24 offset1:28
	ds_read2st64_b32 v[46:47], v13 offset1:4
	ds_read2st64_b32 v[48:49], v13 offset0:8 offset1:12
	ds_read2st64_b32 v[50:51], v13 offset0:16 offset1:20
	ds_read2st64_b32 v[52:53], v13 offset0:24 offset1:28
	s_waitcnt lgkmcnt(14)
	v_cvt_pk_bf16_f32 v22, v22, v23
	v_cvt_pk_bf16_f32 v23, v24, v25
	s_waitcnt lgkmcnt(13)
	v_cvt_pk_bf16_f32 v24, v26, v27
	s_waitcnt lgkmcnt(12)
	v_cvt_pk_bf16_f32 v25, v28, v29
	s_waitcnt lgkmcnt(11)
	v_cvt_pk_bf16_f32 v26, v30, v31
	s_waitcnt lgkmcnt(10)
	v_cvt_pk_bf16_f32 v27, v32, v33
	s_waitcnt lgkmcnt(9)
	v_cvt_pk_bf16_f32 v28, v34, v35
	s_waitcnt lgkmcnt(8)
	v_cvt_pk_bf16_f32 v29, v36, v37
	s_waitcnt lgkmcnt(7)
	v_cvt_pk_bf16_f32 v30, v38, v39
	s_waitcnt lgkmcnt(6)
	v_cvt_pk_bf16_f32 v31, v40, v41
	s_waitcnt lgkmcnt(5)
	v_cvt_pk_bf16_f32 v32, v42, v43
	s_waitcnt lgkmcnt(4)
	v_cvt_pk_bf16_f32 v33, v44, v45
	s_waitcnt lgkmcnt(3)
	v_cvt_pk_bf16_f32 v34, v46, v47
	s_waitcnt lgkmcnt(2)
	v_cvt_pk_bf16_f32 v35, v48, v49
	s_waitcnt lgkmcnt(1)
	v_cvt_pk_bf16_f32 v36, v50, v51
	s_waitcnt lgkmcnt(0)
	v_cvt_pk_bf16_f32 v37, v52, v53
	global_store_dwordx4 v[54:55], v[22:25], off
	global_store_dwordx4 v[56:57], v[26:29], off
	global_store_dwordx4 v[58:59], v[30:33], off
	global_store_dwordx4 v[60:61], v[34:37], off
	s_waitcnt lgkmcnt(0)
	s_barrier
	s_cbranch_scc1 .LBB0_79

; __device__ __forceinline__ unsigned xb_add(unsigned* p, unsigned v) { return __hip_atomic_fetch_add(p, v, __ATOMIC_RELAXED, __HIP_MEMORY_SCOPE_AGENT); }
; __device__ __forceinline__ void gbar(unsigned* bar, unsigned n, volatile LAS unsigned* st) {
;     ...
;       __builtin_amdgcn_fence(__ATOMIC_ACQUIRE, "agent");
;       xb_add(&bar[XB_XGEN(x)], 1u);
;       asm volatile("s_waitcnt vmcnt(0)" ::: "memory");
.LBB0_81:
	s_or_b64 exec, exec, s[36:37]
	v_lshlrev_b64 v[0:1], 2, v[80:81]
	v_lshl_add_u64 v[0:1], s[4:5], 0, v[0:1]
	buffer_inv sc1
	global_atomic_add v[0:1], v230, off
	s_waitcnt vmcnt(0)

; __device__ __forceinline__ int otid() { int t = threadIdx.x; asm volatile("" : "+v"(t)); return t; }
; __device__ __forceinline__ int obid() { extern __shared__ __attribute__((aligned(16))) unsigned char shm_vb[]; return __builtin_amdgcn_readfirstlane(*(volatile LAS int*)((LAS unsigned char*)shm_vb + VB_OFF)); }
; __device__ __forceinline__ void phase_x0(const float* __restrict__ x, bf16_t* __restrict__ xb, unsigned long long* __restrict__ ss, int rows) {
;   const int tid = otid(), lane = tid & 63, nw = gridDim.x * 8;
;   for (int r = obid() * 8 + (tid >> 6); r < rows; r += nw) {
;     const float4* xr = (const float4*)(x + (size_t)r * DM);
.LBB0_84:
	v_readlane_b32 s0, v255, 32
	v_readlane_b32 s1, v255, 33
	s_andn2_b64 vcc, exec, s[0:1]
	s_mov_b32 s89, s12
	s_cbranch_vccnz .LBB0_91
	s_lshl_b64 s[0:1], s[88:89], 3
	v_readlane_b32 s2, v255, 0
	v_readlane_b32 s3, v255, 1
	s_add_u32 s0, s2, s0
	s_addc_u32 s1, s3, s1
	v_mov_b64_e32 v[0:1], s[0:1]
	global_load_dwordx2 v[2:3], v[0:1], off sc0 sc1
	s_waitcnt vmcnt(0)
	v_mov_b64_e32 v[0:1], s[2:3]
	global_load_dwordx2 v[4:5], v[0:1], off offset:120 sc0 sc1
	s_waitcnt vmcnt(0)
	global_load_dwordx2 v[8:9], v[0:1], off offset:120 sc0 sc1
	s_waitcnt vmcnt(0)
	v_mov_b32_e32 v1, v252
	v_mov_b32_e32 v0, s74
	ds_read_b32 v6, v0
	v_ashrrev_i32_e32 v0, 6, v1
	s_movk_i32 s4, 0x4000
	s_waitcnt lgkmcnt(0)
	v_readfirstlane_b32 s0, v6
	s_lshl_b32 s8, s0, 3
	v_add_u32_e32 v6, s8, v0
	v_cmp_gt_i32_e32 vcc, s4, v6
	v_readfirstlane_b32 s3, v3
	v_readfirstlane_b32 s2, v2
	v_readfirstlane_b32 s7, v5
	v_readfirstlane_b32 s6, v4
	v_readfirstlane_b32 s0, v9
	v_readfirstlane_b32 s1, v8
	s_and_saveexec_b64 s[4:5], vcc
	s_cbranch_execz .LBB0_90
	v_and_b32_e32 v13, 63, v1
	v_and_b32_e32 v1, 64, v189
	v_add_u32_e32 v1, 64, v1
	v_xor_b32_e32 v2, 32, v189
	v_cmp_lt_i32_e32 vcc, v2, v1
	s_lshl_b64 s[18:19], s[88:89], 17
	s_ashr_i32 s9, s8, 31
	v_cndmask_b32_e32 v2, v189, v2, vcc
	v_lshlrev_b32_e32 v7, 2, v2
	v_xor_b32_e32 v2, 16, v189
	v_cmp_lt_i32_e32 vcc, v2, v1
	s_nop 1
	v_cndmask_b32_e32 v2, v189, v2, vcc
	v_lshlrev_b32_e32 v8, 2, v2
	v_xor_b32_e32 v2, 8, v189
	v_cmp_lt_i32_e32 vcc, v2, v1
	s_nop 1
	v_cndmask_b32_e32 v2, v189, v2, vcc
	v_lshlrev_b32_e32 v9, 2, v2
	v_xor_b32_e32 v2, 4, v189
	v_cmp_lt_i32_e32 vcc, v2, v1
	s_nop 1
	v_cndmask_b32_e32 v2, v189, v2, vcc
	v_lshlrev_b32_e32 v10, 2, v2
	v_xor_b32_e32 v2, 2, v189
	v_cmp_lt_i32_e32 vcc, v2, v1
	s_nop 1
	v_cndmask_b32_e32 v2, v189, v2, vcc
	v_lshlrev_b32_e32 v11, 2, v2
	v_xor_b32_e32 v2, 1, v189
	v_cmp_lt_i32_e32 vcc, v2, v1
	s_nop 1
	v_cndmask_b32_e32 v1, v189, v2, vcc
	v_lshlrev_b32_e32 v12, 2, v1
	v_ashrrev_i32_e32 v1, 31, v0
	v_lshl_add_u64 v[4:5], v[0:1], 0, s[8:9]
	s_add_u32 s8, s1, s18
	s_addc_u32 s9, s0, s19
	v_lshl_add_u64 v[0:1], v[4:5], 3, s[8:9]
	s_mov_b64 s[0:1], 0x13940000
	v_lshl_add_u64 v[0:1], v[0:1], 0, s[0:1]
	s_lshl_b64 s[0:1], s[88:89], 26
	v_lshlrev_b64 v[2:3], 12, v[4:5]
	v_lshl_add_u64 v[2:3], s[0:1], 0, v[2:3]
	v_lshl_or_b32 v2, v13, 3, v2
	v_lshlrev_b64 v[4:5], 13, v[4:5]
	v_lshl_add_u64 v[2:3], s[6:7], 0, v[2:3]
	s_mov_b64 s[0:1], 0xb920000
	v_lshl_or_b32 v4, v13, 4, v4
	v_cmp_eq_u32_e32 vcc, 0, v13
	v_lshl_add_u64 v[2:3], v[2:3], 0, s[0:1]
	v_lshl_add_u64 v[4:5], s[2:3], 0, v[4:5]
	s_mov_b64 s[6:7], 0
	s_branch .LBB0_88

; __device__ __forceinline__ unsigned cvt_pk_bf16(float lo, float hi) { unsigned r; asm("v_cvt_pk_bf16_f32 %0, %1, %2" : "=v"(r) : "v"(lo), "v"(hi)); return r; }
; __device__ __forceinline__ unsigned long long ss_fix(float s) { return (unsigned long long)(s * 16777216.f); }
; __device__ __forceinline__ void phase_x0(const float* __restrict__ x, bf16_t* __restrict__ xb, unsigned long long* __restrict__ ss, int rows) {
;     ...
;     float4 v[8]; float s = 0.f;
; #pragma unroll
;     for (int i = 0; i < 8; ++i) { v[i] = xr[lane + 64 * i]; s += v[i].x * v[i].x + v[i].y * v[i].y + v[i].z * v[i].z + v[i].w * v[i].w; }
;     s = wave_sum(s);
; #pragma unroll
;     for (int i = 0; i < 8; ++i) {
;       uint2 o; o.x = cvt_pk_bf16(v[i].x, v[i].y); o.y = cvt_pk_bf16(v[i].z, v[i].w);
;       *(uint2*)(xb + (size_t)r * DM + (lane + 64 * i) * 4) = o;
;     }
;     if (lane == 0) ss[r] = ss_fix(s);
;   }
.LBB0_88:
	s_waitcnt lgkmcnt(0)
	global_load_dwordx4 v[14:17], v[4:5], off
	global_load_dwordx4 v[18:21], v[4:5], off offset:1024
	global_load_dwordx4 v[22:25], v[4:5], off offset:2048
	global_load_dwordx4 v[26:29], v[4:5], off offset:3072
	v_add_co_u32_e64 v42, s[2:3], s77, v4
	s_waitcnt vmcnt(0) lgkmcnt(0)
	v_mul_f32_e32 v13, v15, v15
	v_addc_co_u32_e64 v43, s[2:3], 0, v5, s[2:3]
	global_load_dwordx4 v[30:33], v[42:43], off
	global_load_dwordx4 v[34:37], v[42:43], off offset:1024
	global_load_dwordx4 v[38:41], v[42:43], off offset:2048
	s_nop 0
	global_load_dwordx4 v[42:45], v[42:43], off offset:3072
	v_mul_f32_e32 v46, v19, v19
	v_mul_f32_e32 v47, v23, v23
	v_fmac_f32_e32 v13, v14, v14
	v_fmac_f32_e32 v46, v18, v18
	v_mul_f32_e32 v48, v27, v27
	v_fmac_f32_e32 v47, v22, v22
	v_fmac_f32_e32 v13, v16, v16
	v_fmac_f32_e32 v46, v20, v20
	v_fmac_f32_e32 v48, v26, v26
	v_fmac_f32_e32 v47, v24, v24
	v_fmac_f32_e32 v13, v17, v17
	v_fmac_f32_e32 v46, v21, v21
	v_fmac_f32_e32 v48, v28, v28
	v_fmac_f32_e32 v47, v25, v25
	v_add_f32_e32 v13, v13, v46
	v_fmac_f32_e32 v48, v29, v29
	v_add_f32_e32 v13, v13, v47
	v_add_f32_e32 v13, v13, v48
	v_cvt_pk_bf16_f32 v14, v14, v15
	v_cvt_pk_bf16_f32 v15, v16, v17
	v_cvt_pk_bf16_f32 v16, v18, v19
	v_cvt_pk_bf16_f32 v18, v22, v23
	v_cvt_pk_bf16_f32 v17, v20, v21
	v_cvt_pk_bf16_f32 v19, v24, v25
	global_store_dwordx2 v[2:3], v[14:15], off
	global_store_dwordx2 v[2:3], v[16:17], off offset:512
	global_store_dwordx2 v[2:3], v[18:19], off offset:1024
	s_waitcnt vmcnt(0) lgkmcnt(0)
	v_cvt_pk_bf16_f32 v14, v30, v31
	v_mul_f32_e32 v49, v31, v31
	v_mul_f32_e32 v50, v35, v35
	v_fmac_f32_e32 v49, v30, v30
	v_mul_f32_e32 v51, v39, v39
	v_fmac_f32_e32 v50, v34, v34
	v_fmac_f32_e32 v49, v32, v32
	v_mul_f32_e32 v52, v43, v43
	v_fmac_f32_e32 v51, v38, v38
	v_fmac_f32_e32 v50, v36, v36
	v_fmac_f32_e32 v49, v33, v33
	v_fmac_f32_e32 v52, v42, v42
	v_fmac_f32_e32 v51, v40, v40
	v_fmac_f32_e32 v50, v37, v37
	v_add_f32_e32 v13, v13, v49
	v_fmac_f32_e32 v52, v44, v44
	v_fmac_f32_e32 v51, v41, v41
	v_add_f32_e32 v13, v13, v50
	v_fmac_f32_e32 v52, v45, v45
	v_add_f32_e32 v13, v13, v51
	v_add_f32_e32 v13, v13, v52
	ds_bpermute_b32 v46, v7, v13
	v_cvt_pk_bf16_f32 v15, v32, v33
	v_cvt_pk_bf16_f32 v20, v26, v27
	v_cvt_pk_bf16_f32 v21, v28, v29
	global_store_dwordx2 v[2:3], v[20:21], off offset:1536
	s_waitcnt lgkmcnt(0)
	v_add_f32_e32 v13, v13, v46
	ds_bpermute_b32 v46, v8, v13
	v_cvt_pk_bf16_f32 v16, v34, v35
	v_cvt_pk_bf16_f32 v18, v38, v39
	s_waitcnt lgkmcnt(0)
	v_add_f32_e32 v13, v13, v46
	ds_bpermute_b32 v22, v9, v13
	s_waitcnt lgkmcnt(0)
	v_add_f32_e32 v13, v13, v22
	ds_bpermute_b32 v17, v10, v13
	s_waitcnt lgkmcnt(0)
	v_add_f32_e32 v13, v13, v17
	ds_bpermute_b32 v19, v11, v13
	v_cvt_pk_bf16_f32 v17, v36, v37
	global_store_dwordx2 v[2:3], v[14:15], off offset:2048
	global_store_dwordx2 v[2:3], v[16:17], off offset:2560
	v_cvt_pk_bf16_f32 v16, v42, v43
	v_cvt_pk_bf16_f32 v17, v44, v45
	s_waitcnt lgkmcnt(0)
	v_add_f32_e32 v13, v13, v19
	ds_bpermute_b32 v14, v12, v13
	v_cvt_pk_bf16_f32 v19, v40, v41
	global_store_dwordx2 v[2:3], v[18:19], off offset:3072
	global_store_dwordx2 v[2:3], v[16:17], off offset:3584
	s_and_saveexec_b64 s[2:3], vcc
	s_cbranch_execz .LBB0_87
	s_waitcnt lgkmcnt(0)
	v_add_f32_e32 v13, v13, v14
	v_mul_f32_e32 v13, 0x4b800000, v13
	v_trunc_f32_e32 v13, v13
	v_mul_f32_e32 v14, 0x2f800000, v13
	v_floor_f32_e32 v15, v14
	v_fmac_f32_e32 v13, 0xcf800000, v15
	v_cvt_u32_f32_e32 v14, v13
	v_cvt_u32_f32_e32 v15, v15
	global_store_dwordx2 v[0:1], v[14:15], off
	s_branch .LBB0_87

; #define LAS __attribute__((address_space(3)))
; __device__ __forceinline__ unsigned cvt_pk_bf16(float lo, float hi) { unsigned r; asm("v_cvt_pk_bf16_f32 %0, %1, %2" : "=v"(r) : "v"(lo), "v"(hi)); return r; }
; __device__ __forceinline__ int otid() { int t = threadIdx.x; asm volatile("" : "+v"(t)); return t; }
; __device__ __forceinline__ void phase_cvt(const float* __restrict__ src, int ld, int rows, int ncols, bf16_t* __restrict__ dst, const float* __restrict__ gain = nullptr) {
;   const size_t n8 = (size_t)rows * ncols / 8, gs = (size_t)gridDim.x * 512;
;   const int c8 = ncols / 8;
;   for (size_t i = (size_t)obid() * 512 + otid(); i < n8; i += gs) {
;     const size_t r = i / c8; const int c = (int)(i % c8) * 8;
;     const float* s = src + r * ld + c;
;     float4 v0 = *(const float4*)s, v1 = *(const float4*)(s + 4);
;     if (gain) { const float g = gain[r]; v0.x *= g; v0.y *= g; v0.z *= g; v0.w *= g; v1.x *= g; v1.y *= g; v1.z *= g; v1.w *= g; }
;     uint4 o; o.x = cvt_pk_bf16(v0.x, v0.y); o.y = cvt_pk_bf16(v0.z, v0.w); o.z = cvt_pk_bf16(v1.x, v1.y); o.w = cvt_pk_bf16(v1.z, v1.w);
;     *(uint4*)(dst + r * ncols + c) = o;
;   }
; __device__ __forceinline__ void phase_zero(unsigned long long* __restrict__ p, int n) {
;   for (int i = obid() * 512 + otid(); i < n; i += gridDim.x * 512) { unsigned z = 0; asm volatile("" : "+v"(z)); p[i] = z; }
; }
; __device__ __forceinline__ void gbar(unsigned* bar, unsigned n, volatile LAS unsigned* st) {
;   asm volatile("s_waitcnt vmcnt(0)" ::: "memory");
;   __syncthreads();
;   if (otid() == 0) {
;     __builtin_amdgcn_s_waitcnt(0);
;     const unsigned x = st[0], nloc = st[1], nx = st[2];
;     const unsigned old = xb_add(&bar[XB_XSUB(x)], 1u);
;     unsigned sp = 0;
;     if (old + 1u == (n + 1u) * nloc) {
;       __builtin_amdgcn_fence(__ATOMIC_RELEASE, "agent");
;       asm volatile("s_waitcnt vmcnt(0)" ::: "memory");
;       xb_add(&bar[XB_TOP], 1u);
;       while (xb_ld(&bar[XB_TOP]) < (n + 1u) * nx) { __builtin_amdgcn_s_sleep(1); if (++sp > (1u << 24)) break; }
;       __builtin_amdgcn_fence(__ATOMIC_ACQUIRE, "agent");
;       xb_add(&bar[XB_XGEN(x)], 1u);
;       asm volatile("s_waitcnt vmcnt(0)" ::: "memory");
;     } else {
;       while (xb_ld(&bar[XB_XGEN(x)]) <= n) { __builtin_amdgcn_s_sleep(1); if (++sp > (1u << 24)) break; }
.LBB0_91:
	s_lshl_b64 s[0:1], s[88:89], 3
	v_readlane_b32 s2, v255, 0
	v_readlane_b32 s3, v255, 1
	s_add_u32 s0, s2, s0
	s_addc_u32 s1, s3, s1
	v_mov_b64_e32 v[0:1], s[0:1]
	global_load_dwordx2 v[4:5], v[0:1], off offset:16 sc0 sc1
	s_waitcnt vmcnt(0)
	v_mov_b64_e32 v[0:1], s[2:3]
	global_load_dwordx2 v[6:7], v[0:1], off offset:120 sc0 sc1
	s_waitcnt vmcnt(0)
	v_mov_b32_e32 v0, s74
	ds_read_b32 v0, v0
	v_mov_b32_e32 v2, v252
	s_mov_b64 s[2:3], 0x80000
	v_ashrrev_i32_e32 v3, 31, v2
	s_waitcnt lgkmcnt(0)
	v_readfirstlane_b32 s8, v0
	s_ashr_i32 s9, s8, 31
	s_lshl_b64 s[0:1], s[8:9], 9
	v_lshl_add_u64 v[0:1], s[0:1], 0, v[2:3]
	v_cmp_gt_u64_e32 vcc, s[2:3], v[0:1]
	v_readfirstlane_b32 s1, v5
	v_readfirstlane_b32 s4, v4
	v_readfirstlane_b32 s0, v7
	v_readfirstlane_b32 s6, v6
	s_and_saveexec_b64 s[2:3], vcc
	s_cbranch_execz .LBB0_94
	v_readlane_b32 s18, v255, 30
	v_readlane_b32 s19, v255, 31
	s_add_u32 s4, s4, s18
	s_addc_u32 s5, s1, s19
	s_add_u32 s6, s6, 0x13980000
	s_addc_u32 s7, s0, 0
	s_lshl_b64 s[0:1], s[8:9], 12
	v_lshl_add_u64 v[2:3], v[2:3], 3, s[0:1]
	s_mov_b64 s[8:9], 0
.LBB0_93:
	v_and_b32_e32 v12, 0x3fff00, v2
	v_and_b32_e32 v14, 0xf8, v2
	v_lshlrev_b32_e32 v80, 2, v12
	v_lshl_add_u64 v[4:5], s[4:5], 0, v[80:81]
	v_lshlrev_b32_e32 v80, 2, v14
	v_lshl_add_u64 v[8:9], v[4:5], 0, v[80:81]
	global_load_dwordx4 v[4:7], v[8:9], off
	s_nop 0
	global_load_dwordx4 v[8:11], v[8:9], off offset:16
	v_lshl_add_u64 v[0:1], v[0:1], 0, s[14:15]
	s_mov_b64 s[0:1], 0x7ffff
	v_lshlrev_b32_e32 v80, 1, v12
	v_cmp_lt_u64_e32 vcc, s[0:1], v[0:1]
	v_lshl_add_u64 v[12:13], s[6:7], 0, v[80:81]
	v_lshlrev_b32_e32 v80, 1, v14
	v_lshl_add_u64 v[2:3], v[2:3], 0, s[24:25]
	s_or_b64 s[8:9], vcc, s[8:9]
	v_lshl_add_u64 v[12:13], v[12:13], 0, v[80:81]
	s_waitcnt vmcnt(0) lgkmcnt(0)
	v_cvt_pk_bf16_f32 v4, v4, v5
	v_cvt_pk_bf16_f32 v5, v6, v7
	v_cvt_pk_bf16_f32 v6, v8, v9
	v_cvt_pk_bf16_f32 v7, v10, v11
	global_store_dwordx4 v[12:13], v[4:7], off
	s_andn2_b64 exec, exec, s[8:9]
	s_cbranch_execnz .LBB0_93
.LBB0_94:
	s_or_b64 exec, exec, s[2:3]
	v_mov_b64_e32 v[0:1], s[10:11]
	global_load_dwordx2 v[2:3], v[0:1], off sc0 sc1
	s_waitcnt vmcnt(0)
	v_mov_b32_e32 v0, s74
	ds_read_b32 v0, v0
	s_xor_b64 s[0:1], s[92:93], -1
	v_writelane_b32 v255, s0, 36
	v_mov_b32_e32 v1, v252
	s_movk_i32 s2, 0x4000
	v_writelane_b32 v255, s1, 37
	s_waitcnt lgkmcnt(0)
	v_readfirstlane_b32 s0, v0
	v_readfirstlane_b32 s1, v2
	s_nop 0
	v_lshl_add_u32 v0, s0, 9, v1
	v_readfirstlane_b32 s0, v3
	v_cmp_gt_i32_e32 vcc, s2, v0
	s_and_saveexec_b64 s[2:3], vcc
	s_cbranch_execz .LBB0_97
	s_add_u32 s4, s1, 0x13920000
	s_addc_u32 s5, s0, 0
	s_mov_b64 s[6:7], 0
.LBB0_96:
	v_ashrrev_i32_e32 v1, 31, v0
	v_lshl_add_u64 v[2:3], v[0:1], 3, s[4:5]
	v_add_u32_e32 v0, s33, v0
	v_cmp_lt_i32_e32 vcc, s80, v0
	v_mov_b32_e32 v80, v81
	s_or_b64 s[6:7], vcc, s[6:7]
	global_store_dwordx2 v[2:3], v[80:81], off
	s_andn2_b64 exec, exec, s[6:7]
	s_cbranch_execnz .LBB0_96
.LBB0_97:
	s_or_b64 exec, exec, s[2:3]
	v_mov_b64_e32 v[0:1], s[10:11]
	global_load_dwordx2 v[0:1], v[0:1], off sc0 sc1
	s_waitcnt vmcnt(0)
	s_waitcnt vmcnt(0)
	v_mov_b32_e32 v2, v252
	s_waitcnt lgkmcnt(0)
	s_barrier
	v_readfirstlane_b32 s0, v1
	v_readfirstlane_b32 s1, v0
	v_cmp_ne_u32_e32 vcc, 0, v2
	s_and_saveexec_b64 s[2:3], vcc
	s_xor_b64 s[2:3], exec, s[2:3]
	v_add_u32_e32 v162, 1, v236
	s_andn2_saveexec_b64 s[2:3], s[2:3]
	s_cbranch_execz .LBB0_147
	v_readlane_b32 s6, v255, 15
	s_waitcnt vmcnt(0) expcnt(0) lgkmcnt(0)
	s_add_u32 s4, s1, 0x4cc80000
	v_mov_b32_e32 v0, s6
	ds_read_b32 v1, v0
	v_readlane_b32 s6, v255, 16
	s_addc_u32 s5, s0, 0
	v_add_u32_e32 v162, 1, v236
	v_mov_b32_e32 v0, s6
	s_waitcnt lgkmcnt(0)
	v_lshlrev_b32_e32 v1, 6, v1
	v_add_u32_e32 v80, 0x440, v1
	v_readlane_b32 s6, v255, 17
	v_lshlrev_b64 v[2:3], 2, v[80:81]
	ds_read_b32 v4, v0
	v_mov_b32_e32 v0, s6
	v_lshl_add_u64 v[2:3], s[4:5], 0, v[2:3]
	ds_read_b32 v0, v0
	global_atomic_add v2, v[2:3], v230, off sc0
	s_waitcnt lgkmcnt(0)
	v_mul_lo_u32 v3, v4, v162
	v_add_u32_e32 v80, 0x840, v1
	s_waitcnt vmcnt(0)
	v_add_u32_e32 v2, 1, v2
	v_cmp_ne_u32_e32 vcc, v2, v3
	s_and_saveexec_b64 s[6:7], vcc
	s_xor_b64 s[6:7], exec, s[6:7]
	s_cbranch_execz .LBB0_123
	v_lshlrev_b64 v[0:1], 2, v[80:81]
	v_lshl_add_u64 v[0:1], s[4:5], 0, v[0:1]
	s_mov_b32 s13, 0x1000000
	s_mov_b64 s[8:9], 0
	s_branch .LBB0_111

; __device__ __forceinline__ unsigned xb_ld(unsigned* p) { return __hip_atomic_load(p, __ATOMIC_RELAXED, __HIP_MEMORY_SCOPE_AGENT); }
; __device__ __forceinline__ void gbar(unsigned* bar, unsigned n, volatile LAS unsigned* st) {
;     ...
;       while (xb_ld(&bar[XB_XGEN(x)]) <= n) { __builtin_amdgcn_s_sleep(1); if (++sp > (1u << 24)) break; }
.LBB0_111:
	global_load_dword v2, v[0:1], off sc1
	s_or_b64 s[36:37], s[36:37], exec
	s_waitcnt vmcnt(0) lgkmcnt(0)
	v_cmp_le_u32_e32 vcc, v2, v236
	s_and_saveexec_b64 s[38:39], vcc
	s_cbranch_execz .LBB0_110
	s_cmp_lg_u32 s13, 0
	s_sleep 1
	s_cbranch_scc0 .LBB0_121
	global_load_dword v2, v[0:1], off sc1
	s_mov_b64 s[18:19], -1
	s_waitcnt vmcnt(0) lgkmcnt(0)
	v_cmp_le_u32_e32 vcc, v2, v236
	s_and_saveexec_b64 s[40:41], vcc
	s_cbranch_execz .LBB0_108
	s_sleep 1
	global_load_dword v2, v[0:1], off sc1
	s_waitcnt vmcnt(0) lgkmcnt(0)
	v_cmp_le_u32_e32 vcc, v2, v236
	s_and_saveexec_b64 s[42:43], vcc
	s_cbranch_execz .LBB0_107
	s_sleep 1
	global_load_dword v2, v[0:1], off sc1
	s_waitcnt vmcnt(0) lgkmcnt(0)
	v_cmp_le_u32_e32 vcc, v2, v236
	s_and_saveexec_b64 s[44:45], vcc
	s_cbranch_execz .LBB0_106
	s_sleep 1
	global_load_dword v2, v[0:1], off sc1
	s_waitcnt vmcnt(0) lgkmcnt(0)
	v_cmp_le_u32_e32 vcc, v2, v236
	s_and_saveexec_b64 s[46:47], vcc
	s_cbranch_execz .LBB0_105
	s_sleep 1
	global_load_dword v2, v[0:1], off sc1
	s_waitcnt vmcnt(0) lgkmcnt(0)
	v_cmp_le_u32_e32 vcc, v2, v236
	s_and_saveexec_b64 s[68:69], vcc
	s_cbranch_execz .LBB0_104
	s_sleep 1
	global_load_dword v2, v[0:1], off sc1
	s_mov_b64 s[90:91], -1
	s_waitcnt vmcnt(0) lgkmcnt(0)
	v_cmp_le_u32_e32 vcc, v2, v236
	s_and_saveexec_b64 s[18:19], vcc
	s_cbranch_execz .LBB0_103
	s_sleep 1
	global_load_dword v2, v[0:1], off sc1
	s_mov_b64 s[48:49], -1
	s_waitcnt vmcnt(0) lgkmcnt(0)
	v_cmp_le_u32_e32 vcc, v2, v236
	s_and_saveexec_b64 s[90:91], vcc
	s_cbranch_execz .LBB0_102
	s_add_i32 s13, s13, -8
	s_xor_b64 s[48:49], exec, -1
	s_sleep 1
	s_branch .LBB0_102

; __device__ __forceinline__ unsigned xb_ld(unsigned* p) { return __hip_atomic_load(p, __ATOMIC_RELAXED, __HIP_MEMORY_SCOPE_AGENT); }
; __device__ __forceinline__ unsigned xb_add(unsigned* p, unsigned v) { return __hip_atomic_fetch_add(p, v, __ATOMIC_RELAXED, __HIP_MEMORY_SCOPE_AGENT); }
; __device__ __forceinline__ void gbar(unsigned* bar, unsigned n, volatile LAS unsigned* st) {
;     ...
;     if (old + 1u == (n + 1u) * nloc) {
;       __builtin_amdgcn_fence(__ATOMIC_RELEASE, "agent");
;       asm volatile("s_waitcnt vmcnt(0)" ::: "memory");
;       xb_add(&bar[XB_TOP], 1u);
;       while (xb_ld(&bar[XB_TOP]) < (n + 1u) * nx) { __builtin_amdgcn_s_sleep(1); if (++sp > (1u << 24)) break; }
.LBB0_123:
	s_andn2_saveexec_b64 s[6:7], s[6:7]
	s_cbranch_execz .LBB0_146
	v_mov_b32_e32 v1, s1
	v_add_co_u32_e32 v2, vcc, 0x4cc83000, v1
	v_mov_b32_e32 v1, s0
	buffer_wbl2 sc1
	s_waitcnt vmcnt(0)
	v_addc_co_u32_e32 v3, vcc, 0, v1, vcc
	global_atomic_add v[2:3], v230, off offset:256
	s_add_u32 s8, s1, 0x4cc83100
	s_addc_u32 s9, s0, 0
	v_mul_lo_u32 v0, v0, v162
	s_mov_b32 s0, 0x1000000
	s_mov_b64 s[36:37], 0
	s_branch .LBB0_134

; __device__ __forceinline__ unsigned xb_ld(unsigned* p) { return __hip_atomic_load(p, __ATOMIC_RELAXED, __HIP_MEMORY_SCOPE_AGENT); }
; __device__ __forceinline__ void gbar(unsigned* bar, unsigned n, volatile LAS unsigned* st) {
;     ...
;       while (xb_ld(&bar[XB_TOP]) < (n + 1u) * nx) { __builtin_amdgcn_s_sleep(1); if (++sp > (1u << 24)) break; }
.LBB0_134:
	v_mov_b64_e32 v[2:3], s[8:9]
	global_load_dword v1, v[2:3], off sc1
	s_or_b64 s[38:39], s[38:39], exec
	s_waitcnt vmcnt(0) lgkmcnt(0)
	v_cmp_lt_u32_e32 vcc, v1, v0
	s_and_saveexec_b64 s[40:41], vcc
	s_cbranch_execz .LBB0_133
	s_cmp_lg_u32 s0, 0
	s_sleep 1
	s_cbranch_scc0 .LBB0_144
	v_mov_b64_e32 v[2:3], s[8:9]
	global_load_dword v1, v[2:3], off sc1
	s_mov_b64 s[18:19], -1
	s_waitcnt vmcnt(0) lgkmcnt(0)
	v_cmp_lt_u32_e32 vcc, v1, v0
	s_and_saveexec_b64 s[42:43], vcc
	s_cbranch_execz .LBB0_131
	v_mov_b64_e32 v[2:3], s[8:9]
	s_sleep 1
	global_load_dword v1, v[2:3], off sc1
	s_waitcnt vmcnt(0) lgkmcnt(0)
	v_cmp_lt_u32_e32 vcc, v1, v0
	s_and_saveexec_b64 s[44:45], vcc
	s_cbranch_execz .LBB0_130
	v_mov_b64_e32 v[2:3], s[8:9]
	s_sleep 1
	global_load_dword v1, v[2:3], off sc1
	s_waitcnt vmcnt(0) lgkmcnt(0)
	v_cmp_lt_u32_e32 vcc, v1, v0
	s_and_saveexec_b64 s[46:47], vcc
	s_cbranch_execz .LBB0_129
	v_mov_b64_e32 v[2:3], s[8:9]
	s_sleep 1
	global_load_dword v1, v[2:3], off sc1
	s_waitcnt vmcnt(0) lgkmcnt(0)
	v_cmp_lt_u32_e32 vcc, v1, v0
	s_and_saveexec_b64 s[68:69], vcc
	s_cbranch_execz .LBB0_128
	v_mov_b64_e32 v[2:3], s[8:9]
	s_sleep 1
	global_load_dword v1, v[2:3], off sc1
	s_waitcnt vmcnt(0) lgkmcnt(0)
	v_cmp_lt_u32_e32 vcc, v1, v0
	s_and_saveexec_b64 s[90:91], vcc
	s_cbranch_execz .LBB0_127
	v_mov_b64_e32 v[2:3], s[8:9]
	s_sleep 1
	global_load_dword v1, v[2:3], off sc1
	s_waitcnt vmcnt(0) lgkmcnt(0)
	v_cmp_lt_u32_e32 vcc, v1, v0
	s_and_saveexec_b64 s[94:95], vcc
	s_cbranch_execz .LBB0_126
	v_mov_b64_e32 v[2:3], s[8:9]
	s_sleep 1
	global_load_dword v1, v[2:3], off sc1
	s_waitcnt vmcnt(0) lgkmcnt(0)
	v_cmp_lt_u32_e32 vcc, v1, v0
	s_and_saveexec_b64 s[48:49], vcc
	s_cbranch_execz .LBB0_125
	s_add_i32 s0, s0, -8
	s_xor_b64 s[18:19], exec, -1
	s_sleep 1
	s_branch .LBB0_125

; #define LAS __attribute__((address_space(3)))
; __device__ __forceinline__ int otid() { int t = threadIdx.x; asm volatile("" : "+v"(t)); return t; }
;   __device__ __forceinline__ bool next(int i, Unit& u) const {
;     ...
;     } else if (mode == 2) {
;       const int g = L >> 3, dt = L & 7;
;       u.a0 = A;
;       u.b0 = B + ((size_t)dt * 256 * 4096 + (size_t)g * 256) * 2; u.b1 = u.b0 + (size_t)128 * 4096 * 2;
;       u.r0 = g * 128; u.c0 = dt * 256; u.C = C;
; __device__ __forceinline__ int build_units(LAS unsigned char* lds, const Map& m) {
;   LAS Unit* ul = (LAS Unit*)(lds + STAGE_BYTES);
;   __syncthreads();
;   const int tid_ = otid();
;   if (tid_ < MAX_UNITS) { Unit u; if (m.next(tid_, u)) {
;       LAS unsigned long long* w = (LAS unsigned long long*)(ul + tid_);
;       w[0] = (unsigned long long)u.a0; w[1] = (unsigned long long)u.b0; w[2] = (unsigned long long)u.b1; w[3] = (unsigned long long)u.C;
;       w[4] = ((unsigned long long)(unsigned)u.c0 << 32) | (unsigned)u.r0; } }
;   __syncthreads();
.LBB0_147:
	s_or_b64 exec, exec, s[2:3]
	s_and_b64 s[0:1], s[92:93], exec
	s_movk_i32 s0, 0x2000
	s_cselect_b32 s17, s0, 0x4000
	v_readlane_b32 s0, v255, 26
	v_readlane_b32 s1, v255, 27
	s_cselect_b32 s89, 2, 1
	s_lshl_b32 s90, s88, 25
	s_mov_b32 s91, s12
	s_mov_b64 s[2:3], -1
	s_and_b64 vcc, exec, s[0:1]
	s_waitcnt lgkmcnt(0)
	s_barrier
	s_cbranch_vccz .LBB0_575
	s_andn2_b64 vcc, exec, s[92:93]
	v_mov_b32_e32 v158, v162
	s_cbranch_vccnz .LBB0_218
	v_mov_b64_e32 v[0:1], s[10:11]
	global_load_dwordx2 v[2:3], v[0:1], off sc0 sc1
	s_waitcnt vmcnt(0) lgkmcnt(0)
	v_readfirstlane_b32 s0, v3
	v_readfirstlane_b32 s1, v2
	global_load_dwordx2 v[2:3], v[0:1], off sc0 sc1
	s_waitcnt vmcnt(0) lgkmcnt(0)
	v_readfirstlane_b32 s4, v2
	global_load_dwordx2 v[0:1], v[0:1], off sc0 sc1
	s_waitcnt vmcnt(0)
	v_mov_b32_e32 v2, v252
	v_readfirstlane_b32 s5, v3
	s_waitcnt lgkmcnt(0)
	v_readfirstlane_b32 s8, v0
	v_mov_b32_e32 v0, s74
	ds_read_b32 v0, v0
	v_readfirstlane_b32 s7, v1
	s_waitcnt lgkmcnt(0)
	s_barrier
	v_readfirstlane_b32 s6, v0
	s_ashr_i32 s9, s6, 31
	v_mov_b32_e32 v1, s9
	v_mov_b32_e32 v0, s6
	s_nop 0
	v_mad_i64_i32 v[0:1], s[2:3], v2, s20, v[0:1]
	v_cmp_gt_i32_e32 vcc, 40, v2
	v_cmp_gt_i64_e64 s[2:3], s[52:53], v[0:1]
	s_and_b64 s[18:19], vcc, s[2:3]
	s_and_saveexec_b64 s[2:3], s[18:19]
	s_cbranch_execz .LBB0_151
	v_ashrrev_i32_e32 v8, 3, v0
	v_ashrrev_i32_e32 v9, 31, v8
	v_lshlrev_b32_e32 v1, 21, v0
	v_lshlrev_b64 v[4:5], 9, v[8:9]
	v_and_b32_e32 v80, 0xe00000, v1
	v_lshl_add_u64 v[4:5], s[4:5], 0, v[4:5]
	v_lshl_add_u64 v[6:7], v[4:5], 0, v[80:81]
	s_mov_b64 s[4:5], 0x6900000
	v_lshl_add_u64 v[4:5], v[6:7], 0, s[4:5]
	s_mov_b64 s[4:5], 0x6a00000
	v_lshlrev_b32_e32 v0, 8, v0
	s_add_u32 s1, s1, 0x7900000
	v_lshl_add_u64 v[6:7], v[6:7], 0, s[4:5]
	v_and_b32_e32 v11, 0x700, v0
	v_mad_u64_u32 v[0:1], s[4:5], v2, 48, v[232:233]
	s_addc_u32 s0, s0, 0
	v_lshlrev_b32_e32 v10, 7, v8
	v_add_u32_e32 v0, 0x20000, v0
	v_mov_b32_e32 v2, s1
	v_mov_b32_e32 v3, s0
	v_mov_b32_e32 v8, s8
	v_mov_b32_e32 v9, s7
	ds_write_b128 v0, v[2:5]
	ds_write_b128 v0, v[6:9] offset:16
	ds_write_b64 v0, v[10:11] offset:32

; #define G_STAGE(bufoff, gbase, voff) do { _Pragma("unroll") for (int _i = 0; _i < 2; ++_i) { unsigned _vo = (voff)[_i]; asm volatile("" : "+v"(_vo));   \
;     __builtin_amdgcn_global_load_lds((const unsigned*)((const char*)(gbase) + _vo), (LAS unsigned*)(lds + (bufoff) + ldsw + _i * 8192), 16, 0, 0); } } while (0)
; #define G_LDA(dst, b, h) do { _Pragma("unroll") for (int m = 0; m < 4; ++m) _Pragma("unroll") for (int k = 0; k < 2; ++k) dst[m][k] = *(const LAS bf16x8*)(lds + G_SA(b, h) + aoff + m * 2048 + k * 1024); } while (0)
; #define G_LDB(dst, b, h) do { _Pragma("unroll") for (int n = 0; n < 2; ++n) _Pragma("unroll") for (int k = 0; k < 2; ++k) dst[n][k] = *(const LAS bf16x8*)(lds + G_SB(b, h) + boff + n * 2048 + k * 1024); } while (0)
; #define G_MMA(ai, bj, At, Bt) do { __builtin_amdgcn_s_setprio(1); _Pragma("unroll") for (int m = 0; m < 4; ++m) _Pragma("unroll") for (int n = 0; n < 2; ++n) _Pragma("unroll") for (int k = 0; k < 2; ++k) \
;     acc[ai][bj][m][n] = __builtin_amdgcn_mfma_f32_16x16x32_bf16(Bt[n][k], At[m][k], acc[ai][bj][m][n], 0, 0, 0); __builtin_amdgcn_s_setprio(0); } while (0)
; #define G_WAIT_V(n) asm volatile("s_waitcnt vmcnt(" #n ")" ::: "memory")
; #define G_WAIT_L(n) asm volatile("s_waitcnt lgkmcnt(" #n ")" ::: "memory")
; #define G_BAR __builtin_amdgcn_s_barrier()
; #define G_SCHED __builtin_amdgcn_sched_barrier(0)
; template <class Epi>
; __device__ __forceinline__ void gemm_phase(LAS unsigned char* lds, const int K, const unsigned lda_b, const unsigned ldb_b, const Map& M, const Epi& E) {
;     ...
;       G_LDB(B0, 0, 0); G_SCHED; G_LDA(At, 0, 0); G_STAGE(G_SA(1, 1), a1h1, voffA);
;       G_WAIT_L(8); G_BAR; G_WAIT_L(0); G_MMA(0, 0, At, B0); G_BAR; G_SCHED;
;       G_LDB(B1, 0, 1); G_STAGE(G_SB(0, 0), b2h0, voffB);
;       G_BAR; G_WAIT_L(0); G_MMA(0, 1, At, B1); G_BAR;
;       G_LDA(At, 0, 1); G_STAGE(G_SA(0, 0), a2h0, voffA);
;       G_BAR; G_WAIT_L(0); G_MMA(1, 0, At, B0); G_BAR; G_SCHED;
;       G_STAGE(G_SB(0, 1), b2h1, voffB);
;       G_WAIT_V(6); G_BAR; G_MMA(1, 1, At, B1); G_BAR;
.LBB0_161:
	s_mov_b64 s[42:43], s[2:3]
	s_add_i32 s2, s61, -1
	s_cmp_lt_i32 s61, s0
	s_cselect_b32 s2, s61, s2
	s_mul_i32 s2, s2, 48
	s_add_i32 s2, s2, 0
	s_add_i32 s2, s2, 0x20000
	v_mov_b32_e32 v4, s2
	ds_read_b128 v[0:3], v4
	s_waitcnt lgkmcnt(0)
	v_readfirstlane_b32 s8, v2
	v_readfirstlane_b32 s9, v3
	s_add_u32 s2, s8, 0x40000
	s_addc_u32 s3, s9, 0
	s_add_i32 s30, 0, 0x10000
	v_add_u32_e32 v83, s30, v89
	v_readfirstlane_b32 s6, v0
	v_readfirstlane_b32 s7, v1
	ds_read2_b64 v[0:3], v4 offset0:3 offset1:4
	ds_read_b128 v[4:7], v83
	ds_read_b128 v[8:11], v83 offset:1024
	ds_read_b128 v[12:15], v83 offset:2048
	ds_read_b128 v[16:19], v83 offset:3072
	s_add_u32 s34, s38, 0x10080
	s_addc_u32 s35, s39, 0
	s_waitcnt lgkmcnt(0)
	v_readfirstlane_b32 s36, v0
	v_readfirstlane_b32 s37, v1
	s_add_u32 s44, s38, 0x10100
	s_addc_u32 s45, s39, 0
	v_mov_b32_e32 v0, v84
	s_add_i32 s31, s46, 0xc000
	ds_read_b128 v[20:23], v97
	ds_read_b128 v[24:27], v97 offset:1024
	ds_read_b128 v[28:31], v97 offset:2048
	ds_read_b128 v[32:35], v97 offset:3072
	ds_read_b128 v[36:39], v97 offset:4096
	ds_read_b128 v[40:43], v97 offset:5120
	ds_read_b128 v[44:47], v97 offset:6144
	ds_read_b128 v[48:51], v97 offset:7168
	s_mov_b32 m0, s31
	s_add_i32 s28, s46, 0xe000
	global_load_lds_dwordx4 v0, s[34:35]
	v_mov_b32_e32 v0, v86
	s_mov_b32 m0, s28
	s_nop 0
	global_load_lds_dwordx4 v0, s[34:35]
	s_waitcnt lgkmcnt(8)
	s_barrier
	s_waitcnt lgkmcnt(0)
	s_setprio 1
	s_waitcnt lgkmcnt(0)
	v_mfma_f32_16x16x32_bf16 v[52:55], v[4:7], v[20:23], 0
	v_mfma_f32_16x16x32_bf16 v[56:59], v[12:15], v[20:23], 0
	v_mfma_f32_16x16x32_bf16 v[60:63], v[4:7], v[28:31], 0
	v_mfma_f32_16x16x32_bf16 v[64:67], v[12:15], v[28:31], 0
	v_mfma_f32_16x16x32_bf16 v[68:71], v[4:7], v[36:39], 0
	v_mfma_f32_16x16x32_bf16 v[72:75], v[12:15], v[36:39], 0
	v_mfma_f32_16x16x32_bf16 v[76:79], v[4:7], v[44:47], 0
	v_mfma_f32_16x16x32_bf16 v[98:101], v[12:15], v[44:47], 0
	v_mfma_f32_16x16x32_bf16 v[52:55], v[8:11], v[24:27], v[52:55]
	v_mfma_f32_16x16x32_bf16 v[56:59], v[16:19], v[24:27], v[56:59]
	v_mfma_f32_16x16x32_bf16 v[60:63], v[8:11], v[32:35], v[60:63]
	v_mfma_f32_16x16x32_bf16 v[64:67], v[16:19], v[32:35], v[64:67]
	v_mfma_f32_16x16x32_bf16 v[68:71], v[8:11], v[40:43], v[68:71]
	v_mfma_f32_16x16x32_bf16 v[72:75], v[16:19], v[40:43], v[72:75]
	v_mfma_f32_16x16x32_bf16 v[76:79], v[8:11], v[48:51], v[76:79]
	v_mfma_f32_16x16x32_bf16 v[98:101], v[16:19], v[48:51], v[98:101]
	s_setprio 0
	s_barrier
	s_add_i32 s34, 0, 0x14000
	v_add_u32_e32 v90, s34, v89
	v_mov_b32_e32 v80, v85
	ds_read_b128 v[102:105], v90
	ds_read_b128 v[106:109], v90 offset:1024
	ds_read_b128 v[110:113], v90 offset:2048
	ds_read_b128 v[114:117], v90 offset:3072
	s_add_i32 s30, s30, s13
	v_lshl_add_u64 v[0:1], s[40:41], 0, v[80:81]
	v_lshl_add_u64 v[0:1], v[0:1], 0, s[54:55]
	s_mov_b32 m0, s30
	v_mov_b32_e32 v80, v87
	global_load_lds_dwordx4 v[0:1], off
	s_add_i32 s29, s30, 0x2000
	v_lshl_add_u64 v[0:1], s[40:41], 0, v[80:81]
	v_lshl_add_u64 v[0:1], v[0:1], 0, s[54:55]
	s_mov_b32 m0, s29
	s_nop 0
	global_load_lds_dwordx4 v[0:1], off
	s_barrier
	s_waitcnt lgkmcnt(0)
	s_setprio 1
	s_waitcnt lgkmcnt(0)
	v_mfma_f32_16x16x32_bf16 v[118:121], v[102:105], v[20:23], 0
	v_mfma_f32_16x16x32_bf16 v[20:23], v[110:113], v[20:23], 0
	v_mfma_f32_16x16x32_bf16 v[118:121], v[106:109], v[24:27], v[118:121]
	v_mfma_f32_16x16x32_bf16 v[20:23], v[114:117], v[24:27], v[20:23]
	v_mfma_f32_16x16x32_bf16 v[24:27], v[102:105], v[28:31], 0
	v_mfma_f32_16x16x32_bf16 v[28:31], v[110:113], v[28:31], 0
	v_mfma_f32_16x16x32_bf16 v[24:27], v[106:109], v[32:35], v[24:27]
	v_mfma_f32_16x16x32_bf16 v[28:31], v[114:117], v[32:35], v[28:31]
	v_mfma_f32_16x16x32_bf16 v[32:35], v[102:105], v[36:39], 0
	v_mfma_f32_16x16x32_bf16 v[36:39], v[110:113], v[36:39], 0
	v_mfma_f32_16x16x32_bf16 v[32:35], v[106:109], v[40:43], v[32:35]
	v_mfma_f32_16x16x32_bf16 v[36:39], v[114:117], v[40:43], v[36:39]
	v_mfma_f32_16x16x32_bf16 v[40:43], v[102:105], v[44:47], 0
	v_mfma_f32_16x16x32_bf16 v[44:47], v[110:113], v[44:47], 0
	v_mfma_f32_16x16x32_bf16 v[40:43], v[106:109], v[48:51], v[40:43]
	v_mfma_f32_16x16x32_bf16 v[44:47], v[114:117], v[48:51], v[44:47]
	s_setprio 0
	v_mov_b32_e32 v80, v84
	s_barrier
	ds_read_b128 v[48:51], v97 offset:16384
	ds_read_b128 v[122:125], v97 offset:17408
	ds_read_b128 v[126:129], v97 offset:18432
	ds_read_b128 v[130:133], v97 offset:19456
	ds_read_b128 v[134:137], v97 offset:20480
	ds_read_b128 v[138:141], v97 offset:21504
	ds_read_b128 v[142:145], v97 offset:22528
	ds_read_b128 v[146:149], v97 offset:23552
	s_mov_b32 m0, s46
	v_lshl_add_u64 v[0:1], s[38:39], 0, v[80:81]
	v_lshl_add_u64 v[0:1], v[0:1], 0, s[54:55]
	v_mov_b32_e32 v80, v86
	global_load_lds_dwordx4 v[0:1], off
	s_mov_b32 m0, s47
	v_lshl_add_u64 v[0:1], s[38:39], 0, v[80:81]
	v_lshl_add_u64 v[0:1], v[0:1], 0, s[54:55]
	global_load_lds_dwordx4 v[0:1], off
	s_barrier
	s_waitcnt lgkmcnt(0)
	s_setprio 1
	s_waitcnt lgkmcnt(0)
	v_mfma_f32_16x16x32_bf16 v[150:153], v[4:7], v[48:51], 0
	v_mfma_f32_16x16x32_bf16 v[158:161], v[4:7], v[126:129], 0
	v_mfma_f32_16x16x32_bf16 v[168:171], v[4:7], v[134:137], 0
	v_mfma_f32_16x16x32_bf16 v[4:7], v[4:7], v[142:145], 0
	v_mfma_f32_16x16x32_bf16 v[150:153], v[8:11], v[122:125], v[150:153]
	v_mfma_f32_16x16x32_bf16 v[154:157], v[12:15], v[48:51], 0
	v_mfma_f32_16x16x32_bf16 v[158:161], v[8:11], v[130:133], v[158:161]
	v_mfma_f32_16x16x32_bf16 v[164:167], v[12:15], v[126:129], 0
	v_mfma_f32_16x16x32_bf16 v[168:171], v[8:11], v[138:141], v[168:171]
	v_mfma_f32_16x16x32_bf16 v[172:175], v[12:15], v[134:137], 0
	v_mfma_f32_16x16x32_bf16 v[4:7], v[8:11], v[146:149], v[4:7]
	v_mfma_f32_16x16x32_bf16 v[8:11], v[12:15], v[142:145], 0
	v_mfma_f32_16x16x32_bf16 v[154:157], v[16:19], v[122:125], v[154:157]
	v_mfma_f32_16x16x32_bf16 v[164:167], v[16:19], v[130:133], v[164:167]
	v_mfma_f32_16x16x32_bf16 v[172:175], v[16:19], v[138:141], v[172:175]
	v_mfma_f32_16x16x32_bf16 v[8:11], v[16:19], v[146:149], v[8:11]
	s_setprio 0
	s_barrier
; #define G_STAGE(bufoff, gbase, voff) do { _Pragma("unroll") for (int _i = 0; _i < 2; ++_i) { unsigned _vo = (voff)[_i]; asm volatile("" : "+v"(_vo));   \
;     __builtin_amdgcn_global_load_lds((const unsigned*)((const char*)(gbase) + _vo), (LAS unsigned*)(lds + (bufoff) + ldsw + _i * 8192), 16, 0, 0); } } while (0)
; #define G_LDA(dst, b, h) do { _Pragma("unroll") for (int m = 0; m < 4; ++m) _Pragma("unroll") for (int k = 0; k < 2; ++k) dst[m][k] = *(const LAS bf16x8*)(lds + G_SA(b, h) + aoff + m * 2048 + k * 1024); } while (0)
; #define G_LDB(dst, b, h) do { _Pragma("unroll") for (int n = 0; n < 2; ++n) _Pragma("unroll") for (int k = 0; k < 2; ++k) dst[n][k] = *(const LAS bf16x8*)(lds + G_SB(b, h) + boff + n * 2048 + k * 1024); } while (0)
; #define G_MMA(ai, bj, At, Bt) do { __builtin_amdgcn_s_setprio(1); _Pragma("unroll") for (int m = 0; m < 4; ++m) _Pragma("unroll") for (int n = 0; n < 2; ++n) _Pragma("unroll") for (int k = 0; k < 2; ++k) \
;     acc[ai][bj][m][n] = __builtin_amdgcn_mfma_f32_16x16x32_bf16(Bt[n][k], At[m][k], acc[ai][bj][m][n], 0, 0, 0); __builtin_amdgcn_s_setprio(0); } while (0)
; #define G_WAIT_V(n) asm volatile("s_waitcnt vmcnt(" #n ")" ::: "memory")
; #define G_WAIT_L(n) asm volatile("s_waitcnt lgkmcnt(" #n ")" ::: "memory")
; #define G_BAR __builtin_amdgcn_s_barrier()
; #define G_SCHED __builtin_amdgcn_sched_barrier(0)
; template <class Epi>
; __device__ __forceinline__ void gemm_phase(LAS unsigned char* lds, const int K, const unsigned lda_b, const unsigned ldb_b, const Map& M, const Epi& E) {
;     ...
;       G_WAIT_V(6); G_BAR; G_MMA(1, 1, At, B1); G_BAR;
;       G_LDB(B0, 1, 0); G_SCHED; G_LDA(At, 1, 0); G_STAGE(G_SA(0, 1), a2h1, voffA);
;       G_WAIT_L(8); G_BAR; G_WAIT_L(0); G_MMA(0, 0, At, B0); G_BAR; G_SCHED;
;       G_LDB(B1, 1, 1); G_STAGE(G_SB(1, 0), b2h0 + kstep, voffB);
;       G_BAR; G_WAIT_L(0); G_MMA(0, 1, At, B1); G_BAR;
;       G_LDA(At, 1, 1); G_STAGE(G_SA(1, 0), a2h0 + kstep, voffA);
;       G_BAR; G_WAIT_L(0); G_MMA(1, 0, At, B0); G_BAR; G_SCHED;
;       G_STAGE(G_SB(1, 1), b2h1 + kstep, voffB);
;       G_WAIT_V(6); G_BAR; G_MMA(1, 1, At, B1); G_BAR;
	v_mov_b32_e32 v80, v85
	s_add_i32 s34, s34, s13
	v_lshl_add_u64 v[0:1], s[42:43], 0, v[80:81]
	v_lshl_add_u64 v[0:1], v[0:1], 0, s[54:55]
	s_mov_b32 m0, s34
	v_mov_b32_e32 v80, v87
	global_load_lds_dwordx4 v[0:1], off
	s_add_i32 s35, s34, 0x2000
	v_lshl_add_u64 v[0:1], s[42:43], 0, v[80:81]
	v_lshl_add_u64 v[0:1], v[0:1], 0, s[54:55]
	s_mov_b32 m0, s35
	s_nop 0
	global_load_lds_dwordx4 v[0:1], off
	s_waitcnt vmcnt(6)
	s_barrier
	s_setprio 1
	v_mfma_f32_16x16x32_bf16 v[12:15], v[102:105], v[48:51], 0
	v_mfma_f32_16x16x32_bf16 v[16:19], v[110:113], v[48:51], 0
	v_mfma_f32_16x16x32_bf16 v[12:15], v[106:109], v[122:125], v[12:15]
	v_mfma_f32_16x16x32_bf16 v[16:19], v[114:117], v[122:125], v[16:19]
	v_mfma_f32_16x16x32_bf16 v[48:51], v[102:105], v[126:129], 0
	v_mfma_f32_16x16x32_bf16 v[122:125], v[110:113], v[126:129], 0
	v_mfma_f32_16x16x32_bf16 v[126:129], v[102:105], v[134:137], 0
	v_mfma_f32_16x16x32_bf16 v[102:105], v[102:105], v[142:145], 0
	v_mfma_f32_16x16x32_bf16 v[48:51], v[106:109], v[130:133], v[48:51]
	v_mfma_f32_16x16x32_bf16 v[122:125], v[114:117], v[130:133], v[122:125]
	v_mfma_f32_16x16x32_bf16 v[126:129], v[106:109], v[138:141], v[126:129]
	v_mfma_f32_16x16x32_bf16 v[130:133], v[110:113], v[134:137], 0
	v_mfma_f32_16x16x32_bf16 v[102:105], v[106:109], v[146:149], v[102:105]
	v_mfma_f32_16x16x32_bf16 v[106:109], v[110:113], v[142:145], 0
	v_mfma_f32_16x16x32_bf16 v[130:133], v[114:117], v[138:141], v[130:133]
	v_mfma_f32_16x16x32_bf16 v[106:109], v[114:117], v[146:149], v[106:109]
	s_setprio 0
	s_add_i32 s22, 0, 0x18000
	v_add_u32_e32 v91, s22, v89
	s_barrier
	ds_read_b128 v[110:113], v91
	ds_read_b128 v[114:117], v91 offset:1024
	ds_read_b128 v[134:137], v91 offset:2048
	ds_read_b128 v[138:141], v91 offset:3072
	v_mov_b32_e32 v0, v84
	s_mov_b32 m0, s48
	ds_read_b128 v[142:145], v97 offset:32768
	ds_read_b128 v[146:149], v97 offset:33792
	ds_read_b128 v[190:193], v97 offset:34816
	ds_read_b128 v[194:197], v97 offset:35840
	ds_read_b128 v[198:201], v97 offset:36864
	ds_read_b128 v[202:205], v97 offset:37888
	ds_read_b128 v[206:209], v97 offset:38912
	ds_read_b128 v[210:213], v97 offset:39936
	s_nop 0
	global_load_lds_dwordx4 v0, s[44:45]
	v_mov_b32_e32 v0, v86
	s_mov_b32 m0, s49
	s_nop 0
	global_load_lds_dwordx4 v0, s[44:45]
	s_waitcnt lgkmcnt(8)
	s_barrier
	s_waitcnt lgkmcnt(0)
	s_setprio 1
	s_waitcnt lgkmcnt(0)
	v_mfma_f32_16x16x32_bf16 v[52:55], v[110:113], v[142:145], v[52:55]
	v_mfma_f32_16x16x32_bf16 v[56:59], v[134:137], v[142:145], v[56:59]
	v_mfma_f32_16x16x32_bf16 v[60:63], v[110:113], v[190:193], v[60:63]
	v_mfma_f32_16x16x32_bf16 v[64:67], v[134:137], v[190:193], v[64:67]
	v_mfma_f32_16x16x32_bf16 v[68:71], v[110:113], v[198:201], v[68:71]
	v_mfma_f32_16x16x32_bf16 v[72:75], v[134:137], v[198:201], v[72:75]
	v_mfma_f32_16x16x32_bf16 v[76:79], v[110:113], v[206:209], v[76:79]
	v_mfma_f32_16x16x32_bf16 v[98:101], v[134:137], v[206:209], v[98:101]
	v_mfma_f32_16x16x32_bf16 v[52:55], v[114:117], v[146:149], v[52:55]
	v_mfma_f32_16x16x32_bf16 v[56:59], v[138:141], v[146:149], v[56:59]
	v_mfma_f32_16x16x32_bf16 v[60:63], v[114:117], v[194:197], v[60:63]
	v_mfma_f32_16x16x32_bf16 v[64:67], v[138:141], v[194:197], v[64:67]
	v_mfma_f32_16x16x32_bf16 v[68:71], v[114:117], v[202:205], v[68:71]
	v_mfma_f32_16x16x32_bf16 v[72:75], v[138:141], v[202:205], v[72:75]
	v_mfma_f32_16x16x32_bf16 v[76:79], v[114:117], v[210:213], v[76:79]
	v_mfma_f32_16x16x32_bf16 v[98:101], v[138:141], v[210:213], v[98:101]
	s_setprio 0
	s_barrier
	s_add_i32 s44, 0, 0x1c000
	v_add_u32_e32 v92, s44, v89
	v_mov_b32_e32 v80, v85
	ds_read_b128 v[214:217], v92
	ds_read_b128 v[226:229], v92 offset:1024
	ds_read_b128 v[238:241], v92 offset:2048
	ds_read_b128 v[242:245], v92 offset:3072
	s_add_i32 s45, s22, s13
	v_lshl_add_u64 v[0:1], s[40:41], 0, v[80:81]
	v_lshl_add_u64 v[0:1], v[0:1], 0, s[56:57]
	s_mov_b32 m0, s45
	v_mov_b32_e32 v80, v87
	global_load_lds_dwordx4 v[0:1], off
	s_nop 0
	v_lshl_add_u64 v[0:1], s[40:41], 0, v[80:81]
	s_add_i32 s40, s45, 0x2000
	v_lshl_add_u64 v[0:1], v[0:1], 0, s[56:57]
	s_mov_b32 m0, s40
	s_nop 0
	global_load_lds_dwordx4 v[0:1], off
	s_barrier
	s_waitcnt lgkmcnt(0)
	s_setprio 1
	s_waitcnt lgkmcnt(0)
	v_mfma_f32_16x16x32_bf16 v[118:121], v[214:217], v[142:145], v[118:121]
	v_mfma_f32_16x16x32_bf16 v[20:23], v[238:241], v[142:145], v[20:23]
	v_mfma_f32_16x16x32_bf16 v[24:27], v[214:217], v[190:193], v[24:27]
	v_mfma_f32_16x16x32_bf16 v[28:31], v[238:241], v[190:193], v[28:31]
	v_mfma_f32_16x16x32_bf16 v[32:35], v[214:217], v[198:201], v[32:35]
	v_mfma_f32_16x16x32_bf16 v[36:39], v[238:241], v[198:201], v[36:39]
	v_mfma_f32_16x16x32_bf16 v[40:43], v[214:217], v[206:209], v[40:43]
	v_mfma_f32_16x16x32_bf16 v[44:47], v[238:241], v[206:209], v[44:47]
	v_mfma_f32_16x16x32_bf16 v[118:121], v[226:229], v[146:149], v[118:121]
	v_mfma_f32_16x16x32_bf16 v[20:23], v[242:245], v[146:149], v[20:23]
	v_mfma_f32_16x16x32_bf16 v[24:27], v[226:229], v[194:197], v[24:27]
	v_mfma_f32_16x16x32_bf16 v[28:31], v[242:245], v[194:197], v[28:31]
	v_mfma_f32_16x16x32_bf16 v[32:35], v[226:229], v[202:205], v[32:35]
	v_mfma_f32_16x16x32_bf16 v[36:39], v[242:245], v[202:205], v[36:39]
	v_mfma_f32_16x16x32_bf16 v[40:43], v[226:229], v[210:213], v[40:43]
	v_mfma_f32_16x16x32_bf16 v[44:47], v[242:245], v[210:213], v[44:47]
	s_setprio 0
	v_mov_b32_e32 v80, v84
	s_barrier
; #define G_STAGE(bufoff, gbase, voff) do { _Pragma("unroll") for (int _i = 0; _i < 2; ++_i) { unsigned _vo = (voff)[_i]; asm volatile("" : "+v"(_vo));   \
;     __builtin_amdgcn_global_load_lds((const unsigned*)((const char*)(gbase) + _vo), (LAS unsigned*)(lds + (bufoff) + ldsw + _i * 8192), 16, 0, 0); } } while (0)
; #define G_LDA(dst, b, h) do { _Pragma("unroll") for (int m = 0; m < 4; ++m) _Pragma("unroll") for (int k = 0; k < 2; ++k) dst[m][k] = *(const LAS bf16x8*)(lds + G_SA(b, h) + aoff + m * 2048 + k * 1024); } while (0)
; #define G_LDB(dst, b, h) do { _Pragma("unroll") for (int n = 0; n < 2; ++n) _Pragma("unroll") for (int k = 0; k < 2; ++k) dst[n][k] = *(const LAS bf16x8*)(lds + G_SB(b, h) + boff + n * 2048 + k * 1024); } while (0)
; #define G_MMA(ai, bj, At, Bt) do { __builtin_amdgcn_s_setprio(1); _Pragma("unroll") for (int m = 0; m < 4; ++m) _Pragma("unroll") for (int n = 0; n < 2; ++n) _Pragma("unroll") for (int k = 0; k < 2; ++k) \
;     acc[ai][bj][m][n] = __builtin_amdgcn_mfma_f32_16x16x32_bf16(Bt[n][k], At[m][k], acc[ai][bj][m][n], 0, 0, 0); __builtin_amdgcn_s_setprio(0); } while (0)
; #define G_WAIT_V(n) asm volatile("s_waitcnt vmcnt(" #n ")" ::: "memory")
; template <class Epi>
; __device__ __forceinline__ void gemm_phase(LAS unsigned char* lds, const int K, const unsigned lda_b, const unsigned ldb_b, const Map& M, const Epi& E) {
;     ...
;       G_LDB(B0, 0, 0); G_SCHED; G_LDA(At, 0, 0); G_STAGE(G_SA(1, 1), a1h1, voffA);
;       G_WAIT_L(8); G_BAR; G_WAIT_L(0); G_MMA(0, 0, At, B0); G_BAR; G_SCHED;
;       G_LDB(B1, 0, 1); G_STAGE(G_SB(0, 0), b2h0, voffB);
;       G_BAR; G_WAIT_L(0); G_MMA(0, 1, At, B1); G_BAR;
;       G_LDA(At, 0, 1); G_STAGE(G_SA(0, 0), a2h0, voffA);
;       G_BAR; G_WAIT_L(0); G_MMA(1, 0, At, B0); G_BAR; G_SCHED;
;       G_STAGE(G_SB(0, 1), b2h1, voffB);
;       G_WAIT_V(6); G_BAR; G_MMA(1, 1, At, B1); G_BAR;
;       G_LDB(B0, 1, 0); G_SCHED; G_LDA(At, 1, 0); G_STAGE(G_SA(0, 1), a2h1, voffA);
;       G_WAIT_L(8); G_BAR; G_WAIT_L(0); G_MMA(0, 0, At, B0); G_BAR; G_SCHED;
;       G_LDB(B1, 1, 1); G_STAGE(G_SB(1, 0), b2h0 + kstep, voffB);
;       G_BAR; G_WAIT_L(0); G_MMA(0, 1, At, B1); G_BAR;
;       G_LDA(At, 1, 1); G_STAGE(G_SA(1, 0), a2h0 + kstep, voffA);
;       G_BAR; G_WAIT_L(0); G_MMA(1, 0, At, B0); G_BAR; G_SCHED;
;       G_STAGE(G_SB(1, 1), b2h1 + kstep, voffB);
;       G_WAIT_V(6); G_BAR; G_MMA(1, 1, At, B1); G_BAR;
	ds_read_b128 v[142:145], v97 offset:49152
	ds_read_b128 v[146:149], v97 offset:50176
	ds_read_b128 v[190:193], v97 offset:51200
	ds_read_b128 v[194:197], v97 offset:52224
	ds_read_b128 v[198:201], v97 offset:53248
	ds_read_b128 v[202:205], v97 offset:54272
	ds_read_b128 v[206:209], v97 offset:55296
	ds_read_b128 v[210:213], v97 offset:56320
	s_mov_b32 m0, s66
	v_lshl_add_u64 v[0:1], s[38:39], 0, v[80:81]
	v_lshl_add_u64 v[0:1], v[0:1], 0, s[56:57]
	v_mov_b32_e32 v80, v86
	global_load_lds_dwordx4 v[0:1], off
	s_mov_b32 m0, s67
	v_lshl_add_u64 v[0:1], s[38:39], 0, v[80:81]
	v_lshl_add_u64 v[0:1], v[0:1], 0, s[56:57]
	global_load_lds_dwordx4 v[0:1], off
	s_barrier
	s_waitcnt lgkmcnt(0)
	s_setprio 1
	s_waitcnt lgkmcnt(0)
	v_mfma_f32_16x16x32_bf16 v[150:153], v[110:113], v[142:145], v[150:153]
	v_mfma_f32_16x16x32_bf16 v[154:157], v[134:137], v[142:145], v[154:157]
	v_mfma_f32_16x16x32_bf16 v[158:161], v[110:113], v[190:193], v[158:161]
	v_mfma_f32_16x16x32_bf16 v[164:167], v[134:137], v[190:193], v[164:167]
	v_mfma_f32_16x16x32_bf16 v[168:171], v[110:113], v[198:201], v[168:171]
	v_mfma_f32_16x16x32_bf16 v[172:175], v[134:137], v[198:201], v[172:175]
	v_mfma_f32_16x16x32_bf16 v[4:7], v[110:113], v[206:209], v[4:7]
	v_mfma_f32_16x16x32_bf16 v[8:11], v[134:137], v[206:209], v[8:11]
	v_mfma_f32_16x16x32_bf16 v[150:153], v[114:117], v[146:149], v[150:153]
	v_mfma_f32_16x16x32_bf16 v[154:157], v[138:141], v[146:149], v[154:157]
	v_mfma_f32_16x16x32_bf16 v[158:161], v[114:117], v[194:197], v[158:161]
	v_mfma_f32_16x16x32_bf16 v[164:167], v[138:141], v[194:197], v[164:167]
	v_mfma_f32_16x16x32_bf16 v[168:171], v[114:117], v[202:205], v[168:171]
	v_mfma_f32_16x16x32_bf16 v[172:175], v[138:141], v[202:205], v[172:175]
	v_mfma_f32_16x16x32_bf16 v[4:7], v[114:117], v[210:213], v[4:7]
	v_mfma_f32_16x16x32_bf16 v[8:11], v[138:141], v[210:213], v[8:11]
	s_setprio 0
	s_barrier
	v_mov_b32_e32 v80, v85
	s_add_i32 s44, s44, s13
	v_lshl_add_u64 v[0:1], s[42:43], 0, v[80:81]
	v_lshl_add_u64 v[0:1], v[0:1], 0, s[56:57]
	s_mov_b32 m0, s44
	v_mov_b32_e32 v80, v87
	global_load_lds_dwordx4 v[0:1], off
	s_add_i32 s41, s44, 0x2000
	v_lshl_add_u64 v[0:1], s[42:43], 0, v[80:81]
	v_lshl_add_u64 v[0:1], v[0:1], 0, s[56:57]
	s_mov_b32 m0, s41
	s_nop 0
	global_load_lds_dwordx4 v[0:1], off
	s_waitcnt vmcnt(6)
	s_barrier
	s_setprio 1
	v_mfma_f32_16x16x32_bf16 v[12:15], v[214:217], v[142:145], v[12:15]
	v_mfma_f32_16x16x32_bf16 v[16:19], v[238:241], v[142:145], v[16:19]
	v_mfma_f32_16x16x32_bf16 v[48:51], v[214:217], v[190:193], v[48:51]
	v_mfma_f32_16x16x32_bf16 v[110:113], v[238:241], v[190:193], v[122:125]
	v_mfma_f32_16x16x32_bf16 v[114:117], v[214:217], v[198:201], v[126:129]
	v_mfma_f32_16x16x32_bf16 v[122:125], v[238:241], v[198:201], v[130:133]
	v_mfma_f32_16x16x32_bf16 v[102:105], v[214:217], v[206:209], v[102:105]
	v_mfma_f32_16x16x32_bf16 v[106:109], v[238:241], v[206:209], v[106:109]
	v_mfma_f32_16x16x32_bf16 v[12:15], v[226:229], v[146:149], v[12:15]
	v_mfma_f32_16x16x32_bf16 v[16:19], v[242:245], v[146:149], v[16:19]
	v_mfma_f32_16x16x32_bf16 v[48:51], v[226:229], v[194:197], v[48:51]
	v_mfma_f32_16x16x32_bf16 v[110:113], v[242:245], v[194:197], v[110:113]
	v_mfma_f32_16x16x32_bf16 v[114:117], v[226:229], v[202:205], v[114:117]
	v_mfma_f32_16x16x32_bf16 v[122:125], v[242:245], v[202:205], v[122:125]
	v_mfma_f32_16x16x32_bf16 v[102:105], v[226:229], v[210:213], v[102:105]
	v_mfma_f32_16x16x32_bf16 v[106:109], v[242:245], v[210:213], v[106:109]
	s_setprio 0
	s_barrier
	ds_read_b128 v[126:129], v83
	ds_read_b128 v[130:133], v83 offset:1024
	ds_read_b128 v[134:137], v83 offset:2048
	ds_read_b128 v[138:141], v83 offset:3072
	s_add_u32 s38, s38, 0x10180
	s_addc_u32 s39, s39, 0
	v_mov_b32_e32 v0, v84
	s_mov_b32 m0, s31
	ds_read_b128 v[142:145], v97
	ds_read_b128 v[146:149], v97 offset:1024
	ds_read_b128 v[190:193], v97 offset:2048
	ds_read_b128 v[194:197], v97 offset:3072
	ds_read_b128 v[198:201], v97 offset:4096
	ds_read_b128 v[202:205], v97 offset:5120
	ds_read_b128 v[206:209], v97 offset:6144
	ds_read_b128 v[210:213], v97 offset:7168
	s_nop 0
	global_load_lds_dwordx4 v0, s[38:39]
	v_mov_b32_e32 v0, v86
	s_mov_b32 m0, s28
	s_nop 0
	global_load_lds_dwordx4 v0, s[38:39]
	s_waitcnt lgkmcnt(8)
	s_barrier
	s_waitcnt lgkmcnt(0)
	s_add_u32 s38, s6, 0x10000
	s_addc_u32 s39, s7, 0
	s_setprio 1
	s_waitcnt lgkmcnt(0)
	v_mfma_f32_16x16x32_bf16 v[52:55], v[126:129], v[142:145], v[52:55]
	v_mfma_f32_16x16x32_bf16 v[56:59], v[134:137], v[142:145], v[56:59]
	v_mfma_f32_16x16x32_bf16 v[60:63], v[126:129], v[190:193], v[60:63]
	v_mfma_f32_16x16x32_bf16 v[64:67], v[134:137], v[190:193], v[64:67]
	v_mfma_f32_16x16x32_bf16 v[68:71], v[126:129], v[198:201], v[68:71]
	v_mfma_f32_16x16x32_bf16 v[72:75], v[134:137], v[198:201], v[72:75]
	v_mfma_f32_16x16x32_bf16 v[76:79], v[126:129], v[206:209], v[76:79]
	v_mfma_f32_16x16x32_bf16 v[98:101], v[134:137], v[206:209], v[98:101]
	v_mfma_f32_16x16x32_bf16 v[52:55], v[130:133], v[146:149], v[52:55]
	v_mfma_f32_16x16x32_bf16 v[56:59], v[138:141], v[146:149], v[56:59]
	v_mfma_f32_16x16x32_bf16 v[60:63], v[130:133], v[194:197], v[60:63]
	v_mfma_f32_16x16x32_bf16 v[64:67], v[138:141], v[194:197], v[64:67]
	v_mfma_f32_16x16x32_bf16 v[68:71], v[130:133], v[202:205], v[68:71]
	v_mfma_f32_16x16x32_bf16 v[72:75], v[138:141], v[202:205], v[72:75]
	v_mfma_f32_16x16x32_bf16 v[76:79], v[130:133], v[210:213], v[76:79]
	v_mfma_f32_16x16x32_bf16 v[98:101], v[138:141], v[210:213], v[98:101]
	s_setprio 0
	s_barrier
; #define G_STAGE(bufoff, gbase, voff) do { _Pragma("unroll") for (int _i = 0; _i < 2; ++_i) { unsigned _vo = (voff)[_i]; asm volatile("" : "+v"(_vo));   \
;     __builtin_amdgcn_global_load_lds((const unsigned*)((const char*)(gbase) + _vo), (LAS unsigned*)(lds + (bufoff) + ldsw + _i * 8192), 16, 0, 0); } } while (0)
; #define G_LDA(dst, b, h) do { _Pragma("unroll") for (int m = 0; m < 4; ++m) _Pragma("unroll") for (int k = 0; k < 2; ++k) dst[m][k] = *(const LAS bf16x8*)(lds + G_SA(b, h) + aoff + m * 2048 + k * 1024); } while (0)
; #define G_LDB(dst, b, h) do { _Pragma("unroll") for (int n = 0; n < 2; ++n) _Pragma("unroll") for (int k = 0; k < 2; ++k) dst[n][k] = *(const LAS bf16x8*)(lds + G_SB(b, h) + boff + n * 2048 + k * 1024); } while (0)
; #define G_MMA(ai, bj, At, Bt) do { __builtin_amdgcn_s_setprio(1); _Pragma("unroll") for (int m = 0; m < 4; ++m) _Pragma("unroll") for (int n = 0; n < 2; ++n) _Pragma("unroll") for (int k = 0; k < 2; ++k) \
;     acc[ai][bj][m][n] = __builtin_amdgcn_mfma_f32_16x16x32_bf16(Bt[n][k], At[m][k], acc[ai][bj][m][n], 0, 0, 0); __builtin_amdgcn_s_setprio(0); } while (0)
; #define G_WAIT_V(n) asm volatile("s_waitcnt vmcnt(" #n ")" ::: "memory")
; template <class Epi>
; __device__ __forceinline__ void gemm_phase(LAS unsigned char* lds, const int K, const unsigned lda_b, const unsigned ldb_b, const Map& M, const Epi& E) {
;     ...
;       G_LDB(B0, 0, 0); G_SCHED; G_LDA(At, 0, 0); G_STAGE(G_SA(1, 1), a1h1, voffA);
;       G_WAIT_L(8); G_BAR; G_WAIT_L(0); G_MMA(0, 0, At, B0); G_BAR; G_SCHED;
;       G_LDB(B1, 0, 1); G_STAGE(G_SB(0, 0), b2h0, voffB);
;       G_BAR; G_WAIT_L(0); G_MMA(0, 1, At, B1); G_BAR;
;       G_LDA(At, 0, 1); G_STAGE(G_SA(0, 0), a2h0, voffA);
;       G_BAR; G_WAIT_L(0); G_MMA(1, 0, At, B0); G_BAR; G_SCHED;
;       G_STAGE(G_SB(0, 1), b2h1, voffB);
;       G_WAIT_V(6); G_BAR; G_MMA(1, 1, At, B1); G_BAR;
;       G_LDB(B0, 1, 0); G_SCHED; G_LDA(At, 1, 0); G_STAGE(G_SA(0, 1), a2h1, voffA);
;       G_WAIT_L(8); G_BAR; G_WAIT_L(0); G_MMA(0, 0, At, B0); G_BAR; G_SCHED;
;       G_LDB(B1, 1, 1); G_STAGE(G_SB(1, 0), b2h0 + kstep, voffB);
;       G_BAR; G_WAIT_L(0); G_MMA(0, 1, At, B1); G_BAR;
;       G_LDA(At, 1, 1); G_STAGE(G_SA(1, 0), a2h0 + kstep, voffA);
;       G_BAR; G_WAIT_L(0); G_MMA(1, 0, At, B0); G_BAR; G_SCHED;
;       G_STAGE(G_SB(1, 1), b2h1 + kstep, voffB);
;       G_WAIT_V(6); G_BAR; G_MMA(1, 1, At, B1); G_BAR;
	v_mov_b32_e32 v0, v85
	s_mov_b32 m0, s30
	ds_read_b128 v[214:217], v90
	ds_read_b128 v[226:229], v90 offset:1024
	ds_read_b128 v[238:241], v90 offset:2048
	ds_read_b128 v[242:245], v90 offset:3072
	s_nop 0
	global_load_lds_dwordx4 v0, s[8:9]
	v_mov_b32_e32 v0, v87
	s_mov_b32 m0, s29
	s_nop 0
	global_load_lds_dwordx4 v0, s[8:9]
	s_barrier
	s_waitcnt lgkmcnt(0)
	s_setprio 1
	s_waitcnt lgkmcnt(0)
	v_mfma_f32_16x16x32_bf16 v[40:43], v[214:217], v[206:209], v[40:43]
	v_mfma_f32_16x16x32_bf16 v[118:121], v[214:217], v[142:145], v[118:121]
	v_mfma_f32_16x16x32_bf16 v[20:23], v[238:241], v[142:145], v[20:23]
	v_mfma_f32_16x16x32_bf16 v[24:27], v[214:217], v[190:193], v[24:27]
	v_mfma_f32_16x16x32_bf16 v[28:31], v[238:241], v[190:193], v[28:31]
	v_mfma_f32_16x16x32_bf16 v[32:35], v[214:217], v[198:201], v[32:35]
	v_mfma_f32_16x16x32_bf16 v[36:39], v[238:241], v[198:201], v[36:39]
	v_mfma_f32_16x16x32_bf16 v[142:145], v[226:229], v[210:213], v[40:43]
	v_mfma_f32_16x16x32_bf16 v[40:43], v[238:241], v[206:209], v[44:47]
	v_mfma_f32_16x16x32_bf16 v[118:121], v[226:229], v[146:149], v[118:121]
	v_mfma_f32_16x16x32_bf16 v[20:23], v[242:245], v[146:149], v[20:23]
	v_mfma_f32_16x16x32_bf16 v[24:27], v[226:229], v[194:197], v[24:27]
	v_mfma_f32_16x16x32_bf16 v[28:31], v[242:245], v[194:197], v[28:31]
	v_mfma_f32_16x16x32_bf16 v[32:35], v[226:229], v[202:205], v[32:35]
	v_mfma_f32_16x16x32_bf16 v[36:39], v[242:245], v[202:205], v[36:39]
	v_mfma_f32_16x16x32_bf16 v[44:47], v[242:245], v[210:213], v[40:43]
	s_setprio 0
	v_mov_b32_e32 v0, v84
	s_mov_b32 m0, s46
	s_barrier
	ds_read_b128 v[40:43], v97 offset:16384
	ds_read_b128 v[146:149], v97 offset:17408
	ds_read_b128 v[190:193], v97 offset:18432
	ds_read_b128 v[194:197], v97 offset:19456
	ds_read_b128 v[198:201], v97 offset:20480
	ds_read_b128 v[202:205], v97 offset:21504
	ds_read_b128 v[206:209], v97 offset:22528
	ds_read_b128 v[210:213], v97 offset:23552
	s_nop 0
	global_load_lds_dwordx4 v0, s[6:7]
	v_mov_b32_e32 v0, v86
	s_mov_b32 m0, s47
	s_nop 0
	global_load_lds_dwordx4 v0, s[6:7]
	s_barrier
	s_waitcnt lgkmcnt(0)
	s_setprio 1
	s_waitcnt lgkmcnt(0)
	v_mfma_f32_16x16x32_bf16 v[150:153], v[126:129], v[40:43], v[150:153]
	v_mfma_f32_16x16x32_bf16 v[154:157], v[134:137], v[40:43], v[154:157]
	v_mfma_f32_16x16x32_bf16 v[158:161], v[126:129], v[190:193], v[158:161]
	v_mfma_f32_16x16x32_bf16 v[164:167], v[134:137], v[190:193], v[164:167]
	v_mfma_f32_16x16x32_bf16 v[168:171], v[126:129], v[198:201], v[168:171]
	v_mfma_f32_16x16x32_bf16 v[172:175], v[134:137], v[198:201], v[172:175]
	v_mfma_f32_16x16x32_bf16 v[4:7], v[126:129], v[206:209], v[4:7]
	v_mfma_f32_16x16x32_bf16 v[8:11], v[134:137], v[206:209], v[8:11]
	v_mfma_f32_16x16x32_bf16 v[150:153], v[130:133], v[146:149], v[150:153]
	v_mfma_f32_16x16x32_bf16 v[154:157], v[138:141], v[146:149], v[154:157]
	v_mfma_f32_16x16x32_bf16 v[158:161], v[130:133], v[194:197], v[158:161]
	v_mfma_f32_16x16x32_bf16 v[164:167], v[138:141], v[194:197], v[164:167]
	v_mfma_f32_16x16x32_bf16 v[168:171], v[130:133], v[202:205], v[168:171]
	v_mfma_f32_16x16x32_bf16 v[172:175], v[138:141], v[202:205], v[172:175]
	v_mfma_f32_16x16x32_bf16 v[4:7], v[130:133], v[210:213], v[4:7]
	v_mfma_f32_16x16x32_bf16 v[126:129], v[138:141], v[210:213], v[8:11]
	s_setprio 0
	s_barrier
	v_mov_b32_e32 v0, v85
	s_mov_b32 m0, s34
	s_nop 0
	global_load_lds_dwordx4 v0, s[2:3]
	v_mov_b32_e32 v0, v87
	s_mov_b32 m0, s35
	s_nop 0
	global_load_lds_dwordx4 v0, s[2:3]
	s_waitcnt vmcnt(6)
	s_barrier
	s_setprio 1
	v_mfma_f32_16x16x32_bf16 v[8:11], v[214:217], v[40:43], v[12:15]
	v_mfma_f32_16x16x32_bf16 v[12:15], v[226:229], v[146:149], v[8:11]
	v_mfma_f32_16x16x32_bf16 v[8:11], v[238:241], v[40:43], v[16:19]
	v_mfma_f32_16x16x32_bf16 v[16:19], v[242:245], v[146:149], v[8:11]
	v_mfma_f32_16x16x32_bf16 v[8:11], v[214:217], v[190:193], v[48:51]
	v_mfma_f32_16x16x32_bf16 v[130:133], v[226:229], v[194:197], v[8:11]
	v_mfma_f32_16x16x32_bf16 v[8:11], v[238:241], v[190:193], v[110:113]
	v_mfma_f32_16x16x32_bf16 v[110:113], v[242:245], v[194:197], v[8:11]
	v_mfma_f32_16x16x32_bf16 v[8:11], v[214:217], v[198:201], v[114:117]
	v_mfma_f32_16x16x32_bf16 v[114:117], v[226:229], v[202:205], v[8:11]
	v_mfma_f32_16x16x32_bf16 v[8:11], v[238:241], v[198:201], v[122:125]
	v_mfma_f32_16x16x32_bf16 v[122:125], v[242:245], v[202:205], v[8:11]
	v_mfma_f32_16x16x32_bf16 v[8:11], v[214:217], v[206:209], v[102:105]
	v_mfma_f32_16x16x32_bf16 v[102:105], v[226:229], v[210:213], v[8:11]
	v_mfma_f32_16x16x32_bf16 v[8:11], v[238:241], v[206:209], v[106:109]
	v_mfma_f32_16x16x32_bf16 v[106:109], v[242:245], v[210:213], v[8:11]
	s_setprio 0
	s_barrier
	s_nop 4
	ds_read_b128 v[8:11], v91
	ds_read_b128 v[134:137], v91 offset:1024
	ds_read_b128 v[138:141], v91 offset:2048
	ds_read_b128 v[146:149], v91 offset:3072
	v_mov_b32_e32 v0, v84
	s_mov_b32 m0, s48
	ds_read_b128 v[190:193], v97 offset:32768
	ds_read_b128 v[194:197], v97 offset:33792
	ds_read_b128 v[198:201], v97 offset:34816
	ds_read_b128 v[202:205], v97 offset:35840
	ds_read_b128 v[206:209], v97 offset:36864
	ds_read_b128 v[210:213], v97 offset:37888
	ds_read_b128 v[214:217], v97 offset:38912
	ds_read_b128 v[226:229], v97 offset:39936
	s_nop 0
	global_load_lds_dwordx4 v0, s[38:39]
	v_mov_b32_e32 v0, v86
	s_mov_b32 m0, s49
	s_nop 0
	global_load_lds_dwordx4 v0, s[38:39]
	s_waitcnt lgkmcnt(8)
	s_barrier
; #define G_STAGE(bufoff, gbase, voff) do { _Pragma("unroll") for (int _i = 0; _i < 2; ++_i) { unsigned _vo = (voff)[_i]; asm volatile("" : "+v"(_vo));   \
;     __builtin_amdgcn_global_load_lds((const unsigned*)((const char*)(gbase) + _vo), (LAS unsigned*)(lds + (bufoff) + ldsw + _i * 8192), 16, 0, 0); } } while (0)
; #define G_LDA(dst, b, h) do { _Pragma("unroll") for (int m = 0; m < 4; ++m) _Pragma("unroll") for (int k = 0; k < 2; ++k) dst[m][k] = *(const LAS bf16x8*)(lds + G_SA(b, h) + aoff + m * 2048 + k * 1024); } while (0)
; #define G_LDB(dst, b, h) do { _Pragma("unroll") for (int n = 0; n < 2; ++n) _Pragma("unroll") for (int k = 0; k < 2; ++k) dst[n][k] = *(const LAS bf16x8*)(lds + G_SB(b, h) + boff + n * 2048 + k * 1024); } while (0)
; #define G_MMA(ai, bj, At, Bt) do { __builtin_amdgcn_s_setprio(1); _Pragma("unroll") for (int m = 0; m < 4; ++m) _Pragma("unroll") for (int n = 0; n < 2; ++n) _Pragma("unroll") for (int k = 0; k < 2; ++k) \
;     acc[ai][bj][m][n] = __builtin_amdgcn_mfma_f32_16x16x32_bf16(Bt[n][k], At[m][k], acc[ai][bj][m][n], 0, 0, 0); __builtin_amdgcn_s_setprio(0); } while (0)
; #define G_WAIT_V(n) asm volatile("s_waitcnt vmcnt(" #n ")" ::: "memory")
; template <class Epi>
; __device__ __forceinline__ void gemm_phase(LAS unsigned char* lds, const int K, const unsigned lda_b, const unsigned ldb_b, const Map& M, const Epi& E) {
;     ...
;       G_LDB(B0, 0, 0); G_SCHED; G_LDA(At, 0, 0); G_STAGE(G_SA(1, 1), a1h1, voffA);
;       G_WAIT_L(8); G_BAR; G_WAIT_L(0); G_MMA(0, 0, At, B0); G_BAR; G_SCHED;
;       G_LDB(B1, 0, 1); G_STAGE(G_SB(0, 0), b2h0, voffB);
;       G_BAR; G_WAIT_L(0); G_MMA(0, 1, At, B1); G_BAR;
;       G_LDA(At, 0, 1); G_STAGE(G_SA(0, 0), a2h0, voffA);
;       G_BAR; G_WAIT_L(0); G_MMA(1, 0, At, B0); G_BAR; G_SCHED;
;       G_STAGE(G_SB(0, 1), b2h1, voffB);
;       G_WAIT_V(6); G_BAR; G_MMA(1, 1, At, B1); G_BAR;
;       G_LDB(B0, 1, 0); G_SCHED; G_LDA(At, 1, 0); G_STAGE(G_SA(0, 1), a2h1, voffA);
;       G_WAIT_L(8); G_BAR; G_WAIT_L(0); G_MMA(0, 0, At, B0); G_BAR; G_SCHED;
;       G_LDB(B1, 1, 1); G_STAGE(G_SB(1, 0), b2h0 + kstep, voffB);
;       G_BAR; G_WAIT_L(0); G_MMA(0, 1, At, B1); G_BAR;
;       G_LDA(At, 1, 1); G_STAGE(G_SA(1, 0), a2h0 + kstep, voffA);
;       G_BAR; G_WAIT_L(0); G_MMA(1, 0, At, B0); G_BAR; G_SCHED;
;       G_STAGE(G_SB(1, 1), b2h1 + kstep, voffB);
;       G_WAIT_V(6); G_BAR; G_MMA(1, 1, At, B1); G_BAR;
	s_waitcnt lgkmcnt(0)
	s_setprio 1
	s_waitcnt lgkmcnt(0)
	v_mfma_f32_16x16x32_bf16 v[40:43], v[8:11], v[190:193], v[52:55]
	v_mfma_f32_16x16x32_bf16 v[238:241], v[134:137], v[194:197], v[40:43]
	v_mfma_f32_16x16x32_bf16 v[40:43], v[138:141], v[190:193], v[56:59]
	v_mfma_f32_16x16x32_bf16 v[242:245], v[146:149], v[194:197], v[40:43]
	v_mfma_f32_16x16x32_bf16 v[40:43], v[8:11], v[198:201], v[60:63]
	v_mfma_f32_16x16x32_bf16 v[246:249], v[134:137], v[202:205], v[40:43]
	v_mfma_f32_16x16x32_bf16 v[40:43], v[138:141], v[198:201], v[64:67]
	v_mfma_f32_16x16x32_bf16 v[250:253], v[146:149], v[202:205], v[40:43]
	v_mfma_f32_16x16x32_bf16 v[40:43], v[8:11], v[206:209], v[68:71]
	v_mfma_f32_16x16x32_bf16 v[184:187], v[134:137], v[210:213], v[40:43]
	v_mfma_f32_16x16x32_bf16 v[40:43], v[138:141], v[206:209], v[72:75]
	v_mfma_f32_16x16x32_bf16 v[72:75], v[146:149], v[210:213], v[40:43]
	v_mfma_f32_16x16x32_bf16 v[40:43], v[8:11], v[214:217], v[76:79]
	v_mfma_f32_16x16x32_bf16 v[48:51], v[134:137], v[226:229], v[40:43]
	v_mfma_f32_16x16x32_bf16 v[40:43], v[138:141], v[214:217], v[98:101]
	v_mfma_f32_16x16x32_bf16 v[40:43], v[146:149], v[226:229], v[40:43]
	s_setprio 0
	s_barrier
	v_mov_b32_e32 v80, v85
	ds_read_b128 v[98:101], v92
	ds_read_b128 v[230:233], v92 offset:1024
	ds_read_b128 v[176:179], v92 offset:2048
	ds_read_b128 v[90:93], v92 offset:3072
	s_mov_b32 m0, s45
	v_lshl_add_u64 v[0:1], s[8:9], 0, v[80:81]
	v_lshl_add_u64 v[0:1], v[0:1], 0, s[52:53]
	v_mov_b32_e32 v80, v87
	global_load_lds_dwordx4 v[0:1], off
	s_mov_b32 m0, s40
	v_lshl_add_u64 v[0:1], s[8:9], 0, v[80:81]
	v_lshl_add_u64 v[0:1], v[0:1], 0, s[52:53]
	global_load_lds_dwordx4 v[0:1], off
	s_barrier
	s_waitcnt lgkmcnt(0)
	s_setprio 1
	s_waitcnt lgkmcnt(0)
	v_mfma_f32_16x16x32_bf16 v[20:23], v[176:179], v[190:193], v[20:23]
	v_mfma_f32_16x16x32_bf16 v[52:55], v[98:101], v[190:193], v[118:121]
	v_mfma_f32_16x16x32_bf16 v[190:193], v[90:93], v[194:197], v[20:23]
	v_mfma_f32_16x16x32_bf16 v[20:23], v[98:101], v[198:201], v[24:27]
	v_mfma_f32_16x16x32_bf16 v[118:121], v[230:233], v[194:197], v[52:55]
	v_mfma_f32_16x16x32_bf16 v[194:197], v[230:233], v[202:205], v[20:23]
	v_mfma_f32_16x16x32_bf16 v[20:23], v[176:179], v[198:201], v[28:31]
	v_mfma_f32_16x16x32_bf16 v[198:201], v[90:93], v[202:205], v[20:23]
	v_mfma_f32_16x16x32_bf16 v[20:23], v[98:101], v[206:209], v[32:35]
	v_mfma_f32_16x16x32_bf16 v[202:205], v[230:233], v[210:213], v[20:23]
	v_mfma_f32_16x16x32_bf16 v[20:23], v[176:179], v[206:209], v[36:39]
	v_mfma_f32_16x16x32_bf16 v[206:209], v[90:93], v[210:213], v[20:23]
	v_mfma_f32_16x16x32_bf16 v[20:23], v[98:101], v[214:217], v[142:145]
	v_mfma_f32_16x16x32_bf16 v[64:67], v[230:233], v[226:229], v[20:23]
	v_mfma_f32_16x16x32_bf16 v[20:23], v[176:179], v[214:217], v[44:47]
	v_mfma_f32_16x16x32_bf16 v[60:63], v[90:93], v[226:229], v[20:23]
	s_setprio 0
	v_mov_b32_e32 v80, v84
	s_barrier
	ds_read_b128 v[28:31], v97 offset:49152
	ds_read_b128 v[32:35], v97 offset:50176
	ds_read_b128 v[52:55], v97 offset:51200
	ds_read_b128 v[142:145], v97 offset:52224
	ds_read_b128 v[210:213], v97 offset:53248
	ds_read_b128 v[214:217], v97 offset:54272
	ds_read_b128 v[226:229], v97 offset:55296
	ds_read_b128 v[218:221], v97 offset:56320
	s_mov_b32 m0, s66
	v_lshl_add_u64 v[0:1], s[6:7], 0, v[80:81]
	v_lshl_add_u64 v[0:1], v[0:1], 0, s[52:53]
	v_mov_b32_e32 v80, v86
	global_load_lds_dwordx4 v[0:1], off
	s_mov_b32 m0, s67
	v_lshl_add_u64 v[0:1], s[6:7], 0, v[80:81]
	v_lshl_add_u64 v[0:1], v[0:1], 0, s[52:53]
	global_load_lds_dwordx4 v[0:1], off
	s_barrier
	s_waitcnt lgkmcnt(0)
	s_setprio 1
	s_waitcnt lgkmcnt(0)
	v_mfma_f32_16x16x32_bf16 v[20:23], v[8:11], v[28:31], v[150:153]
	v_mfma_f32_16x16x32_bf16 v[76:79], v[134:137], v[32:35], v[20:23]
	v_mfma_f32_16x16x32_bf16 v[20:23], v[138:141], v[28:31], v[154:157]
	v_mfma_f32_16x16x32_bf16 v[68:71], v[146:149], v[32:35], v[20:23]
	v_mfma_f32_16x16x32_bf16 v[20:23], v[8:11], v[52:55], v[158:161]
	v_mfma_f32_16x16x32_bf16 v[44:47], v[134:137], v[142:145], v[20:23]
	v_mfma_f32_16x16x32_bf16 v[20:23], v[138:141], v[52:55], v[164:167]
	v_mfma_f32_16x16x32_bf16 v[36:39], v[146:149], v[142:145], v[20:23]
	v_mfma_f32_16x16x32_bf16 v[20:23], v[8:11], v[210:213], v[168:171]
	v_mfma_f32_16x16x32_bf16 v[4:7], v[8:11], v[226:229], v[4:7]
	v_mfma_f32_16x16x32_bf16 v[24:27], v[134:137], v[214:217], v[20:23]
	v_mfma_f32_16x16x32_bf16 v[20:23], v[138:141], v[210:213], v[172:175]
	v_mfma_f32_16x16x32_bf16 v[8:11], v[134:137], v[218:221], v[4:7]
	v_mfma_f32_16x16x32_bf16 v[4:7], v[138:141], v[226:229], v[126:129]
	v_mfma_f32_16x16x32_bf16 v[20:23], v[146:149], v[214:217], v[20:23]
	v_mfma_f32_16x16x32_bf16 v[4:7], v[146:149], v[218:221], v[4:7]
	s_setprio 0
	s_barrier
	s_add_u32 s28, s8, 0x40080
	v_mov_b32_e32 v0, v85
	s_mov_b32 m0, s44
	s_addc_u32 s29, s9, 0
	s_nop 0
	global_load_lds_dwordx4 v0, s[28:29]
	v_mov_b32_e32 v0, v87
	s_mov_b32 m0, s41
	s_nop 0
	global_load_lds_dwordx4 v0, s[28:29]
	s_waitcnt vmcnt(6)
	s_barrier
; __device__ __forceinline__ unsigned cvt_pk_bf16(float lo, float hi) { unsigned r; asm("v_cvt_pk_bf16_f32 %0, %1, %2" : "=v"(r) : "v"(lo), "v"(hi)); return r; }
; __device__ __forceinline__ float rinv_of(unsigned long long ss) { return rsqrtf((float)ss * (1.f / 16777216.f) * (1.f / DM) + 1e-6f); }
;   __device__ __forceinline__ void operator()(const f32x4 (&acc)[2][2][4][2], const Unit& u, const EpiCtx& x_, int wr, int wc, int fr, int fq) const {
;     ...
;     for (int ai = 0; ai < 2; ++ai)
; #pragma unroll
;       for (int m = 0; m < 4; ++m) {
;         const int row = (u.r0 + (ai ? x_.rdelta : 0)) + wr * 64 + m * 16 + fr;
;         bf16_t* rowp = (bf16_t*)u.C + (size_t)row * x_.ldc;
;         const float rs = (SCALE == 1) ? rinv_of(x_.ss[row]) : 1.f;
; #pragma unroll
;         for (int bj = 0; bj < 2; ++bj) {
;           const int cb = PERM ? (u.c0 + wc * 64 + bj * 32) : (u.c0 + bj * 128) + wc * 32;
;           f32x4 v0 = acc[ai][bj][m][0], v1 = acc[ai][bj][m][1];
;           if (SCALE == 1) { v0 *= rs; v1 *= rs; }
;           if (SCALE == 2) { v0 *= cs[bj][0]; v1 *= cs[bj][1]; }
;           if (PERM) {
;             uint4 o; o.x = cvt_pk_bf16(v0[0], v0[1]); o.y = cvt_pk_bf16(v0[2], v0[3]); o.z = cvt_pk_bf16(v1[0], v1[1]); o.w = cvt_pk_bf16(v1[2], v1[3]);
;             *(uint4*)(rowp + cb + 8 * fq) = o;
;           } else {
;             uint2 o0, o1; o0.x = cvt_pk_bf16(v0[0], v0[1]); o0.y = cvt_pk_bf16(v0[2], v0[3]); o1.x = cvt_pk_bf16(v1[0], v1[1]); o1.y = cvt_pk_bf16(v1[2], v1[3]);
;             *(uint2*)(rowp + cb + 4 * fq) = o0; *(uint2*)(rowp + cb + 16 + 4 * fq) = o1;
;           }
;         }
;       }
; template <class Epi>
; __device__ __forceinline__ void gemm_phase(LAS unsigned char* lds, const int K, const unsigned lda_b, const unsigned ldb_b, const Map& M, const Epi& E) {
;     ...
;     E(acc, cur, X, wr, wc, fr, fq);
;     if (!has_next) break;
; #pragma unroll
;     for (int a = 0; a < 2; ++a)
; #pragma unroll
;       for (int b = 0; b < 2; ++b)
; #pragma unroll
;         for (int m = 0; m < 4; ++m)
; #pragma unroll
;           for (int n = 0; n < 2; ++n) acc[a][b][m][n] = (f32x4){0.f, 0.f, 0.f, 0.f};
;     cur = nxt; ++ui;
;   }
	s_setprio 1
	v_mfma_f32_16x16x32_bf16 v[12:15], v[98:101], v[28:31], v[12:15]
	v_mfma_f32_16x16x32_bf16 v[126:129], v[230:233], v[32:35], v[12:15]
	v_mfma_f32_16x16x32_bf16 v[12:15], v[176:179], v[28:31], v[16:19]
	v_mfma_f32_16x16x32_bf16 v[134:137], v[90:93], v[32:35], v[12:15]
	v_mfma_f32_16x16x32_bf16 v[12:15], v[98:101], v[52:55], v[130:133]
	v_mfma_f32_16x16x32_bf16 v[56:59], v[230:233], v[142:145], v[12:15]
	v_mfma_f32_16x16x32_bf16 v[12:15], v[176:179], v[52:55], v[110:113]
	v_mfma_f32_16x16x32_bf16 v[52:55], v[90:93], v[142:145], v[12:15]
	v_mfma_f32_16x16x32_bf16 v[12:15], v[98:101], v[210:213], v[114:117]
	v_mfma_f32_16x16x32_bf16 v[32:35], v[230:233], v[214:217], v[12:15]
	v_mfma_f32_16x16x32_bf16 v[12:15], v[176:179], v[210:213], v[122:125]
	v_mfma_f32_16x16x32_bf16 v[28:31], v[90:93], v[214:217], v[12:15]
	v_mfma_f32_16x16x32_bf16 v[12:15], v[98:101], v[226:229], v[102:105]
	v_mfma_f32_16x16x32_bf16 v[16:19], v[230:233], v[218:221], v[12:15]
	v_mfma_f32_16x16x32_bf16 v[12:15], v[176:179], v[226:229], v[106:109]
	v_mfma_f32_16x16x32_bf16 v[12:15], v[90:93], v[218:221], v[12:15]
	s_setprio 0
	v_add_u32_e32 v0, s18, v88
	v_ashrrev_i32_e32 v1, 31, v0
	s_add_i32 s30, s19, s68
	v_lshlrev_b64 v[0:1], 12, v[0:1]
	s_ashr_i32 s31, s30, 31
	v_lshl_add_u64 v[0:1], s[4:5], 0, v[0:1]
	v_mov_b32_e32 v83, v81
	s_lshl_b64 s[38:39], s[30:31], 1
	s_add_i32 s30, s69, s19
	v_lshl_add_u64 v[90:91], v[0:1], 0, v[82:83]
	s_ashr_i32 s31, s30, 31
	v_cvt_pk_bf16_f32 v0, v238, v239
	v_lshl_add_u64 v[92:93], v[90:91], 0, s[38:39]
	s_lshl_b64 s[40:41], s[30:31], 1
	s_barrier
	v_readfirstlane_b32 s28, v2
	v_readfirstlane_b32 s29, v3
	v_cvt_pk_bf16_f32 v1, v240, v241
	v_cvt_pk_bf16_f32 v2, v242, v243
	v_cvt_pk_bf16_f32 v3, v244, v245
	s_waitcnt vmcnt(0)
	global_store_dwordx4 v[92:93], v[0:3], off
	v_lshl_add_u64 v[90:91], v[90:91], 0, s[40:41]
	s_cmp_eq_u32 s75, s61
	v_cvt_pk_bf16_f32 v0, v118, v119
	v_cvt_pk_bf16_f32 v1, v120, v121
	v_cvt_pk_bf16_f32 v2, v190, v191
	v_cvt_pk_bf16_f32 v3, v192, v193
	global_store_dwordx4 v[90:91], v[0:3], off
	s_nop 1
	v_add_u32_e32 v0, s18, v163
	v_ashrrev_i32_e32 v1, 31, v0
	v_lshlrev_b64 v[0:1], 12, v[0:1]
	v_lshl_add_u64 v[0:1], s[4:5], 0, v[0:1]
	v_lshl_add_u64 v[90:91], v[0:1], 0, v[82:83]
	v_cvt_pk_bf16_f32 v0, v246, v247
	v_lshl_add_u64 v[92:93], v[90:91], 0, s[38:39]
	v_cvt_pk_bf16_f32 v1, v248, v249
	v_cvt_pk_bf16_f32 v2, v250, v251
	v_cvt_pk_bf16_f32 v3, v252, v253
	global_store_dwordx4 v[92:93], v[0:3], off
	v_lshl_add_u64 v[90:91], v[90:91], 0, s[40:41]
	s_nop 0
	v_cvt_pk_bf16_f32 v0, v194, v195
	v_cvt_pk_bf16_f32 v1, v196, v197
	v_cvt_pk_bf16_f32 v2, v198, v199
	v_cvt_pk_bf16_f32 v3, v200, v201
	global_store_dwordx4 v[90:91], v[0:3], off
	s_nop 1
	v_add_u32_e32 v0, s18, v181
	v_ashrrev_i32_e32 v1, 31, v0
	v_lshlrev_b64 v[0:1], 12, v[0:1]
	v_lshl_add_u64 v[0:1], s[4:5], 0, v[0:1]
	v_lshl_add_u64 v[90:91], v[0:1], 0, v[82:83]
	v_cvt_pk_bf16_f32 v0, v184, v185
	v_cvt_pk_bf16_f32 v2, v72, v73
	v_lshl_add_u64 v[72:73], v[90:91], 0, s[38:39]
	v_cvt_pk_bf16_f32 v1, v186, v187
	v_cvt_pk_bf16_f32 v3, v74, v75
	global_store_dwordx4 v[72:73], v[0:3], off
	v_lshl_add_u64 v[72:73], v[90:91], 0, s[40:41]
	s_nop 0
	v_cvt_pk_bf16_f32 v0, v202, v203
	v_cvt_pk_bf16_f32 v1, v204, v205
	v_cvt_pk_bf16_f32 v2, v206, v207
	v_cvt_pk_bf16_f32 v3, v208, v209
	global_store_dwordx4 v[72:73], v[0:3], off
	s_nop 1
	v_add_u32_e32 v0, s18, v183
	v_ashrrev_i32_e32 v1, 31, v0
	v_lshlrev_b64 v[0:1], 12, v[0:1]
	v_lshl_add_u64 v[0:1], s[4:5], 0, v[0:1]
	v_lshl_add_u64 v[72:73], v[0:1], 0, v[82:83]
	v_cvt_pk_bf16_f32 v0, v48, v49
	v_cvt_pk_bf16_f32 v2, v40, v41
	v_lshl_add_u64 v[40:41], v[72:73], 0, s[38:39]
	v_cvt_pk_bf16_f32 v1, v50, v51
	v_cvt_pk_bf16_f32 v3, v42, v43
	global_store_dwordx4 v[40:41], v[0:3], off
	v_lshl_add_u64 v[40:41], v[72:73], 0, s[40:41]
	s_nop 0
	v_cvt_pk_bf16_f32 v0, v64, v65
	v_cvt_pk_bf16_f32 v1, v66, v67
	v_cvt_pk_bf16_f32 v2, v60, v61
	v_cvt_pk_bf16_f32 v3, v62, v63
	global_store_dwordx4 v[40:41], v[0:3], off
	s_nop 1
	v_add_u32_e32 v0, s18, v188
	v_ashrrev_i32_e32 v1, 31, v0
	v_lshlrev_b64 v[0:1], 12, v[0:1]
	v_lshl_add_u64 v[0:1], s[4:5], 0, v[0:1]
	v_lshl_add_u64 v[40:41], v[0:1], 0, v[82:83]
	v_cvt_pk_bf16_f32 v0, v76, v77
	v_lshl_add_u64 v[42:43], v[40:41], 0, s[38:39]
	v_cvt_pk_bf16_f32 v1, v78, v79
	v_cvt_pk_bf16_f32 v2, v68, v69
	v_cvt_pk_bf16_f32 v3, v70, v71
	global_store_dwordx4 v[42:43], v[0:3], off
	v_lshl_add_u64 v[40:41], v[40:41], 0, s[40:41]
	s_nop 0
	v_cvt_pk_bf16_f32 v0, v126, v127
	v_cvt_pk_bf16_f32 v1, v128, v129
	v_cvt_pk_bf16_f32 v2, v134, v135
	v_cvt_pk_bf16_f32 v3, v136, v137
	global_store_dwordx4 v[40:41], v[0:3], off
	s_nop 1
	v_add_u32_e32 v0, s18, v94
	v_ashrrev_i32_e32 v1, 31, v0
	v_lshlrev_b64 v[0:1], 12, v[0:1]
	v_lshl_add_u64 v[0:1], s[4:5], 0, v[0:1]
	v_lshl_add_u64 v[40:41], v[0:1], 0, v[82:83]
	v_cvt_pk_bf16_f32 v0, v44, v45
	v_cvt_pk_bf16_f32 v2, v36, v37
	v_lshl_add_u64 v[36:37], v[40:41], 0, s[38:39]
	v_cvt_pk_bf16_f32 v1, v46, v47
	v_cvt_pk_bf16_f32 v3, v38, v39
	global_store_dwordx4 v[36:37], v[0:3], off
	v_lshl_add_u64 v[36:37], v[40:41], 0, s[40:41]
	s_nop 0
	v_cvt_pk_bf16_f32 v0, v56, v57
	v_cvt_pk_bf16_f32 v1, v58, v59
	v_cvt_pk_bf16_f32 v2, v52, v53
	v_cvt_pk_bf16_f32 v3, v54, v55
	global_store_dwordx4 v[36:37], v[0:3], off
	s_nop 1
	v_add_u32_e32 v0, s18, v95
	v_ashrrev_i32_e32 v1, 31, v0
	v_lshlrev_b64 v[0:1], 12, v[0:1]
	v_lshl_add_u64 v[0:1], s[4:5], 0, v[0:1]
	v_lshl_add_u64 v[36:37], v[0:1], 0, v[82:83]
	v_cvt_pk_bf16_f32 v0, v24, v25
	v_cvt_pk_bf16_f32 v2, v20, v21
	v_lshl_add_u64 v[20:21], v[36:37], 0, s[38:39]
	v_cvt_pk_bf16_f32 v1, v26, v27
	v_cvt_pk_bf16_f32 v3, v22, v23
	global_store_dwordx4 v[20:21], v[0:3], off
	v_lshl_add_u64 v[20:21], v[36:37], 0, s[40:41]
	s_nop 0
	v_cvt_pk_bf16_f32 v0, v32, v33
	v_cvt_pk_bf16_f32 v1, v34, v35
	v_cvt_pk_bf16_f32 v2, v28, v29
	v_cvt_pk_bf16_f32 v3, v30, v31
	global_store_dwordx4 v[20:21], v[0:3], off
	s_nop 1
	v_add_u32_e32 v0, s18, v96
	v_ashrrev_i32_e32 v1, 31, v0
	v_lshlrev_b64 v[0:1], 12, v[0:1]
	v_lshl_add_u64 v[0:1], s[4:5], 0, v[0:1]
	v_lshl_add_u64 v[20:21], v[0:1], 0, v[82:83]
	v_cvt_pk_bf16_f32 v2, v4, v5
	v_lshl_add_u64 v[4:5], v[20:21], 0, s[38:39]
	v_cvt_pk_bf16_f32 v0, v8, v9
	v_cvt_pk_bf16_f32 v1, v10, v11
	v_cvt_pk_bf16_f32 v3, v6, v7
	global_store_dwordx4 v[4:5], v[0:3], off
	v_lshl_add_u64 v[4:5], v[20:21], 0, s[40:41]
	s_mov_b64 s[18:19], -1
	v_cvt_pk_bf16_f32 v0, v16, v17
	v_cvt_pk_bf16_f32 v1, v18, v19
	v_cvt_pk_bf16_f32 v2, v12, v13
	v_cvt_pk_bf16_f32 v3, v14, v15
	global_store_dwordx4 v[4:5], v[0:3], off
	s_cbranch_scc1 .LBB0_160
	s_add_i32 s61, s61, 1
	s_mov_b64 s[18:19], 0
	s_mov_b64 s[4:5], s[36:37]
	s_mov_b64 s[40:41], s[8:9]
	s_mov_b64 s[38:39], s[6:7]
	s_branch .LBB0_160

; #define LAS __attribute__((address_space(3)))
; __device__ __forceinline__ int otid() { int t = threadIdx.x; asm volatile("" : "+v"(t)); return t; }
; __device__ __forceinline__ unsigned xb_add(unsigned* p, unsigned v) { return __hip_atomic_fetch_add(p, v, __ATOMIC_RELAXED, __HIP_MEMORY_SCOPE_AGENT); }
; __device__ __forceinline__ void gbar(unsigned* bar, unsigned n, volatile LAS unsigned* st) {
;   asm volatile("s_waitcnt vmcnt(0)" ::: "memory");
;   __syncthreads();
;   if (otid() == 0) {
;     __builtin_amdgcn_s_waitcnt(0);
;     const unsigned x = st[0], nloc = st[1], nx = st[2];
;     const unsigned old = xb_add(&bar[XB_XSUB(x)], 1u);
;     unsigned sp = 0;
;     if (old + 1u == (n + 1u) * nloc) {
; __device__ __forceinline__ unsigned long long karg(int i) {
;   const volatile unsigned long long* ka = (const volatile unsigned long long*)__builtin_amdgcn_kernarg_segment_ptr();
;   const unsigned long long v = ka[i];
;   return ((unsigned long long)__builtin_amdgcn_readfirstlane((unsigned)(v >> 32)) << 32) | (unsigned)__builtin_amdgcn_readfirstlane((unsigned)v);
.LBB0_166:
	v_mov_b64_e32 v[0:1], s[10:11]
	global_load_dwordx2 v[0:1], v[0:1], off sc0 sc1
	s_waitcnt vmcnt(0)
	s_waitcnt vmcnt(0)
	v_mov_b32_e32 v2, v252
	s_waitcnt lgkmcnt(0)
	s_barrier
	v_readfirstlane_b32 s0, v1
	v_readfirstlane_b32 s1, v0
	v_cmp_ne_u32_e32 vcc, 0, v2
	s_and_saveexec_b64 s[2:3], vcc
	s_xor_b64 s[2:3], exec, s[2:3]
	v_add_u32_e32 v158, 2, v236
	s_andn2_saveexec_b64 s[2:3], s[2:3]
	s_cbranch_execz .LBB0_217
	v_readlane_b32 s6, v255, 15
	s_waitcnt vmcnt(0) expcnt(0) lgkmcnt(0)
	s_add_u32 s4, s1, 0x4cc80000
	v_mov_b32_e32 v0, s6
	ds_read_b32 v0, v0
	v_readlane_b32 s6, v255, 16
	s_addc_u32 s5, s0, 0
	v_add_u32_e32 v158, 2, v236
	v_mov_b32_e32 v1, s6
	s_waitcnt lgkmcnt(0)
	v_lshlrev_b32_e32 v0, 6, v0
	v_add_u32_e32 v80, 0x440, v0
	v_readlane_b32 s6, v255, 17
	v_lshlrev_b64 v[2:3], 2, v[80:81]
	ds_read_b32 v4, v1
	v_mov_b32_e32 v1, s6
	v_lshl_add_u64 v[2:3], s[4:5], 0, v[2:3]
	ds_read_b32 v1, v1
	global_atomic_add v2, v[2:3], v230, off sc0
	s_waitcnt lgkmcnt(0)
	v_mul_lo_u32 v3, v4, v158
	s_waitcnt vmcnt(0)
	v_add_u32_e32 v2, 1, v2
	v_cmp_ne_u32_e32 vcc, v2, v3
	s_and_saveexec_b64 s[6:7], vcc
	s_xor_b64 s[6:7], exec, s[6:7]
	s_cbranch_execz .LBB0_193
	v_add_u32_e32 v80, 0x840, v0
	v_lshlrev_b64 v[0:1], 2, v[80:81]
	v_lshl_add_u64 v[0:1], s[4:5], 0, v[0:1]
	s_mov_b32 s13, 0x1000000
	s_mov_b64 s[8:9], 0
	s_branch .LBB0_181

; __device__ __forceinline__ unsigned xb_ld(unsigned* p) { return __hip_atomic_load(p, __ATOMIC_RELAXED, __HIP_MEMORY_SCOPE_AGENT); }
; __device__ __forceinline__ void gbar(unsigned* bar, unsigned n, volatile LAS unsigned* st) {
;     ...
;     } else {
;       while (xb_ld(&bar[XB_XGEN(x)]) <= n) { __builtin_amdgcn_s_sleep(1); if (++sp > (1u << 24)) break; }
.LBB0_181:
	global_load_dword v2, v[0:1], off sc1
	s_or_b64 s[36:37], s[36:37], exec
	s_waitcnt vmcnt(0) lgkmcnt(0)
	v_cmp_le_u32_e32 vcc, v2, v162
	s_and_saveexec_b64 s[38:39], vcc
	s_cbranch_execz .LBB0_180
	s_cmp_lg_u32 s13, 0
	s_sleep 1
	s_cbranch_scc0 .LBB0_191
	global_load_dword v2, v[0:1], off sc1
	s_mov_b64 s[18:19], -1
	s_waitcnt vmcnt(0) lgkmcnt(0)
	v_cmp_le_u32_e32 vcc, v2, v162
	s_and_saveexec_b64 s[40:41], vcc
	s_cbranch_execz .LBB0_178
	s_sleep 1
	global_load_dword v2, v[0:1], off sc1
	s_waitcnt vmcnt(0) lgkmcnt(0)
	v_cmp_le_u32_e32 vcc, v2, v162
	s_and_saveexec_b64 s[42:43], vcc
	s_cbranch_execz .LBB0_177
	s_sleep 1
	global_load_dword v2, v[0:1], off sc1
	s_waitcnt vmcnt(0) lgkmcnt(0)
	v_cmp_le_u32_e32 vcc, v2, v162
	s_and_saveexec_b64 s[44:45], vcc
	s_cbranch_execz .LBB0_176
	s_sleep 1
	global_load_dword v2, v[0:1], off sc1
	s_waitcnt vmcnt(0) lgkmcnt(0)
	v_cmp_le_u32_e32 vcc, v2, v162
	s_and_saveexec_b64 s[46:47], vcc
	s_cbranch_execz .LBB0_175
	s_sleep 1
	global_load_dword v2, v[0:1], off sc1
	s_waitcnt vmcnt(0) lgkmcnt(0)
	v_cmp_le_u32_e32 vcc, v2, v162
	s_and_saveexec_b64 s[68:69], vcc
	s_cbranch_execz .LBB0_174
	s_sleep 1
	global_load_dword v2, v[0:1], off sc1
	s_mov_b64 s[48:49], -1
	s_waitcnt vmcnt(0) lgkmcnt(0)
	v_cmp_le_u32_e32 vcc, v2, v162
	s_and_saveexec_b64 s[18:19], vcc
	s_cbranch_execz .LBB0_173
	s_sleep 1
	global_load_dword v2, v[0:1], off sc1
	s_waitcnt vmcnt(0) lgkmcnt(0)
	v_cmp_le_u32_e32 vcc, v2, v162
	s_and_saveexec_b64 s[66:67], vcc
	s_cbranch_execz .LBB0_172
	s_add_i32 s13, s13, -8
	s_xor_b64 s[48:49], exec, -1
	s_sleep 1
	s_branch .LBB0_172

; __device__ __forceinline__ unsigned xb_add(unsigned* p, unsigned v) { return __hip_atomic_fetch_add(p, v, __ATOMIC_RELAXED, __HIP_MEMORY_SCOPE_AGENT); }
; __device__ __forceinline__ void gbar(unsigned* bar, unsigned n, volatile LAS unsigned* st) {
;     ...
;     if (old + 1u == (n + 1u) * nloc) {
;       __builtin_amdgcn_fence(__ATOMIC_RELEASE, "agent");
;       asm volatile("s_waitcnt vmcnt(0)" ::: "memory");
;       xb_add(&bar[XB_TOP], 1u);
.LBB0_193:
	s_andn2_saveexec_b64 s[6:7], s[6:7]
	s_cbranch_execz .LBB0_216
	v_mov_b32_e32 v2, s1
	v_add_co_u32_e32 v2, vcc, 0x4cc83000, v2
	v_mov_b32_e32 v3, s0
	buffer_wbl2 sc1
	s_waitcnt vmcnt(0)
	v_addc_co_u32_e32 v3, vcc, 0, v3, vcc
	global_atomic_add v[2:3], v230, off offset:256
	s_add_u32 s8, s1, 0x4cc83100
	s_addc_u32 s9, s0, 0
	v_mul_lo_u32 v1, v1, v158
	s_mov_b32 s0, 0x1000000
	s_mov_b64 s[36:37], 0
	s_branch .LBB0_204

; __device__ __forceinline__ unsigned xb_ld(unsigned* p) { return __hip_atomic_load(p, __ATOMIC_RELAXED, __HIP_MEMORY_SCOPE_AGENT); }
; __device__ __forceinline__ void gbar(unsigned* bar, unsigned n, volatile LAS unsigned* st) {
;     ...
;       while (xb_ld(&bar[XB_TOP]) < (n + 1u) * nx) { __builtin_amdgcn_s_sleep(1); if (++sp > (1u << 24)) break; }
.LBB0_204:
	v_mov_b64_e32 v[2:3], s[8:9]
	global_load_dword v2, v[2:3], off sc1
	s_or_b64 s[38:39], s[38:39], exec
	s_waitcnt vmcnt(0) lgkmcnt(0)
	v_cmp_lt_u32_e32 vcc, v2, v1
	s_and_saveexec_b64 s[40:41], vcc
	s_cbranch_execz .LBB0_203
	s_cmp_lg_u32 s0, 0
	s_sleep 1
	s_cbranch_scc0 .LBB0_214
	v_mov_b64_e32 v[2:3], s[8:9]
	global_load_dword v2, v[2:3], off sc1
	s_mov_b64 s[18:19], -1
	s_waitcnt vmcnt(0) lgkmcnt(0)
	v_cmp_lt_u32_e32 vcc, v2, v1
	s_and_saveexec_b64 s[42:43], vcc
	s_cbranch_execz .LBB0_201
	v_mov_b64_e32 v[2:3], s[8:9]
	s_sleep 1
	global_load_dword v2, v[2:3], off sc1
	s_waitcnt vmcnt(0) lgkmcnt(0)
	v_cmp_lt_u32_e32 vcc, v2, v1
	s_and_saveexec_b64 s[44:45], vcc
	s_cbranch_execz .LBB0_200
	v_mov_b64_e32 v[2:3], s[8:9]
	s_sleep 1
	global_load_dword v2, v[2:3], off sc1
	s_waitcnt vmcnt(0) lgkmcnt(0)
	v_cmp_lt_u32_e32 vcc, v2, v1
	s_and_saveexec_b64 s[46:47], vcc
	s_cbranch_execz .LBB0_199
	v_mov_b64_e32 v[2:3], s[8:9]
	s_sleep 1
	global_load_dword v2, v[2:3], off sc1
	s_waitcnt vmcnt(0) lgkmcnt(0)
	v_cmp_lt_u32_e32 vcc, v2, v1
	s_and_saveexec_b64 s[68:69], vcc
	s_cbranch_execz .LBB0_198
	v_mov_b64_e32 v[2:3], s[8:9]
	s_sleep 1
	global_load_dword v2, v[2:3], off sc1
	s_waitcnt vmcnt(0) lgkmcnt(0)
	v_cmp_lt_u32_e32 vcc, v2, v1
	s_and_saveexec_b64 s[94:95], vcc
	s_cbranch_execz .LBB0_197
	v_mov_b64_e32 v[2:3], s[8:9]
	s_sleep 1
	global_load_dword v2, v[2:3], off sc1
	s_mov_b64 s[48:49], -1
	s_waitcnt vmcnt(0) lgkmcnt(0)
	v_cmp_lt_u32_e32 vcc, v2, v1
	s_and_saveexec_b64 s[18:19], vcc
	s_cbranch_execz .LBB0_196
	v_mov_b64_e32 v[2:3], s[8:9]
	s_sleep 1
	global_load_dword v2, v[2:3], off sc1
	s_waitcnt vmcnt(0) lgkmcnt(0)
	v_cmp_lt_u32_e32 vcc, v2, v1
	s_and_saveexec_b64 s[66:67], vcc
	s_cbranch_execz .LBB0_195
	s_add_i32 s0, s0, -8
	s_xor_b64 s[48:49], exec, -1
	s_sleep 1
	s_branch .LBB0_195

; __device__ __forceinline__ unsigned xb_add(unsigned* p, unsigned v) { return __hip_atomic_fetch_add(p, v, __ATOMIC_RELAXED, __HIP_MEMORY_SCOPE_AGENT); }
; __device__ __forceinline__ void gbar(unsigned* bar, unsigned n, volatile LAS unsigned* st) {
;     ...
;       __builtin_amdgcn_fence(__ATOMIC_ACQUIRE, "agent");
;       xb_add(&bar[XB_XGEN(x)], 1u);
;       asm volatile("s_waitcnt vmcnt(0)" ::: "memory");
.LBB0_215:
	s_or_b64 exec, exec, s[36:37]
	v_add_u32_e32 v80, 0x840, v0
	v_lshlrev_b64 v[0:1], 2, v[80:81]
	v_lshl_add_u64 v[0:1], s[4:5], 0, v[0:1]
	buffer_inv sc1
	global_atomic_add v[0:1], v230, off
	s_waitcnt vmcnt(0)

; #define LAS __attribute__((address_space(3)))
; __device__ __forceinline__ int otid() { int t = threadIdx.x; asm volatile("" : "+v"(t)); return t; }
;   __device__ __forceinline__ bool next(int i, Unit& u) const {
;     const long Ll = (long)i * G + c;
;     if (Ll >= total) return false;
;     const int L = (int)Ll;
;     int pm, pn;
;     u.pad0 = 0; u.pad1 = 0;
;     if (mode == 0) {
;       tile_order(L, nM, nN, pm, pn);
;       if (p1 == -77 && pm >= p0) ++pm;
;       u.a0 = A + (size_t)pm * a_t; u.b0 = B + (size_t)pn * b_t; u.b1 = u.b0 + b_h;
;       u.r0 = pm * 256; u.c0 = pn * 256; u.C = C;
; __device__ __forceinline__ int build_units(LAS unsigned char* lds, const Map& m) {
;   LAS Unit* ul = (LAS Unit*)(lds + STAGE_BYTES);
;   __syncthreads();
;   const int tid_ = otid();
;   if (tid_ < MAX_UNITS) { Unit u; if (m.next(tid_, u)) {
;       LAS unsigned long long* w = (LAS unsigned long long*)(ul + tid_);
;       w[0] = (unsigned long long)u.a0; w[1] = (unsigned long long)u.b0; w[2] = (unsigned long long)u.b1; w[3] = (unsigned long long)u.C;
;       w[4] = ((unsigned long long)(unsigned)u.c0 << 32) | (unsigned)u.r0; } }
;   __syncthreads();
;   const long rest = (long)m.total - m.c;
;   int n = rest > 0 ? (int)((rest + m.G - 1) / m.G) : 0;
;   return n < MAX_UNITS ? n : MAX_UNITS;
; }
.LBB0_218:
	v_mov_b64_e32 v[0:1], s[10:11]
	global_load_dwordx2 v[2:3], v[0:1], off sc0 sc1
	s_waitcnt vmcnt(0) lgkmcnt(0)
	v_readfirstlane_b32 s3, v3
	v_readfirstlane_b32 s2, v2
	global_load_dwordx2 v[2:3], v[0:1], off sc0 sc1
	s_waitcnt vmcnt(0) lgkmcnt(0)
	v_readfirstlane_b32 s18, v3
	v_readfirstlane_b32 s19, v2
	global_load_dwordx2 v[2:3], v[0:1], off sc0 sc1
	s_waitcnt vmcnt(0) lgkmcnt(0)
	v_readfirstlane_b32 s9, v2
	v_mov_b32_e32 v2, s74
	ds_read_b32 v2, v2
	global_load_dwordx2 v[0:1], v[0:1], off sc0 sc1
	s_waitcnt vmcnt(0)
	v_readfirstlane_b32 s1, v3
	s_waitcnt lgkmcnt(0)
	s_barrier
	v_readfirstlane_b32 s13, v2
	v_mov_b32_e32 v2, v252
	v_readfirstlane_b32 s0, v1
	v_readfirstlane_b32 s8, v0
	v_cmp_gt_i32_e32 vcc, 40, v2
	s_and_saveexec_b64 s[4:5], vcc
	s_cbranch_execz .LBB0_225
	s_ashr_i32 s6, s13, 31
	v_mov_b32_e32 v0, s13
	v_mov_b32_e32 v1, s6
	v_mad_i64_i32 v[0:1], s[6:7], v2, s20, v[0:1]
	v_cmp_gt_i64_e32 vcc, s[58:59], v[0:1]
	s_and_b64 exec, exec, vcc
	s_cbranch_execz .LBB0_225
	v_ashrrev_i32_e32 v1, 31, v0
	v_lshrrev_b32_e32 v1, 29, v1
	v_add_u32_e32 v1, v0, v1
	v_and_b32_e32 v3, -8, v1
	v_sub_u32_e32 v3, v0, v3
	v_cmp_lt_i32_e32 vcc, -1, v3
	s_and_saveexec_b64 s[6:7], vcc
	s_xor_b64 s[6:7], exec, s[6:7]
	v_lshlrev_b32_e32 v0, 7, v3
	s_andn2_saveexec_b64 s[6:7], s[6:7]
	v_lshl_add_u32 v0, v3, 7, v3
	s_or_b64 exec, exec, s[6:7]
	v_ashrrev_i32_e32 v1, 3, v1
	v_add_u32_e32 v0, v0, v1
	v_ashrrev_i32_e32 v1, 31, v0
	v_add_u32_sdwa v1, v0, v1 dst_sel:DWORD dst_unused:UNUSED_PAD src0_sel:DWORD src1_sel:BYTE_3
	v_ashrrev_i32_e32 v1, 8, v1
	v_lshlrev_b32_e32 v3, 2, v1
	v_sub_u32_e32 v4, 16, v3
	v_min_i32_e32 v4, 4, v4
	v_sub_u32_e32 v5, 0, v4
	v_max_i32_e32 v5, v4, v5
	v_cvt_f32_u32_e32 v6, v5
	v_mul_i32_i24_e32 v1, 0x100, v1
	v_sub_u32_e32 v8, 0, v5
	v_sub_u32_e32 v0, v0, v1
	v_rcp_iflag_f32_e32 v6, v6
	v_sub_u32_e32 v7, 0, v0
	v_max_i32_e32 v7, v0, v7
	v_xor_b32_e32 v1, v0, v4
	v_mul_f32_e32 v6, 0x4f7ffffe, v6
	v_cvt_u32_f32_e32 v6, v6
	v_ashrrev_i32_e32 v1, 31, v1
	s_lshl_b32 s6, s90, 1
	s_add_u32 s6, s19, s6
	v_mul_lo_u32 v8, v8, v6
	v_mul_hi_u32 v8, v6, v8
	v_add_u32_e32 v6, v6, v8
	v_mul_hi_u32 v6, v7, v6
	v_mul_lo_u32 v8, v6, v5
	v_sub_u32_e32 v7, v7, v8
	v_add_u32_e32 v8, 1, v6
	v_cmp_ge_u32_e32 vcc, v7, v5
	s_addc_u32 s7, s18, 0
	s_nop 0
	v_cndmask_b32_e32 v6, v6, v8, vcc
	v_sub_u32_e32 v8, v7, v5
	v_cndmask_b32_e32 v7, v7, v8, vcc
	v_add_u32_e32 v8, 1, v6
	v_cmp_ge_u32_e32 vcc, v7, v5
	s_nop 1
	v_cndmask_b32_e32 v5, v6, v8, vcc
	v_xor_b32_e32 v5, v5, v1
	v_sub_u32_e32 v6, v5, v1
	v_mul_lo_u32 v1, v6, v4
	v_sub_u32_e32 v0, v0, v1
	v_add_u32_e32 v1, v3, v0
	v_cmp_lt_i32_e32 vcc, 7, v1
	v_ashrrev_i32_e32 v7, 31, v6
	s_nop 0
	v_addc_co_u32_e32 v8, vcc, v3, v0, vcc
	v_lshlrev_b64 v[0:1], 20, v[6:7]
	v_lshl_add_u64 v[0:1], s[6:7], 0, v[0:1]
	s_mov_b64 s[6:7], 0xb920000
	v_ashrrev_i32_e32 v9, 31, v8
	v_lshl_add_u64 v[4:5], v[0:1], 0, s[6:7]
	s_mov_b64 s[6:7], 0xb9a0000
	v_lshlrev_b64 v[10:11], 20, v[8:9]
	v_lshl_add_u64 v[0:1], v[0:1], 0, s[6:7]
	v_mad_u64_u32 v[2:3], s[6:7], v2, 48, v[232:233]
	v_add_u32_e32 v7, 0x20000, v2
	v_lshl_add_u64 v[2:3], v[10:11], 0, s[2:3]
	s_add_u32 s2, s9, 0x18180000
	s_addc_u32 s1, s1, 0
	v_lshlrev_b32_e32 v8, 8, v8
	ds_write_b128 v7, v[2:5]
	v_mov_b32_e32 v2, s2
	v_mov_b32_e32 v3, s1
	v_lshlrev_b32_e32 v9, 8, v6
	ds_write_b128 v7, v[0:3] offset:16
	ds_write_b64 v7, v[8:9] offset:32

; #define LAS __attribute__((address_space(3)))
; __device__ __forceinline__ int otid() { int t = threadIdx.x; asm volatile("" : "+v"(t)); return t; }
;   __device__ __forceinline__ bool next(int i, Unit& u) const {
;     const long Ll = (long)i * G + c;
;     if (Ll >= total) return false;
;     const int L = (int)Ll;
;     int pm, pn;
;     u.pad0 = 0; u.pad1 = 0;
;     if (mode == 0) {
;       tile_order(L, nM, nN, pm, pn);
;       if (p1 == -77 && pm >= p0) ++pm;
;       u.a0 = A + (size_t)pm * a_t; u.b0 = B + (size_t)pn * b_t; u.b1 = u.b0 + b_h;
;       u.r0 = pm * 256; u.c0 = pn * 256; u.C = C;
; __device__ __forceinline__ int build_units(LAS unsigned char* lds, const Map& m) {
;   LAS Unit* ul = (LAS Unit*)(lds + STAGE_BYTES);
;   __syncthreads();
;   const int tid_ = otid();
;   if (tid_ < MAX_UNITS) { Unit u; if (m.next(tid_, u)) {
;       LAS unsigned long long* w = (LAS unsigned long long*)(ul + tid_);
;       w[0] = (unsigned long long)u.a0; w[1] = (unsigned long long)u.b0; w[2] = (unsigned long long)u.b1; w[3] = (unsigned long long)u.C;
;       w[4] = ((unsigned long long)(unsigned)u.c0 << 32) | (unsigned)u.r0; } }
;   __syncthreads();
;   const long rest = (long)m.total - m.c;
;   int n = rest > 0 ? (int)((rest + m.G - 1) / m.G) : 0;
;   return n < MAX_UNITS ? n : MAX_UNITS;
; }
.LBB0_240:
	v_mov_b64_e32 v[0:1], s[10:11]
	global_load_dwordx2 v[2:3], v[0:1], off sc0 sc1
	s_waitcnt vmcnt(0) lgkmcnt(0)
	v_readfirstlane_b32 s0, v3
	v_readfirstlane_b32 s1, v2
	global_load_dwordx2 v[2:3], v[0:1], off sc0 sc1
	s_waitcnt vmcnt(0) lgkmcnt(0)
	v_readfirstlane_b32 s3, v3
	v_readfirstlane_b32 s2, v2
	global_load_dwordx2 v[2:3], v[0:1], off sc0 sc1
	s_waitcnt vmcnt(0) lgkmcnt(0)
	v_readfirstlane_b32 s18, v2
	v_mov_b32_e32 v2, s74
	ds_read_b32 v2, v2
	global_load_dwordx2 v[0:1], v[0:1], off sc0 sc1
	s_waitcnt vmcnt(0)
	v_readfirstlane_b32 s13, v3
	s_waitcnt lgkmcnt(0)
	s_barrier
	v_readfirstlane_b32 s19, v2
	v_mov_b32_e32 v2, v252
	v_readfirstlane_b32 s8, v1
	v_readfirstlane_b32 s9, v0
	v_cmp_gt_i32_e32 vcc, 40, v2
	s_and_saveexec_b64 s[4:5], vcc
	s_cbranch_execz .LBB0_247
	s_ashr_i32 s6, s19, 31
	v_mov_b32_e32 v0, s19
	v_mov_b32_e32 v1, s6
	v_mad_i64_i32 v[0:1], s[6:7], v2, s20, v[0:1]
	v_cmp_gt_i64_e32 vcc, s[58:59], v[0:1]
	s_and_b64 exec, exec, vcc
	s_cbranch_execz .LBB0_247
	v_ashrrev_i32_e32 v1, 31, v0
	v_lshrrev_b32_e32 v1, 29, v1
	v_add_u32_e32 v1, v0, v1
	v_and_b32_e32 v3, -8, v1
	v_sub_u32_e32 v3, v0, v3
	v_cmp_lt_i32_e32 vcc, -1, v3
	s_and_saveexec_b64 s[6:7], vcc
	s_xor_b64 s[6:7], exec, s[6:7]
	v_lshlrev_b32_e32 v0, 7, v3
	s_andn2_saveexec_b64 s[6:7], s[6:7]
	v_lshl_add_u32 v0, v3, 7, v3
	s_or_b64 exec, exec, s[6:7]
	v_ashrrev_i32_e32 v1, 3, v1
	v_add_u32_e32 v0, v0, v1
	v_ashrrev_i32_e32 v1, 31, v0
	v_lshrrev_b32_e32 v1, 26, v1
	v_add_u32_e32 v1, v0, v1
	v_ashrrev_i32_e32 v3, 6, v1
	v_lshlrev_b32_e32 v3, 2, v3
	v_sub_u32_e32 v4, 64, v3
	v_min_i32_e32 v4, 4, v4
	v_sub_u32_e32 v5, 0, v4
	v_max_i32_e32 v5, v4, v5
	v_cvt_f32_u32_e32 v6, v5
	v_and_b32_e32 v1, 0xffffffc0, v1
	v_sub_u32_e32 v8, 0, v5
	v_sub_u32_e32 v0, v0, v1
	v_rcp_iflag_f32_e32 v6, v6
	v_sub_u32_e32 v1, 0, v0
	v_max_i32_e32 v1, v0, v1
	v_xor_b32_e32 v7, v0, v4
	v_mul_f32_e32 v6, 0x4f7ffffe, v6
	v_cvt_u32_f32_e32 v6, v6
	v_ashrrev_i32_e32 v7, 31, v7
	v_mul_lo_u32 v8, v8, v6
	v_mul_hi_u32 v8, v6, v8
	v_add_u32_e32 v6, v6, v8
	v_mul_hi_u32 v6, v1, v6
	v_mul_lo_u32 v8, v6, v5
	v_sub_u32_e32 v1, v1, v8
	v_add_u32_e32 v9, 1, v6
	v_cmp_ge_u32_e32 vcc, v1, v5
	v_sub_u32_e32 v8, v1, v5
	s_nop 0
	v_cndmask_b32_e32 v6, v6, v9, vcc
	v_cndmask_b32_e32 v1, v1, v8, vcc
	v_add_u32_e32 v8, 1, v6
	v_cmp_ge_u32_e32 vcc, v1, v5
	s_nop 1
	v_cndmask_b32_e32 v1, v6, v8, vcc
	v_xor_b32_e32 v1, v1, v7
	v_sub_u32_e32 v6, v1, v7
	v_mul_lo_u32 v1, v6, v4
	v_sub_u32_e32 v0, v0, v1
	v_ashrrev_i32_e32 v7, 31, v6
	v_add_u32_e32 v8, v3, v0
	v_lshlrev_b64 v[0:1], 20, v[6:7]
	v_lshl_add_u64 v[0:1], s[2:3], 0, v[0:1]
	s_mov_b64 s[2:3], 0x1100000
	v_lshl_add_u64 v[4:5], v[0:1], 0, s[2:3]
	s_mov_b64 s[2:3], 0x1180000
	v_lshl_add_u64 v[0:1], v[0:1], 0, s[2:3]
	v_mad_u64_u32 v[2:3], s[2:3], v2, 48, v[232:233]
	s_lshl_b32 s2, s90, 1
	s_or_b32 s2, s2, 0xb920000
	s_add_u32 s2, s2, s1
	v_ashrrev_i32_e32 v9, 31, v8
	s_addc_u32 s3, 0, s0
	v_lshlrev_b64 v[10:11], 20, v[8:9]
	s_add_u32 s0, s18, 0x251c0000
	v_add_u32_e32 v7, 0x20000, v2
	v_lshl_add_u64 v[2:3], s[2:3], 0, v[10:11]
	s_addc_u32 s1, s13, 0
	v_lshlrev_b32_e32 v8, 8, v8
	ds_write_b128 v7, v[2:5]
	v_mov_b32_e32 v2, s0
	v_mov_b32_e32 v3, s1
	v_lshlrev_b32_e32 v9, 8, v6
	ds_write_b128 v7, v[0:3] offset:16
	ds_write_b64 v7, v[8:9] offset:32

; #define LAS __attribute__((address_space(3)))
; __device__ __forceinline__ int otid() { int t = threadIdx.x; asm volatile("" : "+v"(t)); return t; }
; __device__ __forceinline__ int obid() { extern __shared__ __attribute__((aligned(16))) unsigned char shm_vb[]; return __builtin_amdgcn_readfirstlane(*(volatile LAS int*)((LAS unsigned char*)shm_vb + VB_OFF)); }
; __device__ __forceinline__ void phase_z128(const bf16_t* __restrict__ xb, const bf16_t* __restrict__ w128, const unsigned long long* __restrict__ ss, bf16_t* __restrict__ zt, LAS float* red) {
;   const int tid = otid(), lane = tid & 63, wid = tid >> 6;
;   for (int task = obid(); task < TS / 16; task += gridDim.x) {
;     const int t0 = task * 16;
;     const bf16_t* ap = xb + (size_t)(t0 + (lane & 15)) * DM + 8 * (lane >> 4) + wid * 256;
;     const bf16_t* bp = w128 + (size_t)(lane & 15) * DM + 8 * (lane >> 4) + wid * 256;
;     f32x4 acc = {0.f, 0.f, 0.f, 0.f};
; #pragma unroll
;     for (int ch = 0; ch < 8; ++ch) {
;       const bf16x8 av = *(const bf16x8*)(ap + ch * 32), bv = *(const bf16x8*)(bp + ch * 32);
;       acc = __builtin_amdgcn_mfma_f32_16x16x32_bf16(av, bv, acc, 0, 0, 0);
;     }
.LBB0_262:
	v_mov_b64_e32 v[0:1], s[10:11]
	global_load_dwordx2 v[2:3], v[0:1], off sc0 sc1
	s_waitcnt vmcnt(0)
	v_mov_b32_e32 v34, v252
	s_waitcnt lgkmcnt(0)
	v_readfirstlane_b32 s1, v3
	v_readfirstlane_b32 s6, v2
	global_load_dwordx2 v[2:3], v[0:1], off sc0 sc1
	s_waitcnt vmcnt(0) lgkmcnt(0)
	v_readfirstlane_b32 s5, v3
	v_readfirstlane_b32 s4, v2
	global_load_dwordx2 v[2:3], v[0:1], off sc0 sc1
	s_waitcnt vmcnt(0) lgkmcnt(0)
	v_readfirstlane_b32 s7, v3
	global_load_dwordx2 v[0:1], v[0:1], off sc0 sc1
	s_waitcnt vmcnt(0)
	v_readfirstlane_b32 s8, v2
	s_waitcnt lgkmcnt(0)
	v_readfirstlane_b32 s2, v0
	v_mov_b32_e32 v0, s74
	ds_read_b32 v0, v0
	v_readfirstlane_b32 s3, v1
	s_waitcnt lgkmcnt(0)
	v_readfirstlane_b32 s0, v0
	s_cmpk_gt_i32 s0, 0x3ff
	s_cbranch_scc1 .LBB0_267
	v_ashrrev_i32_e32 v40, 6, v34
	v_lshlrev_b32_e32 v0, 8, v40
	v_and_b32_e32 v36, 15, v34
	v_ashrrev_i32_e32 v1, 31, v0
	v_lshlrev_b64 v[32:33], 1, v[0:1]
	v_lshlrev_b32_e32 v0, 12, v36
	v_mov_b32_e32 v1, v81
	v_and_b32_e32 v80, 48, v34
	v_lshl_add_u64 v[0:1], s[4:5], 0, v[0:1]
	v_lshl_add_u64 v[0:1], v[0:1], 0, v[80:81]
	v_lshl_add_u64 v[0:1], v[0:1], 0, v[32:33]
	s_mov_b64 s[4:5], 0x800000
	v_add_co_u32_e32 v24, vcc, s50, v0
	v_lshl_add_u64 v[28:29], v[0:1], 0, s[4:5]
	s_nop 0
	v_addc_co_u32_e32 v25, vcc, 0, v1, vcc
	global_load_dwordx4 v[0:3], v[28:29], off offset:64
	global_load_dwordx4 v[4:7], v[28:29], off offset:128
	global_load_dwordx4 v[8:11], v[28:29], off offset:192
	global_load_dwordx4 v[12:15], v[28:29], off offset:256
	global_load_dwordx4 v[16:19], v[28:29], off offset:320
	global_load_dwordx4 v[20:23], v[28:29], off offset:384
	s_nop 0
	global_load_dwordx4 v[24:27], v[24:25], off
	s_nop 0
	global_load_dwordx4 v[28:31], v[28:29], off offset:448
	s_lshl_b64 s[4:5], s[36:37], 3
	s_add_u32 s4, s8, s4
	s_addc_u32 s5, s7, s5
	s_add_u32 s4, s4, 0x13940000
	s_addc_u32 s5, s5, 0
	s_lshl_b32 s7, s90, 1
	s_add_u32 s6, s6, s7
	s_addc_u32 s7, s1, 0
	v_and_b32_e32 v35, 63, v34
	s_movk_i32 s1, 0x100
	v_lshl_add_u32 v41, v35, 2, 0
	v_lshl_add_u64 v[38:39], s[6:7], 0, v[80:81]
	v_cmp_gt_i32_e32 vcc, s1, v34
	v_and_b32_e32 v35, 0x3fffffc0, v34
	v_lshrrev_b32_e32 v34, 2, v34
	v_lshlrev_b32_e32 v80, 15, v36
	v_lshl_add_u64 v[32:33], v[38:39], 0, v[32:33]
	s_mov_b64 s[6:7], 0xb920000
	v_lshlrev_b32_e32 v39, 10, v40
	v_lshl_add_u32 v37, v35, 2, v41
	v_and_b32_e32 v38, 12, v34
	v_lshl_add_u64 v[34:35], s[2:3], 0, v[80:81]
	s_mov_b64 s[2:3], 0x1c180000
	v_lshl_add_u64 v[32:33], v[32:33], 0, s[6:7]
	v_lshl_add_u64 v[34:35], v[34:35], 0, s[2:3]
	v_add_u32_e32 v38, v40, v38
	s_lshl_b32 s1, s0, 4
	v_add_u32_e32 v39, v41, v39
	s_branch .LBB0_265

; #define LAS __attribute__((address_space(3)))
; __device__ __forceinline__ unsigned cvt_pk_bf16(float lo, float hi) { unsigned r; asm("v_cvt_pk_bf16_f32 %0, %1, %2" : "=v"(r) : "v"(lo), "v"(hi)); return r; }
; __device__ __forceinline__ int otid() { int t = threadIdx.x; asm volatile("" : "+v"(t)); return t; }
; __device__ __forceinline__ float rinv_of(unsigned long long ss) { return rsqrtf((float)ss * (1.f / 16777216.f) * (1.f / DM) + 1e-6f); }
; __device__ __forceinline__ unsigned xb_add(unsigned* p, unsigned v) { return __hip_atomic_fetch_add(p, v, __ATOMIC_RELAXED, __HIP_MEMORY_SCOPE_AGENT); }
; __device__ __forceinline__ void phase_z128(const bf16_t* __restrict__ xb, const bf16_t* __restrict__ w128, const unsigned long long* __restrict__ ss, bf16_t* __restrict__ zt, LAS float* red) {
;     ...
;     for (int ch = 0; ch < 8; ++ch) {
;       const bf16x8 av = *(const bf16x8*)(ap + ch * 32), bv = *(const bf16x8*)(bp + ch * 32);
;       acc = __builtin_amdgcn_mfma_f32_16x16x32_bf16(av, bv, acc, 0, 0, 0);
;     }
;     __syncthreads();
; #pragma unroll
;     for (int r = 0; r < 4; ++r) red[(wid * 4 + r) * 64 + lane] = acc[r];
;     __syncthreads();
;     if (tid < 256) {
;       const int r = tid >> 6, l = tid & 63;
;       float s = 0.f;
; #pragma unroll
;       for (int w = 0; w < 8; ++w) s += red[(w * 4 + r) * 64 + l];
;       const int t = t0 + (l >> 4) * 4 + r;
;       zt[(size_t)(2048 + (l & 15)) * TS + t] = (bf16_t)(cvt_pk_bf16(s * rinv_of(ss[t]), 0.f) & 0xffffu);
;     }
;   }
; __device__ __forceinline__ void gbar(unsigned* bar, unsigned n, volatile LAS unsigned* st) {
;   asm volatile("s_waitcnt vmcnt(0)" ::: "memory");
;   __syncthreads();
;   if (otid() == 0) {
;     __builtin_amdgcn_s_waitcnt(0);
;     const unsigned x = st[0], nloc = st[1], nx = st[2];
;     const unsigned old = xb_add(&bar[XB_XSUB(x)], 1u);
;     unsigned sp = 0;
;     if (old + 1u == (n + 1u) * nloc) {
.LBB0_265:
	v_add_u32_e32 v40, s1, v36
	v_ashrrev_i32_e32 v41, 31, v40
	v_lshlrev_b64 v[40:41], 12, v[40:41]
	v_lshl_add_u64 v[48:49], v[32:33], 0, v[40:41]
	global_load_dwordx4 v[40:43], v[48:49], off
	global_load_dwordx4 v[44:47], v[48:49], off offset:64
	s_waitcnt vmcnt(0) lgkmcnt(0)
	v_mfma_f32_16x16x32_bf16 v[40:43], v[40:43], v[24:27], 0
	v_mfma_f32_16x16x32_bf16 v[40:43], v[44:47], v[0:3], v[40:43]
	global_load_dwordx4 v[44:47], v[48:49], off offset:128
	s_waitcnt vmcnt(0) lgkmcnt(0)
	v_mfma_f32_16x16x32_bf16 v[40:43], v[44:47], v[4:7], v[40:43]
	global_load_dwordx4 v[44:47], v[48:49], off offset:192
	s_waitcnt vmcnt(0) lgkmcnt(0)
	v_mfma_f32_16x16x32_bf16 v[40:43], v[44:47], v[8:11], v[40:43]
	global_load_dwordx4 v[44:47], v[48:49], off offset:256
	s_waitcnt vmcnt(0) lgkmcnt(0)
	v_mfma_f32_16x16x32_bf16 v[40:43], v[44:47], v[12:15], v[40:43]
	global_load_dwordx4 v[44:47], v[48:49], off offset:320
	s_waitcnt vmcnt(0) lgkmcnt(0)
	v_mfma_f32_16x16x32_bf16 v[40:43], v[44:47], v[16:19], v[40:43]
	global_load_dwordx4 v[44:47], v[48:49], off offset:384
	s_waitcnt vmcnt(0) lgkmcnt(0)
	v_mfma_f32_16x16x32_bf16 v[40:43], v[44:47], v[20:23], v[40:43]
	global_load_dwordx4 v[44:47], v[48:49], off offset:448
	s_waitcnt lgkmcnt(0)
	s_barrier
	s_waitcnt vmcnt(0)
	v_mfma_f32_16x16x32_bf16 v[40:43], v[44:47], v[28:31], v[40:43]
	s_nop 7
	ds_write2st64_b32 v39, v40, v41 offset1:1
	ds_write2st64_b32 v39, v42, v43 offset0:2 offset1:3
	s_waitcnt lgkmcnt(0)
	s_barrier
	s_and_saveexec_b64 s[6:7], vcc
	s_cbranch_execz .LBB0_264
	ds_read2st64_b32 v[40:41], v37 offset1:4
	s_waitcnt lgkmcnt(0)
	v_add_f32_e32 v40, 0, v40
	v_add_f32_e32 v42, v40, v41
	ds_read2st64_b32 v[40:41], v37 offset0:8 offset1:12
	s_waitcnt lgkmcnt(0)
	v_add_f32_e32 v40, v42, v40
	v_add_f32_e32 v42, v40, v41
	ds_read2st64_b32 v[40:41], v37 offset0:16 offset1:20
	s_waitcnt lgkmcnt(0)
	v_add_f32_e32 v40, v42, v40
	v_add_f32_e32 v42, v40, v41
	ds_read2st64_b32 v[40:41], v37 offset0:24 offset1:28
	s_waitcnt lgkmcnt(0)
	v_add_f32_e32 v40, v42, v40
	v_add_f32_e32 v44, v40, v41
	v_add_u32_e32 v40, s1, v38
	v_ashrrev_i32_e32 v41, 31, v40
	v_lshl_add_u64 v[42:43], v[40:41], 3, s[4:5]
	global_load_dwordx2 v[42:43], v[42:43], off
	v_lshl_add_u64 v[40:41], v[40:41], 1, v[34:35]
	s_waitcnt vmcnt(0) lgkmcnt(0)
	v_ffbh_u32_e32 v45, v43
	v_min_u32_e32 v45, 32, v45
	v_lshlrev_b64 v[42:43], v45, v[42:43]
	v_min_u32_e32 v42, 1, v42
	v_or_b32_e32 v42, v43, v42
	v_cvt_f32_u32_e32 v42, v42
	v_sub_u32_e32 v43, 32, v45
	v_ldexp_f32 v42, v42, v43
	v_mul_f32_e32 v42, 0x33800000, v42
	v_fmamk_f32 v42, v42, 0x3a000000, v234
	v_cmp_gt_f32_e64 s[2:3], s50, v42
	v_mul_f32_e32 v43, 0x4b800000, v42
	s_nop 0
	v_cndmask_b32_e64 v42, v42, v43, s[2:3]
	v_rsq_f32_e32 v42, v42
	s_nop 0
	v_mul_f32_e32 v43, 0x45800000, v42
	v_cndmask_b32_e64 v42, v42, v43, s[2:3]
	v_mul_f32_e32 v42, v44, v42
	v_cvt_pk_bf16_f32 v42, v42, v81
	global_store_short v[40:41], v42, off
	s_branch .LBB0_264
.LBB0_267:
	v_mov_b64_e32 v[0:1], s[10:11]
	global_load_dwordx2 v[0:1], v[0:1], off sc0 sc1
	s_waitcnt vmcnt(0)
	s_waitcnt vmcnt(0)
	v_mov_b32_e32 v2, v252
	s_waitcnt lgkmcnt(0)
	s_barrier
	v_add_u32_e32 v56, 1, v158
	v_cmp_ne_u32_e32 vcc, 0, v2
	v_readfirstlane_b32 s0, v1
	v_readfirstlane_b32 s1, v0
	s_and_saveexec_b64 s[2:3], vcc
	s_xor_b64 s[2:3], exec, s[2:3]
	v_add_u32_e32 v56, 1, v158
	s_andn2_saveexec_b64 s[2:3], s[2:3]
	s_cbranch_execz .LBB0_319
	v_readlane_b32 s6, v255, 15
	s_waitcnt vmcnt(0) expcnt(0) lgkmcnt(0)
	s_add_u32 s4, s1, 0x4cc80000
	v_mov_b32_e32 v0, s6
	ds_read_b32 v1, v0
	v_readlane_b32 s6, v255, 16
	s_addc_u32 s5, s0, 0
	s_waitcnt lgkmcnt(0)
	v_lshlrev_b32_e32 v1, 6, v1
	v_add_u32_e32 v80, 0x440, v1
	v_mov_b32_e32 v0, s6
	v_readlane_b32 s6, v255, 17
	v_lshlrev_b64 v[2:3], 2, v[80:81]
	ds_read_b32 v4, v0
	v_mov_b32_e32 v0, s6
	v_lshl_add_u64 v[2:3], s[4:5], 0, v[2:3]
	ds_read_b32 v0, v0
	global_atomic_add v2, v[2:3], v230, off sc0
	s_waitcnt lgkmcnt(0)
	v_mul_lo_u32 v3, v4, v56
	v_add_u32_e32 v80, 0x840, v1
	s_waitcnt vmcnt(0)
	v_add_u32_e32 v2, 1, v2
	v_cmp_ne_u32_e32 vcc, v2, v3
	s_and_saveexec_b64 s[6:7], vcc
	s_xor_b64 s[6:7], exec, s[6:7]
	s_cbranch_execz .LBB0_295
	v_lshlrev_b64 v[0:1], 2, v[80:81]
	v_lshl_add_u64 v[0:1], s[4:5], 0, v[0:1]
	s_mov_b32 s13, 0x1000000
	s_mov_b64 s[8:9], 0
	s_branch .LBB0_283

; __device__ __forceinline__ unsigned xb_ld(unsigned* p) { return __hip_atomic_load(p, __ATOMIC_RELAXED, __HIP_MEMORY_SCOPE_AGENT); }
; __device__ __forceinline__ void gbar(unsigned* bar, unsigned n, volatile LAS unsigned* st) {
;     ...
;     } else {
;       while (xb_ld(&bar[XB_XGEN(x)]) <= n) { __builtin_amdgcn_s_sleep(1); if (++sp > (1u << 24)) break; }
.LBB0_283:
	global_load_dword v2, v[0:1], off sc1
	s_or_b64 s[38:39], s[38:39], exec
	s_waitcnt vmcnt(0) lgkmcnt(0)
	v_cmp_le_u32_e32 vcc, v2, v158
	s_and_saveexec_b64 s[40:41], vcc
	s_cbranch_execz .LBB0_282
	s_cmp_lg_u32 s13, 0
	s_sleep 1
	s_cbranch_scc0 .LBB0_293
	global_load_dword v2, v[0:1], off sc1
	s_mov_b64 s[18:19], -1
	s_waitcnt vmcnt(0) lgkmcnt(0)
	v_cmp_le_u32_e32 vcc, v2, v158
	s_and_saveexec_b64 s[42:43], vcc
	s_cbranch_execz .LBB0_280
	s_sleep 1
	global_load_dword v2, v[0:1], off sc1
	s_waitcnt vmcnt(0) lgkmcnt(0)
	v_cmp_le_u32_e32 vcc, v2, v158
	s_and_saveexec_b64 s[44:45], vcc
	s_cbranch_execz .LBB0_279
	s_sleep 1
	global_load_dword v2, v[0:1], off sc1
	s_waitcnt vmcnt(0) lgkmcnt(0)
	v_cmp_le_u32_e32 vcc, v2, v158
	s_and_saveexec_b64 s[46:47], vcc
	s_cbranch_execz .LBB0_278
	s_sleep 1
	global_load_dword v2, v[0:1], off sc1
	s_waitcnt vmcnt(0) lgkmcnt(0)
	v_cmp_le_u32_e32 vcc, v2, v158
	s_and_saveexec_b64 s[68:69], vcc
	s_cbranch_execz .LBB0_277
	s_sleep 1
	global_load_dword v2, v[0:1], off sc1
	s_waitcnt vmcnt(0) lgkmcnt(0)
	v_cmp_le_u32_e32 vcc, v2, v158
	s_and_saveexec_b64 s[94:95], vcc
	s_cbranch_execz .LBB0_276
	s_sleep 1
	global_load_dword v2, v[0:1], off sc1
	s_mov_b64 s[48:49], -1
	s_waitcnt vmcnt(0) lgkmcnt(0)
	v_cmp_le_u32_e32 vcc, v2, v158
	s_and_saveexec_b64 s[18:19], vcc
	s_cbranch_execz .LBB0_275
	s_sleep 1
	global_load_dword v2, v[0:1], off sc1
	s_waitcnt vmcnt(0) lgkmcnt(0)
	v_cmp_le_u32_e32 vcc, v2, v158
	s_and_saveexec_b64 s[66:67], vcc
	s_cbranch_execz .LBB0_274
	s_add_i32 s13, s13, -8
	s_xor_b64 s[48:49], exec, -1
	s_sleep 1
	s_branch .LBB0_274

; __device__ __forceinline__ unsigned xb_add(unsigned* p, unsigned v) { return __hip_atomic_fetch_add(p, v, __ATOMIC_RELAXED, __HIP_MEMORY_SCOPE_AGENT); }
; __device__ __forceinline__ void gbar(unsigned* bar, unsigned n, volatile LAS unsigned* st) {
;     ...
;     if (old + 1u == (n + 1u) * nloc) {
;       __builtin_amdgcn_fence(__ATOMIC_RELEASE, "agent");
;       asm volatile("s_waitcnt vmcnt(0)" ::: "memory");
;       xb_add(&bar[XB_TOP], 1u);
.LBB0_295:
	s_andn2_saveexec_b64 s[6:7], s[6:7]
	s_cbranch_execz .LBB0_318
	v_mov_b32_e32 v1, s1
	v_add_co_u32_e32 v2, vcc, 0x4cc83000, v1
	v_mov_b32_e32 v1, s0
	buffer_wbl2 sc1
	s_waitcnt vmcnt(0)
	v_addc_co_u32_e32 v3, vcc, 0, v1, vcc
	global_atomic_add v[2:3], v230, off offset:256
	s_add_u32 s8, s1, 0x4cc83100
	s_addc_u32 s9, s0, 0
	v_mul_lo_u32 v0, v0, v56
	s_mov_b32 s0, 0x1000000
	s_mov_b64 s[38:39], 0
	s_branch .LBB0_306

; __device__ __forceinline__ unsigned xb_ld(unsigned* p) { return __hip_atomic_load(p, __ATOMIC_RELAXED, __HIP_MEMORY_SCOPE_AGENT); }
; __device__ __forceinline__ void gbar(unsigned* bar, unsigned n, volatile LAS unsigned* st) {
;     ...
;       while (xb_ld(&bar[XB_TOP]) < (n + 1u) * nx) { __builtin_amdgcn_s_sleep(1); if (++sp > (1u << 24)) break; }
.LBB0_306:
	v_mov_b64_e32 v[2:3], s[8:9]
	global_load_dword v1, v[2:3], off sc1
	s_or_b64 s[40:41], s[40:41], exec
	s_waitcnt vmcnt(0) lgkmcnt(0)
	v_cmp_lt_u32_e32 vcc, v1, v0
	s_and_saveexec_b64 s[42:43], vcc
	s_cbranch_execz .LBB0_305
	s_cmp_lg_u32 s0, 0
	s_sleep 1
	s_cbranch_scc0 .LBB0_316
	v_mov_b64_e32 v[2:3], s[8:9]
	global_load_dword v1, v[2:3], off sc1
	s_mov_b64 s[18:19], -1
	s_waitcnt vmcnt(0) lgkmcnt(0)
	v_cmp_lt_u32_e32 vcc, v1, v0
	s_and_saveexec_b64 s[44:45], vcc
	s_cbranch_execz .LBB0_303
	v_mov_b64_e32 v[2:3], s[8:9]
	s_sleep 1
	global_load_dword v1, v[2:3], off sc1
	s_waitcnt vmcnt(0) lgkmcnt(0)
	v_cmp_lt_u32_e32 vcc, v1, v0
	s_and_saveexec_b64 s[68:69], vcc
	s_cbranch_execz .LBB0_302
	v_mov_b64_e32 v[2:3], s[8:9]
	s_sleep 1
	global_load_dword v1, v[2:3], off sc1
	s_waitcnt vmcnt(0) lgkmcnt(0)
	v_cmp_lt_u32_e32 vcc, v1, v0
	s_and_saveexec_b64 s[46:47], vcc
	s_cbranch_execz .LBB0_301
	v_mov_b64_e32 v[2:3], s[8:9]
	s_sleep 1
	global_load_dword v1, v[2:3], off sc1
	s_waitcnt vmcnt(0) lgkmcnt(0)
	v_cmp_lt_u32_e32 vcc, v1, v0
	s_and_saveexec_b64 s[94:95], vcc
	s_cbranch_execz .LBB0_300
	v_mov_b64_e32 v[2:3], s[8:9]
	s_sleep 1
	global_load_dword v1, v[2:3], off sc1
	s_waitcnt vmcnt(0) lgkmcnt(0)
	v_cmp_lt_u32_e32 vcc, v1, v0
	s_and_saveexec_b64 s[96:97], vcc
	s_cbranch_execz .LBB0_299
	v_mov_b64_e32 v[2:3], s[8:9]
	s_sleep 1
	global_load_dword v1, v[2:3], off sc1
	s_mov_b64 s[48:49], -1
	s_waitcnt vmcnt(0) lgkmcnt(0)
	v_cmp_lt_u32_e32 vcc, v1, v0
	s_and_saveexec_b64 s[18:19], vcc
	s_cbranch_execz .LBB0_298
	v_mov_b64_e32 v[2:3], s[8:9]
	s_sleep 1
	global_load_dword v1, v[2:3], off sc1
	s_waitcnt vmcnt(0) lgkmcnt(0)
	v_cmp_lt_u32_e32 vcc, v1, v0
	s_and_saveexec_b64 s[66:67], vcc
	s_cbranch_execz .LBB0_297
	s_add_i32 s0, s0, -8
	s_xor_b64 s[48:49], exec, -1
	s_sleep 1
	s_branch .LBB0_297

; __device__ __forceinline__ unsigned xb_add(unsigned* p, unsigned v) { return __hip_atomic_fetch_add(p, v, __ATOMIC_RELAXED, __HIP_MEMORY_SCOPE_AGENT); }
; __device__ __forceinline__ void gbar(unsigned* bar, unsigned n, volatile LAS unsigned* st) {
;     ...
;       __builtin_amdgcn_fence(__ATOMIC_ACQUIRE, "agent");
;       xb_add(&bar[XB_XGEN(x)], 1u);
;       asm volatile("s_waitcnt vmcnt(0)" ::: "memory");
.LBB0_317:
	s_or_b64 exec, exec, s[38:39]
	v_lshlrev_b64 v[0:1], 2, v[80:81]
	v_lshl_add_u64 v[0:1], s[4:5], 0, v[0:1]
	buffer_inv sc1
	global_atomic_add v[0:1], v230, off
	s_waitcnt vmcnt(0)

; __device__ __forceinline__ int otid() { int t = threadIdx.x; asm volatile("" : "+v"(t)); return t; }
; __device__ __forceinline__ int obid() { extern __shared__ __attribute__((aligned(16))) unsigned char shm_vb[]; return __builtin_amdgcn_readfirstlane(*(volatile LAS int*)((LAS unsigned char*)shm_vb + VB_OFF)); }
; __device__ __forceinline__ void phase_fold(const bf16_t* __restrict__ zt, bf16_t* __restrict__ zf, float* __restrict__ ph, const int nseq, const int S) {
;   const int tid = otid(), lane = tid & 63, nw = gridDim.x * 8;
;   const int K2 = S / 4 + 128, H = S / 2, Q4 = S / 4;
;   for (int task = obid() * 8 + (tid >> 6); task < ZT_ROWS * nseq; task += nw) {
;     const int c = task / nseq, seq = task % nseq;
;     const bool cosrow = c < 2304;
;     const bf16_t* a = zt + (size_t)c * TS + (size_t)seq * S;
;     bf16_t* f = zf + (size_t)c * ZFLD + (size_t)seq * 2 * K2;
;     float alt = 0.f;
;     for (int j = lane * 8; j < K2; j += 512) {
; __device__ __forceinline__ void gbar(unsigned* bar, unsigned n, volatile LAS unsigned* st) {
;     ...
;   __syncthreads();
.LBB0_319:
	s_or_b64 exec, exec, s[2:3]
	v_mov_b64_e32 v[0:1], s[10:11]
	s_waitcnt lgkmcnt(0)
	s_barrier
	global_load_dwordx2 v[2:3], v[0:1], off sc0 sc1
	s_waitcnt vmcnt(0)
	s_xor_b32 s1, s88, 1
	s_lshr_b32 s13, s17, 2
	s_or_b32 s61, s13, 0x80
	s_lshr_b32 s40, s17, 1
	s_waitcnt lgkmcnt(0)
	v_readfirstlane_b32 s5, v3
	v_readfirstlane_b32 s4, v2
	global_load_dwordx2 v[2:3], v[0:1], off sc0 sc1
	s_waitcnt vmcnt(0) lgkmcnt(0)
	v_readfirstlane_b32 s7, v3
	global_load_dwordx2 v[0:1], v[0:1], off sc0 sc1
	s_waitcnt vmcnt(0)
	v_readfirstlane_b32 s6, v2
	s_waitcnt lgkmcnt(0)
	v_readfirstlane_b32 s2, v1
	v_readfirstlane_b32 s3, v0
	v_mov_b32_e32 v0, v252
	v_mov_b32_e32 v1, s74
	ds_read_b32 v1, v1
	s_waitcnt lgkmcnt(0)
	v_readfirstlane_b32 s0, v1
	v_ashrrev_i32_e32 v1, 6, v0
	s_nop 0
	v_lshl_add_u32 v57, s0, 3, v1
	s_lshl_b32 s0, 0x1100, s1
	v_cmp_gt_i32_e32 vcc, s0, v57
	s_and_saveexec_b64 s[38:39], vcc
	s_cbranch_execz .LBB0_338
	v_cvt_f32_ubyte0_e32 v1, s89
	v_rcp_iflag_f32_e32 v1, v1
	s_add_u32 s42, s4, 0x18180000
	s_addc_u32 s43, s5, 0
	s_add_u32 s44, s3, 0x35240000
	v_mul_f32_e32 v1, 0x4f7ffffe, v1
	v_cvt_u32_f32_e32 v1, v1
	s_addc_u32 s45, s2, 0
	s_and_b64 s[8:9], s[92:93], exec
	s_cselect_b32 s28, 13, 14
	s_sub_i32 s8, 0, s89
	v_and_b32_e32 v0, 63, v0
	v_mul_lo_u32 v2, s8, v1
	v_mul_hi_u32 v2, v1, v2
	v_lshlrev_b32_e32 v80, 4, v0
	v_lshlrev_b32_e32 v58, 3, v0
	v_cmp_eq_u32_e64 s[2:3], 0, v0
	v_add_u32_e32 v59, v1, v2
	v_lshl_add_u64 v[0:1], s[6:7], 0, v[80:81]
	s_mov_b64 s[6:7], 0x20980000
	v_lshl_add_u64 v[18:19], v[0:1], 0, s[6:7]
	s_lshl_b32 s6, s40, 1
	s_add_u32 s29, s6, 0x200
	s_add_u32 s6, s4, s17
	s_addc_u32 s7, s5, 0
	v_sub_co_u32_e32 v0, vcc, s17, v80
	v_lshl_add_u64 v[22:23], s[6:7], 0, v[80:81]
	s_nop 0
	v_subb_co_u32_e64 v1, s[6:7], 0, 0, vcc
	s_lshl_b32 s6, s17, 1
	v_lshl_add_u64 v[24:25], s[4:5], 0, v[0:1]
	v_sub_co_u32_e32 v0, vcc, s6, v80
	v_sub_u32_e32 v16, 0, v58
	s_nop 0
	v_subb_co_u32_e64 v1, s[6:7], 0, 0, vcc
	s_mov_b32 s41, s12
	v_ashrrev_i32_e32 v17, 31, v16
	v_lshl_add_u64 v[20:21], s[4:5], 0, v[80:81]
	v_lshl_add_u64 v[26:27], s[4:5], 0, v[0:1]
	s_mov_b64 s[68:69], 0
	s_branch .LBB0_322

; __device__ __forceinline__ float bf_lo(unsigned u) { return __uint_as_float(u << 16); }
; __device__ __forceinline__ void phase_fold(const bf16_t* __restrict__ zt, bf16_t* __restrict__ zf, float* __restrict__ ph, const int nseq, const int S) {
;     ...
;     for (int j = lane * 8; j < K2; j += 512) {
;       unsigned z = 0; asm volatile("" : "+v"(z));
;       uint4 oe = make_uint4(z, z, z, z), oo = oe;
;       if (j <= Q4) {
;         const uint4 w1 = *(const uint4*)(a + j), w2 = *(const uint4*)(a + S - j - 8), w3 = *(const uint4*)(a + H - j - 8), w4 = *(const uint4*)(a + H + j);
;         const float s2 = (j > 0) ? __uint_as_float(((unsigned)a[S - j]) << 16) : 0.f;
;         const float s3 = __uint_as_float(((unsigned)a[H - j]) << 16);
;         const float v1[8] = {bf_lo(w1.x), bf_hi(w1.x), bf_lo(w1.y), bf_hi(w1.y), bf_lo(w1.z), bf_hi(w1.z), bf_lo(w1.w), bf_hi(w1.w)};
;         const float v2[8] = {s2, bf_hi(w2.w), bf_lo(w2.w), bf_hi(w2.z), bf_lo(w2.z), bf_hi(w2.y), bf_lo(w2.y), bf_hi(w2.x)};
;         const float v3[8] = {s3, bf_hi(w3.w), bf_lo(w3.w), bf_hi(w3.z), bf_lo(w3.z), bf_hi(w3.y), bf_lo(w3.y), bf_hi(w3.x)};
;         const float v4[8] = {bf_lo(w4.x), bf_hi(w4.x), bf_lo(w4.y), bf_hi(w4.y), bf_lo(w4.z), bf_hi(w4.z), bf_lo(w4.w), bf_hi(w4.w)};
;         float ve[8], vo[8];
; #pragma unroll
;         for (int e = 0; e < 8; ++e) {
;           const int jj = j + e;
;           float f1, f2;
;           if (cosrow) { f1 = v1[e] + v2[e]; f2 = v3[e] + v4[e]; if (jj == 0) { f1 = v1[e]; f2 = v3[e]; } }
;           else        { f1 = v1[e] - v2[e]; f2 = v3[e] - v4[e]; if (jj == 0) { f1 = 0.f; f2 = 0.f; } }
;           float xe = cosrow ? f1 + f2 : f1 - f2, xo = cosrow ? f1 - f2 : f1 + f2;
;           if (jj == Q4) { xe = cosrow ? f1 : 0.f; xo = cosrow ? 0.f : f1; }
;           if (jj > Q4) { xe = 0.f; xo = 0.f; }
;           ve[e] = xe; vo[e] = xo;
;         }
;         oe.x = cvt_pk_bf16(ve[0], ve[1]); oe.y = cvt_pk_bf16(ve[2], ve[3]); oe.z = cvt_pk_bf16(ve[4], ve[5]); oe.w = cvt_pk_bf16(ve[6], ve[7]);
;         oo.x = cvt_pk_bf16(vo[0], vo[1]); oo.y = cvt_pk_bf16(vo[2], vo[3]); oo.z = cvt_pk_bf16(vo[4], vo[5]); oo.w = cvt_pk_bf16(vo[6], vo[7]);
;         alt += (bf_lo(oe.x) - bf_hi(oe.x)) + (bf_lo(oe.y) - bf_hi(oe.y)) + (bf_lo(oe.z) - bf_hi(oe.z)) + (bf_lo(oe.w) - bf_hi(oe.w));
;       }
;       *(uint4*)(f + j) = oe; *(uint4*)(f + K2 + j) = oo;
.LBB0_325:
	s_andn2_saveexec_b64 s[8:9], s[96:97]
	s_or_b64 exec, exec, s[8:9]
	v_add_u32_e32 v31, 0x200, v31
	s_movk_i32 s8, 0xfe00
	s_mov_b32 s9, -1
	v_cmp_le_u32_e32 vcc, s61, v31
	global_store_dwordx4 v[36:37], v[0:3], off
	v_lshl_add_u64 v[46:47], v[46:47], 0, s[8:9]
	v_lshl_add_u64 v[38:39], v[38:39], 0, s[58:59]
	v_lshl_add_u64 v[0:1], v[36:37], 0, s[40:41]
	v_lshl_add_u64 v[36:37], v[36:37], 0, s[58:59]
	v_lshl_add_u64 v[40:41], v[40:41], 0, s[58:59]
	v_lshl_add_u64 v[42:43], v[42:43], 0, s[72:73]
	s_or_b64 s[94:95], vcc, s[94:95]
	v_lshl_add_u64 v[44:45], v[44:45], 0, s[72:73]
	global_store_dwordx4 v[0:1], v[4:7], off offset:256
	s_andn2_b64 exec, exec, s[94:95]
	s_cbranch_execz .LBB0_336
.LBB0_326:
	v_mov_b32_e32 v2, v81
	v_cmp_ge_u32_e32 vcc, s13, v31
	v_mov_b32_e32 v3, v2
	v_mov_b64_e32 v[0:1], v[2:3]
	v_mov_b64_e32 v[6:7], v[2:3]
	v_mov_b64_e32 v[4:5], v[2:3]
	s_and_saveexec_b64 s[8:9], vcc
	s_xor_b64 s[96:97], exec, s[8:9]
	s_cbranch_execz .LBB0_325
	v_lshl_add_u64 v[0:1], v[38:39], 0, v[32:33]
	v_add_co_u32_e32 v0, vcc, 0x18180000, v0
	v_lshl_add_u64 v[4:5], v[44:45], 0, v[32:33]
	s_nop 0
	v_addc_co_u32_e32 v1, vcc, 0, v1, vcc
	v_add_co_u32_e32 v4, vcc, 0x1817f000, v4
	v_lshl_add_u64 v[8:9], v[42:43], 0, v[32:33]
	s_nop 0
	v_addc_co_u32_e32 v5, vcc, 0, v5, vcc
	v_add_co_u32_e32 v8, vcc, 0x1817f000, v8
	v_lshl_add_u64 v[12:13], v[40:41], 0, v[32:33]
	s_nop 0
	v_addc_co_u32_e32 v9, vcc, 0, v9, vcc
	v_add_co_u32_e32 v12, vcc, 0x18180000, v12
	global_load_dwordx4 v[0:3], v[0:1], off
	s_nop 0
	v_addc_co_u32_e32 v13, vcc, 0, v13, vcc
	global_load_dwordx4 v[4:7], v[4:5], off offset:4080
	v_cmp_eq_u32_e32 vcc, 0, v31
	global_load_dwordx4 v[8:11], v[8:9], off offset:4080
	v_cmp_ne_u32_e64 s[8:9], 0, v31
	global_load_dwordx4 v[12:15], v[12:13], off
	v_mov_b32_e32 v52, 0
	s_and_saveexec_b64 s[18:19], s[8:9]
	s_cbranch_execz .LBB0_329
	v_add_u32_e32 v80, s17, v46
	v_lshl_add_u64 v[48:49], v[80:81], 1, v[34:35]
	global_load_ushort v48, v[48:49], off
	s_waitcnt vmcnt(0) lgkmcnt(0)
	v_lshlrev_b32_e32 v52, 16, v48
.LBB0_329:
	s_or_b64 exec, exec, s[18:19]
	v_add_u32_e32 v80, s40, v46
	v_lshl_add_u64 v[48:49], v[80:81], 1, v[34:35]
	global_load_ushort v48, v[48:49], off
	s_waitcnt vmcnt(0) lgkmcnt(0)
	v_lshlrev_b32_e32 v54, 16, v0
	v_lshlrev_b32_e32 v53, 16, v12
	v_lshlrev_b32_e32 v55, 16, v48
	s_and_saveexec_b64 s[8:9], s[6:7]
	s_xor_b64 s[8:9], exec, s[8:9]
	s_cbranch_execz .LBB0_333
	v_pk_add_f32 v[48:49], v[54:55], v[52:53] neg_lo:[0,1] neg_hi:[0,1]
	s_and_saveexec_b64 s[18:19], vcc
	v_mov_b32_e32 v49, 0
	v_mov_b32_e32 v48, v49
	s_or_b64 exec, exec, s[18:19]

; __device__ __forceinline__ int otid() { int t = threadIdx.x; asm volatile("" : "+v"(t)); return t; }
; __device__ __forceinline__ int obid() { extern __shared__ __attribute__((aligned(16))) unsigned char shm_vb[]; return __builtin_amdgcn_readfirstlane(*(volatile LAS int*)((LAS unsigned char*)shm_vb + VB_OFF)); }
; __device__ __forceinline__ void phase_zero(unsigned long long* __restrict__ p, int n) {
;   for (int i = obid() * 512 + otid(); i < n; i += gridDim.x * 512) { unsigned z = 0; asm volatile("" : "+v"(z)); p[i] = z; }
; }
; __device__ __forceinline__ void phase_fold(const bf16_t* __restrict__ zt, bf16_t* __restrict__ zf, float* __restrict__ ph, const int nseq, const int S) {
;     ...
;     alt = wave_sum(alt);
;     if (lane == 0 && cosrow) ph[seq * 2304 + c] = alt;
.LBB0_336:
	s_or_b64 exec, exec, s[94:95]
	v_and_b32_e32 v0, 64, v189
	v_add_u32_e32 v1, 64, v0
	v_xor_b32_e32 v0, 32, v189
	v_cmp_lt_i32_e32 vcc, v0, v1
	v_xor_b32_e32 v2, 16, v189
	s_and_b64 s[6:7], s[2:3], s[4:5]
	v_cndmask_b32_e32 v0, v189, v0, vcc
	v_lshlrev_b32_e32 v0, 2, v0
	ds_bpermute_b32 v0, v0, v29
	v_cmp_lt_i32_e32 vcc, v2, v1
	s_waitcnt lgkmcnt(0)
	v_add_f32_e32 v0, v29, v0
	v_cndmask_b32_e32 v2, v189, v2, vcc
	v_lshlrev_b32_e32 v2, 2, v2
	ds_bpermute_b32 v2, v2, v0
	s_waitcnt lgkmcnt(0)
	v_add_f32_e32 v0, v0, v2
	v_xor_b32_e32 v2, 8, v189
	v_cmp_lt_i32_e32 vcc, v2, v1
	s_nop 1
	v_cndmask_b32_e32 v2, v189, v2, vcc
	v_lshlrev_b32_e32 v2, 2, v2
	ds_bpermute_b32 v2, v2, v0
	s_waitcnt lgkmcnt(0)
	v_add_f32_e32 v0, v0, v2
	v_xor_b32_e32 v2, 4, v189
	v_cmp_lt_i32_e32 vcc, v2, v1
	s_nop 1
	v_cndmask_b32_e32 v2, v189, v2, vcc
	v_lshlrev_b32_e32 v2, 2, v2
	ds_bpermute_b32 v2, v2, v0
	s_waitcnt lgkmcnt(0)
	v_add_f32_e32 v0, v0, v2
	v_xor_b32_e32 v2, 2, v189
	v_cmp_lt_i32_e32 vcc, v2, v1
	s_nop 1
	v_cndmask_b32_e32 v2, v189, v2, vcc
	v_lshlrev_b32_e32 v2, 2, v2
	ds_bpermute_b32 v2, v2, v0
	s_waitcnt lgkmcnt(0)
	v_add_f32_e32 v0, v0, v2
	v_xor_b32_e32 v2, 1, v189
	v_cmp_lt_i32_e32 vcc, v2, v1
	s_nop 1
	v_cndmask_b32_e32 v1, v189, v2, vcc
	v_lshlrev_b32_e32 v1, 2, v1
	ds_bpermute_b32 v1, v1, v0
	s_and_saveexec_b64 s[4:5], s[6:7]
	s_cbranch_execz .LBB0_321
	s_movk_i32 s6, 0x900
	v_mad_u64_u32 v[2:3], s[6:7], v30, s6, v[28:29]
	v_ashrrev_i32_e32 v3, 31, v2
	v_lshl_add_u64 v[2:3], v[2:3], 2, s[44:45]
	s_waitcnt lgkmcnt(0)
	v_add_f32_e32 v0, v0, v1
	global_store_dword v[2:3], v0, off
	s_branch .LBB0_321
.LBB0_338:
	s_or_b64 exec, exec, s[38:39]
	s_waitcnt lgkmcnt(0)
	v_mov_b64_e32 v[0:1], s[10:11]
	global_load_dwordx2 v[2:3], v[0:1], off sc0 sc1
	s_waitcnt vmcnt(0)
	v_mov_b32_e32 v0, s74
	ds_read_b32 v0, v0
	v_mov_b32_e32 v1, v252
	s_movk_i32 s2, 0x4000
	s_waitcnt lgkmcnt(0)
	v_readfirstlane_b32 s0, v0
	v_readfirstlane_b32 s4, v2
	s_nop 0
	v_lshl_add_u32 v0, s0, 9, v1
	v_readfirstlane_b32 s0, v3
	v_cmp_gt_i32_e32 vcc, s2, v0
	s_and_saveexec_b64 s[2:3], vcc
	s_cbranch_execz .LBB0_341
	s_lshl_b64 s[6:7], s[36:37], 3
	s_add_u32 s4, s4, s6
	s_addc_u32 s0, s0, s7
	s_add_u32 s4, s4, 0x13940000
	s_addc_u32 s5, s0, 0
	s_mov_b64 s[6:7], 0

; #define LAS __attribute__((address_space(3)))
; __device__ __forceinline__ int otid() { int t = threadIdx.x; asm volatile("" : "+v"(t)); return t; }
; __device__ __forceinline__ unsigned xb_add(unsigned* p, unsigned v) { return __hip_atomic_fetch_add(p, v, __ATOMIC_RELAXED, __HIP_MEMORY_SCOPE_AGENT); }
; __device__ __forceinline__ void gbar(unsigned* bar, unsigned n, volatile LAS unsigned* st) {
;   asm volatile("s_waitcnt vmcnt(0)" ::: "memory");
;   __syncthreads();
;   if (otid() == 0) {
;     __builtin_amdgcn_s_waitcnt(0);
;     const unsigned x = st[0], nloc = st[1], nx = st[2];
;     const unsigned old = xb_add(&bar[XB_XSUB(x)], 1u);
;     unsigned sp = 0;
;     if (old + 1u == (n + 1u) * nloc) {
; __device__ __forceinline__ unsigned long long karg(int i) {
;   const volatile unsigned long long* ka = (const volatile unsigned long long*)__builtin_amdgcn_kernarg_segment_ptr();
;   const unsigned long long v = ka[i];
;   return ((unsigned long long)__builtin_amdgcn_readfirstlane((unsigned)(v >> 32)) << 32) | (unsigned)__builtin_amdgcn_readfirstlane((unsigned)v);
.LBB0_341:
	s_or_b64 exec, exec, s[2:3]
	v_mov_b64_e32 v[0:1], s[10:11]
	global_load_dwordx2 v[0:1], v[0:1], off sc0 sc1
	s_waitcnt vmcnt(0)
	s_waitcnt vmcnt(0)
	v_mov_b32_e32 v2, v252
	s_waitcnt lgkmcnt(0)
	s_barrier
	v_add_u32_e32 v140, 2, v158
	v_cmp_ne_u32_e32 vcc, 0, v2
	v_readfirstlane_b32 s0, v1
	v_readfirstlane_b32 s28, v0
	s_and_saveexec_b64 s[2:3], vcc
	s_xor_b64 s[2:3], exec, s[2:3]
	v_add_u32_e32 v140, 2, v158
	s_andn2_saveexec_b64 s[2:3], s[2:3]
	s_cbranch_execz .LBB0_391
	v_readlane_b32 s6, v255, 15
	s_waitcnt vmcnt(0) expcnt(0) lgkmcnt(0)
	s_add_u32 s4, s28, 0x4cc80000
	v_mov_b32_e32 v0, s6
	ds_read_b32 v1, v0
	v_readlane_b32 s6, v255, 16
	s_addc_u32 s5, s0, 0
	s_waitcnt lgkmcnt(0)
	v_lshlrev_b32_e32 v1, 6, v1
	v_add_u32_e32 v80, 0x440, v1
	v_mov_b32_e32 v0, s6
	v_readlane_b32 s6, v255, 17
	v_lshlrev_b64 v[2:3], 2, v[80:81]
	ds_read_b32 v4, v0
	v_mov_b32_e32 v0, s6
	v_lshl_add_u64 v[2:3], s[4:5], 0, v[2:3]
	ds_read_b32 v0, v0
	global_atomic_add v2, v[2:3], v230, off sc0
	s_waitcnt lgkmcnt(0)
	v_mul_lo_u32 v3, v4, v140
	v_add_u32_e32 v80, 0x840, v1
	s_waitcnt vmcnt(0)
	v_add_u32_e32 v2, 1, v2
	v_cmp_ne_u32_e32 vcc, v2, v3
	s_and_saveexec_b64 s[6:7], vcc
	s_xor_b64 s[6:7], exec, s[6:7]
	s_cbranch_execz .LBB0_367
	v_lshlrev_b64 v[0:1], 2, v[80:81]
	v_lshl_add_u64 v[0:1], s[4:5], 0, v[0:1]
	s_mov_b32 s29, 0x1000000
	s_mov_b64 s[8:9], 0
	s_branch .LBB0_355

; __device__ __forceinline__ unsigned xb_ld(unsigned* p) { return __hip_atomic_load(p, __ATOMIC_RELAXED, __HIP_MEMORY_SCOPE_AGENT); }
; __device__ __forceinline__ void gbar(unsigned* bar, unsigned n, volatile LAS unsigned* st) {
;     ...
;     } else {
;       while (xb_ld(&bar[XB_XGEN(x)]) <= n) { __builtin_amdgcn_s_sleep(1); if (++sp > (1u << 24)) break; }
.LBB0_355:
	global_load_dword v2, v[0:1], off sc1
	s_or_b64 s[36:37], s[36:37], exec
	s_waitcnt vmcnt(0) lgkmcnt(0)
	v_cmp_le_u32_e32 vcc, v2, v56
	s_and_saveexec_b64 s[38:39], vcc
	s_cbranch_execz .LBB0_354
	s_cmp_lg_u32 s29, 0
	s_sleep 1
	s_cbranch_scc0 .LBB0_365
	global_load_dword v2, v[0:1], off sc1
	s_mov_b64 s[18:19], -1
	s_waitcnt vmcnt(0) lgkmcnt(0)
	v_cmp_le_u32_e32 vcc, v2, v56
	s_and_saveexec_b64 s[42:43], vcc
	s_cbranch_execz .LBB0_352
	s_sleep 1
	global_load_dword v2, v[0:1], off sc1
	s_waitcnt vmcnt(0) lgkmcnt(0)
	v_cmp_le_u32_e32 vcc, v2, v56
	s_and_saveexec_b64 s[44:45], vcc
	s_cbranch_execz .LBB0_351
	s_sleep 1
	global_load_dword v2, v[0:1], off sc1
	s_waitcnt vmcnt(0) lgkmcnt(0)
	v_cmp_le_u32_e32 vcc, v2, v56
	s_and_saveexec_b64 s[46:47], vcc
	s_cbranch_execz .LBB0_350
	s_sleep 1
	global_load_dword v2, v[0:1], off sc1
	s_waitcnt vmcnt(0) lgkmcnt(0)
	v_cmp_le_u32_e32 vcc, v2, v56
	s_and_saveexec_b64 s[68:69], vcc
	s_cbranch_execz .LBB0_349
	s_sleep 1
	global_load_dword v2, v[0:1], off sc1
	s_waitcnt vmcnt(0) lgkmcnt(0)
	v_cmp_le_u32_e32 vcc, v2, v56
	s_and_saveexec_b64 s[94:95], vcc
	s_cbranch_execz .LBB0_348
	s_sleep 1
	global_load_dword v2, v[0:1], off sc1
	s_mov_b64 s[48:49], -1
	s_waitcnt vmcnt(0) lgkmcnt(0)
	v_cmp_le_u32_e32 vcc, v2, v56
	s_and_saveexec_b64 s[18:19], vcc
	s_cbranch_execz .LBB0_347
	s_sleep 1
	global_load_dword v2, v[0:1], off sc1
	s_waitcnt vmcnt(0) lgkmcnt(0)
	v_cmp_le_u32_e32 vcc, v2, v56
	s_and_saveexec_b64 s[66:67], vcc
	s_cbranch_execz .LBB0_346
	s_add_i32 s29, s29, -8
	s_xor_b64 s[48:49], exec, -1
	s_sleep 1
	s_branch .LBB0_346

; __device__ __forceinline__ unsigned xb_add(unsigned* p, unsigned v) { return __hip_atomic_fetch_add(p, v, __ATOMIC_RELAXED, __HIP_MEMORY_SCOPE_AGENT); }
; __device__ __forceinline__ void gbar(unsigned* bar, unsigned n, volatile LAS unsigned* st) {
;     ...
;     if (old + 1u == (n + 1u) * nloc) {
;       __builtin_amdgcn_fence(__ATOMIC_RELEASE, "agent");
;       asm volatile("s_waitcnt vmcnt(0)" ::: "memory");
;       xb_add(&bar[XB_TOP], 1u);
.LBB0_367:
	s_andn2_saveexec_b64 s[6:7], s[6:7]
	s_cbranch_execz .LBB0_390
	v_mov_b32_e32 v1, s28
	v_add_co_u32_e32 v2, vcc, 0x4cc83000, v1
	v_mov_b32_e32 v1, s0
	buffer_wbl2 sc1
	s_waitcnt vmcnt(0)
	v_addc_co_u32_e32 v3, vcc, 0, v1, vcc
	global_atomic_add v[2:3], v230, off offset:256
	s_add_u32 s8, s28, 0x4cc83100
	s_addc_u32 s9, s0, 0
	v_mul_lo_u32 v0, v0, v140
	s_mov_b32 s0, 0x1000000
	s_mov_b64 s[36:37], 0
	s_branch .LBB0_378

; __device__ __forceinline__ unsigned xb_ld(unsigned* p) { return __hip_atomic_load(p, __ATOMIC_RELAXED, __HIP_MEMORY_SCOPE_AGENT); }
; __device__ __forceinline__ void gbar(unsigned* bar, unsigned n, volatile LAS unsigned* st) {
;     ...
;       while (xb_ld(&bar[XB_TOP]) < (n + 1u) * nx) { __builtin_amdgcn_s_sleep(1); if (++sp > (1u << 24)) break; }
.LBB0_378:
	v_mov_b64_e32 v[2:3], s[8:9]
	global_load_dword v1, v[2:3], off sc1
	s_or_b64 s[38:39], s[38:39], exec
	s_waitcnt vmcnt(0) lgkmcnt(0)
	v_cmp_lt_u32_e32 vcc, v1, v0
	s_and_saveexec_b64 s[42:43], vcc
	s_cbranch_execz .LBB0_377
	s_cmp_lg_u32 s0, 0
	s_sleep 1
	s_cbranch_scc0 .LBB0_388
	v_mov_b64_e32 v[2:3], s[8:9]
	global_load_dword v1, v[2:3], off sc1
	s_mov_b64 s[18:19], -1
	s_waitcnt vmcnt(0) lgkmcnt(0)
	v_cmp_lt_u32_e32 vcc, v1, v0
	s_and_saveexec_b64 s[44:45], vcc
	s_cbranch_execz .LBB0_375
	v_mov_b64_e32 v[2:3], s[8:9]
	s_sleep 1
	global_load_dword v1, v[2:3], off sc1
	s_waitcnt vmcnt(0) lgkmcnt(0)
	v_cmp_lt_u32_e32 vcc, v1, v0
	s_and_saveexec_b64 s[68:69], vcc
	s_cbranch_execz .LBB0_374
	v_mov_b64_e32 v[2:3], s[8:9]
	s_sleep 1
	global_load_dword v1, v[2:3], off sc1
	s_waitcnt vmcnt(0) lgkmcnt(0)
	v_cmp_lt_u32_e32 vcc, v1, v0
	s_and_saveexec_b64 s[46:47], vcc
	s_cbranch_execz .LBB0_373
	v_mov_b64_e32 v[2:3], s[8:9]
	s_sleep 1
	global_load_dword v1, v[2:3], off sc1
	s_waitcnt vmcnt(0) lgkmcnt(0)
	v_cmp_lt_u32_e32 vcc, v1, v0
	s_and_saveexec_b64 s[94:95], vcc
	s_cbranch_execz .LBB0_372
	v_mov_b64_e32 v[2:3], s[8:9]
	s_sleep 1
	global_load_dword v1, v[2:3], off sc1
	s_waitcnt vmcnt(0) lgkmcnt(0)
	v_cmp_lt_u32_e32 vcc, v1, v0
	s_and_saveexec_b64 s[96:97], vcc
	s_cbranch_execz .LBB0_371
	v_mov_b64_e32 v[2:3], s[8:9]
	s_sleep 1
	global_load_dword v1, v[2:3], off sc1
	s_mov_b64 s[48:49], -1
	s_waitcnt vmcnt(0) lgkmcnt(0)
	v_cmp_lt_u32_e32 vcc, v1, v0
	s_and_saveexec_b64 s[18:19], vcc
	s_cbranch_execz .LBB0_370
	v_mov_b64_e32 v[2:3], s[8:9]
	s_sleep 1
	global_load_dword v1, v[2:3], off sc1
	s_waitcnt vmcnt(0) lgkmcnt(0)
	v_cmp_lt_u32_e32 vcc, v1, v0
	s_and_saveexec_b64 s[66:67], vcc
	s_cbranch_execz .LBB0_369
	s_add_i32 s0, s0, -8
	s_xor_b64 s[48:49], exec, -1
	s_sleep 1
	s_branch .LBB0_369

; #define WSB(off) ((bf16_t*)((unsigned char*)karg(15) + (off)))
; #define WSF(off) ((float*)((unsigned char*)karg(15) + (off)))
;   __device__ __forceinline__ bool next(int i, Unit& u) const {
;     ...
;       const int S = p0, nMh = S / 1024, nT = nMh * 8, per = 4 * nT, K2 = S / 4 + 128;
;       const int seq = L / per; int rem = L % per;
;       const int jb = rem / nT; rem %= nT;
;       const bool isq = jb >= 2; const int odd = jb & 1;
;       tile_order(rem, nMh, 8, pm, pn);
;       const size_t rowoff = (size_t)odd * (S == 16384 ? 1 : 2) * DLD * 2;
;       u.a0 = (isq ? A2 : A) + rowoff + (size_t)pm * a_t;
;       u.b0 = B + (isq ? (size_t)2304 * ZFLD * 2 : 0) + ((size_t)seq * 2 * K2 + (size_t)odd * K2) * 2 + (size_t)pn * b_t; u.b1 = u.b0 + b_h;
;       u.C = (isq ? C2 : C) + (size_t)seq * 4096 * 2048 * 4 + (size_t)odd * 2048 * 4;
;       u.r0 = pm * 256; u.c0 = pn * 256;
;     }
; __global__ void __launch_bounds__(512, 2) mega(Params p) {
;     ...
;         { const unsigned lda = (S == 16384) ? (unsigned)DLD * 4u : (unsigned)DLD * 8u; const int K2 = S / 4 + 128;
;           Map m = map_std(WSB(WS_DC), lda, 1, WSB(WS_ZF), (size_t)ZFLD * 2, 1, WSF(WS_P), 4096, nullptr); m.mode = 3; m.p0 = S; m.p1 = nseq; m.A2 = (const char*)WSB(WS_DS); m.C2 = (char*)WSF(WS_Q);
;           m.total = nseq * 4 * (S / 1024) * 8;
;           gemm_phase(lds, K2, lda, ZFLD * 2, m, EpiF32{}); }
.LBB0_391:
	s_or_b64 exec, exec, s[2:3]
	v_mov_b64_e32 v[0:1], s[10:11]
	s_waitcnt lgkmcnt(0)
	s_barrier
	global_load_dwordx2 v[2:3], v[0:1], off sc0 sc1
	s_waitcnt vmcnt(0)
	s_and_b64 s[2:3], s[92:93], exec
	s_mov_b32 s0, 0x8800
	s_cselect_b32 s28, s0, 0x4400
	s_lshr_b32 s0, s17, 10
	v_mov_b32_e32 v4, v252
	s_waitcnt lgkmcnt(0)
	v_readfirstlane_b32 s18, v3
	v_readfirstlane_b32 s19, v2
	global_load_dwordx2 v[2:3], v[0:1], off sc0 sc1
	s_waitcnt vmcnt(0) lgkmcnt(0)
	v_readfirstlane_b32 s7, v3
	v_readfirstlane_b32 s6, v2
	global_load_dwordx2 v[2:3], v[0:1], off sc0 sc1
	s_waitcnt vmcnt(0) lgkmcnt(0)
	v_readfirstlane_b32 s30, v2
	v_mov_b32_e32 v2, s74
	ds_read_b32 v2, v2
	v_readfirstlane_b32 s29, v3
	s_waitcnt lgkmcnt(0)
	v_readfirstlane_b32 s2, v2
	global_load_dwordx2 v[2:3], v[0:1], off sc0 sc1
	s_waitcnt vmcnt(0)
	s_xor_b32 s3, s88, 3
	global_load_dwordx2 v[0:1], v[0:1], off sc0 sc1
	s_waitcnt vmcnt(0)
	s_lshl_b32 s3, s0, s3
	s_lshl_b32 s4, s3, 3
	s_waitcnt lgkmcnt(0)
	s_barrier
	v_readfirstlane_b32 s31, v3
	v_readfirstlane_b32 s34, v2
	v_readfirstlane_b32 s35, v1
	v_readfirstlane_b32 s38, v0
	v_cmp_lt_i32_e32 vcc, 39, v4
	s_and_saveexec_b64 s[8:9], vcc
	s_xor_b64 s[8:9], exec, s[8:9]
	s_mov_b32 s5, s12
	s_ashr_i32 s3, s2, 31
	s_or_saveexec_b64 s[8:9], s[8:9]
	v_mov_b64_e32 v[0:1], s[2:3]
	v_mov_b64_e32 v[2:3], s[4:5]
	s_xor_b64 exec, exec, s[8:9]
	s_cbranch_execz .LBB0_397
	s_ashr_i32 s3, s2, 31
	v_mov_b64_e32 v[0:1], s[2:3]
	v_mad_i64_i32 v[0:1], s[36:37], v4, s20, v[0:1]
	s_mov_b32 s5, s12
	v_cmp_gt_i64_e32 vcc, s[4:5], v[0:1]
	s_and_saveexec_b64 s[36:37], vcc
	s_cbranch_execz .LBB0_396
	s_add_u32 s19, s19, 0x44480000
	s_addc_u32 s18, s18, 0
	s_add_u32 s22, s30, 0x2d1c0000
	s_addc_u32 s29, s29, 0
	s_add_u32 s30, s34, 0x48880000
	s_addc_u32 s31, s31, 0
	s_add_u32 s34, s38, 0x311c0000
	s_addc_u32 s35, s35, 0
	s_lshr_b32 s38, s17, 5
	v_cvt_f32_u32_e32 v1, s38
	s_sub_i32 s41, 0, s38
	v_sub_u32_e32 v3, 0, v0
	v_max_i32_e32 v3, v0, v3
	v_rcp_iflag_f32_e32 v1, v1
	v_ashrrev_i32_e32 v2, 31, v0
	s_lshr_b32 s39, s17, 7
	v_mov_b32_e32 v11, s35
	v_mul_f32_e32 v1, 0x4f7ffffe, v1
	v_cvt_u32_f32_e32 v1, v1
	v_mov_b32_e32 v13, s34
	v_mul_lo_u32 v5, s41, v1
	v_mul_hi_u32 v5, v1, v5
	v_add_u32_e32 v1, v1, v5
	v_mul_hi_u32 v1, v3, v1
	v_mul_lo_u32 v5, v1, s38
	v_sub_u32_e32 v3, v3, v5
	v_add_u32_e32 v6, 1, v1
	v_cmp_le_u32_e32 vcc, s38, v3
	v_subrev_u32_e32 v5, s38, v3
	s_nop 0
	v_cndmask_b32_e32 v1, v1, v6, vcc
	v_cndmask_b32_e32 v3, v3, v5, vcc
	v_add_u32_e32 v5, 1, v1
	v_cmp_le_u32_e32 vcc, s38, v3
	s_nop 1
	v_cndmask_b32_e32 v1, v1, v5, vcc
	v_xor_b32_e32 v1, v1, v2
	v_sub_u32_e32 v8, v1, v2
	v_mul_lo_u32 v1, v8, s38
	v_sub_u32_e32 v0, v0, v1
	v_cvt_f32_ubyte0_e32 v2, s39
	v_cvt_f32_i32_sdwa v1, sext(v0) dst_sel:DWORD dst_unused:UNUSED_PAD src0_sel:WORD_0
	v_rcp_iflag_f32_e32 v3, v2
	v_ashrrev_i32_sdwa v5, v223, sext(v0) dst_sel:DWORD dst_unused:UNUSED_PAD src0_sel:DWORD src1_sel:WORD_0
	v_or_b32_e32 v5, 1, v5
	s_or_b32 s38, s40, 0x100
	v_mul_f32_e32 v3, v1, v3
	v_trunc_f32_e32 v3, v3
	v_cvt_i32_f32_e32 v6, v3
	v_fma_f32 v1, -v3, v2, v1
	v_cmp_ge_f32_e64 vcc, |v1|, v2
	s_nop 1
	v_cndmask_b32_e32 v1, 0, v5, vcc
	v_add_u32_e32 v2, v6, v1
	v_mul_lo_u32 v1, v2, s39
	v_sub_u32_e32 v0, v0, v1
	v_mov_b32_e32 v1, 12
	v_lshrrev_b16_sdwa v1, v1, sext(v0) dst_sel:DWORD dst_unused:UNUSED_PAD src0_sel:DWORD src1_sel:BYTE_0
	v_and_b32_e32 v1, 7, v1
	v_add_u16_e32 v1, v0, v1
	v_and_b32_e32 v3, 0xf8, v1
	v_sub_u16_e32 v0, v0, v3
	v_bfe_i32 v0, v0, 0, 8
	v_lshrrev_b32_e32 v3, 31, v0
	v_mov_b32_e32 v5, 3
	v_or_b32_e32 v3, s0, v3
	v_ashrrev_i16_sdwa v1, v5, sext(v1) dst_sel:DWORD dst_unused:UNUSED_PAD src0_sel:DWORD src1_sel:BYTE_0
	v_mad_i32_i24 v0, v3, v0, v1
	v_ashrrev_i16_e32 v1, 15, v0
	v_lshrrev_b16_e32 v1, 11, v1
	v_add_u16_e32 v1, v0, v1
	v_ashrrev_i16_e32 v3, 5, v1
	v_mov_b32_e32 v5, 2
	v_lshlrev_b32_sdwa v3, v5, sext(v3) dst_sel:DWORD dst_unused:UNUSED_PAD src0_sel:DWORD src1_sel:WORD_0
	v_sub_u32_e32 v5, s0, v3
	v_min_i32_e32 v5, 4, v5
	v_cvt_f32_i32_sdwa v6, sext(v5) dst_sel:DWORD dst_unused:UNUSED_PAD src0_sel:BYTE_0
	v_and_b32_e32 v1, 0xffffffe0, v1
	v_sub_u16_e32 v0, v0, v1
	v_cvt_f32_i32_sdwa v1, sext(v0) dst_sel:DWORD dst_unused:UNUSED_PAD src0_sel:WORD_0
	v_rcp_iflag_f32_e32 v7, v6
	v_xor_b32_sdwa v9, sext(v0), sext(v5) dst_sel:DWORD dst_unused:UNUSED_PAD src0_sel:WORD_0 src1_sel:BYTE_0
	v_ashrrev_i32_e32 v9, 30, v9
	v_or_b32_e32 v9, 1, v9
	v_mul_f32_e32 v7, v1, v7
	v_trunc_f32_e32 v7, v7
	v_cvt_i32_f32_e32 v10, v7
	v_fma_f32 v1, -v7, v6, v1
	v_cmp_ge_f32_e64 vcc, |v1|, |v6|
	v_and_b32_e32 v80, 1, v2
	v_mov_b32_e32 v6, s31
	v_cndmask_b32_e32 v1, 0, v9, vcc
	v_add_u32_e32 v12, v10, v1
	v_mul_lo_u32 v1, v12, v5
	v_sub_u32_sdwa v0, sext(v0), v1 dst_sel:DWORD dst_unused:UNUSED_PAD src0_sel:WORD_0 src1_sel:DWORD
	v_add_u32_sdwa v5, v3, sext(v0) dst_sel:DWORD dst_unused:UNUSED_PAD src0_sel:DWORD src1_sel:BYTE_0
	v_lshlrev_b64 v[0:1], s1, v[80:81]
	v_cmp_lt_i16_e32 vcc, 1, v2
	v_mov_b32_e32 v1, 0x2640000
	v_mov_b32_e32 v3, v81
	v_cndmask_b32_e32 v2, 0, v1, vcc
	v_mov_b32_e32 v1, s18
	v_cndmask_b32_e32 v7, v1, v6, vcc
	v_mov_b32_e32 v1, s19
	v_mov_b32_e32 v6, s30
	v_cndmask_b32_e32 v6, v1, v6, vcc
	s_movk_i32 s0, 0x2200
	v_lshl_add_u64 v[2:3], s[6:7], 0, v[2:3]
	s_mov_b64 s[6:7], 0x20980000
	v_mad_u64_u32 v[0:1], s[18:19], v0, s0, v[6:7]
	s_lshl_b32 s0, s28, 8
	v_lshl_add_u64 v[2:3], v[2:3], 0, s[6:7]
	v_lshl_or_b32 v6, v8, 1, v80
	v_mov_b32_e32 v10, s29
	v_mad_i64_i32 v[0:1], s[18:19], s0, v5, v[0:1]
	v_ashrrev_i32_e32 v9, 31, v8
	v_mad_u64_u32 v[2:3], s[6:7], v6, s38, v[2:3]
	s_mov_b32 s0, 0x440000
	v_cndmask_b32_e32 v11, v10, v11, vcc
	v_mov_b32_e32 v10, s22
	v_mad_i32_i24 v3, v9, s38, v3
	v_mul_hi_i32_i24_sdwa v7, sext(v12), s0 dst_sel:DWORD dst_unused:UNUSED_PAD src0_sel:BYTE_0 src1_sel:DWORD
	v_mul_i32_i24_sdwa v6, sext(v12), s0 dst_sel:DWORD dst_unused:UNUSED_PAD src0_sel:BYTE_0 src1_sel:DWORD
	v_cndmask_b32_e32 v10, v10, v13, vcc
	v_lshlrev_b64 v[8:9], 25, v[8:9]
	v_lshl_add_u64 v[2:3], v[2:3], 0, v[6:7]
	s_mov_b64 s[6:7], 0x220000
	v_lshl_add_u64 v[8:9], v[10:11], 0, v[8:9]
	v_lshlrev_b32_e32 v10, 8, v5
	v_mov_b32_e32 v5, 8
	v_lshl_add_u64 v[6:7], v[2:3], 0, s[6:7]
	v_lshlrev_b32_sdwa v11, v5, sext(v12) dst_sel:DWORD dst_unused:UNUSED_PAD src0_sel:DWORD src1_sel:BYTE_0
	v_mad_u64_u32 v[4:5], s[6:7], v4, 48, v[232:233]
	v_lshlrev_b32_e32 v80, 13, v80
	v_add_u32_e32 v4, 0x20000, v4
	v_lshl_add_u64 v[8:9], v[8:9], 0, v[80:81]
	ds_write_b128 v4, v[0:3]
	ds_write_b128 v4, v[6:9] offset:16
	ds_write_b64 v4, v[10:11] offset:32

; #define G_STAGE(bufoff, gbase, voff) do { _Pragma("unroll") for (int _i = 0; _i < 2; ++_i) { unsigned _vo = (voff)[_i]; asm volatile("" : "+v"(_vo));   \
;     __builtin_amdgcn_global_load_lds((const unsigned*)((const char*)(gbase) + _vo), (LAS unsigned*)(lds + (bufoff) + ldsw + _i * 8192), 16, 0, 0); } } while (0)
; #define G_LDA(dst, b, h) do { _Pragma("unroll") for (int m = 0; m < 4; ++m) _Pragma("unroll") for (int k = 0; k < 2; ++k) dst[m][k] = *(const LAS bf16x8*)(lds + G_SA(b, h) + aoff + m * 2048 + k * 1024); } while (0)
; #define G_LDB(dst, b, h) do { _Pragma("unroll") for (int n = 0; n < 2; ++n) _Pragma("unroll") for (int k = 0; k < 2; ++k) dst[n][k] = *(const LAS bf16x8*)(lds + G_SB(b, h) + boff + n * 2048 + k * 1024); } while (0)
; template <class Epi>
; __device__ __forceinline__ void gemm_phase(LAS unsigned char* lds, const int K, const unsigned lda_b, const unsigned ldb_b, const Map& M, const Epi& E) {
;     ...
;     for (int t = 0; t < nt; t += 2) {
;       const bool last = (t == nt - 2);
;       const char* a1h1 = cur.a0 + a_h + (size_t)(t + 1) * kstep;
;       const char* a2h0 = last ? nxt.a0 : cur.a0 + (size_t)(t + 2) * kstep; const char* a2h1 = a2h0 + a_h;
;       const char* b2h0 = last ? nxt.b0 : cur.b0 + (size_t)(t + 2) * kstep; const char* b2h1 = last ? nxt.b1 : cur.b1 + (size_t)(t + 2) * kstep;
;       G_LDB(B0, 0, 0); G_SCHED; G_LDA(At, 0, 0); G_STAGE(G_SA(1, 1), a1h1, voffA);
;       G_WAIT_L(8); G_BAR; G_WAIT_L(0); G_MMA(0, 0, At, B0); G_BAR; G_SCHED;
;       G_LDB(B1, 0, 1); G_STAGE(G_SB(0, 0), b2h0, voffB);
;       G_BAR; G_WAIT_L(0); G_MMA(0, 1, At, B1); G_BAR;
;       G_LDA(At, 0, 1); G_STAGE(G_SA(0, 0), a2h0, voffA);
;       G_BAR; G_WAIT_L(0); G_MMA(1, 0, At, B0); G_BAR; G_SCHED;
;       G_STAGE(G_SB(0, 1), b2h1, voffB);
;       G_WAIT_V(6); G_BAR; G_MMA(1, 1, At, B1); G_BAR;
;       G_LDB(B0, 1, 0); G_SCHED; G_LDA(At, 1, 0); G_STAGE(G_SA(0, 1), a2h1, voffA);
;       G_WAIT_L(8); G_BAR; G_WAIT_L(0); G_MMA(0, 0, At, B0); G_BAR; G_SCHED;
;       G_LDB(B1, 1, 1); G_STAGE(G_SB(1, 0), b2h0 + kstep, voffB);
;       G_BAR; G_WAIT_L(0); G_MMA(0, 1, At, B1); G_BAR;
;       G_LDA(At, 1, 1); G_STAGE(G_SA(1, 0), a2h0 + kstep, voffA);
;       G_BAR; G_WAIT_L(0); G_MMA(1, 0, At, B0); G_BAR; G_SCHED;
;       G_STAGE(G_SB(1, 1), b2h1 + kstep, voffB);
;       G_WAIT_V(6); G_BAR; G_MMA(1, 1, At, B1); G_BAR;
.LBB0_408:
	s_add_i32 s30, s29, 2
	s_add_u32 s42, s38, 0x100
	s_addc_u32 s43, s39, 0
	s_add_i32 s22, 0, 0x10000
	v_add_u32_e32 v80, s22, v133
	ds_read_b128 v[146:149], v80
	ds_read_b128 v[150:153], v80 offset:1024
	ds_read_b128 v[154:157], v80 offset:2048
	ds_read_b128 v[164:167], v80 offset:3072
	s_cmp_eq_u32 s76, s29
	s_cselect_b32 s69, s5, s43
	s_cselect_b32 s68, s4, s42
	s_cselect_b32 s95, s7, s28
	s_cselect_b32 s94, s6, vcc_hi
	s_cselect_b32 s44, s8, s87
	s_cselect_b32 s45, s9, vcc_lo
	s_add_u32 s96, s68, s18
	s_addc_u32 s97, s69, 0
	v_mov_b32_e32 v80, v130
	s_add_u32 s34, s38, s82
	ds_read_b128 v[168:171], v144
	ds_read_b128 v[172:175], v144 offset:1024
	ds_read_b128 v[176:179], v144 offset:2048
	ds_read_b128 v[184:187], v144 offset:3072
	ds_read_b128 v[190:193], v144 offset:4096
	ds_read_b128 v[194:197], v144 offset:5120
	ds_read_b128 v[198:201], v144 offset:6144
	ds_read_b128 v[202:205], v144 offset:7168
	s_addc_u32 s35, s39, s83
	s_add_i32 m0, s46, 0xc000
	s_nop 0
	global_load_lds_dwordx4 v80, s[34:35]
	v_mov_b32_e32 v80, v134
	s_add_i32 m0, s46, 0xe000
	s_nop 0
	global_load_lds_dwordx4 v80, s[34:35]
	s_waitcnt lgkmcnt(8)
	s_barrier
	s_waitcnt lgkmcnt(0)
	s_setprio 1
	s_waitcnt lgkmcnt(0)
	v_mfma_f32_16x16x32_bf16 v[126:129], v[146:149], v[168:171], v[126:129]
	v_mfma_f32_16x16x32_bf16 v[122:125], v[154:157], v[168:171], v[122:125]
	v_mfma_f32_16x16x32_bf16 v[118:121], v[146:149], v[176:179], v[118:121]
	v_mfma_f32_16x16x32_bf16 v[114:117], v[154:157], v[176:179], v[114:117]
	v_mfma_f32_16x16x32_bf16 v[102:105], v[146:149], v[190:193], v[102:105]
	v_mfma_f32_16x16x32_bf16 v[98:101], v[154:157], v[190:193], v[98:101]
	v_mfma_f32_16x16x32_bf16 v[86:89], v[146:149], v[198:201], v[86:89]
	v_mfma_f32_16x16x32_bf16 v[82:85], v[154:157], v[198:201], v[82:85]
	v_mfma_f32_16x16x32_bf16 v[126:129], v[150:153], v[172:175], v[126:129]
	v_mfma_f32_16x16x32_bf16 v[122:125], v[164:167], v[172:175], v[122:125]
	v_mfma_f32_16x16x32_bf16 v[118:121], v[150:153], v[184:187], v[118:121]
	v_mfma_f32_16x16x32_bf16 v[114:117], v[164:167], v[184:187], v[114:117]
	v_mfma_f32_16x16x32_bf16 v[102:105], v[150:153], v[194:197], v[102:105]
	v_mfma_f32_16x16x32_bf16 v[98:101], v[164:167], v[194:197], v[98:101]
	v_mfma_f32_16x16x32_bf16 v[86:89], v[150:153], v[202:205], v[86:89]
	v_mfma_f32_16x16x32_bf16 v[82:85], v[164:167], v[202:205], v[82:85]
	s_setprio 0
	s_barrier
	s_add_i32 s31, 0, 0x14000
	v_add_u32_e32 v80, s31, v133
	ds_read_b128 v[206:209], v80
	ds_read_b128 v[210:213], v80 offset:1024
	ds_read_b128 v[214:217], v80 offset:2048
	ds_read_b128 v[218:221], v80 offset:3072
	v_mov_b32_e32 v80, v132
	s_add_i32 s22, s22, s41
	s_mov_b32 m0, s22
	s_nop 0
	global_load_lds_dwordx4 v80, s[94:95]
	v_mov_b32_e32 v80, v136
	s_add_i32 m0, s22, 0x2000
	s_nop 0
	global_load_lds_dwordx4 v80, s[94:95]
	s_barrier
	s_waitcnt lgkmcnt(0)
	s_setprio 1
	s_waitcnt lgkmcnt(0)
	v_mfma_f32_16x16x32_bf16 v[110:113], v[206:209], v[168:171], v[110:113]
	v_mfma_f32_16x16x32_bf16 v[106:109], v[214:217], v[168:171], v[106:109]
	v_mfma_f32_16x16x32_bf16 v[94:97], v[206:209], v[176:179], v[94:97]
	v_mfma_f32_16x16x32_bf16 v[90:93], v[214:217], v[176:179], v[90:93]
	v_mfma_f32_16x16x32_bf16 v[76:79], v[206:209], v[190:193], v[76:79]
	v_mfma_f32_16x16x32_bf16 v[72:75], v[214:217], v[190:193], v[72:75]
	v_mfma_f32_16x16x32_bf16 v[68:71], v[206:209], v[198:201], v[68:71]
	v_mfma_f32_16x16x32_bf16 v[64:67], v[214:217], v[198:201], v[64:67]
	v_mfma_f32_16x16x32_bf16 v[110:113], v[210:213], v[172:175], v[110:113]
	v_mfma_f32_16x16x32_bf16 v[106:109], v[218:221], v[172:175], v[106:109]
	v_mfma_f32_16x16x32_bf16 v[94:97], v[210:213], v[184:187], v[94:97]
	v_mfma_f32_16x16x32_bf16 v[90:93], v[218:221], v[184:187], v[90:93]
	v_mfma_f32_16x16x32_bf16 v[76:79], v[210:213], v[194:197], v[76:79]
	v_mfma_f32_16x16x32_bf16 v[72:75], v[218:221], v[194:197], v[72:75]
	v_mfma_f32_16x16x32_bf16 v[68:71], v[210:213], v[202:205], v[68:71]
	v_mfma_f32_16x16x32_bf16 v[64:67], v[218:221], v[202:205], v[64:67]
	s_setprio 0
	v_mov_b32_e32 v80, v130
	s_mov_b32 m0, s46
	s_barrier
	ds_read_b128 v[168:171], v144 offset:16384
	ds_read_b128 v[172:175], v144 offset:17408
	ds_read_b128 v[176:179], v144 offset:18432
	ds_read_b128 v[184:187], v144 offset:19456
	ds_read_b128 v[190:193], v144 offset:20480
	ds_read_b128 v[194:197], v144 offset:21504
	ds_read_b128 v[198:201], v144 offset:22528
	ds_read_b128 v[202:205], v144 offset:23552
	s_nop 0
	global_load_lds_dwordx4 v80, s[68:69]
	v_mov_b32_e32 v80, v134
	s_mov_b32 m0, s47
	s_nop 0
	global_load_lds_dwordx4 v80, s[68:69]
	s_barrier
	s_waitcnt lgkmcnt(0)
	s_setprio 1
	s_waitcnt lgkmcnt(0)
	v_mfma_f32_16x16x32_bf16 v[60:63], v[146:149], v[168:171], v[60:63]
	v_mfma_f32_16x16x32_bf16 v[56:59], v[154:157], v[168:171], v[56:59]
	v_mfma_f32_16x16x32_bf16 v[52:55], v[146:149], v[176:179], v[52:55]
	v_mfma_f32_16x16x32_bf16 v[48:51], v[154:157], v[176:179], v[48:51]
	v_mfma_f32_16x16x32_bf16 v[36:39], v[146:149], v[190:193], v[36:39]
	v_mfma_f32_16x16x32_bf16 v[32:35], v[154:157], v[190:193], v[32:35]
	v_mfma_f32_16x16x32_bf16 v[20:23], v[146:149], v[198:201], v[20:23]
	v_mfma_f32_16x16x32_bf16 v[16:19], v[154:157], v[198:201], v[16:19]
	v_mfma_f32_16x16x32_bf16 v[60:63], v[150:153], v[172:175], v[60:63]
	v_mfma_f32_16x16x32_bf16 v[56:59], v[164:167], v[172:175], v[56:59]
	v_mfma_f32_16x16x32_bf16 v[52:55], v[150:153], v[184:187], v[52:55]
	v_mfma_f32_16x16x32_bf16 v[48:51], v[164:167], v[184:187], v[48:51]
	v_mfma_f32_16x16x32_bf16 v[36:39], v[150:153], v[194:197], v[36:39]
	v_mfma_f32_16x16x32_bf16 v[32:35], v[164:167], v[194:197], v[32:35]
	v_mfma_f32_16x16x32_bf16 v[20:23], v[150:153], v[202:205], v[20:23]
	v_mfma_f32_16x16x32_bf16 v[16:19], v[164:167], v[202:205], v[16:19]
	s_setprio 0
	s_barrier
; #define G_STAGE(bufoff, gbase, voff) do { _Pragma("unroll") for (int _i = 0; _i < 2; ++_i) { unsigned _vo = (voff)[_i]; asm volatile("" : "+v"(_vo));   \
;     __builtin_amdgcn_global_load_lds((const unsigned*)((const char*)(gbase) + _vo), (LAS unsigned*)(lds + (bufoff) + ldsw + _i * 8192), 16, 0, 0); } } while (0)
; #define G_LDA(dst, b, h) do { _Pragma("unroll") for (int m = 0; m < 4; ++m) _Pragma("unroll") for (int k = 0; k < 2; ++k) dst[m][k] = *(const LAS bf16x8*)(lds + G_SA(b, h) + aoff + m * 2048 + k * 1024); } while (0)
; #define G_LDB(dst, b, h) do { _Pragma("unroll") for (int n = 0; n < 2; ++n) _Pragma("unroll") for (int k = 0; k < 2; ++k) dst[n][k] = *(const LAS bf16x8*)(lds + G_SB(b, h) + boff + n * 2048 + k * 1024); } while (0)
; #define G_MMA(ai, bj, At, Bt) do { __builtin_amdgcn_s_setprio(1); _Pragma("unroll") for (int m = 0; m < 4; ++m) _Pragma("unroll") for (int n = 0; n < 2; ++n) _Pragma("unroll") for (int k = 0; k < 2; ++k) \
;     acc[ai][bj][m][n] = __builtin_amdgcn_mfma_f32_16x16x32_bf16(Bt[n][k], At[m][k], acc[ai][bj][m][n], 0, 0, 0); __builtin_amdgcn_s_setprio(0); } while (0)
; #define G_WAIT_V(n) asm volatile("s_waitcnt vmcnt(" #n ")" ::: "memory")
; template <class Epi>
; __device__ __forceinline__ void gemm_phase(LAS unsigned char* lds, const int K, const unsigned lda_b, const unsigned ldb_b, const Map& M, const Epi& E) {
;     ...
;       G_LDB(B0, 0, 0); G_SCHED; G_LDA(At, 0, 0); G_STAGE(G_SA(1, 1), a1h1, voffA);
;       G_WAIT_L(8); G_BAR; G_WAIT_L(0); G_MMA(0, 0, At, B0); G_BAR; G_SCHED;
;       G_LDB(B1, 0, 1); G_STAGE(G_SB(0, 0), b2h0, voffB);
;       G_BAR; G_WAIT_L(0); G_MMA(0, 1, At, B1); G_BAR;
;       G_LDA(At, 0, 1); G_STAGE(G_SA(0, 0), a2h0, voffA);
;       G_BAR; G_WAIT_L(0); G_MMA(1, 0, At, B0); G_BAR; G_SCHED;
;       G_STAGE(G_SB(0, 1), b2h1, voffB);
;       G_WAIT_V(6); G_BAR; G_MMA(1, 1, At, B1); G_BAR;
;       G_LDB(B0, 1, 0); G_SCHED; G_LDA(At, 1, 0); G_STAGE(G_SA(0, 1), a2h1, voffA);
;       G_WAIT_L(8); G_BAR; G_WAIT_L(0); G_MMA(0, 0, At, B0); G_BAR; G_SCHED;
;       G_LDB(B1, 1, 1); G_STAGE(G_SB(1, 0), b2h0 + kstep, voffB);
;       G_BAR; G_WAIT_L(0); G_MMA(0, 1, At, B1); G_BAR;
;       G_LDA(At, 1, 1); G_STAGE(G_SA(1, 0), a2h0 + kstep, voffA);
;       G_BAR; G_WAIT_L(0); G_MMA(1, 0, At, B0); G_BAR; G_SCHED;
;       G_STAGE(G_SB(1, 1), b2h1 + kstep, voffB);
;       G_WAIT_V(6); G_BAR; G_MMA(1, 1, At, B1); G_BAR;
	v_mov_b32_e32 v80, v132
	s_add_i32 s22, s31, s41
	s_mov_b32 m0, s22
	s_nop 0
	global_load_lds_dwordx4 v80, s[44:45]
	v_mov_b32_e32 v80, v136
	s_add_i32 m0, s22, 0x2000
	s_nop 0
	global_load_lds_dwordx4 v80, s[44:45]
	s_waitcnt vmcnt(6)
	s_barrier
	s_setprio 1
	v_mfma_f32_16x16x32_bf16 v[44:47], v[206:209], v[168:171], v[44:47]
	v_mfma_f32_16x16x32_bf16 v[40:43], v[214:217], v[168:171], v[40:43]
	v_mfma_f32_16x16x32_bf16 v[28:31], v[206:209], v[176:179], v[28:31]
	v_mfma_f32_16x16x32_bf16 v[24:27], v[214:217], v[176:179], v[24:27]
	v_mfma_f32_16x16x32_bf16 v[12:15], v[206:209], v[190:193], v[12:15]
	v_mfma_f32_16x16x32_bf16 v[8:11], v[214:217], v[190:193], v[8:11]
	v_mfma_f32_16x16x32_bf16 v[4:7], v[206:209], v[198:201], v[4:7]
	v_mfma_f32_16x16x32_bf16 v[0:3], v[214:217], v[198:201], v[0:3]
	v_mfma_f32_16x16x32_bf16 v[44:47], v[210:213], v[172:175], v[44:47]
	v_mfma_f32_16x16x32_bf16 v[40:43], v[218:221], v[172:175], v[40:43]
	v_mfma_f32_16x16x32_bf16 v[28:31], v[210:213], v[184:187], v[28:31]
	v_mfma_f32_16x16x32_bf16 v[24:27], v[218:221], v[184:187], v[24:27]
	v_mfma_f32_16x16x32_bf16 v[12:15], v[210:213], v[194:197], v[12:15]
	v_mfma_f32_16x16x32_bf16 v[8:11], v[218:221], v[194:197], v[8:11]
	v_mfma_f32_16x16x32_bf16 v[4:7], v[210:213], v[202:205], v[4:7]
	v_mfma_f32_16x16x32_bf16 v[0:3], v[218:221], v[202:205], v[0:3]
	s_setprio 0
	s_add_i32 s22, 0, 0x18000
	v_add_u32_e32 v80, s22, v133
	s_barrier
	ds_read_b128 v[146:149], v80
	ds_read_b128 v[150:153], v80 offset:1024
	ds_read_b128 v[154:157], v80 offset:2048
	ds_read_b128 v[164:167], v80 offset:3072
	v_mov_b32_e32 v80, v130
	s_mov_b32 m0, s48
	ds_read_b128 v[168:171], v144 offset:32768
	ds_read_b128 v[172:175], v144 offset:33792
	ds_read_b128 v[176:179], v144 offset:34816
	ds_read_b128 v[184:187], v144 offset:35840
	ds_read_b128 v[190:193], v144 offset:36864
	ds_read_b128 v[194:197], v144 offset:37888
	ds_read_b128 v[198:201], v144 offset:38912
	ds_read_b128 v[202:205], v144 offset:39936
	s_nop 0
	global_load_lds_dwordx4 v80, s[96:97]
	v_mov_b32_e32 v80, v134
	s_mov_b32 m0, s49
	s_nop 0
	global_load_lds_dwordx4 v80, s[96:97]
	s_waitcnt lgkmcnt(8)
	s_barrier
	s_waitcnt lgkmcnt(0)
	s_setprio 1
	s_waitcnt lgkmcnt(0)
	v_mfma_f32_16x16x32_bf16 v[126:129], v[146:149], v[168:171], v[126:129]
	v_mfma_f32_16x16x32_bf16 v[122:125], v[154:157], v[168:171], v[122:125]
	v_mfma_f32_16x16x32_bf16 v[118:121], v[146:149], v[176:179], v[118:121]
	v_mfma_f32_16x16x32_bf16 v[114:117], v[154:157], v[176:179], v[114:117]
	v_mfma_f32_16x16x32_bf16 v[102:105], v[146:149], v[190:193], v[102:105]
	v_mfma_f32_16x16x32_bf16 v[98:101], v[154:157], v[190:193], v[98:101]
	v_mfma_f32_16x16x32_bf16 v[86:89], v[146:149], v[198:201], v[86:89]
	v_mfma_f32_16x16x32_bf16 v[82:85], v[154:157], v[198:201], v[82:85]
	v_mfma_f32_16x16x32_bf16 v[126:129], v[150:153], v[172:175], v[126:129]
	v_mfma_f32_16x16x32_bf16 v[122:125], v[164:167], v[172:175], v[122:125]
	v_mfma_f32_16x16x32_bf16 v[118:121], v[150:153], v[184:187], v[118:121]
	v_mfma_f32_16x16x32_bf16 v[114:117], v[164:167], v[184:187], v[114:117]
	v_mfma_f32_16x16x32_bf16 v[102:105], v[150:153], v[194:197], v[102:105]
	v_mfma_f32_16x16x32_bf16 v[98:101], v[164:167], v[194:197], v[98:101]
	v_mfma_f32_16x16x32_bf16 v[86:89], v[150:153], v[202:205], v[86:89]
	v_mfma_f32_16x16x32_bf16 v[82:85], v[164:167], v[202:205], v[82:85]
	s_setprio 0
	s_barrier
	s_add_i32 s31, 0, 0x1c000
	v_add_u32_e32 v80, s31, v133
	ds_read_b128 v[206:209], v80
	ds_read_b128 v[210:213], v80 offset:1024
	ds_read_b128 v[214:217], v80 offset:2048
	ds_read_b128 v[218:221], v80 offset:3072
	v_mov_b32_e32 v80, v132
	s_add_i32 s22, s22, s41
	v_lshl_add_u64 v[160:161], s[94:95], 0, v[80:81]
	v_lshl_add_u64 v[160:161], v[160:161], 0, s[52:53]
	s_mov_b32 m0, s22
	v_mov_b32_e32 v80, v136
	global_load_lds_dwordx4 v[160:161], off
	s_add_i32 m0, s22, 0x2000
	v_lshl_add_u64 v[160:161], s[94:95], 0, v[80:81]
	v_lshl_add_u64 v[160:161], v[160:161], 0, s[52:53]
	global_load_lds_dwordx4 v[160:161], off
	s_barrier
	s_waitcnt lgkmcnt(0)
	s_setprio 1
	s_waitcnt lgkmcnt(0)
	v_mfma_f32_16x16x32_bf16 v[110:113], v[206:209], v[168:171], v[110:113]
	v_mfma_f32_16x16x32_bf16 v[106:109], v[214:217], v[168:171], v[106:109]
	v_mfma_f32_16x16x32_bf16 v[94:97], v[206:209], v[176:179], v[94:97]
	v_mfma_f32_16x16x32_bf16 v[90:93], v[214:217], v[176:179], v[90:93]
	v_mfma_f32_16x16x32_bf16 v[76:79], v[206:209], v[190:193], v[76:79]
	v_mfma_f32_16x16x32_bf16 v[72:75], v[214:217], v[190:193], v[72:75]
	v_mfma_f32_16x16x32_bf16 v[68:71], v[206:209], v[198:201], v[68:71]
	v_mfma_f32_16x16x32_bf16 v[64:67], v[214:217], v[198:201], v[64:67]
	v_mfma_f32_16x16x32_bf16 v[110:113], v[210:213], v[172:175], v[110:113]
	v_mfma_f32_16x16x32_bf16 v[106:109], v[218:221], v[172:175], v[106:109]
	v_mfma_f32_16x16x32_bf16 v[94:97], v[210:213], v[184:187], v[94:97]
	v_mfma_f32_16x16x32_bf16 v[90:93], v[218:221], v[184:187], v[90:93]
	v_mfma_f32_16x16x32_bf16 v[76:79], v[210:213], v[194:197], v[76:79]
	v_mfma_f32_16x16x32_bf16 v[72:75], v[218:221], v[194:197], v[72:75]
	v_mfma_f32_16x16x32_bf16 v[68:71], v[210:213], v[202:205], v[68:71]
	v_mfma_f32_16x16x32_bf16 v[64:67], v[218:221], v[202:205], v[64:67]
	s_setprio 0
	v_mov_b32_e32 v80, v130
	s_barrier
	ds_read_b128 v[168:171], v144 offset:49152
	ds_read_b128 v[172:175], v144 offset:50176
	ds_read_b128 v[176:179], v144 offset:51200
	ds_read_b128 v[184:187], v144 offset:52224
	ds_read_b128 v[190:193], v144 offset:53248
	ds_read_b128 v[194:197], v144 offset:54272
	ds_read_b128 v[198:201], v144 offset:55296
	ds_read_b128 v[202:205], v144 offset:56320
	s_mov_b32 m0, s66
	v_lshl_add_u64 v[160:161], s[68:69], 0, v[80:81]
	v_lshl_add_u64 v[160:161], v[160:161], 0, s[52:53]
	v_mov_b32_e32 v80, v134
	global_load_lds_dwordx4 v[160:161], off
	s_mov_b32 m0, s75
	v_lshl_add_u64 v[160:161], s[68:69], 0, v[80:81]
	v_lshl_add_u64 v[160:161], v[160:161], 0, s[52:53]
	global_load_lds_dwordx4 v[160:161], off
	s_barrier
; #define G_STAGE(bufoff, gbase, voff) do { _Pragma("unroll") for (int _i = 0; _i < 2; ++_i) { unsigned _vo = (voff)[_i]; asm volatile("" : "+v"(_vo));   \
;     __builtin_amdgcn_global_load_lds((const unsigned*)((const char*)(gbase) + _vo), (LAS unsigned*)(lds + (bufoff) + ldsw + _i * 8192), 16, 0, 0); } } while (0)
; #define G_LDA(dst, b, h) do { _Pragma("unroll") for (int m = 0; m < 4; ++m) _Pragma("unroll") for (int k = 0; k < 2; ++k) dst[m][k] = *(const LAS bf16x8*)(lds + G_SA(b, h) + aoff + m * 2048 + k * 1024); } while (0)
; #define G_LDB(dst, b, h) do { _Pragma("unroll") for (int n = 0; n < 2; ++n) _Pragma("unroll") for (int k = 0; k < 2; ++k) dst[n][k] = *(const LAS bf16x8*)(lds + G_SB(b, h) + boff + n * 2048 + k * 1024); } while (0)
; #define G_MMA(ai, bj, At, Bt) do { __builtin_amdgcn_s_setprio(1); _Pragma("unroll") for (int m = 0; m < 4; ++m) _Pragma("unroll") for (int n = 0; n < 2; ++n) _Pragma("unroll") for (int k = 0; k < 2; ++k) \
;     acc[ai][bj][m][n] = __builtin_amdgcn_mfma_f32_16x16x32_bf16(Bt[n][k], At[m][k], acc[ai][bj][m][n], 0, 0, 0); __builtin_amdgcn_s_setprio(0); } while (0)
; #define G_WAIT_V(n) asm volatile("s_waitcnt vmcnt(" #n ")" ::: "memory")
; template <class Epi>
; __device__ __forceinline__ void gemm_phase(LAS unsigned char* lds, const int K, const unsigned lda_b, const unsigned ldb_b, const Map& M, const Epi& E) {
;     ...
;       G_LDB(B0, 0, 0); G_SCHED; G_LDA(At, 0, 0); G_STAGE(G_SA(1, 1), a1h1, voffA);
;       G_WAIT_L(8); G_BAR; G_WAIT_L(0); G_MMA(0, 0, At, B0); G_BAR; G_SCHED;
;       G_LDB(B1, 0, 1); G_STAGE(G_SB(0, 0), b2h0, voffB);
;       G_BAR; G_WAIT_L(0); G_MMA(0, 1, At, B1); G_BAR;
;       G_LDA(At, 0, 1); G_STAGE(G_SA(0, 0), a2h0, voffA);
;       G_BAR; G_WAIT_L(0); G_MMA(1, 0, At, B0); G_BAR; G_SCHED;
;       G_STAGE(G_SB(0, 1), b2h1, voffB);
;       G_WAIT_V(6); G_BAR; G_MMA(1, 1, At, B1); G_BAR;
;       G_LDB(B0, 1, 0); G_SCHED; G_LDA(At, 1, 0); G_STAGE(G_SA(0, 1), a2h1, voffA);
;       G_WAIT_L(8); G_BAR; G_WAIT_L(0); G_MMA(0, 0, At, B0); G_BAR; G_SCHED;
;       G_LDB(B1, 1, 1); G_STAGE(G_SB(1, 0), b2h0 + kstep, voffB);
;       G_BAR; G_WAIT_L(0); G_MMA(0, 1, At, B1); G_BAR;
;       G_LDA(At, 1, 1); G_STAGE(G_SA(1, 0), a2h0 + kstep, voffA);
;       G_BAR; G_WAIT_L(0); G_MMA(1, 0, At, B0); G_BAR; G_SCHED;
;       G_STAGE(G_SB(1, 1), b2h1 + kstep, voffB);
;       G_WAIT_V(6); G_BAR; G_MMA(1, 1, At, B1); G_BAR;
	s_waitcnt lgkmcnt(0)
	s_setprio 1
	s_waitcnt lgkmcnt(0)
	v_mfma_f32_16x16x32_bf16 v[60:63], v[146:149], v[168:171], v[60:63]
	v_mfma_f32_16x16x32_bf16 v[56:59], v[154:157], v[168:171], v[56:59]
	v_mfma_f32_16x16x32_bf16 v[52:55], v[146:149], v[176:179], v[52:55]
	v_mfma_f32_16x16x32_bf16 v[48:51], v[154:157], v[176:179], v[48:51]
	v_mfma_f32_16x16x32_bf16 v[36:39], v[146:149], v[190:193], v[36:39]
	v_mfma_f32_16x16x32_bf16 v[32:35], v[154:157], v[190:193], v[32:35]
	v_mfma_f32_16x16x32_bf16 v[20:23], v[146:149], v[198:201], v[20:23]
	v_mfma_f32_16x16x32_bf16 v[16:19], v[154:157], v[198:201], v[16:19]
	v_mfma_f32_16x16x32_bf16 v[60:63], v[150:153], v[172:175], v[60:63]
	v_mfma_f32_16x16x32_bf16 v[56:59], v[164:167], v[172:175], v[56:59]
	v_mfma_f32_16x16x32_bf16 v[52:55], v[150:153], v[184:187], v[52:55]
	v_mfma_f32_16x16x32_bf16 v[48:51], v[164:167], v[184:187], v[48:51]
	v_mfma_f32_16x16x32_bf16 v[36:39], v[150:153], v[194:197], v[36:39]
	v_mfma_f32_16x16x32_bf16 v[32:35], v[164:167], v[194:197], v[32:35]
	v_mfma_f32_16x16x32_bf16 v[20:23], v[150:153], v[202:205], v[20:23]
	v_mfma_f32_16x16x32_bf16 v[16:19], v[164:167], v[202:205], v[16:19]
	s_setprio 0
	s_barrier
	v_mov_b32_e32 v80, v132
	s_add_i32 s22, s31, s41
	v_lshl_add_u64 v[146:147], s[44:45], 0, v[80:81]
	v_lshl_add_u64 v[146:147], v[146:147], 0, s[52:53]
	s_mov_b32 m0, s22
	v_mov_b32_e32 v80, v136
	global_load_lds_dwordx4 v[146:147], off
	s_add_i32 m0, s22, 0x2000
	v_lshl_add_u64 v[146:147], s[44:45], 0, v[80:81]
	v_lshl_add_u64 v[146:147], v[146:147], 0, s[52:53]
	global_load_lds_dwordx4 v[146:147], off
	s_waitcnt vmcnt(6)
	s_barrier
	s_setprio 1
	v_mfma_f32_16x16x32_bf16 v[44:47], v[206:209], v[168:171], v[44:47]
	v_mfma_f32_16x16x32_bf16 v[40:43], v[214:217], v[168:171], v[40:43]
	v_mfma_f32_16x16x32_bf16 v[28:31], v[206:209], v[176:179], v[28:31]
	v_mfma_f32_16x16x32_bf16 v[24:27], v[214:217], v[176:179], v[24:27]
	v_mfma_f32_16x16x32_bf16 v[12:15], v[206:209], v[190:193], v[12:15]
	v_mfma_f32_16x16x32_bf16 v[8:11], v[214:217], v[190:193], v[8:11]
	v_mfma_f32_16x16x32_bf16 v[4:7], v[206:209], v[198:201], v[4:7]
	v_mfma_f32_16x16x32_bf16 v[0:3], v[214:217], v[198:201], v[0:3]
	v_mfma_f32_16x16x32_bf16 v[44:47], v[210:213], v[172:175], v[44:47]
	v_mfma_f32_16x16x32_bf16 v[40:43], v[218:221], v[172:175], v[40:43]
	v_mfma_f32_16x16x32_bf16 v[28:31], v[210:213], v[184:187], v[28:31]
	v_mfma_f32_16x16x32_bf16 v[24:27], v[218:221], v[184:187], v[24:27]
	v_mfma_f32_16x16x32_bf16 v[12:15], v[210:213], v[194:197], v[12:15]
	v_mfma_f32_16x16x32_bf16 v[8:11], v[218:221], v[194:197], v[8:11]
	v_mfma_f32_16x16x32_bf16 v[4:7], v[210:213], v[202:205], v[4:7]
	v_mfma_f32_16x16x32_bf16 v[0:3], v[218:221], v[202:205], v[0:3]
	s_setprio 0
	s_add_u32 s87, s87, 0x100
	s_addc_u32 vcc_lo, vcc_lo, 0
	s_add_u32 vcc_hi, vcc_hi, 0x100
	s_addc_u32 s28, s28, 0
	s_cmp_ge_u32 s29, s76
	s_mov_b64 s[38:39], s[42:43]
	s_mov_b32 s29, s30
	s_barrier
	s_cbranch_scc0 .LBB0_408
;   __device__ __forceinline__ void operator()(const f32x4 (&acc)[2][2][4][2], const Unit& u, const EpiCtx& x_, int wr, int wc, int fr, int fq) const {
; #pragma unroll
;     for (int ai = 0; ai < 2; ++ai)
; #pragma unroll
;       for (int m = 0; m < 4; ++m) {
;         const int row = (u.r0 + (ai ? x_.rdelta : 0)) + wr * 64 + m * 16 + fr;
;         float* rowp = (float*)u.C + (size_t)row * x_.ldc;
; #pragma unroll
;         for (int bj = 0; bj < 2; ++bj) {
;           const int cb = (u.c0 + bj * 128) + wc * 32 + 4 * fq;
;           *(f32x4*)(rowp + cb) = acc[ai][bj][m][0]; *(f32x4*)(rowp + cb + 16) = acc[ai][bj][m][1];
;         }
;       }
;   }
; template <class Epi>
; __device__ __forceinline__ void gemm_phase(LAS unsigned char* lds, const int K, const unsigned lda_b, const unsigned ldb_b, const Map& M, const Epi& E) {
;     ...
;     E(acc, cur, X, wr, wc, fr, fq);
;     if (!has_next) break;
; #pragma unroll
;     for (int a = 0; a < 2; ++a)
; #pragma unroll
;       for (int b = 0; b < 2; ++b)
; #pragma unroll
;         for (int m = 0; m < 4; ++m)
; #pragma unroll
;           for (int n = 0; n < 2; ++n) acc[a][b][m][n] = (f32x4){0.f, 0.f, 0.f, 0.f};
;     cur = nxt; ++ui;
;   }
	v_readfirstlane_b32 s22, v138
	v_add_u32_e32 v138, s67, v131
	v_readfirstlane_b32 s28, v139
	v_ashrrev_i32_e32 v139, 31, v138
	v_add_u32_e32 v148, s79, v135
	v_lshlrev_b64 v[146:147], 14, v[138:139]
	v_ashrrev_i32_e32 v149, 31, v148
	v_lshl_add_u64 v[146:147], s[2:3], 0, v[146:147]
	v_lshlrev_b64 v[148:149], 2, v[148:149]
	v_lshl_add_u64 v[150:151], v[146:147], 0, v[148:149]
	global_store_dwordx4 v[150:151], v[126:129], off
	global_store_dwordx4 v[150:151], v[122:125], off offset:64
	s_cmp_eq_u32 s86, s81
	s_mov_b64 s[38:39], s[4:5]
	v_add_u32_e32 v122, s79, v137
	v_ashrrev_i32_e32 v123, 31, v122
	v_lshlrev_b64 v[122:123], 2, v[122:123]
	v_lshl_add_u64 v[124:125], v[146:147], 0, v[122:123]
	global_store_dwordx4 v[124:125], v[110:113], off
	global_store_dwordx4 v[124:125], v[106:109], off offset:64
	s_mov_b64 s[42:43], s[6:7]
	s_mov_b64 s[44:45], s[8:9]
	v_add_u32_e32 v106, s67, v141
	v_ashrrev_i32_e32 v107, 31, v106
	v_lshlrev_b64 v[106:107], 14, v[106:107]
	v_lshl_add_u64 v[106:107], s[2:3], 0, v[106:107]
	v_lshl_add_u64 v[108:109], v[106:107], 0, v[148:149]
	v_lshl_add_u64 v[106:107], v[106:107], 0, v[122:123]
	global_store_dwordx4 v[108:109], v[118:121], off
	global_store_dwordx4 v[108:109], v[114:117], off offset:64
	global_store_dwordx4 v[106:107], v[94:97], off
	global_store_dwordx4 v[106:107], v[90:93], off offset:64
	s_mov_b32 s79, s28
	s_nop 0
	v_add_u32_e32 v90, s67, v142
	v_ashrrev_i32_e32 v91, 31, v90
	v_lshlrev_b64 v[90:91], 14, v[90:91]
	v_lshl_add_u64 v[90:91], s[2:3], 0, v[90:91]
	v_lshl_add_u64 v[92:93], v[90:91], 0, v[148:149]
	v_lshl_add_u64 v[90:91], v[90:91], 0, v[122:123]
	global_store_dwordx4 v[92:93], v[102:105], off
	global_store_dwordx4 v[92:93], v[98:101], off offset:64
	global_store_dwordx4 v[90:91], v[76:79], off
	global_store_dwordx4 v[90:91], v[72:75], off offset:64
	s_nop 1
	v_add_u32_e32 v72, s67, v143
	v_ashrrev_i32_e32 v73, 31, v72
	v_lshlrev_b64 v[72:73], 14, v[72:73]
	v_lshl_add_u64 v[72:73], s[2:3], 0, v[72:73]
	v_lshl_add_u64 v[74:75], v[72:73], 0, v[148:149]
	v_lshl_add_u64 v[72:73], v[72:73], 0, v[122:123]
	global_store_dwordx4 v[74:75], v[86:89], off
	global_store_dwordx4 v[74:75], v[82:85], off offset:64
	global_store_dwordx4 v[72:73], v[68:71], off
	global_store_dwordx4 v[72:73], v[64:67], off offset:64
	s_mov_b32 s67, s22
	s_nop 0
	v_add_u32_e32 v64, 0x80, v138
	v_ashrrev_i32_e32 v65, 31, v64
	v_lshlrev_b64 v[64:65], 14, v[64:65]
	v_lshl_add_u64 v[64:65], s[2:3], 0, v[64:65]
	v_lshl_add_u64 v[66:67], v[64:65], 0, v[148:149]
	global_store_dwordx4 v[66:67], v[60:63], off
	global_store_dwordx4 v[66:67], v[56:59], off offset:64
	s_nop 1
	v_lshl_add_u64 v[56:57], v[64:65], 0, v[122:123]
	global_store_dwordx4 v[56:57], v[44:47], off
	global_store_dwordx4 v[56:57], v[40:43], off offset:64
	s_nop 1
	v_add_u32_e32 v40, 0x90, v138
	v_ashrrev_i32_e32 v41, 31, v40
	v_lshlrev_b64 v[40:41], 14, v[40:41]
	v_lshl_add_u64 v[40:41], s[2:3], 0, v[40:41]
	v_lshl_add_u64 v[42:43], v[40:41], 0, v[148:149]
	v_lshl_add_u64 v[40:41], v[40:41], 0, v[122:123]
	global_store_dwordx4 v[42:43], v[52:55], off
	global_store_dwordx4 v[42:43], v[48:51], off offset:64
	global_store_dwordx4 v[40:41], v[28:31], off
	global_store_dwordx4 v[40:41], v[24:27], off offset:64
	s_nop 1
	v_add_u32_e32 v24, 0xa0, v138
	v_ashrrev_i32_e32 v25, 31, v24
	v_lshlrev_b64 v[24:25], 14, v[24:25]
	v_lshl_add_u64 v[24:25], s[2:3], 0, v[24:25]
	v_lshl_add_u64 v[26:27], v[24:25], 0, v[148:149]
	v_lshl_add_u64 v[24:25], v[24:25], 0, v[122:123]
	global_store_dwordx4 v[26:27], v[36:39], off
	global_store_dwordx4 v[26:27], v[32:35], off offset:64
	global_store_dwordx4 v[24:25], v[12:15], off
	global_store_dwordx4 v[24:25], v[8:11], off offset:64
	s_nop 1
	v_add_u32_e32 v8, 0xb0, v138
	v_ashrrev_i32_e32 v9, 31, v8
	v_lshlrev_b64 v[8:9], 14, v[8:9]
	v_lshl_add_u64 v[8:9], s[2:3], 0, v[8:9]
	v_lshl_add_u64 v[10:11], v[8:9], 0, v[148:149]
	v_lshl_add_u64 v[8:9], v[8:9], 0, v[122:123]
	s_mov_b64 s[2:3], s[36:37]
	global_store_dwordx4 v[10:11], v[20:23], off
	global_store_dwordx4 v[10:11], v[16:19], off offset:64
	global_store_dwordx4 v[8:9], v[4:7], off
	global_store_dwordx4 v[8:9], v[0:3], off offset:64
	s_cbranch_scc0 .LBB0_407
	s_waitcnt vmcnt(0)
	s_cmpk_gt_u32 s19, 0xff
	s_mov_b32 s86, 0x7f800000
	s_brev_b32 s82, 1
	s_cbranch_scc1 .LBB0_412
	s_barrier

; #define LAS __attribute__((address_space(3)))
; __device__ __forceinline__ int otid() { int t = threadIdx.x; asm volatile("" : "+v"(t)); return t; }
; __device__ __forceinline__ int obid() { extern __shared__ __attribute__((aligned(16))) unsigned char shm_vb[]; return __builtin_amdgcn_readfirstlane(*(volatile LAS int*)((LAS unsigned char*)shm_vb + VB_OFF)); }
; __device__ __forceinline__ void phase_p128(const bf16_t* __restrict__ dc, const bf16_t* __restrict__ zf, float* __restrict__ p128, LAS float* red, const int nseq, const int S) {
;   const int tid = otid(), lane = tid & 63, wid = tid >> 6;
;   const int K2 = S / 4 + 128, nrb = S / 64, nchunk = K2 / 32;
;   const size_t rmul = (S == 16384) ? 1 : 2;
;   for (int task = obid(); task < nrb * 2 * nseq; task += gridDim.x) {
;     const int seq = task / (2 * nrb), odd = (task / nrb) & 1, rb = task % nrb;
;     const int kap = rb * 16 + (lane & 15);
;     const bf16_t* ap = dc + (size_t)(2 * kap + odd) * rmul * DLD + 8 * (lane >> 4);
;     const bf16_t* bp = zf + (size_t)(2048 + (lane & 15)) * ZFLD + (size_t)seq * 2 * K2 + (size_t)odd * K2 + 8 * (lane >> 4);
;     f32x4 acc = {0.f, 0.f, 0.f, 0.f};
.LBB0_413:
	v_mov_b64_e32 v[0:1], s[10:11]
	global_load_dwordx2 v[2:3], v[0:1], off sc0 sc1
	s_waitcnt vmcnt(0)
	global_load_dwordx2 v[4:5], v[0:1], off sc0 sc1
	s_waitcnt vmcnt(0)
	global_load_dwordx2 v[6:7], v[0:1], off sc0 sc1
	s_waitcnt vmcnt(0)
	v_mov_b32_e32 v0, v252
	v_mov_b32_e32 v1, s74
	ds_read_b32 v1, v1
	s_and_b64 s[2:3], s[92:93], exec
	s_cselect_b32 s0, 8, 9
	s_lshl_b32 s0, s89, s0
	s_waitcnt lgkmcnt(0)
	v_readfirstlane_b32 s18, v1
	s_cmp_ge_i32 s18, s0
	v_readfirstlane_b32 s5, v3
	v_readfirstlane_b32 s4, v2
	v_readfirstlane_b32 s7, v5
	v_readfirstlane_b32 s6, v4
	v_readfirstlane_b32 s2, v7
	v_readfirstlane_b32 s3, v6
	s_cbranch_scc1 .LBB0_422
	s_add_u32 s19, s3, 0x351c0000
	s_addc_u32 s28, s2, 0
	s_lshr_b32 s31, s17, 5
	v_cvt_f32_u32_e32 v2, s31
	s_lshr_b32 s29, s17, 6
	v_and_b32_e32 v1, 63, v0
	v_cvt_f32_u32_e32 v6, s29
	v_rcp_iflag_f32_e32 v2, v2
	v_lshl_add_u32 v10, v1, 2, 0
	v_and_b32_e32 v3, 0x3fffffc0, v0
	v_lshl_add_u32 v14, v3, 2, v10
	v_lshrrev_b32_e32 v3, 2, v0
	v_ashrrev_i32_e32 v5, 6, v0
	v_and_b32_e32 v3, 12, v3
	v_mul_f32_e32 v2, 0x4f7ffffe, v2
	v_cvt_u32_f32_e32 v2, v2
	v_add_u32_e32 v15, v3, v5
	v_rcp_iflag_f32_e32 v3, v6
	s_sub_i32 s8, 0, s31
	v_readfirstlane_b32 s9, v2
	s_mul_i32 s8, s8, s9
	v_mul_f32_e32 v2, 0x4f7ffffe, v3
	v_cvt_u32_f32_e32 v2, v2
	s_mul_hi_u32 s8, s9, s8
	s_add_i32 s34, s9, s8
	v_and_b32_e32 v4, 15, v0
	v_readfirstlane_b32 s9, v2
	v_lshlrev_b32_e32 v2, 5, v5
	v_ashrrev_i32_e32 v3, 31, v2
	v_mul_u32_u24_e32 v1, 0x2200, v4
	v_lshlrev_b64 v[2:3], 1, v[2:3]
	s_movk_i32 s2, 0x100
	v_and_or_b32 v2, v0, 48, v2
	v_lshlrev_b32_e32 v80, 1, v1
	v_cmp_gt_i32_e64 s[2:3], s2, v0
	s_sub_i32 s8, 0, s29
	v_lshl_add_u64 v[0:1], v[2:3], 0, v[80:81]
	s_mul_i32 s8, s8, s9
	v_lshl_add_u64 v[0:1], s[6:7], 0, v[0:1]
	s_mov_b64 s[6:7], 0x22b80000
	s_lshr_b32 s30, s61, 5
	v_lshlrev_b32_e32 v11, 10, v5
	s_mul_hi_u32 s8, s9, s8
	v_lshl_add_u64 v[6:7], v[0:1], 0, s[6:7]
	s_and_b32 s6, s17, 0x7ffe
	v_lshl_add_u64 v[0:1], s[4:5], 0, v[2:3]
	s_mov_b64 s[4:5], 0x44480000
	v_cmp_gt_i32_e32 vcc, s30, v5
	s_add_i32 s35, s9, s8
	s_add_u32 s38, s6, 0x200
	s_addk_i32 s13, 0x80
	v_lshl_add_u64 v[8:9], v[0:1], 0, s[4:5]
	v_add_u32_e32 v16, v10, v11
	s_branch .LBB0_416

; #define LAS __attribute__((address_space(3)))
; __device__ __forceinline__ int otid() { int t = threadIdx.x; asm volatile("" : "+v"(t)); return t; }
; __device__ __forceinline__ unsigned xb_add(unsigned* p, unsigned v) { return __hip_atomic_fetch_add(p, v, __ATOMIC_RELAXED, __HIP_MEMORY_SCOPE_AGENT); }
; __device__ __forceinline__ void phase_p128(const bf16_t* __restrict__ dc, const bf16_t* __restrict__ zf, float* __restrict__ p128, LAS float* red, const int nseq, const int S) {
;     ...
;     for (int ch = wid; ch < nchunk; ch += 8) {
;       const bf16x8 av = *(const bf16x8*)(ap + ch * 32), bv = *(const bf16x8*)(bp + ch * 32);
;       acc = __builtin_amdgcn_mfma_f32_16x16x32_bf16(av, bv, acc, 0, 0, 0);
;     }
;     __syncthreads();
; #pragma unroll
;     for (int r = 0; r < 4; ++r) red[(wid * 4 + r) * 64 + lane] = acc[r];
;     __syncthreads();
;     if (tid < 256) {
;       const int r = tid >> 6, l = tid & 63;
;       float s = 0.f;
; #pragma unroll
;       for (int w = 0; w < 8; ++w) s += red[(w * 4 + r) * 64 + l];
;       const int kk = 2 * (rb * 16 + (l >> 4) * 4 + r) + odd;
;       p128[((size_t)seq * 4096 + kk) * 16 + (l & 15)] = s;
;     }
; __device__ __forceinline__ void gbar(unsigned* bar, unsigned n, volatile LAS unsigned* st) {
;   asm volatile("s_waitcnt vmcnt(0)" ::: "memory");
;   __syncthreads();
;   if (otid() == 0) {
;     __builtin_amdgcn_s_waitcnt(0);
;     const unsigned x = st[0], nloc = st[1], nx = st[2];
;     const unsigned old = xb_add(&bar[XB_XSUB(x)], 1u);
;     unsigned sp = 0;
;     if (old + 1u == (n + 1u) * nloc) {
.LBB0_418:
	global_load_dwordx4 v[18:21], v[12:13], off
	global_load_dwordx4 v[22:25], v[10:11], off
	v_add_u32_e32 v17, 8, v17
	v_cmp_le_i32_e64 s[4:5], s30, v17
	v_lshl_add_u64 v[10:11], v[10:11], 0, s[70:71]
	s_or_b64 s[36:37], s[4:5], s[36:37]
	v_lshl_add_u64 v[12:13], v[12:13], 0, s[70:71]
	s_waitcnt vmcnt(0) lgkmcnt(0)
	v_mfma_f32_16x16x32_bf16 v[0:3], v[18:21], v[22:25], v[0:3]
	s_andn2_b64 exec, exec, s[36:37]
	s_cbranch_execnz .LBB0_418
	s_or_b64 exec, exec, s[36:37]
.LBB0_420:
	s_or_b64 exec, exec, s[8:9]
	s_barrier
	s_nop 2
	ds_write2st64_b32 v16, v0, v1 offset1:1
	ds_write2st64_b32 v16, v2, v3 offset0:2 offset1:3
	s_waitcnt lgkmcnt(0)
	s_barrier
	s_and_saveexec_b64 s[4:5], s[2:3]
	s_cbranch_execz .LBB0_415
	ds_read2st64_b32 v[0:1], v14 offset1:4
	s_lshl_b64 s[6:7], s[6:7], 18
	s_add_u32 s6, s19, s6
	s_addc_u32 s7, s28, s7
	v_lshlrev_b32_e32 v80, 2, v4
	s_waitcnt lgkmcnt(0)
	v_add_f32_e32 v0, 0, v0
	v_add_f32_e32 v2, v0, v1
	ds_read2st64_b32 v[0:1], v14 offset0:8 offset1:12
	s_waitcnt lgkmcnt(0)
	v_add_f32_e32 v0, v2, v0
	v_add_f32_e32 v2, v0, v1
	ds_read2st64_b32 v[0:1], v14 offset0:16 offset1:20
	s_waitcnt lgkmcnt(0)
	v_add_f32_e32 v0, v2, v0
	v_add_f32_e32 v2, v0, v1
	ds_read2st64_b32 v[0:1], v14 offset0:24 offset1:28
	s_waitcnt lgkmcnt(0)
	v_add_f32_e32 v0, v2, v0
	v_add_f32_e32 v2, v0, v1
	v_add_u32_e32 v0, s41, v15
	v_lshl_or_b32 v0, v0, 1, s39
	v_ashrrev_i32_e32 v1, 31, v0
	v_lshlrev_b64 v[0:1], 6, v[0:1]
	v_lshl_add_u64 v[0:1], s[6:7], 0, v[0:1]
	v_lshl_add_u64 v[0:1], v[0:1], 0, v[80:81]
	global_store_dword v[0:1], v2, off
	s_branch .LBB0_415
.LBB0_422:
	v_mov_b64_e32 v[0:1], s[10:11]
	global_load_dwordx2 v[0:1], v[0:1], off sc0 sc1
	s_waitcnt vmcnt(0)
	s_waitcnt vmcnt(0)
	v_mov_b32_e32 v2, v252
	s_waitcnt lgkmcnt(0)
	s_barrier
	v_add_u32_e32 v42, 3, v158
	v_cmp_ne_u32_e32 vcc, 0, v2
	v_readfirstlane_b32 s0, v1
	v_readfirstlane_b32 s1, v0
	s_and_saveexec_b64 s[2:3], vcc
	s_xor_b64 s[2:3], exec, s[2:3]
	v_add_u32_e32 v42, 3, v158
	s_andn2_saveexec_b64 s[2:3], s[2:3]
	s_cbranch_execz .LBB0_472
	v_readlane_b32 s6, v255, 15
	s_waitcnt vmcnt(0) expcnt(0) lgkmcnt(0)
	s_add_u32 s4, s1, 0x4cc80000
	v_mov_b32_e32 v0, s6
	ds_read_b32 v1, v0
	v_readlane_b32 s6, v255, 16
	s_addc_u32 s5, s0, 0
	s_waitcnt lgkmcnt(0)
	v_lshlrev_b32_e32 v1, 6, v1
	v_add_u32_e32 v80, 0x440, v1
	v_mov_b32_e32 v0, s6
	v_readlane_b32 s6, v255, 17
	v_lshlrev_b64 v[2:3], 2, v[80:81]
	ds_read_b32 v4, v0
	v_mov_b32_e32 v0, s6
	v_lshl_add_u64 v[2:3], s[4:5], 0, v[2:3]
	ds_read_b32 v0, v0
	global_atomic_add v2, v[2:3], v230, off sc0
	s_waitcnt lgkmcnt(0)
	v_mul_lo_u32 v3, v4, v42
	v_add_u32_e32 v80, 0x840, v1
	s_waitcnt vmcnt(0)
	v_add_u32_e32 v2, 1, v2
	v_cmp_ne_u32_e32 vcc, v2, v3
	s_and_saveexec_b64 s[6:7], vcc
	s_xor_b64 s[6:7], exec, s[6:7]
	s_cbranch_execz .LBB0_448
	v_lshlrev_b64 v[0:1], 2, v[80:81]
	v_lshl_add_u64 v[0:1], s[4:5], 0, v[0:1]
	s_mov_b32 s13, 0x1000000
	s_mov_b64 s[8:9], 0
	s_branch .LBB0_436

; __device__ __forceinline__ unsigned xb_ld(unsigned* p) { return __hip_atomic_load(p, __ATOMIC_RELAXED, __HIP_MEMORY_SCOPE_AGENT); }
; __device__ __forceinline__ void gbar(unsigned* bar, unsigned n, volatile LAS unsigned* st) {
;     ...
;     } else {
;       while (xb_ld(&bar[XB_XGEN(x)]) <= n) { __builtin_amdgcn_s_sleep(1); if (++sp > (1u << 24)) break; }
.LBB0_436:
	global_load_dword v2, v[0:1], off sc1
	s_or_b64 s[36:37], s[36:37], exec
	s_waitcnt vmcnt(0) lgkmcnt(0)
	v_cmp_le_u32_e32 vcc, v2, v140
	s_and_saveexec_b64 s[38:39], vcc
	s_cbranch_execz .LBB0_435
	s_cmp_lg_u32 s13, 0
	s_sleep 1
	s_cbranch_scc0 .LBB0_446
	global_load_dword v2, v[0:1], off sc1
	s_mov_b64 s[18:19], -1
	s_waitcnt vmcnt(0) lgkmcnt(0)
	v_cmp_le_u32_e32 vcc, v2, v140
	s_and_saveexec_b64 s[42:43], vcc
	s_cbranch_execz .LBB0_433
	s_sleep 1
	global_load_dword v2, v[0:1], off sc1
	s_waitcnt vmcnt(0) lgkmcnt(0)
	v_cmp_le_u32_e32 vcc, v2, v140
	s_and_saveexec_b64 s[44:45], vcc
	s_cbranch_execz .LBB0_432
	s_sleep 1
	global_load_dword v2, v[0:1], off sc1
	s_waitcnt vmcnt(0) lgkmcnt(0)
	v_cmp_le_u32_e32 vcc, v2, v140
	s_and_saveexec_b64 s[46:47], vcc
	s_cbranch_execz .LBB0_431
	s_sleep 1
	global_load_dword v2, v[0:1], off sc1
	s_waitcnt vmcnt(0) lgkmcnt(0)
	v_cmp_le_u32_e32 vcc, v2, v140
	s_and_saveexec_b64 s[68:69], vcc
	s_cbranch_execz .LBB0_430
	s_sleep 1
	global_load_dword v2, v[0:1], off sc1
	s_waitcnt vmcnt(0) lgkmcnt(0)
	v_cmp_le_u32_e32 vcc, v2, v140
	s_and_saveexec_b64 s[94:95], vcc
	s_cbranch_execz .LBB0_429
	s_sleep 1
	global_load_dword v2, v[0:1], off sc1
	s_mov_b64 s[48:49], -1
	s_waitcnt vmcnt(0) lgkmcnt(0)
	v_cmp_le_u32_e32 vcc, v2, v140
	s_and_saveexec_b64 s[18:19], vcc
	s_cbranch_execz .LBB0_428
	s_sleep 1
	global_load_dword v2, v[0:1], off sc1
	s_waitcnt vmcnt(0) lgkmcnt(0)
	v_cmp_le_u32_e32 vcc, v2, v140
	s_and_saveexec_b64 s[66:67], vcc
	s_cbranch_execz .LBB0_427
	s_add_i32 s13, s13, -8
	s_xor_b64 s[48:49], exec, -1
	s_sleep 1
	s_branch .LBB0_427

; __device__ __forceinline__ unsigned xb_add(unsigned* p, unsigned v) { return __hip_atomic_fetch_add(p, v, __ATOMIC_RELAXED, __HIP_MEMORY_SCOPE_AGENT); }
; __device__ __forceinline__ void gbar(unsigned* bar, unsigned n, volatile LAS unsigned* st) {
;     ...
;     if (old + 1u == (n + 1u) * nloc) {
;       __builtin_amdgcn_fence(__ATOMIC_RELEASE, "agent");
;       asm volatile("s_waitcnt vmcnt(0)" ::: "memory");
;       xb_add(&bar[XB_TOP], 1u);
.LBB0_448:
	s_andn2_saveexec_b64 s[6:7], s[6:7]
	s_cbranch_execz .LBB0_471
	v_mov_b32_e32 v1, s1
	v_add_co_u32_e32 v2, vcc, 0x4cc83000, v1
	v_mov_b32_e32 v1, s0
	buffer_wbl2 sc1
	s_waitcnt vmcnt(0)
	v_addc_co_u32_e32 v3, vcc, 0, v1, vcc
	global_atomic_add v[2:3], v230, off offset:256
	s_add_u32 s8, s1, 0x4cc83100
	s_addc_u32 s9, s0, 0
	v_mul_lo_u32 v0, v0, v42
	s_mov_b32 s0, 0x1000000
	s_mov_b64 s[36:37], 0
	s_branch .LBB0_459

; __device__ __forceinline__ int otid() { int t = threadIdx.x; asm volatile("" : "+v"(t)); return t; }
; __device__ __forceinline__ int obid() { extern __shared__ __attribute__((aligned(16))) unsigned char shm_vb[]; return __builtin_amdgcn_readfirstlane(*(volatile LAS int*)((LAS unsigned char*)shm_vb + VB_OFF)); }
; __device__ __forceinline__ void phase_fnet_combine(bf16_t* __restrict__ fg, const float* __restrict__ P, const float* __restrict__ Q, const float* __restrict__ P128, const float* __restrict__ PH, const int S) {
;   const size_t n8 = (size_t)TS * 512, gs = (size_t)gridDim.x * 512;
;   const float norm = rsqrtf((float)S);
;   for (size_t i = (size_t)obid() * 512 + otid(); i < n8; i += gs) {
;     const size_t t = i >> 9; const int col = (int)(i & 511) * 8, g = col >> 8, l0 = col & 255;
;     const int seq = (int)(t / S), k = (int)(t % S);
;     const bool klo = (k <= S / 2); const int kk = klo ? k : S - k;
;     const bool mid = (kk == S / 2), hi = (l0 >= 128);
;     const float* Pr = mid ? PH + seq * 2304 : P + ((size_t)seq * 4096 + kk) * 2048;
;     const float* Qr = Q + ((size_t)seq * 4096 + (mid ? 0 : kk)) * 2048;
;     const int vb = g * 128 + (hi ? 248 - l0 : l0);
;     const f32x4 p0 = *(const f32x4*)(Pr + vb), p1 = *(const f32x4*)(Pr + vb + 4);
;     const f32x4 q0 = *(const f32x4*)(Qr + vb), q1 = *(const f32x4*)(Qr + vb + 4);
;     const float pw[8] = {p0[0], p0[1], p0[2], p0[3], p1[0], p1[1], p1[2], p1[3]}, qw[8] = {q0[0], q0[1], q0[2], q0[3], q1[0], q1[1], q1[2], q1[3]};
;     float ps = 0.f, qs = 0.f;
;     if (hi) {
;       if (l0 == 128) ps = mid ? PH[seq * 2304 + 2048 + g] : P128[((size_t)seq * 4096 + kk) * 16 + g];
;       else { ps = Pr[g * 128 + 256 - l0]; qs = Qr[g * 128 + 256 - l0]; }
;     }
.LBB0_472:
	s_or_b64 exec, exec, s[2:3]
	v_mov_b64_e32 v[0:1], s[10:11]
	s_waitcnt lgkmcnt(0)
	s_barrier
	global_load_dwordx2 v[2:3], v[0:1], off sc0 sc1
	s_waitcnt vmcnt(0)
	global_load_dwordx2 v[4:5], v[0:1], off sc0 sc1
	s_waitcnt vmcnt(0)
	global_load_dwordx2 v[6:7], v[0:1], off sc0 sc1
	s_waitcnt vmcnt(0)
	global_load_dwordx2 v[8:9], v[0:1], off sc0 sc1
	s_waitcnt vmcnt(0)
	global_load_dwordx2 v[10:11], v[0:1], off sc0 sc1
	s_waitcnt vmcnt(0)
	v_mov_b32_e32 v0, s74
	ds_read_b32 v12, v0
	v_mov_b32_e32 v0, v252
	s_mov_b64 s[18:19], 0x800000
	v_ashrrev_i32_e32 v1, 31, v0
	s_waitcnt lgkmcnt(0)
	v_readfirstlane_b32 s2, v12
	s_ashr_i32 s3, s2, 31
	s_lshl_b64 s[0:1], s[2:3], 9
	v_lshl_add_u64 v[36:37], s[0:1], 0, v[0:1]
	v_cmp_gt_u64_e32 vcc, s[18:19], v[36:37]
	v_readfirstlane_b32 s8, v3
	v_readfirstlane_b32 s13, v2
	v_readfirstlane_b32 s6, v5
	v_readfirstlane_b32 s9, v4
	v_readfirstlane_b32 s4, v7
	v_readfirstlane_b32 s7, v6
	v_readfirstlane_b32 s0, v9
	v_readfirstlane_b32 s5, v8
	v_readfirstlane_b32 s1, v11
	v_readfirstlane_b32 s3, v10
	s_and_saveexec_b64 s[36:37], vcc
	s_cbranch_execz .LBB0_489
	s_add_u32 s38, s13, 0x251c0000
	s_addc_u32 s39, s8, 0
	s_add_u32 s94, s9, 0x2d1c0000
	s_addc_u32 s95, s6, 0
	s_add_u32 s96, s7, 0x311c0000
	v_cvt_f32_u32_e32 v1, s17
	s_addc_u32 s97, s4, 0
	s_add_u32 s42, s5, 0x351c0000
	s_addc_u32 s43, s0, 0
	s_add_u32 s44, s3, 0x35240000
	v_rsq_f32_e32 v43, v1
	s_addc_u32 s45, s1, 0
	s_and_b64 s[0:1], s[92:93], exec
	v_lshlrev_b32_e32 v0, 3, v0
	s_cselect_b32 s0, 13, 14
	s_add_i32 s1, s17, 0x3fff
	v_lshl_add_u32 v44, s2, 12, v0
	s_mov_b64 s[68:69], 0
	s_branch .LBB0_477
.LBB0_474:
	s_or_b64 exec, exec, s[6:7]
	s_waitcnt vmcnt(0) lgkmcnt(0)
	global_load_dword v46, v[2:3], off
	v_mov_b32_e32 v47, 0

; __device__ __forceinline__ unsigned cvt_pk_bf16(float lo, float hi) { unsigned r; asm("v_cvt_pk_bf16_f32 %0, %1, %2" : "=v"(r) : "v"(lo), "v"(hi)); return r; }
; __device__ __forceinline__ float bf_lo(unsigned u) { return __uint_as_float(u << 16); }
; __device__ __forceinline__ float bf_hi(unsigned u) { return __uint_as_float(u & 0xffff0000u); }
; __device__ __forceinline__ float sigmoidf_(float x) { return 1.f / (1.f + __expf(-x)); }
; __device__ __forceinline__ void phase_fnet_combine(bf16_t* __restrict__ fg, const float* __restrict__ P, const float* __restrict__ Q, const float* __restrict__ P128, const float* __restrict__ PH, const int S) {
;     ...
;     const float sq = (mid ? 0.f : 1.f) * (klo ? 1.f : -1.f) * (hi ? -1.f : 1.f);
;     bf16_t* gp = fg + t * 4096 + col;
;     const uint4 gt = *(const uint4*)gp;
;     const unsigned gu[4] = {gt.x, gt.y, gt.z, gt.w};
;     float mv[8];
; #pragma unroll
;     for (int e = 0; e < 8; ++e) {
;       float pv, qv;
;       if (!hi) { pv = pw[e]; qv = (l0 + e == 0) ? 0.f : qw[e]; }
;       else if (e == 0) { pv = ps; qv = qs; }
;       else { pv = pw[8 - e]; qv = qw[8 - e]; }
;       mv[e] = (pv - sq * qv) * norm;
;     }
;     unsigned ou[4];
; #pragma unroll
;     for (int q = 0; q < 4; ++q) {
;       const float g0 = bf_lo(gu[q]), g1 = bf_hi(gu[q]);
;       ou[q] = cvt_pk_bf16(mv[2 * q] * g0 * sigmoidf_(g0), mv[2 * q + 1] * g1 * sigmoidf_(g1));
;     }
;     uint4 o; o.x = ou[0]; o.y = ou[1]; o.z = ou[2]; o.w = ou[3];
;     *(uint4*)gp = o;
;   }
.LBB0_476:
	s_or_b64 exec, exec, s[46:47]
	v_lshrrev_b64 v[0:1], 9, v[36:37]
	v_and_b32_e32 v2, 0xff8, v44
	v_lshlrev_b64 v[0:1], 13, v[0:1]
	v_cndmask_b32_e64 v3, 1.0, 0, s[4:5]
	v_lshl_add_u64 v[0:1], s[38:39], 0, v[0:1]
	v_lshlrev_b32_e32 v80, 1, v2
	v_cndmask_b32_e64 v3, v3, -v3, s[2:3]
	v_lshl_add_u64 v[20:21], v[0:1], 0, v[80:81]
	v_mul_f32_e32 v10, v3, v49
	global_load_dwordx4 v[0:3], v[20:21], off
	v_cmp_ne_u32_e64 s[2:3], 0, v45
	s_waitcnt vmcnt(0) lgkmcnt(0)
	v_cndmask_b32_e32 v4, v4, v46, vcc
	v_lshl_add_u64 v[36:37], v[36:37], 0, s[14:15]
	v_cndmask_b32_e64 v6, 0, v16, s[2:3]
	v_cndmask_b32_e32 v6, v6, v47, vcc
	v_fma_f32 v4, -v10, v6, v4
	v_mul_f32_e32 v14, v43, v4
	v_cndmask_b32_e32 v4, v17, v15, vcc
	v_cndmask_b32_e32 v6, v5, v11, vcc
	v_fma_f32 v4, -v4, v10, v6
	v_mul_f32_e32 v16, v43, v4
	v_fma_f32 v4, -v34, v10, v30
	v_mul_f32_e32 v18, v43, v4
	v_cndmask_b32_e32 v4, v19, v13, vcc
	v_cndmask_b32_e32 v6, v7, v9, vcc
	v_fma_f32 v4, -v4, v10, v6
	v_cndmask_b32_e32 v6, v9, v7, vcc
	v_cndmask_b32_e32 v7, v15, v17, vcc
	v_cndmask_b32_e32 v5, v11, v5, vcc
	v_fma_f32 v5, -v7, v10, v5
	v_mul_f32_e32 v23, v43, v4
	v_fma_f32 v4, -v12, v10, v8
	v_mul_f32_e32 v8, v43, v4
	v_cndmask_b32_e32 v4, v13, v19, vcc
	v_fma_f32 v4, -v4, v10, v6
	v_mul_f32_e32 v6, v43, v4
	v_fma_f32 v4, -v26, v10, v22
	v_mul_f32_e32 v4, v43, v4
	v_mul_f32_e32 v5, v43, v5
	v_lshlrev_b32_e32 v7, 16, v0
	v_mul_f32_e32 v9, v14, v7
	v_mul_f32_e32 v7, 0xbfb8aa3b, v7
	v_exp_f32_e32 v7, v7
	v_and_b32_e32 v0, 0xffff0000, v0
	v_add_f32_e32 v7, 1.0, v7
	v_div_scale_f32 v10, s[2:3], v7, v7, 1.0
	v_rcp_f32_e32 v11, v10
	s_nop 0
	v_fma_f32 v12, -v10, v11, 1.0
	v_fmac_f32_e32 v11, v12, v11
	v_div_scale_f32 v12, vcc, 1.0, v7, 1.0
	v_mul_f32_e32 v13, v12, v11
	v_fma_f32 v14, -v10, v13, v12
	v_fmac_f32_e32 v13, v14, v11
	v_fma_f32 v10, -v10, v13, v12
	v_div_fmas_f32 v10, v10, v11, v13
	v_div_fixup_f32 v7, v10, v7, 1.0
	v_mul_f32_e32 v7, v9, v7
	v_mul_f32_e32 v9, v16, v0
	v_mul_f32_e32 v0, 0xbfb8aa3b, v0
	v_exp_f32_e32 v0, v0
	s_nop 0
	v_add_f32_e32 v0, 1.0, v0
	v_div_scale_f32 v10, s[2:3], v0, v0, 1.0
	v_rcp_f32_e32 v11, v10
	s_nop 0
	v_fma_f32 v12, -v10, v11, 1.0
	v_fmac_f32_e32 v11, v12, v11
	v_div_scale_f32 v12, vcc, 1.0, v0, 1.0
	v_mul_f32_e32 v13, v12, v11
	v_fma_f32 v14, -v10, v13, v12
	v_fmac_f32_e32 v13, v14, v11
	v_fma_f32 v10, -v10, v13, v12
	v_div_fmas_f32 v10, v10, v11, v13
	v_div_fixup_f32 v0, v10, v0, 1.0
	v_mul_f32_e32 v0, v9, v0
	v_cvt_pk_bf16_f32 v0, v7, v0
	v_lshlrev_b32_e32 v7, 16, v1
	v_mul_f32_e32 v9, v18, v7
	v_mul_f32_e32 v7, 0xbfb8aa3b, v7
	v_exp_f32_e32 v7, v7
	v_and_b32_e32 v1, 0xffff0000, v1
	v_add_f32_e32 v7, 1.0, v7
	v_div_scale_f32 v10, s[2:3], v7, v7, 1.0
	v_rcp_f32_e32 v11, v10
	s_nop 0
	v_fma_f32 v12, -v10, v11, 1.0
	v_fmac_f32_e32 v11, v12, v11
	v_div_scale_f32 v12, vcc, 1.0, v7, 1.0
	v_mul_f32_e32 v13, v12, v11
	v_fma_f32 v14, -v10, v13, v12
	v_fmac_f32_e32 v13, v14, v11
	v_fma_f32 v10, -v10, v13, v12
	v_div_fmas_f32 v10, v10, v11, v13
	v_div_fixup_f32 v7, v10, v7, 1.0
	v_mul_f32_e32 v7, v9, v7
	v_mul_f32_e32 v9, v23, v1
	v_mul_f32_e32 v1, 0xbfb8aa3b, v1
	v_exp_f32_e32 v1, v1
	s_nop 0
	v_add_f32_e32 v1, 1.0, v1
	v_div_scale_f32 v10, s[2:3], v1, v1, 1.0
	v_rcp_f32_e32 v11, v10
	s_nop 0
	v_fma_f32 v12, -v10, v11, 1.0
	v_fmac_f32_e32 v11, v12, v11
	v_div_scale_f32 v12, vcc, 1.0, v1, 1.0
	v_mul_f32_e32 v13, v12, v11
	v_fma_f32 v14, -v10, v13, v12
	v_fmac_f32_e32 v13, v14, v11
	v_fma_f32 v10, -v10, v13, v12
	v_div_fmas_f32 v10, v10, v11, v13
	v_div_fixup_f32 v1, v10, v1, 1.0
	v_mul_f32_e32 v1, v9, v1
	v_cvt_pk_bf16_f32 v1, v7, v1
	v_lshlrev_b32_e32 v7, 16, v2
	v_mul_f32_e32 v8, v8, v7
	v_mul_f32_e32 v7, 0xbfb8aa3b, v7
	v_exp_f32_e32 v7, v7
	v_and_b32_e32 v2, 0xffff0000, v2
	v_mul_f32_e32 v6, v6, v2
	v_mul_f32_e32 v2, 0xbfb8aa3b, v2
	v_add_f32_e32 v7, 1.0, v7
	v_div_scale_f32 v9, s[2:3], v7, v7, 1.0
	v_rcp_f32_e32 v10, v9
	v_exp_f32_e32 v2, v2
	v_fma_f32 v11, -v9, v10, 1.0
	v_fmac_f32_e32 v10, v11, v10
	v_div_scale_f32 v11, vcc, 1.0, v7, 1.0
	v_mul_f32_e32 v12, v11, v10
	v_fma_f32 v13, -v9, v12, v11
	v_fmac_f32_e32 v12, v13, v10
	v_fma_f32 v9, -v9, v12, v11
	v_div_fmas_f32 v9, v9, v10, v12
	v_div_fixup_f32 v7, v9, v7, 1.0
	v_add_f32_e32 v2, 1.0, v2
	v_mul_f32_e32 v7, v8, v7
	v_div_scale_f32 v8, s[2:3], v2, v2, 1.0
	v_rcp_f32_e32 v9, v8
	s_nop 0
	v_fma_f32 v10, -v8, v9, 1.0
	v_fmac_f32_e32 v9, v10, v9
	v_div_scale_f32 v10, vcc, 1.0, v2, 1.0
	v_mul_f32_e32 v11, v10, v9
	v_fma_f32 v12, -v8, v11, v10
	v_fmac_f32_e32 v11, v12, v9
	v_fma_f32 v8, -v8, v11, v10
	v_div_fmas_f32 v8, v8, v9, v11
	v_div_fixup_f32 v2, v8, v2, 1.0
	v_mul_f32_e32 v2, v6, v2
	v_lshlrev_b32_e32 v6, 16, v3
	v_mul_f32_e32 v4, v4, v6
	v_mul_f32_e32 v6, 0xbfb8aa3b, v6
	v_exp_f32_e32 v6, v6
	v_cvt_pk_bf16_f32 v2, v7, v2
	v_and_b32_e32 v3, 0xffff0000, v3
	v_mul_f32_e32 v5, v5, v3
	v_add_f32_e32 v6, 1.0, v6
	v_div_scale_f32 v7, s[2:3], v6, v6, 1.0
	v_rcp_f32_e32 v8, v7
	v_mul_f32_e32 v3, 0xbfb8aa3b, v3
	v_exp_f32_e32 v3, v3
	v_fma_f32 v9, -v7, v8, 1.0
	v_fmac_f32_e32 v8, v9, v8
	v_div_scale_f32 v9, vcc, 1.0, v6, 1.0
	v_mul_f32_e32 v10, v9, v8
	v_fma_f32 v11, -v7, v10, v9
	v_fmac_f32_e32 v10, v11, v8
	v_fma_f32 v7, -v7, v10, v9
	v_div_fmas_f32 v7, v7, v8, v10
	v_div_fixup_f32 v6, v7, v6, 1.0
	v_add_f32_e32 v3, 1.0, v3
	v_mul_f32_e32 v4, v4, v6
	v_div_scale_f32 v6, s[2:3], v3, v3, 1.0
	v_rcp_f32_e32 v7, v6
	v_readlane_b32 s2, v255, 14
	v_fma_f32 v8, -v6, v7, 1.0
	v_fmac_f32_e32 v7, v8, v7
	v_div_scale_f32 v8, vcc, 1.0, v3, 1.0
	v_mul_f32_e32 v9, v8, v7
	v_fma_f32 v10, -v6, v9, v8
	v_fmac_f32_e32 v9, v10, v7
	v_fma_f32 v6, -v6, v9, v8
	v_div_fmas_f32 v6, v6, v7, v9
	v_add_u32_e32 v44, s2, v44
	s_mov_b64 s[2:3], 0x7fffff
	v_div_fixup_f32 v3, v6, v3, 1.0
	v_cmp_lt_u64_e32 vcc, s[2:3], v[36:37]
	v_mul_f32_e32 v3, v5, v3
	s_or_b64 s[68:69], vcc, s[68:69]
	v_cvt_pk_bf16_f32 v3, v4, v3
	global_store_dwordx4 v[20:21], v[0:3], off
	s_andn2_b64 exec, exec, s[68:69]
	s_cbranch_execz .LBB0_489
; __device__ __forceinline__ int otid() { int t = threadIdx.x; asm volatile("" : "+v"(t)); return t; }
; __device__ __forceinline__ int obid() { extern __shared__ __attribute__((aligned(16))) unsigned char shm_vb[]; return __builtin_amdgcn_readfirstlane(*(volatile LAS int*)((LAS unsigned char*)shm_vb + VB_OFF)); }
; __device__ __forceinline__ void phase_fnet_combine(bf16_t* __restrict__ fg, const float* __restrict__ P, const float* __restrict__ Q, const float* __restrict__ P128, const float* __restrict__ PH, const int S) {
;     ...
;   for (size_t i = (size_t)obid() * 512 + otid(); i < n8; i += gs) {
;     const size_t t = i >> 9; const int col = (int)(i & 511) * 8, g = col >> 8, l0 = col & 255;
;     const int seq = (int)(t / S), k = (int)(t % S);
;     const bool klo = (k <= S / 2); const int kk = klo ? k : S - k;
;     const bool mid = (kk == S / 2), hi = (l0 >= 128);
;     const float* Pr = mid ? PH + seq * 2304 : P + ((size_t)seq * 4096 + kk) * 2048;
;     const float* Qr = Q + ((size_t)seq * 4096 + (mid ? 0 : kk)) * 2048;
;     const int vb = g * 128 + (hi ? 248 - l0 : l0);
;     const f32x4 p0 = *(const f32x4*)(Pr + vb), p1 = *(const f32x4*)(Pr + vb + 4);
;     const f32x4 q0 = *(const f32x4*)(Qr + vb), q1 = *(const f32x4*)(Qr + vb + 4);
;     const float pw[8] = {p0[0], p0[1], p0[2], p0[3], p1[0], p1[1], p1[2], p1[3]}, qw[8] = {q0[0], q0[1], q0[2], q0[3], q1[0], q1[1], q1[2], q1[3]};
;     float ps = 0.f, qs = 0.f;
;     if (hi) {
;       if (l0 == 128) ps = mid ? PH[seq * 2304 + 2048 + g] : P128[((size_t)seq * 4096 + kk) * 16 + g];
;       else { ps = Pr[g * 128 + 256 - l0]; qs = Qr[g * 128 + 256 - l0]; }
;     }
.LBB0_477:
	v_alignbit_b32 v0, v37, v36, 9
	v_lshrrev_b32_e32 v80, s0, v0
	v_and_b32_e32 v0, s1, v0
	v_sub_u32_e32 v1, s17, v0
	v_cmp_lt_u32_e64 s[2:3], s40, v0
	s_nop 1
	v_cndmask_b32_e64 v0, v0, v1, s[2:3]
	v_cmp_eq_u32_e64 s[4:5], s40, v0
	v_cmp_ne_u32_e64 s[6:7], s40, v0
	s_and_saveexec_b64 s[8:9], s[6:7]
	s_xor_b64 s[8:9], exec, s[8:9]
	v_ashrrev_i32_e32 v1, 31, v0
	v_lshlrev_b64 v[2:3], 25, v[80:81]
	v_lshl_add_u64 v[2:3], s[94:95], 0, v[2:3]
	v_lshlrev_b64 v[4:5], 13, v[0:1]
	v_lshl_add_u64 v[2:3], v[2:3], 0, v[4:5]
	v_mov_b64_e32 v[4:5], v[0:1]
	s_andn2_saveexec_b64 s[8:9], s[8:9]
	v_mov_b64_e32 v[2:3], s[44:45]
	s_movk_i32 s13, 0x2400
	v_mad_u64_u32 v[2:3], s[18:19], v80, s13, v[2:3]
	v_mov_b64_e32 v[4:5], 0
	s_or_b64 exec, exec, s[8:9]
	v_lshlrev_b64 v[38:39], 12, v[80:81]
	v_lshl_add_u64 v[4:5], v[4:5], 0, v[38:39]
	v_lshlrev_b64 v[4:5], 13, v[4:5]
	s_movk_i32 s8, 0xf8
	v_and_b32_e32 v45, 0xf8, v44
	v_lshl_add_u64 v[40:41], s[96:97], 0, v[4:5]
	v_bitop3_b32 v4, v44, s8, v44 bitop3:0xc
	s_movk_i32 s8, 0x7f
	v_bfe_u32 v48, v44, 8, 4
	v_cmp_lt_u32_e32 vcc, s8, v45
	v_lshlrev_b32_e32 v1, 7, v48
	v_mov_b32_e32 v13, v81
	v_cndmask_b32_e32 v4, v45, v4, vcc
	v_add_lshl_u32 v12, v1, v4, 2
	v_lshl_add_u64 v[8:9], v[2:3], 0, v[12:13]
	v_lshl_add_u64 v[16:17], v[40:41], 0, v[12:13]
	global_load_dwordx4 v[4:7], v[8:9], off
	s_nop 0
	global_load_dwordx4 v[8:11], v[8:9], off offset:16
	s_nop 0
	global_load_dwordx4 v[12:15], v[16:17], off offset:16
	s_nop 0
	global_load_dwordx4 v[16:19], v[16:17], off
	v_mov_b32_e32 v47, 0
	v_mov_b32_e32 v49, 1.0
	v_mov_b32_e32 v46, 0
	s_waitcnt vmcnt(0) lgkmcnt(0)
	v_mov_b64_e32 v[30:31], v[6:7]
	v_mov_b64_e32 v[22:23], v[10:11]
	v_mov_b64_e32 v[26:27], v[14:15]
	v_mov_b64_e32 v[34:35], v[18:19]
	v_mov_b64_e32 v[20:21], v[8:9]
	v_mov_b64_e32 v[28:29], v[4:5]
	v_mov_b64_e32 v[24:25], v[12:13]
	v_mov_b64_e32 v[32:33], v[16:17]
	s_and_saveexec_b64 s[46:47], vcc
	s_cbranch_execz .LBB0_476
	s_movk_i32 s8, 0x80
	v_cmp_ne_u32_e64 s[8:9], s8, v45
	s_and_saveexec_b64 s[18:19], s[8:9]
	s_xor_b64 s[8:9], exec, s[18:19]
	s_cbranch_execz .LBB0_484
	v_sub_u32_e32 v0, v1, v45
	v_add_u32_e32 v80, 0x100, v0
	v_lshlrev_b64 v[0:1], 2, v[80:81]
	v_lshl_add_u64 v[2:3], v[2:3], 0, v[0:1]
	v_lshl_add_u64 v[0:1], v[40:41], 0, v[0:1]
	global_load_dword v46, v[2:3], off
	global_load_dword v47, v[0:1], off

; #define LAS __attribute__((address_space(3)))
; __device__ __forceinline__ int otid() { int t = threadIdx.x; asm volatile("" : "+v"(t)); return t; }
; __device__ __forceinline__ unsigned xb_add(unsigned* p, unsigned v) { return __hip_atomic_fetch_add(p, v, __ATOMIC_RELAXED, __HIP_MEMORY_SCOPE_AGENT); }
; __device__ __forceinline__ void gbar(unsigned* bar, unsigned n, volatile LAS unsigned* st) {
;   asm volatile("s_waitcnt vmcnt(0)" ::: "memory");
;   __syncthreads();
;   if (otid() == 0) {
;     __builtin_amdgcn_s_waitcnt(0);
;     const unsigned x = st[0], nloc = st[1], nx = st[2];
;     const unsigned old = xb_add(&bar[XB_XSUB(x)], 1u);
;     unsigned sp = 0;
;     if (old + 1u == (n + 1u) * nloc) {
; __device__ __forceinline__ unsigned long long karg(int i) {
;   const volatile unsigned long long* ka = (const volatile unsigned long long*)__builtin_amdgcn_kernarg_segment_ptr();
;   const unsigned long long v = ka[i];
;   return ((unsigned long long)__builtin_amdgcn_readfirstlane((unsigned)(v >> 32)) << 32) | (unsigned)__builtin_amdgcn_readfirstlane((unsigned)v);
.LBB0_489:
	s_or_b64 exec, exec, s[36:37]
	v_mov_b64_e32 v[0:1], s[10:11]
	global_load_dwordx2 v[0:1], v[0:1], off sc0 sc1
	s_waitcnt vmcnt(0)
	s_waitcnt vmcnt(0)
	v_mov_b32_e32 v2, v252
	s_waitcnt lgkmcnt(0)
	s_barrier
	v_readfirstlane_b32 s0, v1
	v_readfirstlane_b32 s1, v0
	v_cmp_eq_u32_e32 vcc, 0, v2
	s_and_saveexec_b64 s[2:3], vcc
	s_cbranch_execz .LBB0_536
	v_readlane_b32 s6, v255, 15
	s_waitcnt vmcnt(0) expcnt(0) lgkmcnt(0)
	s_add_u32 s4, s1, 0x4cc80000
	v_mov_b32_e32 v0, s6
	ds_read_b32 v1, v0
	v_readlane_b32 s6, v255, 16
	s_addc_u32 s5, s0, 0
	s_waitcnt lgkmcnt(0)
	v_lshlrev_b32_e32 v5, 6, v1
	v_add_u32_e32 v80, 0x440, v5
	v_mov_b32_e32 v0, s6
	v_readlane_b32 s6, v255, 17
	v_lshlrev_b64 v[2:3], 2, v[80:81]
	ds_read_b32 v4, v0
	v_mov_b32_e32 v0, s6
	v_lshl_add_u64 v[2:3], s[4:5], 0, v[2:3]
	ds_read_b32 v0, v0
	global_atomic_add v2, v[2:3], v230, off sc0
	v_add_u32_e32 v1, 4, v158
	s_waitcnt lgkmcnt(0)
	v_mul_lo_u32 v3, v4, v1
	v_add_u32_e32 v80, 0x840, v5
	s_waitcnt vmcnt(0)
	v_add_u32_e32 v2, 1, v2
	v_cmp_ne_u32_e32 vcc, v2, v3
	s_and_saveexec_b64 s[6:7], vcc
	s_xor_b64 s[6:7], exec, s[6:7]
	s_cbranch_execz .LBB0_513
	v_lshlrev_b64 v[0:1], 2, v[80:81]
	v_lshl_add_u64 v[0:1], s[4:5], 0, v[0:1]
	s_mov_b32 s13, 0x1000000
	s_mov_b64 s[8:9], 0
	s_branch .LBB0_501

; __device__ __forceinline__ unsigned xb_ld(unsigned* p) { return __hip_atomic_load(p, __ATOMIC_RELAXED, __HIP_MEMORY_SCOPE_AGENT); }
; __device__ __forceinline__ void gbar(unsigned* bar, unsigned n, volatile LAS unsigned* st) {
;     ...
;     } else {
;       while (xb_ld(&bar[XB_XGEN(x)]) <= n) { __builtin_amdgcn_s_sleep(1); if (++sp > (1u << 24)) break; }
.LBB0_501:
	global_load_dword v2, v[0:1], off sc1
	s_or_b64 s[36:37], s[36:37], exec
	s_waitcnt vmcnt(0) lgkmcnt(0)
	v_cmp_le_u32_e32 vcc, v2, v42
	s_and_saveexec_b64 s[38:39], vcc
	s_cbranch_execz .LBB0_500
	s_cmp_lg_u32 s13, 0
	s_sleep 1
	s_cbranch_scc0 .LBB0_511
	global_load_dword v2, v[0:1], off sc1
	s_mov_b64 s[18:19], -1
	s_waitcnt vmcnt(0) lgkmcnt(0)
	v_cmp_le_u32_e32 vcc, v2, v42
	s_and_saveexec_b64 s[40:41], vcc
	s_cbranch_execz .LBB0_498
	s_sleep 1
	global_load_dword v2, v[0:1], off sc1
	s_waitcnt vmcnt(0) lgkmcnt(0)
	v_cmp_le_u32_e32 vcc, v2, v42
	s_and_saveexec_b64 s[42:43], vcc
	s_cbranch_execz .LBB0_497
	s_sleep 1
	global_load_dword v2, v[0:1], off sc1
	s_waitcnt vmcnt(0) lgkmcnt(0)
	v_cmp_le_u32_e32 vcc, v2, v42
	s_and_saveexec_b64 s[44:45], vcc
	s_cbranch_execz .LBB0_496
	s_sleep 1
	global_load_dword v2, v[0:1], off sc1
	s_waitcnt vmcnt(0) lgkmcnt(0)
	v_cmp_le_u32_e32 vcc, v2, v42
	s_and_saveexec_b64 s[46:47], vcc
	s_cbranch_execz .LBB0_495
	s_sleep 1
	global_load_dword v2, v[0:1], off sc1
	s_waitcnt vmcnt(0) lgkmcnt(0)
	v_cmp_le_u32_e32 vcc, v2, v42
	s_and_saveexec_b64 s[68:69], vcc
	s_cbranch_execz .LBB0_494
	s_sleep 1
	global_load_dword v2, v[0:1], off sc1
	s_mov_b64 s[48:49], -1
	s_waitcnt vmcnt(0) lgkmcnt(0)
	v_cmp_le_u32_e32 vcc, v2, v42
	s_and_saveexec_b64 s[18:19], vcc
	s_cbranch_execz .LBB0_493
	s_sleep 1
	global_load_dword v2, v[0:1], off sc1
	s_waitcnt vmcnt(0) lgkmcnt(0)
	v_cmp_le_u32_e32 vcc, v2, v42
	s_and_saveexec_b64 s[66:67], vcc
	s_cbranch_execz .LBB0_492
	s_add_i32 s13, s13, -8
	s_xor_b64 s[48:49], exec, -1
	s_sleep 1
	s_branch .LBB0_492

; __device__ __forceinline__ unsigned xb_add(unsigned* p, unsigned v) { return __hip_atomic_fetch_add(p, v, __ATOMIC_RELAXED, __HIP_MEMORY_SCOPE_AGENT); }
; __device__ __forceinline__ void gbar(unsigned* bar, unsigned n, volatile LAS unsigned* st) {
;     ...
;     if (old + 1u == (n + 1u) * nloc) {
;       __builtin_amdgcn_fence(__ATOMIC_RELEASE, "agent");
;       asm volatile("s_waitcnt vmcnt(0)" ::: "memory");
;       xb_add(&bar[XB_TOP], 1u);
.LBB0_513:
	s_andn2_saveexec_b64 s[6:7], s[6:7]
	s_cbranch_execz .LBB0_536
	v_mov_b32_e32 v2, s1
	v_add_co_u32_e32 v2, vcc, 0x4cc83000, v2
	v_mov_b32_e32 v3, s0
	buffer_wbl2 sc1
	s_waitcnt vmcnt(0)
	v_addc_co_u32_e32 v3, vcc, 0, v3, vcc
	global_atomic_add v[2:3], v230, off offset:256
	s_add_u32 s6, s1, 0x4cc83100
	s_addc_u32 s7, s0, 0
	v_mul_lo_u32 v0, v0, v1
	s_mov_b32 s0, 0x1000000
	s_mov_b64 s[8:9], 0
	s_branch .LBB0_524

; __device__ __forceinline__ unsigned xb_ld(unsigned* p) { return __hip_atomic_load(p, __ATOMIC_RELAXED, __HIP_MEMORY_SCOPE_AGENT); }
; __device__ __forceinline__ void gbar(unsigned* bar, unsigned n, volatile LAS unsigned* st) {
;     ...
;       while (xb_ld(&bar[XB_TOP]) < (n + 1u) * nx) { __builtin_amdgcn_s_sleep(1); if (++sp > (1u << 24)) break; }
.LBB0_524:
	v_mov_b64_e32 v[2:3], s[6:7]
	global_load_dword v1, v[2:3], off sc1
	s_or_b64 s[36:37], s[36:37], exec
	s_waitcnt vmcnt(0) lgkmcnt(0)
	v_cmp_lt_u32_e32 vcc, v1, v0
	s_and_saveexec_b64 s[38:39], vcc
	s_cbranch_execz .LBB0_523
	s_cmp_lg_u32 s0, 0
	s_sleep 1
	s_cbranch_scc0 .LBB0_534
	v_mov_b64_e32 v[2:3], s[6:7]
	global_load_dword v1, v[2:3], off sc1
	s_mov_b64 s[18:19], -1
	s_waitcnt vmcnt(0) lgkmcnt(0)
	v_cmp_lt_u32_e32 vcc, v1, v0
	s_and_saveexec_b64 s[40:41], vcc
	s_cbranch_execz .LBB0_521
	v_mov_b64_e32 v[2:3], s[6:7]
	s_sleep 1
	global_load_dword v1, v[2:3], off sc1
	s_waitcnt vmcnt(0) lgkmcnt(0)
	v_cmp_lt_u32_e32 vcc, v1, v0
	s_and_saveexec_b64 s[42:43], vcc
	s_cbranch_execz .LBB0_520
	v_mov_b64_e32 v[2:3], s[6:7]
	s_sleep 1
	global_load_dword v1, v[2:3], off sc1
	s_waitcnt vmcnt(0) lgkmcnt(0)
	v_cmp_lt_u32_e32 vcc, v1, v0
	s_and_saveexec_b64 s[44:45], vcc
	s_cbranch_execz .LBB0_519
	v_mov_b64_e32 v[2:3], s[6:7]
	s_sleep 1
	global_load_dword v1, v[2:3], off sc1
	s_waitcnt vmcnt(0) lgkmcnt(0)
	v_cmp_lt_u32_e32 vcc, v1, v0
	s_and_saveexec_b64 s[46:47], vcc
	s_cbranch_execz .LBB0_518
	v_mov_b64_e32 v[2:3], s[6:7]
	s_sleep 1
	global_load_dword v1, v[2:3], off sc1
	s_waitcnt vmcnt(0) lgkmcnt(0)
	v_cmp_lt_u32_e32 vcc, v1, v0
	s_and_saveexec_b64 s[68:69], vcc
	s_cbranch_execz .LBB0_517
	v_mov_b64_e32 v[2:3], s[6:7]
	s_sleep 1
	global_load_dword v1, v[2:3], off sc1
	s_mov_b64 s[48:49], -1
	s_waitcnt vmcnt(0) lgkmcnt(0)
	v_cmp_lt_u32_e32 vcc, v1, v0
	s_and_saveexec_b64 s[18:19], vcc
	s_cbranch_execz .LBB0_516
	v_mov_b64_e32 v[2:3], s[6:7]
	s_sleep 1
	global_load_dword v1, v[2:3], off sc1
	s_waitcnt vmcnt(0) lgkmcnt(0)
	v_cmp_lt_u32_e32 vcc, v1, v0
	s_and_saveexec_b64 s[66:67], vcc
	s_cbranch_execz .LBB0_515
	s_add_i32 s0, s0, -8
	s_xor_b64 s[48:49], exec, -1
	s_sleep 1
	s_branch .LBB0_515

; #define LAS __attribute__((address_space(3)))
; __device__ __forceinline__ int otid() { int t = threadIdx.x; asm volatile("" : "+v"(t)); return t; }
;   __device__ __forceinline__ bool next(int i, Unit& u) const {
;     const long Ll = (long)i * G + c;
;     if (Ll >= total) return false;
;     const int L = (int)Ll;
;     int pm, pn;
;     u.pad0 = 0; u.pad1 = 0;
;     if (mode == 0) {
;       tile_order(L, nM, nN, pm, pn);
;       if (p1 == -77 && pm >= p0) ++pm;
;       u.a0 = A + (size_t)pm * a_t; u.b0 = B + (size_t)pn * b_t; u.b1 = u.b0 + b_h;
;       u.r0 = pm * 256; u.c0 = pn * 256; u.C = C;
; __device__ __forceinline__ int build_units(LAS unsigned char* lds, const Map& m) {
;   LAS Unit* ul = (LAS Unit*)(lds + STAGE_BYTES);
;   __syncthreads();
;   const int tid_ = otid();
;   if (tid_ < MAX_UNITS) { Unit u; if (m.next(tid_, u)) {
;       LAS unsigned long long* w = (LAS unsigned long long*)(ul + tid_);
;       w[0] = (unsigned long long)u.a0; w[1] = (unsigned long long)u.b0; w[2] = (unsigned long long)u.b1; w[3] = (unsigned long long)u.C;
;       w[4] = ((unsigned long long)(unsigned)u.c0 << 32) | (unsigned)u.r0; } }
;   __syncthreads();
;   const long rest = (long)m.total - m.c;
;   int n = rest > 0 ? (int)((rest + m.G - 1) / m.G) : 0;
;   return n < MAX_UNITS ? n : MAX_UNITS;
; }
.LBB0_535:
	s_or_b64 exec, exec, s[8:9]
	v_lshlrev_b64 v[0:1], 2, v[80:81]
	v_lshl_add_u64 v[0:1], s[4:5], 0, v[0:1]
	buffer_inv sc1
	global_atomic_add v[0:1], v230, off
	s_waitcnt vmcnt(0)
.LBB0_536:
	s_or_b64 exec, exec, s[2:3]
	v_mov_b64_e32 v[0:1], s[10:11]
	s_waitcnt lgkmcnt(0)
	s_barrier
	global_load_dwordx2 v[2:3], v[0:1], off sc0 sc1
	s_waitcnt vmcnt(0) lgkmcnt(0)
	v_readfirstlane_b32 s0, v3
	v_readfirstlane_b32 s1, v2
	global_load_dwordx2 v[2:3], v[0:1], off sc0 sc1
	s_waitcnt vmcnt(0) lgkmcnt(0)
	v_readfirstlane_b32 s3, v3
	v_readfirstlane_b32 s2, v2
	global_load_dwordx2 v[2:3], v[0:1], off sc0 sc1
	s_waitcnt vmcnt(0) lgkmcnt(0)
	v_readfirstlane_b32 s9, v2
	v_mov_b32_e32 v2, s74
	ds_read_b32 v2, v2
	v_readfirstlane_b32 s8, v3
	s_waitcnt lgkmcnt(0)
	v_readfirstlane_b32 s13, v2
	global_load_dwordx2 v[2:3], v[0:1], off sc0 sc1
	s_waitcnt vmcnt(0) lgkmcnt(0)
	v_readfirstlane_b32 s29, v2
	global_load_dwordx2 v[0:1], v[0:1], off sc0 sc1
	s_waitcnt vmcnt(0)
	v_mov_b32_e32 v2, v252
	v_readfirstlane_b32 s28, v3
	s_waitcnt lgkmcnt(0)
	s_barrier
	v_readfirstlane_b32 s30, v1
	v_readfirstlane_b32 s31, v0
	v_cmp_gt_i32_e32 vcc, 40, v2
	s_and_saveexec_b64 s[4:5], vcc
	s_cbranch_execz .LBB0_543
	s_ashr_i32 s6, s13, 31
	v_mov_b32_e32 v0, s13
	v_mov_b32_e32 v1, s6
	v_mad_i64_i32 v[0:1], s[6:7], v2, s20, v[0:1]
	v_cmp_gt_i64_e32 vcc, s[70:71], v[0:1]
	s_and_b64 exec, exec, vcc
	s_cbranch_execz .LBB0_543
	v_ashrrev_i32_e32 v1, 31, v0
	v_lshrrev_b32_e32 v1, 29, v1
	v_add_u32_e32 v1, v0, v1
	v_and_b32_e32 v3, -8, v1
	v_sub_u32_e32 v3, v0, v3
	v_cmp_lt_i32_e32 vcc, -1, v3
	s_and_saveexec_b64 s[6:7], vcc
	s_xor_b64 s[6:7], exec, s[6:7]
	v_lshlrev_b32_e32 v0, 6, v3
	s_andn2_saveexec_b64 s[6:7], s[6:7]
	v_lshl_add_u32 v0, v3, 6, v3
	s_or_b64 exec, exec, s[6:7]
	v_ashrrev_i32_e32 v1, 3, v1
	v_add_u32_e32 v0, v0, v1
	v_ashrrev_i32_e32 v1, 31, v0
	v_lshrrev_b32_e32 v1, 27, v1
	v_add_u32_e32 v1, v0, v1
	v_ashrrev_i32_e32 v3, 5, v1
	v_lshlrev_b32_e32 v3, 2, v3
	v_sub_u32_e32 v4, 64, v3
	v_min_i32_e32 v4, 4, v4
	v_sub_u32_e32 v5, 0, v4
	v_max_i32_e32 v5, v4, v5
	v_cvt_f32_u32_e32 v6, v5
	v_and_b32_e32 v1, 0xffffffe0, v1
	v_sub_u32_e32 v8, 0, v5
	v_sub_u32_e32 v1, v0, v1
	v_rcp_iflag_f32_e32 v6, v6
	v_sub_u32_e32 v0, 0, v1
	v_max_i32_e32 v0, v1, v0
	v_xor_b32_e32 v7, v1, v4
	v_mul_f32_e32 v6, 0x4f7ffffe, v6
	v_cvt_u32_f32_e32 v6, v6
	v_ashrrev_i32_e32 v7, 31, v7
	v_mov_b32_e32 v80, v81
	v_mul_lo_u32 v8, v8, v6
	v_mul_hi_u32 v8, v6, v8
	v_add_u32_e32 v6, v6, v8
	v_mul_hi_u32 v6, v0, v6
	v_mul_lo_u32 v8, v6, v5
	v_sub_u32_e32 v0, v0, v8
	v_add_u32_e32 v9, 1, v6
	v_cmp_ge_u32_e32 vcc, v0, v5
	v_sub_u32_e32 v8, v0, v5
	s_nop 0
	v_cndmask_b32_e32 v6, v6, v9, vcc
	v_cndmask_b32_e32 v0, v0, v8, vcc
	v_add_u32_e32 v8, 1, v6
	v_cmp_ge_u32_e32 vcc, v0, v5
	s_nop 1
	v_cndmask_b32_e32 v0, v6, v8, vcc
	v_xor_b32_e32 v0, v0, v7
	v_sub_u32_e32 v0, v0, v7
	v_mul_lo_u32 v4, v0, v4
	v_sub_u32_e32 v1, v1, v4
	v_add_u32_e32 v6, v3, v1
	v_ashrrev_i32_e32 v1, 31, v0
	v_lshlrev_b64 v[4:5], 21, v[0:1]
	v_lshl_add_u64 v[10:11], s[2:3], 0, v[4:5]
	s_mov_b64 s[2:3], 0x5000000
	v_lshl_add_u64 v[4:5], v[10:11], 0, s[2:3]
	s_mov_b64 s[2:3], 0x5100000
	v_lshl_add_u64 v[78:79], v[10:11], 0, s[2:3]
	v_mad_u64_u32 v[2:3], s[2:3], v2, 48, v[232:233]
	v_ashrrev_i32_e32 v7, 31, v6
	s_add_u32 s2, s1, 0x251c0000
	v_lshlrev_b64 v[8:9], 21, v[6:7]
	s_addc_u32 s3, s0, 0
	v_lshlrev_b32_e32 v6, 8, v6
	v_add_u32_e32 v1, 0x20000, v2
	v_lshl_add_u64 v[2:3], s[2:3], 0, v[8:9]
	v_lshlrev_b32_e32 v7, 8, v0
	ds_write_b128 v1, v[2:5]
	ds_write_b128 v1, v[78:81] offset:16
	ds_write_b64 v1, v[6:7] offset:32

; #define LAS __attribute__((address_space(3)))
; __device__ __forceinline__ int otid() { int t = threadIdx.x; asm volatile("" : "+v"(t)); return t; }
;   __device__ __forceinline__ bool next(int i, Unit& u) const {
;     const long Ll = (long)i * G + c;
;     if (Ll >= total) return false;
;     const int L = (int)Ll;
;     int pm, pn;
;     u.pad0 = 0; u.pad1 = 0;
;     if (mode == 0) {
;       tile_order(L, nM, nN, pm, pn);
;       if (p1 == -77 && pm >= p0) ++pm;
;       u.a0 = A + (size_t)pm * a_t; u.b0 = B + (size_t)pn * b_t; u.b1 = u.b0 + b_h;
;       u.r0 = pm * 256; u.c0 = pn * 256; u.C = C;
; __device__ __forceinline__ int build_units(LAS unsigned char* lds, const Map& m) {
;   LAS Unit* ul = (LAS Unit*)(lds + STAGE_BYTES);
;   __syncthreads();
;   const int tid_ = otid();
;   if (tid_ < MAX_UNITS) { Unit u; if (m.next(tid_, u)) {
;       LAS unsigned long long* w = (LAS unsigned long long*)(ul + tid_);
;       w[0] = (unsigned long long)u.a0; w[1] = (unsigned long long)u.b0; w[2] = (unsigned long long)u.b1; w[3] = (unsigned long long)u.C;
;       w[4] = ((unsigned long long)(unsigned)u.c0 << 32) | (unsigned)u.r0; } }
;   __syncthreads();
;   const long rest = (long)m.total - m.c;
;   int n = rest > 0 ? (int)((rest + m.G - 1) / m.G) : 0;
;   return n < MAX_UNITS ? n : MAX_UNITS;
; }
.LBB0_575:
	s_and_b64 vcc, exec, s[2:3]
	s_cbranch_vccz .LBB0_865
	v_readlane_b32 s0, v255, 0
	v_readlane_b32 s1, v255, 1
	v_mov_b32_e32 v2, s74
	s_waitcnt lgkmcnt(0)
	v_mov_b64_e32 v[0:1], s[0:1]
	global_load_dwordx2 v[4:5], v[0:1], off offset:120 sc0 sc1
	s_waitcnt vmcnt(0)
	global_load_dwordx2 v[6:7], v[0:1], off offset:120 sc0 sc1
	s_waitcnt vmcnt(0)
	global_load_dwordx2 v[8:9], v[0:1], off offset:120 sc0 sc1
	s_waitcnt vmcnt(0)
	global_load_dwordx2 v[10:11], v[0:1], off offset:48 sc0 sc1
	s_waitcnt vmcnt(0)
	ds_read_b32 v3, v2
	global_load_dwordx2 v[12:13], v[0:1], off offset:56 sc0 sc1
	s_waitcnt vmcnt(0)
	global_load_dwordx2 v[14:15], v[0:1], off offset:120 sc0 sc1
	s_waitcnt vmcnt(0)
	global_load_dwordx2 v[16:17], v[0:1], off offset:120 sc0 sc1
	s_waitcnt vmcnt(0)
	v_mov_b32_e32 v2, v252
	s_waitcnt lgkmcnt(0)
	s_barrier
	v_readfirstlane_b32 s0, v3
	s_ashr_i32 s1, s0, 31
	v_mov_b32_e32 v1, s1
	v_mov_b32_e32 v0, s0
	v_readfirstlane_b32 s8, v5
	v_mad_i64_i32 v[0:1], s[2:3], v2, s20, v[0:1]
	s_mov_b64 s[2:3], 0xc00
	v_cmp_gt_i32_e32 vcc, 40, v2
	v_cmp_gt_i64_e64 s[2:3], s[2:3], v[0:1]
	v_readfirstlane_b32 s9, v4
	v_readfirstlane_b32 s5, v7
	v_readfirstlane_b32 s4, v6
	v_readfirstlane_b32 s6, v9
	v_readfirstlane_b32 s7, v8
	v_readfirstlane_b32 s18, v11
	v_readfirstlane_b32 s19, v10
	v_readfirstlane_b32 s46, v13
	v_readfirstlane_b32 s47, v12
	v_readfirstlane_b32 s29, v15
	v_readfirstlane_b32 s31, v14
	v_readfirstlane_b32 s28, v17
	v_readfirstlane_b32 s30, v16
	s_and_b64 s[34:35], vcc, s[2:3]
	s_and_saveexec_b64 s[2:3], s[34:35]
	s_cbranch_execz .LBB0_578
	v_ashrrev_i32_e32 v1, 31, v0
	v_lshrrev_b32_e32 v1, 29, v1
	v_add_u32_e32 v1, v0, v1
	v_ashrrev_i32_e32 v3, 3, v1
	v_and_b32_e32 v1, -8, v1
	v_sub_u32_e32 v0, v0, v1
	v_cmp_gt_i32_e32 vcc, 0, v0
	v_mov_b32_e32 v1, 0x180
	v_mov_b32_e32 v4, 0x181
	v_cndmask_b32_e32 v1, v1, v4, vcc
	v_mul_lo_u32 v0, v0, v1
	v_add_u32_e32 v0, v0, v3
	s_mov_b32 s13, 0x2aaaaaab
	v_mul_hi_i32 v1, v0, s13
	v_lshrrev_b32_e32 v3, 31, v1
	v_ashrrev_i32_e32 v1, 5, v1
	v_add_u32_e32 v1, v1, v3
	v_lshlrev_b32_e32 v3, 2, v1
	v_sub_u32_e32 v4, 64, v3
	v_min_i32_e32 v4, 4, v4
	v_sub_u32_e32 v5, 0, v4
	v_max_i32_e32 v5, v4, v5
	v_cvt_f32_u32_e32 v6, v5
	s_movk_i32 s13, 0xc0
	v_mul_lo_u32 v1, v1, s13
	v_sub_u32_e32 v8, 0, v5
	v_rcp_iflag_f32_e32 v6, v6
	v_sub_u32_e32 v0, v0, v1
	v_sub_u32_e32 v1, 0, v0
	v_max_i32_e32 v1, v0, v1
	v_mul_f32_e32 v6, 0x4f7ffffe, v6
	v_cvt_u32_f32_e32 v6, v6
	v_xor_b32_e32 v7, v0, v4
	v_ashrrev_i32_e32 v7, 31, v7
	v_mul_lo_u32 v8, v8, v6
	v_mul_hi_u32 v8, v6, v8
	v_add_u32_e32 v6, v6, v8
	v_mul_hi_u32 v6, v1, v6
	v_mul_lo_u32 v8, v6, v5
	v_sub_u32_e32 v1, v1, v8
	v_add_u32_e32 v8, 1, v6
	v_cmp_ge_u32_e32 vcc, v1, v5
	s_nop 1
	v_cndmask_b32_e32 v6, v6, v8, vcc
	v_sub_u32_e32 v8, v1, v5
	v_cndmask_b32_e32 v1, v1, v8, vcc
	v_add_u32_e32 v8, 1, v6
	v_cmp_ge_u32_e32 vcc, v1, v5
	s_nop 1
	v_cndmask_b32_e32 v1, v6, v8, vcc
	v_xor_b32_e32 v1, v1, v7
	v_sub_u32_e32 v6, v1, v7
	v_mul_lo_u32 v1, v6, v4
	v_sub_u32_e32 v0, v0, v1
	v_ashrrev_i32_e32 v7, 31, v6
	v_add_u32_e32 v8, v3, v0
	v_lshlrev_b64 v[0:1], 20, v[6:7]
	v_lshl_add_u64 v[4:5], s[4:5], 0, v[0:1]
	s_mov_b64 s[4:5], 0x80000
	v_lshl_add_u64 v[0:1], v[4:5], 0, s[4:5]
	v_mad_u64_u32 v[2:3], s[4:5], v2, 48, v[232:233]
	s_lshl_b32 s4, s90, 1
	s_or_b32 s4, s4, 0xb920000
	v_ashrrev_i32_e32 v9, 31, v8
	s_add_u32 s4, s4, s9
	v_lshlrev_b64 v[10:11], 20, v[8:9]
	s_addc_u32 s5, 0, s8
	v_add_u32_e32 v7, 0x20000, v2
	v_lshl_add_u64 v[2:3], s[4:5], 0, v[10:11]
	s_add_u32 s4, s7, 0x18180000
	s_addc_u32 s5, s6, 0
	v_lshlrev_b32_e32 v8, 8, v8
	ds_write_b128 v7, v[2:5]
	v_mov_b32_e32 v2, s4
	v_mov_b32_e32 v3, s5
	v_lshlrev_b32_e32 v9, 8, v6
	ds_write_b128 v7, v[0:3] offset:16
	ds_write_b64 v7, v[8:9] offset:32

; #define LAS __attribute__((address_space(3)))
; __device__ __forceinline__ int otid() { int t = threadIdx.x; asm volatile("" : "+v"(t)); return t; }
;   __device__ __forceinline__ bool next(int i, Unit& u) const {
;     const long Ll = (long)i * G + c;
;     if (Ll >= total) return false;
;     const int L = (int)Ll;
;     int pm, pn;
;     u.pad0 = 0; u.pad1 = 0;
;     if (mode == 0) {
;       tile_order(L, nM, nN, pm, pn);
;       if (p1 == -77 && pm >= p0) ++pm;
;       u.a0 = A + (size_t)pm * a_t; u.b0 = B + (size_t)pn * b_t; u.b1 = u.b0 + b_h;
;       u.r0 = pm * 256; u.c0 = pn * 256; u.C = C;
; __device__ __forceinline__ int build_units(LAS unsigned char* lds, const Map& m) {
;   LAS Unit* ul = (LAS Unit*)(lds + STAGE_BYTES);
;   __syncthreads();
;   const int tid_ = otid();
;   if (tid_ < MAX_UNITS) { Unit u; if (m.next(tid_, u)) {
;       LAS unsigned long long* w = (LAS unsigned long long*)(ul + tid_);
;       w[0] = (unsigned long long)u.a0; w[1] = (unsigned long long)u.b0; w[2] = (unsigned long long)u.b1; w[3] = (unsigned long long)u.C;
;       w[4] = ((unsigned long long)(unsigned)u.c0 << 32) | (unsigned)u.r0; } }
;   __syncthreads();
;   const long rest = (long)m.total - m.c;
;   int n = rest > 0 ? (int)((rest + m.G - 1) / m.G) : 0;
;   return n < MAX_UNITS ? n : MAX_UNITS;
; }
.LBB0_609:
	v_mov_b64_e32 v[0:1], s[10:11]
	global_load_dwordx2 v[2:3], v[0:1], off sc0 sc1
	s_waitcnt vmcnt(0) lgkmcnt(0)
	v_readfirstlane_b32 s0, v3
	v_readfirstlane_b32 s1, v2
	global_load_dwordx2 v[2:3], v[0:1], off sc0 sc1
	s_waitcnt vmcnt(0) lgkmcnt(0)
	v_readfirstlane_b32 s3, v3
	v_readfirstlane_b32 s2, v2
	global_load_dwordx2 v[2:3], v[0:1], off sc0 sc1
	s_waitcnt vmcnt(0) lgkmcnt(0)
	v_readfirstlane_b32 s18, v2
	v_mov_b32_e32 v2, s74
	ds_read_b32 v2, v2
	global_load_dwordx2 v[0:1], v[0:1], off sc0 sc1
	s_waitcnt vmcnt(0)
	v_readfirstlane_b32 s13, v3
	s_waitcnt lgkmcnt(0)
	s_barrier
	v_readfirstlane_b32 s19, v2
	v_mov_b32_e32 v2, v252
	v_readfirstlane_b32 s28, v1
	v_readfirstlane_b32 s29, v0
	v_cmp_gt_i32_e32 vcc, 40, v2
	s_and_saveexec_b64 s[4:5], vcc
	s_cbranch_execz .LBB0_616
	s_ashr_i32 s8, s19, 31
	v_mov_b32_e32 v0, s19
	v_mov_b32_e32 v1, s8
	v_mad_i64_i32 v[0:1], s[8:9], v2, s20, v[0:1]
	v_cmp_gt_i64_e32 vcc, s[70:71], v[0:1]
	s_and_b64 exec, exec, vcc
	s_cbranch_execz .LBB0_616
	v_ashrrev_i32_e32 v1, 31, v0
	v_lshrrev_b32_e32 v1, 29, v1
	v_add_u32_e32 v1, v0, v1
	v_and_b32_e32 v3, -8, v1
	v_sub_u32_e32 v3, v0, v3
	v_cmp_lt_i32_e32 vcc, -1, v3
	s_and_saveexec_b64 s[8:9], vcc
	s_xor_b64 s[8:9], exec, s[8:9]
	v_lshlrev_b32_e32 v0, 6, v3
	s_andn2_saveexec_b64 s[8:9], s[8:9]
	v_lshl_add_u32 v0, v3, 6, v3
	s_or_b64 exec, exec, s[8:9]
	v_ashrrev_i32_e32 v1, 3, v1
	v_add_u32_e32 v0, v0, v1
	v_ashrrev_i32_e32 v1, 31, v0
	v_lshrrev_b32_e32 v1, 27, v1
	v_add_u32_e32 v1, v0, v1
	v_ashrrev_i32_e32 v3, 5, v1
	v_lshlrev_b32_e32 v3, 2, v3
	v_sub_u32_e32 v4, 64, v3
	v_min_i32_e32 v4, 4, v4
	v_sub_u32_e32 v5, 0, v4
	v_max_i32_e32 v5, v4, v5
	v_cvt_f32_u32_e32 v6, v5
	v_and_b32_e32 v1, 0xffffffe0, v1
	v_sub_u32_e32 v8, 0, v5
	v_sub_u32_e32 v0, v0, v1
	v_rcp_iflag_f32_e32 v6, v6
	v_sub_u32_e32 v1, 0, v0
	v_max_i32_e32 v1, v0, v1
	v_xor_b32_e32 v7, v0, v4
	v_mul_f32_e32 v6, 0x4f7ffffe, v6
	v_cvt_u32_f32_e32 v6, v6
	v_ashrrev_i32_e32 v7, 31, v7
	v_mul_lo_u32 v8, v8, v6
	v_mul_hi_u32 v8, v6, v8
	v_add_u32_e32 v6, v6, v8
	v_mul_hi_u32 v6, v1, v6
	v_mul_lo_u32 v8, v6, v5
	v_sub_u32_e32 v1, v1, v8
	v_add_u32_e32 v9, 1, v6
	v_cmp_ge_u32_e32 vcc, v1, v5
	v_sub_u32_e32 v8, v1, v5
	s_nop 0
	v_cndmask_b32_e32 v6, v6, v9, vcc
	v_cndmask_b32_e32 v1, v1, v8, vcc
	v_add_u32_e32 v8, 1, v6
	v_cmp_ge_u32_e32 vcc, v1, v5
	s_nop 1
	v_cndmask_b32_e32 v1, v6, v8, vcc
	v_xor_b32_e32 v1, v1, v7
	v_sub_u32_e32 v6, v1, v7
	v_mul_lo_u32 v1, v6, v4
	v_sub_u32_e32 v0, v0, v1
	v_ashrrev_i32_e32 v7, 31, v6
	v_add_u32_e32 v8, v3, v0
	v_lshlrev_b64 v[0:1], 20, v[6:7]
	v_lshl_add_u64 v[0:1], s[2:3], 0, v[0:1]
	s_mov_b64 s[2:3], 0x3000000
	v_lshl_add_u64 v[4:5], v[0:1], 0, s[2:3]
	s_mov_b64 s[2:3], 0x3080000
	v_lshl_add_u64 v[0:1], v[0:1], 0, s[2:3]
	v_mad_u64_u32 v[2:3], s[2:3], v2, 48, v[232:233]
	s_lshl_b32 s2, s90, 1
	s_or_b32 s2, s2, 0xb920000
	s_add_u32 s2, s2, s1
	v_ashrrev_i32_e32 v9, 31, v8
	s_addc_u32 s3, 0, s0
	v_lshlrev_b64 v[10:11], 20, v[8:9]
	s_add_u32 s0, s18, 0x3c180000
	v_add_u32_e32 v7, 0x20000, v2
	v_lshl_add_u64 v[2:3], s[2:3], 0, v[10:11]
	s_addc_u32 s1, s13, 0
	v_lshlrev_b32_e32 v8, 8, v8
	ds_write_b128 v7, v[2:5]
	v_mov_b32_e32 v2, s0
	v_mov_b32_e32 v3, s1
	v_lshlrev_b32_e32 v9, 8, v6
	ds_write_b128 v7, v[0:3] offset:16
	ds_write_b64 v7, v[8:9] offset:32

; #define LAS __attribute__((address_space(3)))
; __device__ __forceinline__ int otid() { int t = threadIdx.x; asm volatile("" : "+v"(t)); return t; }
;   __device__ __forceinline__ bool next(int i, Unit& u) const {
;     ...
;     } else if (mode == 1) {
;       tile_order(L, nM, nN, pm, pn);
;       u.a0 = A + (size_t)pm * a_t;
;       const int lg = p0, S = p1, Lsub = S >> lg;
;       { const int col = (2 * pn) * 128, seq = col / S, rem = col % S, r = rem / Lsub, m0 = rem % Lsub; u.b0 = B + ((size_t)seq * S + ((size_t)m0 << lg) + r) * 4096; }
;       { const int col = (2 * pn + 1) * 128, seq = col / S, rem = col % S, r = rem / Lsub, m0 = rem % Lsub; u.b1 = B + ((size_t)seq * S + ((size_t)m0 << lg) + r) * 4096; }
;       u.r0 = pm * 256; u.c0 = pn * 256; u.C = C;
; __device__ __forceinline__ int build_units(LAS unsigned char* lds, const Map& m) {
;   LAS Unit* ul = (LAS Unit*)(lds + STAGE_BYTES);
;   __syncthreads();
;   const int tid_ = otid();
;   if (tid_ < MAX_UNITS) { Unit u; if (m.next(tid_, u)) {
;       LAS unsigned long long* w = (LAS unsigned long long*)(ul + tid_);
;       w[0] = (unsigned long long)u.a0; w[1] = (unsigned long long)u.b0; w[2] = (unsigned long long)u.b1; w[3] = (unsigned long long)u.C;
;       w[4] = ((unsigned long long)(unsigned)u.c0 << 32) | (unsigned)u.r0; } }
;   __syncthreads();
;   const long rest = (long)m.total - m.c;
;   int n = rest > 0 ? (int)((rest + m.G - 1) / m.G) : 0;
;   return n < MAX_UNITS ? n : MAX_UNITS;
; }
.LBB0_634:
	v_mov_b64_e32 v[0:1], s[10:11]
	global_load_dwordx2 v[2:3], v[0:1], off sc0 sc1
	s_waitcnt vmcnt(0)
	s_lshl_b32 s18, s1, 1
	s_waitcnt lgkmcnt(0)
	v_readfirstlane_b32 s8, v3
	v_readfirstlane_b32 s9, v2
	global_load_dwordx2 v[2:3], v[0:1], off sc0 sc1
	s_waitcnt vmcnt(0) lgkmcnt(0)
	v_readfirstlane_b32 s30, v3
	v_readfirstlane_b32 s31, v2
	global_load_dwordx2 v[2:3], v[0:1], off sc0 sc1
	s_waitcnt vmcnt(0) lgkmcnt(0)
	v_readfirstlane_b32 s19, v2
	v_mov_b32_e32 v2, s74
	ds_read_b32 v2, v2
	global_load_dwordx2 v[0:1], v[0:1], off sc0 sc1
	s_waitcnt vmcnt(0)
	v_readfirstlane_b32 s13, v3
	s_waitcnt lgkmcnt(0)
	s_barrier
	v_readfirstlane_b32 s29, v2
	v_mov_b32_e32 v2, v252
	v_readfirstlane_b32 s0, v1
	v_readfirstlane_b32 s28, v0
	v_cmp_gt_i32_e32 vcc, 40, v2
	s_and_saveexec_b64 s[2:3], vcc
	s_cbranch_execz .LBB0_641
	s_ashr_i32 s4, s29, 31
	v_mov_b32_e32 v0, s29
	v_mov_b32_e32 v1, s4
	v_mad_i64_i32 v[0:1], s[4:5], v2, s20, v[0:1]
	v_cmp_gt_i64_e32 vcc, s[70:71], v[0:1]
	s_and_b64 exec, exec, vcc
	s_cbranch_execz .LBB0_641
	v_ashrrev_i32_e32 v1, 31, v0
	v_lshrrev_b32_e32 v1, 29, v1
	v_add_u32_e32 v1, v0, v1
	v_and_b32_e32 v3, -8, v1
	v_sub_u32_e32 v3, v0, v3
	v_cmp_lt_i32_e32 vcc, -1, v3
	s_and_saveexec_b64 s[4:5], vcc
	s_xor_b64 s[4:5], exec, s[4:5]
	v_lshlrev_b32_e32 v0, 6, v3
	s_andn2_saveexec_b64 s[4:5], s[4:5]
	v_lshl_add_u32 v0, v3, 6, v3
	s_or_b64 exec, exec, s[4:5]
	v_ashrrev_i32_e32 v1, 3, v1
	v_add_u32_e32 v0, v0, v1
	v_ashrrev_i32_e32 v1, 31, v0
	v_add_u32_sdwa v1, v0, v1 dst_sel:DWORD dst_unused:UNUSED_PAD src0_sel:DWORD src1_sel:BYTE_3
	v_ashrrev_i32_e32 v1, 8, v1
	v_lshlrev_b32_e32 v3, 2, v1
	v_sub_u32_e32 v4, 8, v3
	v_min_i32_e32 v4, 4, v4
	v_sub_u32_e32 v5, 0, v4
	v_max_i32_e32 v5, v4, v5
	v_cvt_f32_u32_e32 v6, v5
	v_mul_i32_i24_e32 v1, 0x100, v1
	v_sub_u32_e32 v8, 0, v5
	v_sub_u32_e32 v0, v0, v1
	v_rcp_iflag_f32_e32 v6, v6
	v_sub_u32_e32 v7, 0, v0
	v_max_i32_e32 v7, v0, v7
	v_xor_b32_e32 v1, v0, v4
	v_mul_f32_e32 v6, 0x4f7ffffe, v6
	v_cvt_u32_f32_e32 v6, v6
	v_ashrrev_i32_e32 v1, 31, v1
	s_lshl_b32 s22, s1, 23
	s_lshl_b32 s4, s90, 1
	v_mul_lo_u32 v8, v8, v6
	v_mul_hi_u32 v8, v6, v8
	v_add_u32_e32 v6, v6, v8
	v_mul_hi_u32 v6, v7, v6
	v_mul_lo_u32 v8, v6, v5
	v_sub_u32_e32 v7, v7, v8
	v_add_u32_e32 v8, 1, v6
	v_cmp_ge_u32_e32 vcc, v7, v5
	s_add_u32 s4, s31, s4
	s_addc_u32 s5, s30, 0
	v_cndmask_b32_e32 v6, v6, v8, vcc
	v_sub_u32_e32 v8, v7, v5
	v_cndmask_b32_e32 v7, v7, v8, vcc
	v_add_u32_e32 v8, 1, v6
	v_cmp_ge_u32_e32 vcc, v7, v5
	s_add_u32 s4, s4, 0xb920000
	s_addc_u32 s5, s5, 0
	v_cndmask_b32_e32 v5, v6, v8, vcc
	v_xor_b32_e32 v5, v5, v1
	v_sub_u32_e32 v1, v5, v1
	v_mul_lo_u32 v4, v1, v4
	v_sub_u32_e32 v0, v0, v4
	v_lshlrev_b32_e32 v9, 8, v1
	v_add_u32_e32 v6, v3, v0
	v_sub_u32_e32 v0, 0, v9
	v_max_i32_e32 v0, v9, v0
	v_bfe_i32 v3, v1, 23, 1
	v_mul_hi_u32 v1, v0, v152
	v_mul_lo_u32 v4, v1, s17
	v_sub_u32_e32 v0, v0, v4
	v_add_u32_e32 v4, 1, v1
	v_cmp_le_u32_e32 vcc, s17, v0
	s_lshr_b32 s30, s17, s18
	v_cvt_f32_i32_e32 v8, s30
	v_cndmask_b32_e32 v1, v1, v4, vcc
	v_subrev_u32_e32 v4, s17, v0
	v_cndmask_b32_e32 v0, v0, v4, vcc
	v_add_u32_e32 v4, 1, v1
	v_cmp_le_u32_e32 vcc, s17, v0
	v_rcp_iflag_f32_e32 v14, v8
	v_ashrrev_i32_e32 v7, 31, v6
	v_cndmask_b32_e32 v0, v1, v4, vcc
	v_xor_b32_e32 v0, v0, v3
	v_sub_u32_e32 v0, v0, v3
	v_mul_lo_u32 v1, v0, s17
	v_sub_u32_e32 v1, v9, v1
	v_cvt_f32_i32_sdwa v4, sext(v1) dst_sel:DWORD dst_unused:UNUSED_PAD src0_sel:WORD_0
	v_lshlrev_b64 v[10:11], 20, v[6:7]
	v_ashrrev_i32_sdwa v5, v223, sext(v1) dst_sel:DWORD dst_unused:UNUSED_PAD src0_sel:DWORD src1_sel:WORD_0
	v_or_b32_e32 v5, 1, v5
	v_mul_f32_e32 v7, v4, v14
	v_trunc_f32_e32 v7, v7
	v_cvt_i32_f32_e32 v12, v7
	v_fma_f32 v4, -v7, v8, v4
	v_cmp_ge_f32_e64 vcc, |v4|, v8
	s_add_i32 s22, s22, 0x3800000
	s_nop 0
	v_cndmask_b32_e32 v4, 0, v5, vcc
	v_add_u32_e32 v7, v12, v4
	v_mul_lo_u32 v4, v7, s30
	v_sub_u32_e32 v4, v1, v4
	v_ashrrev_i32_e32 v1, 31, v0
	v_bfe_i32 v4, v4, 0, 16
	v_bfe_i32 v12, v7, 0, 16
	v_lshlrev_b64 v[0:1], s81, v[0:1]
	v_ashrrev_i32_e32 v5, 31, v4
	v_ashrrev_i32_e32 v13, 31, v12
	v_lshlrev_b64 v[4:5], s18, v[4:5]
	v_lshl_add_u64 v[0:1], v[0:1], 0, v[12:13]
	v_lshl_add_u64 v[0:1], v[0:1], 0, v[4:5]
	v_or_b32_e32 v4, 0x80, v9
	v_sub_u32_e32 v5, 0, v4
	v_max_i32_e32 v5, v4, v5
	v_mul_hi_u32 v7, v5, v152
	v_mul_lo_u32 v12, v7, s17
	v_sub_u32_e32 v5, v5, v12
	v_add_u32_e32 v12, 1, v7
	v_cmp_le_u32_e32 vcc, s17, v5
	v_lshlrev_b64 v[0:1], 12, v[0:1]
	s_nop 0
	v_cndmask_b32_e32 v7, v7, v12, vcc
	v_subrev_u32_e32 v12, s17, v5
	v_cndmask_b32_e32 v5, v5, v12, vcc
	v_add_u32_e32 v12, 1, v7
	v_cmp_le_u32_e32 vcc, s17, v5
	s_nop 1
	v_cndmask_b32_e32 v5, v7, v12, vcc
	v_xor_b32_e32 v5, v5, v3
	v_sub_u32_e32 v12, v5, v3
	v_mul_lo_u32 v3, v12, s17
	v_sub_u32_e32 v3, v4, v3
	v_cvt_f32_i32_sdwa v7, sext(v3) dst_sel:DWORD dst_unused:UNUSED_PAD src0_sel:WORD_0
	v_lshl_add_u64 v[4:5], s[4:5], 0, v[0:1]
	v_ashrrev_i32_sdwa v0, v223, sext(v3) dst_sel:DWORD dst_unused:UNUSED_PAD src0_sel:DWORD src1_sel:WORD_0
	v_or_b32_e32 v0, 1, v0
	v_mul_f32_e32 v1, v7, v14
	v_trunc_f32_e32 v1, v1
	v_cvt_i32_f32_e32 v13, v1
	v_fma_f32 v1, -v1, v8, v7
	v_cmp_ge_f32_e64 vcc, |v1|, v8
	v_lshlrev_b32_e32 v8, 8, v6
	s_nop 0
	v_cndmask_b32_e32 v0, 0, v0, vcc
	v_add_u32_e32 v7, v13, v0
	v_mul_lo_u32 v0, v7, s30
	v_sub_u32_e32 v3, v3, v0
	v_ashrrev_i32_e32 v13, 31, v12
	v_lshlrev_b64 v[0:1], s81, v[12:13]
	v_bfe_i32 v12, v3, 0, 16
	v_bfe_i32 v14, v7, 0, 16
	v_ashrrev_i32_e32 v13, 31, v12
	v_ashrrev_i32_e32 v15, 31, v14
	v_lshlrev_b64 v[12:13], s18, v[12:13]
	v_lshl_add_u64 v[0:1], v[0:1], 0, v[14:15]
	v_lshl_add_u64 v[0:1], v[0:1], 0, v[12:13]
	v_lshlrev_b64 v[0:1], 12, v[0:1]
	v_lshl_add_u64 v[0:1], s[4:5], 0, v[0:1]
	v_mad_u64_u32 v[2:3], s[4:5], v2, 48, v[232:233]
	s_add_u32 s4, s9, s22
	s_addc_u32 s5, s8, 0
	v_add_u32_e32 v6, 0x20000, v2
	v_lshl_add_u64 v[2:3], s[4:5], 0, v[10:11]
	s_add_u32 s4, s19, 0x30180000
	s_addc_u32 s5, s13, 0
	ds_write_b128 v6, v[2:5]
	v_mov_b32_e32 v2, s4
	v_mov_b32_e32 v3, s5
	ds_write_b128 v6, v[0:3] offset:16
	ds_write_b64 v6, v[8:9] offset:32

; #define G_STAGE(bufoff, gbase, voff) do { _Pragma("unroll") for (int _i = 0; _i < 2; ++_i) { unsigned _vo = (voff)[_i]; asm volatile("" : "+v"(_vo));   \
;     __builtin_amdgcn_global_load_lds((const unsigned*)((const char*)(gbase) + _vo), (LAS unsigned*)(lds + (bufoff) + ldsw + _i * 8192), 16, 0, 0); } } while (0)
; #define G_LDA(dst, b, h) do { _Pragma("unroll") for (int m = 0; m < 4; ++m) _Pragma("unroll") for (int k = 0; k < 2; ++k) dst[m][k] = *(const LAS bf16x8*)(lds + G_SA(b, h) + aoff + m * 2048 + k * 1024); } while (0)
; #define G_LDB(dst, b, h) do { _Pragma("unroll") for (int n = 0; n < 2; ++n) _Pragma("unroll") for (int k = 0; k < 2; ++k) dst[n][k] = *(const LAS bf16x8*)(lds + G_SB(b, h) + boff + n * 2048 + k * 1024); } while (0)
; #define G_MMA(ai, bj, At, Bt) do { __builtin_amdgcn_s_setprio(1); _Pragma("unroll") for (int m = 0; m < 4; ++m) _Pragma("unroll") for (int n = 0; n < 2; ++n) _Pragma("unroll") for (int k = 0; k < 2; ++k) \
;     acc[ai][bj][m][n] = __builtin_amdgcn_mfma_f32_16x16x32_bf16(Bt[n][k], At[m][k], acc[ai][bj][m][n], 0, 0, 0); __builtin_amdgcn_s_setprio(0); } while (0)
; #define G_WAIT_V(n) asm volatile("s_waitcnt vmcnt(" #n ")" ::: "memory")
; #define G_WAIT_L(n) asm volatile("s_waitcnt lgkmcnt(" #n ")" ::: "memory")
; #define G_BAR __builtin_amdgcn_s_barrier()
; #define G_SCHED __builtin_amdgcn_sched_barrier(0)
; template <class Epi>
; __device__ __forceinline__ void gemm_phase(LAS unsigned char* lds, const int K, const unsigned lda_b, const unsigned ldb_b, const Map& M, const Epi& E) {
;     ...
;       G_LDB(B0, 0, 0); G_SCHED; G_LDA(At, 0, 0); G_STAGE(G_SA(1, 1), a1h1, voffA);
;       G_WAIT_L(8); G_BAR; G_WAIT_L(0); G_MMA(0, 0, At, B0); G_BAR; G_SCHED;
;       G_LDB(B1, 0, 1); G_STAGE(G_SB(0, 0), b2h0, voffB);
;       G_BAR; G_WAIT_L(0); G_MMA(0, 1, At, B1); G_BAR;
;       G_LDA(At, 0, 1); G_STAGE(G_SA(0, 0), a2h0, voffA);
;       G_BAR; G_WAIT_L(0); G_MMA(1, 0, At, B0); G_BAR; G_SCHED;
;       G_STAGE(G_SB(0, 1), b2h1, voffB);
;       G_WAIT_V(6); G_BAR; G_MMA(1, 1, At, B1); G_BAR;
.LBB0_651:
	s_add_u32 s22, s2, 0xfff80080
	s_addc_u32 s34, s3, -1
	s_add_u32 s35, s29, s46
	s_addc_u32 s38, s30, 0
	s_add_i32 vcc_lo, 0, 0x10000
	v_add_u32_e32 v80, vcc_lo, v158
	ds_read_b128 v[132:135], v80
	ds_read_b128 v[136:139], v80 offset:1024
	ds_read_b128 v[140:143], v80 offset:2048
	ds_read_b128 v[144:147], v80 offset:3072
	s_cmp_eq_u32 s31, 28
	s_cselect_b32 s43, s9, s34
	s_cselect_b32 s42, s8, s22
	s_cselect_b32 s45, s37, s30
	s_cselect_b32 s44, s36, s29
	v_mov_b32_e32 v80, v153
	s_cselect_b32 s39, s28, s38
	s_cselect_b32 s38, s0, s35
	s_add_u32 s68, s42, 0x80000
	ds_read_b128 v[148:151], v170
	ds_read_b128 v[172:175], v170 offset:1024
	ds_read_b128 v[190:193], v170 offset:2048
	ds_read_b128 v[194:197], v170 offset:3072
	ds_read_b128 v[198:201], v170 offset:4096
	ds_read_b128 v[202:205], v170 offset:5120
	ds_read_b128 v[206:209], v170 offset:6144
	ds_read_b128 v[210:213], v170 offset:7168
	s_addc_u32 s69, s43, 0
	s_add_i32 m0, s48, 0xc000
	s_nop 0
	global_load_lds_dwordx4 v80, s[2:3]
	v_mov_b32_e32 v80, v155
	s_add_i32 m0, s48, 0xe000
	s_nop 0
	global_load_lds_dwordx4 v80, s[2:3]
	s_waitcnt lgkmcnt(8)
	s_barrier
	s_waitcnt lgkmcnt(0)
	s_setprio 1
	s_waitcnt lgkmcnt(0)
	v_mfma_f32_16x16x32_bf16 v[126:129], v[132:135], v[148:151], v[126:129]
	v_mfma_f32_16x16x32_bf16 v[122:125], v[140:143], v[148:151], v[122:125]
	v_mfma_f32_16x16x32_bf16 v[110:113], v[132:135], v[190:193], v[110:113]
	v_mfma_f32_16x16x32_bf16 v[106:109], v[140:143], v[190:193], v[106:109]
	v_mfma_f32_16x16x32_bf16 v[94:97], v[132:135], v[198:201], v[94:97]
	v_mfma_f32_16x16x32_bf16 v[90:93], v[140:143], v[198:201], v[90:93]
	v_mfma_f32_16x16x32_bf16 v[76:79], v[132:135], v[206:209], v[76:79]
	v_mfma_f32_16x16x32_bf16 v[72:75], v[140:143], v[206:209], v[72:75]
	v_mfma_f32_16x16x32_bf16 v[126:129], v[136:139], v[172:175], v[126:129]
	v_mfma_f32_16x16x32_bf16 v[122:125], v[144:147], v[172:175], v[122:125]
	v_mfma_f32_16x16x32_bf16 v[110:113], v[136:139], v[194:197], v[110:113]
	v_mfma_f32_16x16x32_bf16 v[106:109], v[144:147], v[194:197], v[106:109]
	v_mfma_f32_16x16x32_bf16 v[94:97], v[136:139], v[202:205], v[94:97]
	v_mfma_f32_16x16x32_bf16 v[90:93], v[144:147], v[202:205], v[90:93]
	v_mfma_f32_16x16x32_bf16 v[76:79], v[136:139], v[210:213], v[76:79]
	v_mfma_f32_16x16x32_bf16 v[72:75], v[144:147], v[210:213], v[72:75]
	s_setprio 0
	s_barrier
	s_add_i32 s22, 0, 0x14000
	v_add_u32_e32 v80, s22, v158
	ds_read_b128 v[214:217], v80
	ds_read_b128 v[226:229], v80 offset:1024
	ds_read_b128 v[238:241], v80 offset:2048
	ds_read_b128 v[242:245], v80 offset:3072
	v_mov_b32_e32 v80, v154
	s_add_i32 s34, vcc_lo, s47
	s_mov_b32 m0, s34
	s_nop 0
	global_load_lds_dwordx4 v80, s[44:45]
	v_mov_b32_e32 v80, v156
	s_add_i32 m0, s34, 0x2000
	s_nop 0
	global_load_lds_dwordx4 v80, s[44:45]
	s_barrier
	s_waitcnt lgkmcnt(0)
	s_setprio 1
	s_waitcnt lgkmcnt(0)
	v_mfma_f32_16x16x32_bf16 v[118:121], v[214:217], v[148:151], v[118:121]
	v_mfma_f32_16x16x32_bf16 v[114:117], v[238:241], v[148:151], v[114:117]
	v_mfma_f32_16x16x32_bf16 v[102:105], v[214:217], v[190:193], v[102:105]
	v_mfma_f32_16x16x32_bf16 v[98:101], v[238:241], v[190:193], v[98:101]
	v_mfma_f32_16x16x32_bf16 v[86:89], v[214:217], v[198:201], v[86:89]
	v_mfma_f32_16x16x32_bf16 v[82:85], v[238:241], v[198:201], v[82:85]
	v_mfma_f32_16x16x32_bf16 v[68:71], v[214:217], v[206:209], v[68:71]
	v_mfma_f32_16x16x32_bf16 v[64:67], v[238:241], v[206:209], v[64:67]
	v_mfma_f32_16x16x32_bf16 v[118:121], v[226:229], v[172:175], v[118:121]
	v_mfma_f32_16x16x32_bf16 v[114:117], v[242:245], v[172:175], v[114:117]
	v_mfma_f32_16x16x32_bf16 v[102:105], v[226:229], v[194:197], v[102:105]
	v_mfma_f32_16x16x32_bf16 v[98:101], v[242:245], v[194:197], v[98:101]
	v_mfma_f32_16x16x32_bf16 v[86:89], v[226:229], v[202:205], v[86:89]
	v_mfma_f32_16x16x32_bf16 v[82:85], v[242:245], v[202:205], v[82:85]
	v_mfma_f32_16x16x32_bf16 v[68:71], v[226:229], v[210:213], v[68:71]
	v_mfma_f32_16x16x32_bf16 v[64:67], v[242:245], v[210:213], v[64:67]
	s_setprio 0
	v_mov_b32_e32 v80, v153
	s_mov_b32 m0, s48
	s_barrier
	ds_read_b128 v[148:151], v170 offset:16384
	ds_read_b128 v[172:175], v170 offset:17408
	ds_read_b128 v[190:193], v170 offset:18432
	ds_read_b128 v[194:197], v170 offset:19456
	ds_read_b128 v[198:201], v170 offset:20480
	ds_read_b128 v[202:205], v170 offset:21504
	ds_read_b128 v[206:209], v170 offset:22528
	ds_read_b128 v[210:213], v170 offset:23552
	s_nop 0
	global_load_lds_dwordx4 v80, s[42:43]
	v_mov_b32_e32 v80, v155
	s_mov_b32 m0, s49
	s_nop 0
	global_load_lds_dwordx4 v80, s[42:43]
	s_barrier
	s_waitcnt lgkmcnt(0)
	s_setprio 1
	s_waitcnt lgkmcnt(0)
	v_mfma_f32_16x16x32_bf16 v[60:63], v[132:135], v[148:151], v[60:63]
	v_mfma_f32_16x16x32_bf16 v[56:59], v[140:143], v[148:151], v[56:59]
	v_mfma_f32_16x16x32_bf16 v[44:47], v[132:135], v[190:193], v[44:47]
	v_mfma_f32_16x16x32_bf16 v[40:43], v[140:143], v[190:193], v[40:43]
	v_mfma_f32_16x16x32_bf16 v[28:31], v[132:135], v[198:201], v[28:31]
	v_mfma_f32_16x16x32_bf16 v[24:27], v[140:143], v[198:201], v[24:27]
	v_mfma_f32_16x16x32_bf16 v[12:15], v[132:135], v[206:209], v[12:15]
	v_mfma_f32_16x16x32_bf16 v[8:11], v[140:143], v[206:209], v[8:11]
	v_mfma_f32_16x16x32_bf16 v[60:63], v[136:139], v[172:175], v[60:63]
	v_mfma_f32_16x16x32_bf16 v[56:59], v[144:147], v[172:175], v[56:59]
	v_mfma_f32_16x16x32_bf16 v[44:47], v[136:139], v[194:197], v[44:47]
	v_mfma_f32_16x16x32_bf16 v[40:43], v[144:147], v[194:197], v[40:43]
	v_mfma_f32_16x16x32_bf16 v[28:31], v[136:139], v[202:205], v[28:31]
	v_mfma_f32_16x16x32_bf16 v[24:27], v[144:147], v[202:205], v[24:27]
	v_mfma_f32_16x16x32_bf16 v[12:15], v[136:139], v[210:213], v[12:15]
	v_mfma_f32_16x16x32_bf16 v[8:11], v[144:147], v[210:213], v[8:11]
	s_setprio 0
	s_barrier
; #define G_STAGE(bufoff, gbase, voff) do { _Pragma("unroll") for (int _i = 0; _i < 2; ++_i) { unsigned _vo = (voff)[_i]; asm volatile("" : "+v"(_vo));   \
;     __builtin_amdgcn_global_load_lds((const unsigned*)((const char*)(gbase) + _vo), (LAS unsigned*)(lds + (bufoff) + ldsw + _i * 8192), 16, 0, 0); } } while (0)
; #define G_LDA(dst, b, h) do { _Pragma("unroll") for (int m = 0; m < 4; ++m) _Pragma("unroll") for (int k = 0; k < 2; ++k) dst[m][k] = *(const LAS bf16x8*)(lds + G_SA(b, h) + aoff + m * 2048 + k * 1024); } while (0)
; #define G_LDB(dst, b, h) do { _Pragma("unroll") for (int n = 0; n < 2; ++n) _Pragma("unroll") for (int k = 0; k < 2; ++k) dst[n][k] = *(const LAS bf16x8*)(lds + G_SB(b, h) + boff + n * 2048 + k * 1024); } while (0)
; #define G_MMA(ai, bj, At, Bt) do { __builtin_amdgcn_s_setprio(1); _Pragma("unroll") for (int m = 0; m < 4; ++m) _Pragma("unroll") for (int n = 0; n < 2; ++n) _Pragma("unroll") for (int k = 0; k < 2; ++k) \
;     acc[ai][bj][m][n] = __builtin_amdgcn_mfma_f32_16x16x32_bf16(Bt[n][k], At[m][k], acc[ai][bj][m][n], 0, 0, 0); __builtin_amdgcn_s_setprio(0); } while (0)
; #define G_WAIT_V(n) asm volatile("s_waitcnt vmcnt(" #n ")" ::: "memory")
; #define G_WAIT_L(n) asm volatile("s_waitcnt lgkmcnt(" #n ")" ::: "memory")
; #define G_BAR __builtin_amdgcn_s_barrier()
; #define G_SCHED __builtin_amdgcn_sched_barrier(0)
; template <class Epi>
; __device__ __forceinline__ void gemm_phase(LAS unsigned char* lds, const int K, const unsigned lda_b, const unsigned ldb_b, const Map& M, const Epi& E) {
;     ...
;       G_STAGE(G_SB(0, 1), b2h1, voffB);
;       G_WAIT_V(6); G_BAR; G_MMA(1, 1, At, B1); G_BAR;
;       G_LDB(B0, 1, 0); G_SCHED; G_LDA(At, 1, 0); G_STAGE(G_SA(0, 1), a2h1, voffA);
;       G_WAIT_L(8); G_BAR; G_WAIT_L(0); G_MMA(0, 0, At, B0); G_BAR; G_SCHED;
;       G_LDB(B1, 1, 1); G_STAGE(G_SB(1, 0), b2h0 + kstep, voffB);
;       G_BAR; G_WAIT_L(0); G_MMA(0, 1, At, B1); G_BAR;
;       G_LDA(At, 1, 1); G_STAGE(G_SA(1, 0), a2h0 + kstep, voffA);
;       G_BAR; G_WAIT_L(0); G_MMA(1, 0, At, B0); G_BAR; G_SCHED;
;       G_STAGE(G_SB(1, 1), b2h1 + kstep, voffB);
	v_mov_b32_e32 v80, v154
	s_add_i32 s22, s22, s47
	s_mov_b32 m0, s22
	s_nop 0
	global_load_lds_dwordx4 v80, s[38:39]
	v_mov_b32_e32 v80, v156
	s_add_i32 m0, s22, 0x2000
	s_nop 0
	global_load_lds_dwordx4 v80, s[38:39]
	s_waitcnt vmcnt(6)
	s_barrier
	s_setprio 1
	v_mfma_f32_16x16x32_bf16 v[52:55], v[214:217], v[148:151], v[52:55]
	v_mfma_f32_16x16x32_bf16 v[48:51], v[238:241], v[148:151], v[48:51]
	v_mfma_f32_16x16x32_bf16 v[36:39], v[214:217], v[190:193], v[36:39]
	v_mfma_f32_16x16x32_bf16 v[32:35], v[238:241], v[190:193], v[32:35]
	v_mfma_f32_16x16x32_bf16 v[20:23], v[214:217], v[198:201], v[20:23]
	v_mfma_f32_16x16x32_bf16 v[16:19], v[238:241], v[198:201], v[16:19]
	v_mfma_f32_16x16x32_bf16 v[4:7], v[214:217], v[206:209], v[4:7]
	v_mfma_f32_16x16x32_bf16 v[0:3], v[238:241], v[206:209], v[0:3]
	v_mfma_f32_16x16x32_bf16 v[52:55], v[226:229], v[172:175], v[52:55]
	v_mfma_f32_16x16x32_bf16 v[48:51], v[242:245], v[172:175], v[48:51]
	v_mfma_f32_16x16x32_bf16 v[36:39], v[226:229], v[194:197], v[36:39]
	v_mfma_f32_16x16x32_bf16 v[32:35], v[242:245], v[194:197], v[32:35]
	v_mfma_f32_16x16x32_bf16 v[20:23], v[226:229], v[202:205], v[20:23]
	v_mfma_f32_16x16x32_bf16 v[16:19], v[242:245], v[202:205], v[16:19]
	v_mfma_f32_16x16x32_bf16 v[4:7], v[226:229], v[210:213], v[4:7]
	v_mfma_f32_16x16x32_bf16 v[0:3], v[242:245], v[210:213], v[0:3]
	s_setprio 0
	s_add_i32 s22, 0, 0x18000
	v_add_u32_e32 v80, s22, v158
	s_barrier
	ds_read_b128 v[132:135], v80
	ds_read_b128 v[136:139], v80 offset:1024
	ds_read_b128 v[140:143], v80 offset:2048
	ds_read_b128 v[144:147], v80 offset:3072
	v_mov_b32_e32 v80, v153
	s_mov_b32 m0, s61
	ds_read_b128 v[148:151], v170 offset:32768
	ds_read_b128 v[172:175], v170 offset:33792
	ds_read_b128 v[190:193], v170 offset:34816
	ds_read_b128 v[194:197], v170 offset:35840
	ds_read_b128 v[198:201], v170 offset:36864
	ds_read_b128 v[202:205], v170 offset:37888
	ds_read_b128 v[206:209], v170 offset:38912
	ds_read_b128 v[210:213], v170 offset:39936
	s_nop 0
	global_load_lds_dwordx4 v80, s[68:69]
	v_mov_b32_e32 v80, v155
	s_mov_b32 m0, s66
	s_nop 0
	global_load_lds_dwordx4 v80, s[68:69]
	s_waitcnt lgkmcnt(8)
	s_barrier
	s_waitcnt lgkmcnt(0)
	s_setprio 1
	s_waitcnt lgkmcnt(0)
	v_mfma_f32_16x16x32_bf16 v[126:129], v[132:135], v[148:151], v[126:129]
	v_mfma_f32_16x16x32_bf16 v[122:125], v[140:143], v[148:151], v[122:125]
	v_mfma_f32_16x16x32_bf16 v[110:113], v[132:135], v[190:193], v[110:113]
	v_mfma_f32_16x16x32_bf16 v[106:109], v[140:143], v[190:193], v[106:109]
	v_mfma_f32_16x16x32_bf16 v[94:97], v[132:135], v[198:201], v[94:97]
	v_mfma_f32_16x16x32_bf16 v[90:93], v[140:143], v[198:201], v[90:93]
	v_mfma_f32_16x16x32_bf16 v[76:79], v[132:135], v[206:209], v[76:79]
	v_mfma_f32_16x16x32_bf16 v[72:75], v[140:143], v[206:209], v[72:75]
	v_mfma_f32_16x16x32_bf16 v[126:129], v[136:139], v[172:175], v[126:129]
	v_mfma_f32_16x16x32_bf16 v[122:125], v[144:147], v[172:175], v[122:125]
	v_mfma_f32_16x16x32_bf16 v[110:113], v[136:139], v[194:197], v[110:113]
	v_mfma_f32_16x16x32_bf16 v[106:109], v[144:147], v[194:197], v[106:109]
	v_mfma_f32_16x16x32_bf16 v[94:97], v[136:139], v[202:205], v[94:97]
	v_mfma_f32_16x16x32_bf16 v[90:93], v[144:147], v[202:205], v[90:93]
	v_mfma_f32_16x16x32_bf16 v[76:79], v[136:139], v[210:213], v[76:79]
	v_mfma_f32_16x16x32_bf16 v[72:75], v[144:147], v[210:213], v[72:75]
	s_setprio 0
	s_barrier
	s_add_i32 s34, 0, 0x1c000
	v_add_u32_e32 v80, s34, v158
	ds_read_b128 v[214:217], v80
	ds_read_b128 v[226:229], v80 offset:1024
	ds_read_b128 v[238:241], v80 offset:2048
	ds_read_b128 v[242:245], v80 offset:3072
	v_mov_b32_e32 v80, v154
	s_add_i32 s22, s22, s47
	v_lshl_add_u64 v[176:177], s[44:45], 0, v[80:81]
	v_lshl_add_u64 v[176:177], v[176:177], 0, s[52:53]
	s_mov_b32 m0, s22
	v_mov_b32_e32 v80, v156
	global_load_lds_dwordx4 v[176:177], off
	s_add_i32 m0, s22, 0x2000
	v_lshl_add_u64 v[176:177], s[44:45], 0, v[80:81]
	v_lshl_add_u64 v[176:177], v[176:177], 0, s[52:53]
	global_load_lds_dwordx4 v[176:177], off
	s_barrier
	s_waitcnt lgkmcnt(0)
	s_setprio 1
	s_waitcnt lgkmcnt(0)
	v_mfma_f32_16x16x32_bf16 v[118:121], v[214:217], v[148:151], v[118:121]
	v_mfma_f32_16x16x32_bf16 v[114:117], v[238:241], v[148:151], v[114:117]
	v_mfma_f32_16x16x32_bf16 v[102:105], v[214:217], v[190:193], v[102:105]
	v_mfma_f32_16x16x32_bf16 v[98:101], v[238:241], v[190:193], v[98:101]
	v_mfma_f32_16x16x32_bf16 v[86:89], v[214:217], v[198:201], v[86:89]
	v_mfma_f32_16x16x32_bf16 v[82:85], v[238:241], v[198:201], v[82:85]
	v_mfma_f32_16x16x32_bf16 v[68:71], v[214:217], v[206:209], v[68:71]
	v_mfma_f32_16x16x32_bf16 v[64:67], v[238:241], v[206:209], v[64:67]
	v_mfma_f32_16x16x32_bf16 v[118:121], v[226:229], v[172:175], v[118:121]
	v_mfma_f32_16x16x32_bf16 v[114:117], v[242:245], v[172:175], v[114:117]
	v_mfma_f32_16x16x32_bf16 v[102:105], v[226:229], v[194:197], v[102:105]
	v_mfma_f32_16x16x32_bf16 v[98:101], v[242:245], v[194:197], v[98:101]
	v_mfma_f32_16x16x32_bf16 v[86:89], v[226:229], v[202:205], v[86:89]
	v_mfma_f32_16x16x32_bf16 v[82:85], v[242:245], v[202:205], v[82:85]
	v_mfma_f32_16x16x32_bf16 v[68:71], v[226:229], v[210:213], v[68:71]
	v_mfma_f32_16x16x32_bf16 v[64:67], v[242:245], v[210:213], v[64:67]
	s_setprio 0
	v_mov_b32_e32 v80, v153
	s_barrier
	ds_read_b128 v[148:151], v170 offset:49152
	ds_read_b128 v[172:175], v170 offset:50176
	ds_read_b128 v[190:193], v170 offset:51200
	ds_read_b128 v[194:197], v170 offset:52224
	ds_read_b128 v[198:201], v170 offset:53248
	ds_read_b128 v[202:205], v170 offset:54272
	ds_read_b128 v[206:209], v170 offset:55296
	ds_read_b128 v[210:213], v170 offset:56320
	s_mov_b32 m0, s67
	v_lshl_add_u64 v[176:177], s[42:43], 0, v[80:81]
	v_lshl_add_u64 v[176:177], v[176:177], 0, s[52:53]
	v_mov_b32_e32 v80, v155
	global_load_lds_dwordx4 v[176:177], off
	s_mov_b32 m0, s76
	v_lshl_add_u64 v[176:177], s[42:43], 0, v[80:81]
	v_lshl_add_u64 v[176:177], v[176:177], 0, s[52:53]
	global_load_lds_dwordx4 v[176:177], off
	s_barrier
; __device__ __forceinline__ float rinv_of(unsigned long long ss) { return rsqrtf((float)ss * (1.f / 16777216.f) * (1.f / DM) + 1e-6f); }
; #define G_STAGE(bufoff, gbase, voff) do { _Pragma("unroll") for (int _i = 0; _i < 2; ++_i) { unsigned _vo = (voff)[_i]; asm volatile("" : "+v"(_vo));   \
;     __builtin_amdgcn_global_load_lds((const unsigned*)((const char*)(gbase) + _vo), (LAS unsigned*)(lds + (bufoff) + ldsw + _i * 8192), 16, 0, 0); } } while (0)
; #define G_LDA(dst, b, h) do { _Pragma("unroll") for (int m = 0; m < 4; ++m) _Pragma("unroll") for (int k = 0; k < 2; ++k) dst[m][k] = *(const LAS bf16x8*)(lds + G_SA(b, h) + aoff + m * 2048 + k * 1024); } while (0)
; #define G_MMA(ai, bj, At, Bt) do { __builtin_amdgcn_s_setprio(1); _Pragma("unroll") for (int m = 0; m < 4; ++m) _Pragma("unroll") for (int n = 0; n < 2; ++n) _Pragma("unroll") for (int k = 0; k < 2; ++k) \
;     acc[ai][bj][m][n] = __builtin_amdgcn_mfma_f32_16x16x32_bf16(Bt[n][k], At[m][k], acc[ai][bj][m][n], 0, 0, 0); __builtin_amdgcn_s_setprio(0); } while (0)
; #define G_WAIT_V(n) asm volatile("s_waitcnt vmcnt(" #n ")" ::: "memory")
; #define G_WAIT_L(n) asm volatile("s_waitcnt lgkmcnt(" #n ")" ::: "memory")
; #define G_BAR __builtin_amdgcn_s_barrier()
; #define G_SCHED __builtin_amdgcn_sched_barrier(0)
;   __device__ __forceinline__ void operator()(const f32x4 (&acc)[2][2][4][2], const Unit& u, const EpiCtx& x_, int wr, int wc, int fr, int fq) const {
;     ...
;     { const int lg = x_.p0, S = x_.p1, L = S >> lg;
; #pragma unroll
;       for (int bj = 0; bj < 2; ++bj) {
;         const int col = u.c0 + wc * 64 + bj * 32 + 8 * fq, seq = col / S, rem = col % S, r = rem / L, m0 = rem % L;
;         const unsigned long long* sp = x_.ss + (size_t)seq * S + r;
; #pragma unroll
;         for (int i = 0; i < 8; ++i) cs[bj][i >> 2][i & 3] = rinv_of(sp[(size_t)(m0 + i) << lg]);
;       } }
; template <class Epi>
; __device__ __forceinline__ void gemm_phase(LAS unsigned char* lds, const int K, const unsigned lda_b, const unsigned ldb_b, const Map& M, const Epi& E) {
;     ...
;       G_BAR; G_WAIT_L(0); G_MMA(0, 1, At, B1); G_BAR;
;       G_LDA(At, 1, 1); G_STAGE(G_SA(1, 0), a2h0 + kstep, voffA);
;       G_BAR; G_WAIT_L(0); G_MMA(1, 0, At, B0); G_BAR; G_SCHED;
;       G_STAGE(G_SB(1, 1), b2h1 + kstep, voffB);
;       G_WAIT_V(6); G_BAR; G_MMA(1, 1, At, B1); G_BAR;
;     }
;     E(acc, cur, X, wr, wc, fr, fq);
	s_waitcnt lgkmcnt(0)
	s_setprio 1
	s_waitcnt lgkmcnt(0)
	v_mfma_f32_16x16x32_bf16 v[60:63], v[132:135], v[148:151], v[60:63]
	v_mfma_f32_16x16x32_bf16 v[56:59], v[140:143], v[148:151], v[56:59]
	v_mfma_f32_16x16x32_bf16 v[44:47], v[132:135], v[190:193], v[44:47]
	v_mfma_f32_16x16x32_bf16 v[40:43], v[140:143], v[190:193], v[40:43]
	v_mfma_f32_16x16x32_bf16 v[28:31], v[132:135], v[198:201], v[28:31]
	v_mfma_f32_16x16x32_bf16 v[24:27], v[140:143], v[198:201], v[24:27]
	v_mfma_f32_16x16x32_bf16 v[12:15], v[132:135], v[206:209], v[12:15]
	v_mfma_f32_16x16x32_bf16 v[8:11], v[140:143], v[206:209], v[8:11]
	v_mfma_f32_16x16x32_bf16 v[60:63], v[136:139], v[172:175], v[60:63]
	v_mfma_f32_16x16x32_bf16 v[56:59], v[144:147], v[172:175], v[56:59]
	v_mfma_f32_16x16x32_bf16 v[44:47], v[136:139], v[194:197], v[44:47]
	v_mfma_f32_16x16x32_bf16 v[40:43], v[144:147], v[194:197], v[40:43]
	v_mfma_f32_16x16x32_bf16 v[28:31], v[136:139], v[202:205], v[28:31]
	v_mfma_f32_16x16x32_bf16 v[24:27], v[144:147], v[202:205], v[24:27]
	v_mfma_f32_16x16x32_bf16 v[12:15], v[136:139], v[210:213], v[12:15]
	v_mfma_f32_16x16x32_bf16 v[8:11], v[144:147], v[210:213], v[8:11]
	s_setprio 0
	s_barrier
	v_mov_b32_e32 v80, v154
	s_add_i32 s22, s34, s47
	v_lshl_add_u64 v[132:133], s[38:39], 0, v[80:81]
	v_lshl_add_u64 v[132:133], v[132:133], 0, s[52:53]
	s_mov_b32 m0, s22
	v_mov_b32_e32 v80, v156
	global_load_lds_dwordx4 v[132:133], off
	s_add_i32 m0, s22, 0x2000
	v_lshl_add_u64 v[132:133], s[38:39], 0, v[80:81]
	v_lshl_add_u64 v[132:133], v[132:133], 0, s[52:53]
	global_load_lds_dwordx4 v[132:133], off
	s_waitcnt vmcnt(6)
	s_barrier
	s_setprio 1
	v_mfma_f32_16x16x32_bf16 v[52:55], v[214:217], v[148:151], v[52:55]
	v_mfma_f32_16x16x32_bf16 v[48:51], v[238:241], v[148:151], v[48:51]
	v_mfma_f32_16x16x32_bf16 v[36:39], v[214:217], v[190:193], v[36:39]
	v_mfma_f32_16x16x32_bf16 v[32:35], v[238:241], v[190:193], v[32:35]
	v_mfma_f32_16x16x32_bf16 v[20:23], v[214:217], v[198:201], v[20:23]
	v_mfma_f32_16x16x32_bf16 v[16:19], v[238:241], v[198:201], v[16:19]
	v_mfma_f32_16x16x32_bf16 v[4:7], v[214:217], v[206:209], v[4:7]
	v_mfma_f32_16x16x32_bf16 v[0:3], v[238:241], v[206:209], v[0:3]
	v_mfma_f32_16x16x32_bf16 v[52:55], v[226:229], v[172:175], v[52:55]
	v_mfma_f32_16x16x32_bf16 v[48:51], v[242:245], v[172:175], v[48:51]
	v_mfma_f32_16x16x32_bf16 v[36:39], v[226:229], v[194:197], v[36:39]
	v_mfma_f32_16x16x32_bf16 v[32:35], v[242:245], v[194:197], v[32:35]
	v_mfma_f32_16x16x32_bf16 v[20:23], v[226:229], v[202:205], v[20:23]
	v_mfma_f32_16x16x32_bf16 v[16:19], v[242:245], v[202:205], v[16:19]
	v_mfma_f32_16x16x32_bf16 v[4:7], v[226:229], v[210:213], v[4:7]
	v_mfma_f32_16x16x32_bf16 v[0:3], v[242:245], v[210:213], v[0:3]
	s_setprio 0
	s_add_i32 s31, s31, 2
	s_add_u32 s29, s29, 0x100
	s_addc_u32 s30, s30, 0
	s_add_u32 s2, s2, 0x100
	s_addc_u32 s3, s3, 0
	s_cmp_gt_u32 s31, 29
	s_barrier
	s_cbranch_scc0 .LBB0_651
	v_add_u32_e32 v171, s97, v159
	v_readfirstlane_b32 s0, v130
	v_sub_u32_e32 v130, 0, v171
	v_max_i32_e32 v130, v171, v130
	v_readfirstlane_b32 s42, v131
	v_mul_hi_u32 v131, v130, v152
	v_mul_lo_u32 v132, v131, s17
	v_sub_u32_e32 v130, v130, v132
	v_cmp_le_u32_e32 vcc, s17, v130
	v_add_u32_e32 v132, 1, v131
	v_ashrrev_i32_e32 v80, 31, v171
	v_cndmask_b32_e32 v131, v131, v132, vcc
	v_subrev_u32_e32 v132, s17, v130
	v_cndmask_b32_e32 v130, v130, v132, vcc
	v_cmp_le_u32_e32 vcc, s17, v130
	v_add_u32_e32 v130, 1, v131
	v_mov_b64_e32 v[136:137], s[62:63]
	v_cndmask_b32_e32 v130, v131, v130, vcc
	v_xor_b32_e32 v130, v130, v80
	v_sub_u32_e32 v130, v130, v80
	v_mul_lo_u32 v80, v130, s17
	v_sub_u32_e32 v80, v171, v80
	v_sub_u32_e32 v132, 0, v80
	v_max_i32_e32 v132, v80, v132
	v_mul_hi_u32 v133, v132, v169
	v_mul_lo_u32 v134, v133, s83
	v_sub_u32_e32 v132, v132, v134
	v_cmp_le_u32_e32 vcc, s83, v132
	v_add_u32_e32 v134, 1, v133
	v_ashrrev_i32_e32 v131, 31, v80
	v_cndmask_b32_e32 v133, v133, v134, vcc
	v_subrev_u32_e32 v134, s83, v132
	v_cndmask_b32_e32 v132, v132, v134, vcc
	v_cmp_le_u32_e32 vcc, s83, v132
	v_add_u32_e32 v132, 1, v133
	v_xor_b32_e32 v131, s87, v131
	v_cndmask_b32_e32 v132, v133, v132, vcc
	v_xor_b32_e32 v132, v132, v131
	v_sub_u32_e32 v132, v132, v131
	v_mul_lo_u32 v131, v132, s79
	v_sub_u32_e32 v138, v80, v131
	v_ashrrev_i32_e32 v131, 31, v130
	v_lshlrev_b64 v[130:131], s81, v[130:131]
	v_lshl_add_u64 v[130:131], v[130:131], 3, s[4:5]
	v_ashrrev_i32_e32 v133, 31, v132
	v_ashrrev_i32_e32 v139, 31, v138
	v_lshl_add_u64 v[140:141], v[132:133], 3, v[130:131]
	v_lshlrev_b64 v[130:131], s18, v[138:139]
	v_lshl_add_u64 v[130:131], v[130:131], 3, v[140:141]
	global_load_dwordx2 v[130:131], v[130:131], off
	v_add_u32_e32 v132, 1, v138
	v_ashrrev_i32_e32 v133, 31, v132
	v_lshlrev_b64 v[132:133], s18, v[132:133]
	v_lshl_add_u64 v[132:133], v[132:133], 3, v[140:141]
	global_load_dwordx2 v[132:133], v[132:133], off
	v_add_u32_e32 v134, 3, v138
	v_ashrrev_i32_e32 v135, 31, v134
	v_lshlrev_b64 v[134:135], s18, v[134:135]
	v_lshl_add_u64 v[134:135], v[134:135], 3, v[140:141]
	global_load_dwordx2 v[134:135], v[134:135], off
	v_add_u32_e32 v142, 5, v138
	v_ashrrev_i32_e32 v143, 31, v142
	v_lshlrev_b64 v[142:143], s18, v[142:143]
	v_lshl_add_u64 v[142:143], v[142:143], 3, v[140:141]
	s_cmp_eq_u32 s96, s86
	s_mov_b64 s[38:39], s[36:37]
	global_load_dwordx2 v[142:143], v[142:143], off
	s_waitcnt vmcnt(0) lgkmcnt(0)
; __device__ __forceinline__ float rinv_of(unsigned long long ss) { return rsqrtf((float)ss * (1.f / 16777216.f) * (1.f / DM) + 1e-6f); }
;   __device__ __forceinline__ void operator()(const f32x4 (&acc)[2][2][4][2], const Unit& u, const EpiCtx& x_, int wr, int wc, int fr, int fq) const {
;     ...
;     { const int lg = x_.p0, S = x_.p1, L = S >> lg;
; #pragma unroll
;       for (int bj = 0; bj < 2; ++bj) {
;         const int col = u.c0 + wc * 64 + bj * 32 + 8 * fq, seq = col / S, rem = col % S, r = rem / L, m0 = rem % L;
;         const unsigned long long* sp = x_.ss + (size_t)seq * S + r;
; #pragma unroll
;         for (int i = 0; i < 8; ++i) cs[bj][i >> 2][i & 3] = rinv_of(sp[(size_t)(m0 + i) << lg]);
;       } }
; #pragma unroll
;     for (int ai = 0; ai < 2; ++ai)
; #pragma unroll
;       for (int m = 0; m < 4; ++m) {
;         const int row = u.r0 + ai * 128 + wr * 64 + m * 16 + fr, hh = (x_.p0 >> 1) * 16 + (row >> 7), d = row & 127;
; #pragma unroll
;         for (int bj = 0; bj < 2; ++bj) {
;           const int col = u.c0 + wc * 64 + bj * 32 + 8 * fq;
;           const f32x4 v0 = acc[ai][bj][m][0] * cs[bj][0], v1 = acc[ai][bj][m][1] * cs[bj][1];
	v_ffbh_u32_e32 v80, v131
	v_min_u32_e32 v80, 32, v80
	v_lshlrev_b64 v[130:131], v80, v[130:131]
	v_min_u32_e32 v130, 1, v130
	v_or_b32_e32 v130, v131, v130
	v_cvt_f32_u32_e32 v130, v130
	v_sub_u32_e32 v80, 32, v80
	v_ldexp_f32 v130, v130, v80
	v_ffbh_u32_e32 v80, v133
	v_min_u32_e32 v80, 32, v80
	v_lshlrev_b64 v[132:133], v80, v[132:133]
	v_min_u32_e32 v131, 1, v132
	v_or_b32_e32 v131, v133, v131
	v_cvt_f32_u32_e32 v131, v131
	v_sub_u32_e32 v80, 32, v80
	v_ldexp_f32 v131, v131, v80
	v_pk_mul_f32 v[130:131], v[130:131], s[60:61] op_sel_hi:[1,0]
	s_nop 0
	v_pk_fma_f32 v[130:131], v[130:131], s[26:27], v[136:137] op_sel_hi:[1,0,0]
	s_nop 0
	v_mul_f32_e32 v80, 0x4b800000, v130
	v_cmp_gt_f32_e64 s[2:3], s50, v130
	v_cmp_gt_f32_e32 vcc, s50, v131
	s_nop 0
	v_cndmask_b32_e64 v80, v130, v80, s[2:3]
	v_rsq_f32_e32 v130, v80
	v_mul_f32_e32 v80, 0x4b800000, v131
	v_cndmask_b32_e32 v80, v131, v80, vcc
	v_rsq_f32_e32 v131, v80
	v_ffbh_u32_e32 v80, v135
	v_min_u32_e32 v80, 32, v80
	v_lshlrev_b64 v[134:135], v80, v[134:135]
	v_pk_mul_f32 v[132:133], v[130:131], s[64:65] op_sel_hi:[1,0]
	v_min_u32_e32 v134, 1, v134
	v_cndmask_b32_e64 v130, v130, v132, s[2:3]
	v_add_u32_e32 v132, 2, v138
	v_cndmask_b32_e32 v131, v131, v133, vcc
	v_ashrrev_i32_e32 v133, 31, v132
	v_lshlrev_b64 v[132:133], s18, v[132:133]
	v_lshl_add_u64 v[132:133], v[132:133], 3, v[140:141]
	global_load_dwordx2 v[132:133], v[132:133], off
	v_or_b32_e32 v134, v135, v134
	v_cvt_f32_u32_e32 v134, v134
	v_sub_u32_e32 v80, 32, v80
	v_pk_mul_f32 v[126:127], v[126:127], v[130:131]
	v_pk_mul_f32 v[110:111], v[110:111], v[130:131]
	v_ldexp_f32 v135, v134, v80
	v_cvt_pk_bf16_f32 v126, v126, v127
	v_pk_mul_f32 v[94:95], v[94:95], v[130:131]
	v_pk_mul_f32 v[76:77], v[76:77], v[130:131]
	v_pk_mul_f32 v[60:61], v[60:61], v[130:131]
	v_pk_mul_f32 v[44:45], v[44:45], v[130:131]
	v_pk_mul_f32 v[28:29], v[28:29], v[130:131]
	v_pk_mul_f32 v[12:13], v[12:13], v[130:131]
	s_waitcnt vmcnt(0) lgkmcnt(0)
	v_ffbh_u32_e32 v80, v133
	v_min_u32_e32 v80, 32, v80
	v_lshlrev_b64 v[132:133], v80, v[132:133]
	v_min_u32_e32 v132, 1, v132
	v_or_b32_e32 v132, v133, v132
	v_cvt_f32_u32_e32 v132, v132
	v_sub_u32_e32 v80, 32, v80
	v_ldexp_f32 v134, v132, v80
	v_pk_mul_f32 v[132:133], v[134:135], s[60:61] op_sel_hi:[1,0]
	s_nop 0
	v_pk_fma_f32 v[132:133], v[132:133], s[26:27], v[136:137] op_sel_hi:[1,0,0]
	s_nop 0
	v_mul_f32_e32 v80, 0x4b800000, v132
	v_cmp_gt_f32_e64 s[2:3], s50, v132
	v_cmp_gt_f32_e32 vcc, s50, v133
	s_nop 0
	v_cndmask_b32_e64 v80, v132, v80, s[2:3]
	v_rsq_f32_e32 v132, v80
	v_mul_f32_e32 v80, 0x4b800000, v133
	v_cndmask_b32_e32 v80, v133, v80, vcc
	v_rsq_f32_e32 v133, v80
	v_ffbh_u32_e32 v80, v143
	v_min_u32_e32 v80, 32, v80
	v_lshlrev_b64 v[142:143], v80, v[142:143]
	v_pk_mul_f32 v[134:135], v[132:133], s[64:65] op_sel_hi:[1,0]
	v_min_u32_e32 v139, 1, v142
	v_cndmask_b32_e64 v132, v132, v134, s[2:3]
	v_add_u32_e32 v134, 4, v138
	v_cndmask_b32_e32 v133, v133, v135, vcc
	v_ashrrev_i32_e32 v135, 31, v134
	v_lshlrev_b64 v[134:135], s18, v[134:135]
	v_lshl_add_u64 v[134:135], v[134:135], 3, v[140:141]
	global_load_dwordx2 v[134:135], v[134:135], off
	v_or_b32_e32 v139, v143, v139
	v_cvt_f32_u32_e32 v139, v139
	v_sub_u32_e32 v80, 32, v80
	v_pk_mul_f32 v[128:129], v[128:129], v[132:133]
	v_pk_mul_f32 v[112:113], v[112:113], v[132:133]
	v_ldexp_f32 v143, v139, v80
	v_cvt_pk_bf16_f32 v127, v128, v129
	v_pk_mul_f32 v[96:97], v[96:97], v[132:133]
	v_pk_mul_f32 v[78:79], v[78:79], v[132:133]
	v_pk_mul_f32 v[62:63], v[62:63], v[132:133]
	v_pk_mul_f32 v[46:47], v[46:47], v[132:133]
	v_pk_mul_f32 v[30:31], v[30:31], v[132:133]
	v_pk_mul_f32 v[14:15], v[14:15], v[132:133]
	s_waitcnt vmcnt(0) lgkmcnt(0)
	v_ffbh_u32_e32 v80, v135
	v_min_u32_e32 v80, 32, v80
	v_lshlrev_b64 v[134:135], v80, v[134:135]
	v_min_u32_e32 v134, 1, v134
	v_or_b32_e32 v134, v135, v134
	v_cvt_f32_u32_e32 v134, v134
	v_sub_u32_e32 v80, 32, v80
	v_ldexp_f32 v142, v134, v80
	v_pk_mul_f32 v[134:135], v[142:143], s[60:61] op_sel_hi:[1,0]
	s_nop 0
	v_pk_fma_f32 v[134:135], v[134:135], s[26:27], v[136:137] op_sel_hi:[1,0,0]
	s_nop 0
	v_mul_f32_e32 v80, 0x4b800000, v134
	v_cmp_gt_f32_e64 s[2:3], s50, v134
	v_cmp_gt_f32_e32 vcc, s50, v135
	s_nop 0
	v_cndmask_b32_e64 v80, v134, v80, s[2:3]
	v_rsq_f32_e32 v134, v80
	v_mul_f32_e32 v80, 0x4b800000, v135
	v_cndmask_b32_e32 v80, v135, v80, vcc
	v_rsq_f32_e32 v135, v80
	s_nop 0
	v_pk_mul_f32 v[142:143], v[134:135], s[64:65] op_sel_hi:[1,0]
	s_nop 0
	v_cndmask_b32_e64 v134, v134, v142, s[2:3]
	v_add_u32_e32 v142, 6, v138
	v_add_u32_e32 v138, 7, v138
	v_cndmask_b32_e32 v135, v135, v143, vcc
	v_ashrrev_i32_e32 v143, 31, v142
	v_ashrrev_i32_e32 v139, 31, v138
	v_lshlrev_b64 v[142:143], s18, v[142:143]
	v_lshlrev_b64 v[138:139], s18, v[138:139]
	v_lshl_add_u64 v[142:143], v[142:143], 3, v[140:141]
	v_lshl_add_u64 v[138:139], v[138:139], 3, v[140:141]
	global_load_dwordx2 v[142:143], v[142:143], off
	v_pk_mul_f32 v[122:123], v[122:123], v[134:135]
	global_load_dwordx2 v[138:139], v[138:139], off
	v_cvt_pk_bf16_f32 v128, v122, v123
	v_ashrrev_i32_e32 v122, 5, v171
	v_ashrrev_i32_e32 v123, 31, v122
	v_lshlrev_b64 v[122:123], 13, v[122:123]
	v_lshl_add_u64 v[122:123], s[94:95], 0, v[122:123]
	s_waitcnt vmcnt(0) lgkmcnt(0)
; __device__ __forceinline__ float rinv_of(unsigned long long ss) { return rsqrtf((float)ss * (1.f / 16777216.f) * (1.f / DM) + 1e-6f); }
;   __device__ __forceinline__ void operator()(const f32x4 (&acc)[2][2][4][2], const Unit& u, const EpiCtx& x_, int wr, int wc, int fr, int fq) const {
;     ...
;     { const int lg = x_.p0, S = x_.p1, L = S >> lg;
; #pragma unroll
;       for (int bj = 0; bj < 2; ++bj) {
;         const int col = u.c0 + wc * 64 + bj * 32 + 8 * fq, seq = col / S, rem = col % S, r = rem / L, m0 = rem % L;
;         const unsigned long long* sp = x_.ss + (size_t)seq * S + r;
; #pragma unroll
;         for (int i = 0; i < 8; ++i) cs[bj][i >> 2][i & 3] = rinv_of(sp[(size_t)(m0 + i) << lg]);
;       } }
; #pragma unroll
;     for (int ai = 0; ai < 2; ++ai)
; #pragma unroll
;       for (int m = 0; m < 4; ++m) {
;         const int row = u.r0 + ai * 128 + wr * 64 + m * 16 + fr, hh = (x_.p0 >> 1) * 16 + (row >> 7), d = row & 127;
; #pragma unroll
;         for (int bj = 0; bj < 2; ++bj) {
;           const int col = u.c0 + wc * 64 + bj * 32 + 8 * fq;
;           const f32x4 v0 = acc[ai][bj][m][0] * cs[bj][0], v1 = acc[ai][bj][m][1] * cs[bj][1];
	v_ffbh_u32_e32 v80, v139
	v_min_u32_e32 v80, 32, v80
	v_lshlrev_b64 v[138:139], v80, v[138:139]
	v_min_u32_e32 v138, 1, v138
	v_or_b32_e32 v138, v139, v138
	v_cvt_f32_u32_e32 v138, v138
	v_sub_u32_e32 v80, 32, v80
	v_ldexp_f32 v139, v138, v80
	v_ffbh_u32_e32 v80, v143
	v_min_u32_e32 v80, 32, v80
	v_lshlrev_b64 v[140:141], v80, v[142:143]
	v_min_u32_e32 v138, 1, v140
	v_or_b32_e32 v138, v141, v138
	v_cvt_f32_u32_e32 v138, v138
	v_sub_u32_e32 v80, 32, v80
	v_ldexp_f32 v138, v138, v80
	v_pk_mul_f32 v[138:139], v[138:139], s[60:61] op_sel_hi:[1,0]
	s_nop 0
	v_pk_fma_f32 v[138:139], v[138:139], s[26:27], v[136:137] op_sel_hi:[1,0,0]
	s_nop 0
	v_mul_f32_e32 v80, 0x4b800000, v138
	v_cmp_gt_f32_e64 s[2:3], s50, v138
	v_cmp_gt_f32_e32 vcc, s50, v139
	s_nop 0
	v_cndmask_b32_e64 v80, v138, v80, s[2:3]
	v_rsq_f32_e32 v138, v80
	v_mul_f32_e32 v80, 0x4b800000, v139
	v_cndmask_b32_e32 v80, v139, v80, vcc
	v_rsq_f32_e32 v139, v80
	v_add_u32_e32 v80, 32, v171
	v_pk_mul_f32 v[140:141], v[138:139], s[64:65] op_sel_hi:[1,0]
	s_nop 0
	v_cndmask_b32_e32 v139, v139, v141, vcc
	v_sub_u32_e32 v141, 0xffffffe0, v171
	v_max_i32_e32 v141, v80, v141
	v_mul_hi_u32 v142, v141, v152
	v_mul_lo_u32 v143, v142, s17
	v_sub_u32_e32 v141, v141, v143
	v_cmp_le_u32_e32 vcc, s17, v141
	v_add_u32_e32 v143, 1, v142
	v_cndmask_b32_e64 v138, v138, v140, s[2:3]
	v_cndmask_b32_e32 v142, v142, v143, vcc
	v_subrev_u32_e32 v143, s17, v141
	v_cndmask_b32_e32 v141, v141, v143, vcc
	v_cmp_le_u32_e32 vcc, s17, v141
	v_add_u32_e32 v141, 1, v142
	v_ashrrev_i32_e32 v140, 31, v80
	v_cndmask_b32_e32 v141, v142, v141, vcc
	v_xor_b32_e32 v141, v141, v140
	v_sub_u32_e32 v140, v141, v140
	v_mul_lo_u32 v141, v140, s17
	v_sub_u32_e32 v80, v80, v141
	v_sub_u32_e32 v142, 0, v80
	v_max_i32_e32 v142, v80, v142
	v_mul_hi_u32 v143, v142, v169
	v_mul_lo_u32 v144, v143, s83
	v_sub_u32_e32 v142, v142, v144
	v_cmp_le_u32_e32 vcc, s83, v142
	v_add_u32_e32 v144, 1, v143
	v_ashrrev_i32_e32 v141, 31, v80
	v_cndmask_b32_e32 v143, v143, v144, vcc
	v_subrev_u32_e32 v144, s83, v142
	v_cndmask_b32_e32 v142, v142, v144, vcc
	v_cmp_le_u32_e32 vcc, s83, v142
	v_add_u32_e32 v142, 1, v143
	v_xor_b32_e32 v141, s87, v141
	v_cndmask_b32_e32 v142, v143, v142, vcc
	v_xor_b32_e32 v142, v142, v141
	v_sub_u32_e32 v142, v142, v141
	v_mul_lo_u32 v141, v142, s79
	v_sub_u32_e32 v146, v80, v141
	v_ashrrev_i32_e32 v141, 31, v140
	v_lshlrev_b64 v[140:141], s81, v[140:141]
	v_lshl_add_u64 v[140:141], v[140:141], 3, s[4:5]
	v_ashrrev_i32_e32 v143, 31, v142
	v_ashrrev_i32_e32 v147, 31, v146
	v_lshl_add_u64 v[148:149], v[142:143], 3, v[140:141]
	v_lshlrev_b64 v[140:141], s18, v[146:147]
	v_lshl_add_u64 v[140:141], v[140:141], 3, v[148:149]
	global_load_dwordx2 v[140:141], v[140:141], off
	v_add_u32_e32 v142, 1, v146
	v_ashrrev_i32_e32 v143, 31, v142
	v_lshlrev_b64 v[142:143], s18, v[142:143]
	v_lshl_add_u64 v[142:143], v[142:143], 3, v[148:149]
	global_load_dwordx2 v[142:143], v[142:143], off
	v_add_u32_e32 v144, 3, v146
	v_ashrrev_i32_e32 v145, 31, v144
	v_lshlrev_b64 v[144:145], s18, v[144:145]
	v_lshl_add_u64 v[144:145], v[144:145], 3, v[148:149]
	global_load_dwordx2 v[144:145], v[144:145], off
	v_add_u32_e32 v150, 5, v146
	v_ashrrev_i32_e32 v151, 31, v150
	v_lshlrev_b64 v[150:151], s18, v[150:151]
	v_lshl_add_u64 v[150:151], v[150:151], 3, v[148:149]
	v_pk_mul_f32 v[124:125], v[124:125], v[138:139]
	global_load_dwordx2 v[150:151], v[150:151], off
	v_cvt_pk_bf16_f32 v129, v124, v125
	s_waitcnt vmcnt(0) lgkmcnt(0)
	v_ffbh_u32_e32 v80, v141
	v_min_u32_e32 v80, 32, v80
	v_lshlrev_b64 v[140:141], v80, v[140:141]
	v_min_u32_e32 v140, 1, v140
	v_or_b32_e32 v140, v141, v140
	v_cvt_f32_u32_e32 v140, v140
	v_sub_u32_e32 v80, 32, v80
	v_ldexp_f32 v140, v140, v80
	v_ffbh_u32_e32 v80, v143
	v_min_u32_e32 v80, 32, v80
	v_lshlrev_b64 v[142:143], v80, v[142:143]
	v_min_u32_e32 v141, 1, v142
	v_or_b32_e32 v141, v143, v141
	v_cvt_f32_u32_e32 v141, v141
	v_sub_u32_e32 v80, 32, v80
	v_ldexp_f32 v141, v141, v80
	v_pk_mul_f32 v[140:141], v[140:141], s[60:61] op_sel_hi:[1,0]
	s_nop 0
	v_pk_fma_f32 v[140:141], v[140:141], s[26:27], v[136:137] op_sel_hi:[1,0,0]
	s_nop 0
	v_mul_f32_e32 v80, 0x4b800000, v140
	v_cmp_gt_f32_e64 s[2:3], s50, v140
	v_cmp_gt_f32_e32 vcc, s50, v141
	s_nop 0
	v_cndmask_b32_e64 v80, v140, v80, s[2:3]
	v_rsq_f32_e32 v140, v80
	v_mul_f32_e32 v80, 0x4b800000, v141
	v_cndmask_b32_e32 v80, v141, v80, vcc
	v_rsq_f32_e32 v141, v80
	v_ffbh_u32_e32 v80, v145
	v_min_u32_e32 v80, 32, v80
	v_lshlrev_b64 v[144:145], v80, v[144:145]
	v_pk_mul_f32 v[142:143], v[140:141], s[64:65] op_sel_hi:[1,0]
	v_min_u32_e32 v144, 1, v144
	v_cndmask_b32_e64 v140, v140, v142, s[2:3]
	v_add_u32_e32 v142, 2, v146
	v_cndmask_b32_e32 v141, v141, v143, vcc
	v_ashrrev_i32_e32 v143, 31, v142
	v_lshlrev_b64 v[142:143], s18, v[142:143]
	v_lshl_add_u64 v[142:143], v[142:143], 3, v[148:149]
	global_load_dwordx2 v[142:143], v[142:143], off
	v_or_b32_e32 v144, v145, v144
	v_cvt_f32_u32_e32 v144, v144
	v_sub_u32_e32 v80, 32, v80
	v_pk_mul_f32 v[118:119], v[118:119], v[140:141]
	v_pk_mul_f32 v[102:103], v[102:103], v[140:141]
	v_ldexp_f32 v145, v144, v80
	v_pk_mul_f32 v[86:87], v[86:87], v[140:141]
	v_pk_mul_f32 v[68:69], v[68:69], v[140:141]
	v_pk_mul_f32 v[52:53], v[52:53], v[140:141]
	v_pk_mul_f32 v[36:37], v[36:37], v[140:141]
	v_pk_mul_f32 v[20:21], v[20:21], v[140:141]
	v_pk_mul_f32 v[4:5], v[4:5], v[140:141]
	s_waitcnt vmcnt(0) lgkmcnt(0)
; __device__ __forceinline__ unsigned cvt_pk_bf16(float lo, float hi) { unsigned r; asm("v_cvt_pk_bf16_f32 %0, %1, %2" : "=v"(r) : "v"(lo), "v"(hi)); return r; }
; __device__ __forceinline__ float rinv_of(unsigned long long ss) { return rsqrtf((float)ss * (1.f / 16777216.f) * (1.f / DM) + 1e-6f); }
;   __device__ __forceinline__ void operator()(const f32x4 (&acc)[2][2][4][2], const Unit& u, const EpiCtx& x_, int wr, int wc, int fr, int fq) const {
;     ...
;     { const int lg = x_.p0, S = x_.p1, L = S >> lg;
; #pragma unroll
;       for (int bj = 0; bj < 2; ++bj) {
;         const int col = u.c0 + wc * 64 + bj * 32 + 8 * fq, seq = col / S, rem = col % S, r = rem / L, m0 = rem % L;
;         const unsigned long long* sp = x_.ss + (size_t)seq * S + r;
; #pragma unroll
;         for (int i = 0; i < 8; ++i) cs[bj][i >> 2][i & 3] = rinv_of(sp[(size_t)(m0 + i) << lg]);
;       } }
; #pragma unroll
;     for (int ai = 0; ai < 2; ++ai)
; #pragma unroll
;       for (int m = 0; m < 4; ++m) {
;         const int row = u.r0 + ai * 128 + wr * 64 + m * 16 + fr, hh = (x_.p0 >> 1) * 16 + (row >> 7), d = row & 127;
; #pragma unroll
;         for (int bj = 0; bj < 2; ++bj) {
;           const int col = u.c0 + wc * 64 + bj * 32 + 8 * fq;
;           const f32x4 v0 = acc[ai][bj][m][0] * cs[bj][0], v1 = acc[ai][bj][m][1] * cs[bj][1];
;           uint4 o; o.x = cvt_pk_bf16(v0[0], v0[1]); o.y = cvt_pk_bf16(v0[2], v0[3]); o.z = cvt_pk_bf16(v1[0], v1[1]); o.w = cvt_pk_bf16(v1[2], v1[3]);
;           *(uint4*)((bf16_t*)u.C + (((size_t)hh * (TS / 32) + (col >> 5)) * 128 + d) * 32 + (col & 31)) = o;
;         }
	v_ffbh_u32_e32 v80, v143
	v_min_u32_e32 v80, 32, v80
	v_lshlrev_b64 v[142:143], v80, v[142:143]
	v_min_u32_e32 v142, 1, v142
	v_or_b32_e32 v142, v143, v142
	v_cvt_f32_u32_e32 v142, v142
	v_sub_u32_e32 v80, 32, v80
	v_ldexp_f32 v144, v142, v80
	v_pk_mul_f32 v[142:143], v[144:145], s[60:61] op_sel_hi:[1,0]
	s_nop 0
	v_pk_fma_f32 v[142:143], v[142:143], s[26:27], v[136:137] op_sel_hi:[1,0,0]
	s_nop 0
	v_mul_f32_e32 v80, 0x4b800000, v142
	v_cmp_gt_f32_e64 s[2:3], s50, v142
	v_cmp_gt_f32_e32 vcc, s50, v143
	s_nop 0
	v_cndmask_b32_e64 v80, v142, v80, s[2:3]
	v_rsq_f32_e32 v142, v80
	v_mul_f32_e32 v80, 0x4b800000, v143
	v_cndmask_b32_e32 v80, v143, v80, vcc
	v_rsq_f32_e32 v143, v80
	v_ffbh_u32_e32 v80, v151
	v_min_u32_e32 v80, 32, v80
	v_lshlrev_b64 v[150:151], v80, v[150:151]
	v_pk_mul_f32 v[144:145], v[142:143], s[64:65] op_sel_hi:[1,0]
	v_min_u32_e32 v147, 1, v150
	v_cndmask_b32_e64 v142, v142, v144, s[2:3]
	v_add_u32_e32 v144, 4, v146
	v_cndmask_b32_e32 v143, v143, v145, vcc
	v_ashrrev_i32_e32 v145, 31, v144
	v_lshlrev_b64 v[144:145], s18, v[144:145]
	v_lshl_add_u64 v[144:145], v[144:145], 3, v[148:149]
	global_load_dwordx2 v[144:145], v[144:145], off
	v_or_b32_e32 v147, v151, v147
	v_cvt_f32_u32_e32 v147, v147
	v_sub_u32_e32 v80, 32, v80
	v_pk_mul_f32 v[120:121], v[120:121], v[142:143]
	v_pk_mul_f32 v[104:105], v[104:105], v[142:143]
	v_ldexp_f32 v151, v147, v80
	v_pk_mul_f32 v[88:89], v[88:89], v[142:143]
	v_pk_mul_f32 v[70:71], v[70:71], v[142:143]
	v_pk_mul_f32 v[54:55], v[54:55], v[142:143]
	v_pk_mul_f32 v[38:39], v[38:39], v[142:143]
	v_pk_mul_f32 v[22:23], v[22:23], v[142:143]
	v_pk_mul_f32 v[6:7], v[6:7], v[142:143]
	s_waitcnt vmcnt(0) lgkmcnt(0)
	v_ffbh_u32_e32 v80, v145
	v_min_u32_e32 v80, 32, v80
	v_lshlrev_b64 v[144:145], v80, v[144:145]
	v_min_u32_e32 v144, 1, v144
	v_or_b32_e32 v144, v145, v144
	v_cvt_f32_u32_e32 v144, v144
	v_sub_u32_e32 v80, 32, v80
	v_ldexp_f32 v150, v144, v80
	v_pk_mul_f32 v[144:145], v[150:151], s[60:61] op_sel_hi:[1,0]
	s_nop 0
	v_pk_fma_f32 v[144:145], v[144:145], s[26:27], v[136:137] op_sel_hi:[1,0,0]
	s_nop 0
	v_mul_f32_e32 v80, 0x4b800000, v144
	v_cmp_gt_f32_e64 s[2:3], s50, v144
	v_cmp_gt_f32_e32 vcc, s50, v145
	s_nop 0
	v_cndmask_b32_e64 v80, v144, v80, s[2:3]
	v_rsq_f32_e32 v144, v80
	v_mul_f32_e32 v80, 0x4b800000, v145
	v_cndmask_b32_e32 v80, v145, v80, vcc
	v_rsq_f32_e32 v145, v80
	s_nop 0
	v_pk_mul_f32 v[150:151], v[144:145], s[64:65] op_sel_hi:[1,0]
	s_nop 0
	v_cndmask_b32_e64 v144, v144, v150, s[2:3]
	v_add_u32_e32 v150, 6, v146
	v_add_u32_e32 v146, 7, v146
	v_cndmask_b32_e32 v145, v145, v151, vcc
	v_ashrrev_i32_e32 v151, 31, v150
	v_ashrrev_i32_e32 v147, 31, v146
	v_lshlrev_b64 v[150:151], s18, v[150:151]
	v_lshlrev_b64 v[146:147], s18, v[146:147]
	v_lshl_add_u64 v[150:151], v[150:151], 3, v[148:149]
	v_lshl_add_u64 v[146:147], v[146:147], 3, v[148:149]
	global_load_dwordx2 v[150:151], v[150:151], off
	v_pk_mul_f32 v[114:115], v[114:115], v[144:145]
	global_load_dwordx2 v[146:147], v[146:147], off
	s_waitcnt vmcnt(0) lgkmcnt(0)
	v_ffbh_u32_e32 v80, v147
	v_min_u32_e32 v80, 32, v80
	v_lshlrev_b64 v[146:147], v80, v[146:147]
	v_min_u32_e32 v146, 1, v146
	v_or_b32_e32 v146, v147, v146
	v_cvt_f32_u32_e32 v146, v146
	v_sub_u32_e32 v80, 32, v80
	v_ldexp_f32 v147, v146, v80
	v_ffbh_u32_e32 v80, v151
	v_min_u32_e32 v80, 32, v80
	v_lshlrev_b64 v[148:149], v80, v[150:151]
	v_min_u32_e32 v146, 1, v148
	v_or_b32_e32 v146, v149, v146
	v_cvt_f32_u32_e32 v146, v146
	v_sub_u32_e32 v80, 32, v80
	v_ldexp_f32 v146, v146, v80
	v_pk_mul_f32 v[146:147], v[146:147], s[60:61] op_sel_hi:[1,0]
	s_nop 0
	v_pk_fma_f32 v[136:137], v[146:147], s[26:27], v[136:137] op_sel_hi:[1,0,0]
	s_nop 0
	v_mul_f32_e32 v80, 0x4b800000, v136
	v_cmp_gt_f32_e64 s[2:3], s50, v136
	v_cmp_gt_f32_e32 vcc, s50, v137
	s_nop 0
	v_cndmask_b32_e64 v80, v136, v80, s[2:3]
	v_rsq_f32_e32 v136, v80
	v_mul_f32_e32 v80, 0x4b800000, v137
	v_cndmask_b32_e32 v80, v137, v80, vcc
	v_rsq_f32_e32 v137, v80
	v_add_u32_e32 v80, s75, v157
	v_pk_mul_f32 v[146:147], v[136:137], s[64:65] op_sel_hi:[1,0]
	s_nop 0
	v_cndmask_b32_e64 v136, v136, v146, s[2:3]
	v_ashrrev_i32_e32 v146, 7, v80
	v_add_u32_e32 v146, s82, v146
	v_cndmask_b32_e32 v137, v137, v147, vcc
	v_ashrrev_i32_e32 v147, 31, v146
	v_lshlrev_b64 v[146:147], 22, v[146:147]
	v_lshlrev_b32_e32 v80, 6, v80
	v_and_b32_e32 v80, 0x1fc0, v80
	v_lshl_add_u64 v[124:125], v[122:123], 0, v[146:147]
	v_lshl_add_u64 v[148:149], v[124:125], 0, v[80:81]
	v_and_b32_e32 v124, 31, v171
	v_lshlrev_b32_e32 v124, 1, v124
	v_mov_b32_e32 v125, v81
	v_lshl_add_u64 v[148:149], v[148:149], 0, v[124:125]
	global_store_dwordx4 v[148:149], v[126:129], off
	s_mov_b64 s[2:3], s[8:9]
	s_nop 0
	v_add_u32_e32 v128, s97, v160
	v_pk_mul_f32 v[126:127], v[116:117], v[136:137]
	v_cvt_pk_bf16_f32 v116, v118, v119
	v_cvt_pk_bf16_f32 v118, v114, v115
	v_ashrrev_i32_e32 v114, 5, v128
	v_ashrrev_i32_e32 v115, 31, v114
	v_lshlrev_b64 v[114:115], 13, v[114:115]
	v_lshl_add_u64 v[114:115], s[94:95], 0, v[114:115]
	v_cvt_pk_bf16_f32 v117, v120, v121
	v_lshl_add_u64 v[120:121], v[114:115], 0, v[146:147]
	v_lshl_add_u64 v[120:121], v[120:121], 0, v[80:81]
	v_and_b32_e32 v80, 31, v128
	v_lshlrev_b32_e32 v80, 1, v80
	v_lshl_add_u64 v[120:121], v[120:121], 0, v[80:81]
	v_cvt_pk_bf16_f32 v119, v126, v127
	global_store_dwordx4 v[120:121], v[116:119], off
	v_add_u32_e32 v120, s75, v161
	s_mov_b64 s[94:95], s[40:41]
	v_ashrrev_i32_e32 v116, 7, v120
	v_add_u32_e32 v116, s82, v116
	v_ashrrev_i32_e32 v117, 31, v116
	v_pk_mul_f32 v[118:119], v[108:109], v[138:139]
	v_pk_mul_f32 v[108:109], v[106:107], v[134:135]
	v_cvt_pk_bf16_f32 v106, v110, v111
; __device__ __forceinline__ unsigned cvt_pk_bf16(float lo, float hi) { unsigned r; asm("v_cvt_pk_bf16_f32 %0, %1, %2" : "=v"(r) : "v"(lo), "v"(hi)); return r; }
;   __device__ __forceinline__ void operator()(const f32x4 (&acc)[2][2][4][2], const Unit& u, const EpiCtx& x_, int wr, int wc, int fr, int fq) const {
;     ...
; #pragma unroll
;     for (int ai = 0; ai < 2; ++ai)
; #pragma unroll
;       for (int m = 0; m < 4; ++m) {
;         const int row = u.r0 + ai * 128 + wr * 64 + m * 16 + fr, hh = (x_.p0 >> 1) * 16 + (row >> 7), d = row & 127;
; #pragma unroll
;         for (int bj = 0; bj < 2; ++bj) {
;           const int col = u.c0 + wc * 64 + bj * 32 + 8 * fq;
;           const f32x4 v0 = acc[ai][bj][m][0] * cs[bj][0], v1 = acc[ai][bj][m][1] * cs[bj][1];
;           uint4 o; o.x = cvt_pk_bf16(v0[0], v0[1]); o.y = cvt_pk_bf16(v0[2], v0[3]); o.z = cvt_pk_bf16(v1[0], v1[1]); o.w = cvt_pk_bf16(v1[2], v1[3]);
;           *(uint4*)((bf16_t*)u.C + (((size_t)hh * (TS / 32) + (col >> 5)) * 128 + d) * 32 + (col & 31)) = o;
;         }
	v_cvt_pk_bf16_f32 v107, v112, v113
	v_lshlrev_b64 v[110:111], 22, v[116:117]
	v_lshlrev_b32_e32 v112, 6, v120
	v_and_b32_e32 v112, 0x1fc0, v112
	v_mov_b32_e32 v113, v81
	v_lshl_add_u64 v[116:117], v[122:123], 0, v[110:111]
	v_lshl_add_u64 v[116:117], v[116:117], 0, v[112:113]
	v_lshl_add_u64 v[116:117], v[116:117], 0, v[124:125]
	v_cvt_pk_bf16_f32 v108, v108, v109
	v_cvt_pk_bf16_f32 v109, v118, v119
	global_store_dwordx4 v[116:117], v[106:109], off
	s_mov_b32 s97, s42
	s_nop 0
	v_pk_mul_f32 v[106:107], v[100:101], v[136:137]
	v_pk_mul_f32 v[100:101], v[98:99], v[144:145]
	v_cvt_pk_bf16_f32 v98, v102, v103
	v_lshl_add_u64 v[102:103], v[114:115], 0, v[110:111]
	v_lshl_add_u64 v[102:103], v[102:103], 0, v[112:113]
	v_lshl_add_u64 v[102:103], v[102:103], 0, v[80:81]
	v_cvt_pk_bf16_f32 v99, v104, v105
	v_cvt_pk_bf16_f32 v100, v100, v101
	v_cvt_pk_bf16_f32 v101, v106, v107
	global_store_dwordx4 v[102:103], v[98:101], off
	v_add_u32_e32 v102, s75, v163
	s_nop 0
	v_ashrrev_i32_e32 v98, 7, v102
	v_add_u32_e32 v98, s82, v98
	v_ashrrev_i32_e32 v99, 31, v98
	v_pk_mul_f32 v[100:101], v[92:93], v[138:139]
	v_pk_mul_f32 v[92:93], v[90:91], v[134:135]
	v_cvt_pk_bf16_f32 v90, v94, v95
	v_cvt_pk_bf16_f32 v91, v96, v97
	v_lshlrev_b64 v[94:95], 22, v[98:99]
	v_lshlrev_b32_e32 v96, 6, v102
	v_and_b32_e32 v96, 0x1fc0, v96
	v_mov_b32_e32 v97, v81
	v_lshl_add_u64 v[98:99], v[122:123], 0, v[94:95]
	v_lshl_add_u64 v[98:99], v[98:99], 0, v[96:97]
	v_lshl_add_u64 v[98:99], v[98:99], 0, v[124:125]
	v_cvt_pk_bf16_f32 v92, v92, v93
	v_cvt_pk_bf16_f32 v93, v100, v101
	global_store_dwordx4 v[98:99], v[90:93], off
	s_nop 1
	v_pk_mul_f32 v[90:91], v[84:85], v[136:137]
	v_pk_mul_f32 v[84:85], v[82:83], v[144:145]
	v_cvt_pk_bf16_f32 v82, v86, v87
	v_lshl_add_u64 v[86:87], v[114:115], 0, v[94:95]
	v_lshl_add_u64 v[86:87], v[86:87], 0, v[96:97]
	v_lshl_add_u64 v[86:87], v[86:87], 0, v[80:81]
	v_cvt_pk_bf16_f32 v83, v88, v89
	v_cvt_pk_bf16_f32 v84, v84, v85
	v_cvt_pk_bf16_f32 v85, v90, v91
	global_store_dwordx4 v[86:87], v[82:85], off
	v_add_u32_e32 v86, s75, v164
	s_nop 0
	v_ashrrev_i32_e32 v82, 7, v86
	v_add_u32_e32 v82, s82, v82
	v_ashrrev_i32_e32 v83, 31, v82
	v_pk_mul_f32 v[84:85], v[74:75], v[138:139]
	v_pk_mul_f32 v[74:75], v[72:73], v[134:135]
	v_cvt_pk_bf16_f32 v72, v76, v77
	v_cvt_pk_bf16_f32 v73, v78, v79
	v_lshlrev_b64 v[76:77], 22, v[82:83]
	v_lshlrev_b32_e32 v78, 6, v86
	v_and_b32_e32 v78, 0x1fc0, v78
	v_mov_b32_e32 v79, v81
	v_lshl_add_u64 v[82:83], v[122:123], 0, v[76:77]
	v_lshl_add_u64 v[82:83], v[82:83], 0, v[78:79]
	v_lshl_add_u64 v[82:83], v[82:83], 0, v[124:125]
	v_cvt_pk_bf16_f32 v74, v74, v75
	v_cvt_pk_bf16_f32 v75, v84, v85
	global_store_dwordx4 v[82:83], v[72:75], off
	s_nop 1
	v_pk_mul_f32 v[72:73], v[66:67], v[136:137]
	v_pk_mul_f32 v[66:67], v[64:65], v[144:145]
	v_cvt_pk_bf16_f32 v64, v68, v69
	v_lshl_add_u64 v[68:69], v[114:115], 0, v[76:77]
	v_lshl_add_u64 v[68:69], v[68:69], 0, v[78:79]
	v_lshl_add_u64 v[68:69], v[68:69], 0, v[80:81]
	v_cvt_pk_bf16_f32 v65, v70, v71
	v_cvt_pk_bf16_f32 v66, v66, v67
	v_cvt_pk_bf16_f32 v67, v72, v73
	global_store_dwordx4 v[68:69], v[64:67], off
	v_add_u32_e32 v68, s75, v165
	s_nop 0
	v_ashrrev_i32_e32 v64, 7, v68
	v_add_u32_e32 v64, s82, v64
	v_ashrrev_i32_e32 v65, 31, v64
	v_pk_mul_f32 v[66:67], v[58:59], v[138:139]
	v_pk_mul_f32 v[58:59], v[56:57], v[134:135]
	v_cvt_pk_bf16_f32 v56, v60, v61
	v_cvt_pk_bf16_f32 v57, v62, v63
	v_lshlrev_b64 v[60:61], 22, v[64:65]
	v_lshlrev_b32_e32 v62, 6, v68
	v_and_b32_e32 v62, 0x1fc0, v62
	v_mov_b32_e32 v63, v81
	v_lshl_add_u64 v[64:65], v[122:123], 0, v[60:61]
	v_lshl_add_u64 v[64:65], v[64:65], 0, v[62:63]
	v_lshl_add_u64 v[64:65], v[64:65], 0, v[124:125]
	v_cvt_pk_bf16_f32 v58, v58, v59
	v_cvt_pk_bf16_f32 v59, v66, v67
	global_store_dwordx4 v[64:65], v[56:59], off
	s_nop 1
; __device__ __forceinline__ unsigned cvt_pk_bf16(float lo, float hi) { unsigned r; asm("v_cvt_pk_bf16_f32 %0, %1, %2" : "=v"(r) : "v"(lo), "v"(hi)); return r; }
; #define G_WAIT_V(n) asm volatile("s_waitcnt vmcnt(" #n ")" ::: "memory")
; #define G_BAR __builtin_amdgcn_s_barrier()
;   __device__ __forceinline__ void operator()(const f32x4 (&acc)[2][2][4][2], const Unit& u, const EpiCtx& x_, int wr, int wc, int fr, int fq) const {
;     ...
; #pragma unroll
;     for (int ai = 0; ai < 2; ++ai)
; #pragma unroll
;       for (int m = 0; m < 4; ++m) {
;         const int row = u.r0 + ai * 128 + wr * 64 + m * 16 + fr, hh = (x_.p0 >> 1) * 16 + (row >> 7), d = row & 127;
; #pragma unroll
;         for (int bj = 0; bj < 2; ++bj) {
;           const int col = u.c0 + wc * 64 + bj * 32 + 8 * fq;
;           const f32x4 v0 = acc[ai][bj][m][0] * cs[bj][0], v1 = acc[ai][bj][m][1] * cs[bj][1];
;           uint4 o; o.x = cvt_pk_bf16(v0[0], v0[1]); o.y = cvt_pk_bf16(v0[2], v0[3]); o.z = cvt_pk_bf16(v1[0], v1[1]); o.w = cvt_pk_bf16(v1[2], v1[3]);
;           *(uint4*)((bf16_t*)u.C + (((size_t)hh * (TS / 32) + (col >> 5)) * 128 + d) * 32 + (col & 31)) = o;
;         }
; template <class Epi>
; __device__ __forceinline__ void gemm_phase(LAS unsigned char* lds, const int K, const unsigned lda_b, const unsigned ldb_b, const Map& M, const Epi& E) {
;     ...
;     if (!has_next) break;
; #pragma unroll
;     for (int a = 0; a < 2; ++a)
; #pragma unroll
;       for (int b = 0; b < 2; ++b)
; #pragma unroll
;         for (int m = 0; m < 4; ++m)
; #pragma unroll
;           for (int n = 0; n < 2; ++n) acc[a][b][m][n] = (f32x4){0.f, 0.f, 0.f, 0.f};
;     cur = nxt; ++ui;
;   }
;   G_WAIT_V(0);
;   if (wr == 0) G_BAR;
;   G_BAR;
	v_pk_mul_f32 v[56:57], v[50:51], v[136:137]
	v_pk_mul_f32 v[50:51], v[48:49], v[144:145]
	v_cvt_pk_bf16_f32 v48, v52, v53
	v_lshl_add_u64 v[52:53], v[114:115], 0, v[60:61]
	v_lshl_add_u64 v[52:53], v[52:53], 0, v[62:63]
	v_lshl_add_u64 v[52:53], v[52:53], 0, v[80:81]
	v_cvt_pk_bf16_f32 v49, v54, v55
	v_cvt_pk_bf16_f32 v50, v50, v51
	v_cvt_pk_bf16_f32 v51, v56, v57
	global_store_dwordx4 v[52:53], v[48:51], off
	v_add_u32_e32 v52, s75, v166
	s_nop 0
	v_ashrrev_i32_e32 v48, 7, v52
	v_add_u32_e32 v48, s82, v48
	v_ashrrev_i32_e32 v49, 31, v48
	v_pk_mul_f32 v[50:51], v[42:43], v[138:139]
	v_pk_mul_f32 v[42:43], v[40:41], v[134:135]
	v_cvt_pk_bf16_f32 v40, v44, v45
	v_cvt_pk_bf16_f32 v41, v46, v47
	v_lshlrev_b64 v[44:45], 22, v[48:49]
	v_lshlrev_b32_e32 v46, 6, v52
	v_and_b32_e32 v46, 0x1fc0, v46
	v_mov_b32_e32 v47, v81
	v_lshl_add_u64 v[48:49], v[122:123], 0, v[44:45]
	v_lshl_add_u64 v[48:49], v[48:49], 0, v[46:47]
	v_lshl_add_u64 v[48:49], v[48:49], 0, v[124:125]
	v_cvt_pk_bf16_f32 v42, v42, v43
	v_cvt_pk_bf16_f32 v43, v50, v51
	global_store_dwordx4 v[48:49], v[40:43], off
	s_nop 1
	v_pk_mul_f32 v[40:41], v[34:35], v[136:137]
	v_pk_mul_f32 v[34:35], v[32:33], v[144:145]
	v_cvt_pk_bf16_f32 v32, v36, v37
	v_lshl_add_u64 v[36:37], v[114:115], 0, v[44:45]
	v_lshl_add_u64 v[36:37], v[36:37], 0, v[46:47]
	v_lshl_add_u64 v[36:37], v[36:37], 0, v[80:81]
	v_cvt_pk_bf16_f32 v33, v38, v39
	v_cvt_pk_bf16_f32 v34, v34, v35
	v_cvt_pk_bf16_f32 v35, v40, v41
	global_store_dwordx4 v[36:37], v[32:35], off
	v_add_u32_e32 v36, s75, v167
	s_nop 0
	v_ashrrev_i32_e32 v32, 7, v36
	v_add_u32_e32 v32, s82, v32
	v_ashrrev_i32_e32 v33, 31, v32
	v_pk_mul_f32 v[34:35], v[26:27], v[138:139]
	v_pk_mul_f32 v[26:27], v[24:25], v[134:135]
	v_cvt_pk_bf16_f32 v24, v28, v29
	v_cvt_pk_bf16_f32 v25, v30, v31
	v_lshlrev_b64 v[28:29], 22, v[32:33]
	v_lshlrev_b32_e32 v30, 6, v36
	v_and_b32_e32 v30, 0x1fc0, v30
	v_mov_b32_e32 v31, v81
	v_lshl_add_u64 v[32:33], v[122:123], 0, v[28:29]
	v_lshl_add_u64 v[32:33], v[32:33], 0, v[30:31]
	v_lshl_add_u64 v[32:33], v[32:33], 0, v[124:125]
	v_cvt_pk_bf16_f32 v26, v26, v27
	v_cvt_pk_bf16_f32 v27, v34, v35
	global_store_dwordx4 v[32:33], v[24:27], off
	s_nop 1
	v_pk_mul_f32 v[24:25], v[18:19], v[136:137]
	v_pk_mul_f32 v[18:19], v[16:17], v[144:145]
	v_cvt_pk_bf16_f32 v16, v20, v21
	v_lshl_add_u64 v[20:21], v[114:115], 0, v[28:29]
	v_lshl_add_u64 v[20:21], v[20:21], 0, v[30:31]
	v_lshl_add_u64 v[20:21], v[20:21], 0, v[80:81]
	v_cvt_pk_bf16_f32 v17, v22, v23
	v_cvt_pk_bf16_f32 v18, v18, v19
	v_cvt_pk_bf16_f32 v19, v24, v25
	global_store_dwordx4 v[20:21], v[16:19], off
	v_add_u32_e32 v20, s75, v168
	s_mov_b32 s75, s0
	v_ashrrev_i32_e32 v16, 7, v20
	v_add_u32_e32 v16, s82, v16
	v_ashrrev_i32_e32 v17, 31, v16
	v_pk_mul_f32 v[18:19], v[10:11], v[138:139]
	v_pk_mul_f32 v[10:11], v[8:9], v[134:135]
	v_cvt_pk_bf16_f32 v8, v12, v13
	v_cvt_pk_bf16_f32 v9, v14, v15
	v_lshlrev_b64 v[12:13], 22, v[16:17]
	v_lshlrev_b32_e32 v14, 6, v20
	v_and_b32_e32 v14, 0x1fc0, v14
	v_mov_b32_e32 v15, v81
	v_lshl_add_u64 v[16:17], v[122:123], 0, v[12:13]
	v_lshl_add_u64 v[16:17], v[16:17], 0, v[14:15]
	v_lshl_add_u64 v[16:17], v[16:17], 0, v[124:125]
	v_cvt_pk_bf16_f32 v10, v10, v11
	v_cvt_pk_bf16_f32 v11, v18, v19
	global_store_dwordx4 v[16:17], v[8:11], off
	s_nop 1
	v_pk_mul_f32 v[8:9], v[2:3], v[136:137]
	v_pk_mul_f32 v[2:3], v[0:1], v[144:145]
	v_cvt_pk_bf16_f32 v0, v4, v5
	v_lshl_add_u64 v[4:5], v[114:115], 0, v[12:13]
	v_lshl_add_u64 v[4:5], v[4:5], 0, v[14:15]
	v_lshl_add_u64 v[4:5], v[4:5], 0, v[80:81]
	v_cvt_pk_bf16_f32 v1, v6, v7
	v_cvt_pk_bf16_f32 v2, v2, v3
	v_cvt_pk_bf16_f32 v3, v8, v9
	global_store_dwordx4 v[4:5], v[0:3], off
	s_cbranch_scc0 .LBB0_650
	s_waitcnt vmcnt(0)
	s_cmpk_gt_u32 s19, 0xff
	s_mov_b32 s86, 0x7f800000
	s_brev_b32 s82, 1
	s_cbranch_scc1 .LBB0_632
	s_barrier
	s_branch .LBB0_632

; #define LAS __attribute__((address_space(3)))
; __device__ __forceinline__ int otid() { int t = threadIdx.x; asm volatile("" : "+v"(t)); return t; }
; __device__ __forceinline__ unsigned xb_ld(unsigned* p) { return __hip_atomic_load(p, __ATOMIC_RELAXED, __HIP_MEMORY_SCOPE_AGENT); }
; __device__ __forceinline__ unsigned xb_add(unsigned* p, unsigned v) { return __hip_atomic_fetch_add(p, v, __ATOMIC_RELAXED, __HIP_MEMORY_SCOPE_AGENT); }
; __device__ __forceinline__ void gbar(unsigned* bar, unsigned n, volatile LAS unsigned* st) {
;   asm volatile("s_waitcnt vmcnt(0)" ::: "memory");
;   __syncthreads();
;   if (otid() == 0) {
;     __builtin_amdgcn_s_waitcnt(0);
;     const unsigned x = st[0], nloc = st[1], nx = st[2];
;     const unsigned old = xb_add(&bar[XB_XSUB(x)], 1u);
;     unsigned sp = 0;
;     if (old + 1u == (n + 1u) * nloc) {
;       __builtin_amdgcn_fence(__ATOMIC_RELEASE, "agent");
;       asm volatile("s_waitcnt vmcnt(0)" ::: "memory");
;       xb_add(&bar[XB_TOP], 1u);
;       while (xb_ld(&bar[XB_TOP]) < (n + 1u) * nx) { __builtin_amdgcn_s_sleep(1); if (++sp > (1u << 24)) break; }
;       __builtin_amdgcn_fence(__ATOMIC_ACQUIRE, "agent");
;       xb_add(&bar[XB_XGEN(x)], 1u);
;       asm volatile("s_waitcnt vmcnt(0)" ::: "memory");
;     } else {
;       while (xb_ld(&bar[XB_XGEN(x)]) <= n) { __builtin_amdgcn_s_sleep(1); if (++sp > (1u << 24)) break; }
;       __builtin_amdgcn_fence(__ATOMIC_ACQUIRE, "agent");
;       asm volatile("s_waitcnt vmcnt(0)" ::: "memory");
;     }
;   }
;   __syncthreads();
; }
.LBB0_656:
	v_mov_b64_e32 v[0:1], s[10:11]
	global_load_dwordx2 v[0:1], v[0:1], off sc0 sc1
	s_waitcnt vmcnt(0)
	s_waitcnt vmcnt(0)
	v_mov_b32_e32 v2, v252
	s_waitcnt lgkmcnt(0)
	s_barrier
	v_add_u32_e32 v181, 2, v236
	v_cmp_ne_u32_e32 vcc, 0, v2
	v_readfirstlane_b32 s0, v1
	v_readfirstlane_b32 s1, v0
	s_and_saveexec_b64 s[2:3], vcc
	s_xor_b64 s[2:3], exec, s[2:3]
	v_add_u32_e32 v181, 2, v236
	s_andn2_saveexec_b64 s[2:3], s[2:3]
	s_cbranch_execz .LBB0_709
	v_readlane_b32 s8, v255, 15
	s_waitcnt vmcnt(0) expcnt(0) lgkmcnt(0)
	s_add_u32 s4, s1, 0x4cc80000
	v_mov_b32_e32 v0, s8
	ds_read_b32 v1, v0
	v_readlane_b32 s8, v255, 16
	s_addc_u32 s5, s0, 0
	s_waitcnt lgkmcnt(0)
	v_lshlrev_b32_e32 v1, 6, v1
	v_add_u32_e32 v80, 0x440, v1
	v_mov_b32_e32 v0, s8
	v_readlane_b32 s8, v255, 17
	v_lshlrev_b64 v[2:3], 2, v[80:81]
	ds_read_b32 v4, v0
	v_mov_b32_e32 v0, s8
	v_lshl_add_u64 v[2:3], s[4:5], 0, v[2:3]
	ds_read_b32 v0, v0
	global_atomic_add v2, v[2:3], v230, off sc0
	s_waitcnt lgkmcnt(0)
	v_mul_lo_u32 v3, v4, v181
	v_add_u32_e32 v80, 0x840, v1
	s_waitcnt vmcnt(0)
	v_add_u32_e32 v2, 1, v2
	v_cmp_ne_u32_e32 vcc, v2, v3
	s_and_saveexec_b64 s[8:9], vcc
	s_xor_b64 s[8:9], exec, s[8:9]
	s_cbranch_execz .LBB0_685
	v_lshlrev_b64 v[0:1], 2, v[80:81]
	v_lshl_add_u64 v[0:1], s[4:5], 0, v[0:1]
	s_mov_b32 s13, 0x1000000
	s_mov_b64 s[36:37], 0
	s_branch .LBB0_673

; __device__ __forceinline__ unsigned xb_ld(unsigned* p) { return __hip_atomic_load(p, __ATOMIC_RELAXED, __HIP_MEMORY_SCOPE_AGENT); }
; __device__ __forceinline__ void gbar(unsigned* bar, unsigned n, volatile LAS unsigned* st) {
;     ...
;       while (xb_ld(&bar[XB_XGEN(x)]) <= n) { __builtin_amdgcn_s_sleep(1); if (++sp > (1u << 24)) break; }
.LBB0_673:
	global_load_dword v2, v[0:1], off sc1
	s_or_b64 s[38:39], s[38:39], exec
	s_waitcnt vmcnt(0) lgkmcnt(0)
	v_cmp_le_u32_e32 vcc, v2, v162
	s_and_saveexec_b64 s[40:41], vcc
	s_cbranch_execz .LBB0_672
	s_cmp_lg_u32 s13, 0
	s_sleep 1
	s_cbranch_scc0 .LBB0_683
	global_load_dword v2, v[0:1], off sc1
	s_mov_b64 s[18:19], -1
	s_waitcnt vmcnt(0) lgkmcnt(0)
	v_cmp_le_u32_e32 vcc, v2, v162
	s_and_saveexec_b64 s[42:43], vcc
	s_cbranch_execz .LBB0_670
	s_sleep 1
	global_load_dword v2, v[0:1], off sc1
	s_waitcnt vmcnt(0) lgkmcnt(0)
	v_cmp_le_u32_e32 vcc, v2, v162
	s_and_saveexec_b64 s[44:45], vcc
	s_cbranch_execz .LBB0_669
	s_sleep 1
	global_load_dword v2, v[0:1], off sc1
	s_waitcnt vmcnt(0) lgkmcnt(0)
	v_cmp_le_u32_e32 vcc, v2, v162
	s_and_saveexec_b64 s[46:47], vcc
	s_cbranch_execz .LBB0_668
	s_sleep 1
	global_load_dword v2, v[0:1], off sc1
	s_waitcnt vmcnt(0) lgkmcnt(0)
	v_cmp_le_u32_e32 vcc, v2, v162
	s_and_saveexec_b64 s[68:69], vcc
	s_cbranch_execz .LBB0_667
	s_sleep 1
	global_load_dword v2, v[0:1], off sc1
	s_waitcnt vmcnt(0) lgkmcnt(0)
	v_cmp_le_u32_e32 vcc, v2, v162
	s_and_saveexec_b64 s[94:95], vcc
	s_cbranch_execz .LBB0_666
	s_sleep 1
	global_load_dword v2, v[0:1], off sc1
	s_mov_b64 s[48:49], -1
	s_waitcnt vmcnt(0) lgkmcnt(0)
	v_cmp_le_u32_e32 vcc, v2, v162
	s_and_saveexec_b64 s[18:19], vcc
	s_cbranch_execz .LBB0_665
	s_sleep 1
	global_load_dword v2, v[0:1], off sc1
	s_waitcnt vmcnt(0) lgkmcnt(0)
	v_cmp_le_u32_e32 vcc, v2, v162
	s_and_saveexec_b64 s[66:67], vcc
	s_cbranch_execz .LBB0_664
	s_add_i32 s13, s13, -8
	s_xor_b64 s[48:49], exec, -1
	s_sleep 1
	s_branch .LBB0_664

; __device__ __forceinline__ unsigned xb_ld(unsigned* p) { return __hip_atomic_load(p, __ATOMIC_RELAXED, __HIP_MEMORY_SCOPE_AGENT); }
; __device__ __forceinline__ unsigned xb_add(unsigned* p, unsigned v) { return __hip_atomic_fetch_add(p, v, __ATOMIC_RELAXED, __HIP_MEMORY_SCOPE_AGENT); }
; __device__ __forceinline__ void gbar(unsigned* bar, unsigned n, volatile LAS unsigned* st) {
;     ...
;     if (old + 1u == (n + 1u) * nloc) {
;       __builtin_amdgcn_fence(__ATOMIC_RELEASE, "agent");
;       asm volatile("s_waitcnt vmcnt(0)" ::: "memory");
;       xb_add(&bar[XB_TOP], 1u);
;       while (xb_ld(&bar[XB_TOP]) < (n + 1u) * nx) { __builtin_amdgcn_s_sleep(1); if (++sp > (1u << 24)) break; }
.LBB0_685:
	s_andn2_saveexec_b64 s[8:9], s[8:9]
	s_cbranch_execz .LBB0_708
	v_mov_b32_e32 v1, s1
	v_add_co_u32_e32 v2, vcc, 0x4cc83000, v1
	v_mov_b32_e32 v1, s0
	buffer_wbl2 sc1
	s_waitcnt vmcnt(0)
	v_addc_co_u32_e32 v3, vcc, 0, v1, vcc
	global_atomic_add v[2:3], v230, off offset:256
	s_add_u32 s36, s1, 0x4cc83100
	s_addc_u32 s37, s0, 0
	v_mul_lo_u32 v0, v0, v181
	s_mov_b32 s0, 0x1000000
	s_mov_b64 s[38:39], 0
	s_branch .LBB0_696

; __device__ __forceinline__ unsigned xb_ld(unsigned* p) { return __hip_atomic_load(p, __ATOMIC_RELAXED, __HIP_MEMORY_SCOPE_AGENT); }
; __device__ __forceinline__ void gbar(unsigned* bar, unsigned n, volatile LAS unsigned* st) {
;     ...
;       while (xb_ld(&bar[XB_TOP]) < (n + 1u) * nx) { __builtin_amdgcn_s_sleep(1); if (++sp > (1u << 24)) break; }
.LBB0_696:
	v_mov_b64_e32 v[2:3], s[36:37]
	global_load_dword v1, v[2:3], off sc1
	s_or_b64 s[40:41], s[40:41], exec
	s_waitcnt vmcnt(0) lgkmcnt(0)
	v_cmp_lt_u32_e32 vcc, v1, v0
	s_and_saveexec_b64 s[42:43], vcc
	s_cbranch_execz .LBB0_695
	s_cmp_lg_u32 s0, 0
	s_sleep 1
	s_cbranch_scc0 .LBB0_706
	v_mov_b64_e32 v[2:3], s[36:37]
	global_load_dword v1, v[2:3], off sc1
	s_mov_b64 s[18:19], -1
	s_waitcnt vmcnt(0) lgkmcnt(0)
	v_cmp_lt_u32_e32 vcc, v1, v0
	s_and_saveexec_b64 s[44:45], vcc
	s_cbranch_execz .LBB0_693
	v_mov_b64_e32 v[2:3], s[36:37]
	s_sleep 1
	global_load_dword v1, v[2:3], off sc1
	s_waitcnt vmcnt(0) lgkmcnt(0)
	v_cmp_lt_u32_e32 vcc, v1, v0
	s_and_saveexec_b64 s[68:69], vcc
	s_cbranch_execz .LBB0_692
	v_mov_b64_e32 v[2:3], s[36:37]
	s_sleep 1
	global_load_dword v1, v[2:3], off sc1
	s_waitcnt vmcnt(0) lgkmcnt(0)
	v_cmp_lt_u32_e32 vcc, v1, v0
	s_and_saveexec_b64 s[46:47], vcc
	s_cbranch_execz .LBB0_691
	v_mov_b64_e32 v[2:3], s[36:37]
	s_sleep 1
	global_load_dword v1, v[2:3], off sc1
	s_waitcnt vmcnt(0) lgkmcnt(0)
	v_cmp_lt_u32_e32 vcc, v1, v0
	s_and_saveexec_b64 s[94:95], vcc
	s_cbranch_execz .LBB0_690
	v_mov_b64_e32 v[2:3], s[36:37]
	s_sleep 1
	global_load_dword v1, v[2:3], off sc1
	s_waitcnt vmcnt(0) lgkmcnt(0)
	v_cmp_lt_u32_e32 vcc, v1, v0
	s_and_saveexec_b64 s[96:97], vcc
	s_cbranch_execz .LBB0_689
	v_mov_b64_e32 v[2:3], s[36:37]
	s_sleep 1
	global_load_dword v1, v[2:3], off sc1
	s_mov_b64 s[48:49], -1
	s_waitcnt vmcnt(0) lgkmcnt(0)
	v_cmp_lt_u32_e32 vcc, v1, v0
	s_and_saveexec_b64 s[18:19], vcc
	s_cbranch_execz .LBB0_688
	v_mov_b64_e32 v[2:3], s[36:37]
	s_sleep 1
	global_load_dword v1, v[2:3], off sc1
	s_waitcnt vmcnt(0) lgkmcnt(0)
	v_cmp_lt_u32_e32 vcc, v1, v0
	s_and_saveexec_b64 s[66:67], vcc
	s_cbranch_execz .LBB0_687
	s_add_i32 s0, s0, -8
	s_xor_b64 s[48:49], exec, -1
	s_sleep 1
	s_branch .LBB0_687

; #define LAS __attribute__((address_space(3)))
; __device__ __forceinline__ int otid() { int t = threadIdx.x; asm volatile("" : "+v"(t)); return t; }
; __device__ __forceinline__ void phase_attention(bf16_t* __restrict__ qh, const bf16_t* __restrict__ kh, const bf16_t* __restrict__ vb, float* __restrict__ lse, LAS unsigned char* obuf, const int nseq, const int S) {
;   const int tid = otid(), lane = tid & 63, rl = lane & 31, h = lane >> 5;
;   const int nw = gridDim.x * 8, wv = tid >> 6;
;   const int nitem = 48 * (TS / 32), per = (nitem + nw - 1) / nw;
;   const int bbase = obid() * per * 8;
;   const int ipq = S / 32;
;   const int kap = (rl & ~12) | ((rl & 4) << 1) | ((rl & 8) >> 1);
;   const float SC = 0.08838834764831845f * LOG2E;
; #pragma nounroll
;   for (int it = 0; it < per; ++it) {
;     const int item = bbase + it * 8 + wv;
;     if (item >= nitem) break;
;     const int hs = item / ipq, rem = item % ipq;
;     const int hh = hs / nseq, seq = hs % nseq;
;     const int g = hh >> 4, lg = 2 * g, dil = 1 << lg, L = S >> lg, nqb = L >> 5;
;     const int r = rem / nqb, qb = rem % nqb, m0 = qb * 32;
;     const float sl2 = exp2f(-8.f * (float)(hh + 1) / 48.f) * (float)dil * LOG2E;
;     const size_t pbase = (size_t)seq * S + (size_t)r * L;
;     bf16_t* qrow = qh + ((size_t)hh * TS + pbase + m0 + rl) * 128;
;     bf16x8 qf[8];
;     { LAS unsigned char* qb_ = obuf + wv * 10240;
;       const bf16_t* qt = qrow - (size_t)rl * 128 + (size_t)lane * 8;
;       u32x4 qraw[8];
; #pragma unroll
;       for (int i = 0; i < 8; ++i) qraw[i] = *(const u32x4*)(qt + i * 512);
; #pragma unroll
;       for (int i = 0; i < 8; ++i) *(LAS u32x4*)(qb_ + (lane >> 4) * 272 + (lane & 15) * 16 + i * (4 * 272)) = qraw[i];
; #pragma unroll
;       for (int kk = 0; kk < 8; ++kk) qf[kk] = *(const LAS bf16x8*)(qb_ + rl * 272 + 16 * h + 32 * kk); }
;     const bf16_t* kt0 = kh + ((size_t)hh * TS + pbase) * 128 + (size_t)lane * 8;
;     const bf16_t* vt0 = vb + ((size_t)hh * (TS / 32) + (pbase >> 5)) * 4096 + (size_t)lane * 8;
;     LAS unsigned char* tb = obuf + wv * 10240;
;     const int kw = ((lane >> 4)) * 272 + (lane & 15) * 16, kr = kap * 272 + 16 * h;
;     const int vw = (lane >> 2) * 80 + (lane & 3) * 16, vr = rl * 80 + 16 * h;
.LBB0_709:
	s_or_b64 exec, exec, s[2:3]
	v_mov_b64_e32 v[0:1], s[10:11]
	s_waitcnt lgkmcnt(0)
	s_barrier
	global_load_dwordx2 v[2:3], v[0:1], off sc0 sc1
	s_waitcnt vmcnt(0)
	global_load_dwordx2 v[4:5], v[0:1], off sc0 sc1
	s_waitcnt vmcnt(0)
	global_load_dwordx2 v[6:7], v[0:1], off sc0 sc1
	s_waitcnt vmcnt(0)
	global_load_dwordx2 v[8:9], v[0:1], off sc0 sc1
	s_waitcnt vmcnt(0)
	v_mov_b32_e32 v0, v252
	v_mov_b32_e32 v1, s74
	ds_read_b32 v1, v1
	v_readlane_b32 s0, v255, 11
	v_readlane_b32 s1, v255, 12
	s_andn2_b64 vcc, exec, s[0:1]
	s_waitcnt lgkmcnt(0)
	v_readfirstlane_b32 s0, v1
	v_readfirstlane_b32 s5, v3
	v_readfirstlane_b32 s4, v2
	v_readfirstlane_b32 s3, v5
	v_readfirstlane_b32 s2, v4
	v_readfirstlane_b32 s9, v7
	v_readfirstlane_b32 s8, v6
	v_readfirstlane_b32 s1, v9
	v_readfirstlane_b32 s13, v8
	s_cbranch_vccnz .LBB0_723
	s_add_u32 s8, s8, 0x30180000
	s_addc_u32 s9, s9, 0
	s_add_u32 s36, s13, 0x40180000
	s_addc_u32 s37, s1, 0
	v_readlane_b32 s1, v255, 10
	s_mul_i32 s0, s0, s1
	s_lshr_b32 s1, s17, 5
	v_cvt_f32_u32_e32 v12, s1
	v_cvt_f32_ubyte0_e32 v18, s89
	v_lshlrev_b32_e32 v2, 1, v0
	v_lshrrev_b32_e32 v3, 1, v0
	v_rcp_iflag_f32_e32 v17, v12
	v_rcp_iflag_f32_e32 v18, v18
	v_ashrrev_i32_e32 v237, 6, v0
	v_and_b32_e32 v1, 19, v0
	v_and_b32_e32 v2, 8, v2
	v_and_b32_e32 v3, 4, v3
	s_movk_i32 s13, 0x2800
	v_or3_b32 v1, v1, v2, v3
	v_and_b32_e32 v184, 31, v0
	v_mul_lo_u32 v2, v237, s13
	v_mul_f32_e32 v17, 0x4f7ffffe, v17
	v_add_u32_e32 v6, 0, v2
	v_mul_hi_i32_i24_e32 v3, 0xffffff00, v184
	v_mul_i32_i24_e32 v2, 0xffffff00, v184
	v_cvt_u32_f32_e32 v17, v17
	v_lshl_add_u64 v[2:3], s[4:5], 0, v[2:3]
	s_mov_b64 s[4:5], 0x18180000
	v_mul_f32_e32 v18, 0x4f7ffffe, v18
	v_and_b32_e32 v4, 63, v0
	v_lshl_add_u64 v[186:187], v[2:3], 0, s[4:5]
	v_bfe_u32 v7, v0, 4, 2
	s_movk_i32 s4, 0x110
	v_cvt_u32_f32_e32 v18, v18
	v_mad_u32_u24 v238, v7, s4, v6
	v_mad_u32_u24 v239, v184, s4, v6
	v_lshlrev_b32_e32 v80, 4, v4
	v_mad_u32_u24 v1, v1, s4, v6
	s_sub_i32 s4, 0, s1
	v_lshl_add_u64 v[2:3], s[2:3], 0, v[80:81]
	s_mov_b64 s[2:3], 0x24180000
	v_mul_lo_u32 v19, s4, v17
	v_bfe_u32 v5, v0, 5, 1
	v_lshlrev_b32_e32 v8, 4, v0
	v_lshl_add_u64 v[190:191], v[2:3], 0, s[2:3]
	v_and_b32_e32 v2, 15, v0
	v_bfe_u32 v0, v0, 2, 4
	s_movk_i32 s2, 0x50
	v_mul_hi_u32 v19, v17, v19
	s_sub_i32 s4, 0, s89
	v_lshlrev_b32_e32 v188, 3, v4
	v_lshlrev_b32_e32 v241, 4, v2
	v_mad_u32_u24 v13, v0, s2, v6
	v_mad_u32_u24 v15, v184, s2, v6
	v_lshlrev_b32_e32 v0, 3, v2
	v_cmp_gt_u32_e64 s[2:3], 32, v4
	v_lshlrev_b32_e32 v2, 7, v7
	v_or_b32_e32 v4, 4, v7
	v_add_u32_e32 v243, v17, v19
	v_mul_lo_u32 v17, s4, v18
	v_mul_u32_u24_e32 v9, 0x110, v7
	v_and_b32_e32 v11, 0xf0, v8
	v_lshlrev_b32_e32 v240, 4, v5
	v_and_b32_e32 v3, 48, v8
	v_lshlrev_b32_e32 v242, 3, v5
	v_add_u32_e32 v5, v6, v241
	v_mul_u32_u24_e32 v7, 0x110, v4
	v_lshlrev_b32_e32 v4, 7, v4
	v_or_b32_e32 v6, 0x400, v2
	v_or_b32_e32 v8, 0x600, v2
	v_or_b32_e32 v10, 0x800, v2
	v_or_b32_e32 v12, 0xa00, v2
	v_or_b32_e32 v14, 0xc00, v2
	v_or_b32_e32 v16, 0xe00, v2
	v_mul_hi_u32 v17, v18, v17
	s_mov_b32 s13, 0
	v_add_u32_e32 v244, v18, v17
	v_sub_u32_e32 v245, v242, v184
	s_mov_b64 s[40:41], 0
	v_add_u32_e32 v246, v238, v11
	v_add_u32_e32 v247, v1, v240
	v_add_u32_e32 v248, v13, v3
	v_add_u32_e32 v249, v15, v240
	v_lshlrev_b32_e32 v192, 1, v0
	v_add_u32_e32 v250, v5, v9
	v_lshlrev_b32_e32 v194, 1, v2
	v_add_u32_e32 v251, v5, v7
	v_lshlrev_b32_e32 v196, 1, v4
	v_lshlrev_b32_e32 v198, 1, v6
	v_lshlrev_b32_e32 v200, 1, v8
	v_lshlrev_b32_e32 v202, 1, v10
	v_lshlrev_b32_e32 v204, 1, v12
	v_lshlrev_b32_e32 v206, 1, v14
	v_lshlrev_b32_e32 v208, 1, v16
	s_branch .LBB0_713

; #define LAS __attribute__((address_space(3)))
; __device__ __forceinline__ void phase_attention(bf16_t* __restrict__ qh, const bf16_t* __restrict__ kh, const bf16_t* __restrict__ vb, float* __restrict__ lse, LAS unsigned char* obuf, const int nseq, const int S) {
;     ...
;   for (int it = 0; it < per; ++it) {
;     const int item = bbase + it * 8 + wv;
;     if (item >= nitem) break;
;     const int hs = item / ipq, rem = item % ipq;
;     const int hh = hs / nseq, seq = hs % nseq;
;     const int g = hh >> 4, lg = 2 * g, dil = 1 << lg, L = S >> lg, nqb = L >> 5;
;     const int r = rem / nqb, qb = rem % nqb, m0 = qb * 32;
;     const float sl2 = exp2f(-8.f * (float)(hh + 1) / 48.f) * (float)dil * LOG2E;
;     const size_t pbase = (size_t)seq * S + (size_t)r * L;
;     bf16_t* qrow = qh + ((size_t)hh * TS + pbase + m0 + rl) * 128;
;     bf16x8 qf[8];
;     { LAS unsigned char* qb_ = obuf + wv * 10240;
;       const bf16_t* qt = qrow - (size_t)rl * 128 + (size_t)lane * 8;
;       u32x4 qraw[8];
; #pragma unroll
;       for (int i = 0; i < 8; ++i) qraw[i] = *(const u32x4*)(qt + i * 512);
; #pragma unroll
;       for (int i = 0; i < 8; ++i) *(LAS u32x4*)(qb_ + (lane >> 4) * 272 + (lane & 15) * 16 + i * (4 * 272)) = qraw[i];
; #pragma unroll
;       for (int kk = 0; kk < 8; ++kk) qf[kk] = *(const LAS bf16x8*)(qb_ + rl * 272 + 16 * h + 32 * kk); }
;     const bf16_t* kt0 = kh + ((size_t)hh * TS + pbase) * 128 + (size_t)lane * 8;
;     const bf16_t* vt0 = vb + ((size_t)hh * (TS / 32) + (pbase >> 5)) * 4096 + (size_t)lane * 8;
;     LAS unsigned char* tb = obuf + wv * 10240;
;     const int kw = ((lane >> 4)) * 272 + (lane & 15) * 16, kr = kap * 272 + 16 * h;
;     const int vw = (lane >> 2) * 80 + (lane & 3) * 16, vr = rl * 80 + 16 * h;
;     f32x16 o[4];
; #pragma unroll
;     for (int db = 0; db < 4; ++db)
; #pragma unroll
;       for (int e = 0; e < 16; ++e) o[db][e] = 0.f;
;     float mrun = -1e30f, lrun = 0.f;
;     const int jmin = (2 - qb) > 0 ? (2 - qb) : 0, jmax = (nqb + 1 - qb) < 4 ? (nqb + 1 - qb) : 4;
;     u32x4 kraw[8];
;     { const bf16_t* kp = kt0 + (ptrdiff_t)(m0 - 64 + 32 * jmin) * 128;
; #pragma unroll
;       for (int i = 0; i < 8; ++i) kraw[i] = *(const u32x4*)(kp + i * 512); }
.LBB0_713:
	s_add_i32 s4, s13, s0
	v_lshl_add_u32 v0, s4, 3, v237
	s_movk_i32 s4, 0x6000
	v_cmp_gt_i32_e32 vcc, s4, v0
	s_or_b64 s[94:95], s[94:95], exec
	s_and_saveexec_b64 s[38:39], vcc
	s_cbranch_execz .LBB0_712
	v_sub_u32_e32 v2, 0, v0
	v_max_i32_e32 v2, v0, v2
	v_mul_hi_u32 v3, v2, v243
	v_mul_lo_u32 v4, v3, s1
	v_sub_u32_e32 v2, v2, v4
	v_add_u32_e32 v4, 1, v3
	v_cmp_le_u32_e32 vcc, s1, v2
	v_ashrrev_i32_e32 v1, 31, v0
	v_lshlrev_b32_e32 v80, 1, v188
	v_cndmask_b32_e32 v3, v3, v4, vcc
	v_subrev_u32_e32 v4, s1, v2
	v_cndmask_b32_e32 v2, v2, v4, vcc
	v_add_u32_e32 v4, 1, v3
	v_cmp_le_u32_e32 vcc, s1, v2
	v_mov_b32_e32 v15, 0
	v_mov_b32_e32 v158, 0xf149f2ca
	v_cndmask_b32_e32 v2, v3, v4, vcc
	v_xor_b32_e32 v2, v2, v1
	v_sub_u32_e32 v1, v2, v1
	v_sub_u32_e32 v3, 0, v1
	v_max_i32_e32 v3, v1, v3
	v_mul_hi_u32 v4, v3, v244
	v_mul_lo_u32 v5, v4, s89
	v_sub_u32_e32 v3, v3, v5
	v_add_u32_e32 v5, 1, v4
	v_cmp_le_u32_e32 vcc, s89, v3
	v_ashrrev_i32_e32 v2, 31, v1
	v_mov_b32_e32 v14, v15
	v_cndmask_b32_e32 v4, v4, v5, vcc
	v_subrev_u32_e32 v5, s89, v3
	v_cndmask_b32_e32 v3, v3, v5, vcc
	v_add_u32_e32 v5, 1, v4
	v_cmp_le_u32_e32 vcc, s89, v3
	v_mov_b32_e32 v13, v15
	v_mov_b32_e32 v12, v15
	v_cndmask_b32_e32 v3, v4, v5, vcc
	v_xor_b32_e32 v3, v3, v2
	v_sub_u32_e32 v64, v3, v2
	v_ashrrev_i32_e32 v2, 3, v64
	v_and_b32_e32 v71, -2, v2
	v_lshrrev_b32_e64 v2, v71, s17
	v_lshrrev_b32_e32 v16, 5, v2
	v_cvt_f32_u32_e32 v3, v16
	v_mul_lo_u32 v4, v1, s1
	v_sub_u32_e32 v6, 0, v16
	v_sub_u32_e32 v4, v0, v4
	v_rcp_iflag_f32_e32 v3, v3
	v_sub_u32_e32 v5, 0, v4
	v_max_i32_e32 v5, v4, v5
	v_mul_lo_u32 v0, v64, s89
	v_mul_f32_e32 v3, 0x4f7ffffe, v3
	v_cvt_u32_f32_e32 v3, v3
	v_sub_u32_e32 v0, v1, v0
	v_ashrrev_i32_e32 v1, 31, v4
	v_ashrrev_i32_e32 v65, 31, v64
	v_mul_lo_u32 v6, v6, v3
	v_mul_hi_u32 v6, v3, v6
	v_add_u32_e32 v3, v3, v6
	v_mul_hi_u32 v3, v5, v3
	v_mul_lo_u32 v6, v3, v16
	v_sub_u32_e32 v5, v5, v6
	v_add_u32_e32 v6, 1, v3
	v_cmp_ge_u32_e32 vcc, v5, v16
	v_mov_b32_e32 v11, v15
	v_mov_b32_e32 v10, v15
	v_cndmask_b32_e32 v3, v3, v6, vcc
	v_sub_u32_e32 v6, v5, v16
	v_cndmask_b32_e32 v5, v5, v6, vcc
	v_add_u32_e32 v6, 1, v3
	v_cmp_ge_u32_e32 vcc, v5, v16
	v_mov_b32_e32 v9, v15
	v_mov_b32_e32 v8, v15
	v_cndmask_b32_e32 v3, v3, v6, vcc
	v_xor_b32_e32 v3, v3, v1
	v_sub_u32_e32 v3, v3, v1
	v_mul_lo_u32 v1, v3, v16
	v_sub_u32_e32 v17, v4, v1
	v_ashrrev_i32_e32 v1, 31, v0
	v_lshlrev_b64 v[0:1], s81, v[0:1]
	v_lshlrev_b32_e32 v193, 5, v17
	v_mad_i64_i32 v[66:67], s[4:5], v2, v3, v[0:1]
	v_lshlrev_b64 v[0:1], 14, v[64:65]
	v_lshl_add_u64 v[68:69], v[66:67], 0, v[0:1]
	v_ashrrev_i32_e32 v1, 31, v193
	v_or_b32_e32 v0, v193, v184
	v_lshl_add_u64 v[210:211], v[68:69], 0, v[0:1]
	v_lshlrev_b64 v[0:1], 8, v[210:211]
	v_lshl_add_u64 v[212:213], v[186:187], 0, v[0:1]
	v_lshl_add_u64 v[0:1], v[212:213], 0, v[80:81]
	global_load_dwordx4 v[32:35], v[0:1], off
	global_load_dwordx4 v[36:39], v[0:1], off offset:1024
	global_load_dwordx4 v[40:43], v[0:1], off offset:2048
	global_load_dwordx4 v[44:47], v[0:1], off offset:3072
	v_add_co_u32_e32 v0, vcc, s77, v0
	v_sub_u32_e32 v16, v16, v17
	s_nop 0
	v_addc_co_u32_e32 v1, vcc, 0, v1, vcc
	global_load_dwordx4 v[48:51], v[0:1], off
	global_load_dwordx4 v[52:55], v[0:1], off offset:1024
	global_load_dwordx4 v[56:59], v[0:1], off offset:2048
	global_load_dwordx4 v[60:63], v[0:1], off offset:3072
	v_sub_u32_e32 v70, 2, v17
	v_min_i32_e32 v197, 3, v16
	v_max_i32_e32 v195, 0, v70
	v_add_u32_e32 v16, 1, v197
	v_mov_b32_e32 v7, v15
	v_mov_b32_e32 v6, v15
	v_mov_b32_e32 v5, v15
	v_mov_b32_e32 v4, v15
	v_mov_b32_e32 v3, v15
	v_mov_b32_e32 v2, v15
	v_mov_b32_e32 v1, v15
	v_mov_b32_e32 v0, v15
	v_mov_b32_e32 v31, v15
	v_mov_b32_e32 v30, v15
	v_mov_b32_e32 v29, v15
	v_mov_b32_e32 v28, v15
	v_mov_b32_e32 v27, v15
	v_mov_b32_e32 v26, v15
	v_mov_b32_e32 v25, v15
	v_mov_b32_e32 v24, v15
	v_mov_b32_e32 v23, v15
	v_mov_b32_e32 v22, v15
	v_mov_b32_e32 v21, v15
	v_mov_b32_e32 v20, v15
	v_mov_b32_e32 v19, v15
	v_mov_b32_e32 v18, v15
	v_cmp_le_i32_e32 vcc, v195, v16
	v_mov_b32_e32 v17, v15
	v_mov_b32_e32 v16, v15
	v_mov_b32_e32 v70, v15
	s_waitcnt vmcnt(0) lgkmcnt(0)
	ds_write_b128 v246, v[32:35]
	ds_write_b128 v246, v[36:39] offset:1088
	ds_write_b128 v246, v[40:43] offset:2176
	ds_write_b128 v246, v[44:47] offset:3264
	ds_write_b128 v246, v[48:51] offset:4352
	ds_write_b128 v246, v[52:55] offset:5440
	ds_write_b128 v246, v[56:59] offset:6528
	ds_write_b128 v246, v[60:63] offset:7616
	v_mov_b32_e32 v47, v15
	v_mov_b32_e32 v46, v15
	v_mov_b32_e32 v45, v15
	v_mov_b32_e32 v44, v15
	v_mov_b32_e32 v43, v15
	v_mov_b32_e32 v42, v15
	v_mov_b32_e32 v41, v15
	v_mov_b32_e32 v40, v15
	v_mov_b32_e32 v39, v15
	v_mov_b32_e32 v38, v15
	v_mov_b32_e32 v37, v15
	v_mov_b32_e32 v36, v15
	v_mov_b32_e32 v35, v15
	v_mov_b32_e32 v34, v15
	v_mov_b32_e32 v33, v15
	v_mov_b32_e32 v32, v15
	v_mov_b32_e32 v63, v15
	v_mov_b32_e32 v62, v15
	v_mov_b32_e32 v61, v15
	v_mov_b32_e32 v60, v15
	v_mov_b32_e32 v59, v15
	v_mov_b32_e32 v58, v15
	v_mov_b32_e32 v57, v15
	v_mov_b32_e32 v56, v15
	v_mov_b32_e32 v55, v15
	v_mov_b32_e32 v54, v15
	v_mov_b32_e32 v53, v15
	v_mov_b32_e32 v52, v15
	v_mov_b32_e32 v51, v15
	v_mov_b32_e32 v50, v15
	v_mov_b32_e32 v49, v15
	v_mov_b32_e32 v48, v15
	s_and_saveexec_b64 s[96:97], vcc
	s_cbranch_execz .LBB0_720
; #define LAS __attribute__((address_space(3)))
; __device__ __forceinline__ void phase_attention(bf16_t* __restrict__ qh, const bf16_t* __restrict__ kh, const bf16_t* __restrict__ vb, float* __restrict__ lse, LAS unsigned char* obuf, const int nseq, const int S) {
;     ...
;     const float sl2 = exp2f(-8.f * (float)(hh + 1) / 48.f) * (float)dil * LOG2E;
;     const size_t pbase = (size_t)seq * S + (size_t)r * L;
;     bf16_t* qrow = qh + ((size_t)hh * TS + pbase + m0 + rl) * 128;
;     bf16x8 qf[8];
;     { LAS unsigned char* qb_ = obuf + wv * 10240;
;       const bf16_t* qt = qrow - (size_t)rl * 128 + (size_t)lane * 8;
;       u32x4 qraw[8];
; #pragma unroll
;       for (int i = 0; i < 8; ++i) qraw[i] = *(const u32x4*)(qt + i * 512);
; #pragma unroll
;       for (int i = 0; i < 8; ++i) *(LAS u32x4*)(qb_ + (lane >> 4) * 272 + (lane & 15) * 16 + i * (4 * 272)) = qraw[i];
; #pragma unroll
;       for (int kk = 0; kk < 8; ++kk) qf[kk] = *(const LAS bf16x8*)(qb_ + rl * 272 + 16 * h + 32 * kk); }
;     const bf16_t* kt0 = kh + ((size_t)hh * TS + pbase) * 128 + (size_t)lane * 8;
;     const bf16_t* vt0 = vb + ((size_t)hh * (TS / 32) + (pbase >> 5)) * 4096 + (size_t)lane * 8;
;     LAS unsigned char* tb = obuf + wv * 10240;
;     const int kw = ((lane >> 4)) * 272 + (lane & 15) * 16, kr = kap * 272 + 16 * h;
;     const int vw = (lane >> 2) * 80 + (lane & 3) * 16, vr = rl * 80 + 16 * h;
;     f32x16 o[4];
; #pragma unroll
;     for (int db = 0; db < 4; ++db)
; #pragma unroll
;       for (int e = 0; e < 16; ++e) o[db][e] = 0.f;
;     float mrun = -1e30f, lrun = 0.f;
;     const int jmin = (2 - qb) > 0 ? (2 - qb) : 0, jmax = (nqb + 1 - qb) < 4 ? (nqb + 1 - qb) : 4;
;     u32x4 kraw[8];
;     { const bf16_t* kp = kt0 + (ptrdiff_t)(m0 - 64 + 32 * jmin) * 128;
; #pragma unroll
;       for (int i = 0; i < 8; ++i) kraw[i] = *(const u32x4*)(kp + i * 512); }
	v_add_u32_e32 v0, 1, v64
	v_cvt_f32_i32_e32 v0, v0
	s_mov_b32 s18, 0x42400000
	v_lshlrev_b32_e64 v3, v71, 1
	v_lshlrev_b32_e32 v199, 5, v195
	v_mul_f32_e32 v0, 0xc1000000, v0
	v_div_scale_f32 v1, s[4:5], s18, s18, v0
	v_rcp_f32_e32 v2, v1
	v_div_scale_f32 v4, vcc, v0, s18, v0
	s_mov_b32 s4, 0xc2fc0000
	v_fma_f32 v5, -v1, v2, 1.0
	v_fmac_f32_e32 v2, v5, v2
	v_mul_f32_e32 v5, v4, v2
	v_fma_f32 v6, -v1, v5, v4
	v_fmac_f32_e32 v5, v6, v2
	v_fma_f32 v1, -v1, v5, v4
	v_div_fmas_f32 v1, v1, v2, v5
	v_div_fixup_f32 v0, v1, s18, v0
	v_cmp_gt_f32_e32 vcc, s4, v0
	s_movk_i32 s4, 0xffc0
	v_mov_b32_e32 v201, 0
	v_cndmask_b32_e32 v1, 0, v225, vcc
	v_add_f32_e32 v0, v0, v1
	v_exp_f32_e32 v0, v0
	v_cvt_f32_u32_e32 v1, v3
	v_cndmask_b32_e32 v2, 0, v224, vcc
	v_mov_b32_e32 v205, 0xf149f2ca
	v_ldexp_f32 v0, v0, v2
	v_mul_f32_e32 v6, v0, v1
	v_add_u32_e32 v0, v239, v240
	ds_read_b128 v[82:85], v0
	ds_read_b128 v[86:89], v0 offset:32
	ds_read_b128 v[90:93], v0 offset:64
	ds_read_b128 v[94:97], v0 offset:96
	ds_read_b128 v[98:101], v0 offset:128
	ds_read_b128 v[102:105], v0 offset:160
	ds_read_b128 v[106:109], v0 offset:192
	ds_read_b128 v[110:113], v0 offset:224
	v_lshlrev_b64 v[0:1], 8, v[68:69]
	v_lshl_add_u64 v[214:215], v[190:191], 0, v[0:1]
	v_add3_u32 v0, v193, v199, s4
	v_ashrrev_i32_e32 v1, 31, v0
	v_lshlrev_b64 v[0:1], 8, v[0:1]
	v_lshl_add_u64 v[0:1], v[214:215], 0, v[0:1]
	v_add_co_u32_e32 v4, vcc, s77, v0
	v_lshlrev_b64 v[2:3], 22, v[64:65]
	s_nop 0
	v_addc_co_u32_e32 v5, vcc, 0, v1, vcc
	global_load_dwordx4 v[142:145], v[4:5], off offset:3072
	global_load_dwordx4 v[138:141], v[4:5], off offset:2048
	global_load_dwordx4 v[134:137], v[4:5], off offset:1024
	global_load_dwordx4 v[130:133], v[4:5], off
	global_load_dwordx4 v[126:129], v[0:1], off offset:3072
	global_load_dwordx4 v[122:125], v[0:1], off offset:2048
	global_load_dwordx4 v[118:121], v[0:1], off offset:1024
	global_load_dwordx4 v[114:117], v[0:1], off
	v_lshl_add_u64 v[0:1], s[8:9], 0, v[2:3]
	v_lshlrev_b64 v[2:3], 8, v[66:67]
	v_and_b32_e32 v2, 0xffffe000, v2
	v_lshl_add_u64 v[0:1], v[0:1], 0, v[2:3]
	v_lshl_add_u64 v[218:219], v[0:1], 0, v[80:81]
	v_and_b32_e32 v1, 64, v189
	v_xor_b32_e32 v0, 32, v189
	v_add_u32_e32 v1, 64, v1
	v_cmp_lt_i32_e32 vcc, v0, v1
	v_mul_f32_e32 v217, 0x3fb8aa3b, v6
	s_mov_b64 s[42:43], 0
	v_cndmask_b32_e32 v0, v189, v0, vcc
	v_lshlrev_b32_e32 v80, 2, v0
	v_mov_b32_e32 v203, v245
	v_mov_b32_e32 v48, 0
	v_mov_b32_e32 v49, v201
	v_mov_b32_e32 v50, v201
	v_mov_b32_e32 v51, v201
	v_mov_b32_e32 v52, v201
	v_mov_b32_e32 v53, v201
	v_mov_b32_e32 v54, v201
	v_mov_b32_e32 v55, v201
	v_mov_b32_e32 v56, v201
	v_mov_b32_e32 v57, v201
	v_mov_b32_e32 v58, v201
	v_mov_b32_e32 v59, v201
	v_mov_b32_e32 v60, v201
	v_mov_b32_e32 v61, v201
	v_mov_b32_e32 v62, v201
	v_mov_b32_e32 v63, v201
	v_mov_b32_e32 v32, 0
	v_mov_b32_e32 v33, v201
	v_mov_b32_e32 v34, v201
	v_mov_b32_e32 v35, v201
	v_mov_b32_e32 v36, v201
	v_mov_b32_e32 v37, v201
	v_mov_b32_e32 v38, v201
	v_mov_b32_e32 v39, v201
	v_mov_b32_e32 v40, v201
	v_mov_b32_e32 v41, v201
	v_mov_b32_e32 v42, v201
	v_mov_b32_e32 v43, v201
	v_mov_b32_e32 v44, v201
	v_mov_b32_e32 v45, v201
	v_mov_b32_e32 v46, v201
	v_mov_b32_e32 v47, v201
	v_mov_b32_e32 v16, 0
	v_mov_b32_e32 v17, v201
	v_mov_b32_e32 v18, v201
	v_mov_b32_e32 v19, v201
	v_mov_b32_e32 v20, v201
	v_mov_b32_e32 v21, v201
	v_mov_b32_e32 v22, v201
	v_mov_b32_e32 v23, v201
	v_mov_b32_e32 v24, v201
	v_mov_b32_e32 v25, v201
	v_mov_b32_e32 v26, v201
	v_mov_b32_e32 v27, v201
	v_mov_b32_e32 v28, v201
	v_mov_b32_e32 v29, v201
	v_mov_b32_e32 v30, v201
	v_mov_b32_e32 v31, v201
	v_mov_b32_e32 v0, 0
	v_mov_b32_e32 v1, v201
	v_mov_b32_e32 v2, v201
	v_mov_b32_e32 v3, v201
	v_mov_b32_e32 v4, v201
	v_mov_b32_e32 v5, v201
	v_mov_b32_e32 v6, v201
	v_mov_b32_e32 v7, v201
	v_mov_b32_e32 v8, v201
	v_mov_b32_e32 v9, v201
	v_mov_b32_e32 v10, v201
	v_mov_b32_e32 v11, v201
	v_mov_b32_e32 v12, v201
	v_mov_b32_e32 v13, v201
	v_mov_b32_e32 v14, v201
	v_mov_b32_e32 v15, v201
	s_branch .LBB0_717

; #define LAS __attribute__((address_space(3)))
; __device__ __forceinline__ void phase_attention(bf16_t* __restrict__ qh, const bf16_t* __restrict__ kh, const bf16_t* __restrict__ vb, float* __restrict__ lse, LAS unsigned char* obuf, const int nseq, const int S) {
;     ...
;       for (int i = 0; i < 8; ++i) *(LAS u32x4*)(tb + vw + i * (16 * 80)) = vraw[i];
;       bf16x8 vf[2][4];
; #pragma unroll
;       for (int s2 = 0; s2 < 2; ++s2)
; #pragma unroll
;         for (int db = 0; db < 4; ++db) vf[s2][db] = *(const LAS bf16x8*)(tb + vr + db * (32 * 80) + s2 * 32);
;       float mx = -1e30f;
; #pragma unroll
;       for (int e = 0; e < 16; ++e) {
;         const int j4 = e >> 2, ii = e & 3, ko = 16 * (j4 >> 1) + 8 * h + 4 * (j4 & 1) + ii;
;         const int rel = 32 * j - 64 + ko - rl, arel = rel < 0 ? -rel : rel;
;         float v = s[e] * SC - sl2 * (float)arel;
;         v = (arel <= 64) ? v : -1e30f; s[e] = v; mx = fmaxf(mx, v);
;       }
;       mx = fmaxf(mx, __shfl_xor(mx, 32));
.Lattn_vready:
	ds_write_b128 v248, v[146:149]
	ds_write_b128 v248, v[150:153] offset:1280
	ds_write_b128 v248, v[154:157] offset:2560
	ds_write_b128 v248, v[158:161] offset:3840
	ds_write_b128 v248, v[162:165] offset:5120
	ds_write_b128 v248, v[166:169] offset:6400
	ds_write_b128 v248, v[170:173] offset:7680
	ds_write_b128 v248, v[174:177] offset:8960
	v_add_u32_e32 v156, v199, v203
	v_subrev_u32_e32 v146, 64, v156
	v_sub_u32_e32 v147, 64, v156
	v_max_i32_e32 v157, v146, v147
	v_cvt_f32_u32_e32 v183, v157
	v_mov_b32_e32 v216, v64
	v_cmp_gt_u32_e32 vcc, s51, v157
	s_mov_b32 s18, 0xf149f2ca
	v_pk_mul_f32 v[154:155], v[216:217], v[182:183]
	v_mov_b32_e32 v216, v65
	v_sub_f32_e32 v64, v154, v155
	v_subrev_u32_e32 v154, 63, v156
	v_sub_u32_e32 v155, 63, v156
	v_max_i32_e32 v154, v154, v155
	v_cvt_f32_u32_e32 v183, v154
	v_cndmask_b32_e32 v159, v235, v64, vcc
	v_sub_u32_e32 v155, 62, v156
	v_cmp_gt_u32_e32 vcc, s51, v154
	v_pk_mul_f32 v[64:65], v[216:217], v[182:183]
	v_mov_b32_e32 v216, v66
	v_sub_f32_e32 v64, v64, v65
	v_subrev_u32_e32 v65, 62, v156
	v_max_i32_e32 v155, v65, v155
	v_cvt_f32_u32_e32 v183, v155
	v_cndmask_b32_e32 v164, v235, v64, vcc
	v_sub_u32_e32 v66, 61, v156
	v_cmp_gt_u32_e32 vcc, s51, v155
	v_pk_mul_f32 v[64:65], v[216:217], v[182:183]
	v_mov_b32_e32 v216, v67
	v_sub_f32_e32 v64, v64, v65
	v_subrev_u32_e32 v65, 61, v156
	v_max_i32_e32 v66, v65, v66
	v_cvt_f32_u32_e32 v183, v66
	v_cndmask_b32_e32 v165, v235, v64, vcc
	v_sub_u32_e32 v67, 60, v156
	v_cmp_gt_u32_e32 vcc, s51, v66
	v_pk_mul_f32 v[64:65], v[216:217], v[182:183]
	v_mov_b32_e32 v216, v68
	v_sub_f32_e32 v64, v64, v65
	v_subrev_u32_e32 v65, 60, v156
	v_max_i32_e32 v67, v65, v67
	v_cvt_f32_u32_e32 v183, v67
	v_cndmask_b32_e32 v166, v235, v64, vcc
	v_sub_u32_e32 v68, 59, v156
	v_cmp_gt_u32_e32 vcc, s51, v67
	v_pk_mul_f32 v[64:65], v[216:217], v[182:183]
	v_mov_b32_e32 v216, v69
	v_sub_f32_e32 v64, v64, v65
	v_subrev_u32_e32 v65, 59, v156
	v_max_i32_e32 v68, v65, v68
	v_cvt_f32_u32_e32 v183, v68
	v_cndmask_b32_e32 v167, v235, v64, vcc
	v_sub_u32_e32 v67, 58, v156
	v_cmp_gt_u32_e32 vcc, s51, v68
	v_pk_mul_f32 v[64:65], v[216:217], v[182:183]
	v_mov_b32_e32 v216, v70
	v_sub_f32_e32 v64, v64, v65
	v_subrev_u32_e32 v65, 58, v156
	v_max_i32_e32 v67, v65, v67
	v_cvt_f32_u32_e32 v183, v67
	v_cndmask_b32_e32 v168, v235, v64, vcc
	v_sub_u32_e32 v68, 57, v156
	v_cmp_gt_u32_e32 vcc, s51, v67
	v_pk_mul_f32 v[64:65], v[216:217], v[182:183]
	v_mov_b32_e32 v216, v71
	v_sub_f32_e32 v64, v64, v65
	v_subrev_u32_e32 v65, 57, v156
	v_max_i32_e32 v68, v65, v68
	v_cvt_f32_u32_e32 v183, v68
	v_cndmask_b32_e32 v169, v235, v64, vcc
	v_sub_u32_e32 v67, 48, v156
	v_cmp_gt_u32_e32 vcc, s51, v68
	v_pk_mul_f32 v[64:65], v[216:217], v[182:183]
	v_mov_b32_e32 v216, v72
	v_sub_f32_e32 v64, v64, v65
	v_subrev_u32_e32 v65, 48, v156
	v_max_i32_e32 v67, v65, v67
	v_cvt_f32_u32_e32 v183, v67
	v_cndmask_b32_e32 v170, v235, v64, vcc
	v_sub_u32_e32 v68, 47, v156
	v_cmp_gt_u32_e32 vcc, s51, v67
	v_pk_mul_f32 v[64:65], v[216:217], v[182:183]
	v_mov_b32_e32 v216, v73
	v_sub_f32_e32 v64, v64, v65
	v_subrev_u32_e32 v65, 47, v156
	v_max_i32_e32 v68, v65, v68
	v_cvt_f32_u32_e32 v183, v68
	v_cndmask_b32_e32 v171, v235, v64, vcc
	v_sub_u32_e32 v67, 46, v156
	v_cmp_gt_u32_e32 vcc, s51, v68
	v_pk_mul_f32 v[64:65], v[216:217], v[182:183]
	v_mov_b32_e32 v216, v74
	v_sub_f32_e32 v64, v64, v65
	v_subrev_u32_e32 v65, 46, v156
	v_max_i32_e32 v67, v65, v67
	v_cvt_f32_u32_e32 v183, v67
	v_cndmask_b32_e32 v172, v235, v64, vcc
	v_sub_u32_e32 v68, 45, v156
	v_cmp_gt_u32_e32 vcc, s51, v67
	v_pk_mul_f32 v[64:65], v[216:217], v[182:183]
	v_mov_b32_e32 v216, v75
	v_sub_f32_e32 v64, v64, v65
	v_subrev_u32_e32 v65, 45, v156
	v_max_i32_e32 v68, v65, v68
	v_cvt_f32_u32_e32 v183, v68
	v_cndmask_b32_e32 v173, v235, v64, vcc
	v_sub_u32_e32 v67, 44, v156
	v_cmp_gt_u32_e32 vcc, s51, v68
	v_pk_mul_f32 v[64:65], v[216:217], v[182:183]
	v_mov_b32_e32 v216, v76
	v_sub_f32_e32 v64, v64, v65
	v_subrev_u32_e32 v65, 44, v156
	v_max_i32_e32 v67, v65, v67
	v_cvt_f32_u32_e32 v183, v67
	v_cndmask_b32_e32 v174, v235, v64, vcc
	v_sub_u32_e32 v68, 43, v156
	v_cmp_gt_u32_e32 vcc, s51, v67
	v_pk_mul_f32 v[64:65], v[216:217], v[182:183]
	v_mov_b32_e32 v216, v77
	v_sub_f32_e32 v64, v64, v65
	v_subrev_u32_e32 v65, 43, v156
	v_max_i32_e32 v68, v65, v68
	v_cvt_f32_u32_e32 v183, v68
	v_cndmask_b32_e32 v175, v235, v64, vcc
	v_sub_u32_e32 v67, 42, v156
	v_cmp_gt_u32_e32 vcc, s51, v68
	v_pk_mul_f32 v[64:65], v[216:217], v[182:183]
	v_mov_b32_e32 v216, v78
	v_sub_f32_e32 v64, v64, v65
	v_subrev_u32_e32 v65, 42, v156
	v_max_i32_e32 v67, v65, v67
	v_cvt_f32_u32_e32 v183, v67
	v_cndmask_b32_e32 v176, v235, v64, vcc
	v_sub_u32_e32 v68, 41, v156
	v_max3_f32 v154, v159, s18, v164
	v_pk_mul_f32 v[64:65], v[216:217], v[182:183]
	v_max3_f32 v66, v154, v165, v166
	v_sub_f32_e32 v64, v64, v65
	v_subrev_u32_e32 v65, 41, v156
	v_max_i32_e32 v68, v65, v68
	v_cvt_f32_u32_e32 v183, v68
	v_max3_f32 v66, v66, v167, v168
	v_max3_f32 v66, v66, v169, v170
	v_cmp_gt_u32_e32 vcc, s51, v67
	v_mov_b32_e32 v216, v79
	v_max3_f32 v66, v66, v171, v172
	v_cndmask_b32_e32 v177, v235, v64, vcc
	v_pk_mul_f32 v[64:65], v[216:217], v[182:183]
	v_max3_f32 v66, v66, v173, v174
	v_sub_f32_e32 v64, v64, v65
	v_cmp_gt_u32_e32 vcc, s51, v68
	v_max3_f32 v66, v66, v175, v176
	ds_read_b128 v[150:153], v249
	ds_read_b128 v[146:149], v249 offset:32
	v_cndmask_b32_e32 v178, v235, v64, vcc
	v_max3_f32 v64, v66, v177, v178
	ds_bpermute_b32 v65, v80, v64
	ds_read_b128 v[160:163], v249 offset:2560
	ds_read_b128 v[72:75], v249 offset:2592
	ds_read_b128 v[154:157], v249 offset:5120
	ds_read_b128 v[68:71], v249 offset:5152
	s_and_b64 s[4:5], exec, s[4:5]
	s_or_b64 s[42:43], s[4:5], s[42:43]
	v_add_u32_e32 v195, 1, v195
	s_waitcnt lgkmcnt(0)
; __device__ __forceinline__ unsigned cvt_pk_bf16(float lo, float hi) { unsigned r; asm("v_cvt_pk_bf16_f32 %0, %1, %2" : "=v"(r) : "v"(lo), "v"(hi)); return r; }
; __device__ __forceinline__ float fast_exp2(float x) { return __builtin_amdgcn_exp2f(x); }
; __device__ __forceinline__ void phase_attention(bf16_t* __restrict__ qh, const bf16_t* __restrict__ kh, const bf16_t* __restrict__ vb, float* __restrict__ lse, LAS unsigned char* obuf, const int nseq, const int S) {
;     ...
;       const float mnew = fmaxf(mrun, mx), alpha = fast_exp2(mrun - mnew);
;       float ls = 0.f;
; #pragma unroll
;       for (int e = 0; e < 16; ++e) { const float p = fast_exp2(s[e] - mnew); s[e] = p; ls += p; }
;       ls += __shfl_xor(ls, 32);
;       lrun = lrun * alpha + ls; mrun = mnew;
; #pragma unroll
;       for (int db = 0; db < 4; ++db)
; #pragma unroll
;         for (int e = 0; e < 16; ++e) o[db][e] *= alpha;
;       bf16x8 pf[2];
; #pragma unroll
;       for (int s2 = 0; s2 < 2; ++s2) {
;         union { uint4 u; bf16x8 v; } cv;
;         cv.u.x = cvt_pk_bf16(s[8 * s2 + 0], s[8 * s2 + 1]); cv.u.y = cvt_pk_bf16(s[8 * s2 + 2], s[8 * s2 + 3]);
;         cv.u.z = cvt_pk_bf16(s[8 * s2 + 4], s[8 * s2 + 5]); cv.u.w = cvt_pk_bf16(s[8 * s2 + 6], s[8 * s2 + 7]);
;         pf[s2] = cv.v;
;       }
; #pragma unroll
;       for (int s2 = 0; s2 < 2; ++s2)
; #pragma unroll
;         for (int db = 0; db < 4; ++db) o[db] = __builtin_amdgcn_mfma_f32_32x32x16_bf16(vf[s2][db], pf[s2], o[db], 0, 0, 0);
	v_max3_f32 v158, v205, v64, v65
	v_sub_f32_e32 v164, v164, v158
	v_exp_f32_e32 v185, v164
	v_sub_f32_e32 v164, v165, v158
	v_sub_f32_e32 v179, v205, v158
	v_exp_f32_e32 v205, v164
	v_sub_f32_e32 v164, v166, v158
	v_exp_f32_e32 v207, v164
	v_sub_f32_e32 v164, v167, v158
	v_exp_f32_e32 v209, v164
	v_sub_f32_e32 v164, v168, v158
	v_exp_f32_e32 v216, v164
	v_sub_f32_e32 v164, v169, v158
	v_exp_f32_e32 v169, v164
	v_sub_f32_e32 v164, v170, v158
	v_exp_f32_e32 v170, v164
	v_sub_f32_e32 v164, v171, v158
	v_exp_f32_e32 v171, v164
	v_sub_f32_e32 v164, v172, v158
	v_exp_f32_e32 v168, v179
	v_exp_f32_e32 v172, v164
	v_sub_f32_e32 v164, v173, v158
	v_exp_f32_e32 v173, v164
	v_sub_f32_e32 v164, v174, v158
	v_exp_f32_e32 v174, v164
	v_sub_f32_e32 v164, v175, v158
	v_sub_f32_e32 v64, v159, v158
	v_exp_f32_e32 v175, v164
	v_sub_f32_e32 v164, v176, v158
	v_pk_mul_f32 v[62:63], v[62:63], v[168:169] op_sel_hi:[1,0]
	v_pk_mul_f32 v[60:61], v[60:61], v[168:169] op_sel_hi:[1,0]
	v_pk_mul_f32 v[58:59], v[58:59], v[168:169] op_sel_hi:[1,0]
	v_pk_mul_f32 v[56:57], v[56:57], v[168:169] op_sel_hi:[1,0]
	v_pk_mul_f32 v[54:55], v[54:55], v[168:169] op_sel_hi:[1,0]
	v_pk_mul_f32 v[52:53], v[52:53], v[168:169] op_sel_hi:[1,0]
	v_pk_mul_f32 v[50:51], v[50:51], v[168:169] op_sel_hi:[1,0]
	v_pk_mul_f32 v[48:49], v[48:49], v[168:169] op_sel_hi:[1,0]
	v_exp_f32_e32 v159, v64
	v_exp_f32_e32 v176, v164
	v_cvt_pk_bf16_f32 v164, v159, v185
	v_cvt_pk_bf16_f32 v165, v205, v207
	v_cvt_pk_bf16_f32 v166, v209, v216
	v_cvt_pk_bf16_f32 v167, v169, v170
	ds_read_b128 v[76:79], v249 offset:7680
	ds_read_b128 v[64:67], v249 offset:7712
	v_mfma_f32_32x32x16_bf16 v[48:63], v[150:153], v[164:167], v[48:63]
	v_mul_f32_e64 v46, v46, v168
	v_mul_f32_e64 v47, v47, v168
	v_mul_f32_e64 v44, v44, v168
	v_mul_f32_e64 v45, v45, v168
	v_mul_f32_e64 v42, v42, v168
	v_mul_f32_e64 v43, v43, v168
	v_pk_mul_f32 v[40:41], v[40:41], v[168:169] op_sel_hi:[1,0]
	v_pk_mul_f32 v[38:39], v[38:39], v[168:169] op_sel_hi:[1,0]
	v_pk_mul_f32 v[36:37], v[36:37], v[168:169] op_sel_hi:[1,0]
	v_pk_mul_f32 v[34:35], v[34:35], v[168:169] op_sel_hi:[1,0]
	v_pk_mul_f32 v[32:33], v[32:33], v[168:169] op_sel_hi:[1,0]
	v_pk_mul_f32 v[14:15], v[14:15], v[168:169] op_sel_hi:[1,0]
	v_pk_mul_f32 v[12:13], v[12:13], v[168:169] op_sel_hi:[1,0]
	v_pk_mul_f32 v[10:11], v[10:11], v[168:169] op_sel_hi:[1,0]
	v_pk_mul_f32 v[8:9], v[8:9], v[168:169] op_sel_hi:[1,0]
	v_pk_mul_f32 v[6:7], v[6:7], v[168:169] op_sel_hi:[1,0]
	v_pk_mul_f32 v[4:5], v[4:5], v[168:169] op_sel_hi:[1,0]
	v_pk_mul_f32 v[2:3], v[2:3], v[168:169] op_sel_hi:[1,0]
	v_pk_mul_f32 v[0:1], v[0:1], v[168:169] op_sel_hi:[1,0]
	v_add_f32_e32 v183, 0, v159
	v_sub_f32_e32 v177, v177, v158
	v_mfma_f32_32x32x16_bf16 v[32:47], v[160:163], v[164:167], v[32:47]
	v_exp_f32_e32 v150, v177
	v_pk_mul_f32 v[30:31], v[30:31], v[168:169] op_sel_hi:[1,0]
	v_pk_mul_f32 v[28:29], v[28:29], v[168:169] op_sel_hi:[1,0]
	v_pk_mul_f32 v[26:27], v[26:27], v[168:169] op_sel_hi:[1,0]
	v_pk_mul_f32 v[24:25], v[24:25], v[168:169] op_sel_hi:[1,0]
	v_pk_mul_f32 v[22:23], v[22:23], v[168:169] op_sel_hi:[1,0]
	v_pk_mul_f32 v[20:21], v[20:21], v[168:169] op_sel_hi:[1,0]
	s_waitcnt lgkmcnt(1)
	v_mfma_f32_32x32x16_bf16 v[0:15], v[76:79], v[164:167], v[0:15]
	v_sub_f32_e32 v76, v178, v158
	v_exp_f32_e32 v151, v76
	v_cvt_pk_bf16_f32 v76, v171, v172
	v_cvt_pk_bf16_f32 v77, v173, v174
	v_cvt_pk_bf16_f32 v78, v175, v176
	v_cvt_pk_bf16_f32 v79, v150, v151
	v_pk_mul_f32 v[18:19], v[18:19], v[168:169] op_sel_hi:[1,0]
	v_mfma_f32_32x32x16_bf16 v[48:63], v[146:149], v[76:79], v[48:63]
	v_add_f32_e32 v146, v185, v183
	v_add_f32_e32 v146, v205, v146
	v_add_f32_e32 v146, v207, v146
	v_add_f32_e32 v146, v209, v146
	v_add_f32_e32 v146, v216, v146
	v_pk_mul_f32 v[16:17], v[16:17], v[168:169] op_sel_hi:[1,0]
	v_add_f32_e32 v146, v169, v146
	v_add_f32_e32 v146, v170, v146
	v_mfma_f32_32x32x16_bf16 v[16:31], v[154:157], v[164:167], v[16:31]
	v_add_u32_e32 v203, 32, v203
	v_add_u32_e32 v193, 32, v193
	v_mov_b32_e32 v205, v158
	v_mfma_f32_32x32x16_bf16 v[32:47], v[72:75], v[76:79], v[32:47]
	v_add_f32_e32 v72, v171, v146
	v_add_f32_e32 v72, v172, v72
	v_add_f32_e32 v72, v173, v72
	v_add_f32_e32 v72, v174, v72
	v_add_f32_e32 v72, v175, v72
	v_add_f32_e32 v72, v176, v72
	v_add_f32_e32 v72, v150, v72
	v_mfma_f32_32x32x16_bf16 v[16:31], v[68:71], v[76:79], v[16:31]
	v_add_f32_e32 v68, v151, v72
	ds_bpermute_b32 v69, v80, v68
	s_waitcnt lgkmcnt(0)
	v_add_f32_e32 v70, v68, v69
	v_mfma_f32_32x32x16_bf16 v[0:15], v[64:67], v[76:79], v[0:15]
	v_fmac_f32_e32 v70, v201, v168
	v_mov_b32_e32 v201, v70
	s_andn2_b64 exec, exec, s[42:43]
	s_cbranch_execz .LBB0_719
; #define LAS __attribute__((address_space(3)))
; __device__ __forceinline__ void phase_attention(bf16_t* __restrict__ qh, const bf16_t* __restrict__ kh, const bf16_t* __restrict__ vb, float* __restrict__ lse, LAS unsigned char* obuf, const int nseq, const int S) {
;     ...
;     for (int j = jmin; j <= jmax; ++j) {
;       const int kb = m0 - 64 + 32 * j;
;       u32x4 vraw[8];
;       { const bf16_t* vp = vt0 + (ptrdiff_t)(kb >> 5) * 4096;
; #pragma unroll
;         for (int i = 0; i < 8; ++i) vraw[i] = *(const u32x4*)(vp + i * 512); }
; #pragma unroll
;       for (int i = 0; i < 8; ++i) *(LAS u32x4*)(tb + kw + i * (4 * 272)) = kraw[i];
;       bf16x8 kf[8];
; #pragma unroll
;       for (int kk = 0; kk < 8; ++kk) kf[kk] = *(const LAS bf16x8*)(tb + kr + 32 * kk);
;       f32x16 s;
; #pragma unroll
;       for (int e = 0; e < 16; ++e) s[e] = 0.f;
; #pragma unroll
;       for (int kk = 0; kk < 8; ++kk) s = __builtin_amdgcn_mfma_f32_32x32x16_bf16(kf[kk], qf[kk], s, 0, 0, 0);
;       if (j < jmax) { const bf16_t* kp = kt0 + (ptrdiff_t)(kb + 32) * 128;
; #pragma unroll
;         for (int i = 0; i < 8; ++i) kraw[i] = *(const u32x4*)(kp + i * 512); }
; #pragma unroll
.LBB0_717:
	v_add_u32_e32 v183, v199, v193
	v_subrev_u32_e32 v68, 64, v183
	v_ashrrev_i32_e32 v68, 5, v68
	v_ashrrev_i32_e32 v69, 31, v68
	v_add_u32_e32 v64, v238, v241
	v_lshlrev_b64 v[68:69], 13, v[68:69]
	s_waitcnt vmcnt(0) lgkmcnt(0)
	ds_write_b128 v64, v[114:117]
	ds_write_b128 v64, v[118:121] offset:1088
	ds_write_b128 v64, v[122:125] offset:2176
	ds_write_b128 v64, v[126:129] offset:3264
	ds_write_b128 v64, v[130:133] offset:4352
	ds_write_b128 v64, v[134:137] offset:5440
	ds_write_b128 v64, v[138:141] offset:6528
	ds_write_b128 v64, v[142:145] offset:7616
	v_lshl_add_u64 v[68:69], v[218:219], 0, v[68:69]
	ds_read_b128 v[64:67], v247
	global_load_dwordx4 v[146:149], v[68:69], off
	global_load_dwordx4 v[150:153], v[68:69], off offset:1024
	global_load_dwordx4 v[154:157], v[68:69], off offset:2048
	global_load_dwordx4 v[158:161], v[68:69], off offset:3072
	v_add_co_u32_e32 v68, vcc, s77, v68
	v_cmp_gt_i32_e64 s[4:5], v195, v197
	s_nop 0
	v_addc_co_u32_e32 v69, vcc, 0, v69, vcc
	global_load_dwordx4 v[162:165], v[68:69], off
	global_load_dwordx4 v[166:169], v[68:69], off offset:1024
	global_load_dwordx4 v[170:173], v[68:69], off offset:2048
	global_load_dwordx4 v[174:177], v[68:69], off offset:3072
	ds_read_b128 v[226:229], v247 offset:32
	s_waitcnt lgkmcnt(0)
	v_mfma_f32_32x32x16_bf16 v[64:79], v[64:67], v[82:85], 0
	v_cmp_le_i32_e32 vcc, v195, v197
	v_mfma_f32_32x32x16_bf16 v[64:79], v[226:229], v[86:89], v[64:79]
	ds_read_b128 v[226:229], v247 offset:64
	s_waitcnt lgkmcnt(0)
	v_mfma_f32_32x32x16_bf16 v[64:79], v[226:229], v[90:93], v[64:79]
	ds_read_b128 v[226:229], v247 offset:96
	s_waitcnt lgkmcnt(0)
	v_mfma_f32_32x32x16_bf16 v[64:79], v[226:229], v[94:97], v[64:79]
	ds_read_b128 v[226:229], v247 offset:128
	s_waitcnt lgkmcnt(0)
	v_mfma_f32_32x32x16_bf16 v[64:79], v[226:229], v[98:101], v[64:79]
	ds_read_b128 v[226:229], v247 offset:160
	s_waitcnt lgkmcnt(0)
	v_mfma_f32_32x32x16_bf16 v[64:79], v[226:229], v[102:105], v[64:79]
	ds_read_b128 v[226:229], v247 offset:192
	s_waitcnt lgkmcnt(0)
	v_mfma_f32_32x32x16_bf16 v[64:79], v[226:229], v[106:109], v[64:79]
	ds_read_b128 v[226:229], v247 offset:224
	s_waitcnt lgkmcnt(0)
	v_mfma_f32_32x32x16_bf16 v[64:79], v[226:229], v[110:113], v[64:79]
	s_and_saveexec_b64 s[44:45], vcc
	s_cbranch_execz .LBB0_716
	v_subrev_u32_e32 v114, 32, v183
	v_ashrrev_i32_e32 v115, 31, v114
	v_lshlrev_b64 v[114:115], 8, v[114:115]
	v_lshl_add_u64 v[130:131], v[214:215], 0, v[114:115]
	v_add_co_u32_e32 v142, vcc, 0x1000, v130
	global_load_dwordx4 v[114:117], v[130:131], off
	global_load_dwordx4 v[118:121], v[130:131], off offset:1024
	global_load_dwordx4 v[122:125], v[130:131], off offset:2048
	global_load_dwordx4 v[126:129], v[130:131], off offset:3072
	v_addc_co_u32_e32 v143, vcc, 0, v131, vcc
	global_load_dwordx4 v[130:133], v[142:143], off
	global_load_dwordx4 v[134:137], v[142:143], off offset:1024
	global_load_dwordx4 v[138:141], v[142:143], off offset:2048
	s_nop 0
	global_load_dwordx4 v[142:145], v[142:143], off offset:3072
	s_or_b64 exec, exec, s[44:45]
	s_waitcnt vmcnt(8)
	s_branch .Lattn_vready
.LBB0_719:
	s_or_b64 exec, exec, s[42:43]
	s_waitcnt vmcnt(0)
; #define LAS __attribute__((address_space(3)))
; __device__ __forceinline__ unsigned cvt_pk_bf16(float lo, float hi) { unsigned r; asm("v_cvt_pk_bf16_f32 %0, %1, %2" : "=v"(r) : "v"(lo), "v"(hi)); return r; }
; __device__ __forceinline__ void phase_attention(bf16_t* __restrict__ qh, const bf16_t* __restrict__ kh, const bf16_t* __restrict__ vb, float* __restrict__ lse, LAS unsigned char* obuf, const int nseq, const int S) {
;     ...
;     const float inv = 1.f / lrun;
;     LAS unsigned char* ob = tb;
; #pragma unroll
;     for (int db = 0; db < 4; ++db)
; #pragma unroll
;       for (int j4 = 0; j4 < 4; ++j4) {
;         u32x2 w; w[0] = cvt_pk_bf16(o[db][4 * j4] * inv, o[db][4 * j4 + 1] * inv); w[1] = cvt_pk_bf16(o[db][4 * j4 + 2] * inv, o[db][4 * j4 + 3] * inv);
;         *(LAS u32x2*)(ob + rl * 272 + (32 * db + 8 * j4 + 4 * h) * 2) = w;
;       }
;     { bf16_t* orow0 = qrow - (size_t)rl * 128;
; #pragma unroll
;       for (int k8 = 0; k8 < 8; ++k8) {
;         const int row = (lane >> 4) + 4 * k8;
;         const u32x4 v = *(const LAS u32x4*)(ob + row * 272 + (lane & 15) * 16);
;         *(u32x4*)(orow0 + (size_t)row * 128 + (lane & 15) * 8) = v;
;       } }
;     if (h == 0) lse[(size_t)hh * TS + pbase + m0 + rl] = (mrun + __log2f(lrun)) * LN2;
.LBB0_720:
	s_or_b64 exec, exec, s[96:97]
	v_div_scale_f32 v64, s[4:5], v70, v70, 1.0
	v_rcp_f32_e32 v65, v64
	v_div_scale_f32 v66, vcc, 1.0, v70, 1.0
	v_mov_b32_e32 v193, v81
	v_fma_f32 v67, -v64, v65, 1.0
	v_fmac_f32_e32 v65, v67, v65
	v_mul_f32_e32 v67, v66, v65
	v_fma_f32 v68, -v64, v67, v66
	v_fmac_f32_e32 v67, v68, v65
	v_fma_f32 v64, -v64, v67, v66
	v_div_fmas_f32 v64, v64, v65, v67
	v_div_fixup_f32 v64, v64, v70, 1.0
	v_mul_f32_e32 v48, v48, v64
	v_mul_f32_e32 v49, v49, v64
	v_mul_f32_e32 v32, v32, v64
	v_mul_f32_e32 v33, v33, v64
	v_mul_f32_e32 v16, v16, v64
	v_mul_f32_e32 v17, v17, v64
	v_mul_f32_e32 v0, v0, v64
	v_mul_f32_e32 v1, v1, v64
	v_cvt_pk_bf16_f32 v48, v48, v49
	v_mul_f32_e32 v49, v50, v64
	v_mul_f32_e32 v50, v51, v64
	v_cvt_pk_bf16_f32 v32, v32, v33
	v_mul_f32_e32 v33, v34, v64
	v_mul_f32_e32 v34, v35, v64
	v_cvt_pk_bf16_f32 v16, v16, v17
	v_mul_f32_e32 v17, v18, v64
	v_mul_f32_e32 v18, v19, v64
	v_cvt_pk_bf16_f32 v0, v0, v1
	v_mul_f32_e32 v1, v2, v64
	v_mul_f32_e32 v2, v3, v64
	v_cvt_pk_bf16_f32 v49, v49, v50
	v_mul_f32_e32 v50, v52, v64
	v_mul_f32_e32 v51, v53, v64
	v_cvt_pk_bf16_f32 v33, v33, v34
	v_mul_f32_e32 v34, v36, v64
	v_mul_f32_e32 v35, v37, v64
	v_cvt_pk_bf16_f32 v17, v17, v18
	v_mul_f32_e32 v18, v20, v64
	v_mul_f32_e32 v19, v21, v64
	v_cvt_pk_bf16_f32 v1, v1, v2
	v_mul_f32_e32 v2, v4, v64
	v_mul_f32_e32 v3, v5, v64
	v_add_u32_e32 v65, v239, v242
	v_cvt_pk_bf16_f32 v50, v50, v51
	v_mul_f32_e32 v51, v54, v64
	v_cvt_pk_bf16_f32 v34, v34, v35
	v_mul_f32_e32 v35, v38, v64
	v_cvt_pk_bf16_f32 v18, v18, v19
	v_mul_f32_e32 v19, v22, v64
	v_cvt_pk_bf16_f32 v2, v2, v3
	v_mul_f32_e32 v3, v6, v64
	v_mul_f32_e32 v52, v55, v64
	v_cvt_pk_bf16_f32 v51, v51, v52
	ds_write2_b64 v65, v[48:49], v[50:51] offset1:2
	v_mul_f32_e32 v48, v56, v64
	v_mul_f32_e32 v49, v57, v64
	v_mul_f32_e32 v36, v39, v64
	v_cvt_pk_bf16_f32 v35, v35, v36
	ds_write2_b64 v65, v[32:33], v[34:35] offset0:8 offset1:10
	v_mul_f32_e32 v32, v40, v64
	v_mul_f32_e32 v33, v41, v64
	v_mul_f32_e32 v20, v23, v64
	v_cvt_pk_bf16_f32 v19, v19, v20
	ds_write2_b64 v65, v[16:17], v[18:19] offset0:16 offset1:18
	v_mul_f32_e32 v16, v24, v64
	v_mul_f32_e32 v17, v25, v64
	v_mul_f32_e32 v4, v7, v64
	v_cvt_pk_bf16_f32 v3, v3, v4
	ds_write2_b64 v65, v[0:1], v[2:3] offset0:24 offset1:26
	v_mul_f32_e32 v0, v8, v64
	v_mul_f32_e32 v1, v9, v64
	v_cvt_pk_bf16_f32 v48, v48, v49
	v_mul_f32_e32 v49, v58, v64
	v_mul_f32_e32 v50, v59, v64
	v_cvt_pk_bf16_f32 v32, v32, v33
	v_mul_f32_e32 v33, v42, v64
	v_mul_f32_e32 v34, v43, v64
	v_cvt_pk_bf16_f32 v16, v16, v17
	v_mul_f32_e32 v17, v26, v64
	v_mul_f32_e32 v18, v27, v64
	v_cvt_pk_bf16_f32 v0, v0, v1
	v_mul_f32_e32 v1, v10, v64
	v_mul_f32_e32 v2, v11, v64
	v_cvt_pk_bf16_f32 v49, v49, v50
	v_mul_f32_e32 v50, v60, v64
	v_mul_f32_e32 v51, v61, v64
	v_cvt_pk_bf16_f32 v33, v33, v34
	v_mul_f32_e32 v34, v44, v64
	v_mul_f32_e32 v35, v45, v64
	v_cvt_pk_bf16_f32 v17, v17, v18
	v_mul_f32_e32 v18, v28, v64
	v_mul_f32_e32 v19, v29, v64
	v_cvt_pk_bf16_f32 v1, v1, v2
	v_mul_f32_e32 v2, v12, v64
	v_mul_f32_e32 v3, v13, v64
	v_cvt_pk_bf16_f32 v50, v50, v51
	v_mul_f32_e32 v51, v62, v64
	v_cvt_pk_bf16_f32 v34, v34, v35
	v_mul_f32_e32 v35, v46, v64
	v_cvt_pk_bf16_f32 v18, v18, v19
	v_mul_f32_e32 v19, v30, v64
	v_cvt_pk_bf16_f32 v2, v2, v3
	v_mul_f32_e32 v3, v14, v64
	v_mul_f32_e32 v52, v63, v64
	v_cvt_pk_bf16_f32 v51, v51, v52
	ds_write2_b64 v65, v[48:49], v[50:51] offset0:4 offset1:6
	v_mul_f32_e32 v36, v47, v64
	v_cvt_pk_bf16_f32 v35, v35, v36
	ds_write2_b64 v65, v[32:33], v[34:35] offset0:12 offset1:14
	v_mul_f32_e32 v20, v31, v64
	v_cvt_pk_bf16_f32 v19, v19, v20
	ds_write2_b64 v65, v[16:17], v[18:19] offset0:20 offset1:22
	v_mul_f32_e32 v4, v15, v64
	v_cvt_pk_bf16_f32 v3, v3, v4
	ds_write2_b64 v65, v[0:1], v[2:3] offset0:28 offset1:30
	ds_read_b128 v[0:3], v250
	ds_read_b128 v[4:7], v251
	v_lshl_add_u64 v[8:9], v[212:213], 0, v[192:193]
	v_mov_b32_e32 v195, v81
	v_lshl_add_u64 v[10:11], v[8:9], 0, v[194:195]
	v_mov_b32_e32 v197, v81
	s_waitcnt lgkmcnt(1)
	global_store_dwordx4 v[10:11], v[0:3], off
	v_lshl_add_u64 v[10:11], v[8:9], 0, v[196:197]
	ds_read_b128 v[0:3], v251 offset:1088
	s_waitcnt lgkmcnt(0)
	global_store_dwordx4 v[10:11], v[4:7], off
	ds_read_b128 v[4:7], v251 offset:2176
	v_mov_b32_e32 v199, v81
	v_lshl_add_u64 v[10:11], v[8:9], 0, v[198:199]
	v_mov_b32_e32 v201, v81
	global_store_dwordx4 v[10:11], v[0:3], off
	v_lshl_add_u64 v[10:11], v[8:9], 0, v[200:201]
	ds_read_b128 v[0:3], v251 offset:3264
	s_waitcnt lgkmcnt(0)
	global_store_dwordx4 v[10:11], v[4:7], off
	ds_read_b128 v[4:7], v251 offset:4352
	v_mov_b32_e32 v203, v81
	v_lshl_add_u64 v[10:11], v[8:9], 0, v[202:203]
	v_mov_b32_e32 v205, v81
	global_store_dwordx4 v[10:11], v[0:3], off
	v_lshl_add_u64 v[10:11], v[8:9], 0, v[204:205]
	ds_read_b128 v[0:3], v251 offset:5440
	s_waitcnt lgkmcnt(0)
	global_store_dwordx4 v[10:11], v[4:7], off
	ds_read_b128 v[4:7], v251 offset:6528
	v_mov_b32_e32 v207, v81
	v_lshl_add_u64 v[10:11], v[8:9], 0, v[206:207]
	v_mov_b32_e32 v209, v81
	global_store_dwordx4 v[10:11], v[0:3], off
	s_nop 1
	v_lshl_add_u64 v[0:1], v[8:9], 0, v[208:209]
	s_waitcnt lgkmcnt(0)
	global_store_dwordx4 v[0:1], v[4:7], off
	s_and_saveexec_b64 s[4:5], s[2:3]
	s_cbranch_execz .LBB0_711
	v_log_f32_e32 v0, v70
	s_nop 0
	v_add_f32_e32 v0, v158, v0
	v_mul_f32_e32 v2, 0x3f317218, v0
	v_lshl_add_u64 v[0:1], v[210:211], 2, s[36:37]
	global_store_dword v[0:1], v2, off
	s_branch .LBB0_711

; #define LAS __attribute__((address_space(3)))
; __device__ __forceinline__ int otid() { int t = threadIdx.x; asm volatile("" : "+v"(t)); return t; }
; __device__ __forceinline__ unsigned xb_ld(unsigned* p) { return __hip_atomic_load(p, __ATOMIC_RELAXED, __HIP_MEMORY_SCOPE_AGENT); }
; __device__ __forceinline__ unsigned xb_add(unsigned* p, unsigned v) { return __hip_atomic_fetch_add(p, v, __ATOMIC_RELAXED, __HIP_MEMORY_SCOPE_AGENT); }
; __device__ __forceinline__ void gbar(unsigned* bar, unsigned n, volatile LAS unsigned* st) {
;   asm volatile("s_waitcnt vmcnt(0)" ::: "memory");
;   __syncthreads();
;   if (otid() == 0) {
;     __builtin_amdgcn_s_waitcnt(0);
;     const unsigned x = st[0], nloc = st[1], nx = st[2];
;     const unsigned old = xb_add(&bar[XB_XSUB(x)], 1u);
;     unsigned sp = 0;
;     if (old + 1u == (n + 1u) * nloc) {
;       __builtin_amdgcn_fence(__ATOMIC_RELEASE, "agent");
;       asm volatile("s_waitcnt vmcnt(0)" ::: "memory");
;       xb_add(&bar[XB_TOP], 1u);
;       while (xb_ld(&bar[XB_TOP]) < (n + 1u) * nx) { __builtin_amdgcn_s_sleep(1); if (++sp > (1u << 24)) break; }
;       __builtin_amdgcn_fence(__ATOMIC_ACQUIRE, "agent");
;       xb_add(&bar[XB_XGEN(x)], 1u);
;       asm volatile("s_waitcnt vmcnt(0)" ::: "memory");
;     } else {
;       while (xb_ld(&bar[XB_XGEN(x)]) <= n) { __builtin_amdgcn_s_sleep(1); if (++sp > (1u << 24)) break; }
;       __builtin_amdgcn_fence(__ATOMIC_ACQUIRE, "agent");
;       asm volatile("s_waitcnt vmcnt(0)" ::: "memory");
;     }
;   }
;   __syncthreads();
; }
.LBB0_723:
	v_mov_b64_e32 v[0:1], s[10:11]
	global_load_dwordx2 v[0:1], v[0:1], off sc0 sc1
	s_waitcnt vmcnt(0)
	s_waitcnt vmcnt(0)
	v_mov_b32_e32 v2, v252
	s_waitcnt lgkmcnt(0)
	s_barrier
	v_add_u32_e32 v4, 3, v236
	v_cmp_ne_u32_e32 vcc, 0, v2
	v_readfirstlane_b32 s0, v1
	v_readfirstlane_b32 s1, v0
	s_and_saveexec_b64 s[2:3], vcc
	s_xor_b64 s[2:3], exec, s[2:3]
	v_add_u32_e32 v4, 3, v236
	s_andn2_saveexec_b64 s[2:3], s[2:3]
	s_cbranch_execz .LBB0_773
	v_readlane_b32 s8, v255, 15
	s_waitcnt vmcnt(0) expcnt(0) lgkmcnt(0)
	s_add_u32 s4, s1, 0x4cc80000
	v_mov_b32_e32 v0, s8
	ds_read_b32 v1, v0
	v_readlane_b32 s8, v255, 16
	s_addc_u32 s5, s0, 0
	s_waitcnt lgkmcnt(0)
	v_lshlrev_b32_e32 v1, 6, v1
	v_add_u32_e32 v80, 0x440, v1
	v_mov_b32_e32 v0, s8
	v_readlane_b32 s8, v255, 17
	v_lshlrev_b64 v[2:3], 2, v[80:81]
	ds_read_b32 v5, v0
	v_mov_b32_e32 v0, s8
	v_lshl_add_u64 v[2:3], s[4:5], 0, v[2:3]
	ds_read_b32 v0, v0
	global_atomic_add v2, v[2:3], v230, off sc0
	s_waitcnt lgkmcnt(0)
	v_mul_lo_u32 v3, v5, v4
	v_add_u32_e32 v80, 0x840, v1
	s_waitcnt vmcnt(0)
	v_add_u32_e32 v2, 1, v2
	v_cmp_ne_u32_e32 vcc, v2, v3
	s_and_saveexec_b64 s[8:9], vcc
	s_xor_b64 s[8:9], exec, s[8:9]
	s_cbranch_execz .LBB0_749
	v_lshlrev_b64 v[0:1], 2, v[80:81]
	v_lshl_add_u64 v[0:1], s[4:5], 0, v[0:1]
	s_mov_b32 s13, 0x1000000
	s_mov_b64 s[36:37], 0
	s_branch .LBB0_737

; __device__ __forceinline__ unsigned xb_ld(unsigned* p) { return __hip_atomic_load(p, __ATOMIC_RELAXED, __HIP_MEMORY_SCOPE_AGENT); }
; __device__ __forceinline__ void gbar(unsigned* bar, unsigned n, volatile LAS unsigned* st) {
;     ...
;       while (xb_ld(&bar[XB_XGEN(x)]) <= n) { __builtin_amdgcn_s_sleep(1); if (++sp > (1u << 24)) break; }
.LBB0_737:
	global_load_dword v2, v[0:1], off sc1
	s_or_b64 s[38:39], s[38:39], exec
	s_waitcnt vmcnt(0) lgkmcnt(0)
	v_cmp_le_u32_e32 vcc, v2, v181
	s_and_saveexec_b64 s[40:41], vcc
	s_cbranch_execz .LBB0_736
	s_cmp_lg_u32 s13, 0
	s_sleep 1
	s_cbranch_scc0 .LBB0_747
	global_load_dword v2, v[0:1], off sc1
	s_mov_b64 s[18:19], -1
	s_waitcnt vmcnt(0) lgkmcnt(0)
	v_cmp_le_u32_e32 vcc, v2, v181
	s_and_saveexec_b64 s[42:43], vcc
	s_cbranch_execz .LBB0_734
	s_sleep 1
	global_load_dword v2, v[0:1], off sc1
	s_waitcnt vmcnt(0) lgkmcnt(0)
	v_cmp_le_u32_e32 vcc, v2, v181
	s_and_saveexec_b64 s[44:45], vcc
	s_cbranch_execz .LBB0_733
	s_sleep 1
	global_load_dword v2, v[0:1], off sc1
	s_waitcnt vmcnt(0) lgkmcnt(0)
	v_cmp_le_u32_e32 vcc, v2, v181
	s_and_saveexec_b64 s[46:47], vcc
	s_cbranch_execz .LBB0_732
	s_sleep 1
	global_load_dword v2, v[0:1], off sc1
	s_waitcnt vmcnt(0) lgkmcnt(0)
	v_cmp_le_u32_e32 vcc, v2, v181
	s_and_saveexec_b64 s[68:69], vcc
	s_cbranch_execz .LBB0_731
	s_sleep 1
	global_load_dword v2, v[0:1], off sc1
	s_waitcnt vmcnt(0) lgkmcnt(0)
	v_cmp_le_u32_e32 vcc, v2, v181
	s_and_saveexec_b64 s[94:95], vcc
	s_cbranch_execz .LBB0_730
	s_sleep 1
	global_load_dword v2, v[0:1], off sc1
	s_mov_b64 s[48:49], -1
	s_waitcnt vmcnt(0) lgkmcnt(0)
	v_cmp_le_u32_e32 vcc, v2, v181
	s_and_saveexec_b64 s[18:19], vcc
	s_cbranch_execz .LBB0_729
	s_sleep 1
	global_load_dword v2, v[0:1], off sc1
	s_waitcnt vmcnt(0) lgkmcnt(0)
	v_cmp_le_u32_e32 vcc, v2, v181
	s_and_saveexec_b64 s[66:67], vcc
	s_cbranch_execz .LBB0_728
	s_add_i32 s13, s13, -8
	s_xor_b64 s[48:49], exec, -1
	s_sleep 1
	s_branch .LBB0_728

; __device__ __forceinline__ unsigned xb_ld(unsigned* p) { return __hip_atomic_load(p, __ATOMIC_RELAXED, __HIP_MEMORY_SCOPE_AGENT); }
; __device__ __forceinline__ unsigned xb_add(unsigned* p, unsigned v) { return __hip_atomic_fetch_add(p, v, __ATOMIC_RELAXED, __HIP_MEMORY_SCOPE_AGENT); }
; __device__ __forceinline__ void gbar(unsigned* bar, unsigned n, volatile LAS unsigned* st) {
;     ...
;     if (old + 1u == (n + 1u) * nloc) {
;       __builtin_amdgcn_fence(__ATOMIC_RELEASE, "agent");
;       asm volatile("s_waitcnt vmcnt(0)" ::: "memory");
;       xb_add(&bar[XB_TOP], 1u);
;       while (xb_ld(&bar[XB_TOP]) < (n + 1u) * nx) { __builtin_amdgcn_s_sleep(1); if (++sp > (1u << 24)) break; }
.LBB0_749:
	s_andn2_saveexec_b64 s[8:9], s[8:9]
	s_cbranch_execz .LBB0_772
	v_mov_b32_e32 v1, s1
	v_add_co_u32_e32 v2, vcc, 0x4cc83000, v1
	v_mov_b32_e32 v1, s0
	buffer_wbl2 sc1
	s_waitcnt vmcnt(0)
	v_addc_co_u32_e32 v3, vcc, 0, v1, vcc
	global_atomic_add v[2:3], v230, off offset:256
	s_add_u32 s36, s1, 0x4cc83100
	s_addc_u32 s37, s0, 0
	v_mul_lo_u32 v0, v0, v4
	s_mov_b32 s0, 0x1000000
	s_mov_b64 s[38:39], 0
	s_branch .LBB0_760

; __device__ __forceinline__ int otid() { int t = threadIdx.x; asm volatile("" : "+v"(t)); return t; }
; __device__ __forceinline__ int obid() { extern __shared__ __attribute__((aligned(16))) unsigned char shm_vb[]; return __builtin_amdgcn_readfirstlane(*(volatile LAS int*)((LAS unsigned char*)shm_vb + VB_OFF)); }
; __device__ __forceinline__ void phase_attn_combine(const bf16_t* __restrict__ qh, const bf16_t* __restrict__ gate, const float* __restrict__ lse, bf16_t* __restrict__ y, const int S) {
;   const size_t n8 = (size_t)TS * 256, gs = (size_t)gridDim.x * 512;
; #pragma unroll 2
;   for (size_t i = (size_t)obid() * 512 + otid(); i < n8; i += gs) {
;     const size_t t = i >> 8; const int col = (int)(i & 255) * 8, h16 = col >> 7, dd = col & 127;
;     const int seq = (int)(t / S), n = (int)(t % S);
;     const size_t p0 = t, p1 = (size_t)seq * S + (size_t)(n & 3) * (S >> 2) + (n >> 2), p2 = (size_t)seq * S + (size_t)(n & 15) * (S >> 4) + (n >> 4);
;     const float l0 = lse[(size_t)h16 * TS + p0], l1 = lse[(size_t)(16 + h16) * TS + p1], l2 = lse[(size_t)(32 + h16) * TS + p2];
;     const float mx = fmaxf(l0, fmaxf(l1, l2));
;     float w0 = __expf(l0 - mx), w1 = __expf(l1 - mx), w2 = __expf(l2 - mx);
;     const float wi = 1.f / (w0 + w1 + w2); w0 *= wi; w1 *= wi; w2 *= wi;
;     const uint4 a = *(const uint4*)(qh + ((size_t)h16 * TS + p0) * 128 + dd), b = *(const uint4*)(qh + ((size_t)(16 + h16) * TS + p1) * 128 + dd),
;                 c = *(const uint4*)(qh + ((size_t)(32 + h16) * TS + p2) * 128 + dd);
;     const uint4 gt = *(const uint4*)(gate + t * 2048 + col);
.LBB0_773:
	s_or_b64 exec, exec, s[2:3]
	v_mov_b64_e32 v[0:1], s[10:11]
	s_waitcnt lgkmcnt(0)
	s_barrier
	global_load_dwordx2 v[2:3], v[0:1], off sc0 sc1
	s_waitcnt vmcnt(0)
	global_load_dwordx2 v[6:7], v[0:1], off sc0 sc1
	s_waitcnt vmcnt(0)
	global_load_dwordx2 v[8:9], v[0:1], off sc0 sc1
	s_waitcnt vmcnt(0)
	global_load_dwordx2 v[10:11], v[0:1], off sc0 sc1
	s_waitcnt vmcnt(0)
	v_mov_b32_e32 v0, s74
	ds_read_b32 v5, v0
	v_mov_b32_e32 v0, v252
	s_mov_b64 s[2:3], 0x400000
	v_ashrrev_i32_e32 v1, 31, v0
	s_waitcnt lgkmcnt(0)
	v_readfirstlane_b32 s0, v5
	s_ashr_i32 s1, s0, 31
	s_lshl_b64 s[0:1], s[0:1], 9
	v_lshl_add_u64 v[0:1], s[0:1], 0, v[0:1]
	v_cmp_gt_u64_e32 vcc, s[2:3], v[0:1]
	v_readfirstlane_b32 s5, v3
	v_readfirstlane_b32 s4, v2
	v_readfirstlane_b32 s9, v7
	v_readfirstlane_b32 s8, v6
	v_readfirstlane_b32 s1, v9
	v_readfirstlane_b32 s18, v8
	v_readfirstlane_b32 s0, v11
	v_readfirstlane_b32 s13, v10
	s_and_saveexec_b64 s[2:3], vcc
	s_cbranch_execz .LBB0_776
	s_add_u32 s4, s4, 0x18180000
	s_addc_u32 s5, s5, 0
	s_add_u32 s8, s8, 0x3c180000
	s_addc_u32 s9, s9, 0
	s_add_u32 s36, s18, 0x40180000
	s_addc_u32 s37, s1, 0
	s_add_u32 s40, s13, 0x40480000
	s_addc_u32 s41, s0, 0
	s_and_b64 s[0:1], s[92:93], exec
	s_cselect_b32 s0, 11, 12
	s_cselect_b32 s1, 9, 10
	s_mov_b64 s[92:93], 0
.LBB0_775:
	v_alignbit_b32 v5, v1, v0, 8
	v_cmp_le_u32_e32 vcc, s17, v5
	v_mov_b32_e32 v6, s17
	v_lshrrev_b64 v[2:3], 8, v[0:1]
	v_cndmask_b32_e32 v6, 0, v6, vcc
	v_sub_u32_e32 v5, v5, v6
	v_and_b32_e32 v80, 3, v5
	v_sub_co_u32_e32 v6, vcc, v2, v5
	v_lshlrev_b64 v[8:9], s0, v[80:81]
	v_lshrrev_b32_e32 v80, 2, v5
	v_and_b32_e32 v10, 15, v5
	v_lshrrev_b32_e32 v12, 4, v5
	v_lshlrev_b32_e32 v5, 10, v0
	v_and_b32_e32 v5, 0x3c000, v5
	v_or_b32_e32 v14, v2, v5
	v_mov_b32_e32 v15, v3
	v_lshl_add_u64 v[16:17], v[14:15], 2, s[36:37]
	v_subbrev_co_u32_e32 v7, vcc, 0, v3, vcc
	global_load_dword v20, v[16:17], off
	v_or_b32_e32 v16, 0x40000, v5
	v_mov_b32_e32 v17, v81
	v_lshl_add_u64 v[16:17], v[6:7], 0, v[16:17]
	v_lshl_add_u64 v[16:17], v[16:17], 0, v[80:81]
	v_or_b32_e32 v80, 0x80000, v5
	v_mov_b32_e32 v11, v81
	v_mov_b32_e32 v13, v81
	v_lshl_add_u64 v[6:7], v[6:7], 0, v[80:81]
	v_lshlrev_b64 v[10:11], s1, v[10:11]
	v_lshl_add_u64 v[6:7], v[6:7], 0, v[12:13]
	v_lshl_add_u64 v[16:17], v[16:17], 0, v[8:9]
	v_lshl_add_u64 v[18:19], v[6:7], 0, v[10:11]
	v_lshl_add_u64 v[8:9], v[16:17], 2, s[36:37]
	v_lshl_add_u64 v[6:7], v[18:19], 2, s[36:37]
	global_load_dword v8, v[8:9], off
	v_lshlrev_b64 v[2:3], 12, v[2:3]
	global_load_dword v5, v[6:7], off
	s_waitcnt vmcnt(0) lgkmcnt(0)
	v_max3_f32 v6, v20, v8, v5
	v_sub_f32_e32 v7, v20, v6
	v_sub_f32_e32 v8, v8, v6
	v_mul_f32_e32 v7, 0x3fb8aa3b, v7
	v_mul_f32_e32 v8, 0x3fb8aa3b, v8
	v_sub_f32_e32 v5, v5, v6
	v_exp_f32_e32 v7, v7
	v_exp_f32_e32 v8, v8
	v_mul_f32_e32 v5, 0x3fb8aa3b, v5
	v_exp_f32_e32 v5, v5
	v_lshlrev_b32_e32 v20, 4, v0
	v_add_f32_e32 v6, v7, v8
	v_and_b32_e32 v80, 0xf0, v20
	v_add_f32_e32 v6, v5, v6
	v_div_scale_f32 v9, s[18:19], v6, v6, 1.0
	v_rcp_f32_e32 v10, v9
	v_lshl_add_u64 v[0:1], v[0:1], 0, s[14:15]
	v_fma_f32 v11, -v9, v10, 1.0
	v_fmac_f32_e32 v10, v11, v10
	v_div_scale_f32 v11, vcc, 1.0, v6, 1.0
	v_mul_f32_e32 v12, v11, v10
	v_fma_f32 v13, -v9, v12, v11
	v_fmac_f32_e32 v12, v13, v10
	v_fma_f32 v9, -v9, v12, v11
	v_div_fmas_f32 v9, v9, v10, v12
	v_div_fixup_f32 v6, v9, v6, 1.0
	v_mul_f32_e32 v22, v7, v6
	v_mul_f32_e32 v23, v8, v6
	v_mul_f32_e32 v5, v5, v6
	v_lshlrev_b64 v[6:7], 8, v[14:15]
	v_lshlrev_b64 v[10:11], 8, v[16:17]
	v_lshl_add_u64 v[6:7], s[4:5], 0, v[6:7]
	v_lshl_add_u64 v[10:11], s[4:5], 0, v[10:11]
	v_lshl_add_u64 v[6:7], v[6:7], 0, v[80:81]
	v_lshl_add_u64 v[10:11], v[10:11], 0, v[80:81]
	v_lshlrev_b64 v[14:15], 8, v[18:19]
	global_load_dwordx4 v[6:9], v[6:7], off
	v_lshl_add_u64 v[14:15], s[4:5], 0, v[14:15]
	global_load_dwordx4 v[10:13], v[10:11], off
	v_lshl_add_u64 v[14:15], v[14:15], 0, v[80:81]
	v_lshl_add_u64 v[18:19], s[8:9], 0, v[2:3]
	v_and_b32_e32 v80, 0xff0, v20
	global_load_dwordx4 v[14:17], v[14:15], off
	v_lshl_add_u64 v[18:19], v[18:19], 0, v[80:81]
	global_load_dwordx4 v[18:21], v[18:19], off
	v_lshl_add_u64 v[2:3], s[40:41], 0, v[2:3]
	v_lshl_add_u64 v[2:3], v[2:3], 0, v[80:81]
	s_waitcnt vmcnt(0) lgkmcnt(0)
; __device__ __forceinline__ unsigned cvt_pk_bf16(float lo, float hi) { unsigned r; asm("v_cvt_pk_bf16_f32 %0, %1, %2" : "=v"(r) : "v"(lo), "v"(hi)); return r; }
; __device__ __forceinline__ float bf_lo(unsigned u) { return __uint_as_float(u << 16); }
; __device__ __forceinline__ float bf_hi(unsigned u) { return __uint_as_float(u & 0xffff0000u); }
; __device__ __forceinline__ int otid() { int t = threadIdx.x; asm volatile("" : "+v"(t)); return t; }
; __device__ __forceinline__ int obid() { extern __shared__ __attribute__((aligned(16))) unsigned char shm_vb[]; return __builtin_amdgcn_readfirstlane(*(volatile LAS int*)((LAS unsigned char*)shm_vb + VB_OFF)); }
; __device__ __forceinline__ float sigmoidf_(float x) { return 1.f / (1.f + __expf(-x)); }
; __device__ __forceinline__ void phase_zero(unsigned long long* __restrict__ p, int n) {
;   for (int i = obid() * 512 + otid(); i < n; i += gridDim.x * 512) { unsigned z = 0; asm volatile("" : "+v"(z)); p[i] = z; }
; __device__ __forceinline__ void phase_attn_combine(const bf16_t* __restrict__ qh, const bf16_t* __restrict__ gate, const float* __restrict__ lse, bf16_t* __restrict__ y, const int S) {
;     ...
; #pragma unroll
;     for (int k = 0; k < 4; ++k) {
;       const float g0 = bf_lo(gu[k]), g1 = bf_hi(gu[k]);
;       const float y0 = (w0 * bf_lo(au[k]) + w1 * bf_lo(bu[k]) + w2 * bf_lo(cu[k])) * g0 * sigmoidf_(g0);
;       const float y1 = (w0 * bf_hi(au[k]) + w1 * bf_hi(bu[k]) + w2 * bf_hi(cu[k])) * g1 * sigmoidf_(g1);
;       ou[k] = cvt_pk_bf16(y0, y1);
;     }
;     uint4 o; o.x = ou[0]; o.y = ou[1]; o.z = ou[2]; o.w = ou[3];
;     *(uint4*)(y + t * 2048 + col) = o;
;   }
	v_lshlrev_b32_e32 v25, 16, v6
	v_and_b32_e32 v6, 0xffff0000, v6
	v_lshlrev_b32_e32 v26, 16, v10
	v_mul_f32_e32 v26, v23, v26
	v_fmac_f32_e32 v26, v22, v25
	v_and_b32_e32 v10, 0xffff0000, v10
	v_lshlrev_b32_e32 v25, 16, v14
	v_fmac_f32_e32 v26, v5, v25
	v_lshlrev_b32_e32 v24, 16, v18
	v_mul_f32_e32 v25, v26, v24
	v_mul_f32_e32 v24, 0xbfb8aa3b, v24
	v_exp_f32_e32 v24, v24
	v_mul_f32_e32 v10, v23, v10
	v_fmac_f32_e32 v10, v22, v6
	v_and_b32_e32 v6, 0xffff0000, v14
	v_add_f32_e32 v24, 1.0, v24
	v_div_scale_f32 v26, s[18:19], v24, v24, 1.0
	v_and_b32_e32 v18, 0xffff0000, v18
	v_rcp_f32_e32 v27, v26
	v_fmac_f32_e32 v10, v5, v6
	v_mul_f32_e32 v6, v10, v18
	v_mul_f32_e32 v10, 0xbfb8aa3b, v18
	v_exp_f32_e32 v10, v10
	v_fma_f32 v28, -v26, v27, 1.0
	v_fmac_f32_e32 v27, v28, v27
	v_div_scale_f32 v28, vcc, 1.0, v24, 1.0
	v_mul_f32_e32 v29, v28, v27
	v_add_f32_e32 v10, 1.0, v10
	v_fma_f32 v30, -v26, v29, v28
	v_div_scale_f32 v14, s[18:19], v10, v10, 1.0
	v_fmac_f32_e32 v29, v30, v27
	v_rcp_f32_e32 v18, v14
	v_fma_f32 v26, -v26, v29, v28
	v_div_fmas_f32 v26, v26, v27, v29
	v_div_fixup_f32 v24, v26, v24, 1.0
	v_mul_f32_e32 v24, v25, v24
	v_fma_f32 v25, -v14, v18, 1.0
	v_fmac_f32_e32 v18, v25, v18
	v_div_scale_f32 v25, vcc, 1.0, v10, 1.0
	v_mul_f32_e32 v26, v25, v18
	v_fma_f32 v27, -v14, v26, v25
	v_fmac_f32_e32 v26, v27, v18
	v_fma_f32 v14, -v14, v26, v25
	v_div_fmas_f32 v14, v14, v18, v26
	v_div_fixup_f32 v10, v14, v10, 1.0
	v_mul_f32_e32 v6, v6, v10
	v_lshlrev_b32_e32 v10, 16, v19
	v_and_b32_e32 v14, 0xffff0000, v19
	v_lshlrev_b32_e32 v19, 16, v11
	v_lshlrev_b32_e32 v18, 16, v7
	v_mul_f32_e32 v19, v23, v19
	v_fmac_f32_e32 v19, v22, v18
	v_lshlrev_b32_e32 v18, 16, v15
	v_fmac_f32_e32 v19, v5, v18
	v_mul_f32_e32 v18, v19, v10
	v_mul_f32_e32 v10, 0xbfb8aa3b, v10
	v_exp_f32_e32 v10, v10
	v_and_b32_e32 v11, 0xffff0000, v11
	v_and_b32_e32 v7, 0xffff0000, v7
	v_mul_f32_e32 v11, v23, v11
	v_add_f32_e32 v10, 1.0, v10
	v_div_scale_f32 v19, s[18:19], v10, v10, 1.0
	v_fmac_f32_e32 v11, v22, v7
	v_and_b32_e32 v7, 0xffff0000, v15
	v_cvt_pk_bf16_f32 v6, v24, v6
	v_rcp_f32_e32 v24, v19
	v_fmac_f32_e32 v11, v5, v7
	v_mul_f32_e32 v7, v11, v14
	v_mul_f32_e32 v11, 0xbfb8aa3b, v14
	v_exp_f32_e32 v11, v11
	v_fma_f32 v25, -v19, v24, 1.0
	v_fmac_f32_e32 v24, v25, v24
	v_div_scale_f32 v25, vcc, 1.0, v10, 1.0
	v_mul_f32_e32 v26, v25, v24
	v_add_f32_e32 v11, 1.0, v11
	v_fma_f32 v27, -v19, v26, v25
	v_div_scale_f32 v14, s[18:19], v11, v11, 1.0
	v_fmac_f32_e32 v26, v27, v24
	v_rcp_f32_e32 v15, v14
	v_fma_f32 v19, -v19, v26, v25
	v_div_fmas_f32 v19, v19, v24, v26
	v_div_fixup_f32 v10, v19, v10, 1.0
	v_mul_f32_e32 v10, v18, v10
	v_fma_f32 v18, -v14, v15, 1.0
	v_fmac_f32_e32 v15, v18, v15
	v_div_scale_f32 v18, vcc, 1.0, v11, 1.0
	v_mul_f32_e32 v19, v18, v15
	v_fma_f32 v24, -v14, v19, v18
	v_fmac_f32_e32 v19, v24, v15
	v_fma_f32 v14, -v14, v19, v18
	v_div_fmas_f32 v14, v14, v15, v19
	v_lshlrev_b32_e32 v15, 16, v12
	v_div_fixup_f32 v11, v14, v11, 1.0
	v_lshlrev_b32_e32 v14, 16, v8
	v_mul_f32_e32 v15, v23, v15
	v_mul_f32_e32 v7, v7, v11
	v_fmac_f32_e32 v15, v22, v14
	v_lshlrev_b32_e32 v14, 16, v16
	v_cvt_pk_bf16_f32 v7, v10, v7
	v_lshlrev_b32_e32 v10, 16, v20
	v_fmac_f32_e32 v15, v5, v14
	v_mul_f32_e32 v14, v15, v10
	v_mul_f32_e32 v10, 0xbfb8aa3b, v10
	v_exp_f32_e32 v10, v10
	v_and_b32_e32 v12, 0xffff0000, v12
	v_and_b32_e32 v8, 0xffff0000, v8
	v_mul_f32_e32 v12, v23, v12
	v_add_f32_e32 v10, 1.0, v10
	v_div_scale_f32 v15, s[18:19], v10, v10, 1.0
	v_rcp_f32_e32 v18, v15
	v_fmac_f32_e32 v12, v22, v8
	v_and_b32_e32 v8, 0xffff0000, v16
	v_and_b32_e32 v11, 0xffff0000, v20
	v_fma_f32 v19, -v15, v18, 1.0
	v_fmac_f32_e32 v12, v5, v8
	v_fmac_f32_e32 v18, v19, v18
	v_div_scale_f32 v19, vcc, 1.0, v10, 1.0
	v_mul_f32_e32 v8, v12, v11
	v_mul_f32_e32 v11, 0xbfb8aa3b, v11
	v_mul_f32_e32 v20, v19, v18
	v_exp_f32_e32 v11, v11
	v_fma_f32 v24, -v15, v20, v19
	v_fmac_f32_e32 v20, v24, v18
	v_fma_f32 v15, -v15, v20, v19
	v_div_fmas_f32 v15, v15, v18, v20
	v_add_f32_e32 v11, 1.0, v11
	v_div_fixup_f32 v10, v15, v10, 1.0
	v_div_scale_f32 v12, s[18:19], v11, v11, 1.0
	v_mul_f32_e32 v10, v14, v10
	v_rcp_f32_e32 v14, v12
	s_nop 0
	v_fma_f32 v15, -v12, v14, 1.0
	v_fmac_f32_e32 v14, v15, v14
	v_div_scale_f32 v15, vcc, 1.0, v11, 1.0
	v_mul_f32_e32 v16, v15, v14
	v_fma_f32 v18, -v12, v16, v15
	v_fmac_f32_e32 v16, v18, v14
	v_fma_f32 v12, -v12, v16, v15
	v_div_fmas_f32 v12, v12, v14, v16
	v_lshlrev_b32_e32 v14, 16, v13
	v_div_fixup_f32 v11, v12, v11, 1.0
	v_lshlrev_b32_e32 v12, 16, v9
	v_mul_f32_e32 v14, v23, v14
	v_mul_f32_e32 v8, v8, v11
	v_fmac_f32_e32 v14, v22, v12
	v_lshlrev_b32_e32 v12, 16, v17
	v_cvt_pk_bf16_f32 v8, v10, v8
	v_lshlrev_b32_e32 v10, 16, v21
	v_fmac_f32_e32 v14, v5, v12
	v_mul_f32_e32 v12, v14, v10
	v_mul_f32_e32 v10, 0xbfb8aa3b, v10
	v_exp_f32_e32 v10, v10
	v_and_b32_e32 v9, 0xffff0000, v9
	v_and_b32_e32 v11, 0xffff0000, v21
	v_add_f32_e32 v10, 1.0, v10
	v_div_scale_f32 v14, s[18:19], v10, v10, 1.0
	v_rcp_f32_e32 v15, v14
	s_nop 0
	v_fma_f32 v16, -v14, v15, 1.0
	v_fmac_f32_e32 v15, v16, v15
	v_div_scale_f32 v16, vcc, 1.0, v10, 1.0
	v_mul_f32_e32 v18, v16, v15
	v_fma_f32 v19, -v14, v18, v16
	v_fmac_f32_e32 v18, v19, v15
	v_fma_f32 v14, -v14, v18, v16
	v_div_fmas_f32 v14, v14, v15, v18
	v_div_fixup_f32 v10, v14, v10, 1.0
	v_mul_f32_e32 v10, v12, v10
	v_and_b32_e32 v12, 0xffff0000, v13
	v_mul_f32_e32 v12, v23, v12
	v_fmac_f32_e32 v12, v22, v9
	v_and_b32_e32 v9, 0xffff0000, v17
	v_fmac_f32_e32 v12, v5, v9
	v_mul_f32_e32 v9, 0xbfb8aa3b, v11
	v_exp_f32_e32 v9, v9
	v_mul_f32_e32 v5, v12, v11
	v_add_f32_e32 v9, 1.0, v9
	v_div_scale_f32 v11, s[18:19], v9, v9, 1.0
	v_rcp_f32_e32 v12, v11
	s_mov_b64 s[18:19], 0x3fffff
	v_fma_f32 v13, -v11, v12, 1.0
	v_fmac_f32_e32 v12, v13, v12
	v_div_scale_f32 v13, vcc, 1.0, v9, 1.0
	v_mul_f32_e32 v14, v13, v12
	v_fma_f32 v15, -v11, v14, v13
	v_fmac_f32_e32 v14, v15, v12
	v_fma_f32 v11, -v11, v14, v13
	v_div_fmas_f32 v11, v11, v12, v14
	v_cmp_lt_u64_e32 vcc, s[18:19], v[0:1]
	v_div_fixup_f32 v9, v11, v9, 1.0
	s_or_b64 s[92:93], vcc, s[92:93]
	v_mul_f32_e32 v5, v5, v9
	v_cvt_pk_bf16_f32 v9, v10, v5
	global_store_dwordx4 v[2:3], v[6:9], off
	s_andn2_b64 exec, exec, s[92:93]
	s_cbranch_execnz .LBB0_775
.LBB0_776:
	s_or_b64 exec, exec, s[2:3]
	v_mov_b64_e32 v[0:1], s[10:11]
	global_load_dwordx2 v[2:3], v[0:1], off sc0 sc1
	s_waitcnt vmcnt(0)
	v_mov_b32_e32 v0, s74
	ds_read_b32 v0, v0
	v_mov_b32_e32 v1, v252
	s_movk_i32 s2, 0x4000
	s_waitcnt lgkmcnt(0)
	v_readfirstlane_b32 s0, v0
	v_readfirstlane_b32 s1, v2
	s_nop 0
	v_lshl_add_u32 v0, s0, 9, v1
	v_readfirstlane_b32 s0, v3
	v_cmp_gt_i32_e32 vcc, s2, v0
	s_and_saveexec_b64 s[2:3], vcc
	s_cbranch_execz .LBB0_779
	s_lshl_b64 s[4:5], s[6:7], 3
	s_add_u32 s1, s1, s4
	s_addc_u32 s0, s0, s5
	s_add_u32 s4, s1, 0x13940000
	s_addc_u32 s5, s0, 0
	s_mov_b64 s[6:7], 0

; #define LAS __attribute__((address_space(3)))
; __device__ __forceinline__ int otid() { int t = threadIdx.x; asm volatile("" : "+v"(t)); return t; }
; __device__ __forceinline__ unsigned xb_ld(unsigned* p) { return __hip_atomic_load(p, __ATOMIC_RELAXED, __HIP_MEMORY_SCOPE_AGENT); }
; __device__ __forceinline__ unsigned xb_add(unsigned* p, unsigned v) { return __hip_atomic_fetch_add(p, v, __ATOMIC_RELAXED, __HIP_MEMORY_SCOPE_AGENT); }
; __device__ __forceinline__ void gbar(unsigned* bar, unsigned n, volatile LAS unsigned* st) {
;   asm volatile("s_waitcnt vmcnt(0)" ::: "memory");
;   __syncthreads();
;   if (otid() == 0) {
;     __builtin_amdgcn_s_waitcnt(0);
;     const unsigned x = st[0], nloc = st[1], nx = st[2];
;     const unsigned old = xb_add(&bar[XB_XSUB(x)], 1u);
;     unsigned sp = 0;
;     if (old + 1u == (n + 1u) * nloc) {
;       __builtin_amdgcn_fence(__ATOMIC_RELEASE, "agent");
;       asm volatile("s_waitcnt vmcnt(0)" ::: "memory");
;       xb_add(&bar[XB_TOP], 1u);
;       while (xb_ld(&bar[XB_TOP]) < (n + 1u) * nx) { __builtin_amdgcn_s_sleep(1); if (++sp > (1u << 24)) break; }
;       __builtin_amdgcn_fence(__ATOMIC_ACQUIRE, "agent");
;       xb_add(&bar[XB_XGEN(x)], 1u);
;       asm volatile("s_waitcnt vmcnt(0)" ::: "memory");
;     } else {
;       while (xb_ld(&bar[XB_XGEN(x)]) <= n) { __builtin_amdgcn_s_sleep(1); if (++sp > (1u << 24)) break; }
;       __builtin_amdgcn_fence(__ATOMIC_ACQUIRE, "agent");
;       asm volatile("s_waitcnt vmcnt(0)" ::: "memory");
;     }
;   }
;   __syncthreads();
; }
.LBB0_779:
	s_or_b64 exec, exec, s[2:3]
	v_mov_b64_e32 v[0:1], s[10:11]
	global_load_dwordx2 v[0:1], v[0:1], off sc0 sc1
	s_waitcnt vmcnt(0)
	s_waitcnt vmcnt(0)
	v_mov_b32_e32 v2, v252
	s_waitcnt lgkmcnt(0)
	s_barrier
	v_readfirstlane_b32 s0, v1
	v_readfirstlane_b32 s1, v0
	v_cmp_eq_u32_e32 vcc, 0, v2
	s_and_saveexec_b64 s[2:3], vcc
	s_cbranch_execz .LBB0_826
	v_readlane_b32 s6, v255, 15
	s_waitcnt vmcnt(0) expcnt(0) lgkmcnt(0)
	s_add_u32 s4, s1, 0x4cc80000
	v_mov_b32_e32 v0, s6
	ds_read_b32 v1, v0
	v_readlane_b32 s6, v255, 16
	s_addc_u32 s5, s0, 0
	s_waitcnt lgkmcnt(0)
	v_lshlrev_b32_e32 v6, 6, v1
	v_add_u32_e32 v80, 0x440, v6
	v_mov_b32_e32 v0, s6
	v_readlane_b32 s6, v255, 17
	v_lshlrev_b64 v[2:3], 2, v[80:81]
	ds_read_b32 v5, v0
	v_mov_b32_e32 v0, s6
	v_lshl_add_u64 v[2:3], s[4:5], 0, v[2:3]
	ds_read_b32 v0, v0
	global_atomic_add v2, v[2:3], v230, off sc0
	v_add_u32_e32 v1, 4, v236
	s_waitcnt lgkmcnt(0)
	v_mul_lo_u32 v3, v5, v1
	v_add_u32_e32 v80, 0x840, v6
	s_waitcnt vmcnt(0)
	v_add_u32_e32 v2, 1, v2
	v_cmp_ne_u32_e32 vcc, v2, v3
	s_and_saveexec_b64 s[6:7], vcc
	s_xor_b64 s[6:7], exec, s[6:7]
	s_cbranch_execz .LBB0_803
	v_lshlrev_b64 v[0:1], 2, v[80:81]
	v_lshl_add_u64 v[0:1], s[4:5], 0, v[0:1]
	s_mov_b32 s13, 0x1000000
	s_mov_b64 s[8:9], 0
	s_branch .LBB0_791

; __device__ __forceinline__ unsigned xb_ld(unsigned* p) { return __hip_atomic_load(p, __ATOMIC_RELAXED, __HIP_MEMORY_SCOPE_AGENT); }
; __device__ __forceinline__ void gbar(unsigned* bar, unsigned n, volatile LAS unsigned* st) {
;     ...
;       while (xb_ld(&bar[XB_XGEN(x)]) <= n) { __builtin_amdgcn_s_sleep(1); if (++sp > (1u << 24)) break; }
.LBB0_791:
	global_load_dword v2, v[0:1], off sc1
	s_or_b64 s[36:37], s[36:37], exec
	s_waitcnt vmcnt(0) lgkmcnt(0)
	v_cmp_le_u32_e32 vcc, v2, v4
	s_and_saveexec_b64 s[38:39], vcc
	s_cbranch_execz .LBB0_790
	s_cmp_lg_u32 s13, 0
	s_sleep 1
	s_cbranch_scc0 .LBB0_801
	global_load_dword v2, v[0:1], off sc1
	s_mov_b64 s[18:19], -1
	s_waitcnt vmcnt(0) lgkmcnt(0)
	v_cmp_le_u32_e32 vcc, v2, v4
	s_and_saveexec_b64 s[40:41], vcc
	s_cbranch_execz .LBB0_788
	s_sleep 1
	global_load_dword v2, v[0:1], off sc1
	s_waitcnt vmcnt(0) lgkmcnt(0)
	v_cmp_le_u32_e32 vcc, v2, v4
	s_and_saveexec_b64 s[42:43], vcc
	s_cbranch_execz .LBB0_787
	s_sleep 1
	global_load_dword v2, v[0:1], off sc1
	s_waitcnt vmcnt(0) lgkmcnt(0)
	v_cmp_le_u32_e32 vcc, v2, v4
	s_and_saveexec_b64 s[44:45], vcc
	s_cbranch_execz .LBB0_786
	s_sleep 1
	global_load_dword v2, v[0:1], off sc1
	s_waitcnt vmcnt(0) lgkmcnt(0)
	v_cmp_le_u32_e32 vcc, v2, v4
	s_and_saveexec_b64 s[46:47], vcc
	s_cbranch_execz .LBB0_785
	s_sleep 1
	global_load_dword v2, v[0:1], off sc1
	s_waitcnt vmcnt(0) lgkmcnt(0)
	v_cmp_le_u32_e32 vcc, v2, v4
	s_and_saveexec_b64 s[68:69], vcc
	s_cbranch_execz .LBB0_784
	s_sleep 1
	global_load_dword v2, v[0:1], off sc1
	s_mov_b64 s[48:49], -1
	s_waitcnt vmcnt(0) lgkmcnt(0)
	v_cmp_le_u32_e32 vcc, v2, v4
	s_and_saveexec_b64 s[18:19], vcc
	s_cbranch_execz .LBB0_783
	s_sleep 1
	global_load_dword v2, v[0:1], off sc1
	s_waitcnt vmcnt(0) lgkmcnt(0)
	v_cmp_le_u32_e32 vcc, v2, v4
	s_and_saveexec_b64 s[66:67], vcc
	s_cbranch_execz .LBB0_782
	s_add_i32 s13, s13, -8
	s_xor_b64 s[48:49], exec, -1
	s_sleep 1
	s_branch .LBB0_782

; #define LAS __attribute__((address_space(3)))
; __device__ __forceinline__ int otid() { int t = threadIdx.x; asm volatile("" : "+v"(t)); return t; }
;   __device__ __forceinline__ bool next(int i, Unit& u) const {
;     const long Ll = (long)i * G + c;
;     if (Ll >= total) return false;
;     const int L = (int)Ll;
;     int pm, pn;
;     u.pad0 = 0; u.pad1 = 0;
;     if (mode == 0) {
;       tile_order(L, nM, nN, pm, pn);
;       if (p1 == -77 && pm >= p0) ++pm;
;       u.a0 = A + (size_t)pm * a_t; u.b0 = B + (size_t)pn * b_t; u.b1 = u.b0 + b_h;
;       u.r0 = pm * 256; u.c0 = pn * 256; u.C = C;
; __device__ __forceinline__ int build_units(LAS unsigned char* lds, const Map& m) {
;   LAS Unit* ul = (LAS Unit*)(lds + STAGE_BYTES);
;   __syncthreads();
;   const int tid_ = otid();
;   if (tid_ < MAX_UNITS) { Unit u; if (m.next(tid_, u)) {
;       LAS unsigned long long* w = (LAS unsigned long long*)(ul + tid_);
;       w[0] = (unsigned long long)u.a0; w[1] = (unsigned long long)u.b0; w[2] = (unsigned long long)u.b1; w[3] = (unsigned long long)u.C;
;       w[4] = ((unsigned long long)(unsigned)u.c0 << 32) | (unsigned)u.r0; } }
;   __syncthreads();
;   const long rest = (long)m.total - m.c;
;   int n = rest > 0 ? (int)((rest + m.G - 1) / m.G) : 0;
;   return n < MAX_UNITS ? n : MAX_UNITS;
; }
.LBB0_826:
	s_or_b64 exec, exec, s[2:3]
	v_mov_b64_e32 v[0:1], s[10:11]
	s_waitcnt lgkmcnt(0)
	s_barrier
	global_load_dwordx2 v[2:3], v[0:1], off sc0 sc1
	s_waitcnt vmcnt(0) lgkmcnt(0)
	v_readfirstlane_b32 s0, v3
	v_readfirstlane_b32 s1, v2
	global_load_dwordx2 v[2:3], v[0:1], off sc0 sc1
	s_waitcnt vmcnt(0) lgkmcnt(0)
	v_readfirstlane_b32 s3, v3
	v_readfirstlane_b32 s2, v2
	global_load_dwordx2 v[2:3], v[0:1], off sc0 sc1
	s_waitcnt vmcnt(0) lgkmcnt(0)
	v_readfirstlane_b32 s9, v2
	v_mov_b32_e32 v2, s74
	ds_read_b32 v2, v2
	v_readfirstlane_b32 s8, v3
	s_waitcnt lgkmcnt(0)
	v_readfirstlane_b32 s13, v2
	global_load_dwordx2 v[2:3], v[0:1], off sc0 sc1
	s_waitcnt vmcnt(0) lgkmcnt(0)
	v_readfirstlane_b32 s29, v2
	global_load_dwordx2 v[0:1], v[0:1], off sc0 sc1
	s_waitcnt vmcnt(0)
	v_mov_b32_e32 v2, v252
	v_readfirstlane_b32 s28, v3
	s_waitcnt lgkmcnt(0)
	s_barrier
	v_readfirstlane_b32 s30, v1
	v_readfirstlane_b32 s31, v0
	v_cmp_gt_i32_e32 vcc, 40, v2
	s_and_saveexec_b64 s[4:5], vcc
	s_cbranch_execz .LBB0_833
	s_ashr_i32 s6, s13, 31
	v_mov_b32_e32 v0, s13
	v_mov_b32_e32 v1, s6
	v_mad_i64_i32 v[0:1], s[6:7], v2, s20, v[0:1]
	v_cmp_gt_i64_e32 vcc, s[70:71], v[0:1]
	s_and_b64 exec, exec, vcc
	s_cbranch_execz .LBB0_833
	v_ashrrev_i32_e32 v1, 31, v0
	v_lshrrev_b32_e32 v1, 29, v1
	v_add_u32_e32 v1, v0, v1
	v_and_b32_e32 v3, -8, v1
	v_sub_u32_e32 v3, v0, v3
	v_cmp_lt_i32_e32 vcc, -1, v3
	s_and_saveexec_b64 s[6:7], vcc
	s_xor_b64 s[6:7], exec, s[6:7]
	v_lshlrev_b32_e32 v0, 6, v3
	s_andn2_saveexec_b64 s[6:7], s[6:7]
	v_lshl_add_u32 v0, v3, 6, v3
	s_or_b64 exec, exec, s[6:7]
	v_ashrrev_i32_e32 v1, 3, v1
	v_add_u32_e32 v0, v0, v1
	v_ashrrev_i32_e32 v1, 31, v0
	v_lshrrev_b32_e32 v1, 27, v1
	v_add_u32_e32 v1, v0, v1
	v_ashrrev_i32_e32 v3, 5, v1
	v_lshlrev_b32_e32 v3, 2, v3
	v_sub_u32_e32 v4, 64, v3
	v_min_i32_e32 v4, 4, v4
	v_sub_u32_e32 v5, 0, v4
	v_max_i32_e32 v5, v4, v5
	v_cvt_f32_u32_e32 v6, v5
	v_and_b32_e32 v1, 0xffffffe0, v1
	v_sub_u32_e32 v8, 0, v5
	v_sub_u32_e32 v1, v0, v1
	v_rcp_iflag_f32_e32 v6, v6
	v_sub_u32_e32 v0, 0, v1
	v_max_i32_e32 v0, v1, v0
	v_xor_b32_e32 v7, v1, v4
	v_mul_f32_e32 v6, 0x4f7ffffe, v6
	v_cvt_u32_f32_e32 v6, v6
	v_ashrrev_i32_e32 v7, 31, v7
	v_mov_b32_e32 v80, v81
	v_mul_lo_u32 v8, v8, v6
	v_mul_hi_u32 v8, v6, v8
	v_add_u32_e32 v6, v6, v8
	v_mul_hi_u32 v6, v0, v6
	v_mul_lo_u32 v8, v6, v5
	v_sub_u32_e32 v0, v0, v8
	v_add_u32_e32 v9, 1, v6
	v_cmp_ge_u32_e32 vcc, v0, v5
	v_sub_u32_e32 v8, v0, v5
	s_nop 0
	v_cndmask_b32_e32 v6, v6, v9, vcc
	v_cndmask_b32_e32 v0, v0, v8, vcc
	v_add_u32_e32 v8, 1, v6
	v_cmp_ge_u32_e32 vcc, v0, v5
	s_nop 1
	v_cndmask_b32_e32 v0, v6, v8, vcc
	v_xor_b32_e32 v0, v0, v7
	v_sub_u32_e32 v0, v0, v7
	v_mul_lo_u32 v4, v0, v4
	v_sub_u32_e32 v1, v1, v4
	v_add_u32_e32 v6, v3, v1
	v_ashrrev_i32_e32 v1, 31, v0
	v_lshlrev_b64 v[4:5], 20, v[0:1]
	v_lshl_add_u64 v[10:11], s[2:3], 0, v[4:5]
	s_mov_b64 s[2:3], 0x5000000
	v_lshl_add_u64 v[4:5], v[10:11], 0, s[2:3]
	s_mov_b64 s[2:3], 0x5080000
	v_lshl_add_u64 v[78:79], v[10:11], 0, s[2:3]
	v_mad_u64_u32 v[2:3], s[2:3], v2, 48, v[232:233]
	v_ashrrev_i32_e32 v7, 31, v6
	s_add_u32 s2, s1, 0x40480000
	v_lshlrev_b64 v[8:9], 20, v[6:7]
	s_addc_u32 s3, s0, 0
	v_lshlrev_b32_e32 v6, 8, v6
	v_add_u32_e32 v1, 0x20000, v2
	v_lshl_add_u64 v[2:3], s[2:3], 0, v[8:9]
	v_lshlrev_b32_e32 v7, 8, v0
	ds_write_b128 v1, v[2:5]
	ds_write_b128 v1, v[78:81] offset:16
	ds_write_b64 v1, v[6:7] offset:32

; #define LAS __attribute__((address_space(3)))
; __device__ __forceinline__ int otid() { int t = threadIdx.x; asm volatile("" : "+v"(t)); return t; }
; __device__ __forceinline__ unsigned xb_ld(unsigned* p) { return __hip_atomic_load(p, __ATOMIC_RELAXED, __HIP_MEMORY_SCOPE_AGENT); }
; __device__ __forceinline__ unsigned xb_add(unsigned* p, unsigned v) { return __hip_atomic_fetch_add(p, v, __ATOMIC_RELAXED, __HIP_MEMORY_SCOPE_AGENT); }
; __device__ __forceinline__ void gbar(unsigned* bar, unsigned n, volatile LAS unsigned* st) {
;   asm volatile("s_waitcnt vmcnt(0)" ::: "memory");
;   __syncthreads();
;   if (otid() == 0) {
;     __builtin_amdgcn_s_waitcnt(0);
;     const unsigned x = st[0], nloc = st[1], nx = st[2];
;     const unsigned old = xb_add(&bar[XB_XSUB(x)], 1u);
;     unsigned sp = 0;
;     if (old + 1u == (n + 1u) * nloc) {
;       __builtin_amdgcn_fence(__ATOMIC_RELEASE, "agent");
;       asm volatile("s_waitcnt vmcnt(0)" ::: "memory");
;       xb_add(&bar[XB_TOP], 1u);
;       while (xb_ld(&bar[XB_TOP]) < (n + 1u) * nx) { __builtin_amdgcn_s_sleep(1); if (++sp > (1u << 24)) break; }
;       __builtin_amdgcn_fence(__ATOMIC_ACQUIRE, "agent");
;       xb_add(&bar[XB_XGEN(x)], 1u);
;       asm volatile("s_waitcnt vmcnt(0)" ::: "memory");
;     } else {
;       while (xb_ld(&bar[XB_XGEN(x)]) <= n) { __builtin_amdgcn_s_sleep(1); if (++sp > (1u << 24)) break; }
;       __builtin_amdgcn_fence(__ATOMIC_ACQUIRE, "agent");
;       asm volatile("s_waitcnt vmcnt(0)" ::: "memory");
;     }
;   }
;   __syncthreads();
; }
.LBB0_865:
	s_waitcnt lgkmcnt(0)
	v_mov_b64_e32 v[0:1], s[10:11]
	global_load_dwordx2 v[0:1], v[0:1], off sc0 sc1
	s_waitcnt vmcnt(0)
	s_waitcnt vmcnt(0)
	v_mov_b32_e32 v2, v252
	s_waitcnt lgkmcnt(0)
	s_barrier
	v_readfirstlane_b32 s0, v1
	v_readfirstlane_b32 s1, v0
	v_cmp_ne_u32_e32 vcc, 0, v2
	s_and_saveexec_b64 s[2:3], vcc
	s_xor_b64 s[2:3], exec, s[2:3]
	v_add_u32_e32 v159, 5, v158
	s_andn2_saveexec_b64 s[2:3], s[2:3]
	s_cbranch_execz .LBB0_916
	v_readlane_b32 s6, v255, 15
	s_waitcnt vmcnt(0) expcnt(0) lgkmcnt(0)
	s_add_u32 s4, s1, 0x4cc80000
	v_mov_b32_e32 v0, s6
	ds_read_b32 v1, v0
	v_readlane_b32 s6, v255, 16
	s_addc_u32 s5, s0, 0
	v_add_u32_e32 v159, 5, v158
	v_mov_b32_e32 v0, s6
	s_waitcnt lgkmcnt(0)
	v_lshlrev_b32_e32 v1, 6, v1
	v_add_u32_e32 v80, 0x440, v1
	v_readlane_b32 s6, v255, 17
	v_lshlrev_b64 v[2:3], 2, v[80:81]
	ds_read_b32 v4, v0
	v_mov_b32_e32 v0, s6
	v_lshl_add_u64 v[2:3], s[4:5], 0, v[2:3]
	ds_read_b32 v0, v0
	global_atomic_add v2, v[2:3], v230, off sc0
	s_waitcnt lgkmcnt(0)
	v_mul_lo_u32 v3, v4, v159
	v_add_u32_e32 v80, 0x840, v1
	s_waitcnt vmcnt(0)
	v_add_u32_e32 v2, 1, v2
	v_cmp_ne_u32_e32 vcc, v2, v3
	s_and_saveexec_b64 s[6:7], vcc
	s_xor_b64 s[6:7], exec, s[6:7]
	s_cbranch_execz .LBB0_892
	v_lshlrev_b64 v[0:1], 2, v[80:81]
	v_add_u32_e32 v2, 4, v158
	v_lshl_add_u64 v[0:1], s[4:5], 0, v[0:1]
	s_mov_b32 s13, 0x1000000
	s_mov_b64 s[8:9], 0
	s_branch .LBB0_880

; __device__ __forceinline__ unsigned xb_ld(unsigned* p) { return __hip_atomic_load(p, __ATOMIC_RELAXED, __HIP_MEMORY_SCOPE_AGENT); }
; __device__ __forceinline__ void gbar(unsigned* bar, unsigned n, volatile LAS unsigned* st) {
;     ...
;       while (xb_ld(&bar[XB_XGEN(x)]) <= n) { __builtin_amdgcn_s_sleep(1); if (++sp > (1u << 24)) break; }
.LBB0_880:
	global_load_dword v3, v[0:1], off sc1
	s_or_b64 s[36:37], s[36:37], exec
	s_waitcnt vmcnt(0) lgkmcnt(0)
	v_cmp_le_u32_e32 vcc, v3, v2
	s_and_saveexec_b64 s[38:39], vcc
	s_cbranch_execz .LBB0_879
	s_cmp_lg_u32 s13, 0
	s_sleep 1
	s_cbranch_scc0 .LBB0_890
	global_load_dword v3, v[0:1], off sc1
	s_mov_b64 s[18:19], -1
	s_waitcnt vmcnt(0) lgkmcnt(0)
	v_cmp_le_u32_e32 vcc, v3, v2
	s_and_saveexec_b64 s[40:41], vcc
	s_cbranch_execz .LBB0_877
	s_sleep 1
	global_load_dword v3, v[0:1], off sc1
	s_waitcnt vmcnt(0) lgkmcnt(0)
	v_cmp_le_u32_e32 vcc, v3, v2
	s_and_saveexec_b64 s[42:43], vcc
	s_cbranch_execz .LBB0_876
	s_sleep 1
	global_load_dword v3, v[0:1], off sc1
	s_waitcnt vmcnt(0) lgkmcnt(0)
	v_cmp_le_u32_e32 vcc, v3, v2
	s_and_saveexec_b64 s[44:45], vcc
	s_cbranch_execz .LBB0_875
	s_sleep 1
	global_load_dword v3, v[0:1], off sc1
	s_waitcnt vmcnt(0) lgkmcnt(0)
	v_cmp_le_u32_e32 vcc, v3, v2
	s_and_saveexec_b64 s[46:47], vcc
	s_cbranch_execz .LBB0_874
	s_sleep 1
	global_load_dword v3, v[0:1], off sc1
	s_waitcnt vmcnt(0) lgkmcnt(0)
	v_cmp_le_u32_e32 vcc, v3, v2
	s_and_saveexec_b64 s[68:69], vcc
	s_cbranch_execz .LBB0_873
	s_sleep 1
	global_load_dword v3, v[0:1], off sc1
	s_mov_b64 s[48:49], -1
	s_waitcnt vmcnt(0) lgkmcnt(0)
	v_cmp_le_u32_e32 vcc, v3, v2
	s_and_saveexec_b64 s[18:19], vcc
	s_cbranch_execz .LBB0_872
	s_sleep 1
	global_load_dword v3, v[0:1], off sc1
	s_waitcnt vmcnt(0) lgkmcnt(0)
	v_cmp_le_u32_e32 vcc, v3, v2
	s_and_saveexec_b64 s[66:67], vcc
	s_cbranch_execz .LBB0_871
	s_add_i32 s13, s13, -8
	s_xor_b64 s[48:49], exec, -1
	s_sleep 1
	s_branch .LBB0_871

; __device__ __forceinline__ unsigned xb_ld(unsigned* p) { return __hip_atomic_load(p, __ATOMIC_RELAXED, __HIP_MEMORY_SCOPE_AGENT); }
; __device__ __forceinline__ unsigned xb_add(unsigned* p, unsigned v) { return __hip_atomic_fetch_add(p, v, __ATOMIC_RELAXED, __HIP_MEMORY_SCOPE_AGENT); }
; __device__ __forceinline__ void gbar(unsigned* bar, unsigned n, volatile LAS unsigned* st) {
;     ...
;     if (old + 1u == (n + 1u) * nloc) {
;       __builtin_amdgcn_fence(__ATOMIC_RELEASE, "agent");
;       asm volatile("s_waitcnt vmcnt(0)" ::: "memory");
;       xb_add(&bar[XB_TOP], 1u);
;       while (xb_ld(&bar[XB_TOP]) < (n + 1u) * nx) { __builtin_amdgcn_s_sleep(1); if (++sp > (1u << 24)) break; }
.LBB0_892:
	s_andn2_saveexec_b64 s[6:7], s[6:7]
	s_cbranch_execz .LBB0_915
	v_mov_b32_e32 v1, s1
	v_add_co_u32_e32 v2, vcc, 0x4cc83000, v1
	v_mov_b32_e32 v1, s0
	buffer_wbl2 sc1
	s_waitcnt vmcnt(0)
	v_addc_co_u32_e32 v3, vcc, 0, v1, vcc
	global_atomic_add v[2:3], v230, off offset:256
	s_add_u32 s8, s1, 0x4cc83100
	s_addc_u32 s9, s0, 0
	v_mul_lo_u32 v0, v0, v159
	s_mov_b32 s0, 0x1000000
	s_mov_b64 s[36:37], 0
	s_branch .LBB0_903

; __device__ __forceinline__ unsigned xb_ld(unsigned* p) { return __hip_atomic_load(p, __ATOMIC_RELAXED, __HIP_MEMORY_SCOPE_AGENT); }
; __device__ __forceinline__ void gbar(unsigned* bar, unsigned n, volatile LAS unsigned* st) {
;     ...
;       while (xb_ld(&bar[XB_TOP]) < (n + 1u) * nx) { __builtin_amdgcn_s_sleep(1); if (++sp > (1u << 24)) break; }
.LBB0_903:
	v_mov_b64_e32 v[2:3], s[8:9]
	global_load_dword v1, v[2:3], off sc1
	s_or_b64 s[38:39], s[38:39], exec
	s_waitcnt vmcnt(0) lgkmcnt(0)
	v_cmp_lt_u32_e32 vcc, v1, v0
	s_and_saveexec_b64 s[40:41], vcc
	s_cbranch_execz .LBB0_902
	s_cmp_lg_u32 s0, 0
	s_sleep 1
	s_cbranch_scc0 .LBB0_913
	v_mov_b64_e32 v[2:3], s[8:9]
	global_load_dword v1, v[2:3], off sc1
	s_mov_b64 s[18:19], -1
	s_waitcnt vmcnt(0) lgkmcnt(0)
	v_cmp_lt_u32_e32 vcc, v1, v0
	s_and_saveexec_b64 s[42:43], vcc
	s_cbranch_execz .LBB0_900
	v_mov_b64_e32 v[2:3], s[8:9]
	s_sleep 1
	global_load_dword v1, v[2:3], off sc1
	s_waitcnt vmcnt(0) lgkmcnt(0)
	v_cmp_lt_u32_e32 vcc, v1, v0
	s_and_saveexec_b64 s[44:45], vcc
	s_cbranch_execz .LBB0_899
	v_mov_b64_e32 v[2:3], s[8:9]
	s_sleep 1
	global_load_dword v1, v[2:3], off sc1
	s_waitcnt vmcnt(0) lgkmcnt(0)
	v_cmp_lt_u32_e32 vcc, v1, v0
	s_and_saveexec_b64 s[46:47], vcc
	s_cbranch_execz .LBB0_898
	v_mov_b64_e32 v[2:3], s[8:9]
	s_sleep 1
	global_load_dword v1, v[2:3], off sc1
	s_waitcnt vmcnt(0) lgkmcnt(0)
	v_cmp_lt_u32_e32 vcc, v1, v0
	s_and_saveexec_b64 s[68:69], vcc
	s_cbranch_execz .LBB0_897
	v_mov_b64_e32 v[2:3], s[8:9]
	s_sleep 1
	global_load_dword v1, v[2:3], off sc1
	s_waitcnt vmcnt(0) lgkmcnt(0)
	v_cmp_lt_u32_e32 vcc, v1, v0
	s_and_saveexec_b64 s[92:93], vcc
	s_cbranch_execz .LBB0_896
	v_mov_b64_e32 v[2:3], s[8:9]
	s_sleep 1
	global_load_dword v1, v[2:3], off sc1
	s_mov_b64 s[48:49], -1
	s_waitcnt vmcnt(0) lgkmcnt(0)
	v_cmp_lt_u32_e32 vcc, v1, v0
	s_and_saveexec_b64 s[18:19], vcc
	s_cbranch_execz .LBB0_895
	v_mov_b64_e32 v[2:3], s[8:9]
	s_sleep 1
	global_load_dword v1, v[2:3], off sc1
	s_waitcnt vmcnt(0) lgkmcnt(0)
	v_cmp_lt_u32_e32 vcc, v1, v0
	s_and_saveexec_b64 s[66:67], vcc
	s_cbranch_execz .LBB0_894
	s_add_i32 s0, s0, -8
	s_xor_b64 s[48:49], exec, -1
	s_sleep 1
	s_branch .LBB0_894

; #define LAS __attribute__((address_space(3)))
; __device__ __forceinline__ int otid() { int t = threadIdx.x; asm volatile("" : "+v"(t)); return t; }
;   __device__ __forceinline__ bool next(int i, Unit& u) const {
;     const long Ll = (long)i * G + c;
;     if (Ll >= total) return false;
;     const int L = (int)Ll;
;     int pm, pn;
;     u.pad0 = 0; u.pad1 = 0;
;     if (mode == 0) {
;       tile_order(L, nM, nN, pm, pn);
;       if (p1 == -77 && pm >= p0) ++pm;
;       u.a0 = A + (size_t)pm * a_t; u.b0 = B + (size_t)pn * b_t; u.b1 = u.b0 + b_h;
;       u.r0 = pm * 256; u.c0 = pn * 256; u.C = C;
; __device__ __forceinline__ int build_units(LAS unsigned char* lds, const Map& m) {
;   LAS Unit* ul = (LAS Unit*)(lds + STAGE_BYTES);
;   __syncthreads();
;   const int tid_ = otid();
;   if (tid_ < MAX_UNITS) { Unit u; if (m.next(tid_, u)) {
;       LAS unsigned long long* w = (LAS unsigned long long*)(ul + tid_);
;       w[0] = (unsigned long long)u.a0; w[1] = (unsigned long long)u.b0; w[2] = (unsigned long long)u.b1; w[3] = (unsigned long long)u.C;
;       w[4] = ((unsigned long long)(unsigned)u.c0 << 32) | (unsigned)u.r0; } }
;   __syncthreads();
;   const long rest = (long)m.total - m.c;
;   int n = rest > 0 ? (int)((rest + m.G - 1) / m.G) : 0;
;   return n < MAX_UNITS ? n : MAX_UNITS;
; }
.LBB0_916:
	s_or_b64 exec, exec, s[2:3]
	v_mov_b64_e32 v[0:1], s[10:11]
	s_waitcnt lgkmcnt(0)
	s_barrier
	global_load_dwordx2 v[2:3], v[0:1], off sc0 sc1
	s_waitcnt vmcnt(0) lgkmcnt(0)
	v_readfirstlane_b32 s0, v3
	v_readfirstlane_b32 s8, v2
	global_load_dwordx2 v[2:3], v[0:1], off sc0 sc1
	s_waitcnt vmcnt(0) lgkmcnt(0)
	v_readfirstlane_b32 s2, v2
	global_load_dwordx2 v[0:1], v[0:1], off sc0 sc1
	s_waitcnt vmcnt(0)
	v_mov_b32_e32 v2, v252
	v_readfirstlane_b32 s3, v3
	s_waitcnt lgkmcnt(0)
	v_readfirstlane_b32 s13, v0
	v_mov_b32_e32 v0, s74
	ds_read_b32 v0, v0
	v_readfirstlane_b32 s9, v1
	s_waitcnt lgkmcnt(0)
	s_barrier
	v_readfirstlane_b32 s1, v0
	s_nop 0
	v_cmp_gt_i32_e32 vcc, 40, v2
	s_and_saveexec_b64 s[4:5], vcc
	s_cbranch_execz .LBB0_923
	s_ashr_i32 s6, s1, 31
	v_mov_b32_e32 v0, s1
	v_mov_b32_e32 v1, s6
	v_mad_i64_i32 v[0:1], s[6:7], v2, s20, v[0:1]
	v_cmp_gt_i64_e32 vcc, s[70:71], v[0:1]
	s_and_b64 exec, exec, vcc
	s_cbranch_execz .LBB0_923
	v_ashrrev_i32_e32 v1, 31, v0
	v_lshrrev_b32_e32 v1, 29, v1
	v_add_u32_e32 v1, v0, v1
	v_and_b32_e32 v3, -8, v1
	v_sub_u32_e32 v3, v0, v3
	v_cmp_lt_i32_e32 vcc, -1, v3
	s_and_saveexec_b64 s[6:7], vcc
	s_xor_b64 s[6:7], exec, s[6:7]
	v_lshlrev_b32_e32 v0, 6, v3
	s_andn2_saveexec_b64 s[6:7], s[6:7]
	v_lshl_add_u32 v0, v3, 6, v3
	s_or_b64 exec, exec, s[6:7]
	v_ashrrev_i32_e32 v1, 3, v1
	v_add_u32_e32 v0, v0, v1
	v_ashrrev_i32_e32 v1, 31, v0
	v_lshrrev_b32_e32 v1, 27, v1
	v_add_u32_e32 v1, v0, v1
	v_ashrrev_i32_e32 v3, 5, v1
	v_lshlrev_b32_e32 v3, 2, v3
	v_sub_u32_e32 v4, 64, v3
	v_min_i32_e32 v4, 4, v4
	v_sub_u32_e32 v5, 0, v4
	v_max_i32_e32 v5, v4, v5
	v_cvt_f32_u32_e32 v6, v5
	v_and_b32_e32 v1, 0xffffffe0, v1
	v_sub_u32_e32 v8, 0, v5
	v_sub_u32_e32 v0, v0, v1
	v_rcp_iflag_f32_e32 v6, v6
	v_sub_u32_e32 v1, 0, v0
	v_max_i32_e32 v1, v0, v1
	v_xor_b32_e32 v7, v0, v4
	v_mul_f32_e32 v6, 0x4f7ffffe, v6
	v_cvt_u32_f32_e32 v6, v6
	v_ashrrev_i32_e32 v7, 31, v7
	v_mul_lo_u32 v8, v8, v6
	v_mul_hi_u32 v8, v6, v8
	v_add_u32_e32 v6, v6, v8
	v_mul_hi_u32 v6, v1, v6
	v_mul_lo_u32 v8, v6, v5
	v_sub_u32_e32 v1, v1, v8
	v_add_u32_e32 v9, 1, v6
	v_cmp_ge_u32_e32 vcc, v1, v5
	v_sub_u32_e32 v8, v1, v5
	s_nop 0
	v_cndmask_b32_e32 v6, v6, v9, vcc
	v_cndmask_b32_e32 v1, v1, v8, vcc
	v_add_u32_e32 v8, 1, v6
	v_cmp_ge_u32_e32 vcc, v1, v5
	s_nop 1
	v_cndmask_b32_e32 v1, v6, v8, vcc
	v_xor_b32_e32 v1, v1, v7
	v_sub_u32_e32 v6, v1, v7
	v_mul_lo_u32 v1, v6, v4
	v_sub_u32_e32 v0, v0, v1
	v_ashrrev_i32_e32 v7, 31, v6
	v_add_u32_e32 v8, v3, v0
	v_lshlrev_b64 v[0:1], 17, v[6:7]
	v_lshl_add_u64 v[0:1], s[2:3], 0, v[0:1]
	s_mov_b64 s[2:3], 0x6800000
	v_lshl_add_u64 v[4:5], v[0:1], 0, s[2:3]
	s_mov_b64 s[2:3], 0x6810000
	v_lshl_add_u64 v[0:1], v[0:1], 0, s[2:3]
	v_mad_u64_u32 v[2:3], s[2:3], v2, 48, v[232:233]
	s_add_u32 s2, s8, 0x13980000
	v_ashrrev_i32_e32 v9, 31, v8
	s_addc_u32 s3, s0, 0
	v_lshlrev_b64 v[10:11], 17, v[8:9]
	s_add_u32 s0, s13, 0x14180000
	v_add_u32_e32 v7, 0x20000, v2
	v_lshl_add_u64 v[2:3], s[2:3], 0, v[10:11]
	s_addc_u32 s2, s9, 0
	v_lshlrev_b32_e32 v8, 8, v8
	ds_write_b128 v7, v[2:5]
	v_mov_b32_e32 v2, s0
	v_mov_b32_e32 v3, s2
	v_lshlrev_b32_e32 v9, 8, v6
	ds_write_b128 v7, v[0:3] offset:16
	ds_write_b64 v7, v[8:9] offset:32

; #define LAS __attribute__((address_space(3)))
; #define G_STAGE(bufoff, gbase, voff) do { _Pragma("unroll") for (int _i = 0; _i < 2; ++_i) { unsigned _vo = (voff)[_i]; asm volatile("" : "+v"(_vo));   \
;     __builtin_amdgcn_global_load_lds((const unsigned*)((const char*)(gbase) + _vo), (LAS unsigned*)(lds + (bufoff) + ldsw + _i * 8192), 16, 0, 0); } } while (0)
; #define G_LDA(dst, b, h) do { _Pragma("unroll") for (int m = 0; m < 4; ++m) _Pragma("unroll") for (int k = 0; k < 2; ++k) dst[m][k] = *(const LAS bf16x8*)(lds + G_SA(b, h) + aoff + m * 2048 + k * 1024); } while (0)
; #define G_LDB(dst, b, h) do { _Pragma("unroll") for (int n = 0; n < 2; ++n) _Pragma("unroll") for (int k = 0; k < 2; ++k) dst[n][k] = *(const LAS bf16x8*)(lds + G_SB(b, h) + boff + n * 2048 + k * 1024); } while (0)
; #define G_WAIT_L(n) asm volatile("s_waitcnt lgkmcnt(" #n ")" ::: "memory")
; __device__ __forceinline__ void load_unit(LAS unsigned char* lds, int i, Unit& u) {
;   const LAS unsigned* w = (const LAS unsigned*)(lds + STAGE_BYTES) + i * 12;
;   unsigned v[10];
; #pragma unroll
;   for (int k = 0; k < 10; ++k) v[k] = __builtin_amdgcn_readfirstlane(w[k]);
;   u.a0 = (const char*)(((unsigned long long)v[1] << 32) | v[0]); u.b0 = (const char*)(((unsigned long long)v[3] << 32) | v[2]);
;   u.b1 = (const char*)(((unsigned long long)v[5] << 32) | v[4]); u.C = (char*)(((unsigned long long)v[7] << 32) | v[6]);
;   u.r0 = (int)v[8]; u.c0 = (int)v[9]; u.pad0 = 0; u.pad1 = 0;
; }
; template <class Epi>
; __device__ __forceinline__ void gemm_phase(LAS unsigned char* lds, const int K, const unsigned lda_b, const unsigned ldb_b, const Map& M, const Epi& E) {
;     ...
;   for (;;) {
;     const bool has_next = (ui + 1 < nunits);
;     load_unit(lds, has_next ? ui + 1 : ui, nxt);
;     if (Epi::PERM) nxt.b1 = nxt.b0 + (size_t)32 * ldb_b;
;     for (int t = 0; t < nt; t += 2) {
;       const bool last = (t == nt - 2);
;       const char* a1h1 = cur.a0 + a_h + (size_t)(t + 1) * kstep;
;       const char* a2h0 = last ? nxt.a0 : cur.a0 + (size_t)(t + 2) * kstep; const char* a2h1 = a2h0 + a_h;
;       const char* b2h0 = last ? nxt.b0 : cur.b0 + (size_t)(t + 2) * kstep; const char* b2h1 = last ? nxt.b1 : cur.b1 + (size_t)(t + 2) * kstep;
;       G_LDB(B0, 0, 0); G_SCHED; G_LDA(At, 0, 0); G_STAGE(G_SA(1, 1), a1h1, voffA);
;       G_WAIT_L(8); G_BAR; G_WAIT_L(0); G_MMA(0, 0, At, B0); G_BAR; G_SCHED;
.LBB0_933:
	s_mov_b64 s[42:43], s[2:3]
	s_add_i32 s2, s49, -1
	s_cmp_lt_i32 s49, s0
	s_cselect_b32 s2, s49, s2
	s_mul_i32 s2, s2, 48
	s_add_i32 s2, s2, 0
	s_add_i32 s2, s2, 0x20000
	v_mov_b32_e32 v4, s2
	ds_read_b128 v[0:3], v4
	s_waitcnt lgkmcnt(0)
	v_readfirstlane_b32 s8, v2
	v_readfirstlane_b32 s9, v3
	s_add_u32 s2, s8, 0x4000
	s_addc_u32 s3, s9, 0
	s_add_i32 s30, 0, 0x10000
	v_add_u32_e32 v83, s30, v89
	v_readfirstlane_b32 s6, v0
	v_readfirstlane_b32 s7, v1
	ds_read2_b64 v[0:3], v4 offset0:3 offset1:4
	ds_read_b128 v[4:7], v83
	ds_read_b128 v[8:11], v83 offset:1024
	ds_read_b128 v[12:15], v83 offset:2048
	ds_read_b128 v[16:19], v83 offset:3072
	s_add_u32 s34, s38, 0x10080
	s_addc_u32 s35, s39, 0
	s_waitcnt lgkmcnt(0)
	v_readfirstlane_b32 s36, v0
	v_readfirstlane_b32 s37, v1
	s_add_u32 s44, s38, 0x10100
	s_addc_u32 s45, s39, 0
	v_mov_b32_e32 v0, v84
	s_add_i32 s31, s17, 0xc000
	ds_read_b128 v[20:23], v97
	ds_read_b128 v[24:27], v97 offset:1024
	ds_read_b128 v[28:31], v97 offset:2048
	ds_read_b128 v[32:35], v97 offset:3072
	ds_read_b128 v[36:39], v97 offset:4096
	ds_read_b128 v[40:43], v97 offset:5120
	ds_read_b128 v[44:47], v97 offset:6144
	ds_read_b128 v[48:51], v97 offset:7168
	s_mov_b32 m0, s31
	s_add_i32 s28, s17, 0xe000
	global_load_lds_dwordx4 v0, s[34:35]
	v_mov_b32_e32 v0, v86
	s_mov_b32 m0, s28
	s_nop 0
	global_load_lds_dwordx4 v0, s[34:35]
	s_waitcnt lgkmcnt(8)
	s_barrier
	s_waitcnt lgkmcnt(0)
	s_setprio 1
	s_waitcnt lgkmcnt(0)
	v_mfma_f32_16x16x32_bf16 v[52:55], v[4:7], v[20:23], 0
	v_mfma_f32_16x16x32_bf16 v[56:59], v[12:15], v[20:23], 0
	v_mfma_f32_16x16x32_bf16 v[60:63], v[4:7], v[28:31], 0
	v_mfma_f32_16x16x32_bf16 v[64:67], v[12:15], v[28:31], 0
	v_mfma_f32_16x16x32_bf16 v[68:71], v[4:7], v[36:39], 0
	v_mfma_f32_16x16x32_bf16 v[72:75], v[12:15], v[36:39], 0
	v_mfma_f32_16x16x32_bf16 v[76:79], v[4:7], v[44:47], 0
	v_mfma_f32_16x16x32_bf16 v[98:101], v[12:15], v[44:47], 0
	v_mfma_f32_16x16x32_bf16 v[52:55], v[8:11], v[24:27], v[52:55]
	v_mfma_f32_16x16x32_bf16 v[56:59], v[16:19], v[24:27], v[56:59]
	v_mfma_f32_16x16x32_bf16 v[60:63], v[8:11], v[32:35], v[60:63]
	v_mfma_f32_16x16x32_bf16 v[64:67], v[16:19], v[32:35], v[64:67]
	v_mfma_f32_16x16x32_bf16 v[68:71], v[8:11], v[40:43], v[68:71]
	v_mfma_f32_16x16x32_bf16 v[72:75], v[16:19], v[40:43], v[72:75]
	v_mfma_f32_16x16x32_bf16 v[76:79], v[8:11], v[48:51], v[76:79]
	v_mfma_f32_16x16x32_bf16 v[98:101], v[16:19], v[48:51], v[98:101]
	s_setprio 0
	s_barrier
	s_add_i32 s34, 0, 0x14000
	v_add_u32_e32 v181, s34, v89
	v_mov_b32_e32 v80, v85
	ds_read_b128 v[102:105], v181
	ds_read_b128 v[106:109], v181 offset:1024
	ds_read_b128 v[110:113], v181 offset:2048
	ds_read_b128 v[114:117], v181 offset:3072
	s_add_i32 s30, s30, s13
	v_lshl_add_u64 v[0:1], s[40:41], 0, v[80:81]
	v_lshl_add_u64 v[0:1], v[0:1], 0, s[54:55]
	s_mov_b32 m0, s30
	v_mov_b32_e32 v80, v87
	global_load_lds_dwordx4 v[0:1], off
	s_add_i32 s29, s30, 0x2000
	v_lshl_add_u64 v[0:1], s[40:41], 0, v[80:81]
	v_lshl_add_u64 v[0:1], v[0:1], 0, s[54:55]
	s_mov_b32 m0, s29
	s_nop 0
	global_load_lds_dwordx4 v[0:1], off
	s_barrier
	s_waitcnt lgkmcnt(0)
	s_setprio 1
	s_waitcnt lgkmcnt(0)
	v_mfma_f32_16x16x32_bf16 v[118:121], v[102:105], v[20:23], 0
	v_mfma_f32_16x16x32_bf16 v[20:23], v[110:113], v[20:23], 0
	v_mfma_f32_16x16x32_bf16 v[118:121], v[106:109], v[24:27], v[118:121]
	v_mfma_f32_16x16x32_bf16 v[20:23], v[114:117], v[24:27], v[20:23]
	v_mfma_f32_16x16x32_bf16 v[24:27], v[102:105], v[28:31], 0
	v_mfma_f32_16x16x32_bf16 v[28:31], v[110:113], v[28:31], 0
	v_mfma_f32_16x16x32_bf16 v[24:27], v[106:109], v[32:35], v[24:27]
	v_mfma_f32_16x16x32_bf16 v[28:31], v[114:117], v[32:35], v[28:31]
	v_mfma_f32_16x16x32_bf16 v[32:35], v[102:105], v[36:39], 0
	v_mfma_f32_16x16x32_bf16 v[36:39], v[110:113], v[36:39], 0
	v_mfma_f32_16x16x32_bf16 v[32:35], v[106:109], v[40:43], v[32:35]
	v_mfma_f32_16x16x32_bf16 v[36:39], v[114:117], v[40:43], v[36:39]
	v_mfma_f32_16x16x32_bf16 v[40:43], v[102:105], v[44:47], 0
	v_mfma_f32_16x16x32_bf16 v[44:47], v[110:113], v[44:47], 0
	v_mfma_f32_16x16x32_bf16 v[40:43], v[106:109], v[48:51], v[40:43]
	v_mfma_f32_16x16x32_bf16 v[44:47], v[114:117], v[48:51], v[44:47]
	s_setprio 0
	v_mov_b32_e32 v80, v84
	s_barrier
	ds_read_b128 v[48:51], v97 offset:16384
	ds_read_b128 v[122:125], v97 offset:17408
	ds_read_b128 v[126:129], v97 offset:18432
	ds_read_b128 v[130:133], v97 offset:19456
	ds_read_b128 v[134:137], v97 offset:20480
	ds_read_b128 v[138:141], v97 offset:21504
	ds_read_b128 v[142:145], v97 offset:22528
	ds_read_b128 v[146:149], v97 offset:23552
	s_mov_b32 m0, s17
	v_lshl_add_u64 v[0:1], s[38:39], 0, v[80:81]
	v_lshl_add_u64 v[0:1], v[0:1], 0, s[54:55]
	v_mov_b32_e32 v80, v86
	global_load_lds_dwordx4 v[0:1], off
	s_mov_b32 m0, s46
	v_lshl_add_u64 v[0:1], s[38:39], 0, v[80:81]
	v_lshl_add_u64 v[0:1], v[0:1], 0, s[54:55]
	global_load_lds_dwordx4 v[0:1], off
	s_barrier
	s_waitcnt lgkmcnt(0)
	s_setprio 1
	s_waitcnt lgkmcnt(0)
	v_mfma_f32_16x16x32_bf16 v[150:153], v[4:7], v[48:51], 0
	v_mfma_f32_16x16x32_bf16 v[160:163], v[4:7], v[126:129], 0
	v_mfma_f32_16x16x32_bf16 v[168:171], v[4:7], v[134:137], 0
	v_mfma_f32_16x16x32_bf16 v[4:7], v[4:7], v[142:145], 0
	v_mfma_f32_16x16x32_bf16 v[150:153], v[8:11], v[122:125], v[150:153]
	v_mfma_f32_16x16x32_bf16 v[154:157], v[12:15], v[48:51], 0
	v_mfma_f32_16x16x32_bf16 v[160:163], v[8:11], v[130:133], v[160:163]
	v_mfma_f32_16x16x32_bf16 v[164:167], v[12:15], v[126:129], 0
	v_mfma_f32_16x16x32_bf16 v[168:171], v[8:11], v[138:141], v[168:171]
	v_mfma_f32_16x16x32_bf16 v[172:175], v[12:15], v[134:137], 0
	v_mfma_f32_16x16x32_bf16 v[4:7], v[8:11], v[146:149], v[4:7]
	v_mfma_f32_16x16x32_bf16 v[8:11], v[12:15], v[142:145], 0
	v_mfma_f32_16x16x32_bf16 v[154:157], v[16:19], v[122:125], v[154:157]
	v_mfma_f32_16x16x32_bf16 v[164:167], v[16:19], v[130:133], v[164:167]
	v_mfma_f32_16x16x32_bf16 v[172:175], v[16:19], v[138:141], v[172:175]
	v_mfma_f32_16x16x32_bf16 v[8:11], v[16:19], v[146:149], v[8:11]
	s_setprio 0
	s_barrier
; #define G_STAGE(bufoff, gbase, voff) do { _Pragma("unroll") for (int _i = 0; _i < 2; ++_i) { unsigned _vo = (voff)[_i]; asm volatile("" : "+v"(_vo));   \
;     __builtin_amdgcn_global_load_lds((const unsigned*)((const char*)(gbase) + _vo), (LAS unsigned*)(lds + (bufoff) + ldsw + _i * 8192), 16, 0, 0); } } while (0)
; #define G_LDA(dst, b, h) do { _Pragma("unroll") for (int m = 0; m < 4; ++m) _Pragma("unroll") for (int k = 0; k < 2; ++k) dst[m][k] = *(const LAS bf16x8*)(lds + G_SA(b, h) + aoff + m * 2048 + k * 1024); } while (0)
; #define G_LDB(dst, b, h) do { _Pragma("unroll") for (int n = 0; n < 2; ++n) _Pragma("unroll") for (int k = 0; k < 2; ++k) dst[n][k] = *(const LAS bf16x8*)(lds + G_SB(b, h) + boff + n * 2048 + k * 1024); } while (0)
; #define G_MMA(ai, bj, At, Bt) do { __builtin_amdgcn_s_setprio(1); _Pragma("unroll") for (int m = 0; m < 4; ++m) _Pragma("unroll") for (int n = 0; n < 2; ++n) _Pragma("unroll") for (int k = 0; k < 2; ++k) \
;     acc[ai][bj][m][n] = __builtin_amdgcn_mfma_f32_16x16x32_bf16(Bt[n][k], At[m][k], acc[ai][bj][m][n], 0, 0, 0); __builtin_amdgcn_s_setprio(0); } while (0)
; #define G_WAIT_V(n) asm volatile("s_waitcnt vmcnt(" #n ")" ::: "memory")
; #define G_WAIT_L(n) asm volatile("s_waitcnt lgkmcnt(" #n ")" ::: "memory")
; #define G_BAR __builtin_amdgcn_s_barrier()
; #define G_SCHED __builtin_amdgcn_sched_barrier(0)
; template <class Epi>
; __device__ __forceinline__ void gemm_phase(LAS unsigned char* lds, const int K, const unsigned lda_b, const unsigned ldb_b, const Map& M, const Epi& E) {
;     ...
;       G_LDB(B1, 0, 1); G_STAGE(G_SB(0, 0), b2h0, voffB);
;       G_BAR; G_WAIT_L(0); G_MMA(0, 1, At, B1); G_BAR;
;       G_LDA(At, 0, 1); G_STAGE(G_SA(0, 0), a2h0, voffA);
;       G_BAR; G_WAIT_L(0); G_MMA(1, 0, At, B0); G_BAR; G_SCHED;
;       G_STAGE(G_SB(0, 1), b2h1, voffB);
;       G_WAIT_V(6); G_BAR; G_MMA(1, 1, At, B1); G_BAR;
;       G_LDB(B0, 1, 0); G_SCHED; G_LDA(At, 1, 0); G_STAGE(G_SA(0, 1), a2h1, voffA);
;       G_WAIT_L(8); G_BAR; G_WAIT_L(0); G_MMA(0, 0, At, B0); G_BAR; G_SCHED;
	v_mov_b32_e32 v80, v85
	s_add_i32 s34, s34, s13
	v_lshl_add_u64 v[0:1], s[42:43], 0, v[80:81]
	v_lshl_add_u64 v[0:1], v[0:1], 0, s[54:55]
	s_mov_b32 m0, s34
	v_mov_b32_e32 v80, v87
	global_load_lds_dwordx4 v[0:1], off
	s_add_i32 s35, s34, 0x2000
	v_lshl_add_u64 v[0:1], s[42:43], 0, v[80:81]
	v_lshl_add_u64 v[0:1], v[0:1], 0, s[54:55]
	s_mov_b32 m0, s35
	s_nop 0
	global_load_lds_dwordx4 v[0:1], off
	s_waitcnt vmcnt(6)
	s_barrier
	s_setprio 1
	v_mfma_f32_16x16x32_bf16 v[12:15], v[102:105], v[48:51], 0
	v_mfma_f32_16x16x32_bf16 v[16:19], v[110:113], v[48:51], 0
	v_mfma_f32_16x16x32_bf16 v[12:15], v[106:109], v[122:125], v[12:15]
	v_mfma_f32_16x16x32_bf16 v[16:19], v[114:117], v[122:125], v[16:19]
	v_mfma_f32_16x16x32_bf16 v[48:51], v[102:105], v[126:129], 0
	v_mfma_f32_16x16x32_bf16 v[122:125], v[110:113], v[126:129], 0
	v_mfma_f32_16x16x32_bf16 v[126:129], v[102:105], v[134:137], 0
	v_mfma_f32_16x16x32_bf16 v[102:105], v[102:105], v[142:145], 0
	v_mfma_f32_16x16x32_bf16 v[48:51], v[106:109], v[130:133], v[48:51]
	v_mfma_f32_16x16x32_bf16 v[122:125], v[114:117], v[130:133], v[122:125]
	v_mfma_f32_16x16x32_bf16 v[126:129], v[106:109], v[138:141], v[126:129]
	v_mfma_f32_16x16x32_bf16 v[130:133], v[110:113], v[134:137], 0
	v_mfma_f32_16x16x32_bf16 v[102:105], v[106:109], v[146:149], v[102:105]
	v_mfma_f32_16x16x32_bf16 v[106:109], v[110:113], v[142:145], 0
	v_mfma_f32_16x16x32_bf16 v[130:133], v[114:117], v[138:141], v[130:133]
	v_mfma_f32_16x16x32_bf16 v[106:109], v[114:117], v[146:149], v[106:109]
	s_setprio 0
	s_add_i32 s22, 0, 0x18000
	v_add_u32_e32 v183, s22, v89
	s_barrier
	ds_read_b128 v[110:113], v183
	ds_read_b128 v[114:117], v183 offset:1024
	ds_read_b128 v[134:137], v183 offset:2048
	ds_read_b128 v[138:141], v183 offset:3072
	v_mov_b32_e32 v0, v84
	s_mov_b32 m0, s47
	ds_read_b128 v[142:145], v97 offset:32768
	ds_read_b128 v[146:149], v97 offset:33792
	ds_read_b128 v[176:179], v97 offset:34816
	ds_read_b128 v[184:187], v97 offset:35840
	ds_read_b128 v[190:193], v97 offset:36864
	ds_read_b128 v[194:197], v97 offset:37888
	ds_read_b128 v[198:201], v97 offset:38912
	ds_read_b128 v[202:205], v97 offset:39936
	s_nop 0
	global_load_lds_dwordx4 v0, s[44:45]
	v_mov_b32_e32 v0, v86
	s_mov_b32 m0, s48
	s_nop 0
	global_load_lds_dwordx4 v0, s[44:45]
	s_waitcnt lgkmcnt(8)
	s_barrier
	s_waitcnt lgkmcnt(0)
	s_setprio 1
	s_waitcnt lgkmcnt(0)
	v_mfma_f32_16x16x32_bf16 v[52:55], v[110:113], v[142:145], v[52:55]
	v_mfma_f32_16x16x32_bf16 v[56:59], v[134:137], v[142:145], v[56:59]
	v_mfma_f32_16x16x32_bf16 v[60:63], v[110:113], v[176:179], v[60:63]
	v_mfma_f32_16x16x32_bf16 v[64:67], v[134:137], v[176:179], v[64:67]
	v_mfma_f32_16x16x32_bf16 v[68:71], v[110:113], v[190:193], v[68:71]
	v_mfma_f32_16x16x32_bf16 v[72:75], v[134:137], v[190:193], v[72:75]
	v_mfma_f32_16x16x32_bf16 v[76:79], v[110:113], v[198:201], v[76:79]
	v_mfma_f32_16x16x32_bf16 v[98:101], v[134:137], v[198:201], v[98:101]
	v_mfma_f32_16x16x32_bf16 v[52:55], v[114:117], v[146:149], v[52:55]
	v_mfma_f32_16x16x32_bf16 v[56:59], v[138:141], v[146:149], v[56:59]
	v_mfma_f32_16x16x32_bf16 v[60:63], v[114:117], v[184:187], v[60:63]
	v_mfma_f32_16x16x32_bf16 v[64:67], v[138:141], v[184:187], v[64:67]
	v_mfma_f32_16x16x32_bf16 v[68:71], v[114:117], v[194:197], v[68:71]
	v_mfma_f32_16x16x32_bf16 v[72:75], v[138:141], v[194:197], v[72:75]
	v_mfma_f32_16x16x32_bf16 v[76:79], v[114:117], v[202:205], v[76:79]
	v_mfma_f32_16x16x32_bf16 v[98:101], v[138:141], v[202:205], v[98:101]
	s_setprio 0
	s_barrier
	s_add_i32 s44, 0, 0x1c000
	v_add_u32_e32 v188, s44, v89
	v_mov_b32_e32 v80, v85
	ds_read_b128 v[206:209], v188
	ds_read_b128 v[210:213], v188 offset:1024
	ds_read_b128 v[214:217], v188 offset:2048
	ds_read_b128 v[218:221], v188 offset:3072
	s_add_i32 s45, s22, s13
	v_lshl_add_u64 v[0:1], s[40:41], 0, v[80:81]
	v_lshl_add_u64 v[0:1], v[0:1], 0, s[56:57]
	s_mov_b32 m0, s45
	v_mov_b32_e32 v80, v87
	global_load_lds_dwordx4 v[0:1], off
	s_nop 0
	v_lshl_add_u64 v[0:1], s[40:41], 0, v[80:81]
	s_add_i32 s40, s45, 0x2000
	v_lshl_add_u64 v[0:1], v[0:1], 0, s[56:57]
	s_mov_b32 m0, s40
	s_nop 0
	global_load_lds_dwordx4 v[0:1], off
	s_barrier
	s_waitcnt lgkmcnt(0)
	s_setprio 1
	s_waitcnt lgkmcnt(0)
	v_mfma_f32_16x16x32_bf16 v[118:121], v[206:209], v[142:145], v[118:121]
	v_mfma_f32_16x16x32_bf16 v[20:23], v[214:217], v[142:145], v[20:23]
	v_mfma_f32_16x16x32_bf16 v[24:27], v[206:209], v[176:179], v[24:27]
	v_mfma_f32_16x16x32_bf16 v[28:31], v[214:217], v[176:179], v[28:31]
	v_mfma_f32_16x16x32_bf16 v[32:35], v[206:209], v[190:193], v[32:35]
	v_mfma_f32_16x16x32_bf16 v[36:39], v[214:217], v[190:193], v[36:39]
	v_mfma_f32_16x16x32_bf16 v[40:43], v[206:209], v[198:201], v[40:43]
	v_mfma_f32_16x16x32_bf16 v[44:47], v[214:217], v[198:201], v[44:47]
	v_mfma_f32_16x16x32_bf16 v[118:121], v[210:213], v[146:149], v[118:121]
	v_mfma_f32_16x16x32_bf16 v[20:23], v[218:221], v[146:149], v[20:23]
	v_mfma_f32_16x16x32_bf16 v[24:27], v[210:213], v[184:187], v[24:27]
	v_mfma_f32_16x16x32_bf16 v[28:31], v[218:221], v[184:187], v[28:31]
	v_mfma_f32_16x16x32_bf16 v[32:35], v[210:213], v[194:197], v[32:35]
	v_mfma_f32_16x16x32_bf16 v[36:39], v[218:221], v[194:197], v[36:39]
	v_mfma_f32_16x16x32_bf16 v[40:43], v[210:213], v[202:205], v[40:43]
	v_mfma_f32_16x16x32_bf16 v[44:47], v[218:221], v[202:205], v[44:47]
	s_setprio 0
	v_mov_b32_e32 v80, v84
	s_barrier
; #define G_STAGE(bufoff, gbase, voff) do { _Pragma("unroll") for (int _i = 0; _i < 2; ++_i) { unsigned _vo = (voff)[_i]; asm volatile("" : "+v"(_vo));   \
;     __builtin_amdgcn_global_load_lds((const unsigned*)((const char*)(gbase) + _vo), (LAS unsigned*)(lds + (bufoff) + ldsw + _i * 8192), 16, 0, 0); } } while (0)
; #define G_LDA(dst, b, h) do { _Pragma("unroll") for (int m = 0; m < 4; ++m) _Pragma("unroll") for (int k = 0; k < 2; ++k) dst[m][k] = *(const LAS bf16x8*)(lds + G_SA(b, h) + aoff + m * 2048 + k * 1024); } while (0)
; #define G_LDB(dst, b, h) do { _Pragma("unroll") for (int n = 0; n < 2; ++n) _Pragma("unroll") for (int k = 0; k < 2; ++k) dst[n][k] = *(const LAS bf16x8*)(lds + G_SB(b, h) + boff + n * 2048 + k * 1024); } while (0)
; #define G_MMA(ai, bj, At, Bt) do { __builtin_amdgcn_s_setprio(1); _Pragma("unroll") for (int m = 0; m < 4; ++m) _Pragma("unroll") for (int n = 0; n < 2; ++n) _Pragma("unroll") for (int k = 0; k < 2; ++k) \
;     acc[ai][bj][m][n] = __builtin_amdgcn_mfma_f32_16x16x32_bf16(Bt[n][k], At[m][k], acc[ai][bj][m][n], 0, 0, 0); __builtin_amdgcn_s_setprio(0); } while (0)
; #define G_WAIT_V(n) asm volatile("s_waitcnt vmcnt(" #n ")" ::: "memory")
; #define G_WAIT_L(n) asm volatile("s_waitcnt lgkmcnt(" #n ")" ::: "memory")
; #define G_BAR __builtin_amdgcn_s_barrier()
; #define G_SCHED __builtin_amdgcn_sched_barrier(0)
; template <class Epi>
; __device__ __forceinline__ void gemm_phase(LAS unsigned char* lds, const int K, const unsigned lda_b, const unsigned ldb_b, const Map& M, const Epi& E) {
;     ...
;       G_WAIT_L(8); G_BAR; G_WAIT_L(0); G_MMA(0, 0, At, B0); G_BAR; G_SCHED;
;       G_LDB(B1, 1, 1); G_STAGE(G_SB(1, 0), b2h0 + kstep, voffB);
;       G_BAR; G_WAIT_L(0); G_MMA(0, 1, At, B1); G_BAR;
;       G_LDA(At, 1, 1); G_STAGE(G_SA(1, 0), a2h0 + kstep, voffA);
;       G_BAR; G_WAIT_L(0); G_MMA(1, 0, At, B0); G_BAR; G_SCHED;
;       G_STAGE(G_SB(1, 1), b2h1 + kstep, voffB);
;       G_WAIT_V(6); G_BAR; G_MMA(1, 1, At, B1); G_BAR;
	ds_read_b128 v[142:145], v97 offset:49152
	ds_read_b128 v[146:149], v97 offset:50176
	ds_read_b128 v[176:179], v97 offset:51200
	ds_read_b128 v[184:187], v97 offset:52224
	ds_read_b128 v[190:193], v97 offset:53248
	ds_read_b128 v[194:197], v97 offset:54272
	ds_read_b128 v[198:201], v97 offset:55296
	ds_read_b128 v[202:205], v97 offset:56320
	s_mov_b32 m0, s61
	v_lshl_add_u64 v[0:1], s[38:39], 0, v[80:81]
	v_lshl_add_u64 v[0:1], v[0:1], 0, s[56:57]
	v_mov_b32_e32 v80, v86
	global_load_lds_dwordx4 v[0:1], off
	s_mov_b32 m0, s66
	v_lshl_add_u64 v[0:1], s[38:39], 0, v[80:81]
	v_lshl_add_u64 v[0:1], v[0:1], 0, s[56:57]
	global_load_lds_dwordx4 v[0:1], off
	s_barrier
	s_waitcnt lgkmcnt(0)
	s_setprio 1
	s_waitcnt lgkmcnt(0)
	v_mfma_f32_16x16x32_bf16 v[150:153], v[110:113], v[142:145], v[150:153]
	v_mfma_f32_16x16x32_bf16 v[154:157], v[134:137], v[142:145], v[154:157]
	v_mfma_f32_16x16x32_bf16 v[160:163], v[110:113], v[176:179], v[160:163]
	v_mfma_f32_16x16x32_bf16 v[164:167], v[134:137], v[176:179], v[164:167]
	v_mfma_f32_16x16x32_bf16 v[168:171], v[110:113], v[190:193], v[168:171]
	v_mfma_f32_16x16x32_bf16 v[172:175], v[134:137], v[190:193], v[172:175]
	v_mfma_f32_16x16x32_bf16 v[4:7], v[110:113], v[198:201], v[4:7]
	v_mfma_f32_16x16x32_bf16 v[8:11], v[134:137], v[198:201], v[8:11]
	v_mfma_f32_16x16x32_bf16 v[150:153], v[114:117], v[146:149], v[150:153]
	v_mfma_f32_16x16x32_bf16 v[154:157], v[138:141], v[146:149], v[154:157]
	v_mfma_f32_16x16x32_bf16 v[160:163], v[114:117], v[184:187], v[160:163]
	v_mfma_f32_16x16x32_bf16 v[164:167], v[138:141], v[184:187], v[164:167]
	v_mfma_f32_16x16x32_bf16 v[168:171], v[114:117], v[194:197], v[168:171]
	v_mfma_f32_16x16x32_bf16 v[172:175], v[138:141], v[194:197], v[172:175]
	v_mfma_f32_16x16x32_bf16 v[4:7], v[114:117], v[202:205], v[4:7]
	v_mfma_f32_16x16x32_bf16 v[8:11], v[138:141], v[202:205], v[8:11]
	s_setprio 0
	s_barrier
	v_mov_b32_e32 v80, v85
	s_add_i32 s44, s44, s13
	v_lshl_add_u64 v[0:1], s[42:43], 0, v[80:81]
	v_lshl_add_u64 v[0:1], v[0:1], 0, s[56:57]
	s_mov_b32 m0, s44
	v_mov_b32_e32 v80, v87
	global_load_lds_dwordx4 v[0:1], off
	s_add_i32 s41, s44, 0x2000
	v_lshl_add_u64 v[0:1], s[42:43], 0, v[80:81]
	v_lshl_add_u64 v[0:1], v[0:1], 0, s[56:57]
	s_mov_b32 m0, s41
	s_nop 0
	global_load_lds_dwordx4 v[0:1], off
	s_waitcnt vmcnt(6)
	s_barrier
	s_setprio 1
	v_mfma_f32_16x16x32_bf16 v[12:15], v[206:209], v[142:145], v[12:15]
	v_mfma_f32_16x16x32_bf16 v[16:19], v[214:217], v[142:145], v[16:19]
	v_mfma_f32_16x16x32_bf16 v[48:51], v[206:209], v[176:179], v[48:51]
	v_mfma_f32_16x16x32_bf16 v[110:113], v[214:217], v[176:179], v[122:125]
	v_mfma_f32_16x16x32_bf16 v[114:117], v[206:209], v[190:193], v[126:129]
	v_mfma_f32_16x16x32_bf16 v[122:125], v[214:217], v[190:193], v[130:133]
	v_mfma_f32_16x16x32_bf16 v[102:105], v[206:209], v[198:201], v[102:105]
	v_mfma_f32_16x16x32_bf16 v[106:109], v[214:217], v[198:201], v[106:109]
	v_mfma_f32_16x16x32_bf16 v[12:15], v[210:213], v[146:149], v[12:15]
	v_mfma_f32_16x16x32_bf16 v[16:19], v[218:221], v[146:149], v[16:19]
	v_mfma_f32_16x16x32_bf16 v[48:51], v[210:213], v[184:187], v[48:51]
	v_mfma_f32_16x16x32_bf16 v[110:113], v[218:221], v[184:187], v[110:113]
	v_mfma_f32_16x16x32_bf16 v[114:117], v[210:213], v[194:197], v[114:117]
	v_mfma_f32_16x16x32_bf16 v[122:125], v[218:221], v[194:197], v[122:125]
	v_mfma_f32_16x16x32_bf16 v[102:105], v[210:213], v[202:205], v[102:105]
	v_mfma_f32_16x16x32_bf16 v[106:109], v[218:221], v[202:205], v[106:109]
	s_setprio 0
	s_barrier
	ds_read_b128 v[126:129], v83
	ds_read_b128 v[130:133], v83 offset:1024
	ds_read_b128 v[134:137], v83 offset:2048
	ds_read_b128 v[138:141], v83 offset:3072
	s_add_u32 s38, s38, 0x10180
	s_addc_u32 s39, s39, 0
	v_mov_b32_e32 v0, v84
	s_mov_b32 m0, s31
	ds_read_b128 v[142:145], v97
	ds_read_b128 v[146:149], v97 offset:1024
	ds_read_b128 v[176:179], v97 offset:2048
	ds_read_b128 v[184:187], v97 offset:3072
	ds_read_b128 v[190:193], v97 offset:4096
	ds_read_b128 v[194:197], v97 offset:5120
	ds_read_b128 v[198:201], v97 offset:6144
	ds_read_b128 v[202:205], v97 offset:7168
	s_nop 0
	global_load_lds_dwordx4 v0, s[38:39]
	v_mov_b32_e32 v0, v86
	s_mov_b32 m0, s28
	s_nop 0
	global_load_lds_dwordx4 v0, s[38:39]
	s_waitcnt lgkmcnt(8)
	s_barrier
	s_waitcnt lgkmcnt(0)
	s_add_u32 s38, s6, 0x10000
	s_addc_u32 s39, s7, 0
	s_setprio 1
	s_waitcnt lgkmcnt(0)
	v_mfma_f32_16x16x32_bf16 v[52:55], v[126:129], v[142:145], v[52:55]
	v_mfma_f32_16x16x32_bf16 v[56:59], v[134:137], v[142:145], v[56:59]
	v_mfma_f32_16x16x32_bf16 v[60:63], v[126:129], v[176:179], v[60:63]
	v_mfma_f32_16x16x32_bf16 v[64:67], v[134:137], v[176:179], v[64:67]
	v_mfma_f32_16x16x32_bf16 v[68:71], v[126:129], v[190:193], v[68:71]
	v_mfma_f32_16x16x32_bf16 v[72:75], v[134:137], v[190:193], v[72:75]
	v_mfma_f32_16x16x32_bf16 v[76:79], v[126:129], v[198:201], v[76:79]
	v_mfma_f32_16x16x32_bf16 v[98:101], v[134:137], v[198:201], v[98:101]
	v_mfma_f32_16x16x32_bf16 v[52:55], v[130:133], v[146:149], v[52:55]
	v_mfma_f32_16x16x32_bf16 v[56:59], v[138:141], v[146:149], v[56:59]
	v_mfma_f32_16x16x32_bf16 v[60:63], v[130:133], v[184:187], v[60:63]
	v_mfma_f32_16x16x32_bf16 v[64:67], v[138:141], v[184:187], v[64:67]
	v_mfma_f32_16x16x32_bf16 v[68:71], v[130:133], v[194:197], v[68:71]
	v_mfma_f32_16x16x32_bf16 v[72:75], v[138:141], v[194:197], v[72:75]
	v_mfma_f32_16x16x32_bf16 v[76:79], v[130:133], v[202:205], v[76:79]
	v_mfma_f32_16x16x32_bf16 v[98:101], v[138:141], v[202:205], v[98:101]
	s_setprio 0
	s_barrier
; #define G_STAGE(bufoff, gbase, voff) do { _Pragma("unroll") for (int _i = 0; _i < 2; ++_i) { unsigned _vo = (voff)[_i]; asm volatile("" : "+v"(_vo));   \
;     __builtin_amdgcn_global_load_lds((const unsigned*)((const char*)(gbase) + _vo), (LAS unsigned*)(lds + (bufoff) + ldsw + _i * 8192), 16, 0, 0); } } while (0)
; #define G_LDA(dst, b, h) do { _Pragma("unroll") for (int m = 0; m < 4; ++m) _Pragma("unroll") for (int k = 0; k < 2; ++k) dst[m][k] = *(const LAS bf16x8*)(lds + G_SA(b, h) + aoff + m * 2048 + k * 1024); } while (0)
; #define G_LDB(dst, b, h) do { _Pragma("unroll") for (int n = 0; n < 2; ++n) _Pragma("unroll") for (int k = 0; k < 2; ++k) dst[n][k] = *(const LAS bf16x8*)(lds + G_SB(b, h) + boff + n * 2048 + k * 1024); } while (0)
; #define G_MMA(ai, bj, At, Bt) do { __builtin_amdgcn_s_setprio(1); _Pragma("unroll") for (int m = 0; m < 4; ++m) _Pragma("unroll") for (int n = 0; n < 2; ++n) _Pragma("unroll") for (int k = 0; k < 2; ++k) \
;     acc[ai][bj][m][n] = __builtin_amdgcn_mfma_f32_16x16x32_bf16(Bt[n][k], At[m][k], acc[ai][bj][m][n], 0, 0, 0); __builtin_amdgcn_s_setprio(0); } while (0)
; #define G_WAIT_V(n) asm volatile("s_waitcnt vmcnt(" #n ")" ::: "memory")
; #define G_WAIT_L(n) asm volatile("s_waitcnt lgkmcnt(" #n ")" ::: "memory")
; #define G_BAR __builtin_amdgcn_s_barrier()
; #define G_SCHED __builtin_amdgcn_sched_barrier(0)
; template <class Epi>
; __device__ __forceinline__ void gemm_phase(LAS unsigned char* lds, const int K, const unsigned lda_b, const unsigned ldb_b, const Map& M, const Epi& E) {
;     ...
;       G_LDB(B0, 0, 0); G_SCHED; G_LDA(At, 0, 0); G_STAGE(G_SA(1, 1), a1h1, voffA);
;       G_WAIT_L(8); G_BAR; G_WAIT_L(0); G_MMA(0, 0, At, B0); G_BAR; G_SCHED;
;       G_LDB(B1, 0, 1); G_STAGE(G_SB(0, 0), b2h0, voffB);
;       G_BAR; G_WAIT_L(0); G_MMA(0, 1, At, B1); G_BAR;
;       G_LDA(At, 0, 1); G_STAGE(G_SA(0, 0), a2h0, voffA);
;       G_BAR; G_WAIT_L(0); G_MMA(1, 0, At, B0); G_BAR; G_SCHED;
;       G_STAGE(G_SB(0, 1), b2h1, voffB);
;       G_WAIT_V(6); G_BAR; G_MMA(1, 1, At, B1); G_BAR;
;       G_LDB(B0, 1, 0); G_SCHED; G_LDA(At, 1, 0); G_STAGE(G_SA(0, 1), a2h1, voffA);
;       G_WAIT_L(8); G_BAR; G_WAIT_L(0); G_MMA(0, 0, At, B0); G_BAR; G_SCHED;
	v_mov_b32_e32 v0, v85
	s_mov_b32 m0, s30
	ds_read_b128 v[206:209], v181
	ds_read_b128 v[210:213], v181 offset:1024
	ds_read_b128 v[214:217], v181 offset:2048
	ds_read_b128 v[218:221], v181 offset:3072
	s_nop 0
	global_load_lds_dwordx4 v0, s[8:9]
	v_mov_b32_e32 v0, v87
	s_mov_b32 m0, s29
	s_nop 0
	global_load_lds_dwordx4 v0, s[8:9]
	s_barrier
	s_waitcnt lgkmcnt(0)
	s_setprio 1
	s_waitcnt lgkmcnt(0)
	v_mfma_f32_16x16x32_bf16 v[40:43], v[206:209], v[198:201], v[40:43]
	v_mfma_f32_16x16x32_bf16 v[118:121], v[206:209], v[142:145], v[118:121]
	v_mfma_f32_16x16x32_bf16 v[20:23], v[214:217], v[142:145], v[20:23]
	v_mfma_f32_16x16x32_bf16 v[24:27], v[206:209], v[176:179], v[24:27]
	v_mfma_f32_16x16x32_bf16 v[28:31], v[214:217], v[176:179], v[28:31]
	v_mfma_f32_16x16x32_bf16 v[32:35], v[206:209], v[190:193], v[32:35]
	v_mfma_f32_16x16x32_bf16 v[36:39], v[214:217], v[190:193], v[36:39]
	v_mfma_f32_16x16x32_bf16 v[142:145], v[210:213], v[202:205], v[40:43]
	v_mfma_f32_16x16x32_bf16 v[40:43], v[214:217], v[198:201], v[44:47]
	v_mfma_f32_16x16x32_bf16 v[118:121], v[210:213], v[146:149], v[118:121]
	v_mfma_f32_16x16x32_bf16 v[20:23], v[218:221], v[146:149], v[20:23]
	v_mfma_f32_16x16x32_bf16 v[24:27], v[210:213], v[184:187], v[24:27]
	v_mfma_f32_16x16x32_bf16 v[28:31], v[218:221], v[184:187], v[28:31]
	v_mfma_f32_16x16x32_bf16 v[32:35], v[210:213], v[194:197], v[32:35]
	v_mfma_f32_16x16x32_bf16 v[36:39], v[218:221], v[194:197], v[36:39]
	v_mfma_f32_16x16x32_bf16 v[44:47], v[218:221], v[202:205], v[40:43]
	s_setprio 0
	v_mov_b32_e32 v0, v84
	s_mov_b32 m0, s17
	s_barrier
	ds_read_b128 v[40:43], v97 offset:16384
	ds_read_b128 v[146:149], v97 offset:17408
	ds_read_b128 v[176:179], v97 offset:18432
	ds_read_b128 v[184:187], v97 offset:19456
	ds_read_b128 v[190:193], v97 offset:20480
	ds_read_b128 v[194:197], v97 offset:21504
	ds_read_b128 v[198:201], v97 offset:22528
	ds_read_b128 v[202:205], v97 offset:23552
	s_nop 0
	global_load_lds_dwordx4 v0, s[6:7]
	v_mov_b32_e32 v0, v86
	s_mov_b32 m0, s46
	s_nop 0
	global_load_lds_dwordx4 v0, s[6:7]
	s_barrier
	s_waitcnt lgkmcnt(0)
	s_setprio 1
	s_waitcnt lgkmcnt(0)
	v_mfma_f32_16x16x32_bf16 v[150:153], v[126:129], v[40:43], v[150:153]
	v_mfma_f32_16x16x32_bf16 v[154:157], v[134:137], v[40:43], v[154:157]
	v_mfma_f32_16x16x32_bf16 v[160:163], v[126:129], v[176:179], v[160:163]
	v_mfma_f32_16x16x32_bf16 v[164:167], v[134:137], v[176:179], v[164:167]
	v_mfma_f32_16x16x32_bf16 v[168:171], v[126:129], v[190:193], v[168:171]
	v_mfma_f32_16x16x32_bf16 v[172:175], v[134:137], v[190:193], v[172:175]
	v_mfma_f32_16x16x32_bf16 v[4:7], v[126:129], v[198:201], v[4:7]
	v_mfma_f32_16x16x32_bf16 v[8:11], v[134:137], v[198:201], v[8:11]
	v_mfma_f32_16x16x32_bf16 v[150:153], v[130:133], v[146:149], v[150:153]
	v_mfma_f32_16x16x32_bf16 v[154:157], v[138:141], v[146:149], v[154:157]
	v_mfma_f32_16x16x32_bf16 v[160:163], v[130:133], v[184:187], v[160:163]
	v_mfma_f32_16x16x32_bf16 v[164:167], v[138:141], v[184:187], v[164:167]
	v_mfma_f32_16x16x32_bf16 v[168:171], v[130:133], v[194:197], v[168:171]
	v_mfma_f32_16x16x32_bf16 v[172:175], v[138:141], v[194:197], v[172:175]
	v_mfma_f32_16x16x32_bf16 v[4:7], v[130:133], v[202:205], v[4:7]
	v_mfma_f32_16x16x32_bf16 v[126:129], v[138:141], v[202:205], v[8:11]
	s_setprio 0
	s_barrier
	v_mov_b32_e32 v0, v85
	s_mov_b32 m0, s34
	s_nop 0
	global_load_lds_dwordx4 v0, s[2:3]
	v_mov_b32_e32 v0, v87
	s_mov_b32 m0, s35
	s_nop 0
	global_load_lds_dwordx4 v0, s[2:3]
	s_waitcnt vmcnt(6)
	s_barrier
	s_setprio 1
	v_mfma_f32_16x16x32_bf16 v[8:11], v[206:209], v[40:43], v[12:15]
	v_mfma_f32_16x16x32_bf16 v[12:15], v[210:213], v[146:149], v[8:11]
	v_mfma_f32_16x16x32_bf16 v[8:11], v[214:217], v[40:43], v[16:19]
	v_mfma_f32_16x16x32_bf16 v[16:19], v[218:221], v[146:149], v[8:11]
	v_mfma_f32_16x16x32_bf16 v[8:11], v[206:209], v[176:179], v[48:51]
	v_mfma_f32_16x16x32_bf16 v[130:133], v[210:213], v[184:187], v[8:11]
	v_mfma_f32_16x16x32_bf16 v[8:11], v[214:217], v[176:179], v[110:113]
	v_mfma_f32_16x16x32_bf16 v[110:113], v[218:221], v[184:187], v[8:11]
	v_mfma_f32_16x16x32_bf16 v[8:11], v[206:209], v[190:193], v[114:117]
	v_mfma_f32_16x16x32_bf16 v[114:117], v[210:213], v[194:197], v[8:11]
	v_mfma_f32_16x16x32_bf16 v[8:11], v[214:217], v[190:193], v[122:125]
	v_mfma_f32_16x16x32_bf16 v[122:125], v[218:221], v[194:197], v[8:11]
	v_mfma_f32_16x16x32_bf16 v[8:11], v[206:209], v[198:201], v[102:105]
	v_mfma_f32_16x16x32_bf16 v[102:105], v[210:213], v[202:205], v[8:11]
	v_mfma_f32_16x16x32_bf16 v[8:11], v[214:217], v[198:201], v[106:109]
	v_mfma_f32_16x16x32_bf16 v[106:109], v[218:221], v[202:205], v[8:11]
	s_setprio 0
	s_barrier
	s_nop 4
	ds_read_b128 v[8:11], v183
	ds_read_b128 v[134:137], v183 offset:1024
	ds_read_b128 v[138:141], v183 offset:2048
	ds_read_b128 v[146:149], v183 offset:3072
	v_mov_b32_e32 v0, v84
	s_mov_b32 m0, s47
	ds_read_b128 v[176:179], v97 offset:32768
	ds_read_b128 v[184:187], v97 offset:33792
	ds_read_b128 v[190:193], v97 offset:34816
	ds_read_b128 v[194:197], v97 offset:35840
	ds_read_b128 v[198:201], v97 offset:36864
	ds_read_b128 v[202:205], v97 offset:37888
	ds_read_b128 v[206:209], v97 offset:38912
	ds_read_b128 v[210:213], v97 offset:39936
	s_nop 0
	global_load_lds_dwordx4 v0, s[38:39]
	v_mov_b32_e32 v0, v86
	s_mov_b32 m0, s48
	s_nop 0
	global_load_lds_dwordx4 v0, s[38:39]
	s_waitcnt lgkmcnt(8)
	s_barrier
; #define G_STAGE(bufoff, gbase, voff) do { _Pragma("unroll") for (int _i = 0; _i < 2; ++_i) { unsigned _vo = (voff)[_i]; asm volatile("" : "+v"(_vo));   \
;     __builtin_amdgcn_global_load_lds((const unsigned*)((const char*)(gbase) + _vo), (LAS unsigned*)(lds + (bufoff) + ldsw + _i * 8192), 16, 0, 0); } } while (0)
; #define G_LDA(dst, b, h) do { _Pragma("unroll") for (int m = 0; m < 4; ++m) _Pragma("unroll") for (int k = 0; k < 2; ++k) dst[m][k] = *(const LAS bf16x8*)(lds + G_SA(b, h) + aoff + m * 2048 + k * 1024); } while (0)
; #define G_LDB(dst, b, h) do { _Pragma("unroll") for (int n = 0; n < 2; ++n) _Pragma("unroll") for (int k = 0; k < 2; ++k) dst[n][k] = *(const LAS bf16x8*)(lds + G_SB(b, h) + boff + n * 2048 + k * 1024); } while (0)
; #define G_MMA(ai, bj, At, Bt) do { __builtin_amdgcn_s_setprio(1); _Pragma("unroll") for (int m = 0; m < 4; ++m) _Pragma("unroll") for (int n = 0; n < 2; ++n) _Pragma("unroll") for (int k = 0; k < 2; ++k) \
;     acc[ai][bj][m][n] = __builtin_amdgcn_mfma_f32_16x16x32_bf16(Bt[n][k], At[m][k], acc[ai][bj][m][n], 0, 0, 0); __builtin_amdgcn_s_setprio(0); } while (0)
; #define G_WAIT_V(n) asm volatile("s_waitcnt vmcnt(" #n ")" ::: "memory")
; #define G_WAIT_L(n) asm volatile("s_waitcnt lgkmcnt(" #n ")" ::: "memory")
; #define G_BAR __builtin_amdgcn_s_barrier()
; #define G_SCHED __builtin_amdgcn_sched_barrier(0)
; template <class Epi>
; __device__ __forceinline__ void gemm_phase(LAS unsigned char* lds, const int K, const unsigned lda_b, const unsigned ldb_b, const Map& M, const Epi& E) {
;     ...
;       G_WAIT_L(8); G_BAR; G_WAIT_L(0); G_MMA(0, 0, At, B0); G_BAR; G_SCHED;
;       G_LDB(B1, 1, 1); G_STAGE(G_SB(1, 0), b2h0 + kstep, voffB);
;       G_BAR; G_WAIT_L(0); G_MMA(0, 1, At, B1); G_BAR;
;       G_LDA(At, 1, 1); G_STAGE(G_SA(1, 0), a2h0 + kstep, voffA);
;       G_BAR; G_WAIT_L(0); G_MMA(1, 0, At, B0); G_BAR; G_SCHED;
;       G_STAGE(G_SB(1, 1), b2h1 + kstep, voffB);
;       G_WAIT_V(6); G_BAR; G_MMA(1, 1, At, B1); G_BAR;
	s_waitcnt lgkmcnt(0)
	s_setprio 1
	s_waitcnt lgkmcnt(0)
	v_mfma_f32_16x16x32_bf16 v[40:43], v[8:11], v[176:179], v[52:55]
	v_mfma_f32_16x16x32_bf16 v[214:217], v[134:137], v[184:187], v[40:43]
	v_mfma_f32_16x16x32_bf16 v[40:43], v[138:141], v[176:179], v[56:59]
	v_mfma_f32_16x16x32_bf16 v[218:221], v[146:149], v[184:187], v[40:43]
	v_mfma_f32_16x16x32_bf16 v[40:43], v[8:11], v[190:193], v[60:63]
	v_mfma_f32_16x16x32_bf16 v[226:229], v[134:137], v[194:197], v[40:43]
	v_mfma_f32_16x16x32_bf16 v[40:43], v[138:141], v[190:193], v[64:67]
	v_mfma_f32_16x16x32_bf16 v[230:233], v[146:149], v[194:197], v[40:43]
	v_mfma_f32_16x16x32_bf16 v[40:43], v[8:11], v[198:201], v[68:71]
	v_mfma_f32_16x16x32_bf16 v[236:239], v[134:137], v[202:205], v[40:43]
	v_mfma_f32_16x16x32_bf16 v[40:43], v[138:141], v[198:201], v[72:75]
	v_mfma_f32_16x16x32_bf16 v[72:75], v[146:149], v[202:205], v[40:43]
	v_mfma_f32_16x16x32_bf16 v[40:43], v[8:11], v[206:209], v[76:79]
	v_mfma_f32_16x16x32_bf16 v[48:51], v[134:137], v[210:213], v[40:43]
	v_mfma_f32_16x16x32_bf16 v[40:43], v[138:141], v[206:209], v[98:101]
	v_mfma_f32_16x16x32_bf16 v[40:43], v[146:149], v[210:213], v[40:43]
	s_setprio 0
	s_barrier
	v_mov_b32_e32 v80, v85
	ds_read_b128 v[98:101], v188
	ds_read_b128 v[240:243], v188 offset:1024
	ds_read_b128 v[244:247], v188 offset:2048
	ds_read_b128 v[248:251], v188 offset:3072
	s_mov_b32 m0, s45
	v_lshl_add_u64 v[0:1], s[8:9], 0, v[80:81]
	v_lshl_add_u64 v[0:1], v[0:1], 0, s[52:53]
	v_mov_b32_e32 v80, v87
	global_load_lds_dwordx4 v[0:1], off
	s_mov_b32 m0, s40
	v_lshl_add_u64 v[0:1], s[8:9], 0, v[80:81]
	v_lshl_add_u64 v[0:1], v[0:1], 0, s[52:53]
	global_load_lds_dwordx4 v[0:1], off
	s_barrier
	s_waitcnt lgkmcnt(0)
	s_setprio 1
	s_waitcnt lgkmcnt(0)
	v_mfma_f32_16x16x32_bf16 v[20:23], v[244:247], v[176:179], v[20:23]
	v_mfma_f32_16x16x32_bf16 v[52:55], v[98:101], v[176:179], v[118:121]
	v_mfma_f32_16x16x32_bf16 v[176:179], v[248:251], v[184:187], v[20:23]
	v_mfma_f32_16x16x32_bf16 v[20:23], v[98:101], v[190:193], v[24:27]
	v_mfma_f32_16x16x32_bf16 v[118:121], v[240:243], v[184:187], v[52:55]
	v_mfma_f32_16x16x32_bf16 v[184:187], v[240:243], v[194:197], v[20:23]
	v_mfma_f32_16x16x32_bf16 v[20:23], v[244:247], v[190:193], v[28:31]
	v_mfma_f32_16x16x32_bf16 v[190:193], v[248:251], v[194:197], v[20:23]
	v_mfma_f32_16x16x32_bf16 v[20:23], v[98:101], v[198:201], v[32:35]
	v_mfma_f32_16x16x32_bf16 v[194:197], v[240:243], v[202:205], v[20:23]
	v_mfma_f32_16x16x32_bf16 v[20:23], v[244:247], v[198:201], v[36:39]
	v_mfma_f32_16x16x32_bf16 v[198:201], v[248:251], v[202:205], v[20:23]
	v_mfma_f32_16x16x32_bf16 v[20:23], v[98:101], v[206:209], v[142:145]
	v_mfma_f32_16x16x32_bf16 v[64:67], v[240:243], v[210:213], v[20:23]
	v_mfma_f32_16x16x32_bf16 v[20:23], v[244:247], v[206:209], v[44:47]
	v_mfma_f32_16x16x32_bf16 v[60:63], v[248:251], v[210:213], v[20:23]
	s_setprio 0
	v_mov_b32_e32 v80, v84
	s_barrier
	ds_read_b128 v[28:31], v97 offset:49152
	ds_read_b128 v[32:35], v97 offset:50176
	ds_read_b128 v[52:55], v97 offset:51200
	ds_read_b128 v[142:145], v97 offset:52224
	ds_read_b128 v[202:205], v97 offset:53248
	ds_read_b128 v[206:209], v97 offset:54272
	ds_read_b128 v[210:213], v97 offset:55296
	ds_read_b128 v[222:225], v97 offset:56320
	s_mov_b32 m0, s61
	v_lshl_add_u64 v[0:1], s[6:7], 0, v[80:81]
	v_lshl_add_u64 v[0:1], v[0:1], 0, s[52:53]
	v_mov_b32_e32 v80, v86
	global_load_lds_dwordx4 v[0:1], off
	s_mov_b32 m0, s66
	v_lshl_add_u64 v[0:1], s[6:7], 0, v[80:81]
	v_lshl_add_u64 v[0:1], v[0:1], 0, s[52:53]
	global_load_lds_dwordx4 v[0:1], off
	s_barrier
	s_waitcnt lgkmcnt(0)
	s_setprio 1
	s_waitcnt lgkmcnt(0)
	v_mfma_f32_16x16x32_bf16 v[20:23], v[8:11], v[28:31], v[150:153]
	v_mfma_f32_16x16x32_bf16 v[76:79], v[134:137], v[32:35], v[20:23]
	v_mfma_f32_16x16x32_bf16 v[20:23], v[138:141], v[28:31], v[154:157]
	v_mfma_f32_16x16x32_bf16 v[68:71], v[146:149], v[32:35], v[20:23]
	v_mfma_f32_16x16x32_bf16 v[20:23], v[8:11], v[52:55], v[160:163]
	v_mfma_f32_16x16x32_bf16 v[44:47], v[134:137], v[142:145], v[20:23]
	v_mfma_f32_16x16x32_bf16 v[20:23], v[138:141], v[52:55], v[164:167]
	v_mfma_f32_16x16x32_bf16 v[36:39], v[146:149], v[142:145], v[20:23]
	v_mfma_f32_16x16x32_bf16 v[20:23], v[8:11], v[202:205], v[168:171]
	v_mfma_f32_16x16x32_bf16 v[4:7], v[8:11], v[210:213], v[4:7]
	v_mfma_f32_16x16x32_bf16 v[24:27], v[134:137], v[206:209], v[20:23]
	v_mfma_f32_16x16x32_bf16 v[20:23], v[138:141], v[202:205], v[172:175]
	v_mfma_f32_16x16x32_bf16 v[8:11], v[134:137], v[222:225], v[4:7]
	v_mfma_f32_16x16x32_bf16 v[4:7], v[138:141], v[210:213], v[126:129]
	v_mfma_f32_16x16x32_bf16 v[20:23], v[146:149], v[206:209], v[20:23]
	v_mfma_f32_16x16x32_bf16 v[4:7], v[146:149], v[222:225], v[4:7]
	s_setprio 0
	s_barrier
	s_add_u32 s28, s8, 0x4080
	v_mov_b32_e32 v0, v85
	s_mov_b32 m0, s44
	s_addc_u32 s29, s9, 0
	s_nop 0
	global_load_lds_dwordx4 v0, s[28:29]
	v_mov_b32_e32 v0, v87
	s_mov_b32 m0, s41
	s_nop 0
	global_load_lds_dwordx4 v0, s[28:29]
	s_waitcnt vmcnt(6)
	s_barrier
; __device__ __forceinline__ unsigned cvt_pk_bf16(float lo, float hi) { unsigned r; asm("v_cvt_pk_bf16_f32 %0, %1, %2" : "=v"(r) : "v"(lo), "v"(hi)); return r; }
; #define G_MMA(ai, bj, At, Bt) do { __builtin_amdgcn_s_setprio(1); _Pragma("unroll") for (int m = 0; m < 4; ++m) _Pragma("unroll") for (int n = 0; n < 2; ++n) _Pragma("unroll") for (int k = 0; k < 2; ++k) \
;     acc[ai][bj][m][n] = __builtin_amdgcn_mfma_f32_16x16x32_bf16(Bt[n][k], At[m][k], acc[ai][bj][m][n], 0, 0, 0); __builtin_amdgcn_s_setprio(0); } while (0)
; #define G_WAIT_V(n) asm volatile("s_waitcnt vmcnt(" #n ")" ::: "memory")
; #define G_BAR __builtin_amdgcn_s_barrier()
;   __device__ __forceinline__ void operator()(const f32x4 (&acc)[2][2][4][2], const Unit& u, const EpiCtx& x_, int wr, int wc, int fr, int fq) const {
;     ...
;           const int cb = PERM ? (u.c0 + wc * 64 + bj * 32) : (u.c0 + bj * 128) + wc * 32;
;           f32x4 v0 = acc[ai][bj][m][0], v1 = acc[ai][bj][m][1];
;           if (SCALE == 1) { v0 *= rs; v1 *= rs; }
;           if (SCALE == 2) { v0 *= cs[bj][0]; v1 *= cs[bj][1]; }
;           if (PERM) {
;             uint4 o; o.x = cvt_pk_bf16(v0[0], v0[1]); o.y = cvt_pk_bf16(v0[2], v0[3]); o.z = cvt_pk_bf16(v1[0], v1[1]); o.w = cvt_pk_bf16(v1[2], v1[3]);
;             *(uint4*)(rowp + cb + 8 * fq) = o;
;           } else {
;             uint2 o0, o1; o0.x = cvt_pk_bf16(v0[0], v0[1]); o0.y = cvt_pk_bf16(v0[2], v0[3]); o1.x = cvt_pk_bf16(v1[0], v1[1]); o1.y = cvt_pk_bf16(v1[2], v1[3]);
;             *(uint2*)(rowp + cb + 4 * fq) = o0; *(uint2*)(rowp + cb + 16 + 4 * fq) = o1;
; template <class Epi>
; __device__ __forceinline__ void gemm_phase(LAS unsigned char* lds, const int K, const unsigned lda_b, const unsigned ldb_b, const Map& M, const Epi& E) {
;     ...
;       G_WAIT_V(6); G_BAR; G_MMA(1, 1, At, B1); G_BAR;
;     }
;     E(acc, cur, X, wr, wc, fr, fq);
;     if (!has_next) break;
; #pragma unroll
;     for (int a = 0; a < 2; ++a)
; #pragma unroll
;       for (int b = 0; b < 2; ++b)
; #pragma unroll
;         for (int m = 0; m < 4; ++m)
; #pragma unroll
;           for (int n = 0; n < 2; ++n) acc[a][b][m][n] = (f32x4){0.f, 0.f, 0.f, 0.f};
;     cur = nxt; ++ui;
	s_setprio 1
	v_mfma_f32_16x16x32_bf16 v[12:15], v[98:101], v[28:31], v[12:15]
	v_mfma_f32_16x16x32_bf16 v[126:129], v[240:243], v[32:35], v[12:15]
	v_mfma_f32_16x16x32_bf16 v[12:15], v[244:247], v[28:31], v[16:19]
	v_mfma_f32_16x16x32_bf16 v[134:137], v[248:251], v[32:35], v[12:15]
	v_mfma_f32_16x16x32_bf16 v[12:15], v[98:101], v[52:55], v[130:133]
	v_mfma_f32_16x16x32_bf16 v[56:59], v[240:243], v[142:145], v[12:15]
	v_mfma_f32_16x16x32_bf16 v[12:15], v[244:247], v[52:55], v[110:113]
	v_mfma_f32_16x16x32_bf16 v[52:55], v[248:251], v[142:145], v[12:15]
	v_mfma_f32_16x16x32_bf16 v[12:15], v[98:101], v[202:205], v[114:117]
	v_mfma_f32_16x16x32_bf16 v[32:35], v[240:243], v[206:209], v[12:15]
	v_mfma_f32_16x16x32_bf16 v[12:15], v[244:247], v[202:205], v[122:125]
	v_mfma_f32_16x16x32_bf16 v[28:31], v[248:251], v[206:209], v[12:15]
	v_mfma_f32_16x16x32_bf16 v[12:15], v[98:101], v[210:213], v[102:105]
	v_mfma_f32_16x16x32_bf16 v[16:19], v[240:243], v[222:225], v[12:15]
	v_mfma_f32_16x16x32_bf16 v[12:15], v[244:247], v[210:213], v[106:109]
	v_mfma_f32_16x16x32_bf16 v[12:15], v[248:251], v[222:225], v[12:15]
	s_setprio 0
	v_add_u32_e32 v0, s18, v88
	v_ashrrev_i32_e32 v1, 31, v0
	s_add_i32 s30, s19, s67
	v_lshlrev_b64 v[0:1], 12, v[0:1]
	s_ashr_i32 s31, s30, 31
	v_lshl_add_u64 v[0:1], s[4:5], 0, v[0:1]
	v_mov_b32_e32 v83, v81
	s_lshl_b64 s[38:39], s[30:31], 1
	s_add_i32 s30, s68, s19
	v_lshl_add_u64 v[98:99], v[0:1], 0, v[82:83]
	s_ashr_i32 s31, s30, 31
	v_cvt_pk_bf16_f32 v0, v214, v215
	v_lshl_add_u64 v[100:101], v[98:99], 0, s[38:39]
	s_lshl_b64 s[40:41], s[30:31], 1
	s_barrier
	v_readfirstlane_b32 s28, v2
	v_readfirstlane_b32 s29, v3
	v_cvt_pk_bf16_f32 v1, v216, v217
	v_cvt_pk_bf16_f32 v2, v218, v219
	v_cvt_pk_bf16_f32 v3, v220, v221
	s_waitcnt vmcnt(0)
	global_store_dwordx4 v[100:101], v[0:3], off
	v_lshl_add_u64 v[98:99], v[98:99], 0, s[40:41]
	s_cmp_eq_u32 s69, s49
	v_cvt_pk_bf16_f32 v0, v118, v119
	v_cvt_pk_bf16_f32 v1, v120, v121
	v_cvt_pk_bf16_f32 v2, v176, v177
	v_cvt_pk_bf16_f32 v3, v178, v179
	global_store_dwordx4 v[98:99], v[0:3], off
	s_nop 1
	v_add_u32_e32 v0, s18, v90
	v_ashrrev_i32_e32 v1, 31, v0
	v_lshlrev_b64 v[0:1], 12, v[0:1]
	v_lshl_add_u64 v[0:1], s[4:5], 0, v[0:1]
	v_lshl_add_u64 v[98:99], v[0:1], 0, v[82:83]
	v_cvt_pk_bf16_f32 v0, v226, v227
	v_lshl_add_u64 v[100:101], v[98:99], 0, s[38:39]
	v_cvt_pk_bf16_f32 v1, v228, v229
	v_cvt_pk_bf16_f32 v2, v230, v231
	v_cvt_pk_bf16_f32 v3, v232, v233
	global_store_dwordx4 v[100:101], v[0:3], off
	v_lshl_add_u64 v[98:99], v[98:99], 0, s[40:41]
	s_nop 0
	v_cvt_pk_bf16_f32 v0, v184, v185
	v_cvt_pk_bf16_f32 v1, v186, v187
	v_cvt_pk_bf16_f32 v2, v190, v191
	v_cvt_pk_bf16_f32 v3, v192, v193
	global_store_dwordx4 v[98:99], v[0:3], off
	s_nop 1
	v_add_u32_e32 v0, s18, v91
	v_ashrrev_i32_e32 v1, 31, v0
	v_lshlrev_b64 v[0:1], 12, v[0:1]
	v_lshl_add_u64 v[0:1], s[4:5], 0, v[0:1]
	v_lshl_add_u64 v[98:99], v[0:1], 0, v[82:83]
	v_cvt_pk_bf16_f32 v0, v236, v237
	v_cvt_pk_bf16_f32 v2, v72, v73
	v_lshl_add_u64 v[72:73], v[98:99], 0, s[38:39]
	v_cvt_pk_bf16_f32 v1, v238, v239
	v_cvt_pk_bf16_f32 v3, v74, v75
	global_store_dwordx4 v[72:73], v[0:3], off
	v_lshl_add_u64 v[72:73], v[98:99], 0, s[40:41]
	s_nop 0
	v_cvt_pk_bf16_f32 v0, v194, v195
	v_cvt_pk_bf16_f32 v1, v196, v197
	v_cvt_pk_bf16_f32 v2, v198, v199
	v_cvt_pk_bf16_f32 v3, v200, v201
	global_store_dwordx4 v[72:73], v[0:3], off
	s_nop 1
	v_add_u32_e32 v0, s18, v92
	v_ashrrev_i32_e32 v1, 31, v0
	v_lshlrev_b64 v[0:1], 12, v[0:1]
	v_lshl_add_u64 v[0:1], s[4:5], 0, v[0:1]
	v_lshl_add_u64 v[72:73], v[0:1], 0, v[82:83]
	v_cvt_pk_bf16_f32 v0, v48, v49
	v_cvt_pk_bf16_f32 v2, v40, v41
	v_lshl_add_u64 v[40:41], v[72:73], 0, s[38:39]
	v_cvt_pk_bf16_f32 v1, v50, v51
	v_cvt_pk_bf16_f32 v3, v42, v43
	global_store_dwordx4 v[40:41], v[0:3], off
	v_lshl_add_u64 v[40:41], v[72:73], 0, s[40:41]
	s_nop 0
	v_cvt_pk_bf16_f32 v0, v64, v65
	v_cvt_pk_bf16_f32 v1, v66, v67
	v_cvt_pk_bf16_f32 v2, v60, v61
	v_cvt_pk_bf16_f32 v3, v62, v63
	global_store_dwordx4 v[40:41], v[0:3], off
	s_nop 1
	v_add_u32_e32 v0, s18, v93
	v_ashrrev_i32_e32 v1, 31, v0
	v_lshlrev_b64 v[0:1], 12, v[0:1]
	v_lshl_add_u64 v[0:1], s[4:5], 0, v[0:1]
	v_lshl_add_u64 v[40:41], v[0:1], 0, v[82:83]
	v_cvt_pk_bf16_f32 v0, v76, v77
	v_lshl_add_u64 v[42:43], v[40:41], 0, s[38:39]
	v_cvt_pk_bf16_f32 v1, v78, v79
	v_cvt_pk_bf16_f32 v2, v68, v69
	v_cvt_pk_bf16_f32 v3, v70, v71
	global_store_dwordx4 v[42:43], v[0:3], off
	v_lshl_add_u64 v[40:41], v[40:41], 0, s[40:41]
	s_nop 0
	v_cvt_pk_bf16_f32 v0, v126, v127
	v_cvt_pk_bf16_f32 v1, v128, v129
	v_cvt_pk_bf16_f32 v2, v134, v135
	v_cvt_pk_bf16_f32 v3, v136, v137
	global_store_dwordx4 v[40:41], v[0:3], off
	s_nop 1
	v_add_u32_e32 v0, s18, v94
	v_ashrrev_i32_e32 v1, 31, v0
	v_lshlrev_b64 v[0:1], 12, v[0:1]
	v_lshl_add_u64 v[0:1], s[4:5], 0, v[0:1]
	v_lshl_add_u64 v[40:41], v[0:1], 0, v[82:83]
	v_cvt_pk_bf16_f32 v0, v44, v45
	v_cvt_pk_bf16_f32 v2, v36, v37
	v_lshl_add_u64 v[36:37], v[40:41], 0, s[38:39]
	v_cvt_pk_bf16_f32 v1, v46, v47
	v_cvt_pk_bf16_f32 v3, v38, v39
	global_store_dwordx4 v[36:37], v[0:3], off
	v_lshl_add_u64 v[36:37], v[40:41], 0, s[40:41]
	s_nop 0
	v_cvt_pk_bf16_f32 v0, v56, v57
	v_cvt_pk_bf16_f32 v1, v58, v59
	v_cvt_pk_bf16_f32 v2, v52, v53
	v_cvt_pk_bf16_f32 v3, v54, v55
	global_store_dwordx4 v[36:37], v[0:3], off
	s_nop 1
	v_add_u32_e32 v0, s18, v95
	v_ashrrev_i32_e32 v1, 31, v0
	v_lshlrev_b64 v[0:1], 12, v[0:1]
	v_lshl_add_u64 v[0:1], s[4:5], 0, v[0:1]
	v_lshl_add_u64 v[36:37], v[0:1], 0, v[82:83]
	v_cvt_pk_bf16_f32 v0, v24, v25
	v_cvt_pk_bf16_f32 v2, v20, v21
	v_lshl_add_u64 v[20:21], v[36:37], 0, s[38:39]
	v_cvt_pk_bf16_f32 v1, v26, v27
	v_cvt_pk_bf16_f32 v3, v22, v23
	global_store_dwordx4 v[20:21], v[0:3], off
	v_lshl_add_u64 v[20:21], v[36:37], 0, s[40:41]
	s_nop 0
	v_cvt_pk_bf16_f32 v0, v32, v33
	v_cvt_pk_bf16_f32 v1, v34, v35
	v_cvt_pk_bf16_f32 v2, v28, v29
	v_cvt_pk_bf16_f32 v3, v30, v31
	global_store_dwordx4 v[20:21], v[0:3], off
	s_nop 1
	v_add_u32_e32 v0, s18, v96
	v_ashrrev_i32_e32 v1, 31, v0
	v_lshlrev_b64 v[0:1], 12, v[0:1]
	v_lshl_add_u64 v[0:1], s[4:5], 0, v[0:1]
	v_lshl_add_u64 v[20:21], v[0:1], 0, v[82:83]
	v_cvt_pk_bf16_f32 v2, v4, v5
	v_lshl_add_u64 v[4:5], v[20:21], 0, s[38:39]
	v_cvt_pk_bf16_f32 v0, v8, v9
	v_cvt_pk_bf16_f32 v1, v10, v11
	v_cvt_pk_bf16_f32 v3, v6, v7
	global_store_dwordx4 v[4:5], v[0:3], off
	v_lshl_add_u64 v[4:5], v[20:21], 0, s[40:41]
	s_mov_b64 s[18:19], -1
	v_cvt_pk_bf16_f32 v0, v16, v17
	v_cvt_pk_bf16_f32 v1, v18, v19
	v_cvt_pk_bf16_f32 v2, v12, v13
	v_cvt_pk_bf16_f32 v3, v14, v15
	global_store_dwordx4 v[4:5], v[0:3], off
	s_cbranch_scc1 .LBB0_932
	s_add_i32 s49, s49, 1
	s_mov_b64 s[18:19], 0
	s_mov_b64 s[4:5], s[36:37]
	s_mov_b64 s[40:41], s[8:9]
	s_mov_b64 s[38:39], s[6:7]
	s_branch .LBB0_932

; #define LAS __attribute__((address_space(3)))
; __device__ __forceinline__ int otid() { int t = threadIdx.x; asm volatile("" : "+v"(t)); return t; }
;   __device__ __forceinline__ bool next(int i, Unit& u) const {
;     const long Ll = (long)i * G + c;
;     if (Ll >= total) return false;
;     const int L = (int)Ll;
;     int pm, pn;
;     u.pad0 = 0; u.pad1 = 0;
;     if (mode == 0) {
;       tile_order(L, nM, nN, pm, pn);
;       if (p1 == -77 && pm >= p0) ++pm;
;       u.a0 = A + (size_t)pm * a_t; u.b0 = B + (size_t)pn * b_t; u.b1 = u.b0 + b_h;
;       u.r0 = pm * 256; u.c0 = pn * 256; u.C = C;
; __device__ __forceinline__ int build_units(LAS unsigned char* lds, const Map& m) {
;   LAS Unit* ul = (LAS Unit*)(lds + STAGE_BYTES);
;   __syncthreads();
;   const int tid_ = otid();
;   if (tid_ < MAX_UNITS) { Unit u; if (m.next(tid_, u)) {
;       LAS unsigned long long* w = (LAS unsigned long long*)(ul + tid_);
;       w[0] = (unsigned long long)u.a0; w[1] = (unsigned long long)u.b0; w[2] = (unsigned long long)u.b1; w[3] = (unsigned long long)u.C;
;       w[4] = ((unsigned long long)(unsigned)u.c0 << 32) | (unsigned)u.r0; } }
;   __syncthreads();
;   const long rest = (long)m.total - m.c;
;   int n = rest > 0 ? (int)((rest + m.G - 1) / m.G) : 0;
;   return n < MAX_UNITS ? n : MAX_UNITS;
; }
.LBB0_938:
	v_mov_b64_e32 v[0:1], s[10:11]
	global_load_dwordx2 v[2:3], v[0:1], off sc0 sc1
	s_waitcnt vmcnt(0)
	global_load_dwordx2 v[0:1], v[0:1], off sc0 sc1
	s_waitcnt vmcnt(0)
	v_readlane_b32 s0, v255, 34
	v_readlane_b32 s1, v255, 35
	s_andn2_b64 vcc, exec, s[0:1]
	s_mov_b64 s[2:3], 0
	s_waitcnt lgkmcnt(0)
	v_readfirstlane_b32 s0, v3
	v_readfirstlane_b32 s13, v2
	v_readfirstlane_b32 s5, v1
	v_readfirstlane_b32 s4, v0
	s_cbranch_vccnz .LBB0_940
	v_readlane_b32 s2, v255, 0
	v_readlane_b32 s3, v255, 1
	s_nop 1
	v_mov_b64_e32 v[0:1], s[2:3]
	global_load_dwordx2 v[0:1], v[0:1], off offset:112 sc0 sc1
	s_waitcnt vmcnt(0)
	s_lshl_b64 s[2:3], s[90:91], 2
	s_waitcnt lgkmcnt(0)
	v_readfirstlane_b32 s6, v0
	v_readfirstlane_b32 s1, v1
	s_add_u32 s2, s6, s2
	s_addc_u32 s3, s1, s3
.LBB0_940:
	v_mov_b64_e32 v[0:1], s[10:11]
	global_load_dwordx2 v[2:3], v[0:1], off sc0 sc1
	s_waitcnt vmcnt(0) lgkmcnt(0)
	v_readfirstlane_b32 s18, v2
	v_mov_b32_e32 v2, s74
	ds_read_b32 v2, v2
	v_readfirstlane_b32 s1, v3
	s_waitcnt lgkmcnt(0)
	v_readfirstlane_b32 s17, v2
	global_load_dwordx2 v[2:3], v[0:1], off sc0 sc1
	s_waitcnt vmcnt(0) lgkmcnt(0)
	v_readfirstlane_b32 s19, v3
	v_readfirstlane_b32 s28, v2
	global_load_dwordx2 v[2:3], v[0:1], off sc0 sc1
	s_waitcnt vmcnt(0) lgkmcnt(0)
	v_readfirstlane_b32 s29, v3
	v_readfirstlane_b32 s30, v2
	global_load_dwordx2 v[2:3], v[0:1], off sc0 sc1
	s_waitcnt vmcnt(0) lgkmcnt(0)
	v_readfirstlane_b32 s35, v2
	global_load_dwordx2 v[0:1], v[0:1], off sc0 sc1
	s_waitcnt vmcnt(0)
	v_mov_b32_e32 v2, v252
	v_readfirstlane_b32 s31, v3
	s_waitcnt lgkmcnt(0)
	s_barrier
	v_readfirstlane_b32 s34, v1
	v_readfirstlane_b32 s38, v0
	v_cmp_gt_i32_e32 vcc, 40, v2
	s_and_saveexec_b64 s[6:7], vcc
	s_cbranch_execz .LBB0_947
	s_ashr_i32 s8, s17, 31
	v_mov_b32_e32 v0, s17
	v_mov_b32_e32 v1, s8
	v_mad_i64_i32 v[0:1], s[8:9], v2, s20, v[0:1]
	v_cmp_gt_i64_e32 vcc, s[70:71], v[0:1]
	s_and_b64 exec, exec, vcc
	s_cbranch_execz .LBB0_947
	v_ashrrev_i32_e32 v1, 31, v0
	v_lshrrev_b32_e32 v1, 29, v1
	v_add_u32_e32 v1, v0, v1
	v_and_b32_e32 v3, -8, v1
	v_sub_u32_e32 v3, v0, v3
	v_cmp_lt_i32_e32 vcc, -1, v3
	s_and_saveexec_b64 s[8:9], vcc
	s_xor_b64 s[8:9], exec, s[8:9]
	v_lshlrev_b32_e32 v0, 6, v3
	s_andn2_saveexec_b64 s[8:9], s[8:9]
	v_lshl_add_u32 v0, v3, 6, v3
	s_or_b64 exec, exec, s[8:9]
	v_ashrrev_i32_e32 v1, 3, v1
	v_add_u32_e32 v0, v0, v1
	v_ashrrev_i32_e32 v1, 31, v0
	v_lshrrev_b32_e32 v1, 27, v1
	v_add_u32_e32 v1, v0, v1
	v_ashrrev_i32_e32 v3, 5, v1
	v_lshlrev_b32_e32 v3, 2, v3
	v_sub_u32_e32 v4, 64, v3
	v_min_i32_e32 v4, 4, v4
	v_sub_u32_e32 v5, 0, v4
	v_max_i32_e32 v5, v4, v5
	v_cvt_f32_u32_e32 v6, v5
	v_and_b32_e32 v1, 0xffffffe0, v1
	v_sub_u32_e32 v8, 0, v5
	v_sub_u32_e32 v0, v0, v1
	v_rcp_iflag_f32_e32 v6, v6
	v_sub_u32_e32 v1, 0, v0
	v_max_i32_e32 v1, v0, v1
	v_xor_b32_e32 v7, v0, v4
	v_mul_f32_e32 v6, 0x4f7ffffe, v6
	v_cvt_u32_f32_e32 v6, v6
	v_ashrrev_i32_e32 v7, 31, v7
	v_mul_lo_u32 v8, v8, v6
	v_mul_hi_u32 v8, v6, v8
	v_add_u32_e32 v6, v6, v8
	v_mul_hi_u32 v6, v1, v6
	v_mul_lo_u32 v8, v6, v5
	v_sub_u32_e32 v1, v1, v8
	v_add_u32_e32 v9, 1, v6
	v_cmp_ge_u32_e32 vcc, v1, v5
	v_sub_u32_e32 v8, v1, v5
	s_nop 0
	v_cndmask_b32_e32 v6, v6, v9, vcc
	v_cndmask_b32_e32 v1, v1, v8, vcc
	v_add_u32_e32 v8, 1, v6
	v_cmp_ge_u32_e32 vcc, v1, v5
	s_nop 1
	v_cndmask_b32_e32 v1, v6, v8, vcc
	v_xor_b32_e32 v1, v1, v7
	v_sub_u32_e32 v6, v1, v7
	v_mul_lo_u32 v1, v6, v4
	v_sub_u32_e32 v0, v0, v1
	v_ashrrev_i32_e32 v7, 31, v6
	v_add_u32_e32 v8, v3, v0
	v_lshlrev_b64 v[0:1], 20, v[6:7]
	v_lshl_add_u64 v[0:1], s[4:5], 0, v[0:1]
	s_mov_b64 s[4:5], 0x6000000
	v_lshl_add_u64 v[4:5], v[0:1], 0, s[4:5]
	s_mov_b64 s[4:5], 0x6080000
	v_lshl_add_u64 v[0:1], v[0:1], 0, s[4:5]
	v_mad_u64_u32 v[2:3], s[4:5], v2, 48, v[232:233]
	v_ashrrev_i32_e32 v9, 31, v8
	s_add_u32 s4, s13, 0x7920000
	v_lshlrev_b64 v[10:11], 20, v[8:9]
	s_addc_u32 s5, s0, 0
	v_add_u32_e32 v7, 0x20000, v2
	v_lshl_add_u64 v[2:3], s[4:5], 0, v[10:11]
	v_lshlrev_b32_e32 v8, 8, v8
	ds_write_b128 v7, v[2:5]
	v_mov_b32_e32 v2, s2
	v_mov_b32_e32 v3, s3
	v_lshlrev_b32_e32 v9, 8, v6
	ds_write_b128 v7, v[0:3] offset:16
	ds_write_b64 v7, v[8:9] offset:32

; #define LAS __attribute__((address_space(3)))
; __device__ __forceinline__ int otid() { int t = threadIdx.x; asm volatile("" : "+v"(t)); return t; }
; __device__ __forceinline__ void gbar(unsigned* bar, unsigned n, volatile LAS unsigned* st) {
;   asm volatile("s_waitcnt vmcnt(0)" ::: "memory");
;   __syncthreads();
;   if (otid() == 0) {
;     __builtin_amdgcn_s_waitcnt(0);
;     const unsigned x = st[0], nloc = st[1], nx = st[2];
.LBB0_1010:
	s_waitcnt lgkmcnt(0)
	v_mov_b64_e32 v[0:1], s[10:11]
	global_load_dwordx2 v[0:1], v[0:1], off sc0 sc1
	s_waitcnt vmcnt(0)
	s_waitcnt vmcnt(0)
	v_mov_b32_e32 v2, v252
	s_waitcnt lgkmcnt(0)
	s_barrier
	v_readfirstlane_b32 s0, v1
	v_readfirstlane_b32 s1, v0
	v_cmp_ne_u32_e32 vcc, 0, v2
	s_and_saveexec_b64 s[2:3], vcc
	s_xor_b64 s[2:3], exec, s[2:3]
	v_add_u32_e32 v236, 6, v158
	s_andn2_saveexec_b64 s[2:3], s[2:3]
	s_cbranch_execnz .LBB0_1013
	s_getpc_b64 s[98:99]

; __device__ __forceinline__ int otid() { int t = threadIdx.x; asm volatile("" : "+v"(t)); return t; }
; __device__ __forceinline__ unsigned xb_ld(unsigned* p) { return __hip_atomic_load(p, __ATOMIC_RELAXED, __HIP_MEMORY_SCOPE_AGENT); }
; __device__ __forceinline__ unsigned xb_add(unsigned* p, unsigned v) { return __hip_atomic_fetch_add(p, v, __ATOMIC_RELAXED, __HIP_MEMORY_SCOPE_AGENT); }
; __device__ __forceinline__ void gbar(unsigned* bar, unsigned n, volatile LAS unsigned* st) {
;     ...
;   if (otid() == 0) {
;     __builtin_amdgcn_s_waitcnt(0);
;     const unsigned x = st[0], nloc = st[1], nx = st[2];
;     const unsigned old = xb_add(&bar[XB_XSUB(x)], 1u);
;     unsigned sp = 0;
;     if (old + 1u == (n + 1u) * nloc) {
;       __builtin_amdgcn_fence(__ATOMIC_RELEASE, "agent");
;       asm volatile("s_waitcnt vmcnt(0)" ::: "memory");
;       xb_add(&bar[XB_TOP], 1u);
;       while (xb_ld(&bar[XB_TOP]) < (n + 1u) * nx) { __builtin_amdgcn_s_sleep(1); if (++sp > (1u << 24)) break; }
;       __builtin_amdgcn_fence(__ATOMIC_ACQUIRE, "agent");
;       xb_add(&bar[XB_XGEN(x)], 1u);
;       asm volatile("s_waitcnt vmcnt(0)" ::: "memory");
;     } else {
;       while (xb_ld(&bar[XB_XGEN(x)]) <= n) { __builtin_amdgcn_s_sleep(1); if (++sp > (1u << 24)) break; }
.LBB0_1013:
	v_readlane_b32 s6, v255, 15
	s_waitcnt vmcnt(0) expcnt(0) lgkmcnt(0)
	s_add_u32 s4, s1, 0x4cc80000
	v_mov_b32_e32 v0, s6
	ds_read_b32 v1, v0
	v_readlane_b32 s6, v255, 16
	s_addc_u32 s5, s0, 0
	v_add_u32_e32 v236, 6, v158
	v_mov_b32_e32 v0, s6
	s_waitcnt lgkmcnt(0)
	v_lshlrev_b32_e32 v1, 6, v1
	v_add_u32_e32 v80, 0x440, v1
	v_readlane_b32 s6, v255, 17
	v_lshlrev_b64 v[2:3], 2, v[80:81]
	ds_read_b32 v4, v0
	v_mov_b32_e32 v0, s6
	v_lshl_add_u64 v[2:3], s[4:5], 0, v[2:3]
	ds_read_b32 v0, v0
	global_atomic_add v2, v[2:3], v230, off sc0
	s_waitcnt lgkmcnt(0)
	v_mul_lo_u32 v3, v4, v236
	v_add_u32_e32 v80, 0x840, v1
	s_waitcnt vmcnt(0)
	v_add_u32_e32 v2, 1, v2
	v_cmp_ne_u32_e32 vcc, v2, v3
	s_and_saveexec_b64 s[6:7], vcc
	s_xor_b64 s[6:7], exec, s[6:7]
	s_cbranch_execz .LBB0_1038
	v_lshlrev_b64 v[0:1], 2, v[80:81]
	v_lshl_add_u64 v[0:1], s[4:5], 0, v[0:1]
	s_mov_b32 s13, 0x1000000
	s_mov_b64 s[8:9], 0
	s_branch .LBB0_1026

; __device__ __forceinline__ unsigned xb_ld(unsigned* p) { return __hip_atomic_load(p, __ATOMIC_RELAXED, __HIP_MEMORY_SCOPE_AGENT); }
; __device__ __forceinline__ void gbar(unsigned* bar, unsigned n, volatile LAS unsigned* st) {
;     ...
;       while (xb_ld(&bar[XB_XGEN(x)]) <= n) { __builtin_amdgcn_s_sleep(1); if (++sp > (1u << 24)) break; }
.LBB0_1026:
	global_load_dword v2, v[0:1], off sc1
	s_or_b64 s[36:37], s[36:37], exec
	s_waitcnt vmcnt(0) lgkmcnt(0)
	v_cmp_le_u32_e32 vcc, v2, v159
	s_and_saveexec_b64 s[38:39], vcc
	s_cbranch_execz .LBB0_1025
	s_cmp_lg_u32 s13, 0
	s_sleep 1
	s_cbranch_scc0 .LBB0_1036
	global_load_dword v2, v[0:1], off sc1
	s_mov_b64 s[18:19], -1
	s_waitcnt vmcnt(0) lgkmcnt(0)
	v_cmp_le_u32_e32 vcc, v2, v159
	s_and_saveexec_b64 s[40:41], vcc
	s_cbranch_execz .LBB0_1023
	s_sleep 1
	global_load_dword v2, v[0:1], off sc1
	s_waitcnt vmcnt(0) lgkmcnt(0)
	v_cmp_le_u32_e32 vcc, v2, v159
	s_and_saveexec_b64 s[42:43], vcc
	s_cbranch_execz .LBB0_1022
	s_sleep 1
	global_load_dword v2, v[0:1], off sc1
	s_waitcnt vmcnt(0) lgkmcnt(0)
	v_cmp_le_u32_e32 vcc, v2, v159
	s_and_saveexec_b64 s[44:45], vcc
	s_cbranch_execz .LBB0_1021
	s_sleep 1
	global_load_dword v2, v[0:1], off sc1
	s_waitcnt vmcnt(0) lgkmcnt(0)
	v_cmp_le_u32_e32 vcc, v2, v159
	s_and_saveexec_b64 s[46:47], vcc
	s_cbranch_execz .LBB0_1020
	s_sleep 1
	global_load_dword v2, v[0:1], off sc1
	s_waitcnt vmcnt(0) lgkmcnt(0)
	v_cmp_le_u32_e32 vcc, v2, v159
	s_and_saveexec_b64 s[68:69], vcc
	s_cbranch_execz .LBB0_1019
	s_sleep 1
	global_load_dword v2, v[0:1], off sc1
	s_mov_b64 s[48:49], -1
	s_waitcnt vmcnt(0) lgkmcnt(0)
	v_cmp_le_u32_e32 vcc, v2, v159
	s_and_saveexec_b64 s[18:19], vcc
	s_cbranch_execz .LBB0_1018
	s_sleep 1
	global_load_dword v2, v[0:1], off sc1
	s_waitcnt vmcnt(0) lgkmcnt(0)
	v_cmp_le_u32_e32 vcc, v2, v159
	s_and_saveexec_b64 s[66:67], vcc
	s_cbranch_execz .LBB0_1017
	s_add_i32 s13, s13, -8
	s_xor_b64 s[48:49], exec, -1
	s_sleep 1
	s_branch .LBB0_1017

; __device__ __forceinline__ unsigned xb_ld(unsigned* p) { return __hip_atomic_load(p, __ATOMIC_RELAXED, __HIP_MEMORY_SCOPE_AGENT); }
; __device__ __forceinline__ unsigned xb_add(unsigned* p, unsigned v) { return __hip_atomic_fetch_add(p, v, __ATOMIC_RELAXED, __HIP_MEMORY_SCOPE_AGENT); }
; __device__ __forceinline__ void gbar(unsigned* bar, unsigned n, volatile LAS unsigned* st) {
;     ...
;     if (old + 1u == (n + 1u) * nloc) {
;       __builtin_amdgcn_fence(__ATOMIC_RELEASE, "agent");
;       asm volatile("s_waitcnt vmcnt(0)" ::: "memory");
;       xb_add(&bar[XB_TOP], 1u);
;       while (xb_ld(&bar[XB_TOP]) < (n + 1u) * nx) { __builtin_amdgcn_s_sleep(1); if (++sp > (1u << 24)) break; }
.LBB0_1039:
	v_mov_b32_e32 v1, s1
	v_add_co_u32_e32 v2, vcc, 0x4cc83000, v1
	v_mov_b32_e32 v1, s0
	buffer_wbl2 sc1
	s_waitcnt vmcnt(0)
	v_addc_co_u32_e32 v3, vcc, 0, v1, vcc
	global_atomic_add v[2:3], v230, off offset:256
	s_add_u32 s8, s1, 0x4cc83100
	s_addc_u32 s9, s0, 0
	v_mul_lo_u32 v0, v0, v236
	s_mov_b32 s0, 0x1000000
	s_mov_b64 s[36:37], 0
	s_branch .LBB0_1049

; __device__ __forceinline__ unsigned xb_ld(unsigned* p) { return __hip_atomic_load(p, __ATOMIC_RELAXED, __HIP_MEMORY_SCOPE_AGENT); }
; __device__ __forceinline__ void gbar(unsigned* bar, unsigned n, volatile LAS unsigned* st) {
;     ...
;       while (xb_ld(&bar[XB_TOP]) < (n + 1u) * nx) { __builtin_amdgcn_s_sleep(1); if (++sp > (1u << 24)) break; }
.LBB0_1049:
	v_mov_b64_e32 v[2:3], s[8:9]
	global_load_dword v1, v[2:3], off sc1
	s_or_b64 s[38:39], s[38:39], exec
	s_waitcnt vmcnt(0) lgkmcnt(0)
	v_cmp_lt_u32_e32 vcc, v1, v0
	s_and_saveexec_b64 s[40:41], vcc
	s_cbranch_execz .LBB0_1048
	s_cmp_lg_u32 s0, 0
	s_sleep 1
	s_cbranch_scc0 .LBB0_1059
	v_mov_b64_e32 v[2:3], s[8:9]
	global_load_dword v1, v[2:3], off sc1
	s_mov_b64 s[18:19], -1
	s_waitcnt vmcnt(0) lgkmcnt(0)
	v_cmp_lt_u32_e32 vcc, v1, v0
	s_and_saveexec_b64 s[42:43], vcc
	s_cbranch_execz .LBB0_1046
	v_mov_b64_e32 v[2:3], s[8:9]
	s_sleep 1
	global_load_dword v1, v[2:3], off sc1
	s_waitcnt vmcnt(0) lgkmcnt(0)
	v_cmp_lt_u32_e32 vcc, v1, v0
	s_and_saveexec_b64 s[44:45], vcc
	s_cbranch_execz .LBB0_1045
	v_mov_b64_e32 v[2:3], s[8:9]
	s_sleep 1
	global_load_dword v1, v[2:3], off sc1
	s_waitcnt vmcnt(0) lgkmcnt(0)
	v_cmp_lt_u32_e32 vcc, v1, v0
	s_and_saveexec_b64 s[46:47], vcc
	s_cbranch_execz .LBB0_1044
	v_mov_b64_e32 v[2:3], s[8:9]
	s_sleep 1
	global_load_dword v1, v[2:3], off sc1
	s_waitcnt vmcnt(0) lgkmcnt(0)
	v_cmp_lt_u32_e32 vcc, v1, v0
	s_and_saveexec_b64 s[68:69], vcc
	s_cbranch_execz .LBB0_1043
	v_mov_b64_e32 v[2:3], s[8:9]
	s_sleep 1
	global_load_dword v1, v[2:3], off sc1
	s_waitcnt vmcnt(0) lgkmcnt(0)
	v_cmp_lt_u32_e32 vcc, v1, v0
	s_and_saveexec_b64 s[88:89], vcc
	s_cbranch_execz .LBB0_1042
	v_mov_b64_e32 v[2:3], s[8:9]
	s_sleep 1
	global_load_dword v1, v[2:3], off sc1
	s_mov_b64 s[48:49], -1
	s_waitcnt vmcnt(0) lgkmcnt(0)
	v_cmp_lt_u32_e32 vcc, v1, v0
	s_and_saveexec_b64 s[18:19], vcc
	s_cbranch_execz .LBB0_1041
	v_mov_b64_e32 v[2:3], s[8:9]
	s_sleep 1
	global_load_dword v1, v[2:3], off sc1
	s_waitcnt vmcnt(0) lgkmcnt(0)
	v_cmp_lt_u32_e32 vcc, v1, v0
	s_and_saveexec_b64 s[66:67], vcc
	s_cbranch_execz .LBB0_1040
	s_add_i32 s0, s0, -8
	s_xor_b64 s[48:49], exec, -1
	s_sleep 1
	s_branch .LBB0_1040
